# v24 plus SGPR-base (saddr) form for 323 K-loop LDS-DMA loads: 32-bit VGPR offset instead of 64-bit VGPR address
# speedup vs baseline: 1.0031x; 1.0031x over previous
; #define PG8_STAGE(bufoff, gbase, voff) do { _Pragma("unroll") for (int _i = 0; _i < 2; ++_i) \
;         __builtin_amdgcn_global_load_lds((const unsigned*)((const char*)(gbase) + (voff)[_i]), (PG8_LAS unsigned*)(lds + (bufoff) + ldsw + _i * 8192), 16, 0, 0); } while (0)
; #define PG8_WAIT_V(n) asm volatile("s_waitcnt vmcnt(" #n ")" ::: "memory")
; #define PG8_BAR __builtin_amdgcn_s_barrier()
; template <class Epi, class Sched, bool ALIGN_EPI = false, bool SP2 = false, bool A_TILED = false>
; __device__ __forceinline__ void gemm_phase(PG8_LAS unsigned char* lds, const Gemm g, const Sched& S, const Epi& E, const int wave_s) {
;     ...
;     const unsigned ldsw = (unsigned)wid * 1024u;
;     const int aoff = lds_byte(wr * 64 + fr, fq * 8), boff = lds_byte(wc * 32 + fr, fq * 8);
;     ...
;         PG8_STAGE(PG8_SB(0, 0), cB, voffB); PG8_STAGE(PG8_SB(0, 1), cB + hstep, voffB); PG8_STAGE(PG8_SA(0, 0), cA, voffA); PG8_STAGE(PG8_SA(0, 1), cA + hstepA, voffA);
;         if (wr == 1) PG8_BAR;
;         PG8_WAIT_V(2); PG8_BAR;
;         PG8_STAGE(PG8_SB(1, 0), cB + kstep, voffB); PG8_STAGE(PG8_SA(1, 0), cA + kstepA, voffA); PG8_STAGE(PG8_SB(1, 1), cB + hstep + kstep, voffB);
;         PG8_WAIT_V(6); PG8_BAR;
;     } else {
;         PG8_STAGE(PG8_SB(0, 0), cB, voffB); PG8_STAGE(PG8_SA(0, 0), cA, voffA); PG8_STAGE(PG8_SB(0, 1), cB + hstep, voffB); PG8_STAGE(PG8_SA(0, 1), cA + hstepA, voffA);
;         if (wr == 1) PG8_BAR;
;         PG8_WAIT_V(4); PG8_BAR;
;         PG8_STAGE(PG8_SB(1, 0), cB + kstep, voffB); PG8_STAGE(PG8_SA(1, 0), cA + kstepA, voffA); PG8_STAGE(PG8_SB(1, 1), cB + hstep + kstep, voffB);
;         PG8_WAIT_V(6); PG8_BAR;
.LBB0_771:
	s_ashr_i32 s40, s86, 31
	s_add_u32 s0, s0, s29
	s_addc_u32 s1, s1, 0
	s_add_u32 s60, s0, 0x22600000
	s_addc_u32 s61, s1, 0
	s_lshl_b32 s0, s42, 5
	s_mov_b64 s[62:63], 0x80
	s_and_b32 s42, s0, 0x60
	s_add_i32 m0, s23, 0x18000
	v_lshl_add_u64 v[6:7], v[6:7], 0, s[62:63]
	s_lshl_b32 s41, s43, 6
	s_lshl_b32 s46, s43, 13
	s_lshl_b32 s47, s42, 7
	s_waitcnt vmcnt(2)
	s_barrier
	global_load_lds_dwordx4 v[6:7], off
	v_lshl_add_u64 v[4:5], v[4:5], 0, s[62:63]
	s_add_i32 m0, s23, 0x1a000
	s_add_i32 s43, s23, 0x8000
	s_add_i32 s44, s23, 0xa000
	global_load_lds_dwordx4 v[4:5], off
	v_lshl_add_u64 v[0:1], v[0:1], 0, s[62:63]
	s_mov_b32 m0, s43
	s_add_u32 s0, s80, 0x80080
	global_load_lds_dwordx4 v[0:1], off
	v_lshl_add_u64 v[0:1], v[2:3], 0, s[62:63]
	s_mov_b32 m0, s44
	s_addc_u32 s1, s81, 0
	global_load_lds_dwordx4 v[0:1], off
	s_add_i32 m0, s23, 0x1c000
	v_lshl_add_u64 v[0:1], s[0:1], 0, v[128:129]
	global_load_lds_dwordx4 v128, s[0:1]
	v_lshl_add_u64 v[0:1], s[0:1], 0, v[130:131]
	s_add_i32 m0, s23, 0x1e000
	s_movk_i32 s0, 0x3c0
	global_load_lds_dwordx4 v[0:1], off
	v_and_b32_e32 v0, 48, v8
	v_lshlrev_b32_e32 v1, 6, v8
	v_and_or_b32 v0, v1, s0, v0
	v_lshlrev_b32_e32 v1, 2, v8
	v_and_b32_e32 v1, 32, v1
	v_bitop3_b32 v2, v0, s46, v1 bitop3:0xde
	v_bitop3_b32 v148, s47, v0, v1 bitop3:0xf6
	v_lshlrev_b32_e32 v0, 15, v9
	v_and_b32_e32 v0, 0xffff0000, v0
	v_lshl_add_u32 v0, v10, 12, v0
	v_and_b32_e32 v1, 1, v9
	v_lshl_or_b32 v0, v1, 6, v0
	v_lshl_add_u32 v136, v11, 1, v0
	v_lshlrev_b32_e32 v0, 15, v13
	v_and_b32_e32 v0, 0xffff0000, v0
	s_waitcnt vmcnt(6)
	s_cmpk_lt_u32 s45, 0x100
	v_lshl_add_u32 v0, v12, 12, v0
	v_and_b32_e32 v1, 1, v13
	s_sext_i32_i16 s50, s64
	s_cselect_b64 s[64:65], -1, 0
	v_mov_b32_e32 v137, 0
	v_lshl_or_b32 v0, v1, 6, v0
	s_add_i32 s45, 0, 0x10000
	s_add_i32 s46, 0, 0x14000
	v_lshl_add_u32 v138, v14, 1, v0
	v_mov_b32_e32 v139, v137
	s_mov_b64 s[66:67], 0x180
	v_add_u32_e32 v149, s45, v148
	v_add_u32_e32 v150, s46, v148
	v_add_u32_e32 v151, 0, v2
	s_mov_b64 s[68:69], 0x100
	s_movk_i32 s47, 0x3000
	s_add_i32 s48, s23, 0xc000
	s_add_i32 s49, s23, 0xe000
	s_barrier
	s_branch .LBB0_774

.LBB0_776:
	s_ashr_i32 s73, s72, 31
	ds_read_b128 v[0:3], v149
	ds_read_b128 v[4:7], v149 offset:1024
	ds_read_b128 v[8:11], v149 offset:2048
	ds_read_b128 v[12:15], v149 offset:3072
	ds_read_b128 v[16:19], v150
	ds_read_b128 v[20:23], v150 offset:1024
	ds_read_b128 v[24:27], v150 offset:2048
	ds_read_b128 v[28:31], v150 offset:3072
	s_lshl_b64 s[52:53], s[72:73], 20
	s_add_u32 s74, s7, s52
	s_addc_u32 s75, s8, s53
	s_and_b64 s[52:53], s[0:1], exec
	s_cselect_b32 s51, s75, s83
	s_cselect_b32 s52, s74, s82
	s_ashr_i32 s71, s70, 31
	s_lshl_b64 s[54:55], s[70:71], 20
	s_add_u32 s76, s9, s54
	s_addc_u32 s77, s14, s55
	s_and_b64 s[54:55], s[0:1], exec
	s_cselect_b32 s53, s77, s81
	s_cselect_b32 s54, s76, s80
	s_add_u32 s56, s82, 0x80080
	s_addc_u32 s57, s83, 0
	s_mov_b32 m0, s48
	v_lshl_add_u64 v[64:65], s[56:57], 0, v[134:135]
	ds_read_b128 v[32:35], v151
	ds_read_b128 v[36:39], v151 offset:1024
	ds_read_b128 v[40:43], v151 offset:2048
	ds_read_b128 v[44:47], v151 offset:3072
	ds_read_b128 v[48:51], v151 offset:4096
	ds_read_b128 v[52:55], v151 offset:5120
	ds_read_b128 v[56:59], v151 offset:6144
	ds_read_b128 v[60:63], v151 offset:7168
	global_load_lds_dwordx4 v134, s[56:57]
	v_lshl_add_u64 v[64:65], s[56:57], 0, v[132:133]
	s_mov_b32 m0, s49
	s_nop 0
	global_load_lds_dwordx4 v132, s[56:57]
	s_waitcnt vmcnt(8) lgkmcnt(0)
	s_setprio 1
	s_barrier
	v_mfma_f32_16x16x32_bf16 v[88:91], v[0:3], v[56:59], 0
	v_mfma_f32_16x16x32_bf16 v[64:67], v[0:3], v[32:35], 0
	v_mfma_f32_16x16x32_bf16 v[68:71], v[8:11], v[32:35], 0
	v_mfma_f32_16x16x32_bf16 v[72:75], v[0:3], v[40:43], 0
	v_mfma_f32_16x16x32_bf16 v[76:79], v[8:11], v[40:43], 0
	v_mfma_f32_16x16x32_bf16 v[80:83], v[0:3], v[48:51], 0
	v_mfma_f32_16x16x32_bf16 v[84:87], v[8:11], v[48:51], 0
	v_mfma_f32_16x16x32_bf16 v[92:95], v[4:7], v[60:63], v[88:91]
	v_mfma_f32_16x16x32_bf16 v[88:91], v[8:11], v[56:59], 0
	v_mfma_f32_16x16x32_bf16 v[64:67], v[4:7], v[36:39], v[64:67]
	v_mfma_f32_16x16x32_bf16 v[68:71], v[12:15], v[36:39], v[68:71]
	v_mfma_f32_16x16x32_bf16 v[72:75], v[4:7], v[44:47], v[72:75]
	v_mfma_f32_16x16x32_bf16 v[76:79], v[12:15], v[44:47], v[76:79]
	v_mfma_f32_16x16x32_bf16 v[80:83], v[4:7], v[52:55], v[80:83]
	v_mfma_f32_16x16x32_bf16 v[84:87], v[12:15], v[52:55], v[84:87]
	v_mfma_f32_16x16x32_bf16 v[100:103], v[12:15], v[60:63], v[88:91]
	s_setprio 0
	s_setprio 1
	v_mfma_f32_16x16x32_bf16 v[88:91], v[16:19], v[32:35], 0
	v_mfma_f32_16x16x32_bf16 v[32:35], v[24:27], v[32:35], 0
	v_mfma_f32_16x16x32_bf16 v[108:111], v[20:23], v[36:39], v[88:91]
	v_mfma_f32_16x16x32_bf16 v[32:35], v[28:31], v[36:39], v[32:35]
	v_mfma_f32_16x16x32_bf16 v[36:39], v[16:19], v[40:43], 0
	v_mfma_f32_16x16x32_bf16 v[40:43], v[24:27], v[40:43], 0
	v_mfma_f32_16x16x32_bf16 v[36:39], v[20:23], v[44:47], v[36:39]
	v_mfma_f32_16x16x32_bf16 v[40:43], v[28:31], v[44:47], v[40:43]
	v_mfma_f32_16x16x32_bf16 v[44:47], v[16:19], v[48:51], 0
	v_mfma_f32_16x16x32_bf16 v[48:51], v[24:27], v[48:51], 0
	v_mfma_f32_16x16x32_bf16 v[44:47], v[20:23], v[52:55], v[44:47]
	v_mfma_f32_16x16x32_bf16 v[52:55], v[28:31], v[52:55], v[48:51]
	v_mfma_f32_16x16x32_bf16 v[48:51], v[16:19], v[56:59], 0
	v_mfma_f32_16x16x32_bf16 v[152:155], v[20:23], v[60:63], v[48:51]
	v_mfma_f32_16x16x32_bf16 v[48:51], v[24:27], v[56:59], 0
	v_mfma_f32_16x16x32_bf16 v[156:159], v[28:31], v[60:63], v[48:51]
	s_barrier
	s_setprio 0
	s_add_i32 s55, s45, s15
	v_lshl_add_u64 v[146:147], s[80:81], 0, v[128:129]
	s_add_i32 s56, s55, 0x2000
	v_lshl_add_u64 v[120:121], v[146:147], 0, s[68:69]
	s_mov_b32 m0, s55
	v_lshl_add_u64 v[252:253], s[80:81], 0, v[130:131]
	s_add_u32 s58, s80, 0x80100
	ds_read_b128 v[48:51], v151 offset:16384
	ds_read_b128 v[56:59], v151 offset:17408
	ds_read_b128 v[60:63], v151 offset:18432
	ds_read_b128 v[88:91], v151 offset:19456
	ds_read_b128 v[96:99], v151 offset:20480
	ds_read_b128 v[104:107], v151 offset:21504
	ds_read_b128 v[112:115], v151 offset:22528
	ds_read_b128 v[116:119], v151 offset:23552
	global_load_lds_dwordx4 v[120:121], off
	v_lshl_add_u64 v[120:121], v[252:253], 0, s[68:69]
	s_mov_b32 m0, s56
	s_addc_u32 s59, s81, 0
	s_add_i32 s57, s46, s15
	global_load_lds_dwordx4 v[120:121], off
	v_lshl_add_u64 v[120:121], s[58:59], 0, v[128:129]
	s_mov_b32 m0, s57
	v_lshl_add_u64 v[140:141], s[82:83], 0, v[134:135]
	global_load_lds_dwordx4 v128, s[58:59]
	v_lshl_add_u64 v[120:121], s[58:59], 0, v[130:131]
	s_add_i32 s58, s57, 0x2000
	s_mov_b32 m0, s58
	v_lshl_add_u64 v[142:143], s[82:83], 0, v[132:133]
	global_load_lds_dwordx4 v[120:121], off
	v_lshl_add_u64 v[120:121], v[140:141], 0, s[68:69]
	s_mov_b32 m0, s23
	s_nop 0
	global_load_lds_dwordx4 v[120:121], off
	v_lshl_add_u64 v[120:121], v[142:143], 0, s[68:69]
	s_mov_b32 m0, s36
	s_nop 0
	global_load_lds_dwordx4 v[120:121], off
	s_waitcnt vmcnt(8) lgkmcnt(0)
	s_setprio 1
	s_barrier
	v_mfma_f32_16x16x32_bf16 v[120:123], v[0:3], v[48:51], 0
	v_mfma_f32_16x16x32_bf16 v[160:163], v[4:7], v[56:59], v[120:123]
	v_mfma_f32_16x16x32_bf16 v[120:123], v[8:11], v[48:51], 0
	v_mfma_f32_16x16x32_bf16 v[164:167], v[12:15], v[56:59], v[120:123]
	v_mfma_f32_16x16x32_bf16 v[120:123], v[0:3], v[60:63], 0
	v_mfma_f32_16x16x32_bf16 v[168:171], v[4:7], v[88:91], v[120:123]
	v_mfma_f32_16x16x32_bf16 v[120:123], v[8:11], v[60:63], 0
	v_mfma_f32_16x16x32_bf16 v[172:175], v[12:15], v[88:91], v[120:123]
	v_mfma_f32_16x16x32_bf16 v[120:123], v[0:3], v[96:99], 0
	v_mfma_f32_16x16x32_bf16 v[0:3], v[0:3], v[112:115], 0
	v_mfma_f32_16x16x32_bf16 v[176:179], v[4:7], v[104:107], v[120:123]
	v_mfma_f32_16x16x32_bf16 v[0:3], v[4:7], v[116:119], v[0:3]
	v_mfma_f32_16x16x32_bf16 v[4:7], v[8:11], v[112:115], 0
	v_mfma_f32_16x16x32_bf16 v[120:123], v[8:11], v[96:99], 0
	v_mfma_f32_16x16x32_bf16 v[4:7], v[12:15], v[116:119], v[4:7]
	v_mfma_f32_16x16x32_bf16 v[180:183], v[12:15], v[104:107], v[120:123]
	s_setprio 0
	s_setprio 1
	v_mfma_f32_16x16x32_bf16 v[8:11], v[16:19], v[48:51], 0
	v_mfma_f32_16x16x32_bf16 v[12:15], v[20:23], v[56:59], v[8:11]
	v_mfma_f32_16x16x32_bf16 v[8:11], v[24:27], v[48:51], 0
	v_mfma_f32_16x16x32_bf16 v[184:187], v[28:31], v[56:59], v[8:11]
	v_mfma_f32_16x16x32_bf16 v[8:11], v[16:19], v[60:63], 0
	v_mfma_f32_16x16x32_bf16 v[188:191], v[20:23], v[88:91], v[8:11]
	v_mfma_f32_16x16x32_bf16 v[8:11], v[24:27], v[60:63], 0
	v_mfma_f32_16x16x32_bf16 v[192:195], v[28:31], v[88:91], v[8:11]
	v_mfma_f32_16x16x32_bf16 v[8:11], v[16:19], v[96:99], 0
	v_mfma_f32_16x16x32_bf16 v[196:199], v[20:23], v[104:107], v[8:11]
	v_mfma_f32_16x16x32_bf16 v[8:11], v[24:27], v[96:99], 0
	v_mfma_f32_16x16x32_bf16 v[200:203], v[28:31], v[104:107], v[8:11]
	v_mfma_f32_16x16x32_bf16 v[8:11], v[16:19], v[112:115], 0
	v_mfma_f32_16x16x32_bf16 v[204:207], v[20:23], v[116:119], v[8:11]
	v_mfma_f32_16x16x32_bf16 v[8:11], v[24:27], v[112:115], 0
	v_mfma_f32_16x16x32_bf16 v[208:211], v[28:31], v[116:119], v[8:11]
	s_barrier
	s_setprio 0
	s_add_i32 s59, 0, 0x18000
	s_add_i32 s73, 0, 0x1c000
	v_add_u32_e32 v144, s59, v148
	v_add_u32_e32 v145, s73, v148
	s_nop 0
	ds_read_b128 v[8:11], v144
	ds_read_b128 v[20:23], v144 offset:1024
	ds_read_b128 v[28:31], v144 offset:2048
	ds_read_b128 v[212:215], v144 offset:3072
	ds_read_b128 v[216:219], v145
	ds_read_b128 v[220:223], v145 offset:1024
	ds_read_b128 v[224:227], v145 offset:2048
	ds_read_b128 v[228:231], v145 offset:3072
	s_add_u32 s84, s82, 0x80100
	s_addc_u32 s85, s83, 0
	s_mov_b32 m0, s37
	v_lshl_add_u64 v[48:49], s[84:85], 0, v[134:135]
	ds_read_b128 v[16:19], v151 offset:32768
	ds_read_b128 v[24:27], v151 offset:33792
	ds_read_b128 v[60:63], v151 offset:34816
	ds_read_b128 v[232:235], v151 offset:35840
	ds_read_b128 v[236:239], v151 offset:36864
	ds_read_b128 v[240:243], v151 offset:37888
	ds_read_b128 v[244:247], v151 offset:38912
	ds_read_b128 v[248:251], v151 offset:39936
	global_load_lds_dwordx4 v134, s[84:85]
	v_lshl_add_u64 v[48:49], s[84:85], 0, v[132:133]
	s_mov_b32 m0, s38
	s_nop 0
	global_load_lds_dwordx4 v132, s[84:85]
	s_waitcnt vmcnt(8) lgkmcnt(0)
	s_setprio 1
	s_barrier
	v_mfma_f32_16x16x32_bf16 v[48:51], v[8:11], v[16:19], v[64:67]
	v_mfma_f32_16x16x32_bf16 v[120:123], v[20:23], v[24:27], v[48:51]
	v_mfma_f32_16x16x32_bf16 v[48:51], v[28:31], v[16:19], v[68:71]
	v_mfma_f32_16x16x32_bf16 v[112:115], v[212:215], v[24:27], v[48:51]
	v_mfma_f32_16x16x32_bf16 v[48:51], v[8:11], v[60:63], v[72:75]
	v_mfma_f32_16x16x32_bf16 v[104:107], v[20:23], v[232:235], v[48:51]
	v_mfma_f32_16x16x32_bf16 v[48:51], v[28:31], v[60:63], v[76:79]
	v_mfma_f32_16x16x32_bf16 v[96:99], v[212:215], v[232:235], v[48:51]
	v_mfma_f32_16x16x32_bf16 v[48:51], v[8:11], v[236:239], v[80:83]
	v_mfma_f32_16x16x32_bf16 v[88:91], v[20:23], v[240:243], v[48:51]
	v_mfma_f32_16x16x32_bf16 v[48:51], v[28:31], v[236:239], v[84:87]
	v_mfma_f32_16x16x32_bf16 v[80:83], v[212:215], v[240:243], v[48:51]
	v_mfma_f32_16x16x32_bf16 v[48:51], v[8:11], v[244:247], v[92:95]
	v_mfma_f32_16x16x32_bf16 v[56:59], v[20:23], v[248:251], v[48:51]
	v_mfma_f32_16x16x32_bf16 v[48:51], v[28:31], v[244:247], v[100:103]
	v_mfma_f32_16x16x32_bf16 v[48:51], v[212:215], v[248:251], v[48:51]
	s_setprio 0
	s_setprio 1
	v_mfma_f32_16x16x32_bf16 v[64:67], v[216:219], v[16:19], v[108:111]
	v_mfma_f32_16x16x32_bf16 v[16:19], v[224:227], v[16:19], v[32:35]
	v_mfma_f32_16x16x32_bf16 v[116:119], v[228:231], v[24:27], v[16:19]
	v_mfma_f32_16x16x32_bf16 v[16:19], v[216:219], v[60:63], v[36:39]
	v_mfma_f32_16x16x32_bf16 v[108:111], v[220:223], v[232:235], v[16:19]
	v_mfma_f32_16x16x32_bf16 v[16:19], v[224:227], v[60:63], v[40:43]
	v_mfma_f32_16x16x32_bf16 v[100:103], v[228:231], v[232:235], v[16:19]
	v_mfma_f32_16x16x32_bf16 v[16:19], v[216:219], v[236:239], v[44:47]
	v_mfma_f32_16x16x32_bf16 v[92:95], v[220:223], v[240:243], v[16:19]
	v_mfma_f32_16x16x32_bf16 v[16:19], v[224:227], v[236:239], v[52:55]
	v_mfma_f32_16x16x32_bf16 v[84:87], v[228:231], v[240:243], v[16:19]
	v_mfma_f32_16x16x32_bf16 v[16:19], v[216:219], v[244:247], v[152:155]
	v_mfma_f32_16x16x32_bf16 v[60:63], v[220:223], v[248:251], v[16:19]
	v_mfma_f32_16x16x32_bf16 v[16:19], v[224:227], v[244:247], v[156:159]
	v_mfma_f32_16x16x32_bf16 v[124:127], v[220:223], v[24:27], v[64:67]
	v_mfma_f32_16x16x32_bf16 v[52:55], v[228:231], v[248:251], v[16:19]
	s_barrier
; #define PG8_MMA(ai, bj, At, Bt) do { __builtin_amdgcn_s_setprio(1); _Pragma("unroll") for (int m = 0; m < 4; ++m) _Pragma("unroll") for (int n = 0; n < 2; ++n) _Pragma("unroll") for (int k = 0; k < 2; ++k) \
;         acc[ai][bj][m][n] = __builtin_amdgcn_mfma_f32_16x16x32_bf16(Bt[n][k], At[m][k], acc[ai][bj][m][n], 0, 0, 0); __builtin_amdgcn_s_setprio(0); } while (0)
; template <class Epi, class Sched, bool ALIGN_EPI = false, bool SP2 = false, bool A_TILED = false>
; __device__ __forceinline__ void gemm_phase(PG8_LAS unsigned char* lds, const Gemm g, const Sched& S, const Epi& E, const int wave_s) {
;     ...
;         for (int t = PEEL ? 2 : 0; t < nt; t += 2) {
;             const bool last = (t == nt - 2);
;             const char* a1 = cA + (size_t)(t + 1) * kstepA;
;             const char* a2 = last ? nA : cA + (size_t)(t + 2) * kstepA; const char* b2 = last ? nB : cB + (size_t)(t + 2) * kstep;
;             const char* a3 = a2 + kstepA; const char* b3 = b2 + kstep;
;             if (last && has_next) S.a_ready(nxt);
;             if constexpr (SP2) {
;             PG8_ITER(PG8_MMA)
	s_setprio 0
	s_add_i32 s59, s59, s15
	s_add_i32 s71, s59, 0x2000
	s_nop 1
	v_lshl_add_u64 v[16:17], v[146:147], 0, s[66:67]
	s_mov_b32 m0, s59
	s_add_u32 s84, s80, 0x80180
	ds_read_b128 v[36:39], v151 offset:49152
	ds_read_b128 v[44:47], v151 offset:50176
	ds_read_b128 v[152:155], v151 offset:51200
	ds_read_b128 v[156:159], v151 offset:52224
	ds_read_b128 v[232:235], v151 offset:53248
	ds_read_b128 v[236:239], v151 offset:54272
	ds_read_b128 v[240:243], v151 offset:55296
	ds_read_b128 v[244:247], v151 offset:56320
	global_load_lds_dwordx4 v[16:17], off
	v_lshl_add_u64 v[16:17], v[252:253], 0, s[66:67]
	s_mov_b32 m0, s71
	s_addc_u32 s85, s81, 0
	s_add_i32 s73, s73, s15
	global_load_lds_dwordx4 v[16:17], off
	v_lshl_add_u64 v[16:17], s[84:85], 0, v[128:129]
	s_mov_b32 m0, s73
	s_add_i32 s79, s73, 0x2000
	global_load_lds_dwordx4 v128, s[84:85]
	v_lshl_add_u64 v[16:17], s[84:85], 0, v[130:131]
	s_mov_b32 m0, s79
	s_nop 0
	global_load_lds_dwordx4 v130, s[84:85]
	v_lshl_add_u64 v[16:17], v[140:141], 0, s[66:67]
	s_mov_b32 m0, s43
	s_nop 0
	global_load_lds_dwordx4 v[16:17], off
	v_lshl_add_u64 v[16:17], v[142:143], 0, s[66:67]
	s_mov_b32 m0, s44
	s_nop 0
	global_load_lds_dwordx4 v[16:17], off
	s_waitcnt vmcnt(8) lgkmcnt(0)
	s_setprio 1
	s_barrier
	v_mfma_f32_16x16x32_bf16 v[16:19], v[8:11], v[36:39], v[160:163]
	v_mfma_f32_16x16x32_bf16 v[72:75], v[20:23], v[44:47], v[16:19]
	v_mfma_f32_16x16x32_bf16 v[16:19], v[28:31], v[36:39], v[164:167]
	v_mfma_f32_16x16x32_bf16 v[64:67], v[212:215], v[44:47], v[16:19]
	v_mfma_f32_16x16x32_bf16 v[16:19], v[8:11], v[152:155], v[168:171]
	v_mfma_f32_16x16x32_bf16 v[40:43], v[20:23], v[156:159], v[16:19]
	v_mfma_f32_16x16x32_bf16 v[16:19], v[28:31], v[152:155], v[172:175]
	v_mfma_f32_16x16x32_bf16 v[32:35], v[212:215], v[156:159], v[16:19]
	v_mfma_f32_16x16x32_bf16 v[16:19], v[8:11], v[232:235], v[176:179]
	v_mfma_f32_16x16x32_bf16 v[0:3], v[8:11], v[240:243], v[0:3]
	v_mfma_f32_16x16x32_bf16 v[24:27], v[20:23], v[236:239], v[16:19]
	v_mfma_f32_16x16x32_bf16 v[16:19], v[28:31], v[232:235], v[180:183]
	v_mfma_f32_16x16x32_bf16 v[8:11], v[20:23], v[244:247], v[0:3]
	v_mfma_f32_16x16x32_bf16 v[0:3], v[28:31], v[240:243], v[4:7]
	v_mfma_f32_16x16x32_bf16 v[16:19], v[212:215], v[236:239], v[16:19]
	v_mfma_f32_16x16x32_bf16 v[0:3], v[212:215], v[244:247], v[0:3]
	s_setprio 0
	s_setprio 1
	v_mfma_f32_16x16x32_bf16 v[4:7], v[216:219], v[36:39], v[12:15]
	v_mfma_f32_16x16x32_bf16 v[76:79], v[220:223], v[44:47], v[4:7]
	v_mfma_f32_16x16x32_bf16 v[4:7], v[224:227], v[36:39], v[184:187]
	v_mfma_f32_16x16x32_bf16 v[68:71], v[228:231], v[44:47], v[4:7]
	v_mfma_f32_16x16x32_bf16 v[4:7], v[216:219], v[152:155], v[188:191]
	v_mfma_f32_16x16x32_bf16 v[44:47], v[220:223], v[156:159], v[4:7]
	v_mfma_f32_16x16x32_bf16 v[4:7], v[224:227], v[152:155], v[192:195]
	v_mfma_f32_16x16x32_bf16 v[36:39], v[228:231], v[156:159], v[4:7]
	v_mfma_f32_16x16x32_bf16 v[4:7], v[216:219], v[232:235], v[196:199]
	v_mfma_f32_16x16x32_bf16 v[28:31], v[220:223], v[236:239], v[4:7]
	v_mfma_f32_16x16x32_bf16 v[4:7], v[224:227], v[232:235], v[200:203]
	v_mfma_f32_16x16x32_bf16 v[20:23], v[228:231], v[236:239], v[4:7]
	v_mfma_f32_16x16x32_bf16 v[4:7], v[216:219], v[240:243], v[204:207]
	v_mfma_f32_16x16x32_bf16 v[12:15], v[220:223], v[244:247], v[4:7]
	v_mfma_f32_16x16x32_bf16 v[4:7], v[224:227], v[240:243], v[208:211]
	v_mfma_f32_16x16x32_bf16 v[4:7], v[228:231], v[244:247], v[4:7]
	s_barrier
	s_setprio 0
	s_add_u32 s88, s80, 0x200
	s_addc_u32 s89, s81, 0
	s_add_u32 s80, s82, 0x80180
	s_addc_u32 s81, s83, 0
	s_mov_b32 s90, 0
.LBB0_777:
	ds_read_b128 v[152:155], v149
	ds_read_b128 v[156:159], v149 offset:1024
	ds_read_b128 v[160:163], v149 offset:2048
	ds_read_b128 v[164:167], v149 offset:3072
	ds_read_b128 v[168:171], v150
	ds_read_b128 v[172:175], v150 offset:1024
	ds_read_b128 v[176:179], v150 offset:2048
	ds_read_b128 v[180:183], v150 offset:3072
	s_add_u32 s82, s80, 0xfff80080
	s_addc_u32 s83, s81, -1
	s_cmp_eq_u32 s90, 28
	s_cselect_b32 s85, s51, s83
	s_cselect_b32 s84, s52, s82
	s_cselect_b32 s83, s53, s89
	s_cselect_b32 s82, s54, s88
	s_mov_b32 m0, s48
	v_lshl_add_u64 v[140:141], s[80:81], 0, v[138:139]
	ds_read_b128 v[184:187], v151
	ds_read_b128 v[188:191], v151 offset:1024
	ds_read_b128 v[192:195], v151 offset:2048
	ds_read_b128 v[196:199], v151 offset:3072
	ds_read_b128 v[200:203], v151 offset:4096
	ds_read_b128 v[204:207], v151 offset:5120
	ds_read_b128 v[208:211], v151 offset:6144
	ds_read_b128 v[212:215], v151 offset:7168
	global_load_lds_dwordx4 v138, s[80:81]
	v_lshl_add_u64 v[140:141], s[80:81], 0, v[136:137]
	s_mov_b32 m0, s49
	s_nop 0
	global_load_lds_dwordx4 v136, s[80:81]
	s_waitcnt vmcnt(8) lgkmcnt(0)
	s_setprio 1
	s_barrier
	v_mfma_f32_16x16x32_bf16 v[120:123], v[152:155], v[184:187], v[120:123]
	v_mfma_f32_16x16x32_bf16 v[112:115], v[160:163], v[184:187], v[112:115]
	v_mfma_f32_16x16x32_bf16 v[104:107], v[152:155], v[192:195], v[104:107]
	v_mfma_f32_16x16x32_bf16 v[96:99], v[160:163], v[192:195], v[96:99]
	v_mfma_f32_16x16x32_bf16 v[88:91], v[152:155], v[200:203], v[88:91]
	v_mfma_f32_16x16x32_bf16 v[80:83], v[160:163], v[200:203], v[80:83]
	v_mfma_f32_16x16x32_bf16 v[56:59], v[152:155], v[208:211], v[56:59]
	v_mfma_f32_16x16x32_bf16 v[48:51], v[160:163], v[208:211], v[48:51]
	v_mfma_f32_16x16x32_bf16 v[120:123], v[156:159], v[188:191], v[120:123]
	v_mfma_f32_16x16x32_bf16 v[112:115], v[164:167], v[188:191], v[112:115]
	v_mfma_f32_16x16x32_bf16 v[104:107], v[156:159], v[196:199], v[104:107]
	v_mfma_f32_16x16x32_bf16 v[96:99], v[164:167], v[196:199], v[96:99]
	v_mfma_f32_16x16x32_bf16 v[88:91], v[156:159], v[204:207], v[88:91]
	v_mfma_f32_16x16x32_bf16 v[80:83], v[164:167], v[204:207], v[80:83]
	v_mfma_f32_16x16x32_bf16 v[56:59], v[156:159], v[212:215], v[56:59]
	v_mfma_f32_16x16x32_bf16 v[48:51], v[164:167], v[212:215], v[48:51]
	s_setprio 0
	s_setprio 1
	v_mfma_f32_16x16x32_bf16 v[124:127], v[168:171], v[184:187], v[124:127]
	v_mfma_f32_16x16x32_bf16 v[116:119], v[176:179], v[184:187], v[116:119]
	v_mfma_f32_16x16x32_bf16 v[108:111], v[168:171], v[192:195], v[108:111]
	v_mfma_f32_16x16x32_bf16 v[100:103], v[176:179], v[192:195], v[100:103]
	v_mfma_f32_16x16x32_bf16 v[92:95], v[168:171], v[200:203], v[92:95]
	v_mfma_f32_16x16x32_bf16 v[84:87], v[176:179], v[200:203], v[84:87]
	v_mfma_f32_16x16x32_bf16 v[60:63], v[168:171], v[208:211], v[60:63]
	v_mfma_f32_16x16x32_bf16 v[52:55], v[176:179], v[208:211], v[52:55]
	v_mfma_f32_16x16x32_bf16 v[124:127], v[172:175], v[188:191], v[124:127]
	v_mfma_f32_16x16x32_bf16 v[116:119], v[180:183], v[188:191], v[116:119]
	v_mfma_f32_16x16x32_bf16 v[108:111], v[172:175], v[196:199], v[108:111]
	v_mfma_f32_16x16x32_bf16 v[100:103], v[180:183], v[196:199], v[100:103]
	v_mfma_f32_16x16x32_bf16 v[92:95], v[172:175], v[204:207], v[92:95]
	v_mfma_f32_16x16x32_bf16 v[84:87], v[180:183], v[204:207], v[84:87]
	v_mfma_f32_16x16x32_bf16 v[60:63], v[172:175], v[212:215], v[60:63]
	v_mfma_f32_16x16x32_bf16 v[52:55], v[180:183], v[212:215], v[52:55]
	s_barrier
	s_setprio 0
	s_mov_b32 m0, s55
	v_lshl_add_u64 v[140:141], s[82:83], 0, v[128:129]
	s_add_u32 s94, s82, 0x80000
	ds_read_b128 v[184:187], v151 offset:16384
	ds_read_b128 v[188:191], v151 offset:17408
	ds_read_b128 v[192:195], v151 offset:18432
	ds_read_b128 v[196:199], v151 offset:19456
	ds_read_b128 v[200:203], v151 offset:20480
	ds_read_b128 v[204:207], v151 offset:21504
	ds_read_b128 v[208:211], v151 offset:22528
	ds_read_b128 v[212:215], v151 offset:23552
	global_load_lds_dwordx4 v128, s[82:83]
	v_lshl_add_u64 v[142:143], s[82:83], 0, v[130:131]
	s_mov_b32 m0, s56
	s_addc_u32 s95, s83, 0
	global_load_lds_dwordx4 v130, s[82:83]
	v_lshl_add_u64 v[146:147], s[94:95], 0, v[128:129]
	s_mov_b32 m0, s57
	v_lshl_add_u64 v[216:217], s[84:85], 0, v[132:133]
	global_load_lds_dwordx4 v128, s[94:95]
	v_lshl_add_u64 v[146:147], s[94:95], 0, v[130:131]
	s_mov_b32 m0, s58
	s_nop 0
	global_load_lds_dwordx4 v130, s[94:95]
	v_lshl_add_u64 v[146:147], s[84:85], 0, v[134:135]
	s_mov_b32 m0, s23
	s_nop 0
	global_load_lds_dwordx4 v134, s[84:85]
	s_mov_b32 m0, s36
	s_nop 0
	global_load_lds_dwordx4 v132, s[84:85]
	s_waitcnt vmcnt(8) lgkmcnt(0)
	s_setprio 1
	s_barrier
	v_mfma_f32_16x16x32_bf16 v[72:75], v[152:155], v[184:187], v[72:75]
	v_mfma_f32_16x16x32_bf16 v[64:67], v[160:163], v[184:187], v[64:67]
	v_mfma_f32_16x16x32_bf16 v[40:43], v[152:155], v[192:195], v[40:43]
	v_mfma_f32_16x16x32_bf16 v[32:35], v[160:163], v[192:195], v[32:35]
	v_mfma_f32_16x16x32_bf16 v[24:27], v[152:155], v[200:203], v[24:27]
	v_mfma_f32_16x16x32_bf16 v[16:19], v[160:163], v[200:203], v[16:19]
	v_mfma_f32_16x16x32_bf16 v[8:11], v[152:155], v[208:211], v[8:11]
	v_mfma_f32_16x16x32_bf16 v[0:3], v[160:163], v[208:211], v[0:3]
	v_mfma_f32_16x16x32_bf16 v[72:75], v[156:159], v[188:191], v[72:75]
	v_mfma_f32_16x16x32_bf16 v[64:67], v[164:167], v[188:191], v[64:67]
	v_mfma_f32_16x16x32_bf16 v[40:43], v[156:159], v[196:199], v[40:43]
	v_mfma_f32_16x16x32_bf16 v[32:35], v[164:167], v[196:199], v[32:35]
	v_mfma_f32_16x16x32_bf16 v[24:27], v[156:159], v[204:207], v[24:27]
	v_mfma_f32_16x16x32_bf16 v[16:19], v[164:167], v[204:207], v[16:19]
	v_mfma_f32_16x16x32_bf16 v[8:11], v[156:159], v[212:215], v[8:11]
	v_mfma_f32_16x16x32_bf16 v[0:3], v[164:167], v[212:215], v[0:3]
	s_setprio 0
	s_setprio 1
	v_mfma_f32_16x16x32_bf16 v[76:79], v[168:171], v[184:187], v[76:79]
	v_mfma_f32_16x16x32_bf16 v[68:71], v[176:179], v[184:187], v[68:71]
	v_mfma_f32_16x16x32_bf16 v[44:47], v[168:171], v[192:195], v[44:47]
	v_mfma_f32_16x16x32_bf16 v[36:39], v[176:179], v[192:195], v[36:39]
	v_mfma_f32_16x16x32_bf16 v[28:31], v[168:171], v[200:203], v[28:31]
	v_mfma_f32_16x16x32_bf16 v[20:23], v[176:179], v[200:203], v[20:23]
	v_mfma_f32_16x16x32_bf16 v[12:15], v[168:171], v[208:211], v[12:15]
	v_mfma_f32_16x16x32_bf16 v[4:7], v[176:179], v[208:211], v[4:7]
	v_mfma_f32_16x16x32_bf16 v[76:79], v[172:175], v[188:191], v[76:79]
	v_mfma_f32_16x16x32_bf16 v[68:71], v[180:183], v[188:191], v[68:71]
	v_mfma_f32_16x16x32_bf16 v[44:47], v[172:175], v[196:199], v[44:47]
	v_mfma_f32_16x16x32_bf16 v[36:39], v[180:183], v[196:199], v[36:39]
	v_mfma_f32_16x16x32_bf16 v[28:31], v[172:175], v[204:207], v[28:31]
	v_mfma_f32_16x16x32_bf16 v[20:23], v[180:183], v[204:207], v[20:23]
	v_mfma_f32_16x16x32_bf16 v[12:15], v[172:175], v[212:215], v[12:15]
	v_mfma_f32_16x16x32_bf16 v[4:7], v[180:183], v[212:215], v[4:7]
	s_barrier
; template <class Epi, class Sched, bool ALIGN_EPI = false, bool SP2 = false, bool A_TILED = false>
; __device__ __forceinline__ void gemm_phase(PG8_LAS unsigned char* lds, const Gemm g, const Sched& S, const Epi& E, const int wave_s) {
;     ...
;         for (int t = PEEL ? 2 : 0; t < nt; t += 2) {
;             const bool last = (t == nt - 2);
;             const char* a1 = cA + (size_t)(t + 1) * kstepA;
;             const char* a2 = last ? nA : cA + (size_t)(t + 2) * kstepA; const char* b2 = last ? nB : cB + (size_t)(t + 2) * kstep;
;             const char* a3 = a2 + kstepA; const char* b3 = b2 + kstep;
	s_setprio 0
	ds_read_b128 v[152:155], v144
	ds_read_b128 v[156:159], v144 offset:1024
	ds_read_b128 v[160:163], v144 offset:2048
	ds_read_b128 v[164:167], v144 offset:3072
	ds_read_b128 v[168:171], v145
	ds_read_b128 v[172:175], v145 offset:1024
	ds_read_b128 v[176:179], v145 offset:2048
	ds_read_b128 v[180:183], v145 offset:3072
	s_add_u32 s84, s84, 0x80000
	s_addc_u32 s85, s85, 0
	s_mov_b32 m0, s37
	v_lshl_add_u64 v[218:219], s[84:85], 0, v[134:135]
	ds_read_b128 v[184:187], v151 offset:32768
	ds_read_b128 v[188:191], v151 offset:33792
	ds_read_b128 v[192:195], v151 offset:34816
	ds_read_b128 v[196:199], v151 offset:35840
	ds_read_b128 v[200:203], v151 offset:36864
	ds_read_b128 v[204:207], v151 offset:37888
	ds_read_b128 v[208:211], v151 offset:38912
	ds_read_b128 v[212:215], v151 offset:39936
	global_load_lds_dwordx4 v134, s[84:85]
	v_lshl_add_u64 v[218:219], s[84:85], 0, v[132:133]
	s_mov_b32 m0, s38
	s_nop 0
	global_load_lds_dwordx4 v132, s[84:85]
	s_waitcnt vmcnt(8) lgkmcnt(0)
	s_setprio 1
	s_barrier
	v_mfma_f32_16x16x32_bf16 v[120:123], v[152:155], v[184:187], v[120:123]
	v_mfma_f32_16x16x32_bf16 v[112:115], v[160:163], v[184:187], v[112:115]
	v_mfma_f32_16x16x32_bf16 v[104:107], v[152:155], v[192:195], v[104:107]
	v_mfma_f32_16x16x32_bf16 v[96:99], v[160:163], v[192:195], v[96:99]
	v_mfma_f32_16x16x32_bf16 v[88:91], v[152:155], v[200:203], v[88:91]
	v_mfma_f32_16x16x32_bf16 v[80:83], v[160:163], v[200:203], v[80:83]
	v_mfma_f32_16x16x32_bf16 v[56:59], v[152:155], v[208:211], v[56:59]
	v_mfma_f32_16x16x32_bf16 v[48:51], v[160:163], v[208:211], v[48:51]
	v_mfma_f32_16x16x32_bf16 v[120:123], v[156:159], v[188:191], v[120:123]
	v_mfma_f32_16x16x32_bf16 v[112:115], v[164:167], v[188:191], v[112:115]
	v_mfma_f32_16x16x32_bf16 v[104:107], v[156:159], v[196:199], v[104:107]
	v_mfma_f32_16x16x32_bf16 v[96:99], v[164:167], v[196:199], v[96:99]
	v_mfma_f32_16x16x32_bf16 v[88:91], v[156:159], v[204:207], v[88:91]
	v_mfma_f32_16x16x32_bf16 v[80:83], v[164:167], v[204:207], v[80:83]
	v_mfma_f32_16x16x32_bf16 v[56:59], v[156:159], v[212:215], v[56:59]
	v_mfma_f32_16x16x32_bf16 v[48:51], v[164:167], v[212:215], v[48:51]
	s_setprio 0
	s_setprio 1
	v_mfma_f32_16x16x32_bf16 v[124:127], v[168:171], v[184:187], v[124:127]
	v_mfma_f32_16x16x32_bf16 v[116:119], v[176:179], v[184:187], v[116:119]
	v_mfma_f32_16x16x32_bf16 v[108:111], v[168:171], v[192:195], v[108:111]
	v_mfma_f32_16x16x32_bf16 v[100:103], v[176:179], v[192:195], v[100:103]
	v_mfma_f32_16x16x32_bf16 v[92:95], v[168:171], v[200:203], v[92:95]
	v_mfma_f32_16x16x32_bf16 v[84:87], v[176:179], v[200:203], v[84:87]
	v_mfma_f32_16x16x32_bf16 v[60:63], v[168:171], v[208:211], v[60:63]
	v_mfma_f32_16x16x32_bf16 v[52:55], v[176:179], v[208:211], v[52:55]
	v_mfma_f32_16x16x32_bf16 v[124:127], v[172:175], v[188:191], v[124:127]
	v_mfma_f32_16x16x32_bf16 v[116:119], v[180:183], v[188:191], v[116:119]
	v_mfma_f32_16x16x32_bf16 v[108:111], v[172:175], v[196:199], v[108:111]
	v_mfma_f32_16x16x32_bf16 v[100:103], v[180:183], v[196:199], v[100:103]
	v_mfma_f32_16x16x32_bf16 v[92:95], v[172:175], v[204:207], v[92:95]
	v_mfma_f32_16x16x32_bf16 v[84:87], v[180:183], v[204:207], v[84:87]
	v_mfma_f32_16x16x32_bf16 v[60:63], v[172:175], v[212:215], v[60:63]
	v_mfma_f32_16x16x32_bf16 v[52:55], v[180:183], v[212:215], v[52:55]
	s_barrier
	s_setprio 0
	s_mov_b32 m0, s59
	v_lshl_add_u64 v[140:141], v[140:141], 0, s[62:63]
	s_add_u32 s82, s82, 0x80080
	ds_read_b128 v[184:187], v151 offset:49152
	ds_read_b128 v[188:191], v151 offset:50176
	ds_read_b128 v[192:195], v151 offset:51200
	ds_read_b128 v[196:199], v151 offset:52224
	ds_read_b128 v[200:203], v151 offset:53248
	ds_read_b128 v[204:207], v151 offset:54272
	ds_read_b128 v[208:211], v151 offset:55296
	ds_read_b128 v[212:215], v151 offset:56320
	global_load_lds_dwordx4 v[140:141], off
	v_lshl_add_u64 v[140:141], v[142:143], 0, s[62:63]
	s_mov_b32 m0, s71
	s_addc_u32 s83, s83, 0
	global_load_lds_dwordx4 v[140:141], off
	v_lshl_add_u64 v[140:141], s[82:83], 0, v[128:129]
	s_mov_b32 m0, s73
	s_nop 0
	global_load_lds_dwordx4 v128, s[82:83]
	v_lshl_add_u64 v[140:141], s[82:83], 0, v[130:131]
	s_mov_b32 m0, s79
	s_nop 0
	global_load_lds_dwordx4 v130, s[82:83]
	v_lshl_add_u64 v[140:141], v[146:147], 0, s[62:63]
	s_mov_b32 m0, s43
	s_nop 0
	global_load_lds_dwordx4 v[140:141], off
	v_lshl_add_u64 v[140:141], v[216:217], 0, s[62:63]
	s_mov_b32 m0, s44
	s_nop 0
	global_load_lds_dwordx4 v[140:141], off
	s_waitcnt vmcnt(8) lgkmcnt(0)
	s_setprio 1
	s_barrier
	v_mfma_f32_16x16x32_bf16 v[72:75], v[152:155], v[184:187], v[72:75]
	v_mfma_f32_16x16x32_bf16 v[64:67], v[160:163], v[184:187], v[64:67]
	v_mfma_f32_16x16x32_bf16 v[40:43], v[152:155], v[192:195], v[40:43]
	v_mfma_f32_16x16x32_bf16 v[32:35], v[160:163], v[192:195], v[32:35]
	v_mfma_f32_16x16x32_bf16 v[24:27], v[152:155], v[200:203], v[24:27]
	v_mfma_f32_16x16x32_bf16 v[16:19], v[160:163], v[200:203], v[16:19]
	v_mfma_f32_16x16x32_bf16 v[8:11], v[152:155], v[208:211], v[8:11]
	v_mfma_f32_16x16x32_bf16 v[0:3], v[160:163], v[208:211], v[0:3]
	v_mfma_f32_16x16x32_bf16 v[72:75], v[156:159], v[188:191], v[72:75]
	v_mfma_f32_16x16x32_bf16 v[64:67], v[164:167], v[188:191], v[64:67]
	v_mfma_f32_16x16x32_bf16 v[40:43], v[156:159], v[196:199], v[40:43]
	v_mfma_f32_16x16x32_bf16 v[32:35], v[164:167], v[196:199], v[32:35]
	v_mfma_f32_16x16x32_bf16 v[24:27], v[156:159], v[204:207], v[24:27]
	v_mfma_f32_16x16x32_bf16 v[16:19], v[164:167], v[204:207], v[16:19]
	v_mfma_f32_16x16x32_bf16 v[8:11], v[156:159], v[212:215], v[8:11]
	v_mfma_f32_16x16x32_bf16 v[0:3], v[164:167], v[212:215], v[0:3]
	s_setprio 0
	s_setprio 1
	v_mfma_f32_16x16x32_bf16 v[76:79], v[168:171], v[184:187], v[76:79]
	v_mfma_f32_16x16x32_bf16 v[68:71], v[176:179], v[184:187], v[68:71]
	v_mfma_f32_16x16x32_bf16 v[44:47], v[168:171], v[192:195], v[44:47]
	v_mfma_f32_16x16x32_bf16 v[36:39], v[176:179], v[192:195], v[36:39]
	v_mfma_f32_16x16x32_bf16 v[28:31], v[168:171], v[200:203], v[28:31]
	v_mfma_f32_16x16x32_bf16 v[20:23], v[176:179], v[200:203], v[20:23]
	v_mfma_f32_16x16x32_bf16 v[12:15], v[168:171], v[208:211], v[12:15]
	v_mfma_f32_16x16x32_bf16 v[4:7], v[176:179], v[208:211], v[4:7]
	v_mfma_f32_16x16x32_bf16 v[76:79], v[172:175], v[188:191], v[76:79]
	v_mfma_f32_16x16x32_bf16 v[68:71], v[180:183], v[188:191], v[68:71]
	v_mfma_f32_16x16x32_bf16 v[44:47], v[172:175], v[196:199], v[44:47]
	v_mfma_f32_16x16x32_bf16 v[36:39], v[180:183], v[196:199], v[36:39]
	v_mfma_f32_16x16x32_bf16 v[28:31], v[172:175], v[204:207], v[28:31]
	v_mfma_f32_16x16x32_bf16 v[20:23], v[180:183], v[204:207], v[20:23]
	v_mfma_f32_16x16x32_bf16 v[12:15], v[172:175], v[212:215], v[12:15]
	v_mfma_f32_16x16x32_bf16 v[4:7], v[180:183], v[212:215], v[4:7]
	s_barrier
	s_setprio 0
	s_add_i32 s90, s90, 2
	s_add_u32 s88, s88, 0x100
	s_addc_u32 s89, s89, 0
	s_add_u32 s80, s80, 0x100
	s_addc_u32 s81, s81, 0
	s_cmp_gt_u32 s90, 29
	s_cbranch_scc0 .LBB0_777
	s_and_b64 vcc, exec, s[64:65]
	s_cbranch_vccz .LBB0_780
	s_barrier

; #define PG8_STAGE(bufoff, gbase, voff) do { _Pragma("unroll") for (int _i = 0; _i < 2; ++_i) \
;         __builtin_amdgcn_global_load_lds((const unsigned*)((const char*)(gbase) + (voff)[_i]), (PG8_LAS unsigned*)(lds + (bufoff) + ldsw + _i * 8192), 16, 0, 0); } while (0)
; #define PG8_WAIT_V(n) asm volatile("s_waitcnt vmcnt(" #n ")" ::: "memory")
; template <class Epi, class Sched, bool ALIGN_EPI = false, bool SP2 = false, bool A_TILED = false>
; __device__ __forceinline__ void gemm_phase(PG8_LAS unsigned char* lds, const Gemm g, const Sched& S, const Epi& E, const int wave_s) {
;     ...
;     if constexpr (SP2) {
;         PG8_STAGE(PG8_SB(0, 0), cB, voffB); PG8_STAGE(PG8_SB(0, 1), cB + hstep, voffB); PG8_STAGE(PG8_SA(0, 0), cA, voffA); PG8_STAGE(PG8_SA(0, 1), cA + hstepA, voffA);
;         if (wr == 1) PG8_BAR;
;         PG8_WAIT_V(2); PG8_BAR;
;         PG8_STAGE(PG8_SB(1, 0), cB + kstep, voffB); PG8_STAGE(PG8_SA(1, 0), cA + kstepA, voffA); PG8_STAGE(PG8_SB(1, 1), cB + hstep + kstep, voffB);
;         PG8_WAIT_V(6); PG8_BAR;
;     } else {
;         PG8_STAGE(PG8_SB(0, 0), cB, voffB); PG8_STAGE(PG8_SA(0, 0), cA, voffA); PG8_STAGE(PG8_SB(0, 1), cB + hstep, voffB); PG8_STAGE(PG8_SA(0, 1), cA + hstepA, voffA);
;         if (wr == 1) PG8_BAR;
;         PG8_WAIT_V(4); PG8_BAR;
;         PG8_STAGE(PG8_SB(1, 0), cB + kstep, voffB); PG8_STAGE(PG8_SA(1, 0), cA + kstepA, voffA); PG8_STAGE(PG8_SB(1, 1), cB + hstep + kstep, voffB);
;         PG8_WAIT_V(6); PG8_BAR;
;     }
;     for (;;) {
;         const bool has_next = Epi::AFTER_DRAIN ? false : S.next(ui + 1, nxt);
;         const char* nA = has_next ? (const char*)g.A + (size_t)nxt.pm * tstepA : cA; const char* nB = has_next ? (const char*)g.Bt + (size_t)nxt.pn * tstep : cB;
;         constexpr bool PEEL = SP2 && !Epi::AFTER_DRAIN;
;         if constexpr (PEEL) {
;             const char* a1 = cA + kstepA; const char* a2 = cA + 2 * kstepA; const char* b2 = cB + 2 * kstep; const char* a3 = a2 + kstepA; const char* b3 = b2 + kstep;
;             PG8_ITER(PG8_MMAZ)
;         } else {
; #pragma unroll
;             for (int a = 0; a < 2; ++a)
; #pragma unroll
;                 for (int b = 0; b < 2; ++b)
; #pragma unroll
;                     for (int m = 0; m < 4; ++m)
; #pragma unroll
;                         for (int n = 0; n < 2; ++n) acc[a][b][m][n] = (f32x4){0.f, 0.f, 0.f, 0.f};
.LBB0_1042:
	v_and_b32_e32 v15, 48, v8
	v_lshlrev_b32_e32 v16, 6, v8
	s_movk_i32 s36, 0x3c0
	v_lshlrev_b32_e32 v8, 2, v8
	s_and_b32 s9, s7, 3
	s_lshl_b32 s8, s23, 6
	s_lshl_b32 s23, s23, 13
	v_and_or_b32 v15, v16, s36, v15
	v_and_b32_e32 v8, 32, v8
	s_mov_b64 s[66:67], 0x80
	v_bitop3_b32 v16, v15, s23, v8 bitop3:0xde
	s_lshl_b32 s23, s9, 12
	s_add_i32 m0, s14, 0x18000
	v_lshl_add_u64 v[6:7], v[6:7], 0, s[66:67]
	v_bitop3_b32 v8, v15, s23, v8 bitop3:0xde
	s_waitcnt vmcnt(2)
	s_barrier
	global_load_lds_dwordx4 v[6:7], off
	v_lshl_add_u64 v[4:5], v[4:5], 0, s[66:67]
	s_add_i32 m0, s14, 0x1a000
	s_add_i32 s23, s14, 0x8000
	s_add_i32 s36, s14, 0xa000
	global_load_lds_dwordx4 v[4:5], off
	v_lshl_add_u64 v[2:3], v[2:3], 0, s[66:67]
	s_mov_b32 m0, s23
	s_add_u32 s38, s0, 0x80080
	global_load_lds_dwordx4 v[2:3], off
	v_lshl_add_u64 v[0:1], v[0:1], 0, s[66:67]
	s_mov_b32 m0, s36
	s_addc_u32 s39, s1, 0
	global_load_lds_dwordx4 v[0:1], off
	s_add_i32 m0, s14, 0x1c000
	v_lshl_add_u64 v[0:1], s[38:39], 0, v[130:131]
	global_load_lds_dwordx4 v130, s[38:39]
	v_lshl_add_u64 v[0:1], s[38:39], 0, v[134:135]
	s_add_i32 m0, s14, 0x1e000
	s_mov_b64 s[40:41], 0x20680080
	global_load_lds_dwordx4 v134, s[38:39]
	v_lshlrev_b32_e32 v0, 15, v12
	v_and_b32_e32 v0, 0xffff0000, v0
	v_lshl_add_u32 v0, v13, 12, v0
	v_and_b32_e32 v1, 1, v12
	v_lshl_or_b32 v0, v1, 6, v0
	v_lshl_add_u32 v0, v14, 1, v0
	v_mov_b32_e32 v1, v131
	v_lshl_add_u64 v[0:1], s[68:69], 0, v[0:1]
	v_lshl_add_u64 v[136:137], v[0:1], 0, s[40:41]
	v_lshlrev_b32_e32 v0, 15, v9
	v_and_b32_e32 v0, 0xffff0000, v0
	v_lshl_add_u32 v0, v10, 12, v0
	v_and_b32_e32 v1, 1, v9
	s_add_u32 s37, s70, 0x3200100
	v_lshl_or_b32 v0, v1, 6, v0
	s_addc_u32 s38, s71, 0
	v_lshl_add_u32 v0, v11, 1, v0
	v_mov_b32_e32 v1, v131
	v_lshl_add_u64 v[0:1], s[68:69], 0, v[0:1]
	s_add_u32 s39, s68, 0x20600100
	s_waitcnt vmcnt(6)
	v_lshl_add_u64 v[138:139], v[0:1], 0, s[40:41]
	s_addc_u32 s40, s69, 0
	s_add_i32 s44, 0, 0x10000
	s_add_i32 s46, 0, 0x14000
	s_add_i32 s48, 0, 0x18000
	s_add_i32 s51, 0, 0x1c000
	v_add_u32_e32 v140, s44, v8
	v_add_u32_e32 v141, s46, v8
	s_add_i32 s44, s44, s50
	s_add_i32 s46, s46, s50
	v_add_u32_e32 v143, s48, v8
	s_add_i32 s48, s48, s50
	s_add_i32 s50, s51, s50
	s_mov_b32 s41, -2
	v_add_u32_e32 v142, 0, v16
	s_add_i32 s42, s14, 0xc000
	s_add_i32 s43, s14, 0xe000
	s_add_i32 s45, s44, 0x2000
	s_add_i32 s47, s46, 0x2000
	v_add_u32_e32 v144, s51, v8
	s_add_i32 s49, s48, 0x2000
	s_add_i32 s51, s50, 0x2000
	s_mov_b64 s[68:69], 0x100
	v_mov_b32_e32 v0, v131
	v_mov_b32_e32 v1, v131
	v_mov_b32_e32 v2, v131
	v_mov_b32_e32 v3, v131
	v_mov_b32_e32 v4, v131
	v_mov_b32_e32 v5, v131
	v_mov_b32_e32 v6, v131
	v_mov_b32_e32 v7, v131
	v_mov_b32_e32 v24, v131
	v_mov_b32_e32 v25, v131
	v_mov_b32_e32 v26, v131
	v_mov_b32_e32 v27, v131
	v_mov_b32_e32 v28, v131
	v_mov_b32_e32 v29, v131
	v_mov_b32_e32 v30, v131
	v_mov_b32_e32 v31, v131
	v_mov_b32_e32 v88, v131
	v_mov_b32_e32 v89, v131
	v_mov_b32_e32 v90, v131
	v_mov_b32_e32 v91, v131
	v_mov_b32_e32 v92, v131
	v_mov_b32_e32 v93, v131
	v_mov_b32_e32 v94, v131
	v_mov_b32_e32 v95, v131
	v_mov_b32_e32 v112, v131
	v_mov_b32_e32 v113, v131
	v_mov_b32_e32 v114, v131
	v_mov_b32_e32 v115, v131
	v_mov_b32_e32 v116, v131
	v_mov_b32_e32 v117, v131
	v_mov_b32_e32 v118, v131
	v_mov_b32_e32 v119, v131
	v_mov_b32_e32 v16, v131
	v_mov_b32_e32 v17, v131
	v_mov_b32_e32 v18, v131
	v_mov_b32_e32 v19, v131
	v_mov_b32_e32 v20, v131
	v_mov_b32_e32 v21, v131
	v_mov_b32_e32 v22, v131
	v_mov_b32_e32 v23, v131
	v_mov_b32_e32 v76, v131
	v_mov_b32_e32 v77, v131
	v_mov_b32_e32 v78, v131
	v_mov_b32_e32 v79, v131
	v_mov_b32_e32 v84, v131
	v_mov_b32_e32 v85, v131
	v_mov_b32_e32 v86, v131
	v_mov_b32_e32 v87, v131
	v_mov_b32_e32 v120, v131
	v_mov_b32_e32 v121, v131
	v_mov_b32_e32 v122, v131
	v_mov_b32_e32 v123, v131
	v_mov_b32_e32 v124, v131
	v_mov_b32_e32 v125, v131
	v_mov_b32_e32 v126, v131
	v_mov_b32_e32 v127, v131
	v_mov_b32_e32 v104, v131
	v_mov_b32_e32 v105, v131
	v_mov_b32_e32 v106, v131
	v_mov_b32_e32 v107, v131
	v_mov_b32_e32 v108, v131
	v_mov_b32_e32 v109, v131
	v_mov_b32_e32 v110, v131
	v_mov_b32_e32 v111, v131
	v_mov_b32_e32 v96, v131
	v_mov_b32_e32 v97, v131
	v_mov_b32_e32 v98, v131
	v_mov_b32_e32 v99, v131
	v_mov_b32_e32 v100, v131
	v_mov_b32_e32 v101, v131
	v_mov_b32_e32 v102, v131
	v_mov_b32_e32 v103, v131
	v_mov_b32_e32 v64, v131
	v_mov_b32_e32 v65, v131
	v_mov_b32_e32 v66, v131
	v_mov_b32_e32 v67, v131
	v_mov_b32_e32 v68, v131
	v_mov_b32_e32 v69, v131
	v_mov_b32_e32 v70, v131
	v_mov_b32_e32 v71, v131
	v_mov_b32_e32 v48, v131
	v_mov_b32_e32 v49, v131
	v_mov_b32_e32 v50, v131
	v_mov_b32_e32 v51, v131
	v_mov_b32_e32 v52, v131
	v_mov_b32_e32 v53, v131
	v_mov_b32_e32 v54, v131
	v_mov_b32_e32 v55, v131
	v_mov_b32_e32 v40, v131
	v_mov_b32_e32 v41, v131
	v_mov_b32_e32 v42, v131
	v_mov_b32_e32 v43, v131
	v_mov_b32_e32 v44, v131
	v_mov_b32_e32 v45, v131
	v_mov_b32_e32 v46, v131
	v_mov_b32_e32 v47, v131
	v_mov_b32_e32 v72, v131
	v_mov_b32_e32 v73, v131
	v_mov_b32_e32 v74, v131
	v_mov_b32_e32 v75, v131
	v_mov_b32_e32 v80, v131
	v_mov_b32_e32 v81, v131
	v_mov_b32_e32 v82, v131
	v_mov_b32_e32 v83, v131
	v_mov_b32_e32 v56, v131
	v_mov_b32_e32 v57, v131
	v_mov_b32_e32 v58, v131
	v_mov_b32_e32 v59, v131
	v_mov_b32_e32 v60, v131
	v_mov_b32_e32 v61, v131
	v_mov_b32_e32 v62, v131
	v_mov_b32_e32 v63, v131
	v_mov_b32_e32 v32, v131
	v_mov_b32_e32 v33, v131
	v_mov_b32_e32 v34, v131
	v_mov_b32_e32 v35, v131
	v_mov_b32_e32 v36, v131
	v_mov_b32_e32 v37, v131
	v_mov_b32_e32 v38, v131
	v_mov_b32_e32 v39, v131
	v_mov_b32_e32 v12, v131
	v_mov_b32_e32 v13, v131
	v_mov_b32_e32 v14, v131
	v_mov_b32_e32 v15, v131
	v_mov_b32_e32 v8, v131
	v_mov_b32_e32 v9, v131
	v_mov_b32_e32 v10, v131
	v_mov_b32_e32 v11, v131
	s_barrier
; #define PG8_MMA(ai, bj, At, Bt) do { __builtin_amdgcn_s_setprio(1); _Pragma("unroll") for (int m = 0; m < 4; ++m) _Pragma("unroll") for (int n = 0; n < 2; ++n) _Pragma("unroll") for (int k = 0; k < 2; ++k) \
;         acc[ai][bj][m][n] = __builtin_amdgcn_mfma_f32_16x16x32_bf16(Bt[n][k], At[m][k], acc[ai][bj][m][n], 0, 0, 0); __builtin_amdgcn_s_setprio(0); } while (0)
; template <class Epi, class Sched, bool ALIGN_EPI = false, bool SP2 = false, bool A_TILED = false>
; __device__ __forceinline__ void gemm_phase(PG8_LAS unsigned char* lds, const Gemm g, const Sched& S, const Epi& E, const int wave_s) {
;     ...
;         for (int t = PEEL ? 2 : 0; t < nt; t += 2) {
;             const bool last = (t == nt - 2);
;             const char* a1 = cA + (size_t)(t + 1) * kstepA;
;             const char* a2 = last ? nA : cA + (size_t)(t + 2) * kstepA; const char* b2 = last ? nB : cB + (size_t)(t + 2) * kstep;
;             const char* a3 = a2 + kstepA; const char* b3 = b2 + kstep;
;             if (last && has_next) S.a_ready(nxt);
;             if constexpr (SP2) {
;             PG8_ITER(PG8_MMA)
.LBB0_1043:
	ds_read_b128 v[146:149], v140
	ds_read_b128 v[150:153], v140 offset:1024
	ds_read_b128 v[154:157], v140 offset:2048
	ds_read_b128 v[158:161], v140 offset:3072
	ds_read_b128 v[162:165], v141
	ds_read_b128 v[166:169], v141 offset:1024
	ds_read_b128 v[170:173], v141 offset:2048
	ds_read_b128 v[174:177], v141 offset:3072
	s_add_u32 s52, s62, s39
	s_addc_u32 s53, s63, s40
	s_add_u32 s54, s62, s37
	s_addc_u32 s55, s63, s38
	s_cmp_eq_u32 s41, 28
	s_cselect_b32 s73, s5, s53
	s_cselect_b32 s72, s4, s52
	s_cselect_b32 s71, s1, s55
	s_cselect_b32 s70, s0, s54
	s_mov_b32 m0, s42
	v_lshl_add_u64 v[210:211], s[62:63], 0, v[138:139]
	ds_read_b128 v[178:181], v142
	ds_read_b128 v[182:185], v142 offset:1024
	ds_read_b128 v[186:189], v142 offset:2048
	ds_read_b128 v[190:193], v142 offset:3072
	ds_read_b128 v[194:197], v142 offset:4096
	ds_read_b128 v[198:201], v142 offset:5120
	ds_read_b128 v[202:205], v142 offset:6144
	ds_read_b128 v[206:209], v142 offset:7168
	global_load_lds_dwordx4 v[210:211], off
	v_lshl_add_u64 v[210:211], s[62:63], 0, v[136:137]
	s_mov_b32 m0, s43
	s_nop 0
	global_load_lds_dwordx4 v[210:211], off
	s_waitcnt vmcnt(8) lgkmcnt(0)
	s_setprio 1
	s_barrier
	v_mfma_f32_16x16x32_bf16 v[8:11], v[146:149], v[178:181], v[8:11]
	v_mfma_f32_16x16x32_bf16 v[12:15], v[154:157], v[178:181], v[12:15]
	v_mfma_f32_16x16x32_bf16 v[36:39], v[146:149], v[186:189], v[36:39]
	v_mfma_f32_16x16x32_bf16 v[32:35], v[154:157], v[186:189], v[32:35]
	v_mfma_f32_16x16x32_bf16 v[60:63], v[146:149], v[194:197], v[60:63]
	v_mfma_f32_16x16x32_bf16 v[56:59], v[154:157], v[194:197], v[56:59]
	v_mfma_f32_16x16x32_bf16 v[80:83], v[146:149], v[202:205], v[80:83]
	v_mfma_f32_16x16x32_bf16 v[72:75], v[154:157], v[202:205], v[72:75]
	v_mfma_f32_16x16x32_bf16 v[8:11], v[150:153], v[182:185], v[8:11]
	v_mfma_f32_16x16x32_bf16 v[12:15], v[158:161], v[182:185], v[12:15]
	v_mfma_f32_16x16x32_bf16 v[36:39], v[150:153], v[190:193], v[36:39]
	v_mfma_f32_16x16x32_bf16 v[32:35], v[158:161], v[190:193], v[32:35]
	v_mfma_f32_16x16x32_bf16 v[60:63], v[150:153], v[198:201], v[60:63]
	v_mfma_f32_16x16x32_bf16 v[56:59], v[158:161], v[198:201], v[56:59]
	v_mfma_f32_16x16x32_bf16 v[80:83], v[150:153], v[206:209], v[80:83]
	v_mfma_f32_16x16x32_bf16 v[72:75], v[158:161], v[206:209], v[72:75]
	s_setprio 0
	s_setprio 1
	v_mfma_f32_16x16x32_bf16 v[44:47], v[162:165], v[178:181], v[44:47]
	v_mfma_f32_16x16x32_bf16 v[40:43], v[170:173], v[178:181], v[40:43]
	v_mfma_f32_16x16x32_bf16 v[52:55], v[162:165], v[186:189], v[52:55]
	v_mfma_f32_16x16x32_bf16 v[48:51], v[170:173], v[186:189], v[48:51]
	v_mfma_f32_16x16x32_bf16 v[68:71], v[162:165], v[194:197], v[68:71]
	v_mfma_f32_16x16x32_bf16 v[64:67], v[170:173], v[194:197], v[64:67]
	v_mfma_f32_16x16x32_bf16 v[100:103], v[162:165], v[202:205], v[100:103]
	v_mfma_f32_16x16x32_bf16 v[96:99], v[170:173], v[202:205], v[96:99]
	v_mfma_f32_16x16x32_bf16 v[44:47], v[166:169], v[182:185], v[44:47]
	v_mfma_f32_16x16x32_bf16 v[40:43], v[174:177], v[182:185], v[40:43]
	v_mfma_f32_16x16x32_bf16 v[52:55], v[166:169], v[190:193], v[52:55]
	v_mfma_f32_16x16x32_bf16 v[48:51], v[174:177], v[190:193], v[48:51]
	v_mfma_f32_16x16x32_bf16 v[68:71], v[166:169], v[198:201], v[68:71]
	v_mfma_f32_16x16x32_bf16 v[64:67], v[174:177], v[198:201], v[64:67]
	v_mfma_f32_16x16x32_bf16 v[100:103], v[166:169], v[206:209], v[100:103]
	v_mfma_f32_16x16x32_bf16 v[96:99], v[174:177], v[206:209], v[96:99]
	s_barrier
	s_setprio 0
	s_mov_b32 m0, s44
	v_lshl_add_u64 v[210:211], s[70:71], 0, v[130:131]
	s_add_u32 s52, s70, 0x80000
	ds_read_b128 v[178:181], v142 offset:16384
	ds_read_b128 v[182:185], v142 offset:17408
	ds_read_b128 v[186:189], v142 offset:18432
	ds_read_b128 v[190:193], v142 offset:19456
	ds_read_b128 v[194:197], v142 offset:20480
	ds_read_b128 v[198:201], v142 offset:21504
	ds_read_b128 v[202:205], v142 offset:22528
	ds_read_b128 v[206:209], v142 offset:23552
	global_load_lds_dwordx4 v130, s[70:71]
	v_lshl_add_u64 v[212:213], s[70:71], 0, v[134:135]
	s_mov_b32 m0, s45
	s_addc_u32 s53, s71, 0
	global_load_lds_dwordx4 v134, s[70:71]
	v_lshl_add_u64 v[214:215], s[52:53], 0, v[130:131]
	s_mov_b32 m0, s46
	v_lshl_add_u64 v[216:217], s[72:73], 0, v[132:133]
	global_load_lds_dwordx4 v130, s[52:53]
	v_lshl_add_u64 v[214:215], s[52:53], 0, v[134:135]
	s_mov_b32 m0, s47
	s_nop 0
	global_load_lds_dwordx4 v134, s[52:53]
	v_lshl_add_u64 v[214:215], s[72:73], 0, v[128:129]
	s_mov_b32 m0, s14
	s_nop 0
	global_load_lds_dwordx4 v128, s[72:73]
	s_mov_b32 m0, s15
	s_nop 0
	global_load_lds_dwordx4 v132, s[72:73]
	s_waitcnt vmcnt(8) lgkmcnt(0)
	s_setprio 1
	s_barrier
	v_mfma_f32_16x16x32_bf16 v[108:111], v[146:149], v[178:181], v[108:111]
	v_mfma_f32_16x16x32_bf16 v[104:107], v[154:157], v[178:181], v[104:107]
	v_mfma_f32_16x16x32_bf16 v[124:127], v[146:149], v[186:189], v[124:127]
	v_mfma_f32_16x16x32_bf16 v[120:123], v[154:157], v[186:189], v[120:123]
	v_mfma_f32_16x16x32_bf16 v[84:87], v[146:149], v[194:197], v[84:87]
	v_mfma_f32_16x16x32_bf16 v[76:79], v[154:157], v[194:197], v[76:79]
	v_mfma_f32_16x16x32_bf16 v[20:23], v[146:149], v[202:205], v[20:23]
	v_mfma_f32_16x16x32_bf16 v[16:19], v[154:157], v[202:205], v[16:19]
	v_mfma_f32_16x16x32_bf16 v[108:111], v[150:153], v[182:185], v[108:111]
	v_mfma_f32_16x16x32_bf16 v[104:107], v[158:161], v[182:185], v[104:107]
	v_mfma_f32_16x16x32_bf16 v[124:127], v[150:153], v[190:193], v[124:127]
	v_mfma_f32_16x16x32_bf16 v[120:123], v[158:161], v[190:193], v[120:123]
	v_mfma_f32_16x16x32_bf16 v[84:87], v[150:153], v[198:201], v[84:87]
	v_mfma_f32_16x16x32_bf16 v[76:79], v[158:161], v[198:201], v[76:79]
	v_mfma_f32_16x16x32_bf16 v[20:23], v[150:153], v[206:209], v[20:23]
	v_mfma_f32_16x16x32_bf16 v[16:19], v[158:161], v[206:209], v[16:19]
	s_setprio 0
	s_setprio 1
	v_mfma_f32_16x16x32_bf16 v[116:119], v[162:165], v[178:181], v[116:119]
	v_mfma_f32_16x16x32_bf16 v[112:115], v[170:173], v[178:181], v[112:115]
	v_mfma_f32_16x16x32_bf16 v[92:95], v[162:165], v[186:189], v[92:95]
	v_mfma_f32_16x16x32_bf16 v[88:91], v[170:173], v[186:189], v[88:91]
	v_mfma_f32_16x16x32_bf16 v[28:31], v[162:165], v[194:197], v[28:31]
	v_mfma_f32_16x16x32_bf16 v[24:27], v[170:173], v[194:197], v[24:27]
	v_mfma_f32_16x16x32_bf16 v[4:7], v[162:165], v[202:205], v[4:7]
	v_mfma_f32_16x16x32_bf16 v[0:3], v[170:173], v[202:205], v[0:3]
	v_mfma_f32_16x16x32_bf16 v[116:119], v[166:169], v[182:185], v[116:119]
	v_mfma_f32_16x16x32_bf16 v[112:115], v[174:177], v[182:185], v[112:115]
	v_mfma_f32_16x16x32_bf16 v[92:95], v[166:169], v[190:193], v[92:95]
	v_mfma_f32_16x16x32_bf16 v[88:91], v[174:177], v[190:193], v[88:91]
	v_mfma_f32_16x16x32_bf16 v[28:31], v[166:169], v[198:201], v[28:31]
	v_mfma_f32_16x16x32_bf16 v[24:27], v[174:177], v[198:201], v[24:27]
	v_mfma_f32_16x16x32_bf16 v[4:7], v[166:169], v[206:209], v[4:7]
	v_mfma_f32_16x16x32_bf16 v[0:3], v[174:177], v[206:209], v[0:3]
	s_barrier
	s_setprio 0
	ds_read_b128 v[146:149], v143
	ds_read_b128 v[150:153], v143 offset:1024
	ds_read_b128 v[154:157], v143 offset:2048
	ds_read_b128 v[158:161], v143 offset:3072
	ds_read_b128 v[162:165], v144
	ds_read_b128 v[166:169], v144 offset:1024
	ds_read_b128 v[170:173], v144 offset:2048
	ds_read_b128 v[174:177], v144 offset:3072
	s_add_u32 s52, s72, 0x80000
	s_addc_u32 s53, s73, 0
	s_mov_b32 m0, s21
	v_lshl_add_u64 v[218:219], s[52:53], 0, v[128:129]
	ds_read_b128 v[178:181], v142 offset:32768
	ds_read_b128 v[182:185], v142 offset:33792
	ds_read_b128 v[186:189], v142 offset:34816
	ds_read_b128 v[190:193], v142 offset:35840
	ds_read_b128 v[194:197], v142 offset:36864
	ds_read_b128 v[198:201], v142 offset:37888
	ds_read_b128 v[202:205], v142 offset:38912
	ds_read_b128 v[206:209], v142 offset:39936
	global_load_lds_dwordx4 v128, s[52:53]
	v_lshl_add_u64 v[218:219], s[52:53], 0, v[132:133]
	s_mov_b32 m0, s22
	s_nop 0
	global_load_lds_dwordx4 v132, s[52:53]
	s_waitcnt vmcnt(8) lgkmcnt(0)
	s_setprio 1
	s_barrier
	v_mfma_f32_16x16x32_bf16 v[8:11], v[146:149], v[178:181], v[8:11]
	v_mfma_f32_16x16x32_bf16 v[12:15], v[154:157], v[178:181], v[12:15]
	v_mfma_f32_16x16x32_bf16 v[36:39], v[146:149], v[186:189], v[36:39]
	v_mfma_f32_16x16x32_bf16 v[32:35], v[154:157], v[186:189], v[32:35]
	v_mfma_f32_16x16x32_bf16 v[60:63], v[146:149], v[194:197], v[60:63]
	v_mfma_f32_16x16x32_bf16 v[56:59], v[154:157], v[194:197], v[56:59]
	v_mfma_f32_16x16x32_bf16 v[80:83], v[146:149], v[202:205], v[80:83]
	v_mfma_f32_16x16x32_bf16 v[72:75], v[154:157], v[202:205], v[72:75]
	v_mfma_f32_16x16x32_bf16 v[8:11], v[150:153], v[182:185], v[8:11]
	v_mfma_f32_16x16x32_bf16 v[12:15], v[158:161], v[182:185], v[12:15]
	v_mfma_f32_16x16x32_bf16 v[36:39], v[150:153], v[190:193], v[36:39]
	v_mfma_f32_16x16x32_bf16 v[32:35], v[158:161], v[190:193], v[32:35]
	v_mfma_f32_16x16x32_bf16 v[60:63], v[150:153], v[198:201], v[60:63]
	v_mfma_f32_16x16x32_bf16 v[56:59], v[158:161], v[198:201], v[56:59]
	v_mfma_f32_16x16x32_bf16 v[80:83], v[150:153], v[206:209], v[80:83]
	v_mfma_f32_16x16x32_bf16 v[72:75], v[158:161], v[206:209], v[72:75]
	s_setprio 0
	s_setprio 1
	v_mfma_f32_16x16x32_bf16 v[44:47], v[162:165], v[178:181], v[44:47]
	v_mfma_f32_16x16x32_bf16 v[40:43], v[170:173], v[178:181], v[40:43]
	v_mfma_f32_16x16x32_bf16 v[52:55], v[162:165], v[186:189], v[52:55]
	v_mfma_f32_16x16x32_bf16 v[48:51], v[170:173], v[186:189], v[48:51]
	v_mfma_f32_16x16x32_bf16 v[68:71], v[162:165], v[194:197], v[68:71]
	v_mfma_f32_16x16x32_bf16 v[64:67], v[170:173], v[194:197], v[64:67]
	v_mfma_f32_16x16x32_bf16 v[100:103], v[162:165], v[202:205], v[100:103]
	v_mfma_f32_16x16x32_bf16 v[96:99], v[170:173], v[202:205], v[96:99]
	v_mfma_f32_16x16x32_bf16 v[44:47], v[166:169], v[182:185], v[44:47]
	v_mfma_f32_16x16x32_bf16 v[40:43], v[174:177], v[182:185], v[40:43]
	v_mfma_f32_16x16x32_bf16 v[52:55], v[166:169], v[190:193], v[52:55]
	v_mfma_f32_16x16x32_bf16 v[48:51], v[174:177], v[190:193], v[48:51]
	v_mfma_f32_16x16x32_bf16 v[68:71], v[166:169], v[198:201], v[68:71]
	v_mfma_f32_16x16x32_bf16 v[64:67], v[174:177], v[198:201], v[64:67]
	v_mfma_f32_16x16x32_bf16 v[100:103], v[166:169], v[206:209], v[100:103]
	v_mfma_f32_16x16x32_bf16 v[96:99], v[174:177], v[206:209], v[96:99]
	s_barrier
; #define PG8_WAIT_V(n) asm volatile("s_waitcnt vmcnt(" #n ")" ::: "memory")
; #define PG8_BAR __builtin_amdgcn_s_barrier()
; template <class Epi, class Sched, bool ALIGN_EPI = false, bool SP2 = false, bool A_TILED = false>
; __device__ __forceinline__ void gemm_phase(PG8_LAS unsigned char* lds, const Gemm g, const Sched& S, const Epi& E, const int wave_s) {
;     ...
;     PG8_WAIT_V(0);
;     if constexpr (!ALIGN_EPI) { if (wr == 0) PG8_BAR; }
;     PG8_BAR;
	s_setprio 0
	s_mov_b32 m0, s48
	v_lshl_add_u64 v[210:211], v[210:211], 0, s[66:67]
	s_add_u32 s52, s70, 0x80080
	ds_read_b128 v[178:181], v142 offset:49152
	ds_read_b128 v[182:185], v142 offset:50176
	ds_read_b128 v[186:189], v142 offset:51200
	ds_read_b128 v[190:193], v142 offset:52224
	ds_read_b128 v[194:197], v142 offset:53248
	ds_read_b128 v[198:201], v142 offset:54272
	ds_read_b128 v[202:205], v142 offset:55296
	ds_read_b128 v[206:209], v142 offset:56320
	global_load_lds_dwordx4 v[210:211], off
	v_lshl_add_u64 v[210:211], v[212:213], 0, s[66:67]
	s_mov_b32 m0, s49
	s_addc_u32 s53, s71, 0
	global_load_lds_dwordx4 v[210:211], off
	v_lshl_add_u64 v[210:211], s[52:53], 0, v[130:131]
	s_mov_b32 m0, s50
	s_nop 0
	global_load_lds_dwordx4 v130, s[52:53]
	v_lshl_add_u64 v[210:211], s[52:53], 0, v[134:135]
	s_mov_b32 m0, s51
	s_nop 0
	global_load_lds_dwordx4 v134, s[52:53]
	v_lshl_add_u64 v[210:211], v[214:215], 0, s[66:67]
	s_mov_b32 m0, s23
	s_nop 0
	global_load_lds_dwordx4 v[210:211], off
	v_lshl_add_u64 v[210:211], v[216:217], 0, s[66:67]
	s_mov_b32 m0, s36
	s_nop 0
	global_load_lds_dwordx4 v[210:211], off
	s_waitcnt vmcnt(8) lgkmcnt(0)
	s_setprio 1
	s_barrier
	v_mfma_f32_16x16x32_bf16 v[108:111], v[146:149], v[178:181], v[108:111]
	v_mfma_f32_16x16x32_bf16 v[104:107], v[154:157], v[178:181], v[104:107]
	v_mfma_f32_16x16x32_bf16 v[124:127], v[146:149], v[186:189], v[124:127]
	v_mfma_f32_16x16x32_bf16 v[120:123], v[154:157], v[186:189], v[120:123]
	v_mfma_f32_16x16x32_bf16 v[84:87], v[146:149], v[194:197], v[84:87]
	v_mfma_f32_16x16x32_bf16 v[76:79], v[154:157], v[194:197], v[76:79]
	v_mfma_f32_16x16x32_bf16 v[20:23], v[146:149], v[202:205], v[20:23]
	v_mfma_f32_16x16x32_bf16 v[16:19], v[154:157], v[202:205], v[16:19]
	v_mfma_f32_16x16x32_bf16 v[108:111], v[150:153], v[182:185], v[108:111]
	v_mfma_f32_16x16x32_bf16 v[104:107], v[158:161], v[182:185], v[104:107]
	v_mfma_f32_16x16x32_bf16 v[124:127], v[150:153], v[190:193], v[124:127]
	v_mfma_f32_16x16x32_bf16 v[120:123], v[158:161], v[190:193], v[120:123]
	v_mfma_f32_16x16x32_bf16 v[84:87], v[150:153], v[198:201], v[84:87]
	v_mfma_f32_16x16x32_bf16 v[76:79], v[158:161], v[198:201], v[76:79]
	v_mfma_f32_16x16x32_bf16 v[20:23], v[150:153], v[206:209], v[20:23]
	v_mfma_f32_16x16x32_bf16 v[16:19], v[158:161], v[206:209], v[16:19]
	s_setprio 0
	s_setprio 1
	v_mfma_f32_16x16x32_bf16 v[116:119], v[162:165], v[178:181], v[116:119]
	v_mfma_f32_16x16x32_bf16 v[112:115], v[170:173], v[178:181], v[112:115]
	v_mfma_f32_16x16x32_bf16 v[92:95], v[162:165], v[186:189], v[92:95]
	v_mfma_f32_16x16x32_bf16 v[88:91], v[170:173], v[186:189], v[88:91]
	v_mfma_f32_16x16x32_bf16 v[28:31], v[162:165], v[194:197], v[28:31]
	v_mfma_f32_16x16x32_bf16 v[24:27], v[170:173], v[194:197], v[24:27]
	v_mfma_f32_16x16x32_bf16 v[4:7], v[162:165], v[202:205], v[4:7]
	v_mfma_f32_16x16x32_bf16 v[0:3], v[170:173], v[202:205], v[0:3]
	v_mfma_f32_16x16x32_bf16 v[116:119], v[166:169], v[182:185], v[116:119]
	v_mfma_f32_16x16x32_bf16 v[112:115], v[174:177], v[182:185], v[112:115]
	v_mfma_f32_16x16x32_bf16 v[92:95], v[166:169], v[190:193], v[92:95]
	v_mfma_f32_16x16x32_bf16 v[88:91], v[174:177], v[190:193], v[88:91]
	v_mfma_f32_16x16x32_bf16 v[28:31], v[166:169], v[198:201], v[28:31]
	v_mfma_f32_16x16x32_bf16 v[24:27], v[174:177], v[198:201], v[24:27]
	v_mfma_f32_16x16x32_bf16 v[4:7], v[166:169], v[206:209], v[4:7]
	v_mfma_f32_16x16x32_bf16 v[0:3], v[174:177], v[206:209], v[0:3]
	s_barrier
	s_setprio 0
	s_add_i32 s41, s41, 2
	s_add_u32 s37, s37, 0x100
	s_addc_u32 s38, s38, 0
	s_add_u32 s39, s39, 0x100
	s_addc_u32 s40, s40, 0
	v_lshl_add_u64 v[136:137], v[136:137], 0, s[68:69]
	s_cmp_gt_u32 s41, 29
	v_lshl_add_u64 v[138:139], v[138:139], 0, s[68:69]
	s_cbranch_scc0 .LBB0_1043
	s_waitcnt vmcnt(0)
	s_cmpk_lt_u32 s6, 0x100
	s_cbranch_scc0 .LBB0_1046
	s_barrier

; #define PG8_STAGE(bufoff, gbase, voff) do { _Pragma("unroll") for (int _i = 0; _i < 2; ++_i) \
;         __builtin_amdgcn_global_load_lds((const unsigned*)((const char*)(gbase) + (voff)[_i]), (PG8_LAS unsigned*)(lds + (bufoff) + ldsw + _i * 8192), 16, 0, 0); } while (0)
; #define PG8_WAIT_V(n) asm volatile("s_waitcnt vmcnt(" #n ")" ::: "memory")
; #define PG8_BAR __builtin_amdgcn_s_barrier()
; template <class Epi, class Sched, bool ALIGN_EPI = false, bool SP2 = false, bool A_TILED = false>
; __device__ __forceinline__ void gemm_phase(PG8_LAS unsigned char* lds, const Gemm g, const Sched& S, const Epi& E, const int wave_s) {
;     ...
;     if constexpr (SP2) {
;         PG8_STAGE(PG8_SB(0, 0), cB, voffB); PG8_STAGE(PG8_SB(0, 1), cB + hstep, voffB); PG8_STAGE(PG8_SA(0, 0), cA, voffA); PG8_STAGE(PG8_SA(0, 1), cA + hstepA, voffA);
;         if (wr == 1) PG8_BAR;
;         PG8_WAIT_V(2); PG8_BAR;
;         PG8_STAGE(PG8_SB(1, 0), cB + kstep, voffB); PG8_STAGE(PG8_SA(1, 0), cA + kstepA, voffA); PG8_STAGE(PG8_SB(1, 1), cB + hstep + kstep, voffB);
;         PG8_WAIT_V(6); PG8_BAR;
;     } else {
;         PG8_STAGE(PG8_SB(0, 0), cB, voffB); PG8_STAGE(PG8_SA(0, 0), cA, voffA); PG8_STAGE(PG8_SB(0, 1), cB + hstep, voffB); PG8_STAGE(PG8_SA(0, 1), cA + hstepA, voffA);
;         if (wr == 1) PG8_BAR;
;         PG8_WAIT_V(4); PG8_BAR;
;         PG8_STAGE(PG8_SB(1, 0), cB + kstep, voffB); PG8_STAGE(PG8_SA(1, 0), cA + kstepA, voffA); PG8_STAGE(PG8_SB(1, 1), cB + hstep + kstep, voffB);
;         PG8_WAIT_V(6); PG8_BAR;
;     }
.LBB0_1145:
	s_ashr_i32 s40, s86, 31
	s_add_u32 s41, s0, 0x34600000
	s_addc_u32 s42, s1, 0
	s_lshl_b32 s47, s12, 13
	s_mov_b64 s[12:13], 0x80
	s_and_b32 s0, s46, 3
	s_add_i32 m0, s22, 0x18000
	v_lshl_add_u64 v[6:7], v[6:7], 0, s[12:13]
	s_lshl_b32 s48, s0, 12
	s_waitcnt vmcnt(2)
	s_barrier
	global_load_lds_dwordx4 v[6:7], off
	v_lshl_add_u64 v[4:5], v[4:5], 0, s[12:13]
	s_add_i32 m0, s22, 0x1a000
	s_add_i32 s43, s22, 0x8000
	s_add_i32 s44, s22, 0xa000
	global_load_lds_dwordx4 v[4:5], off
	v_lshl_add_u64 v[0:1], v[0:1], 0, s[12:13]
	s_mov_b32 m0, s43
	s_add_u32 s0, s76, 0x80080
	global_load_lds_dwordx4 v[0:1], off
	v_lshl_add_u64 v[0:1], v[2:3], 0, s[12:13]
	s_mov_b32 m0, s44
	s_addc_u32 s1, s77, 0
	global_load_lds_dwordx4 v[0:1], off
	s_add_i32 m0, s22, 0x1c000
	v_lshl_add_u64 v[0:1], s[0:1], 0, v[128:129]
	global_load_lds_dwordx4 v128, s[0:1]
	v_lshl_add_u64 v[0:1], s[0:1], 0, v[130:131]
	s_add_i32 m0, s22, 0x1e000
	s_cmpk_lt_u32 s45, 0x100
	global_load_lds_dwordx4 v130, s[0:1]
	v_and_b32_e32 v0, 15, v8
	v_and_b32_e32 v1, 48, v8
	v_lshl_or_b32 v0, v0, 6, v1
	v_lshlrev_b32_e32 v1, 2, v8
	v_and_b32_e32 v1, 32, v1
	v_bitop3_b32 v2, v0, s47, v1 bitop3:0xde
	v_bitop3_b32 v144, v0, s48, v1 bitop3:0xde
	v_lshlrev_b32_e32 v0, 15, v9
	v_and_b32_e32 v0, 0xffff0000, v0
	v_lshl_add_u32 v0, v10, 12, v0
	v_and_b32_e32 v1, 1, v9
	v_lshl_or_b32 v0, v1, 6, v0
	v_lshl_add_u32 v136, v11, 1, v0
	v_lshlrev_b32_e32 v0, 15, v13
	v_and_b32_e32 v0, 0xffff0000, v0
	s_sext_i32_i16 s49, s60
	s_waitcnt vmcnt(6)
	s_cselect_b64 s[60:61], -1, 0
	s_and_b32 s0, s15, 0x400
	v_lshl_add_u32 v0, v12, 12, v0
	v_and_b32_e32 v1, 1, v13
	s_bfe_u32 s45, s46, 0x10001
	s_or_b32 s46, s0, s47
	v_mov_b32_e32 v137, 0
	v_lshl_or_b32 v0, v1, 6, v0
	s_add_i32 s47, 0, 0x10000
	s_add_i32 s48, 0, 0x14000
	v_lshl_add_u32 v138, v14, 1, v0
	v_mov_b32_e32 v139, v137
	v_mov_b64_e32 v[140:141], 0x200
	v_mov_b64_e32 v[142:143], 0x1ff
	v_add_u32_e32 v145, s47, v144
	v_add_u32_e32 v146, s48, v144
	v_add_u32_e32 v147, 0, v2
	s_mov_b64 s[62:63], 0x100
	s_mov_b64 s[64:65], 0x180
	s_barrier
	s_branch .LBB0_1148

; template <class Epi, class Sched, bool ALIGN_EPI = false, bool SP2 = false, bool A_TILED = false>
; __device__ __forceinline__ void gemm_phase(PG8_LAS unsigned char* lds, const Gemm g, const Sched& S, const Epi& E, const int wave_s) {
;     ...
;     for (;;) {
;         const bool has_next = Epi::AFTER_DRAIN ? false : S.next(ui + 1, nxt);
;         const char* nA = has_next ? (const char*)g.A + (size_t)nxt.pm * tstepA : cA; const char* nB = has_next ? (const char*)g.Bt + (size_t)nxt.pn * tstep : cB;
;         constexpr bool PEEL = SP2 && !Epi::AFTER_DRAIN;
;         if constexpr (PEEL) {
;             const char* a1 = cA + kstepA; const char* a2 = cA + 2 * kstepA; const char* b2 = cB + 2 * kstep; const char* a3 = a2 + kstepA; const char* b3 = b2 + kstep;
;             PG8_ITER(PG8_MMAZ)
.LBB0_1154:
	s_ashr_i32 s69, s68, 31
	s_lshl_b64 s[50:51], s[68:69], 20
	s_add_u32 s70, s7, s50
	ds_read_b128 v[0:3], v145
	ds_read_b128 v[4:7], v145 offset:1024
	ds_read_b128 v[8:11], v145 offset:2048
	ds_read_b128 v[12:15], v145 offset:3072
	ds_read_b128 v[16:19], v146
	ds_read_b128 v[20:23], v146 offset:1024
	ds_read_b128 v[24:27], v146 offset:2048
	ds_read_b128 v[28:31], v146 offset:3072
	s_addc_u32 s71, s8, s51
	s_ashr_i32 s67, s66, 31
	s_lshl_b64 s[50:51], s[66:67], 20
	s_add_u32 s72, s9, s50
	s_addc_u32 s73, s14, s51
	s_and_b64 s[50:51], s[0:1], exec
	s_cselect_b32 s50, s71, s79
	s_cselect_b32 s51, s70, s78
	s_cselect_b32 s52, s73, s77
	s_cselect_b32 s53, s72, s76
	s_add_u32 s56, s78, 0x80080
	s_addc_u32 s57, s79, 0
	s_add_i32 s54, s22, 0xc000
	v_lshl_add_u64 v[64:65], s[56:57], 0, v[134:135]
	s_mov_b32 m0, s54
	s_add_i32 s55, s22, 0xe000
	ds_read_b128 v[32:35], v147
	ds_read_b128 v[36:39], v147 offset:1024
	ds_read_b128 v[40:43], v147 offset:2048
	ds_read_b128 v[44:47], v147 offset:3072
	ds_read_b128 v[48:51], v147 offset:4096
	ds_read_b128 v[52:55], v147 offset:5120
	ds_read_b128 v[56:59], v147 offset:6144
	ds_read_b128 v[60:63], v147 offset:7168
	global_load_lds_dwordx4 v134, s[56:57]
	v_lshl_add_u64 v[64:65], s[56:57], 0, v[132:133]
	s_mov_b32 m0, s55
	s_nop 0
	global_load_lds_dwordx4 v132, s[56:57]
	s_waitcnt vmcnt(8) lgkmcnt(0)
	s_setprio 1
	s_barrier
	v_mfma_f32_16x16x32_bf16 v[88:91], v[0:3], v[56:59], 0
	v_mfma_f32_16x16x32_bf16 v[64:67], v[0:3], v[32:35], 0
	v_mfma_f32_16x16x32_bf16 v[68:71], v[8:11], v[32:35], 0
	v_mfma_f32_16x16x32_bf16 v[72:75], v[0:3], v[40:43], 0
	v_mfma_f32_16x16x32_bf16 v[76:79], v[8:11], v[40:43], 0
	v_mfma_f32_16x16x32_bf16 v[80:83], v[0:3], v[48:51], 0
	v_mfma_f32_16x16x32_bf16 v[84:87], v[8:11], v[48:51], 0
	v_mfma_f32_16x16x32_bf16 v[96:99], v[4:7], v[60:63], v[88:91]
	v_mfma_f32_16x16x32_bf16 v[88:91], v[8:11], v[56:59], 0
	v_mfma_f32_16x16x32_bf16 v[64:67], v[4:7], v[36:39], v[64:67]
	v_mfma_f32_16x16x32_bf16 v[68:71], v[12:15], v[36:39], v[68:71]
	v_mfma_f32_16x16x32_bf16 v[72:75], v[4:7], v[44:47], v[72:75]
	v_mfma_f32_16x16x32_bf16 v[76:79], v[12:15], v[44:47], v[76:79]
	v_mfma_f32_16x16x32_bf16 v[80:83], v[4:7], v[52:55], v[80:83]
	v_mfma_f32_16x16x32_bf16 v[84:87], v[12:15], v[52:55], v[84:87]
	v_mfma_f32_16x16x32_bf16 v[100:103], v[12:15], v[60:63], v[88:91]
	s_setprio 0
	s_setprio 1
	v_mfma_f32_16x16x32_bf16 v[88:91], v[16:19], v[32:35], 0
	v_mfma_f32_16x16x32_bf16 v[32:35], v[24:27], v[32:35], 0
	v_mfma_f32_16x16x32_bf16 v[112:115], v[20:23], v[36:39], v[88:91]
	v_mfma_f32_16x16x32_bf16 v[32:35], v[28:31], v[36:39], v[32:35]
	v_mfma_f32_16x16x32_bf16 v[36:39], v[16:19], v[40:43], 0
	v_mfma_f32_16x16x32_bf16 v[40:43], v[24:27], v[40:43], 0
	v_mfma_f32_16x16x32_bf16 v[36:39], v[20:23], v[44:47], v[36:39]
	v_mfma_f32_16x16x32_bf16 v[40:43], v[28:31], v[44:47], v[40:43]
	v_mfma_f32_16x16x32_bf16 v[44:47], v[16:19], v[48:51], 0
	v_mfma_f32_16x16x32_bf16 v[48:51], v[24:27], v[48:51], 0
	v_mfma_f32_16x16x32_bf16 v[44:47], v[20:23], v[52:55], v[44:47]
	v_mfma_f32_16x16x32_bf16 v[48:51], v[28:31], v[52:55], v[48:51]
	v_mfma_f32_16x16x32_bf16 v[52:55], v[16:19], v[56:59], 0
	v_mfma_f32_16x16x32_bf16 v[56:59], v[24:27], v[56:59], 0
	v_mfma_f32_16x16x32_bf16 v[52:55], v[20:23], v[60:63], v[52:55]
	v_mfma_f32_16x16x32_bf16 v[56:59], v[28:31], v[60:63], v[56:59]
	s_barrier
	s_setprio 0
	s_add_i32 s56, s47, s15
	v_lshl_add_u64 v[242:243], s[76:77], 0, v[128:129]
	s_add_i32 s57, s56, 0x2000
	v_lshl_add_u64 v[148:149], v[242:243], 0, s[62:63]
	s_mov_b32 m0, s56
	v_lshl_add_u64 v[244:245], s[76:77], 0, v[130:131]
	s_add_u32 s80, s76, 0x80100
	ds_read_b128 v[60:63], v147 offset:16384
	ds_read_b128 v[88:91], v147 offset:17408
	ds_read_b128 v[92:95], v147 offset:18432
	ds_read_b128 v[104:107], v147 offset:19456
	ds_read_b128 v[108:111], v147 offset:20480
	ds_read_b128 v[116:119], v147 offset:21504
	ds_read_b128 v[120:123], v147 offset:22528
	ds_read_b128 v[124:127], v147 offset:23552
	global_load_lds_dwordx4 v[148:149], off
	v_lshl_add_u64 v[148:149], v[244:245], 0, s[62:63]
	s_mov_b32 m0, s57
	s_addc_u32 s81, s77, 0
	s_add_i32 s58, s48, s15
	global_load_lds_dwordx4 v[148:149], off
	v_lshl_add_u64 v[148:149], s[80:81], 0, v[128:129]
	s_mov_b32 m0, s58
	s_add_i32 s59, s58, 0x2000
	global_load_lds_dwordx4 v128, s[80:81]
	v_lshl_add_u64 v[148:149], s[80:81], 0, v[130:131]
	s_mov_b32 m0, s59
	v_lshl_add_u64 v[246:247], s[78:79], 0, v[134:135]
	global_load_lds_dwordx4 v130, s[80:81]
	v_lshl_add_u64 v[148:149], v[246:247], 0, s[62:63]
	s_mov_b32 m0, s22
	v_lshl_add_u64 v[248:249], s[78:79], 0, v[132:133]
	global_load_lds_dwordx4 v[148:149], off
	v_lshl_add_u64 v[148:149], v[248:249], 0, s[62:63]
	s_mov_b32 m0, s23
	s_nop 0
	global_load_lds_dwordx4 v[148:149], off
	s_waitcnt vmcnt(8) lgkmcnt(0)
	s_setprio 1
	s_barrier
	v_mfma_f32_16x16x32_bf16 v[148:151], v[0:3], v[60:63], 0
	v_mfma_f32_16x16x32_bf16 v[158:161], v[0:3], v[92:95], 0
	v_mfma_f32_16x16x32_bf16 v[166:169], v[0:3], v[108:111], 0
	v_mfma_f32_16x16x32_bf16 v[0:3], v[0:3], v[120:123], 0
	v_mfma_f32_16x16x32_bf16 v[150:153], v[4:7], v[88:91], v[148:151]
	v_mfma_f32_16x16x32_bf16 v[158:161], v[4:7], v[104:107], v[158:161]
	v_mfma_f32_16x16x32_bf16 v[166:169], v[4:7], v[116:119], v[166:169]
	v_mfma_f32_16x16x32_bf16 v[0:3], v[4:7], v[124:127], v[0:3]
	v_mfma_f32_16x16x32_bf16 v[4:7], v[8:11], v[120:123], 0
	v_mfma_f32_16x16x32_bf16 v[154:157], v[8:11], v[60:63], 0
	v_mfma_f32_16x16x32_bf16 v[162:165], v[8:11], v[92:95], 0
	v_mfma_f32_16x16x32_bf16 v[170:173], v[8:11], v[108:111], 0
	v_mfma_f32_16x16x32_bf16 v[4:7], v[12:15], v[124:127], v[4:7]
	v_mfma_f32_16x16x32_bf16 v[154:157], v[12:15], v[88:91], v[154:157]
	v_mfma_f32_16x16x32_bf16 v[162:165], v[12:15], v[104:107], v[162:165]
	v_mfma_f32_16x16x32_bf16 v[170:173], v[12:15], v[116:119], v[170:173]
	s_setprio 0
	s_setprio 1
	v_mfma_f32_16x16x32_bf16 v[8:11], v[16:19], v[60:63], 0
	v_mfma_f32_16x16x32_bf16 v[174:177], v[20:23], v[88:91], v[8:11]
	v_mfma_f32_16x16x32_bf16 v[8:11], v[24:27], v[60:63], 0
	v_mfma_f32_16x16x32_bf16 v[60:63], v[28:31], v[88:91], v[8:11]
	v_mfma_f32_16x16x32_bf16 v[8:11], v[16:19], v[92:95], 0
	v_mfma_f32_16x16x32_bf16 v[178:181], v[20:23], v[104:107], v[8:11]
	v_mfma_f32_16x16x32_bf16 v[8:11], v[24:27], v[92:95], 0
	v_mfma_f32_16x16x32_bf16 v[182:185], v[28:31], v[104:107], v[8:11]
	v_mfma_f32_16x16x32_bf16 v[8:11], v[16:19], v[108:111], 0
	v_mfma_f32_16x16x32_bf16 v[186:189], v[20:23], v[116:119], v[8:11]
	v_mfma_f32_16x16x32_bf16 v[8:11], v[24:27], v[108:111], 0
	v_mfma_f32_16x16x32_bf16 v[190:193], v[28:31], v[116:119], v[8:11]
	v_mfma_f32_16x16x32_bf16 v[8:11], v[16:19], v[120:123], 0
	v_mfma_f32_16x16x32_bf16 v[194:197], v[20:23], v[124:127], v[8:11]
	v_mfma_f32_16x16x32_bf16 v[8:11], v[24:27], v[120:123], 0
	v_mfma_f32_16x16x32_bf16 v[198:201], v[28:31], v[124:127], v[8:11]
	s_barrier
	s_setprio 0
	s_add_i32 s67, 0, 0x18000
	s_add_i32 s75, 0, 0x1c000
	v_add_u32_e32 v148, s67, v144
	v_add_u32_e32 v149, s75, v144
	s_nop 0
	ds_read_b128 v[8:11], v148
	ds_read_b128 v[12:15], v148 offset:1024
	ds_read_b128 v[16:19], v148 offset:2048
	ds_read_b128 v[20:23], v148 offset:3072
	ds_read_b128 v[202:205], v149
	ds_read_b128 v[206:209], v149 offset:1024
	ds_read_b128 v[210:213], v149 offset:2048
	ds_read_b128 v[214:217], v149 offset:3072
	s_add_u32 s80, s78, 0x80100
	s_addc_u32 s81, s79, 0
	s_mov_b32 m0, s36
	v_lshl_add_u64 v[88:89], s[80:81], 0, v[134:135]
	ds_read_b128 v[24:27], v147 offset:32768
	ds_read_b128 v[28:31], v147 offset:33792
	ds_read_b128 v[218:221], v147 offset:34816
	ds_read_b128 v[222:225], v147 offset:35840
	ds_read_b128 v[226:229], v147 offset:36864
	ds_read_b128 v[230:233], v147 offset:37888
	ds_read_b128 v[234:237], v147 offset:38912
	ds_read_b128 v[238:241], v147 offset:39936
	global_load_lds_dwordx4 v134, s[80:81]
	v_lshl_add_u64 v[88:89], s[80:81], 0, v[132:133]
	s_mov_b32 m0, s37
	s_nop 0
	global_load_lds_dwordx4 v132, s[80:81]
	s_waitcnt vmcnt(8) lgkmcnt(0)
	s_setprio 1
	s_barrier
	v_mfma_f32_16x16x32_bf16 v[64:67], v[8:11], v[24:27], v[64:67]
	v_mfma_f32_16x16x32_bf16 v[120:123], v[12:15], v[28:31], v[64:67]
	v_mfma_f32_16x16x32_bf16 v[64:67], v[16:19], v[24:27], v[68:71]
	v_mfma_f32_16x16x32_bf16 v[124:127], v[20:23], v[28:31], v[64:67]
	v_mfma_f32_16x16x32_bf16 v[64:67], v[8:11], v[218:221], v[72:75]
	v_mfma_f32_16x16x32_bf16 v[104:107], v[12:15], v[222:225], v[64:67]
	v_mfma_f32_16x16x32_bf16 v[64:67], v[16:19], v[218:221], v[76:79]
	v_mfma_f32_16x16x32_bf16 v[108:111], v[20:23], v[222:225], v[64:67]
	v_mfma_f32_16x16x32_bf16 v[64:67], v[8:11], v[226:229], v[80:83]
	v_mfma_f32_16x16x32_bf16 v[88:91], v[12:15], v[230:233], v[64:67]
	v_mfma_f32_16x16x32_bf16 v[64:67], v[16:19], v[226:229], v[84:87]
	v_mfma_f32_16x16x32_bf16 v[92:95], v[20:23], v[230:233], v[64:67]
	v_mfma_f32_16x16x32_bf16 v[64:67], v[8:11], v[234:237], v[96:99]
	v_mfma_f32_16x16x32_bf16 v[68:71], v[16:19], v[234:237], v[100:103]
	v_mfma_f32_16x16x32_bf16 v[64:67], v[12:15], v[238:241], v[64:67]
	v_mfma_f32_16x16x32_bf16 v[68:71], v[20:23], v[238:241], v[68:71]
	s_setprio 0
	s_setprio 1
	v_mfma_f32_16x16x32_bf16 v[72:75], v[202:205], v[24:27], v[112:115]
	v_mfma_f32_16x16x32_bf16 v[24:27], v[210:213], v[24:27], v[32:35]
	v_mfma_f32_16x16x32_bf16 v[116:119], v[214:217], v[28:31], v[24:27]
	v_mfma_f32_16x16x32_bf16 v[24:27], v[202:205], v[218:221], v[36:39]
	v_mfma_f32_16x16x32_bf16 v[96:99], v[206:209], v[222:225], v[24:27]
	v_mfma_f32_16x16x32_bf16 v[24:27], v[210:213], v[218:221], v[40:43]
	v_mfma_f32_16x16x32_bf16 v[100:103], v[214:217], v[222:225], v[24:27]
	v_mfma_f32_16x16x32_bf16 v[24:27], v[202:205], v[226:229], v[44:47]
	v_mfma_f32_16x16x32_bf16 v[80:83], v[206:209], v[230:233], v[24:27]
	v_mfma_f32_16x16x32_bf16 v[24:27], v[210:213], v[226:229], v[48:51]
	v_mfma_f32_16x16x32_bf16 v[84:87], v[214:217], v[230:233], v[24:27]
	v_mfma_f32_16x16x32_bf16 v[24:27], v[202:205], v[234:237], v[52:55]
	v_mfma_f32_16x16x32_bf16 v[48:51], v[206:209], v[238:241], v[24:27]
	v_mfma_f32_16x16x32_bf16 v[24:27], v[210:213], v[234:237], v[56:59]
	v_mfma_f32_16x16x32_bf16 v[112:115], v[206:209], v[28:31], v[72:75]
	v_mfma_f32_16x16x32_bf16 v[52:55], v[214:217], v[238:241], v[24:27]
	s_barrier
; #define PG8_MMA(ai, bj, At, Bt) do { __builtin_amdgcn_s_setprio(1); _Pragma("unroll") for (int m = 0; m < 4; ++m) _Pragma("unroll") for (int n = 0; n < 2; ++n) _Pragma("unroll") for (int k = 0; k < 2; ++k) \
;         acc[ai][bj][m][n] = __builtin_amdgcn_mfma_f32_16x16x32_bf16(Bt[n][k], At[m][k], acc[ai][bj][m][n], 0, 0, 0); __builtin_amdgcn_s_setprio(0); } while (0)
; template <class Epi, class Sched, bool ALIGN_EPI = false, bool SP2 = false, bool A_TILED = false>
; __device__ __forceinline__ void gemm_phase(PG8_LAS unsigned char* lds, const Gemm g, const Sched& S, const Epi& E, const int wave_s) {
;     ...
;         for (int t = PEEL ? 2 : 0; t < nt; t += 2) {
;             const bool last = (t == nt - 2);
;             const char* a1 = cA + (size_t)(t + 1) * kstepA;
;             const char* a2 = last ? nA : cA + (size_t)(t + 2) * kstepA; const char* b2 = last ? nB : cB + (size_t)(t + 2) * kstep;
;             const char* a3 = a2 + kstepA; const char* b3 = b2 + kstep;
;             if (last && has_next) S.a_ready(nxt);
;             if constexpr (SP2) {
;             PG8_ITER(PG8_MMA)
	s_setprio 0
	s_add_i32 s67, s67, s15
	s_add_i32 s69, s67, 0x2000
	s_nop 1
	v_lshl_add_u64 v[24:25], v[242:243], 0, s[64:65]
	s_mov_b32 m0, s67
	s_add_u32 s80, s76, 0x80180
	ds_read_b128 v[32:35], v147 offset:49152
	ds_read_b128 v[36:39], v147 offset:50176
	ds_read_b128 v[218:221], v147 offset:51200
	ds_read_b128 v[222:225], v147 offset:52224
	ds_read_b128 v[226:229], v147 offset:53248
	ds_read_b128 v[230:233], v147 offset:54272
	ds_read_b128 v[234:237], v147 offset:55296
	ds_read_b128 v[238:241], v147 offset:56320
	global_load_lds_dwordx4 v[24:25], off
	v_lshl_add_u64 v[24:25], v[244:245], 0, s[64:65]
	s_mov_b32 m0, s69
	s_addc_u32 s81, s77, 0
	s_add_i32 s75, s75, s15
	global_load_lds_dwordx4 v[24:25], off
	v_lshl_add_u64 v[24:25], s[80:81], 0, v[128:129]
	s_mov_b32 m0, s75
	s_add_i32 s82, s75, 0x2000
	global_load_lds_dwordx4 v128, s[80:81]
	v_lshl_add_u64 v[24:25], s[80:81], 0, v[130:131]
	s_mov_b32 m0, s82
	s_nop 0
	global_load_lds_dwordx4 v130, s[80:81]
	v_lshl_add_u64 v[24:25], v[246:247], 0, s[64:65]
	s_mov_b32 m0, s43
	s_nop 0
	global_load_lds_dwordx4 v[24:25], off
	v_lshl_add_u64 v[24:25], v[248:249], 0, s[64:65]
	s_mov_b32 m0, s44
	s_nop 0
	global_load_lds_dwordx4 v[24:25], off
	s_waitcnt vmcnt(8) lgkmcnt(0)
	s_setprio 1
	s_barrier
	v_mfma_f32_16x16x32_bf16 v[24:27], v[8:11], v[32:35], v[150:153]
	v_mfma_f32_16x16x32_bf16 v[72:75], v[12:15], v[36:39], v[24:27]
	v_mfma_f32_16x16x32_bf16 v[24:27], v[16:19], v[32:35], v[154:157]
	v_mfma_f32_16x16x32_bf16 v[76:79], v[20:23], v[36:39], v[24:27]
	v_mfma_f32_16x16x32_bf16 v[24:27], v[8:11], v[218:221], v[158:161]
	v_mfma_f32_16x16x32_bf16 v[40:43], v[12:15], v[222:225], v[24:27]
	v_mfma_f32_16x16x32_bf16 v[24:27], v[16:19], v[218:221], v[162:165]
	v_mfma_f32_16x16x32_bf16 v[0:3], v[8:11], v[234:237], v[0:3]
	v_mfma_f32_16x16x32_bf16 v[44:47], v[20:23], v[222:225], v[24:27]
	v_mfma_f32_16x16x32_bf16 v[24:27], v[8:11], v[226:229], v[166:169]
	v_mfma_f32_16x16x32_bf16 v[28:31], v[16:19], v[226:229], v[170:173]
	v_mfma_f32_16x16x32_bf16 v[8:11], v[12:15], v[238:241], v[0:3]
	v_mfma_f32_16x16x32_bf16 v[0:3], v[16:19], v[234:237], v[4:7]
	v_mfma_f32_16x16x32_bf16 v[24:27], v[12:15], v[230:233], v[24:27]
	v_mfma_f32_16x16x32_bf16 v[28:31], v[20:23], v[230:233], v[28:31]
	v_mfma_f32_16x16x32_bf16 v[12:15], v[20:23], v[238:241], v[0:3]
	s_setprio 0
	s_setprio 1
	v_mfma_f32_16x16x32_bf16 v[0:3], v[202:205], v[32:35], v[174:177]
	v_mfma_f32_16x16x32_bf16 v[56:59], v[206:209], v[36:39], v[0:3]
	v_mfma_f32_16x16x32_bf16 v[0:3], v[210:213], v[32:35], v[60:63]
	v_mfma_f32_16x16x32_bf16 v[60:63], v[214:217], v[36:39], v[0:3]
	v_mfma_f32_16x16x32_bf16 v[0:3], v[202:205], v[218:221], v[178:181]
	v_mfma_f32_16x16x32_bf16 v[32:35], v[206:209], v[222:225], v[0:3]
	v_mfma_f32_16x16x32_bf16 v[0:3], v[210:213], v[218:221], v[182:185]
	v_mfma_f32_16x16x32_bf16 v[36:39], v[214:217], v[222:225], v[0:3]
	v_mfma_f32_16x16x32_bf16 v[0:3], v[202:205], v[226:229], v[186:189]
	v_mfma_f32_16x16x32_bf16 v[16:19], v[206:209], v[230:233], v[0:3]
	v_mfma_f32_16x16x32_bf16 v[0:3], v[210:213], v[226:229], v[190:193]
	v_mfma_f32_16x16x32_bf16 v[20:23], v[214:217], v[230:233], v[0:3]
	v_mfma_f32_16x16x32_bf16 v[0:3], v[202:205], v[234:237], v[194:197]
	v_mfma_f32_16x16x32_bf16 v[4:7], v[210:213], v[234:237], v[198:201]
	v_mfma_f32_16x16x32_bf16 v[0:3], v[206:209], v[238:241], v[0:3]
	v_mfma_f32_16x16x32_bf16 v[4:7], v[214:217], v[238:241], v[4:7]
	s_barrier
	s_setprio 0
	s_add_u32 s83, s76, 0x200
	s_addc_u32 s84, s77, 0
	s_add_u32 s76, s78, 0x80180
	s_addc_u32 s77, s79, 0
	s_mov_b32 s85, 0
.LBB0_1155:
	ds_read_b128 v[150:153], v145
	ds_read_b128 v[154:157], v145 offset:1024
	ds_read_b128 v[158:161], v145 offset:2048
	ds_read_b128 v[162:165], v145 offset:3072
	ds_read_b128 v[166:169], v146
	ds_read_b128 v[170:173], v146 offset:1024
	ds_read_b128 v[174:177], v146 offset:2048
	ds_read_b128 v[178:181], v146 offset:3072
	s_add_u32 s78, s76, 0xfff80080
	s_addc_u32 s79, s77, -1
	s_cmp_eq_u32 s85, 28
	s_cselect_b32 s81, s50, s79
	s_cselect_b32 s80, s51, s78
	s_cselect_b32 s79, s52, s84
	s_cselect_b32 s78, s53, s83
	s_mov_b32 m0, s54
	v_lshl_add_u64 v[214:215], s[76:77], 0, v[138:139]
	ds_read_b128 v[182:185], v147
	ds_read_b128 v[186:189], v147 offset:1024
	ds_read_b128 v[190:193], v147 offset:2048
	ds_read_b128 v[194:197], v147 offset:3072
	ds_read_b128 v[198:201], v147 offset:4096
	ds_read_b128 v[202:205], v147 offset:5120
	ds_read_b128 v[206:209], v147 offset:6144
	ds_read_b128 v[210:213], v147 offset:7168
	global_load_lds_dwordx4 v138, s[76:77]
	v_lshl_add_u64 v[214:215], s[76:77], 0, v[136:137]
	s_mov_b32 m0, s55
	s_nop 0
	global_load_lds_dwordx4 v136, s[76:77]
	s_waitcnt vmcnt(8) lgkmcnt(0)
	s_setprio 1
	s_barrier
	v_mfma_f32_16x16x32_bf16 v[120:123], v[150:153], v[182:185], v[120:123]
	v_mfma_f32_16x16x32_bf16 v[124:127], v[158:161], v[182:185], v[124:127]
	v_mfma_f32_16x16x32_bf16 v[104:107], v[150:153], v[190:193], v[104:107]
	v_mfma_f32_16x16x32_bf16 v[108:111], v[158:161], v[190:193], v[108:111]
	v_mfma_f32_16x16x32_bf16 v[88:91], v[150:153], v[198:201], v[88:91]
	v_mfma_f32_16x16x32_bf16 v[92:95], v[158:161], v[198:201], v[92:95]
	v_mfma_f32_16x16x32_bf16 v[64:67], v[150:153], v[206:209], v[64:67]
	v_mfma_f32_16x16x32_bf16 v[68:71], v[158:161], v[206:209], v[68:71]
	v_mfma_f32_16x16x32_bf16 v[120:123], v[154:157], v[186:189], v[120:123]
	v_mfma_f32_16x16x32_bf16 v[124:127], v[162:165], v[186:189], v[124:127]
	v_mfma_f32_16x16x32_bf16 v[104:107], v[154:157], v[194:197], v[104:107]
	v_mfma_f32_16x16x32_bf16 v[108:111], v[162:165], v[194:197], v[108:111]
	v_mfma_f32_16x16x32_bf16 v[88:91], v[154:157], v[202:205], v[88:91]
	v_mfma_f32_16x16x32_bf16 v[92:95], v[162:165], v[202:205], v[92:95]
	v_mfma_f32_16x16x32_bf16 v[64:67], v[154:157], v[210:213], v[64:67]
	v_mfma_f32_16x16x32_bf16 v[68:71], v[162:165], v[210:213], v[68:71]
	s_setprio 0
	s_setprio 1
	v_mfma_f32_16x16x32_bf16 v[112:115], v[166:169], v[182:185], v[112:115]
	v_mfma_f32_16x16x32_bf16 v[116:119], v[174:177], v[182:185], v[116:119]
	v_mfma_f32_16x16x32_bf16 v[96:99], v[166:169], v[190:193], v[96:99]
	v_mfma_f32_16x16x32_bf16 v[100:103], v[174:177], v[190:193], v[100:103]
	v_mfma_f32_16x16x32_bf16 v[80:83], v[166:169], v[198:201], v[80:83]
	v_mfma_f32_16x16x32_bf16 v[84:87], v[174:177], v[198:201], v[84:87]
	v_mfma_f32_16x16x32_bf16 v[48:51], v[166:169], v[206:209], v[48:51]
	v_mfma_f32_16x16x32_bf16 v[52:55], v[174:177], v[206:209], v[52:55]
	v_mfma_f32_16x16x32_bf16 v[112:115], v[170:173], v[186:189], v[112:115]
	v_mfma_f32_16x16x32_bf16 v[116:119], v[178:181], v[186:189], v[116:119]
	v_mfma_f32_16x16x32_bf16 v[96:99], v[170:173], v[194:197], v[96:99]
	v_mfma_f32_16x16x32_bf16 v[100:103], v[178:181], v[194:197], v[100:103]
	v_mfma_f32_16x16x32_bf16 v[80:83], v[170:173], v[202:205], v[80:83]
	v_mfma_f32_16x16x32_bf16 v[84:87], v[178:181], v[202:205], v[84:87]
	v_mfma_f32_16x16x32_bf16 v[48:51], v[170:173], v[210:213], v[48:51]
	v_mfma_f32_16x16x32_bf16 v[52:55], v[178:181], v[210:213], v[52:55]
	s_barrier
	s_setprio 0
	s_mov_b32 m0, s56
	v_lshl_add_u64 v[214:215], s[78:79], 0, v[128:129]
	s_add_u32 s88, s78, 0x80000
	ds_read_b128 v[182:185], v147 offset:16384
	ds_read_b128 v[186:189], v147 offset:17408
	ds_read_b128 v[190:193], v147 offset:18432
	ds_read_b128 v[194:197], v147 offset:19456
	ds_read_b128 v[198:201], v147 offset:20480
	ds_read_b128 v[202:205], v147 offset:21504
	ds_read_b128 v[206:209], v147 offset:22528
	ds_read_b128 v[210:213], v147 offset:23552
	global_load_lds_dwordx4 v128, s[78:79]
	v_lshl_add_u64 v[216:217], s[78:79], 0, v[130:131]
	s_mov_b32 m0, s57
	s_addc_u32 s89, s79, 0
	global_load_lds_dwordx4 v130, s[78:79]
	v_lshl_add_u64 v[218:219], s[88:89], 0, v[128:129]
	s_mov_b32 m0, s58
	v_lshl_add_u64 v[220:221], s[80:81], 0, v[132:133]
	global_load_lds_dwordx4 v128, s[88:89]
	v_lshl_add_u64 v[218:219], s[88:89], 0, v[130:131]
	s_mov_b32 m0, s59
	s_nop 0
	global_load_lds_dwordx4 v130, s[88:89]
	v_lshl_add_u64 v[218:219], s[80:81], 0, v[134:135]
	s_mov_b32 m0, s22
	s_nop 0
	global_load_lds_dwordx4 v134, s[80:81]
	s_mov_b32 m0, s23
	s_nop 0
	global_load_lds_dwordx4 v132, s[80:81]
	s_waitcnt vmcnt(8) lgkmcnt(0)
	s_setprio 1
	s_barrier
	v_mfma_f32_16x16x32_bf16 v[72:75], v[150:153], v[182:185], v[72:75]
	v_mfma_f32_16x16x32_bf16 v[76:79], v[158:161], v[182:185], v[76:79]
	v_mfma_f32_16x16x32_bf16 v[40:43], v[150:153], v[190:193], v[40:43]
	v_mfma_f32_16x16x32_bf16 v[44:47], v[158:161], v[190:193], v[44:47]
	v_mfma_f32_16x16x32_bf16 v[24:27], v[150:153], v[198:201], v[24:27]
	v_mfma_f32_16x16x32_bf16 v[28:31], v[158:161], v[198:201], v[28:31]
	v_mfma_f32_16x16x32_bf16 v[8:11], v[150:153], v[206:209], v[8:11]
	v_mfma_f32_16x16x32_bf16 v[12:15], v[158:161], v[206:209], v[12:15]
	v_mfma_f32_16x16x32_bf16 v[72:75], v[154:157], v[186:189], v[72:75]
	v_mfma_f32_16x16x32_bf16 v[76:79], v[162:165], v[186:189], v[76:79]
	v_mfma_f32_16x16x32_bf16 v[40:43], v[154:157], v[194:197], v[40:43]
	v_mfma_f32_16x16x32_bf16 v[44:47], v[162:165], v[194:197], v[44:47]
	v_mfma_f32_16x16x32_bf16 v[24:27], v[154:157], v[202:205], v[24:27]
	v_mfma_f32_16x16x32_bf16 v[28:31], v[162:165], v[202:205], v[28:31]
	v_mfma_f32_16x16x32_bf16 v[8:11], v[154:157], v[210:213], v[8:11]
	v_mfma_f32_16x16x32_bf16 v[12:15], v[162:165], v[210:213], v[12:15]
	s_setprio 0
	s_setprio 1
	v_mfma_f32_16x16x32_bf16 v[56:59], v[166:169], v[182:185], v[56:59]
	v_mfma_f32_16x16x32_bf16 v[60:63], v[174:177], v[182:185], v[60:63]
	v_mfma_f32_16x16x32_bf16 v[32:35], v[166:169], v[190:193], v[32:35]
	v_mfma_f32_16x16x32_bf16 v[36:39], v[174:177], v[190:193], v[36:39]
	v_mfma_f32_16x16x32_bf16 v[16:19], v[166:169], v[198:201], v[16:19]
	v_mfma_f32_16x16x32_bf16 v[20:23], v[174:177], v[198:201], v[20:23]
	v_mfma_f32_16x16x32_bf16 v[0:3], v[166:169], v[206:209], v[0:3]
	v_mfma_f32_16x16x32_bf16 v[4:7], v[174:177], v[206:209], v[4:7]
	v_mfma_f32_16x16x32_bf16 v[56:59], v[170:173], v[186:189], v[56:59]
	v_mfma_f32_16x16x32_bf16 v[60:63], v[178:181], v[186:189], v[60:63]
	v_mfma_f32_16x16x32_bf16 v[32:35], v[170:173], v[194:197], v[32:35]
	v_mfma_f32_16x16x32_bf16 v[36:39], v[178:181], v[194:197], v[36:39]
	v_mfma_f32_16x16x32_bf16 v[16:19], v[170:173], v[202:205], v[16:19]
	v_mfma_f32_16x16x32_bf16 v[20:23], v[178:181], v[202:205], v[20:23]
	v_mfma_f32_16x16x32_bf16 v[0:3], v[170:173], v[210:213], v[0:3]
	v_mfma_f32_16x16x32_bf16 v[4:7], v[178:181], v[210:213], v[4:7]
	s_barrier
; __device__ __forceinline__ int tid_now(int wave_s) { unsigned z = 0u; asm volatile("" : "+v"(z)); return (wave_s << 6) | (int)__builtin_amdgcn_mbcnt_hi(~0u, __builtin_amdgcn_mbcnt_lo(~0u, z)); }
; #define PG8_BAR __builtin_amdgcn_s_barrier()
; template <class Epi, class Sched, bool ALIGN_EPI = false, bool SP2 = false, bool A_TILED = false>
; __device__ __forceinline__ void gemm_phase(PG8_LAS unsigned char* lds, const Gemm g, const Sched& S, const Epi& E, const int wave_s) {
;     ...
;         if constexpr (ALIGN_EPI) { if (wr == 0) PG8_BAR; }
;         if constexpr (!Epi::AFTER_DRAIN) { int te = tid_now(wave_s); asm volatile("" : "+v"(te));
;             E(acc, cur, wr, wc, te & 15, (te & 63) >> 4); S.done(cur); }
;         if (!has_next) break;
	s_setprio 0
	ds_read_b128 v[150:153], v148
	ds_read_b128 v[154:157], v148 offset:1024
	ds_read_b128 v[158:161], v148 offset:2048
	ds_read_b128 v[162:165], v148 offset:3072
	ds_read_b128 v[166:169], v149
	ds_read_b128 v[170:173], v149 offset:1024
	ds_read_b128 v[174:177], v149 offset:2048
	ds_read_b128 v[178:181], v149 offset:3072
	s_add_u32 s80, s80, 0x80000
	s_addc_u32 s81, s81, 0
	s_mov_b32 m0, s36
	v_lshl_add_u64 v[222:223], s[80:81], 0, v[134:135]
	ds_read_b128 v[182:185], v147 offset:32768
	ds_read_b128 v[186:189], v147 offset:33792
	ds_read_b128 v[190:193], v147 offset:34816
	ds_read_b128 v[194:197], v147 offset:35840
	ds_read_b128 v[198:201], v147 offset:36864
	ds_read_b128 v[202:205], v147 offset:37888
	ds_read_b128 v[206:209], v147 offset:38912
	ds_read_b128 v[210:213], v147 offset:39936
	global_load_lds_dwordx4 v134, s[80:81]
	v_lshl_add_u64 v[222:223], s[80:81], 0, v[132:133]
	s_mov_b32 m0, s37
	s_nop 0
	global_load_lds_dwordx4 v132, s[80:81]
	s_waitcnt vmcnt(8) lgkmcnt(0)
	s_setprio 1
	s_barrier
	v_mfma_f32_16x16x32_bf16 v[120:123], v[150:153], v[182:185], v[120:123]
	v_mfma_f32_16x16x32_bf16 v[124:127], v[158:161], v[182:185], v[124:127]
	v_mfma_f32_16x16x32_bf16 v[104:107], v[150:153], v[190:193], v[104:107]
	v_mfma_f32_16x16x32_bf16 v[108:111], v[158:161], v[190:193], v[108:111]
	v_mfma_f32_16x16x32_bf16 v[88:91], v[150:153], v[198:201], v[88:91]
	v_mfma_f32_16x16x32_bf16 v[92:95], v[158:161], v[198:201], v[92:95]
	v_mfma_f32_16x16x32_bf16 v[64:67], v[150:153], v[206:209], v[64:67]
	v_mfma_f32_16x16x32_bf16 v[68:71], v[158:161], v[206:209], v[68:71]
	v_mfma_f32_16x16x32_bf16 v[120:123], v[154:157], v[186:189], v[120:123]
	v_mfma_f32_16x16x32_bf16 v[124:127], v[162:165], v[186:189], v[124:127]
	v_mfma_f32_16x16x32_bf16 v[104:107], v[154:157], v[194:197], v[104:107]
	v_mfma_f32_16x16x32_bf16 v[108:111], v[162:165], v[194:197], v[108:111]
	v_mfma_f32_16x16x32_bf16 v[88:91], v[154:157], v[202:205], v[88:91]
	v_mfma_f32_16x16x32_bf16 v[92:95], v[162:165], v[202:205], v[92:95]
	v_mfma_f32_16x16x32_bf16 v[64:67], v[154:157], v[210:213], v[64:67]
	v_mfma_f32_16x16x32_bf16 v[68:71], v[162:165], v[210:213], v[68:71]
	s_setprio 0
	s_setprio 1
	v_mfma_f32_16x16x32_bf16 v[112:115], v[166:169], v[182:185], v[112:115]
	v_mfma_f32_16x16x32_bf16 v[116:119], v[174:177], v[182:185], v[116:119]
	v_mfma_f32_16x16x32_bf16 v[96:99], v[166:169], v[190:193], v[96:99]
	v_mfma_f32_16x16x32_bf16 v[100:103], v[174:177], v[190:193], v[100:103]
	v_mfma_f32_16x16x32_bf16 v[80:83], v[166:169], v[198:201], v[80:83]
	v_mfma_f32_16x16x32_bf16 v[84:87], v[174:177], v[198:201], v[84:87]
	v_mfma_f32_16x16x32_bf16 v[48:51], v[166:169], v[206:209], v[48:51]
	v_mfma_f32_16x16x32_bf16 v[52:55], v[174:177], v[206:209], v[52:55]
	v_mfma_f32_16x16x32_bf16 v[112:115], v[170:173], v[186:189], v[112:115]
	v_mfma_f32_16x16x32_bf16 v[116:119], v[178:181], v[186:189], v[116:119]
	v_mfma_f32_16x16x32_bf16 v[96:99], v[170:173], v[194:197], v[96:99]
	v_mfma_f32_16x16x32_bf16 v[100:103], v[178:181], v[194:197], v[100:103]
	v_mfma_f32_16x16x32_bf16 v[80:83], v[170:173], v[202:205], v[80:83]
	v_mfma_f32_16x16x32_bf16 v[84:87], v[178:181], v[202:205], v[84:87]
	v_mfma_f32_16x16x32_bf16 v[48:51], v[170:173], v[210:213], v[48:51]
	v_mfma_f32_16x16x32_bf16 v[52:55], v[178:181], v[210:213], v[52:55]
	s_barrier
	s_setprio 0
	s_mov_b32 m0, s67
	v_lshl_add_u64 v[214:215], v[214:215], 0, s[12:13]
	s_add_u32 s78, s78, 0x80080
	ds_read_b128 v[182:185], v147 offset:49152
	ds_read_b128 v[186:189], v147 offset:50176
	ds_read_b128 v[190:193], v147 offset:51200
	ds_read_b128 v[194:197], v147 offset:52224
	ds_read_b128 v[198:201], v147 offset:53248
	ds_read_b128 v[202:205], v147 offset:54272
	ds_read_b128 v[206:209], v147 offset:55296
	ds_read_b128 v[210:213], v147 offset:56320
	global_load_lds_dwordx4 v[214:215], off
	v_lshl_add_u64 v[214:215], v[216:217], 0, s[12:13]
	s_mov_b32 m0, s69
	s_addc_u32 s79, s79, 0
	global_load_lds_dwordx4 v[214:215], off
	v_lshl_add_u64 v[214:215], s[78:79], 0, v[128:129]
	s_mov_b32 m0, s75
	s_nop 0
	global_load_lds_dwordx4 v128, s[78:79]
	v_lshl_add_u64 v[214:215], s[78:79], 0, v[130:131]
	s_mov_b32 m0, s82
	s_nop 0
	global_load_lds_dwordx4 v130, s[78:79]
	v_lshl_add_u64 v[214:215], v[218:219], 0, s[12:13]
	s_mov_b32 m0, s43
	s_nop 0
	global_load_lds_dwordx4 v[214:215], off
	v_lshl_add_u64 v[214:215], v[220:221], 0, s[12:13]
	s_mov_b32 m0, s44
	s_nop 0
	global_load_lds_dwordx4 v[214:215], off
	s_waitcnt vmcnt(8) lgkmcnt(0)
	s_setprio 1
	s_barrier
	v_mfma_f32_16x16x32_bf16 v[72:75], v[150:153], v[182:185], v[72:75]
	v_mfma_f32_16x16x32_bf16 v[76:79], v[158:161], v[182:185], v[76:79]
	v_mfma_f32_16x16x32_bf16 v[40:43], v[150:153], v[190:193], v[40:43]
	v_mfma_f32_16x16x32_bf16 v[44:47], v[158:161], v[190:193], v[44:47]
	v_mfma_f32_16x16x32_bf16 v[24:27], v[150:153], v[198:201], v[24:27]
	v_mfma_f32_16x16x32_bf16 v[28:31], v[158:161], v[198:201], v[28:31]
	v_mfma_f32_16x16x32_bf16 v[8:11], v[150:153], v[206:209], v[8:11]
	v_mfma_f32_16x16x32_bf16 v[12:15], v[158:161], v[206:209], v[12:15]
	v_mfma_f32_16x16x32_bf16 v[72:75], v[154:157], v[186:189], v[72:75]
	v_mfma_f32_16x16x32_bf16 v[76:79], v[162:165], v[186:189], v[76:79]
	v_mfma_f32_16x16x32_bf16 v[40:43], v[154:157], v[194:197], v[40:43]
	v_mfma_f32_16x16x32_bf16 v[44:47], v[162:165], v[194:197], v[44:47]
	v_mfma_f32_16x16x32_bf16 v[24:27], v[154:157], v[202:205], v[24:27]
	v_mfma_f32_16x16x32_bf16 v[28:31], v[162:165], v[202:205], v[28:31]
	v_mfma_f32_16x16x32_bf16 v[8:11], v[154:157], v[210:213], v[8:11]
	v_mfma_f32_16x16x32_bf16 v[12:15], v[162:165], v[210:213], v[12:15]
	s_setprio 0
	s_setprio 1
	v_mfma_f32_16x16x32_bf16 v[56:59], v[166:169], v[182:185], v[56:59]
	v_mfma_f32_16x16x32_bf16 v[60:63], v[174:177], v[182:185], v[60:63]
	v_mfma_f32_16x16x32_bf16 v[32:35], v[166:169], v[190:193], v[32:35]
	v_mfma_f32_16x16x32_bf16 v[36:39], v[174:177], v[190:193], v[36:39]
	v_mfma_f32_16x16x32_bf16 v[16:19], v[166:169], v[198:201], v[16:19]
	v_mfma_f32_16x16x32_bf16 v[20:23], v[174:177], v[198:201], v[20:23]
	v_mfma_f32_16x16x32_bf16 v[0:3], v[166:169], v[206:209], v[0:3]
	v_mfma_f32_16x16x32_bf16 v[4:7], v[174:177], v[206:209], v[4:7]
	v_mfma_f32_16x16x32_bf16 v[56:59], v[170:173], v[186:189], v[56:59]
	v_mfma_f32_16x16x32_bf16 v[60:63], v[178:181], v[186:189], v[60:63]
	v_mfma_f32_16x16x32_bf16 v[32:35], v[170:173], v[194:197], v[32:35]
	v_mfma_f32_16x16x32_bf16 v[36:39], v[178:181], v[194:197], v[36:39]
	v_mfma_f32_16x16x32_bf16 v[16:19], v[170:173], v[202:205], v[16:19]
	v_mfma_f32_16x16x32_bf16 v[20:23], v[178:181], v[202:205], v[20:23]
	v_mfma_f32_16x16x32_bf16 v[0:3], v[170:173], v[210:213], v[0:3]
	v_mfma_f32_16x16x32_bf16 v[4:7], v[178:181], v[210:213], v[4:7]
	s_barrier
	s_setprio 0
	s_add_i32 s85, s85, 2
	s_add_u32 s83, s83, 0x100
	s_addc_u32 s84, s84, 0
	s_add_u32 s76, s76, 0x100
	s_addc_u32 s77, s77, 0
	s_cmp_gt_u32 s85, 29
	s_cbranch_scc0 .LBB0_1155
	s_and_b64 vcc, exec, s[60:61]
	s_cbranch_vccz .LBB0_1158
	s_barrier

; #define PG8_STAGE(bufoff, gbase, voff) do { _Pragma("unroll") for (int _i = 0; _i < 2; ++_i) \
;         __builtin_amdgcn_global_load_lds((const unsigned*)((const char*)(gbase) + (voff)[_i]), (PG8_LAS unsigned*)(lds + (bufoff) + ldsw + _i * 8192), 16, 0, 0); } while (0)
; #define PG8_WAIT_V(n) asm volatile("s_waitcnt vmcnt(" #n ")" ::: "memory")
; template <class Epi, class Sched, bool ALIGN_EPI = false, bool SP2 = false, bool A_TILED = false>
; __device__ __forceinline__ void gemm_phase(PG8_LAS unsigned char* lds, const Gemm g, const Sched& S, const Epi& E, const int wave_s) {
;     ...
;     if constexpr (SP2) {
;         PG8_STAGE(PG8_SB(0, 0), cB, voffB); PG8_STAGE(PG8_SB(0, 1), cB + hstep, voffB); PG8_STAGE(PG8_SA(0, 0), cA, voffA); PG8_STAGE(PG8_SA(0, 1), cA + hstepA, voffA);
;         if (wr == 1) PG8_BAR;
;         PG8_WAIT_V(2); PG8_BAR;
;         PG8_STAGE(PG8_SB(1, 0), cB + kstep, voffB); PG8_STAGE(PG8_SA(1, 0), cA + kstepA, voffA); PG8_STAGE(PG8_SB(1, 1), cB + hstep + kstep, voffB);
;         PG8_WAIT_V(6); PG8_BAR;
;     } else {
;         PG8_STAGE(PG8_SB(0, 0), cB, voffB); PG8_STAGE(PG8_SA(0, 0), cA, voffA); PG8_STAGE(PG8_SB(0, 1), cB + hstep, voffB); PG8_STAGE(PG8_SA(0, 1), cA + hstepA, voffA);
;         if (wr == 1) PG8_BAR;
;         PG8_WAIT_V(4); PG8_BAR;
;         PG8_STAGE(PG8_SB(1, 0), cB + kstep, voffB); PG8_STAGE(PG8_SA(1, 0), cA + kstepA, voffA); PG8_STAGE(PG8_SB(1, 1), cB + hstep + kstep, voffB);
;         PG8_WAIT_V(6); PG8_BAR;
;     }
;     for (;;) {
;         const bool has_next = Epi::AFTER_DRAIN ? false : S.next(ui + 1, nxt);
;         const char* nA = has_next ? (const char*)g.A + (size_t)nxt.pm * tstepA : cA; const char* nB = has_next ? (const char*)g.Bt + (size_t)nxt.pn * tstep : cB;
;         constexpr bool PEEL = SP2 && !Epi::AFTER_DRAIN;
;         if constexpr (PEEL) {
;             const char* a1 = cA + kstepA; const char* a2 = cA + 2 * kstepA; const char* b2 = cB + 2 * kstep; const char* a3 = a2 + kstepA; const char* b3 = b2 + kstep;
;             PG8_ITER(PG8_MMAZ)
;         } else {
; #pragma unroll
;             for (int a = 0; a < 2; ++a)
; #pragma unroll
;                 for (int b = 0; b < 2; ++b)
; #pragma unroll
;                     for (int m = 0; m < 4; ++m)
; #pragma unroll
;                         for (int n = 0; n < 2; ++n) acc[a][b][m][n] = (f32x4){0.f, 0.f, 0.f, 0.f};
.LBB0_1227:
	v_and_b32_e32 v5, 48, v4
	v_lshlrev_b32_e32 v6, 6, v4
	s_movk_i32 s36, 0x3c0
	v_lshlrev_b32_e32 v4, 2, v4
	s_mov_b64 s[64:65], 0x80
	s_and_b32 s7, s9, 3
	s_lshl_b32 s6, s23, 6
	s_lshl_b32 s23, s23, 13
	v_and_or_b32 v5, v6, s36, v5
	v_and_b32_e32 v4, 32, v4
	s_add_i32 m0, s14, 0x18000
	v_lshl_add_u64 v[2:3], v[2:3], 0, s[64:65]
	v_bitop3_b32 v6, v5, s23, v4 bitop3:0xde
	s_lshl_b32 s23, s7, 12
	s_waitcnt vmcnt(2)
	s_barrier
	global_load_lds_dwordx4 v[2:3], off
	s_add_i32 m0, s14, 0x1a000
	s_add_u32 s36, s4, 0x8000
	v_bitop3_b32 v4, v5, s23, v4 bitop3:0xde
	v_lshl_add_u64 v[0:1], v[0:1], 0, s[64:65]
	s_addc_u32 s37, s5, 0
	s_add_i32 s23, s14, 0x8000
	global_load_lds_dwordx4 v[0:1], off
	v_lshl_add_u64 v[0:1], s[36:37], 0, v[32:33]
	s_mov_b32 m0, s23
	s_mov_b64 s[40:41], 0x3460c000
	global_load_lds_dwordx4 v32, s[36:37]
	v_lshl_add_u64 v[0:1], s[36:37], 0, v[132:133]
	s_add_i32 s36, s14, 0xa000
	s_add_u32 s38, s0, 0x200080
	s_mov_b32 m0, s36
	s_addc_u32 s39, s1, 0
	global_load_lds_dwordx4 v[0:1], off
	s_add_i32 m0, s14, 0x1c000
	v_lshl_add_u64 v[0:1], s[38:39], 0, v[34:35]
	global_load_lds_dwordx4 v34, s[38:39]
	v_lshl_add_u64 v[0:1], s[38:39], 0, v[134:135]
	s_add_i32 m0, s14, 0x1e000
	s_add_u32 s37, s68, 0x12600100
	global_load_lds_dwordx4 v134, s[38:39]
	s_addc_u32 s38, s69, 0
	v_lshl_add_u64 v[0:1], s[66:67], 0, v[132:133]
	v_lshl_add_u64 v[136:137], v[0:1], 0, s[40:41]
	v_lshl_add_u64 v[0:1], s[66:67], 0, v[32:33]
	s_add_u32 s39, s66, 0x34610000
	s_waitcnt vmcnt(6)
	v_lshl_add_u64 v[138:139], v[0:1], 0, s[40:41]
	s_addc_u32 s40, s67, 0
	s_add_i32 s44, 0, 0x10000
	s_add_i32 s46, 0, 0x14000
	s_add_i32 s48, 0, 0x18000
	s_add_i32 s51, 0, 0x1c000
	v_add_u32_e32 v140, s44, v4
	v_add_u32_e32 v141, s46, v4
	s_add_i32 s44, s44, s50
	s_add_i32 s46, s46, s50
	v_add_u32_e32 v143, s48, v4
	s_add_i32 s48, s48, s50
	s_add_i32 s50, s51, s50
	s_mov_b32 s41, -2
	v_add_u32_e32 v142, 0, v6
	s_add_i32 s42, s14, 0xc000
	s_add_i32 s43, s14, 0xe000
	s_add_i32 s45, s44, 0x2000
	s_add_i32 s47, s46, 0x2000
	v_add_u32_e32 v144, s51, v4
	s_add_i32 s49, s48, 0x2000
	s_add_i32 s51, s50, 0x2000
	s_mov_b64 s[66:67], 0x10000
	v_mov_b32_e32 v0, v35
	v_mov_b32_e32 v1, v35
	v_mov_b32_e32 v2, v35
	v_mov_b32_e32 v3, v35
	v_mov_b32_e32 v4, v35
	v_mov_b32_e32 v5, v35
	v_mov_b32_e32 v6, v35
	v_mov_b32_e32 v7, v35
	v_mov_b32_e32 v40, v35
	v_mov_b32_e32 v41, v35
	v_mov_b32_e32 v42, v35
	v_mov_b32_e32 v43, v35
	v_mov_b32_e32 v44, v35
	v_mov_b32_e32 v45, v35
	v_mov_b32_e32 v46, v35
	v_mov_b32_e32 v47, v35
	v_mov_b32_e32 v88, v35
	v_mov_b32_e32 v89, v35
	v_mov_b32_e32 v90, v35
	v_mov_b32_e32 v91, v35
	v_mov_b32_e32 v92, v35
	v_mov_b32_e32 v93, v35
	v_mov_b32_e32 v94, v35
	v_mov_b32_e32 v95, v35
	v_mov_b32_e32 v112, v35
	v_mov_b32_e32 v113, v35
	v_mov_b32_e32 v114, v35
	v_mov_b32_e32 v115, v35
	v_mov_b32_e32 v124, v35
	v_mov_b32_e32 v125, v35
	v_mov_b32_e32 v126, v35
	v_mov_b32_e32 v127, v35
	v_mov_b32_e32 v24, v35
	v_mov_b32_e32 v25, v35
	v_mov_b32_e32 v26, v35
	v_mov_b32_e32 v27, v35
	v_mov_b32_e32 v36, v35
	v_mov_b32_e32 v37, v35
	v_mov_b32_e32 v38, v35
	v_mov_b32_e32 v39, v35
	v_mov_b32_e32 v80, v35
	v_mov_b32_e32 v81, v35
	v_mov_b32_e32 v82, v35
	v_mov_b32_e32 v83, v35
	v_mov_b32_e32 v84, v35
	v_mov_b32_e32 v85, v35
	v_mov_b32_e32 v86, v35
	v_mov_b32_e32 v87, v35
	v_mov_b32_e32 v120, v35
	v_mov_b32_e32 v121, v35
	v_mov_b32_e32 v122, v35
	v_mov_b32_e32 v123, v35
	v_mov_b32_e32 v116, v35
	v_mov_b32_e32 v117, v35
	v_mov_b32_e32 v118, v35
	v_mov_b32_e32 v119, v35
	v_mov_b32_e32 v104, v35
	v_mov_b32_e32 v105, v35
	v_mov_b32_e32 v106, v35
	v_mov_b32_e32 v107, v35
	v_mov_b32_e32 v100, v35
	v_mov_b32_e32 v101, v35
	v_mov_b32_e32 v102, v35
	v_mov_b32_e32 v103, v35
	v_mov_b32_e32 v96, v35
	v_mov_b32_e32 v97, v35
	v_mov_b32_e32 v98, v35
	v_mov_b32_e32 v99, v35
	v_mov_b32_e32 v108, v35
	v_mov_b32_e32 v109, v35
	v_mov_b32_e32 v110, v35
	v_mov_b32_e32 v111, v35
	v_mov_b32_e32 v64, v35
	v_mov_b32_e32 v65, v35
	v_mov_b32_e32 v66, v35
	v_mov_b32_e32 v67, v35
	v_mov_b32_e32 v72, v35
	v_mov_b32_e32 v73, v35
	v_mov_b32_e32 v74, v35
	v_mov_b32_e32 v75, v35
	v_mov_b32_e32 v48, v35
	v_mov_b32_e32 v49, v35
	v_mov_b32_e32 v50, v35
	v_mov_b32_e32 v51, v35
	v_mov_b32_e32 v56, v35
	v_mov_b32_e32 v57, v35
	v_mov_b32_e32 v58, v35
	v_mov_b32_e32 v59, v35
	v_mov_b32_e32 v16, v35
	v_mov_b32_e32 v17, v35
	v_mov_b32_e32 v18, v35
	v_mov_b32_e32 v19, v35
	v_mov_b32_e32 v28, v35
	v_mov_b32_e32 v29, v35
	v_mov_b32_e32 v30, v35
	v_mov_b32_e32 v31, v35
	v_mov_b32_e32 v68, v35
	v_mov_b32_e32 v69, v35
	v_mov_b32_e32 v70, v35
	v_mov_b32_e32 v71, v35
	v_mov_b32_e32 v128, v35
	v_mov_b32_e32 v129, v35
	v_mov_b32_e32 v130, v35
	v_mov_b32_e32 v131, v35
	v_mov_b32_e32 v52, v35
	v_mov_b32_e32 v53, v35
	v_mov_b32_e32 v54, v35
	v_mov_b32_e32 v55, v35
	v_mov_b32_e32 v76, v35
	v_mov_b32_e32 v77, v35
	v_mov_b32_e32 v78, v35
	v_mov_b32_e32 v79, v35
	v_mov_b32_e32 v20, v35
	v_mov_b32_e32 v21, v35
	v_mov_b32_e32 v22, v35
	v_mov_b32_e32 v23, v35
	v_mov_b32_e32 v60, v35
	v_mov_b32_e32 v61, v35
	v_mov_b32_e32 v62, v35
	v_mov_b32_e32 v63, v35
	v_mov_b32_e32 v12, v35
	v_mov_b32_e32 v13, v35
	v_mov_b32_e32 v14, v35
	v_mov_b32_e32 v15, v35
	v_mov_b32_e32 v8, v35
	v_mov_b32_e32 v9, v35
	v_mov_b32_e32 v10, v35
	v_mov_b32_e32 v11, v35
	s_barrier
; #define PG8_MMA(ai, bj, At, Bt) do { __builtin_amdgcn_s_setprio(1); _Pragma("unroll") for (int m = 0; m < 4; ++m) _Pragma("unroll") for (int n = 0; n < 2; ++n) _Pragma("unroll") for (int k = 0; k < 2; ++k) \
;         acc[ai][bj][m][n] = __builtin_amdgcn_mfma_f32_16x16x32_bf16(Bt[n][k], At[m][k], acc[ai][bj][m][n], 0, 0, 0); __builtin_amdgcn_s_setprio(0); } while (0)
; template <class Epi, class Sched, bool ALIGN_EPI = false, bool SP2 = false, bool A_TILED = false>
; __device__ __forceinline__ void gemm_phase(PG8_LAS unsigned char* lds, const Gemm g, const Sched& S, const Epi& E, const int wave_s) {
;     ...
;         for (int t = PEEL ? 2 : 0; t < nt; t += 2) {
;             const bool last = (t == nt - 2);
;             const char* a1 = cA + (size_t)(t + 1) * kstepA;
;             const char* a2 = last ? nA : cA + (size_t)(t + 2) * kstepA; const char* b2 = last ? nB : cB + (size_t)(t + 2) * kstep;
;             const char* a3 = a2 + kstepA; const char* b3 = b2 + kstep;
;             if (last && has_next) S.a_ready(nxt);
;             if constexpr (SP2) {
;             PG8_ITER(PG8_MMA)
.LBB0_1228:
	ds_read_b128 v[146:149], v140
	ds_read_b128 v[150:153], v140 offset:1024
	ds_read_b128 v[154:157], v140 offset:2048
	ds_read_b128 v[158:161], v140 offset:3072
	ds_read_b128 v[162:165], v141
	ds_read_b128 v[166:169], v141 offset:1024
	ds_read_b128 v[170:173], v141 offset:2048
	ds_read_b128 v[174:177], v141 offset:3072
	s_add_u32 s52, s12, s39
	s_addc_u32 s53, s13, s40
	s_add_u32 s54, s12, s37
	s_addc_u32 s55, s13, s38
	s_cmpk_eq_i32 s41, 0x7c
	s_cselect_b32 s72, s4, s52
	s_cselect_b32 s73, s5, s53
	s_cselect_b32 s70, s0, s54
	s_cselect_b32 s71, s1, s55
	s_add_u32 s68, s72, 0x8000
	s_addc_u32 s69, s73, 0
	s_mov_b32 m0, s42
	v_lshl_add_u64 v[210:211], s[12:13], 0, v[138:139]
	ds_read_b128 v[178:181], v142
	ds_read_b128 v[182:185], v142 offset:1024
	ds_read_b128 v[186:189], v142 offset:2048
	ds_read_b128 v[190:193], v142 offset:3072
	ds_read_b128 v[194:197], v142 offset:4096
	ds_read_b128 v[198:201], v142 offset:5120
	ds_read_b128 v[202:205], v142 offset:6144
	ds_read_b128 v[206:209], v142 offset:7168
	global_load_lds_dwordx4 v[210:211], off
	v_lshl_add_u64 v[210:211], s[12:13], 0, v[136:137]
	s_mov_b32 m0, s43
	s_nop 0
	global_load_lds_dwordx4 v[210:211], off
	s_waitcnt vmcnt(8) lgkmcnt(0)
	s_setprio 1
	s_barrier
	v_mfma_f32_16x16x32_bf16 v[8:11], v[146:149], v[178:181], v[8:11]
	v_mfma_f32_16x16x32_bf16 v[12:15], v[154:157], v[178:181], v[12:15]
	v_mfma_f32_16x16x32_bf16 v[60:63], v[146:149], v[186:189], v[60:63]
	v_mfma_f32_16x16x32_bf16 v[20:23], v[154:157], v[186:189], v[20:23]
	v_mfma_f32_16x16x32_bf16 v[76:79], v[146:149], v[194:197], v[76:79]
	v_mfma_f32_16x16x32_bf16 v[52:55], v[154:157], v[194:197], v[52:55]
	v_mfma_f32_16x16x32_bf16 v[128:131], v[146:149], v[202:205], v[128:131]
	v_mfma_f32_16x16x32_bf16 v[68:71], v[154:157], v[202:205], v[68:71]
	v_mfma_f32_16x16x32_bf16 v[8:11], v[150:153], v[182:185], v[8:11]
	v_mfma_f32_16x16x32_bf16 v[12:15], v[158:161], v[182:185], v[12:15]
	v_mfma_f32_16x16x32_bf16 v[60:63], v[150:153], v[190:193], v[60:63]
	v_mfma_f32_16x16x32_bf16 v[20:23], v[158:161], v[190:193], v[20:23]
	v_mfma_f32_16x16x32_bf16 v[76:79], v[150:153], v[198:201], v[76:79]
	v_mfma_f32_16x16x32_bf16 v[52:55], v[158:161], v[198:201], v[52:55]
	v_mfma_f32_16x16x32_bf16 v[128:131], v[150:153], v[206:209], v[128:131]
	v_mfma_f32_16x16x32_bf16 v[68:71], v[158:161], v[206:209], v[68:71]
	s_setprio 0
	s_setprio 1
	v_mfma_f32_16x16x32_bf16 v[28:31], v[162:165], v[178:181], v[28:31]
	v_mfma_f32_16x16x32_bf16 v[16:19], v[170:173], v[178:181], v[16:19]
	v_mfma_f32_16x16x32_bf16 v[56:59], v[162:165], v[186:189], v[56:59]
	v_mfma_f32_16x16x32_bf16 v[48:51], v[170:173], v[186:189], v[48:51]
	v_mfma_f32_16x16x32_bf16 v[72:75], v[162:165], v[194:197], v[72:75]
	v_mfma_f32_16x16x32_bf16 v[64:67], v[170:173], v[194:197], v[64:67]
	v_mfma_f32_16x16x32_bf16 v[108:111], v[162:165], v[202:205], v[108:111]
	v_mfma_f32_16x16x32_bf16 v[96:99], v[170:173], v[202:205], v[96:99]
	v_mfma_f32_16x16x32_bf16 v[28:31], v[166:169], v[182:185], v[28:31]
	v_mfma_f32_16x16x32_bf16 v[16:19], v[174:177], v[182:185], v[16:19]
	v_mfma_f32_16x16x32_bf16 v[56:59], v[166:169], v[190:193], v[56:59]
	v_mfma_f32_16x16x32_bf16 v[48:51], v[174:177], v[190:193], v[48:51]
	v_mfma_f32_16x16x32_bf16 v[72:75], v[166:169], v[198:201], v[72:75]
	v_mfma_f32_16x16x32_bf16 v[64:67], v[174:177], v[198:201], v[64:67]
	v_mfma_f32_16x16x32_bf16 v[108:111], v[166:169], v[206:209], v[108:111]
	v_mfma_f32_16x16x32_bf16 v[96:99], v[174:177], v[206:209], v[96:99]
	s_barrier
	s_setprio 0
	s_mov_b32 m0, s44
	v_lshl_add_u64 v[210:211], s[70:71], 0, v[34:35]
	s_add_u32 s52, s70, 0x200000
	ds_read_b128 v[178:181], v142 offset:16384
	ds_read_b128 v[182:185], v142 offset:17408
	ds_read_b128 v[186:189], v142 offset:18432
	ds_read_b128 v[190:193], v142 offset:19456
	ds_read_b128 v[194:197], v142 offset:20480
	ds_read_b128 v[198:201], v142 offset:21504
	ds_read_b128 v[202:205], v142 offset:22528
	ds_read_b128 v[206:209], v142 offset:23552
	global_load_lds_dwordx4 v34, s[70:71]
	v_lshl_add_u64 v[212:213], s[70:71], 0, v[134:135]
	s_mov_b32 m0, s45
	s_addc_u32 s53, s71, 0
	global_load_lds_dwordx4 v134, s[70:71]
	v_lshl_add_u64 v[214:215], s[52:53], 0, v[34:35]
	s_mov_b32 m0, s46
	s_nop 0
	global_load_lds_dwordx4 v34, s[52:53]
	v_lshl_add_u64 v[214:215], s[52:53], 0, v[134:135]
	s_mov_b32 m0, s47
	s_nop 0
	global_load_lds_dwordx4 v134, s[52:53]
	v_lshl_add_u64 v[214:215], s[72:73], 0, v[32:33]
	s_mov_b32 m0, s14
	s_nop 0
	global_load_lds_dwordx4 v32, s[72:73]
	v_lshl_add_u64 v[214:215], s[72:73], 0, v[132:133]
	s_mov_b32 m0, s15
	s_nop 0
	global_load_lds_dwordx4 v132, s[72:73]
	s_waitcnt vmcnt(8) lgkmcnt(0)
	s_setprio 1
	s_barrier
	v_mfma_f32_16x16x32_bf16 v[100:103], v[146:149], v[178:181], v[100:103]
	v_mfma_f32_16x16x32_bf16 v[104:107], v[154:157], v[178:181], v[104:107]
	v_mfma_f32_16x16x32_bf16 v[116:119], v[146:149], v[186:189], v[116:119]
	v_mfma_f32_16x16x32_bf16 v[120:123], v[154:157], v[186:189], v[120:123]
	v_mfma_f32_16x16x32_bf16 v[84:87], v[146:149], v[194:197], v[84:87]
	v_mfma_f32_16x16x32_bf16 v[80:83], v[154:157], v[194:197], v[80:83]
	v_mfma_f32_16x16x32_bf16 v[36:39], v[146:149], v[202:205], v[36:39]
	v_mfma_f32_16x16x32_bf16 v[24:27], v[154:157], v[202:205], v[24:27]
	v_mfma_f32_16x16x32_bf16 v[100:103], v[150:153], v[182:185], v[100:103]
	v_mfma_f32_16x16x32_bf16 v[104:107], v[158:161], v[182:185], v[104:107]
	v_mfma_f32_16x16x32_bf16 v[116:119], v[150:153], v[190:193], v[116:119]
	v_mfma_f32_16x16x32_bf16 v[120:123], v[158:161], v[190:193], v[120:123]
	v_mfma_f32_16x16x32_bf16 v[84:87], v[150:153], v[198:201], v[84:87]
	v_mfma_f32_16x16x32_bf16 v[80:83], v[158:161], v[198:201], v[80:83]
	v_mfma_f32_16x16x32_bf16 v[36:39], v[150:153], v[206:209], v[36:39]
	v_mfma_f32_16x16x32_bf16 v[24:27], v[158:161], v[206:209], v[24:27]
	s_setprio 0
	s_setprio 1
	v_mfma_f32_16x16x32_bf16 v[124:127], v[162:165], v[178:181], v[124:127]
	v_mfma_f32_16x16x32_bf16 v[112:115], v[170:173], v[178:181], v[112:115]
	v_mfma_f32_16x16x32_bf16 v[92:95], v[162:165], v[186:189], v[92:95]
	v_mfma_f32_16x16x32_bf16 v[88:91], v[170:173], v[186:189], v[88:91]
	v_mfma_f32_16x16x32_bf16 v[44:47], v[162:165], v[194:197], v[44:47]
	v_mfma_f32_16x16x32_bf16 v[40:43], v[170:173], v[194:197], v[40:43]
	v_mfma_f32_16x16x32_bf16 v[4:7], v[162:165], v[202:205], v[4:7]
	v_mfma_f32_16x16x32_bf16 v[0:3], v[170:173], v[202:205], v[0:3]
	v_mfma_f32_16x16x32_bf16 v[124:127], v[166:169], v[182:185], v[124:127]
	v_mfma_f32_16x16x32_bf16 v[112:115], v[174:177], v[182:185], v[112:115]
	v_mfma_f32_16x16x32_bf16 v[92:95], v[166:169], v[190:193], v[92:95]
	v_mfma_f32_16x16x32_bf16 v[88:91], v[174:177], v[190:193], v[88:91]
	v_mfma_f32_16x16x32_bf16 v[44:47], v[166:169], v[198:201], v[44:47]
	v_mfma_f32_16x16x32_bf16 v[40:43], v[174:177], v[198:201], v[40:43]
	v_mfma_f32_16x16x32_bf16 v[4:7], v[166:169], v[206:209], v[4:7]
	v_mfma_f32_16x16x32_bf16 v[0:3], v[174:177], v[206:209], v[0:3]
	s_barrier
	s_setprio 0
	ds_read_b128 v[146:149], v143
	ds_read_b128 v[150:153], v143 offset:1024
	ds_read_b128 v[154:157], v143 offset:2048
	ds_read_b128 v[158:161], v143 offset:3072
	ds_read_b128 v[162:165], v144
	ds_read_b128 v[166:169], v144 offset:1024
	ds_read_b128 v[170:173], v144 offset:2048
	ds_read_b128 v[174:177], v144 offset:3072
	s_add_u32 s52, s72, 0x4000
	s_addc_u32 s53, s73, 0
	s_mov_b32 m0, s21
	v_lshl_add_u64 v[214:215], s[52:53], 0, v[32:33]
	ds_read_b128 v[178:181], v142 offset:32768
	ds_read_b128 v[182:185], v142 offset:33792
	ds_read_b128 v[186:189], v142 offset:34816
	ds_read_b128 v[190:193], v142 offset:35840
	ds_read_b128 v[194:197], v142 offset:36864
	ds_read_b128 v[198:201], v142 offset:37888
	ds_read_b128 v[202:205], v142 offset:38912
	ds_read_b128 v[206:209], v142 offset:39936
	global_load_lds_dwordx4 v32, s[52:53]
	v_lshl_add_u64 v[214:215], s[52:53], 0, v[132:133]
	s_mov_b32 m0, s22
	s_nop 0
	global_load_lds_dwordx4 v132, s[52:53]
	s_waitcnt vmcnt(8) lgkmcnt(0)
	s_setprio 1
	s_barrier
	v_mfma_f32_16x16x32_bf16 v[8:11], v[146:149], v[178:181], v[8:11]
	v_mfma_f32_16x16x32_bf16 v[12:15], v[154:157], v[178:181], v[12:15]
	v_mfma_f32_16x16x32_bf16 v[60:63], v[146:149], v[186:189], v[60:63]
	v_mfma_f32_16x16x32_bf16 v[20:23], v[154:157], v[186:189], v[20:23]
	v_mfma_f32_16x16x32_bf16 v[76:79], v[146:149], v[194:197], v[76:79]
	v_mfma_f32_16x16x32_bf16 v[52:55], v[154:157], v[194:197], v[52:55]
	v_mfma_f32_16x16x32_bf16 v[128:131], v[146:149], v[202:205], v[128:131]
	v_mfma_f32_16x16x32_bf16 v[68:71], v[154:157], v[202:205], v[68:71]
	v_mfma_f32_16x16x32_bf16 v[8:11], v[150:153], v[182:185], v[8:11]
	v_mfma_f32_16x16x32_bf16 v[12:15], v[158:161], v[182:185], v[12:15]
	v_mfma_f32_16x16x32_bf16 v[60:63], v[150:153], v[190:193], v[60:63]
	v_mfma_f32_16x16x32_bf16 v[20:23], v[158:161], v[190:193], v[20:23]
	v_mfma_f32_16x16x32_bf16 v[76:79], v[150:153], v[198:201], v[76:79]
	v_mfma_f32_16x16x32_bf16 v[52:55], v[158:161], v[198:201], v[52:55]
	v_mfma_f32_16x16x32_bf16 v[128:131], v[150:153], v[206:209], v[128:131]
	v_mfma_f32_16x16x32_bf16 v[68:71], v[158:161], v[206:209], v[68:71]
	s_setprio 0
	s_setprio 1
	v_mfma_f32_16x16x32_bf16 v[28:31], v[162:165], v[178:181], v[28:31]
	v_mfma_f32_16x16x32_bf16 v[16:19], v[170:173], v[178:181], v[16:19]
	v_mfma_f32_16x16x32_bf16 v[56:59], v[162:165], v[186:189], v[56:59]
	v_mfma_f32_16x16x32_bf16 v[48:51], v[170:173], v[186:189], v[48:51]
	v_mfma_f32_16x16x32_bf16 v[72:75], v[162:165], v[194:197], v[72:75]
	v_mfma_f32_16x16x32_bf16 v[64:67], v[170:173], v[194:197], v[64:67]
	v_mfma_f32_16x16x32_bf16 v[108:111], v[162:165], v[202:205], v[108:111]
	v_mfma_f32_16x16x32_bf16 v[96:99], v[170:173], v[202:205], v[96:99]
	v_mfma_f32_16x16x32_bf16 v[28:31], v[166:169], v[182:185], v[28:31]
	v_mfma_f32_16x16x32_bf16 v[16:19], v[174:177], v[182:185], v[16:19]
	v_mfma_f32_16x16x32_bf16 v[56:59], v[166:169], v[190:193], v[56:59]
	v_mfma_f32_16x16x32_bf16 v[48:51], v[174:177], v[190:193], v[48:51]
	v_mfma_f32_16x16x32_bf16 v[72:75], v[166:169], v[198:201], v[72:75]
	v_mfma_f32_16x16x32_bf16 v[64:67], v[174:177], v[198:201], v[64:67]
	v_mfma_f32_16x16x32_bf16 v[108:111], v[166:169], v[206:209], v[108:111]
	v_mfma_f32_16x16x32_bf16 v[96:99], v[174:177], v[206:209], v[96:99]
	s_barrier
; #define PG8_WAIT_V(n) asm volatile("s_waitcnt vmcnt(" #n ")" ::: "memory")
; #define PG8_BAR __builtin_amdgcn_s_barrier()
; template <class Epi, class Sched, bool ALIGN_EPI = false, bool SP2 = false, bool A_TILED = false>
; __device__ __forceinline__ void gemm_phase(PG8_LAS unsigned char* lds, const Gemm g, const Sched& S, const Epi& E, const int wave_s) {
;     ...
;     PG8_WAIT_V(0);
;     if constexpr (!ALIGN_EPI) { if (wr == 0) PG8_BAR; }
;     PG8_BAR;
	s_setprio 0
	s_mov_b32 m0, s48
	v_lshl_add_u64 v[210:211], v[210:211], 0, s[64:65]
	s_add_u32 s52, s70, 0x200080
	ds_read_b128 v[178:181], v142 offset:49152
	ds_read_b128 v[182:185], v142 offset:50176
	ds_read_b128 v[186:189], v142 offset:51200
	ds_read_b128 v[190:193], v142 offset:52224
	ds_read_b128 v[194:197], v142 offset:53248
	ds_read_b128 v[198:201], v142 offset:54272
	ds_read_b128 v[202:205], v142 offset:55296
	ds_read_b128 v[206:209], v142 offset:56320
	global_load_lds_dwordx4 v[210:211], off
	v_lshl_add_u64 v[210:211], v[212:213], 0, s[64:65]
	s_mov_b32 m0, s49
	s_addc_u32 s53, s71, 0
	global_load_lds_dwordx4 v[210:211], off
	v_lshl_add_u64 v[210:211], s[52:53], 0, v[34:35]
	s_mov_b32 m0, s50
	s_nop 0
	global_load_lds_dwordx4 v34, s[52:53]
	v_lshl_add_u64 v[210:211], s[52:53], 0, v[134:135]
	s_mov_b32 m0, s51
	s_nop 0
	global_load_lds_dwordx4 v134, s[52:53]
	v_lshl_add_u64 v[210:211], s[68:69], 0, v[32:33]
	s_mov_b32 m0, s23
	s_nop 0
	global_load_lds_dwordx4 v32, s[68:69]
	v_lshl_add_u64 v[210:211], s[68:69], 0, v[132:133]
	s_mov_b32 m0, s36
	s_nop 0
	global_load_lds_dwordx4 v132, s[68:69]
	s_waitcnt vmcnt(8) lgkmcnt(0)
	s_setprio 1
	s_barrier
	v_mfma_f32_16x16x32_bf16 v[100:103], v[146:149], v[178:181], v[100:103]
	v_mfma_f32_16x16x32_bf16 v[104:107], v[154:157], v[178:181], v[104:107]
	v_mfma_f32_16x16x32_bf16 v[116:119], v[146:149], v[186:189], v[116:119]
	v_mfma_f32_16x16x32_bf16 v[120:123], v[154:157], v[186:189], v[120:123]
	v_mfma_f32_16x16x32_bf16 v[84:87], v[146:149], v[194:197], v[84:87]
	v_mfma_f32_16x16x32_bf16 v[80:83], v[154:157], v[194:197], v[80:83]
	v_mfma_f32_16x16x32_bf16 v[36:39], v[146:149], v[202:205], v[36:39]
	v_mfma_f32_16x16x32_bf16 v[24:27], v[154:157], v[202:205], v[24:27]
	v_mfma_f32_16x16x32_bf16 v[100:103], v[150:153], v[182:185], v[100:103]
	v_mfma_f32_16x16x32_bf16 v[104:107], v[158:161], v[182:185], v[104:107]
	v_mfma_f32_16x16x32_bf16 v[116:119], v[150:153], v[190:193], v[116:119]
	v_mfma_f32_16x16x32_bf16 v[120:123], v[158:161], v[190:193], v[120:123]
	v_mfma_f32_16x16x32_bf16 v[84:87], v[150:153], v[198:201], v[84:87]
	v_mfma_f32_16x16x32_bf16 v[80:83], v[158:161], v[198:201], v[80:83]
	v_mfma_f32_16x16x32_bf16 v[36:39], v[150:153], v[206:209], v[36:39]
	v_mfma_f32_16x16x32_bf16 v[24:27], v[158:161], v[206:209], v[24:27]
	s_setprio 0
	s_setprio 1
	v_mfma_f32_16x16x32_bf16 v[124:127], v[162:165], v[178:181], v[124:127]
	v_mfma_f32_16x16x32_bf16 v[112:115], v[170:173], v[178:181], v[112:115]
	v_mfma_f32_16x16x32_bf16 v[92:95], v[162:165], v[186:189], v[92:95]
	v_mfma_f32_16x16x32_bf16 v[88:91], v[170:173], v[186:189], v[88:91]
	v_mfma_f32_16x16x32_bf16 v[44:47], v[162:165], v[194:197], v[44:47]
	v_mfma_f32_16x16x32_bf16 v[40:43], v[170:173], v[194:197], v[40:43]
	v_mfma_f32_16x16x32_bf16 v[4:7], v[162:165], v[202:205], v[4:7]
	v_mfma_f32_16x16x32_bf16 v[0:3], v[170:173], v[202:205], v[0:3]
	v_mfma_f32_16x16x32_bf16 v[124:127], v[166:169], v[182:185], v[124:127]
	v_mfma_f32_16x16x32_bf16 v[112:115], v[174:177], v[182:185], v[112:115]
	v_mfma_f32_16x16x32_bf16 v[92:95], v[166:169], v[190:193], v[92:95]
	v_mfma_f32_16x16x32_bf16 v[88:91], v[174:177], v[190:193], v[88:91]
	v_mfma_f32_16x16x32_bf16 v[44:47], v[166:169], v[198:201], v[44:47]
	v_mfma_f32_16x16x32_bf16 v[40:43], v[174:177], v[198:201], v[40:43]
	v_mfma_f32_16x16x32_bf16 v[4:7], v[166:169], v[206:209], v[4:7]
	v_mfma_f32_16x16x32_bf16 v[0:3], v[174:177], v[206:209], v[0:3]
	s_barrier
	s_setprio 0
	s_add_i32 s41, s41, 2
	s_add_u32 s37, s37, 0x100
	s_addc_u32 s38, s38, 0
	s_add_u32 s39, s39, 0x10000
	s_addc_u32 s40, s40, 0
	v_lshl_add_u64 v[136:137], v[136:137], 0, s[66:67]
	s_cmpk_gt_u32 s41, 0x7d
	v_lshl_add_u64 v[138:139], v[138:139], 0, s[66:67]
	s_cbranch_scc0 .LBB0_1228
	s_waitcnt vmcnt(0)
	s_cmpk_lt_u32 s8, 0x100
	s_cbranch_scc0 .LBB0_1231
	s_barrier

; #define PG8_STAGE(bufoff, gbase, voff) do { _Pragma("unroll") for (int _i = 0; _i < 2; ++_i) \
;         __builtin_amdgcn_global_load_lds((const unsigned*)((const char*)(gbase) + (voff)[_i]), (PG8_LAS unsigned*)(lds + (bufoff) + ldsw + _i * 8192), 16, 0, 0); } while (0)
; #define PG8_WAIT_V(n) asm volatile("s_waitcnt vmcnt(" #n ")" ::: "memory")
; #define PG8_BAR __builtin_amdgcn_s_barrier()
; template <class Epi, class Sched, bool ALIGN_EPI = false, bool SP2 = false, bool A_TILED = false>
; __device__ __forceinline__ void gemm_phase(PG8_LAS unsigned char* lds, const Gemm g, const Sched& S, const Epi& E, const int wave_s) {
;     ...
;     if constexpr (SP2) {
;         PG8_STAGE(PG8_SB(0, 0), cB, voffB); PG8_STAGE(PG8_SB(0, 1), cB + hstep, voffB); PG8_STAGE(PG8_SA(0, 0), cA, voffA); PG8_STAGE(PG8_SA(0, 1), cA + hstepA, voffA);
;         if (wr == 1) PG8_BAR;
;         PG8_WAIT_V(2); PG8_BAR;
;         PG8_STAGE(PG8_SB(1, 0), cB + kstep, voffB); PG8_STAGE(PG8_SA(1, 0), cA + kstepA, voffA); PG8_STAGE(PG8_SB(1, 1), cB + hstep + kstep, voffB);
;         PG8_WAIT_V(6); PG8_BAR;
;     } else {
;         PG8_STAGE(PG8_SB(0, 0), cB, voffB); PG8_STAGE(PG8_SA(0, 0), cA, voffA); PG8_STAGE(PG8_SB(0, 1), cB + hstep, voffB); PG8_STAGE(PG8_SA(0, 1), cA + hstepA, voffA);
;         if (wr == 1) PG8_BAR;
;         PG8_WAIT_V(4); PG8_BAR;
;         PG8_STAGE(PG8_SB(1, 0), cB + kstep, voffB); PG8_STAGE(PG8_SA(1, 0), cA + kstepA, voffA); PG8_STAGE(PG8_SB(1, 1), cB + hstep + kstep, voffB);
;         PG8_WAIT_V(6); PG8_BAR;
;     }
.LBB0_1613:
	s_ashr_i32 s40, s86, 31
	s_sext_i32_i16 s50, s12
	s_add_u32 s12, s2, 0x22600000
	s_addc_u32 s13, s3, 0
	v_and_b32_e32 v15, 48, v14
	v_lshlrev_b32_e32 v16, 6, v14
	s_movk_i32 s3, 0x3c0
	v_lshlrev_b32_e32 v14, 2, v14
	s_mov_b64 s[60:61], 0x80
	s_and_b32 s46, s41, 3
	s_lshl_b32 s2, s42, 13
	v_and_or_b32 v15, v16, s3, v15
	v_and_b32_e32 v14, 32, v14
	s_add_i32 m0, s23, 0x18000
	v_lshl_add_u64 v[6:7], v[6:7], 0, s[60:61]
	s_lshl_b32 s41, s42, 6
	v_bitop3_b32 v16, v15, s2, v14 bitop3:0xde
	s_lshl_b32 s42, s46, 5
	s_lshl_b32 s2, s46, 12
	s_waitcnt vmcnt(2)
	s_barrier
	global_load_lds_dwordx4 v[6:7], off
	v_lshl_add_u64 v[4:5], v[4:5], 0, s[60:61]
	s_add_i32 m0, s23, 0x1a000
	s_add_i32 s43, s23, 0x8000
	s_add_i32 s44, s23, 0xa000
	v_bitop3_b32 v148, v15, s2, v14 bitop3:0xde
	global_load_lds_dwordx4 v[4:5], off
	v_lshl_add_u64 v[0:1], v[0:1], 0, s[60:61]
	s_mov_b32 m0, s43
	s_add_u32 s2, s78, 0x80080
	global_load_lds_dwordx4 v[0:1], off
	v_lshl_add_u64 v[0:1], v[2:3], 0, s[60:61]
	s_mov_b32 m0, s44
	s_addc_u32 s3, s79, 0
	global_load_lds_dwordx4 v[0:1], off
	s_add_i32 m0, s23, 0x1c000
	v_lshl_add_u64 v[0:1], s[2:3], 0, v[128:129]
	global_load_lds_dwordx4 v128, s[2:3]
	v_lshl_add_u64 v[0:1], s[2:3], 0, v[130:131]
	s_add_i32 m0, s23, 0x1e000
	s_cmpk_lt_u32 s45, 0x100
	global_load_lds_dwordx4 v130, s[2:3]
	v_lshlrev_b32_e32 v0, 15, v8
	v_and_b32_e32 v0, 0xffff0000, v0
	v_lshl_add_u32 v0, v9, 12, v0
	v_and_b32_e32 v1, 1, v8
	v_lshl_or_b32 v0, v1, 6, v0
	v_lshl_add_u32 v136, v10, 1, v0
	v_lshlrev_b32_e32 v0, 15, v12
	v_and_b32_e32 v0, 0xffff0000, v0
	s_waitcnt vmcnt(6)
	v_lshl_add_u32 v0, v11, 12, v0
	v_and_b32_e32 v1, 1, v12
	s_cselect_b64 s[62:63], -1, 0
	s_lshl_b32 s45, s46, 4
	v_mov_b32_e32 v137, 0
	v_lshl_or_b32 v0, v1, 6, v0
	s_add_i32 s46, 0, 0x10000
	s_add_i32 s47, 0, 0x14000
	v_lshl_add_u32 v138, v13, 1, v0
	v_mov_b32_e32 v139, v137
	v_add_u32_e32 v149, s46, v148
	v_add_u32_e32 v150, s47, v148
	v_add_u32_e32 v151, 0, v16
	s_mov_b64 s[64:65], 0x100
	s_mov_b64 s[66:67], 0x180
	s_mov_b32 s48, 0xc2fc0000
	s_mov_b32 s49, 0x9000
	v_mov_b32_e32 v152, 0x42800000
	v_not_b32_e32 v153, 63
	s_barrier
	s_branch .LBB0_1616

; template <class Epi, class Sched, bool ALIGN_EPI = false, bool SP2 = false, bool A_TILED = false>
; __device__ __forceinline__ void gemm_phase(PG8_LAS unsigned char* lds, const Gemm g, const Sched& S, const Epi& E, const int wave_s) {
;     ...
;     for (;;) {
;         const bool has_next = Epi::AFTER_DRAIN ? false : S.next(ui + 1, nxt);
;         const char* nA = has_next ? (const char*)g.A + (size_t)nxt.pm * tstepA : cA; const char* nB = has_next ? (const char*)g.Bt + (size_t)nxt.pn * tstep : cB;
;         constexpr bool PEEL = SP2 && !Epi::AFTER_DRAIN;
;         if constexpr (PEEL) {
;             const char* a1 = cA + kstepA; const char* a2 = cA + 2 * kstepA; const char* b2 = cB + 2 * kstep; const char* a3 = a2 + kstepA; const char* b3 = b2 + kstep;
;             PG8_ITER(PG8_MMAZ)
.LBB0_1618:
	s_ashr_i32 s71, s70, 31
	s_lshl_b64 s[52:53], s[70:71], 20
	s_add_u32 s72, s1, s52
	ds_read_b128 v[0:3], v149
	ds_read_b128 v[4:7], v149 offset:1024
	ds_read_b128 v[8:11], v149 offset:2048
	ds_read_b128 v[12:15], v149 offset:3072
	ds_read_b128 v[16:19], v150
	ds_read_b128 v[20:23], v150 offset:1024
	ds_read_b128 v[24:27], v150 offset:2048
	ds_read_b128 v[28:31], v150 offset:3072
	s_addc_u32 s73, s8, s53
	s_ashr_i32 s69, s68, 31
	s_lshl_b64 s[52:53], s[68:69], 20
	s_add_u32 s74, s9, s52
	s_addc_u32 s75, s14, s53
	s_and_b64 s[52:53], s[2:3], exec
	s_cselect_b32 s51, s73, s81
	s_cselect_b32 s52, s72, s80
	s_cselect_b32 s53, s75, s79
	s_cselect_b32 s54, s74, s78
	s_add_u32 s56, s80, 0x80080
	s_addc_u32 s57, s81, 0
	s_add_i32 s55, s23, 0xc000
	v_lshl_add_u64 v[64:65], s[56:57], 0, v[134:135]
	s_mov_b32 m0, s55
	ds_read_b128 v[32:35], v151
	ds_read_b128 v[36:39], v151 offset:1024
	ds_read_b128 v[40:43], v151 offset:2048
	ds_read_b128 v[44:47], v151 offset:3072
	ds_read_b128 v[48:51], v151 offset:4096
	ds_read_b128 v[52:55], v151 offset:5120
	ds_read_b128 v[56:59], v151 offset:6144
	ds_read_b128 v[60:63], v151 offset:7168
	global_load_lds_dwordx4 v134, s[56:57]
	v_lshl_add_u64 v[64:65], s[56:57], 0, v[132:133]
	s_add_i32 s56, s23, 0xe000
	s_mov_b32 m0, s56
	s_nop 0
	global_load_lds_dwordx4 v[64:65], off
	s_waitcnt vmcnt(8) lgkmcnt(0)
	s_setprio 1
	s_barrier
	v_mfma_f32_16x16x32_bf16 v[88:91], v[0:3], v[56:59], 0
	v_mfma_f32_16x16x32_bf16 v[64:67], v[0:3], v[32:35], 0
	v_mfma_f32_16x16x32_bf16 v[68:71], v[8:11], v[32:35], 0
	v_mfma_f32_16x16x32_bf16 v[72:75], v[0:3], v[40:43], 0
	v_mfma_f32_16x16x32_bf16 v[76:79], v[8:11], v[40:43], 0
	v_mfma_f32_16x16x32_bf16 v[80:83], v[0:3], v[48:51], 0
	v_mfma_f32_16x16x32_bf16 v[84:87], v[8:11], v[48:51], 0
	v_mfma_f32_16x16x32_bf16 v[96:99], v[4:7], v[60:63], v[88:91]
	v_mfma_f32_16x16x32_bf16 v[88:91], v[8:11], v[56:59], 0
	v_mfma_f32_16x16x32_bf16 v[64:67], v[4:7], v[36:39], v[64:67]
	v_mfma_f32_16x16x32_bf16 v[68:71], v[12:15], v[36:39], v[68:71]
	v_mfma_f32_16x16x32_bf16 v[72:75], v[4:7], v[44:47], v[72:75]
	v_mfma_f32_16x16x32_bf16 v[76:79], v[12:15], v[44:47], v[76:79]
	v_mfma_f32_16x16x32_bf16 v[80:83], v[4:7], v[52:55], v[80:83]
	v_mfma_f32_16x16x32_bf16 v[84:87], v[12:15], v[52:55], v[84:87]
	v_mfma_f32_16x16x32_bf16 v[100:103], v[12:15], v[60:63], v[88:91]
	s_setprio 0
	s_setprio 1
	v_mfma_f32_16x16x32_bf16 v[88:91], v[16:19], v[32:35], 0
	v_mfma_f32_16x16x32_bf16 v[32:35], v[24:27], v[32:35], 0
	v_mfma_f32_16x16x32_bf16 v[112:115], v[20:23], v[36:39], v[88:91]
	v_mfma_f32_16x16x32_bf16 v[32:35], v[28:31], v[36:39], v[32:35]
	v_mfma_f32_16x16x32_bf16 v[36:39], v[16:19], v[40:43], 0
	v_mfma_f32_16x16x32_bf16 v[40:43], v[24:27], v[40:43], 0
	v_mfma_f32_16x16x32_bf16 v[36:39], v[20:23], v[44:47], v[36:39]
	v_mfma_f32_16x16x32_bf16 v[40:43], v[28:31], v[44:47], v[40:43]
	v_mfma_f32_16x16x32_bf16 v[44:47], v[16:19], v[48:51], 0
	v_mfma_f32_16x16x32_bf16 v[48:51], v[24:27], v[48:51], 0
	v_mfma_f32_16x16x32_bf16 v[44:47], v[20:23], v[52:55], v[44:47]
	v_mfma_f32_16x16x32_bf16 v[48:51], v[28:31], v[52:55], v[48:51]
	v_mfma_f32_16x16x32_bf16 v[52:55], v[16:19], v[56:59], 0
	v_mfma_f32_16x16x32_bf16 v[56:59], v[24:27], v[56:59], 0
	v_mfma_f32_16x16x32_bf16 v[52:55], v[20:23], v[60:63], v[52:55]
	v_mfma_f32_16x16x32_bf16 v[56:59], v[28:31], v[60:63], v[56:59]
	s_barrier
	s_setprio 0
	s_add_i32 s57, s46, s15
	v_lshl_add_u64 v[250:251], s[78:79], 0, v[128:129]
	s_add_i32 s58, s57, 0x2000
	v_lshl_add_u64 v[144:145], v[250:251], 0, s[64:65]
	s_mov_b32 m0, s57
	v_lshl_add_u64 v[252:253], s[78:79], 0, v[130:131]
	s_add_u32 s82, s78, 0x80100
	ds_read_b128 v[60:63], v151 offset:16384
	ds_read_b128 v[88:91], v151 offset:17408
	ds_read_b128 v[92:95], v151 offset:18432
	ds_read_b128 v[104:107], v151 offset:19456
	ds_read_b128 v[108:111], v151 offset:20480
	ds_read_b128 v[116:119], v151 offset:21504
	ds_read_b128 v[120:123], v151 offset:22528
	ds_read_b128 v[124:127], v151 offset:23552
	global_load_lds_dwordx4 v[144:145], off
	v_lshl_add_u64 v[144:145], v[252:253], 0, s[64:65]
	s_mov_b32 m0, s58
	s_addc_u32 s83, s79, 0
	s_add_i32 s59, s47, s15
	global_load_lds_dwordx4 v[144:145], off
	v_lshl_add_u64 v[144:145], s[82:83], 0, v[128:129]
	s_mov_b32 m0, s59
	s_add_i32 s69, s59, 0x2000
	global_load_lds_dwordx4 v128, s[82:83]
	v_lshl_add_u64 v[144:145], s[82:83], 0, v[130:131]
	s_mov_b32 m0, s69
	v_lshl_add_u64 v[140:141], s[80:81], 0, v[134:135]
	global_load_lds_dwordx4 v130, s[82:83]
	v_lshl_add_u64 v[144:145], v[140:141], 0, s[64:65]
	s_mov_b32 m0, s23
	v_lshl_add_u64 v[142:143], s[80:81], 0, v[132:133]
	global_load_lds_dwordx4 v[144:145], off
	v_lshl_add_u64 v[144:145], v[142:143], 0, s[64:65]
	s_mov_b32 m0, s36
	s_nop 0
	global_load_lds_dwordx4 v[144:145], off
	s_waitcnt vmcnt(8) lgkmcnt(0)
	s_setprio 1
	s_barrier
	v_mfma_f32_16x16x32_bf16 v[144:147], v[0:3], v[60:63], 0
	v_mfma_f32_16x16x32_bf16 v[154:157], v[4:7], v[88:91], v[144:147]
	v_mfma_f32_16x16x32_bf16 v[144:147], v[8:11], v[60:63], 0
	v_mfma_f32_16x16x32_bf16 v[158:161], v[12:15], v[88:91], v[144:147]
	v_mfma_f32_16x16x32_bf16 v[144:147], v[0:3], v[92:95], 0
	v_mfma_f32_16x16x32_bf16 v[162:165], v[4:7], v[104:107], v[144:147]
	v_mfma_f32_16x16x32_bf16 v[144:147], v[8:11], v[92:95], 0
	v_mfma_f32_16x16x32_bf16 v[166:169], v[12:15], v[104:107], v[144:147]
	v_mfma_f32_16x16x32_bf16 v[144:147], v[0:3], v[108:111], 0
	v_mfma_f32_16x16x32_bf16 v[0:3], v[0:3], v[120:123], 0
	v_mfma_f32_16x16x32_bf16 v[170:173], v[4:7], v[116:119], v[144:147]
	v_mfma_f32_16x16x32_bf16 v[0:3], v[4:7], v[124:127], v[0:3]
	v_mfma_f32_16x16x32_bf16 v[4:7], v[8:11], v[120:123], 0
	v_mfma_f32_16x16x32_bf16 v[144:147], v[8:11], v[108:111], 0
	v_mfma_f32_16x16x32_bf16 v[4:7], v[12:15], v[124:127], v[4:7]
	v_mfma_f32_16x16x32_bf16 v[174:177], v[12:15], v[116:119], v[144:147]
	s_setprio 0
	s_setprio 1
	v_mfma_f32_16x16x32_bf16 v[8:11], v[16:19], v[60:63], 0
	v_mfma_f32_16x16x32_bf16 v[178:181], v[20:23], v[88:91], v[8:11]
	v_mfma_f32_16x16x32_bf16 v[8:11], v[24:27], v[60:63], 0
	v_mfma_f32_16x16x32_bf16 v[182:185], v[28:31], v[88:91], v[8:11]
	v_mfma_f32_16x16x32_bf16 v[8:11], v[16:19], v[92:95], 0
	v_mfma_f32_16x16x32_bf16 v[186:189], v[20:23], v[104:107], v[8:11]
	v_mfma_f32_16x16x32_bf16 v[8:11], v[24:27], v[92:95], 0
	v_mfma_f32_16x16x32_bf16 v[190:193], v[28:31], v[104:107], v[8:11]
	v_mfma_f32_16x16x32_bf16 v[8:11], v[16:19], v[108:111], 0
	v_mfma_f32_16x16x32_bf16 v[194:197], v[20:23], v[116:119], v[8:11]
	v_mfma_f32_16x16x32_bf16 v[8:11], v[24:27], v[108:111], 0
	v_mfma_f32_16x16x32_bf16 v[198:201], v[28:31], v[116:119], v[8:11]
	v_mfma_f32_16x16x32_bf16 v[8:11], v[16:19], v[120:123], 0
	v_mfma_f32_16x16x32_bf16 v[202:205], v[20:23], v[124:127], v[8:11]
	v_mfma_f32_16x16x32_bf16 v[8:11], v[24:27], v[120:123], 0
	v_mfma_f32_16x16x32_bf16 v[206:209], v[28:31], v[124:127], v[8:11]
	s_barrier
	s_setprio 0
	s_add_i32 s71, 0, 0x18000
	s_add_i32 s88, 0, 0x1c000
	v_add_u32_e32 v144, s71, v148
	v_add_u32_e32 v145, s88, v148
	s_nop 0
	ds_read_b128 v[8:11], v144
	ds_read_b128 v[12:15], v144 offset:1024
	ds_read_b128 v[16:19], v144 offset:2048
	ds_read_b128 v[20:23], v144 offset:3072
	ds_read_b128 v[210:213], v145
	ds_read_b128 v[214:217], v145 offset:1024
	ds_read_b128 v[218:221], v145 offset:2048
	ds_read_b128 v[222:225], v145 offset:3072
	s_add_u32 s82, s80, 0x80100
	s_addc_u32 s83, s81, 0
	s_mov_b32 m0, s37
	v_lshl_add_u64 v[88:89], s[82:83], 0, v[134:135]
	ds_read_b128 v[24:27], v151 offset:32768
	ds_read_b128 v[28:31], v151 offset:33792
	ds_read_b128 v[60:63], v151 offset:34816
	ds_read_b128 v[226:229], v151 offset:35840
	ds_read_b128 v[230:233], v151 offset:36864
	ds_read_b128 v[234:237], v151 offset:37888
	ds_read_b128 v[238:241], v151 offset:38912
	ds_read_b128 v[242:245], v151 offset:39936
	global_load_lds_dwordx4 v134, s[82:83]
	v_lshl_add_u64 v[88:89], s[82:83], 0, v[132:133]
	s_mov_b32 m0, s38
	s_nop 0
	global_load_lds_dwordx4 v132, s[82:83]
	s_waitcnt vmcnt(8) lgkmcnt(0)
	s_setprio 1
	s_barrier
	v_mfma_f32_16x16x32_bf16 v[64:67], v[8:11], v[24:27], v[64:67]
	v_mfma_f32_16x16x32_bf16 v[124:127], v[12:15], v[28:31], v[64:67]
	v_mfma_f32_16x16x32_bf16 v[64:67], v[16:19], v[24:27], v[68:71]
	v_mfma_f32_16x16x32_bf16 v[120:123], v[20:23], v[28:31], v[64:67]
	v_mfma_f32_16x16x32_bf16 v[64:67], v[8:11], v[60:63], v[72:75]
	v_mfma_f32_16x16x32_bf16 v[108:111], v[12:15], v[226:229], v[64:67]
	v_mfma_f32_16x16x32_bf16 v[64:67], v[16:19], v[60:63], v[76:79]
	v_mfma_f32_16x16x32_bf16 v[104:107], v[20:23], v[226:229], v[64:67]
	v_mfma_f32_16x16x32_bf16 v[64:67], v[8:11], v[230:233], v[80:83]
	v_mfma_f32_16x16x32_bf16 v[92:95], v[12:15], v[234:237], v[64:67]
	v_mfma_f32_16x16x32_bf16 v[64:67], v[16:19], v[230:233], v[84:87]
	v_mfma_f32_16x16x32_bf16 v[88:91], v[20:23], v[234:237], v[64:67]
	v_mfma_f32_16x16x32_bf16 v[64:67], v[8:11], v[238:241], v[96:99]
	v_mfma_f32_16x16x32_bf16 v[76:79], v[12:15], v[242:245], v[64:67]
	v_mfma_f32_16x16x32_bf16 v[64:67], v[16:19], v[238:241], v[100:103]
	v_mfma_f32_16x16x32_bf16 v[72:75], v[20:23], v[242:245], v[64:67]
	s_setprio 0
	s_setprio 1
	v_mfma_f32_16x16x32_bf16 v[64:67], v[210:213], v[24:27], v[112:115]
	v_mfma_f32_16x16x32_bf16 v[24:27], v[218:221], v[24:27], v[32:35]
	v_mfma_f32_16x16x32_bf16 v[112:115], v[222:225], v[28:31], v[24:27]
	v_mfma_f32_16x16x32_bf16 v[24:27], v[210:213], v[60:63], v[36:39]
	v_mfma_f32_16x16x32_bf16 v[100:103], v[214:217], v[226:229], v[24:27]
	v_mfma_f32_16x16x32_bf16 v[24:27], v[218:221], v[60:63], v[40:43]
	v_mfma_f32_16x16x32_bf16 v[96:99], v[222:225], v[226:229], v[24:27]
	v_mfma_f32_16x16x32_bf16 v[24:27], v[210:213], v[230:233], v[44:47]
	v_mfma_f32_16x16x32_bf16 v[84:87], v[214:217], v[234:237], v[24:27]
	v_mfma_f32_16x16x32_bf16 v[24:27], v[218:221], v[230:233], v[48:51]
	v_mfma_f32_16x16x32_bf16 v[80:83], v[222:225], v[234:237], v[24:27]
	v_mfma_f32_16x16x32_bf16 v[24:27], v[210:213], v[238:241], v[52:55]
	v_mfma_f32_16x16x32_bf16 v[68:71], v[214:217], v[242:245], v[24:27]
	v_mfma_f32_16x16x32_bf16 v[24:27], v[218:221], v[238:241], v[56:59]
	v_mfma_f32_16x16x32_bf16 v[116:119], v[214:217], v[28:31], v[64:67]
	v_mfma_f32_16x16x32_bf16 v[64:67], v[222:225], v[242:245], v[24:27]
	s_barrier
; #define PG8_MMA(ai, bj, At, Bt) do { __builtin_amdgcn_s_setprio(1); _Pragma("unroll") for (int m = 0; m < 4; ++m) _Pragma("unroll") for (int n = 0; n < 2; ++n) _Pragma("unroll") for (int k = 0; k < 2; ++k) \
;         acc[ai][bj][m][n] = __builtin_amdgcn_mfma_f32_16x16x32_bf16(Bt[n][k], At[m][k], acc[ai][bj][m][n], 0, 0, 0); __builtin_amdgcn_s_setprio(0); } while (0)
; template <class Epi, class Sched, bool ALIGN_EPI = false, bool SP2 = false, bool A_TILED = false>
; __device__ __forceinline__ void gemm_phase(PG8_LAS unsigned char* lds, const Gemm g, const Sched& S, const Epi& E, const int wave_s) {
;     ...
;         for (int t = PEEL ? 2 : 0; t < nt; t += 2) {
;             const bool last = (t == nt - 2);
;             const char* a1 = cA + (size_t)(t + 1) * kstepA;
;             const char* a2 = last ? nA : cA + (size_t)(t + 2) * kstepA; const char* b2 = last ? nB : cB + (size_t)(t + 2) * kstep;
;             const char* a3 = a2 + kstepA; const char* b3 = b2 + kstep;
;             if (last && has_next) S.a_ready(nxt);
;             if constexpr (SP2) {
;             PG8_ITER(PG8_MMA)
	s_setprio 0
	s_add_i32 s71, s71, s15
	s_add_i32 s77, s71, 0x2000
	s_nop 1
	v_lshl_add_u64 v[24:25], v[250:251], 0, s[66:67]
	s_mov_b32 m0, s71
	s_add_u32 s82, s78, 0x80180
	ds_read_b128 v[32:35], v151 offset:49152
	ds_read_b128 v[36:39], v151 offset:50176
	ds_read_b128 v[226:229], v151 offset:51200
	ds_read_b128 v[230:233], v151 offset:52224
	ds_read_b128 v[234:237], v151 offset:53248
	ds_read_b128 v[238:241], v151 offset:54272
	ds_read_b128 v[242:245], v151 offset:55296
	ds_read_b128 v[246:249], v151 offset:56320
	global_load_lds_dwordx4 v[24:25], off
	v_lshl_add_u64 v[24:25], v[252:253], 0, s[66:67]
	s_mov_b32 m0, s77
	s_addc_u32 s83, s79, 0
	s_add_i32 s88, s88, s15
	global_load_lds_dwordx4 v[24:25], off
	v_lshl_add_u64 v[24:25], s[82:83], 0, v[128:129]
	s_mov_b32 m0, s88
	s_add_i32 s89, s88, 0x2000
	global_load_lds_dwordx4 v128, s[82:83]
	v_lshl_add_u64 v[24:25], s[82:83], 0, v[130:131]
	s_mov_b32 m0, s89
	s_nop 0
	global_load_lds_dwordx4 v130, s[82:83]
	v_lshl_add_u64 v[24:25], v[140:141], 0, s[66:67]
	s_mov_b32 m0, s43
	s_nop 0
	global_load_lds_dwordx4 v[24:25], off
	v_lshl_add_u64 v[24:25], v[142:143], 0, s[66:67]
	s_mov_b32 m0, s44
	s_nop 0
	global_load_lds_dwordx4 v[24:25], off
	s_waitcnt vmcnt(8) lgkmcnt(0)
	s_setprio 1
	s_barrier
	v_mfma_f32_16x16x32_bf16 v[24:27], v[8:11], v[32:35], v[154:157]
	v_mfma_f32_16x16x32_bf16 v[60:63], v[12:15], v[36:39], v[24:27]
	v_mfma_f32_16x16x32_bf16 v[24:27], v[16:19], v[32:35], v[158:161]
	v_mfma_f32_16x16x32_bf16 v[56:59], v[20:23], v[36:39], v[24:27]
	v_mfma_f32_16x16x32_bf16 v[24:27], v[8:11], v[226:229], v[162:165]
	v_mfma_f32_16x16x32_bf16 v[44:47], v[12:15], v[230:233], v[24:27]
	v_mfma_f32_16x16x32_bf16 v[24:27], v[16:19], v[226:229], v[166:169]
	v_mfma_f32_16x16x32_bf16 v[40:43], v[20:23], v[230:233], v[24:27]
	v_mfma_f32_16x16x32_bf16 v[24:27], v[8:11], v[234:237], v[170:173]
	v_mfma_f32_16x16x32_bf16 v[0:3], v[8:11], v[242:245], v[0:3]
	v_mfma_f32_16x16x32_bf16 v[28:31], v[12:15], v[238:241], v[24:27]
	v_mfma_f32_16x16x32_bf16 v[24:27], v[16:19], v[234:237], v[174:177]
	v_mfma_f32_16x16x32_bf16 v[12:15], v[12:15], v[246:249], v[0:3]
	v_mfma_f32_16x16x32_bf16 v[0:3], v[16:19], v[242:245], v[4:7]
	v_mfma_f32_16x16x32_bf16 v[24:27], v[20:23], v[238:241], v[24:27]
	v_mfma_f32_16x16x32_bf16 v[8:11], v[20:23], v[246:249], v[0:3]
	s_setprio 0
	s_setprio 1
	v_mfma_f32_16x16x32_bf16 v[0:3], v[210:213], v[32:35], v[178:181]
	v_mfma_f32_16x16x32_bf16 v[52:55], v[214:217], v[36:39], v[0:3]
	v_mfma_f32_16x16x32_bf16 v[0:3], v[218:221], v[32:35], v[182:185]
	v_mfma_f32_16x16x32_bf16 v[48:51], v[222:225], v[36:39], v[0:3]
	v_mfma_f32_16x16x32_bf16 v[0:3], v[210:213], v[226:229], v[186:189]
	v_mfma_f32_16x16x32_bf16 v[36:39], v[214:217], v[230:233], v[0:3]
	v_mfma_f32_16x16x32_bf16 v[0:3], v[218:221], v[226:229], v[190:193]
	v_mfma_f32_16x16x32_bf16 v[32:35], v[222:225], v[230:233], v[0:3]
	v_mfma_f32_16x16x32_bf16 v[0:3], v[210:213], v[234:237], v[194:197]
	v_mfma_f32_16x16x32_bf16 v[20:23], v[214:217], v[238:241], v[0:3]
	v_mfma_f32_16x16x32_bf16 v[0:3], v[218:221], v[234:237], v[198:201]
	v_mfma_f32_16x16x32_bf16 v[16:19], v[222:225], v[238:241], v[0:3]
	v_mfma_f32_16x16x32_bf16 v[0:3], v[210:213], v[242:245], v[202:205]
	v_mfma_f32_16x16x32_bf16 v[4:7], v[214:217], v[246:249], v[0:3]
	v_mfma_f32_16x16x32_bf16 v[0:3], v[218:221], v[242:245], v[206:209]
	v_mfma_f32_16x16x32_bf16 v[0:3], v[222:225], v[246:249], v[0:3]
	s_barrier
	s_setprio 0
	s_add_u32 s90, s78, 0x200
	s_addc_u32 s85, s79, 0
	s_add_u32 s78, s80, 0x80180
	s_addc_u32 s79, s81, 0
	s_mov_b32 s91, 0
.LBB0_1619:
	ds_read_b128 v[154:157], v149
	ds_read_b128 v[158:161], v149 offset:1024
	ds_read_b128 v[162:165], v149 offset:2048
	ds_read_b128 v[166:169], v149 offset:3072
	ds_read_b128 v[170:173], v150
	ds_read_b128 v[174:177], v150 offset:1024
	ds_read_b128 v[178:181], v150 offset:2048
	ds_read_b128 v[182:185], v150 offset:3072
	s_add_u32 s80, s78, 0xfff80080
	s_addc_u32 s81, s79, -1
	s_cmp_eq_u32 s91, 28
	s_cselect_b32 s83, s51, s81
	s_cselect_b32 s82, s52, s80
	s_cselect_b32 s81, s53, s85
	s_cselect_b32 s80, s54, s90
	s_mov_b32 m0, s55
	v_lshl_add_u64 v[140:141], s[78:79], 0, v[138:139]
	ds_read_b128 v[186:189], v151
	ds_read_b128 v[190:193], v151 offset:1024
	ds_read_b128 v[194:197], v151 offset:2048
	ds_read_b128 v[198:201], v151 offset:3072
	ds_read_b128 v[202:205], v151 offset:4096
	ds_read_b128 v[206:209], v151 offset:5120
	ds_read_b128 v[210:213], v151 offset:6144
	ds_read_b128 v[214:217], v151 offset:7168
	global_load_lds_dwordx4 v138, s[78:79]
	v_lshl_add_u64 v[140:141], s[78:79], 0, v[136:137]
	s_mov_b32 m0, s56
	s_nop 0
	global_load_lds_dwordx4 v136, s[78:79]
	s_waitcnt vmcnt(8) lgkmcnt(0)
	s_setprio 1
	s_barrier
	v_mfma_f32_16x16x32_bf16 v[124:127], v[154:157], v[186:189], v[124:127]
	v_mfma_f32_16x16x32_bf16 v[120:123], v[162:165], v[186:189], v[120:123]
	v_mfma_f32_16x16x32_bf16 v[108:111], v[154:157], v[194:197], v[108:111]
	v_mfma_f32_16x16x32_bf16 v[104:107], v[162:165], v[194:197], v[104:107]
	v_mfma_f32_16x16x32_bf16 v[92:95], v[154:157], v[202:205], v[92:95]
	v_mfma_f32_16x16x32_bf16 v[88:91], v[162:165], v[202:205], v[88:91]
	v_mfma_f32_16x16x32_bf16 v[76:79], v[154:157], v[210:213], v[76:79]
	v_mfma_f32_16x16x32_bf16 v[72:75], v[162:165], v[210:213], v[72:75]
	v_mfma_f32_16x16x32_bf16 v[124:127], v[158:161], v[190:193], v[124:127]
	v_mfma_f32_16x16x32_bf16 v[120:123], v[166:169], v[190:193], v[120:123]
	v_mfma_f32_16x16x32_bf16 v[108:111], v[158:161], v[198:201], v[108:111]
	v_mfma_f32_16x16x32_bf16 v[104:107], v[166:169], v[198:201], v[104:107]
	v_mfma_f32_16x16x32_bf16 v[92:95], v[158:161], v[206:209], v[92:95]
	v_mfma_f32_16x16x32_bf16 v[88:91], v[166:169], v[206:209], v[88:91]
	v_mfma_f32_16x16x32_bf16 v[76:79], v[158:161], v[214:217], v[76:79]
	v_mfma_f32_16x16x32_bf16 v[72:75], v[166:169], v[214:217], v[72:75]
	s_setprio 0
	s_setprio 1
	v_mfma_f32_16x16x32_bf16 v[116:119], v[170:173], v[186:189], v[116:119]
	v_mfma_f32_16x16x32_bf16 v[112:115], v[178:181], v[186:189], v[112:115]
	v_mfma_f32_16x16x32_bf16 v[100:103], v[170:173], v[194:197], v[100:103]
	v_mfma_f32_16x16x32_bf16 v[96:99], v[178:181], v[194:197], v[96:99]
	v_mfma_f32_16x16x32_bf16 v[84:87], v[170:173], v[202:205], v[84:87]
	v_mfma_f32_16x16x32_bf16 v[80:83], v[178:181], v[202:205], v[80:83]
	v_mfma_f32_16x16x32_bf16 v[68:71], v[170:173], v[210:213], v[68:71]
	v_mfma_f32_16x16x32_bf16 v[64:67], v[178:181], v[210:213], v[64:67]
	v_mfma_f32_16x16x32_bf16 v[116:119], v[174:177], v[190:193], v[116:119]
	v_mfma_f32_16x16x32_bf16 v[112:115], v[182:185], v[190:193], v[112:115]
	v_mfma_f32_16x16x32_bf16 v[100:103], v[174:177], v[198:201], v[100:103]
	v_mfma_f32_16x16x32_bf16 v[96:99], v[182:185], v[198:201], v[96:99]
	v_mfma_f32_16x16x32_bf16 v[84:87], v[174:177], v[206:209], v[84:87]
	v_mfma_f32_16x16x32_bf16 v[80:83], v[182:185], v[206:209], v[80:83]
	v_mfma_f32_16x16x32_bf16 v[68:71], v[174:177], v[214:217], v[68:71]
	v_mfma_f32_16x16x32_bf16 v[64:67], v[182:185], v[214:217], v[64:67]
	s_barrier
	s_setprio 0
	s_mov_b32 m0, s57
	v_lshl_add_u64 v[140:141], s[80:81], 0, v[128:129]
	s_add_u32 s94, s80, 0x80000
	ds_read_b128 v[186:189], v151 offset:16384
	ds_read_b128 v[190:193], v151 offset:17408
	ds_read_b128 v[194:197], v151 offset:18432
	ds_read_b128 v[198:201], v151 offset:19456
	ds_read_b128 v[202:205], v151 offset:20480
	ds_read_b128 v[206:209], v151 offset:21504
	ds_read_b128 v[210:213], v151 offset:22528
	ds_read_b128 v[214:217], v151 offset:23552
	global_load_lds_dwordx4 v128, s[80:81]
	v_lshl_add_u64 v[142:143], s[80:81], 0, v[130:131]
	s_mov_b32 m0, s58
	s_addc_u32 s95, s81, 0
	global_load_lds_dwordx4 v130, s[80:81]
	v_lshl_add_u64 v[146:147], s[94:95], 0, v[128:129]
	s_mov_b32 m0, s59
	v_lshl_add_u64 v[218:219], s[82:83], 0, v[132:133]
	global_load_lds_dwordx4 v128, s[94:95]
	v_lshl_add_u64 v[146:147], s[94:95], 0, v[130:131]
	s_mov_b32 m0, s69
	s_nop 0
	global_load_lds_dwordx4 v130, s[94:95]
	v_lshl_add_u64 v[146:147], s[82:83], 0, v[134:135]
	s_mov_b32 m0, s23
	s_nop 0
	global_load_lds_dwordx4 v134, s[82:83]
	s_mov_b32 m0, s36
	s_nop 0
	global_load_lds_dwordx4 v132, s[82:83]
	s_waitcnt vmcnt(8) lgkmcnt(0)
	s_setprio 1
	s_barrier
	v_mfma_f32_16x16x32_bf16 v[60:63], v[154:157], v[186:189], v[60:63]
	v_mfma_f32_16x16x32_bf16 v[56:59], v[162:165], v[186:189], v[56:59]
	v_mfma_f32_16x16x32_bf16 v[44:47], v[154:157], v[194:197], v[44:47]
	v_mfma_f32_16x16x32_bf16 v[40:43], v[162:165], v[194:197], v[40:43]
	v_mfma_f32_16x16x32_bf16 v[28:31], v[154:157], v[202:205], v[28:31]
	v_mfma_f32_16x16x32_bf16 v[24:27], v[162:165], v[202:205], v[24:27]
	v_mfma_f32_16x16x32_bf16 v[12:15], v[154:157], v[210:213], v[12:15]
	v_mfma_f32_16x16x32_bf16 v[8:11], v[162:165], v[210:213], v[8:11]
	v_mfma_f32_16x16x32_bf16 v[60:63], v[158:161], v[190:193], v[60:63]
	v_mfma_f32_16x16x32_bf16 v[56:59], v[166:169], v[190:193], v[56:59]
	v_mfma_f32_16x16x32_bf16 v[44:47], v[158:161], v[198:201], v[44:47]
	v_mfma_f32_16x16x32_bf16 v[40:43], v[166:169], v[198:201], v[40:43]
	v_mfma_f32_16x16x32_bf16 v[28:31], v[158:161], v[206:209], v[28:31]
	v_mfma_f32_16x16x32_bf16 v[24:27], v[166:169], v[206:209], v[24:27]
	v_mfma_f32_16x16x32_bf16 v[12:15], v[158:161], v[214:217], v[12:15]
	v_mfma_f32_16x16x32_bf16 v[8:11], v[166:169], v[214:217], v[8:11]
	s_setprio 0
	s_setprio 1
	v_mfma_f32_16x16x32_bf16 v[52:55], v[170:173], v[186:189], v[52:55]
	v_mfma_f32_16x16x32_bf16 v[48:51], v[178:181], v[186:189], v[48:51]
	v_mfma_f32_16x16x32_bf16 v[36:39], v[170:173], v[194:197], v[36:39]
	v_mfma_f32_16x16x32_bf16 v[32:35], v[178:181], v[194:197], v[32:35]
	v_mfma_f32_16x16x32_bf16 v[20:23], v[170:173], v[202:205], v[20:23]
	v_mfma_f32_16x16x32_bf16 v[16:19], v[178:181], v[202:205], v[16:19]
	v_mfma_f32_16x16x32_bf16 v[4:7], v[170:173], v[210:213], v[4:7]
	v_mfma_f32_16x16x32_bf16 v[0:3], v[178:181], v[210:213], v[0:3]
	v_mfma_f32_16x16x32_bf16 v[52:55], v[174:177], v[190:193], v[52:55]
	v_mfma_f32_16x16x32_bf16 v[48:51], v[182:185], v[190:193], v[48:51]
	v_mfma_f32_16x16x32_bf16 v[36:39], v[174:177], v[198:201], v[36:39]
	v_mfma_f32_16x16x32_bf16 v[32:35], v[182:185], v[198:201], v[32:35]
	v_mfma_f32_16x16x32_bf16 v[20:23], v[174:177], v[206:209], v[20:23]
	v_mfma_f32_16x16x32_bf16 v[16:19], v[182:185], v[206:209], v[16:19]
	v_mfma_f32_16x16x32_bf16 v[4:7], v[174:177], v[214:217], v[4:7]
	v_mfma_f32_16x16x32_bf16 v[0:3], v[182:185], v[214:217], v[0:3]
	s_barrier
; #define PG8_MMA(ai, bj, At, Bt) do { __builtin_amdgcn_s_setprio(1); _Pragma("unroll") for (int m = 0; m < 4; ++m) _Pragma("unroll") for (int n = 0; n < 2; ++n) _Pragma("unroll") for (int k = 0; k < 2; ++k) \
;         acc[ai][bj][m][n] = __builtin_amdgcn_mfma_f32_16x16x32_bf16(Bt[n][k], At[m][k], acc[ai][bj][m][n], 0, 0, 0); __builtin_amdgcn_s_setprio(0); } while (0)
; template <class Epi, class Sched, bool ALIGN_EPI = false, bool SP2 = false, bool A_TILED = false>
; __device__ __forceinline__ void gemm_phase(PG8_LAS unsigned char* lds, const Gemm g, const Sched& S, const Epi& E, const int wave_s) {
;     ...
;         for (int t = PEEL ? 2 : 0; t < nt; t += 2) {
;             const bool last = (t == nt - 2);
;             const char* a1 = cA + (size_t)(t + 1) * kstepA;
;             const char* a2 = last ? nA : cA + (size_t)(t + 2) * kstepA; const char* b2 = last ? nB : cB + (size_t)(t + 2) * kstep;
;             const char* a3 = a2 + kstepA; const char* b3 = b2 + kstep;
;             if (last && has_next) S.a_ready(nxt);
;             if constexpr (SP2) {
;             PG8_ITER(PG8_MMA)
	s_setprio 0
	ds_read_b128 v[154:157], v144
	ds_read_b128 v[158:161], v144 offset:1024
	ds_read_b128 v[162:165], v144 offset:2048
	ds_read_b128 v[166:169], v144 offset:3072
	ds_read_b128 v[170:173], v145
	ds_read_b128 v[174:177], v145 offset:1024
	ds_read_b128 v[178:181], v145 offset:2048
	ds_read_b128 v[182:185], v145 offset:3072
	s_add_u32 s82, s82, 0x80000
	s_addc_u32 s83, s83, 0
	s_mov_b32 m0, s37
	v_lshl_add_u64 v[220:221], s[82:83], 0, v[134:135]
	ds_read_b128 v[186:189], v151 offset:32768
	ds_read_b128 v[190:193], v151 offset:33792
	ds_read_b128 v[194:197], v151 offset:34816
	ds_read_b128 v[198:201], v151 offset:35840
	ds_read_b128 v[202:205], v151 offset:36864
	ds_read_b128 v[206:209], v151 offset:37888
	ds_read_b128 v[210:213], v151 offset:38912
	ds_read_b128 v[214:217], v151 offset:39936
	global_load_lds_dwordx4 v134, s[82:83]
	v_lshl_add_u64 v[220:221], s[82:83], 0, v[132:133]
	s_mov_b32 m0, s38
	s_nop 0
	global_load_lds_dwordx4 v132, s[82:83]
	s_waitcnt vmcnt(8) lgkmcnt(0)
	s_setprio 1
	s_barrier
	v_mfma_f32_16x16x32_bf16 v[124:127], v[154:157], v[186:189], v[124:127]
	v_mfma_f32_16x16x32_bf16 v[120:123], v[162:165], v[186:189], v[120:123]
	v_mfma_f32_16x16x32_bf16 v[108:111], v[154:157], v[194:197], v[108:111]
	v_mfma_f32_16x16x32_bf16 v[104:107], v[162:165], v[194:197], v[104:107]
	v_mfma_f32_16x16x32_bf16 v[92:95], v[154:157], v[202:205], v[92:95]
	v_mfma_f32_16x16x32_bf16 v[88:91], v[162:165], v[202:205], v[88:91]
	v_mfma_f32_16x16x32_bf16 v[76:79], v[154:157], v[210:213], v[76:79]
	v_mfma_f32_16x16x32_bf16 v[72:75], v[162:165], v[210:213], v[72:75]
	v_mfma_f32_16x16x32_bf16 v[124:127], v[158:161], v[190:193], v[124:127]
	v_mfma_f32_16x16x32_bf16 v[120:123], v[166:169], v[190:193], v[120:123]
	v_mfma_f32_16x16x32_bf16 v[108:111], v[158:161], v[198:201], v[108:111]
	v_mfma_f32_16x16x32_bf16 v[104:107], v[166:169], v[198:201], v[104:107]
	v_mfma_f32_16x16x32_bf16 v[92:95], v[158:161], v[206:209], v[92:95]
	v_mfma_f32_16x16x32_bf16 v[88:91], v[166:169], v[206:209], v[88:91]
	v_mfma_f32_16x16x32_bf16 v[76:79], v[158:161], v[214:217], v[76:79]
	v_mfma_f32_16x16x32_bf16 v[72:75], v[166:169], v[214:217], v[72:75]
	s_setprio 0
	s_setprio 1
	v_mfma_f32_16x16x32_bf16 v[116:119], v[170:173], v[186:189], v[116:119]
	v_mfma_f32_16x16x32_bf16 v[112:115], v[178:181], v[186:189], v[112:115]
	v_mfma_f32_16x16x32_bf16 v[100:103], v[170:173], v[194:197], v[100:103]
	v_mfma_f32_16x16x32_bf16 v[96:99], v[178:181], v[194:197], v[96:99]
	v_mfma_f32_16x16x32_bf16 v[84:87], v[170:173], v[202:205], v[84:87]
	v_mfma_f32_16x16x32_bf16 v[80:83], v[178:181], v[202:205], v[80:83]
	v_mfma_f32_16x16x32_bf16 v[68:71], v[170:173], v[210:213], v[68:71]
	v_mfma_f32_16x16x32_bf16 v[64:67], v[178:181], v[210:213], v[64:67]
	v_mfma_f32_16x16x32_bf16 v[116:119], v[174:177], v[190:193], v[116:119]
	v_mfma_f32_16x16x32_bf16 v[112:115], v[182:185], v[190:193], v[112:115]
	v_mfma_f32_16x16x32_bf16 v[100:103], v[174:177], v[198:201], v[100:103]
	v_mfma_f32_16x16x32_bf16 v[96:99], v[182:185], v[198:201], v[96:99]
	v_mfma_f32_16x16x32_bf16 v[84:87], v[174:177], v[206:209], v[84:87]
	v_mfma_f32_16x16x32_bf16 v[80:83], v[182:185], v[206:209], v[80:83]
	v_mfma_f32_16x16x32_bf16 v[68:71], v[174:177], v[214:217], v[68:71]
	v_mfma_f32_16x16x32_bf16 v[64:67], v[182:185], v[214:217], v[64:67]
	s_barrier
	s_setprio 0
	s_mov_b32 m0, s71
	v_lshl_add_u64 v[140:141], v[140:141], 0, s[60:61]
	s_add_u32 s80, s80, 0x80080
	ds_read_b128 v[186:189], v151 offset:49152
	ds_read_b128 v[190:193], v151 offset:50176
	ds_read_b128 v[194:197], v151 offset:51200
	ds_read_b128 v[198:201], v151 offset:52224
	ds_read_b128 v[202:205], v151 offset:53248
	ds_read_b128 v[206:209], v151 offset:54272
	ds_read_b128 v[210:213], v151 offset:55296
	ds_read_b128 v[214:217], v151 offset:56320
	global_load_lds_dwordx4 v[140:141], off
	v_lshl_add_u64 v[140:141], v[142:143], 0, s[60:61]
	s_mov_b32 m0, s77
	s_addc_u32 s81, s81, 0
	global_load_lds_dwordx4 v[140:141], off
	v_lshl_add_u64 v[140:141], s[80:81], 0, v[128:129]
	s_mov_b32 m0, s88
	s_nop 0
	global_load_lds_dwordx4 v128, s[80:81]
	v_lshl_add_u64 v[140:141], s[80:81], 0, v[130:131]
	s_mov_b32 m0, s89
	s_nop 0
	global_load_lds_dwordx4 v130, s[80:81]
	v_lshl_add_u64 v[140:141], v[146:147], 0, s[60:61]
	s_mov_b32 m0, s43
	s_nop 0
	global_load_lds_dwordx4 v[140:141], off
	v_lshl_add_u64 v[140:141], v[218:219], 0, s[60:61]
	s_mov_b32 m0, s44
	s_nop 0
	global_load_lds_dwordx4 v[140:141], off
	s_waitcnt vmcnt(8) lgkmcnt(0)
	s_setprio 1
	s_barrier
	v_mfma_f32_16x16x32_bf16 v[60:63], v[154:157], v[186:189], v[60:63]
	v_mfma_f32_16x16x32_bf16 v[56:59], v[162:165], v[186:189], v[56:59]
	v_mfma_f32_16x16x32_bf16 v[44:47], v[154:157], v[194:197], v[44:47]
	v_mfma_f32_16x16x32_bf16 v[40:43], v[162:165], v[194:197], v[40:43]
	v_mfma_f32_16x16x32_bf16 v[28:31], v[154:157], v[202:205], v[28:31]
	v_mfma_f32_16x16x32_bf16 v[24:27], v[162:165], v[202:205], v[24:27]
	v_mfma_f32_16x16x32_bf16 v[12:15], v[154:157], v[210:213], v[12:15]
	v_mfma_f32_16x16x32_bf16 v[8:11], v[162:165], v[210:213], v[8:11]
	v_mfma_f32_16x16x32_bf16 v[60:63], v[158:161], v[190:193], v[60:63]
	v_mfma_f32_16x16x32_bf16 v[56:59], v[166:169], v[190:193], v[56:59]
	v_mfma_f32_16x16x32_bf16 v[44:47], v[158:161], v[198:201], v[44:47]
	v_mfma_f32_16x16x32_bf16 v[40:43], v[166:169], v[198:201], v[40:43]
	v_mfma_f32_16x16x32_bf16 v[28:31], v[158:161], v[206:209], v[28:31]
	v_mfma_f32_16x16x32_bf16 v[24:27], v[166:169], v[206:209], v[24:27]
	v_mfma_f32_16x16x32_bf16 v[12:15], v[158:161], v[214:217], v[12:15]
	v_mfma_f32_16x16x32_bf16 v[8:11], v[166:169], v[214:217], v[8:11]
	s_setprio 0
	s_setprio 1
	v_mfma_f32_16x16x32_bf16 v[52:55], v[170:173], v[186:189], v[52:55]
	v_mfma_f32_16x16x32_bf16 v[48:51], v[178:181], v[186:189], v[48:51]
	v_mfma_f32_16x16x32_bf16 v[36:39], v[170:173], v[194:197], v[36:39]
	v_mfma_f32_16x16x32_bf16 v[32:35], v[178:181], v[194:197], v[32:35]
	v_mfma_f32_16x16x32_bf16 v[20:23], v[170:173], v[202:205], v[20:23]
	v_mfma_f32_16x16x32_bf16 v[16:19], v[178:181], v[202:205], v[16:19]
	v_mfma_f32_16x16x32_bf16 v[4:7], v[170:173], v[210:213], v[4:7]
	v_mfma_f32_16x16x32_bf16 v[0:3], v[178:181], v[210:213], v[0:3]
	v_mfma_f32_16x16x32_bf16 v[52:55], v[174:177], v[190:193], v[52:55]
	v_mfma_f32_16x16x32_bf16 v[48:51], v[182:185], v[190:193], v[48:51]
	v_mfma_f32_16x16x32_bf16 v[36:39], v[174:177], v[198:201], v[36:39]
	v_mfma_f32_16x16x32_bf16 v[32:35], v[182:185], v[198:201], v[32:35]
	v_mfma_f32_16x16x32_bf16 v[20:23], v[174:177], v[206:209], v[20:23]
	v_mfma_f32_16x16x32_bf16 v[16:19], v[182:185], v[206:209], v[16:19]
	v_mfma_f32_16x16x32_bf16 v[4:7], v[174:177], v[214:217], v[4:7]
	v_mfma_f32_16x16x32_bf16 v[0:3], v[182:185], v[214:217], v[0:3]
	s_barrier
	s_setprio 0
	s_add_i32 s91, s91, 2
	s_add_u32 s90, s90, 0x100
	s_addc_u32 s85, s85, 0
	s_add_u32 s78, s78, 0x100
	s_addc_u32 s79, s79, 0
	s_cmp_gt_u32 s91, 29
	s_cbranch_scc0 .LBB0_1619
	s_and_b64 vcc, exec, s[62:63]
	s_cbranch_vccz .LBB0_1622
	s_barrier

; #define PG8_STAGE(bufoff, gbase, voff) do { _Pragma("unroll") for (int _i = 0; _i < 2; ++_i) \
;         __builtin_amdgcn_global_load_lds((const unsigned*)((const char*)(gbase) + (voff)[_i]), (PG8_LAS unsigned*)(lds + (bufoff) + ldsw + _i * 8192), 16, 0, 0); } while (0)
; #define PG8_WAIT_V(n) asm volatile("s_waitcnt vmcnt(" #n ")" ::: "memory")
; template <class Epi, class Sched, bool ALIGN_EPI = false, bool SP2 = false, bool A_TILED = false>
; __device__ __forceinline__ void gemm_phase(PG8_LAS unsigned char* lds, const Gemm g, const Sched& S, const Epi& E, const int wave_s) {
;     ...
;     if constexpr (SP2) {
;         PG8_STAGE(PG8_SB(0, 0), cB, voffB); PG8_STAGE(PG8_SB(0, 1), cB + hstep, voffB); PG8_STAGE(PG8_SA(0, 0), cA, voffA); PG8_STAGE(PG8_SA(0, 1), cA + hstepA, voffA);
;         if (wr == 1) PG8_BAR;
;         PG8_WAIT_V(2); PG8_BAR;
;         PG8_STAGE(PG8_SB(1, 0), cB + kstep, voffB); PG8_STAGE(PG8_SA(1, 0), cA + kstepA, voffA); PG8_STAGE(PG8_SB(1, 1), cB + hstep + kstep, voffB);
;         PG8_WAIT_V(6); PG8_BAR;
;     } else {
;         PG8_STAGE(PG8_SB(0, 0), cB, voffB); PG8_STAGE(PG8_SA(0, 0), cA, voffA); PG8_STAGE(PG8_SB(0, 1), cB + hstep, voffB); PG8_STAGE(PG8_SA(0, 1), cA + hstepA, voffA);
;         if (wr == 1) PG8_BAR;
;         PG8_WAIT_V(4); PG8_BAR;
;         PG8_STAGE(PG8_SB(1, 0), cB + kstep, voffB); PG8_STAGE(PG8_SA(1, 0), cA + kstepA, voffA); PG8_STAGE(PG8_SB(1, 1), cB + hstep + kstep, voffB);
;         PG8_WAIT_V(6); PG8_BAR;
;     }
;     for (;;) {
;         const bool has_next = Epi::AFTER_DRAIN ? false : S.next(ui + 1, nxt);
;         const char* nA = has_next ? (const char*)g.A + (size_t)nxt.pm * tstepA : cA; const char* nB = has_next ? (const char*)g.Bt + (size_t)nxt.pn * tstep : cB;
;         constexpr bool PEEL = SP2 && !Epi::AFTER_DRAIN;
;         if constexpr (PEEL) {
;             const char* a1 = cA + kstepA; const char* a2 = cA + 2 * kstepA; const char* b2 = cB + 2 * kstep; const char* a3 = a2 + kstepA; const char* b3 = b2 + kstep;
;             PG8_ITER(PG8_MMAZ)
;         } else {
; #pragma unroll
;             for (int a = 0; a < 2; ++a)
; #pragma unroll
;                 for (int b = 0; b < 2; ++b)
; #pragma unroll
;                     for (int m = 0; m < 4; ++m)
; #pragma unroll
;                         for (int n = 0; n < 2; ++n) acc[a][b][m][n] = (f32x4){0.f, 0.f, 0.f, 0.f};
.LBB0_1840:
	v_and_b32_e32 v15, 48, v8
	v_lshlrev_b32_e32 v16, 6, v8
	s_movk_i32 s36, 0x3c0
	v_lshlrev_b32_e32 v8, 2, v8
	s_and_b32 s9, s1, 3
	s_lshl_b32 s8, s23, 6
	s_lshl_b32 s23, s23, 13
	v_and_or_b32 v15, v16, s36, v15
	v_and_b32_e32 v8, 32, v8
	s_mov_b64 s[64:65], 0x80
	v_bitop3_b32 v16, v15, s23, v8 bitop3:0xde
	s_lshl_b32 s23, s9, 12
	s_add_i32 m0, s14, 0x18000
	v_lshl_add_u64 v[6:7], v[6:7], 0, s[64:65]
	v_bitop3_b32 v8, v15, s23, v8 bitop3:0xde
	s_waitcnt vmcnt(2)
	s_barrier
	global_load_lds_dwordx4 v[6:7], off
	v_lshl_add_u64 v[4:5], v[4:5], 0, s[64:65]
	s_add_i32 m0, s14, 0x1a000
	s_add_i32 s23, s14, 0x8000
	s_add_i32 s36, s14, 0xa000
	global_load_lds_dwordx4 v[4:5], off
	v_lshl_add_u64 v[2:3], v[2:3], 0, s[64:65]
	s_mov_b32 m0, s23
	s_add_u32 s38, s2, 0x80080
	global_load_lds_dwordx4 v[2:3], off
	v_lshl_add_u64 v[0:1], v[0:1], 0, s[64:65]
	s_mov_b32 m0, s36
	s_addc_u32 s39, s3, 0
	global_load_lds_dwordx4 v[0:1], off
	s_add_i32 m0, s14, 0x1c000
	v_lshl_add_u64 v[0:1], s[38:39], 0, v[34:35]
	global_load_lds_dwordx4 v34, s[38:39]
	v_lshl_add_u64 v[0:1], s[38:39], 0, v[134:135]
	s_add_i32 m0, s14, 0x1e000
	s_mov_b64 s[40:41], 0x20680080
	global_load_lds_dwordx4 v134, s[38:39]
	v_lshlrev_b32_e32 v0, 15, v12
	v_and_b32_e32 v0, 0xffff0000, v0
	v_lshl_add_u32 v0, v13, 12, v0
	v_and_b32_e32 v1, 1, v12
	v_lshl_or_b32 v0, v1, 6, v0
	v_lshl_add_u32 v0, v14, 1, v0
	v_mov_b32_e32 v1, v35
	v_lshl_add_u64 v[0:1], s[66:67], 0, v[0:1]
	v_lshl_add_u64 v[136:137], v[0:1], 0, s[40:41]
	v_lshlrev_b32_e32 v0, 15, v9
	v_and_b32_e32 v0, 0xffff0000, v0
	v_lshl_add_u32 v0, v10, 12, v0
	v_and_b32_e32 v1, 1, v9
	s_add_u32 s37, s68, 0x8a00100
	v_lshl_or_b32 v0, v1, 6, v0
	s_addc_u32 s38, s69, 0
	v_lshl_add_u32 v0, v11, 1, v0
	v_mov_b32_e32 v1, v35
	v_lshl_add_u64 v[0:1], s[66:67], 0, v[0:1]
	s_add_u32 s39, s66, 0x20600100
	s_waitcnt vmcnt(6)
	v_lshl_add_u64 v[138:139], v[0:1], 0, s[40:41]
	s_addc_u32 s40, s67, 0
	s_add_i32 s44, 0, 0x10000
	s_add_i32 s46, 0, 0x14000
	s_add_i32 s48, 0, 0x18000
	s_add_i32 s51, 0, 0x1c000
	v_add_u32_e32 v140, s44, v8
	v_add_u32_e32 v141, s46, v8
	s_add_i32 s44, s44, s50
	s_add_i32 s46, s46, s50
	v_add_u32_e32 v143, s48, v8
	s_add_i32 s48, s48, s50
	s_add_i32 s50, s51, s50
	s_mov_b32 s41, -2
	v_add_u32_e32 v142, 0, v16
	s_add_i32 s42, s14, 0xc000
	s_add_i32 s43, s14, 0xe000
	s_add_i32 s45, s44, 0x2000
	s_add_i32 s47, s46, 0x2000
	v_add_u32_e32 v144, s51, v8
	s_add_i32 s49, s48, 0x2000
	s_add_i32 s51, s50, 0x2000
	s_mov_b64 s[66:67], 0x100
	v_mov_b32_e32 v0, v35
	v_mov_b32_e32 v1, v35
	v_mov_b32_e32 v2, v35
	v_mov_b32_e32 v3, v35
	v_mov_b32_e32 v4, v35
	v_mov_b32_e32 v5, v35
	v_mov_b32_e32 v6, v35
	v_mov_b32_e32 v7, v35
	v_mov_b32_e32 v40, v35
	v_mov_b32_e32 v41, v35
	v_mov_b32_e32 v42, v35
	v_mov_b32_e32 v43, v35
	v_mov_b32_e32 v44, v35
	v_mov_b32_e32 v45, v35
	v_mov_b32_e32 v46, v35
	v_mov_b32_e32 v47, v35
	v_mov_b32_e32 v88, v35
	v_mov_b32_e32 v89, v35
	v_mov_b32_e32 v90, v35
	v_mov_b32_e32 v91, v35
	v_mov_b32_e32 v92, v35
	v_mov_b32_e32 v93, v35
	v_mov_b32_e32 v94, v35
	v_mov_b32_e32 v95, v35
	v_mov_b32_e32 v112, v35
	v_mov_b32_e32 v113, v35
	v_mov_b32_e32 v114, v35
	v_mov_b32_e32 v115, v35
	v_mov_b32_e32 v124, v35
	v_mov_b32_e32 v125, v35
	v_mov_b32_e32 v126, v35
	v_mov_b32_e32 v127, v35
	v_mov_b32_e32 v28, v35
	v_mov_b32_e32 v29, v35
	v_mov_b32_e32 v30, v35
	v_mov_b32_e32 v31, v35
	v_mov_b32_e32 v36, v35
	v_mov_b32_e32 v37, v35
	v_mov_b32_e32 v38, v35
	v_mov_b32_e32 v39, v35
	v_mov_b32_e32 v80, v35
	v_mov_b32_e32 v81, v35
	v_mov_b32_e32 v82, v35
	v_mov_b32_e32 v83, v35
	v_mov_b32_e32 v84, v35
	v_mov_b32_e32 v85, v35
	v_mov_b32_e32 v86, v35
	v_mov_b32_e32 v87, v35
	v_mov_b32_e32 v120, v35
	v_mov_b32_e32 v121, v35
	v_mov_b32_e32 v122, v35
	v_mov_b32_e32 v123, v35
	v_mov_b32_e32 v116, v35
	v_mov_b32_e32 v117, v35
	v_mov_b32_e32 v118, v35
	v_mov_b32_e32 v119, v35
	v_mov_b32_e32 v104, v35
	v_mov_b32_e32 v105, v35
	v_mov_b32_e32 v106, v35
	v_mov_b32_e32 v107, v35
	v_mov_b32_e32 v100, v35
	v_mov_b32_e32 v101, v35
	v_mov_b32_e32 v102, v35
	v_mov_b32_e32 v103, v35
	v_mov_b32_e32 v96, v35
	v_mov_b32_e32 v97, v35
	v_mov_b32_e32 v98, v35
	v_mov_b32_e32 v99, v35
	v_mov_b32_e32 v108, v35
	v_mov_b32_e32 v109, v35
	v_mov_b32_e32 v110, v35
	v_mov_b32_e32 v111, v35
	v_mov_b32_e32 v64, v35
	v_mov_b32_e32 v65, v35
	v_mov_b32_e32 v66, v35
	v_mov_b32_e32 v67, v35
	v_mov_b32_e32 v72, v35
	v_mov_b32_e32 v73, v35
	v_mov_b32_e32 v74, v35
	v_mov_b32_e32 v75, v35
	v_mov_b32_e32 v48, v35
	v_mov_b32_e32 v49, v35
	v_mov_b32_e32 v50, v35
	v_mov_b32_e32 v51, v35
	v_mov_b32_e32 v56, v35
	v_mov_b32_e32 v57, v35
	v_mov_b32_e32 v58, v35
	v_mov_b32_e32 v59, v35
	v_mov_b32_e32 v16, v35
	v_mov_b32_e32 v17, v35
	v_mov_b32_e32 v18, v35
	v_mov_b32_e32 v19, v35
	v_mov_b32_e32 v24, v35
	v_mov_b32_e32 v25, v35
	v_mov_b32_e32 v26, v35
	v_mov_b32_e32 v27, v35
	v_mov_b32_e32 v68, v35
	v_mov_b32_e32 v69, v35
	v_mov_b32_e32 v70, v35
	v_mov_b32_e32 v71, v35
	v_mov_b32_e32 v128, v35
	v_mov_b32_e32 v129, v35
	v_mov_b32_e32 v130, v35
	v_mov_b32_e32 v131, v35
	v_mov_b32_e32 v52, v35
	v_mov_b32_e32 v53, v35
	v_mov_b32_e32 v54, v35
	v_mov_b32_e32 v55, v35
	v_mov_b32_e32 v76, v35
	v_mov_b32_e32 v77, v35
	v_mov_b32_e32 v78, v35
	v_mov_b32_e32 v79, v35
	v_mov_b32_e32 v20, v35
	v_mov_b32_e32 v21, v35
	v_mov_b32_e32 v22, v35
	v_mov_b32_e32 v23, v35
	v_mov_b32_e32 v60, v35
	v_mov_b32_e32 v61, v35
	v_mov_b32_e32 v62, v35
	v_mov_b32_e32 v63, v35
	v_mov_b32_e32 v12, v35
	v_mov_b32_e32 v13, v35
	v_mov_b32_e32 v14, v35
	v_mov_b32_e32 v15, v35
	v_mov_b32_e32 v8, v35
	v_mov_b32_e32 v9, v35
	v_mov_b32_e32 v10, v35
	v_mov_b32_e32 v11, v35
	s_barrier
; #define PG8_MMA(ai, bj, At, Bt) do { __builtin_amdgcn_s_setprio(1); _Pragma("unroll") for (int m = 0; m < 4; ++m) _Pragma("unroll") for (int n = 0; n < 2; ++n) _Pragma("unroll") for (int k = 0; k < 2; ++k) \
;         acc[ai][bj][m][n] = __builtin_amdgcn_mfma_f32_16x16x32_bf16(Bt[n][k], At[m][k], acc[ai][bj][m][n], 0, 0, 0); __builtin_amdgcn_s_setprio(0); } while (0)
; template <class Epi, class Sched, bool ALIGN_EPI = false, bool SP2 = false, bool A_TILED = false>
; __device__ __forceinline__ void gemm_phase(PG8_LAS unsigned char* lds, const Gemm g, const Sched& S, const Epi& E, const int wave_s) {
;     ...
;         for (int t = PEEL ? 2 : 0; t < nt; t += 2) {
;             const bool last = (t == nt - 2);
;             const char* a1 = cA + (size_t)(t + 1) * kstepA;
;             const char* a2 = last ? nA : cA + (size_t)(t + 2) * kstepA; const char* b2 = last ? nB : cB + (size_t)(t + 2) * kstep;
;             const char* a3 = a2 + kstepA; const char* b3 = b2 + kstep;
;             if (last && has_next) S.a_ready(nxt);
;             if constexpr (SP2) {
;             PG8_ITER(PG8_MMA)
.LBB0_1841:
	ds_read_b128 v[146:149], v140
	ds_read_b128 v[150:153], v140 offset:1024
	ds_read_b128 v[154:157], v140 offset:2048
	ds_read_b128 v[158:161], v140 offset:3072
	ds_read_b128 v[162:165], v141
	ds_read_b128 v[166:169], v141 offset:1024
	ds_read_b128 v[170:173], v141 offset:2048
	ds_read_b128 v[174:177], v141 offset:3072
	s_add_u32 s52, s60, s39
	s_addc_u32 s53, s61, s40
	s_add_u32 s54, s60, s37
	s_addc_u32 s55, s61, s38
	s_cmp_eq_u32 s41, 28
	s_cselect_b32 s71, s7, s53
	s_cselect_b32 s70, s6, s52
	s_cselect_b32 s69, s3, s55
	s_cselect_b32 s68, s2, s54
	s_mov_b32 m0, s42
	v_lshl_add_u64 v[210:211], s[60:61], 0, v[138:139]
	ds_read_b128 v[178:181], v142
	ds_read_b128 v[182:185], v142 offset:1024
	ds_read_b128 v[186:189], v142 offset:2048
	ds_read_b128 v[190:193], v142 offset:3072
	ds_read_b128 v[194:197], v142 offset:4096
	ds_read_b128 v[198:201], v142 offset:5120
	ds_read_b128 v[202:205], v142 offset:6144
	ds_read_b128 v[206:209], v142 offset:7168
	global_load_lds_dwordx4 v[210:211], off
	v_lshl_add_u64 v[210:211], s[60:61], 0, v[136:137]
	s_mov_b32 m0, s43
	s_nop 0
	global_load_lds_dwordx4 v[210:211], off
	s_waitcnt vmcnt(8) lgkmcnt(0)
	s_setprio 1
	s_barrier
	v_mfma_f32_16x16x32_bf16 v[8:11], v[146:149], v[178:181], v[8:11]
	v_mfma_f32_16x16x32_bf16 v[12:15], v[154:157], v[178:181], v[12:15]
	v_mfma_f32_16x16x32_bf16 v[60:63], v[146:149], v[186:189], v[60:63]
	v_mfma_f32_16x16x32_bf16 v[20:23], v[154:157], v[186:189], v[20:23]
	v_mfma_f32_16x16x32_bf16 v[76:79], v[146:149], v[194:197], v[76:79]
	v_mfma_f32_16x16x32_bf16 v[52:55], v[154:157], v[194:197], v[52:55]
	v_mfma_f32_16x16x32_bf16 v[128:131], v[146:149], v[202:205], v[128:131]
	v_mfma_f32_16x16x32_bf16 v[68:71], v[154:157], v[202:205], v[68:71]
	v_mfma_f32_16x16x32_bf16 v[8:11], v[150:153], v[182:185], v[8:11]
	v_mfma_f32_16x16x32_bf16 v[12:15], v[158:161], v[182:185], v[12:15]
	v_mfma_f32_16x16x32_bf16 v[60:63], v[150:153], v[190:193], v[60:63]
	v_mfma_f32_16x16x32_bf16 v[20:23], v[158:161], v[190:193], v[20:23]
	v_mfma_f32_16x16x32_bf16 v[76:79], v[150:153], v[198:201], v[76:79]
	v_mfma_f32_16x16x32_bf16 v[52:55], v[158:161], v[198:201], v[52:55]
	v_mfma_f32_16x16x32_bf16 v[128:131], v[150:153], v[206:209], v[128:131]
	v_mfma_f32_16x16x32_bf16 v[68:71], v[158:161], v[206:209], v[68:71]
	s_setprio 0
	s_setprio 1
	v_mfma_f32_16x16x32_bf16 v[24:27], v[162:165], v[178:181], v[24:27]
	v_mfma_f32_16x16x32_bf16 v[16:19], v[170:173], v[178:181], v[16:19]
	v_mfma_f32_16x16x32_bf16 v[56:59], v[162:165], v[186:189], v[56:59]
	v_mfma_f32_16x16x32_bf16 v[48:51], v[170:173], v[186:189], v[48:51]
	v_mfma_f32_16x16x32_bf16 v[72:75], v[162:165], v[194:197], v[72:75]
	v_mfma_f32_16x16x32_bf16 v[64:67], v[170:173], v[194:197], v[64:67]
	v_mfma_f32_16x16x32_bf16 v[108:111], v[162:165], v[202:205], v[108:111]
	v_mfma_f32_16x16x32_bf16 v[96:99], v[170:173], v[202:205], v[96:99]
	v_mfma_f32_16x16x32_bf16 v[24:27], v[166:169], v[182:185], v[24:27]
	v_mfma_f32_16x16x32_bf16 v[16:19], v[174:177], v[182:185], v[16:19]
	v_mfma_f32_16x16x32_bf16 v[56:59], v[166:169], v[190:193], v[56:59]
	v_mfma_f32_16x16x32_bf16 v[48:51], v[174:177], v[190:193], v[48:51]
	v_mfma_f32_16x16x32_bf16 v[72:75], v[166:169], v[198:201], v[72:75]
	v_mfma_f32_16x16x32_bf16 v[64:67], v[174:177], v[198:201], v[64:67]
	v_mfma_f32_16x16x32_bf16 v[108:111], v[166:169], v[206:209], v[108:111]
	v_mfma_f32_16x16x32_bf16 v[96:99], v[174:177], v[206:209], v[96:99]
	s_barrier
	s_setprio 0
	s_mov_b32 m0, s44
	v_lshl_add_u64 v[210:211], s[68:69], 0, v[34:35]
	s_add_u32 s52, s68, 0x80000
	ds_read_b128 v[178:181], v142 offset:16384
	ds_read_b128 v[182:185], v142 offset:17408
	ds_read_b128 v[186:189], v142 offset:18432
	ds_read_b128 v[190:193], v142 offset:19456
	ds_read_b128 v[194:197], v142 offset:20480
	ds_read_b128 v[198:201], v142 offset:21504
	ds_read_b128 v[202:205], v142 offset:22528
	ds_read_b128 v[206:209], v142 offset:23552
	global_load_lds_dwordx4 v34, s[68:69]
	v_lshl_add_u64 v[212:213], s[68:69], 0, v[134:135]
	s_mov_b32 m0, s45
	s_addc_u32 s53, s69, 0
	global_load_lds_dwordx4 v134, s[68:69]
	v_lshl_add_u64 v[214:215], s[52:53], 0, v[34:35]
	s_mov_b32 m0, s46
	v_lshl_add_u64 v[216:217], s[70:71], 0, v[132:133]
	global_load_lds_dwordx4 v34, s[52:53]
	v_lshl_add_u64 v[214:215], s[52:53], 0, v[134:135]
	s_mov_b32 m0, s47
	s_nop 0
	global_load_lds_dwordx4 v134, s[52:53]
	v_lshl_add_u64 v[214:215], s[70:71], 0, v[32:33]
	s_mov_b32 m0, s14
	s_nop 0
	global_load_lds_dwordx4 v32, s[70:71]
	s_mov_b32 m0, s15
	s_nop 0
	global_load_lds_dwordx4 v132, s[70:71]
	s_waitcnt vmcnt(8) lgkmcnt(0)
	s_setprio 1
	s_barrier
; #define PG8_MMA(ai, bj, At, Bt) do { __builtin_amdgcn_s_setprio(1); _Pragma("unroll") for (int m = 0; m < 4; ++m) _Pragma("unroll") for (int n = 0; n < 2; ++n) _Pragma("unroll") for (int k = 0; k < 2; ++k) \
;         acc[ai][bj][m][n] = __builtin_amdgcn_mfma_f32_16x16x32_bf16(Bt[n][k], At[m][k], acc[ai][bj][m][n], 0, 0, 0); __builtin_amdgcn_s_setprio(0); } while (0)
; template <class Epi, class Sched, bool ALIGN_EPI = false, bool SP2 = false, bool A_TILED = false>
; __device__ __forceinline__ void gemm_phase(PG8_LAS unsigned char* lds, const Gemm g, const Sched& S, const Epi& E, const int wave_s) {
;     ...
;         for (int t = PEEL ? 2 : 0; t < nt; t += 2) {
;             const bool last = (t == nt - 2);
;             const char* a1 = cA + (size_t)(t + 1) * kstepA;
;             const char* a2 = last ? nA : cA + (size_t)(t + 2) * kstepA; const char* b2 = last ? nB : cB + (size_t)(t + 2) * kstep;
;             const char* a3 = a2 + kstepA; const char* b3 = b2 + kstep;
;             if (last && has_next) S.a_ready(nxt);
;             if constexpr (SP2) {
;             PG8_ITER(PG8_MMA)
	v_mfma_f32_16x16x32_bf16 v[100:103], v[146:149], v[178:181], v[100:103]
	v_mfma_f32_16x16x32_bf16 v[104:107], v[154:157], v[178:181], v[104:107]
	v_mfma_f32_16x16x32_bf16 v[116:119], v[146:149], v[186:189], v[116:119]
	v_mfma_f32_16x16x32_bf16 v[120:123], v[154:157], v[186:189], v[120:123]
	v_mfma_f32_16x16x32_bf16 v[84:87], v[146:149], v[194:197], v[84:87]
	v_mfma_f32_16x16x32_bf16 v[80:83], v[154:157], v[194:197], v[80:83]
	v_mfma_f32_16x16x32_bf16 v[36:39], v[146:149], v[202:205], v[36:39]
	v_mfma_f32_16x16x32_bf16 v[28:31], v[154:157], v[202:205], v[28:31]
	v_mfma_f32_16x16x32_bf16 v[100:103], v[150:153], v[182:185], v[100:103]
	v_mfma_f32_16x16x32_bf16 v[104:107], v[158:161], v[182:185], v[104:107]
	v_mfma_f32_16x16x32_bf16 v[116:119], v[150:153], v[190:193], v[116:119]
	v_mfma_f32_16x16x32_bf16 v[120:123], v[158:161], v[190:193], v[120:123]
	v_mfma_f32_16x16x32_bf16 v[84:87], v[150:153], v[198:201], v[84:87]
	v_mfma_f32_16x16x32_bf16 v[80:83], v[158:161], v[198:201], v[80:83]
	v_mfma_f32_16x16x32_bf16 v[36:39], v[150:153], v[206:209], v[36:39]
	v_mfma_f32_16x16x32_bf16 v[28:31], v[158:161], v[206:209], v[28:31]
	s_setprio 0
	s_setprio 1
	v_mfma_f32_16x16x32_bf16 v[124:127], v[162:165], v[178:181], v[124:127]
	v_mfma_f32_16x16x32_bf16 v[112:115], v[170:173], v[178:181], v[112:115]
	v_mfma_f32_16x16x32_bf16 v[92:95], v[162:165], v[186:189], v[92:95]
	v_mfma_f32_16x16x32_bf16 v[88:91], v[170:173], v[186:189], v[88:91]
	v_mfma_f32_16x16x32_bf16 v[44:47], v[162:165], v[194:197], v[44:47]
	v_mfma_f32_16x16x32_bf16 v[40:43], v[170:173], v[194:197], v[40:43]
	v_mfma_f32_16x16x32_bf16 v[4:7], v[162:165], v[202:205], v[4:7]
	v_mfma_f32_16x16x32_bf16 v[0:3], v[170:173], v[202:205], v[0:3]
	v_mfma_f32_16x16x32_bf16 v[124:127], v[166:169], v[182:185], v[124:127]
	v_mfma_f32_16x16x32_bf16 v[112:115], v[174:177], v[182:185], v[112:115]
	v_mfma_f32_16x16x32_bf16 v[92:95], v[166:169], v[190:193], v[92:95]
	v_mfma_f32_16x16x32_bf16 v[88:91], v[174:177], v[190:193], v[88:91]
	v_mfma_f32_16x16x32_bf16 v[44:47], v[166:169], v[198:201], v[44:47]
	v_mfma_f32_16x16x32_bf16 v[40:43], v[174:177], v[198:201], v[40:43]
	v_mfma_f32_16x16x32_bf16 v[4:7], v[166:169], v[206:209], v[4:7]
	v_mfma_f32_16x16x32_bf16 v[0:3], v[174:177], v[206:209], v[0:3]
	s_barrier
	s_setprio 0
	ds_read_b128 v[146:149], v143
	ds_read_b128 v[150:153], v143 offset:1024
	ds_read_b128 v[154:157], v143 offset:2048
	ds_read_b128 v[158:161], v143 offset:3072
	ds_read_b128 v[162:165], v144
	ds_read_b128 v[166:169], v144 offset:1024
	ds_read_b128 v[170:173], v144 offset:2048
	ds_read_b128 v[174:177], v144 offset:3072
	s_add_u32 s52, s70, 0x80000
	s_addc_u32 s53, s71, 0
	s_mov_b32 m0, s21
	v_lshl_add_u64 v[218:219], s[52:53], 0, v[32:33]
	ds_read_b128 v[178:181], v142 offset:32768
	ds_read_b128 v[182:185], v142 offset:33792
	ds_read_b128 v[186:189], v142 offset:34816
	ds_read_b128 v[190:193], v142 offset:35840
	ds_read_b128 v[194:197], v142 offset:36864
	ds_read_b128 v[198:201], v142 offset:37888
	ds_read_b128 v[202:205], v142 offset:38912
	ds_read_b128 v[206:209], v142 offset:39936
	global_load_lds_dwordx4 v32, s[52:53]
	v_lshl_add_u64 v[218:219], s[52:53], 0, v[132:133]
	s_mov_b32 m0, s22
	s_nop 0
	global_load_lds_dwordx4 v132, s[52:53]
	s_waitcnt vmcnt(8) lgkmcnt(0)
	s_setprio 1
	s_barrier
	v_mfma_f32_16x16x32_bf16 v[8:11], v[146:149], v[178:181], v[8:11]
	v_mfma_f32_16x16x32_bf16 v[12:15], v[154:157], v[178:181], v[12:15]
	v_mfma_f32_16x16x32_bf16 v[60:63], v[146:149], v[186:189], v[60:63]
	v_mfma_f32_16x16x32_bf16 v[20:23], v[154:157], v[186:189], v[20:23]
	v_mfma_f32_16x16x32_bf16 v[76:79], v[146:149], v[194:197], v[76:79]
	v_mfma_f32_16x16x32_bf16 v[52:55], v[154:157], v[194:197], v[52:55]
	v_mfma_f32_16x16x32_bf16 v[128:131], v[146:149], v[202:205], v[128:131]
	v_mfma_f32_16x16x32_bf16 v[68:71], v[154:157], v[202:205], v[68:71]
	v_mfma_f32_16x16x32_bf16 v[8:11], v[150:153], v[182:185], v[8:11]
	v_mfma_f32_16x16x32_bf16 v[12:15], v[158:161], v[182:185], v[12:15]
	v_mfma_f32_16x16x32_bf16 v[60:63], v[150:153], v[190:193], v[60:63]
	v_mfma_f32_16x16x32_bf16 v[20:23], v[158:161], v[190:193], v[20:23]
	v_mfma_f32_16x16x32_bf16 v[76:79], v[150:153], v[198:201], v[76:79]
	v_mfma_f32_16x16x32_bf16 v[52:55], v[158:161], v[198:201], v[52:55]
	v_mfma_f32_16x16x32_bf16 v[128:131], v[150:153], v[206:209], v[128:131]
	v_mfma_f32_16x16x32_bf16 v[68:71], v[158:161], v[206:209], v[68:71]
	s_setprio 0
	s_setprio 1
	v_mfma_f32_16x16x32_bf16 v[24:27], v[162:165], v[178:181], v[24:27]
	v_mfma_f32_16x16x32_bf16 v[16:19], v[170:173], v[178:181], v[16:19]
	v_mfma_f32_16x16x32_bf16 v[56:59], v[162:165], v[186:189], v[56:59]
	v_mfma_f32_16x16x32_bf16 v[48:51], v[170:173], v[186:189], v[48:51]
	v_mfma_f32_16x16x32_bf16 v[72:75], v[162:165], v[194:197], v[72:75]
	v_mfma_f32_16x16x32_bf16 v[64:67], v[170:173], v[194:197], v[64:67]
	v_mfma_f32_16x16x32_bf16 v[108:111], v[162:165], v[202:205], v[108:111]
	v_mfma_f32_16x16x32_bf16 v[96:99], v[170:173], v[202:205], v[96:99]
	v_mfma_f32_16x16x32_bf16 v[24:27], v[166:169], v[182:185], v[24:27]
	v_mfma_f32_16x16x32_bf16 v[16:19], v[174:177], v[182:185], v[16:19]
	v_mfma_f32_16x16x32_bf16 v[56:59], v[166:169], v[190:193], v[56:59]
	v_mfma_f32_16x16x32_bf16 v[48:51], v[174:177], v[190:193], v[48:51]
	v_mfma_f32_16x16x32_bf16 v[72:75], v[166:169], v[198:201], v[72:75]
	v_mfma_f32_16x16x32_bf16 v[64:67], v[174:177], v[198:201], v[64:67]
	v_mfma_f32_16x16x32_bf16 v[108:111], v[166:169], v[206:209], v[108:111]
	v_mfma_f32_16x16x32_bf16 v[96:99], v[174:177], v[206:209], v[96:99]
	s_barrier
; #define PG8_MMA(ai, bj, At, Bt) do { __builtin_amdgcn_s_setprio(1); _Pragma("unroll") for (int m = 0; m < 4; ++m) _Pragma("unroll") for (int n = 0; n < 2; ++n) _Pragma("unroll") for (int k = 0; k < 2; ++k) \
;         acc[ai][bj][m][n] = __builtin_amdgcn_mfma_f32_16x16x32_bf16(Bt[n][k], At[m][k], acc[ai][bj][m][n], 0, 0, 0); __builtin_amdgcn_s_setprio(0); } while (0)
; template <class Epi, class Sched, bool ALIGN_EPI = false, bool SP2 = false, bool A_TILED = false>
; __device__ __forceinline__ void gemm_phase(PG8_LAS unsigned char* lds, const Gemm g, const Sched& S, const Epi& E, const int wave_s) {
;     ...
;         for (int t = PEEL ? 2 : 0; t < nt; t += 2) {
;             const bool last = (t == nt - 2);
;             const char* a1 = cA + (size_t)(t + 1) * kstepA;
;             const char* a2 = last ? nA : cA + (size_t)(t + 2) * kstepA; const char* b2 = last ? nB : cB + (size_t)(t + 2) * kstep;
;             const char* a3 = a2 + kstepA; const char* b3 = b2 + kstep;
;             if (last && has_next) S.a_ready(nxt);
;             if constexpr (SP2) {
;             PG8_ITER(PG8_MMA)
	s_setprio 0
	s_mov_b32 m0, s48
	v_lshl_add_u64 v[210:211], v[210:211], 0, s[64:65]
	s_add_u32 s52, s68, 0x80080
	ds_read_b128 v[178:181], v142 offset:49152
	ds_read_b128 v[182:185], v142 offset:50176
	ds_read_b128 v[186:189], v142 offset:51200
	ds_read_b128 v[190:193], v142 offset:52224
	ds_read_b128 v[194:197], v142 offset:53248
	ds_read_b128 v[198:201], v142 offset:54272
	ds_read_b128 v[202:205], v142 offset:55296
	ds_read_b128 v[206:209], v142 offset:56320
	global_load_lds_dwordx4 v[210:211], off
	v_lshl_add_u64 v[210:211], v[212:213], 0, s[64:65]
	s_mov_b32 m0, s49
	s_addc_u32 s53, s69, 0
	global_load_lds_dwordx4 v[210:211], off
	v_lshl_add_u64 v[210:211], s[52:53], 0, v[34:35]
	s_mov_b32 m0, s50
	s_nop 0
	global_load_lds_dwordx4 v34, s[52:53]
	v_lshl_add_u64 v[210:211], s[52:53], 0, v[134:135]
	s_mov_b32 m0, s51
	s_nop 0
	global_load_lds_dwordx4 v134, s[52:53]
	v_lshl_add_u64 v[210:211], v[214:215], 0, s[64:65]
	s_mov_b32 m0, s23
	s_nop 0
	global_load_lds_dwordx4 v[210:211], off
	v_lshl_add_u64 v[210:211], v[216:217], 0, s[64:65]
	s_mov_b32 m0, s36
	s_nop 0
	global_load_lds_dwordx4 v[210:211], off
	s_waitcnt vmcnt(8) lgkmcnt(0)
	s_setprio 1
	s_barrier
	v_mfma_f32_16x16x32_bf16 v[100:103], v[146:149], v[178:181], v[100:103]
	v_mfma_f32_16x16x32_bf16 v[104:107], v[154:157], v[178:181], v[104:107]
	v_mfma_f32_16x16x32_bf16 v[116:119], v[146:149], v[186:189], v[116:119]
	v_mfma_f32_16x16x32_bf16 v[120:123], v[154:157], v[186:189], v[120:123]
	v_mfma_f32_16x16x32_bf16 v[84:87], v[146:149], v[194:197], v[84:87]
	v_mfma_f32_16x16x32_bf16 v[80:83], v[154:157], v[194:197], v[80:83]
	v_mfma_f32_16x16x32_bf16 v[36:39], v[146:149], v[202:205], v[36:39]
	v_mfma_f32_16x16x32_bf16 v[28:31], v[154:157], v[202:205], v[28:31]
	v_mfma_f32_16x16x32_bf16 v[100:103], v[150:153], v[182:185], v[100:103]
	v_mfma_f32_16x16x32_bf16 v[104:107], v[158:161], v[182:185], v[104:107]
	v_mfma_f32_16x16x32_bf16 v[116:119], v[150:153], v[190:193], v[116:119]
	v_mfma_f32_16x16x32_bf16 v[120:123], v[158:161], v[190:193], v[120:123]
	v_mfma_f32_16x16x32_bf16 v[84:87], v[150:153], v[198:201], v[84:87]
	v_mfma_f32_16x16x32_bf16 v[80:83], v[158:161], v[198:201], v[80:83]
	v_mfma_f32_16x16x32_bf16 v[36:39], v[150:153], v[206:209], v[36:39]
	v_mfma_f32_16x16x32_bf16 v[28:31], v[158:161], v[206:209], v[28:31]
	s_setprio 0
	s_setprio 1
	v_mfma_f32_16x16x32_bf16 v[124:127], v[162:165], v[178:181], v[124:127]
	v_mfma_f32_16x16x32_bf16 v[112:115], v[170:173], v[178:181], v[112:115]
	v_mfma_f32_16x16x32_bf16 v[92:95], v[162:165], v[186:189], v[92:95]
	v_mfma_f32_16x16x32_bf16 v[88:91], v[170:173], v[186:189], v[88:91]
	v_mfma_f32_16x16x32_bf16 v[44:47], v[162:165], v[194:197], v[44:47]
	v_mfma_f32_16x16x32_bf16 v[40:43], v[170:173], v[194:197], v[40:43]
	v_mfma_f32_16x16x32_bf16 v[4:7], v[162:165], v[202:205], v[4:7]
	v_mfma_f32_16x16x32_bf16 v[0:3], v[170:173], v[202:205], v[0:3]
	v_mfma_f32_16x16x32_bf16 v[124:127], v[166:169], v[182:185], v[124:127]
	v_mfma_f32_16x16x32_bf16 v[112:115], v[174:177], v[182:185], v[112:115]
	v_mfma_f32_16x16x32_bf16 v[92:95], v[166:169], v[190:193], v[92:95]
	v_mfma_f32_16x16x32_bf16 v[88:91], v[174:177], v[190:193], v[88:91]
	v_mfma_f32_16x16x32_bf16 v[44:47], v[166:169], v[198:201], v[44:47]
	v_mfma_f32_16x16x32_bf16 v[40:43], v[174:177], v[198:201], v[40:43]
	v_mfma_f32_16x16x32_bf16 v[4:7], v[166:169], v[206:209], v[4:7]
	v_mfma_f32_16x16x32_bf16 v[0:3], v[174:177], v[206:209], v[0:3]
	s_barrier
	s_setprio 0
	s_add_i32 s41, s41, 2
	s_add_u32 s37, s37, 0x100
	s_addc_u32 s38, s38, 0
	s_add_u32 s39, s39, 0x100
	s_addc_u32 s40, s40, 0
	v_lshl_add_u64 v[136:137], v[136:137], 0, s[66:67]
	s_cmp_gt_u32 s41, 29
	v_lshl_add_u64 v[138:139], v[138:139], 0, s[66:67]
	s_cbranch_scc0 .LBB0_1841
	s_waitcnt vmcnt(0)
	s_cmpk_lt_u32 s0, 0x100
	s_cbranch_scc0 .LBB0_1844
	s_barrier

; #define PG8_STAGE(bufoff, gbase, voff) do { _Pragma("unroll") for (int _i = 0; _i < 2; ++_i) \
;         __builtin_amdgcn_global_load_lds((const unsigned*)((const char*)(gbase) + (voff)[_i]), (PG8_LAS unsigned*)(lds + (bufoff) + ldsw + _i * 8192), 16, 0, 0); } while (0)
; #define PG8_WAIT_V(n) asm volatile("s_waitcnt vmcnt(" #n ")" ::: "memory")
; #define PG8_BAR __builtin_amdgcn_s_barrier()
; template <class Epi, class Sched, bool ALIGN_EPI = false, bool SP2 = false, bool A_TILED = false>
; __device__ __forceinline__ void gemm_phase(PG8_LAS unsigned char* lds, const Gemm g, const Sched& S, const Epi& E, const int wave_s) {
;     ...
;     if constexpr (SP2) {
;         PG8_STAGE(PG8_SB(0, 0), cB, voffB); PG8_STAGE(PG8_SB(0, 1), cB + hstep, voffB); PG8_STAGE(PG8_SA(0, 0), cA, voffA); PG8_STAGE(PG8_SA(0, 1), cA + hstepA, voffA);
;         if (wr == 1) PG8_BAR;
;         PG8_WAIT_V(2); PG8_BAR;
;         PG8_STAGE(PG8_SB(1, 0), cB + kstep, voffB); PG8_STAGE(PG8_SA(1, 0), cA + kstepA, voffA); PG8_STAGE(PG8_SB(1, 1), cB + hstep + kstep, voffB);
;         PG8_WAIT_V(6); PG8_BAR;
.LBB0_1943:
	s_ashr_i32 s40, s86, 31
	s_add_u32 s41, s2, 0x34600000
	s_sext_i32_i16 s49, s12
	s_addc_u32 s42, s3, 0
	s_lshl_b32 s47, s13, 13
	s_mov_b64 s[12:13], 0x80
	s_and_b32 s2, s46, 3
	v_and_b32_e32 v15, 15, v14
	v_and_b32_e32 v16, 48, v14
	v_lshlrev_b32_e32 v14, 2, v14
	s_add_i32 m0, s22, 0x18000
	v_lshl_add_u64 v[6:7], v[6:7], 0, s[12:13]
	v_lshl_or_b32 v15, v15, 6, v16
	v_and_b32_e32 v14, 32, v14
	s_lshl_b32 s2, s2, 12
	s_waitcnt vmcnt(2)
	s_barrier
	global_load_lds_dwordx4 v[6:7], off
	v_lshl_add_u64 v[4:5], v[4:5], 0, s[12:13]
	s_add_i32 m0, s22, 0x1a000
	s_add_i32 s43, s22, 0x8000
	s_add_i32 s44, s22, 0xa000
	v_bitop3_b32 v144, v15, s2, v14 bitop3:0xde
	global_load_lds_dwordx4 v[4:5], off
	v_lshl_add_u64 v[0:1], v[0:1], 0, s[12:13]
	s_mov_b32 m0, s43
	s_add_u32 s2, s76, 0x80080
	global_load_lds_dwordx4 v[0:1], off
	v_lshl_add_u64 v[0:1], v[2:3], 0, s[12:13]
	s_mov_b32 m0, s44
	s_addc_u32 s3, s77, 0
	global_load_lds_dwordx4 v[0:1], off
	s_add_i32 m0, s22, 0x1c000
	v_lshl_add_u64 v[0:1], s[2:3], 0, v[128:129]
	global_load_lds_dwordx4 v128, s[2:3]
	v_lshl_add_u64 v[0:1], s[2:3], 0, v[130:131]
	s_add_i32 m0, s22, 0x1e000
	s_cmpk_lt_u32 s45, 0x100
	global_load_lds_dwordx4 v130, s[2:3]
	v_lshlrev_b32_e32 v0, 15, v8
	v_and_b32_e32 v0, 0xffff0000, v0
	v_lshl_add_u32 v0, v9, 12, v0
	v_and_b32_e32 v1, 1, v8
	v_lshl_or_b32 v0, v1, 6, v0
	v_lshl_add_u32 v136, v10, 1, v0
	v_lshlrev_b32_e32 v0, 15, v12
	v_and_b32_e32 v0, 0xffff0000, v0
	s_waitcnt vmcnt(6)
	s_cselect_b64 s[60:61], -1, 0
	s_and_b32 s2, s15, 0x400
	v_lshl_add_u32 v0, v11, 12, v0
	v_and_b32_e32 v1, 1, v12
	v_bitop3_b32 v16, v15, s47, v14 bitop3:0xde
	s_bfe_u32 s45, s46, 0x10001
	s_or_b32 s46, s2, s47
	v_mov_b32_e32 v137, 0
	v_lshl_or_b32 v0, v1, 6, v0
	s_add_i32 s47, 0, 0x10000
	s_add_i32 s48, 0, 0x14000
	v_lshl_add_u32 v138, v13, 1, v0
	v_mov_b32_e32 v139, v137
	v_mov_b64_e32 v[140:141], 0x200
	v_mov_b64_e32 v[142:143], 0x1ff
	v_add_u32_e32 v145, s47, v144
	v_add_u32_e32 v146, s48, v144
	v_add_u32_e32 v147, 0, v16
	s_mov_b64 s[62:63], 0x100
	s_mov_b64 s[64:65], 0x180
	s_barrier
	s_branch .LBB0_1946

; template <class Epi, class Sched, bool ALIGN_EPI = false, bool SP2 = false, bool A_TILED = false>
; __device__ __forceinline__ void gemm_phase(PG8_LAS unsigned char* lds, const Gemm g, const Sched& S, const Epi& E, const int wave_s) {
;     ...
;         const bool has_next = Epi::AFTER_DRAIN ? false : S.next(ui + 1, nxt);
;         const char* nA = has_next ? (const char*)g.A + (size_t)nxt.pm * tstepA : cA; const char* nB = has_next ? (const char*)g.Bt + (size_t)nxt.pn * tstep : cB;
;         constexpr bool PEEL = SP2 && !Epi::AFTER_DRAIN;
;         if constexpr (PEEL) {
;             const char* a1 = cA + kstepA; const char* a2 = cA + 2 * kstepA; const char* b2 = cB + 2 * kstep; const char* a3 = a2 + kstepA; const char* b3 = b2 + kstep;
;             PG8_ITER(PG8_MMAZ)
.LBB0_1952:
	s_ashr_i32 s69, s68, 31
	s_lshl_b64 s[50:51], s[68:69], 20
	s_add_u32 s70, s1, s50
	ds_read_b128 v[0:3], v145
	ds_read_b128 v[4:7], v145 offset:1024
	ds_read_b128 v[8:11], v145 offset:2048
	ds_read_b128 v[12:15], v145 offset:3072
	ds_read_b128 v[16:19], v146
	ds_read_b128 v[20:23], v146 offset:1024
	ds_read_b128 v[24:27], v146 offset:2048
	ds_read_b128 v[28:31], v146 offset:3072
	s_addc_u32 s71, s8, s51
	s_ashr_i32 s67, s66, 31
	s_lshl_b64 s[50:51], s[66:67], 20
	s_add_u32 s72, s9, s50
	s_addc_u32 s73, s14, s51
	s_and_b64 s[50:51], s[2:3], exec
	s_cselect_b32 s50, s71, s79
	s_cselect_b32 s51, s70, s78
	s_cselect_b32 s52, s73, s77
	s_cselect_b32 s53, s72, s76
	s_add_u32 s56, s78, 0x80080
	s_addc_u32 s57, s79, 0
	s_add_i32 s54, s22, 0xc000
	v_lshl_add_u64 v[64:65], s[56:57], 0, v[134:135]
	s_mov_b32 m0, s54
	s_add_i32 s55, s22, 0xe000
	ds_read_b128 v[32:35], v147
	ds_read_b128 v[36:39], v147 offset:1024
	ds_read_b128 v[40:43], v147 offset:2048
	ds_read_b128 v[44:47], v147 offset:3072
	ds_read_b128 v[48:51], v147 offset:4096
	ds_read_b128 v[52:55], v147 offset:5120
	ds_read_b128 v[56:59], v147 offset:6144
	ds_read_b128 v[60:63], v147 offset:7168
	global_load_lds_dwordx4 v134, s[56:57]
	v_lshl_add_u64 v[64:65], s[56:57], 0, v[132:133]
	s_mov_b32 m0, s55
	s_nop 0
	global_load_lds_dwordx4 v132, s[56:57]
	s_waitcnt vmcnt(8) lgkmcnt(0)
	s_setprio 1
	s_barrier
	v_mfma_f32_16x16x32_bf16 v[88:91], v[0:3], v[56:59], 0
	v_mfma_f32_16x16x32_bf16 v[64:67], v[0:3], v[32:35], 0
	v_mfma_f32_16x16x32_bf16 v[68:71], v[8:11], v[32:35], 0
	v_mfma_f32_16x16x32_bf16 v[72:75], v[0:3], v[40:43], 0
	v_mfma_f32_16x16x32_bf16 v[76:79], v[8:11], v[40:43], 0
	v_mfma_f32_16x16x32_bf16 v[80:83], v[0:3], v[48:51], 0
	v_mfma_f32_16x16x32_bf16 v[84:87], v[8:11], v[48:51], 0
	v_mfma_f32_16x16x32_bf16 v[96:99], v[4:7], v[60:63], v[88:91]
	v_mfma_f32_16x16x32_bf16 v[88:91], v[8:11], v[56:59], 0
	v_mfma_f32_16x16x32_bf16 v[64:67], v[4:7], v[36:39], v[64:67]
	v_mfma_f32_16x16x32_bf16 v[68:71], v[12:15], v[36:39], v[68:71]
	v_mfma_f32_16x16x32_bf16 v[72:75], v[4:7], v[44:47], v[72:75]
	v_mfma_f32_16x16x32_bf16 v[76:79], v[12:15], v[44:47], v[76:79]
	v_mfma_f32_16x16x32_bf16 v[80:83], v[4:7], v[52:55], v[80:83]
	v_mfma_f32_16x16x32_bf16 v[84:87], v[12:15], v[52:55], v[84:87]
	v_mfma_f32_16x16x32_bf16 v[100:103], v[12:15], v[60:63], v[88:91]
	s_setprio 0
	s_setprio 1
	v_mfma_f32_16x16x32_bf16 v[88:91], v[16:19], v[32:35], 0
	v_mfma_f32_16x16x32_bf16 v[32:35], v[24:27], v[32:35], 0
	v_mfma_f32_16x16x32_bf16 v[112:115], v[20:23], v[36:39], v[88:91]
	v_mfma_f32_16x16x32_bf16 v[32:35], v[28:31], v[36:39], v[32:35]
	v_mfma_f32_16x16x32_bf16 v[36:39], v[16:19], v[40:43], 0
	v_mfma_f32_16x16x32_bf16 v[40:43], v[24:27], v[40:43], 0
	v_mfma_f32_16x16x32_bf16 v[36:39], v[20:23], v[44:47], v[36:39]
	v_mfma_f32_16x16x32_bf16 v[40:43], v[28:31], v[44:47], v[40:43]
	v_mfma_f32_16x16x32_bf16 v[44:47], v[16:19], v[48:51], 0
	v_mfma_f32_16x16x32_bf16 v[48:51], v[24:27], v[48:51], 0
	v_mfma_f32_16x16x32_bf16 v[44:47], v[20:23], v[52:55], v[44:47]
	v_mfma_f32_16x16x32_bf16 v[48:51], v[28:31], v[52:55], v[48:51]
	v_mfma_f32_16x16x32_bf16 v[52:55], v[16:19], v[56:59], 0
	v_mfma_f32_16x16x32_bf16 v[56:59], v[24:27], v[56:59], 0
	v_mfma_f32_16x16x32_bf16 v[52:55], v[20:23], v[60:63], v[52:55]
	v_mfma_f32_16x16x32_bf16 v[56:59], v[28:31], v[60:63], v[56:59]
	s_barrier
	s_setprio 0
	s_add_i32 s56, s47, s15
	v_lshl_add_u64 v[242:243], s[76:77], 0, v[128:129]
	s_add_i32 s57, s56, 0x2000
	v_lshl_add_u64 v[148:149], v[242:243], 0, s[62:63]
	s_mov_b32 m0, s56
	v_lshl_add_u64 v[244:245], s[76:77], 0, v[130:131]
	s_add_u32 s80, s76, 0x80100
	ds_read_b128 v[60:63], v147 offset:16384
	ds_read_b128 v[88:91], v147 offset:17408
	ds_read_b128 v[92:95], v147 offset:18432
	ds_read_b128 v[104:107], v147 offset:19456
	ds_read_b128 v[108:111], v147 offset:20480
	ds_read_b128 v[116:119], v147 offset:21504
	ds_read_b128 v[120:123], v147 offset:22528
	ds_read_b128 v[124:127], v147 offset:23552
	global_load_lds_dwordx4 v[148:149], off
	v_lshl_add_u64 v[148:149], v[244:245], 0, s[62:63]
	s_mov_b32 m0, s57
	s_addc_u32 s81, s77, 0
	s_add_i32 s58, s48, s15
	global_load_lds_dwordx4 v[148:149], off
	v_lshl_add_u64 v[148:149], s[80:81], 0, v[128:129]
	s_mov_b32 m0, s58
	s_add_i32 s59, s58, 0x2000
	global_load_lds_dwordx4 v128, s[80:81]
	v_lshl_add_u64 v[148:149], s[80:81], 0, v[130:131]
	s_mov_b32 m0, s59
	v_lshl_add_u64 v[246:247], s[78:79], 0, v[134:135]
	global_load_lds_dwordx4 v130, s[80:81]
	v_lshl_add_u64 v[148:149], v[246:247], 0, s[62:63]
	s_mov_b32 m0, s22
	v_lshl_add_u64 v[248:249], s[78:79], 0, v[132:133]
	global_load_lds_dwordx4 v[148:149], off
	v_lshl_add_u64 v[148:149], v[248:249], 0, s[62:63]
	s_mov_b32 m0, s23
	s_nop 0
	global_load_lds_dwordx4 v[148:149], off
	s_waitcnt vmcnt(8) lgkmcnt(0)
	s_setprio 1
	s_barrier
	v_mfma_f32_16x16x32_bf16 v[148:151], v[0:3], v[60:63], 0
	v_mfma_f32_16x16x32_bf16 v[158:161], v[0:3], v[92:95], 0
	v_mfma_f32_16x16x32_bf16 v[166:169], v[0:3], v[108:111], 0
	v_mfma_f32_16x16x32_bf16 v[0:3], v[0:3], v[120:123], 0
	v_mfma_f32_16x16x32_bf16 v[150:153], v[4:7], v[88:91], v[148:151]
	v_mfma_f32_16x16x32_bf16 v[158:161], v[4:7], v[104:107], v[158:161]
	v_mfma_f32_16x16x32_bf16 v[166:169], v[4:7], v[116:119], v[166:169]
	v_mfma_f32_16x16x32_bf16 v[0:3], v[4:7], v[124:127], v[0:3]
	v_mfma_f32_16x16x32_bf16 v[4:7], v[8:11], v[120:123], 0
	v_mfma_f32_16x16x32_bf16 v[154:157], v[8:11], v[60:63], 0
	v_mfma_f32_16x16x32_bf16 v[162:165], v[8:11], v[92:95], 0
	v_mfma_f32_16x16x32_bf16 v[170:173], v[8:11], v[108:111], 0
	v_mfma_f32_16x16x32_bf16 v[4:7], v[12:15], v[124:127], v[4:7]
	v_mfma_f32_16x16x32_bf16 v[154:157], v[12:15], v[88:91], v[154:157]
	v_mfma_f32_16x16x32_bf16 v[162:165], v[12:15], v[104:107], v[162:165]
	v_mfma_f32_16x16x32_bf16 v[170:173], v[12:15], v[116:119], v[170:173]
	s_setprio 0
	s_setprio 1
	v_mfma_f32_16x16x32_bf16 v[8:11], v[16:19], v[60:63], 0
	v_mfma_f32_16x16x32_bf16 v[174:177], v[20:23], v[88:91], v[8:11]
	v_mfma_f32_16x16x32_bf16 v[8:11], v[24:27], v[60:63], 0
	v_mfma_f32_16x16x32_bf16 v[60:63], v[28:31], v[88:91], v[8:11]
	v_mfma_f32_16x16x32_bf16 v[8:11], v[16:19], v[92:95], 0
	v_mfma_f32_16x16x32_bf16 v[178:181], v[20:23], v[104:107], v[8:11]
	v_mfma_f32_16x16x32_bf16 v[8:11], v[24:27], v[92:95], 0
	v_mfma_f32_16x16x32_bf16 v[182:185], v[28:31], v[104:107], v[8:11]
	v_mfma_f32_16x16x32_bf16 v[8:11], v[16:19], v[108:111], 0
	v_mfma_f32_16x16x32_bf16 v[186:189], v[20:23], v[116:119], v[8:11]
	v_mfma_f32_16x16x32_bf16 v[8:11], v[24:27], v[108:111], 0
	v_mfma_f32_16x16x32_bf16 v[190:193], v[28:31], v[116:119], v[8:11]
	v_mfma_f32_16x16x32_bf16 v[8:11], v[16:19], v[120:123], 0
	v_mfma_f32_16x16x32_bf16 v[194:197], v[20:23], v[124:127], v[8:11]
	v_mfma_f32_16x16x32_bf16 v[8:11], v[24:27], v[120:123], 0
	v_mfma_f32_16x16x32_bf16 v[198:201], v[28:31], v[124:127], v[8:11]
	s_barrier
	s_setprio 0
	s_add_i32 s67, 0, 0x18000
	s_add_i32 s75, 0, 0x1c000
	v_add_u32_e32 v148, s67, v144
	v_add_u32_e32 v149, s75, v144
	s_nop 0
	ds_read_b128 v[8:11], v148
	ds_read_b128 v[12:15], v148 offset:1024
	ds_read_b128 v[16:19], v148 offset:2048
	ds_read_b128 v[20:23], v148 offset:3072
	ds_read_b128 v[202:205], v149
	ds_read_b128 v[206:209], v149 offset:1024
	ds_read_b128 v[210:213], v149 offset:2048
	ds_read_b128 v[214:217], v149 offset:3072
	s_add_u32 s80, s78, 0x80100
	s_addc_u32 s81, s79, 0
	s_mov_b32 m0, s36
	v_lshl_add_u64 v[88:89], s[80:81], 0, v[134:135]
	ds_read_b128 v[24:27], v147 offset:32768
	ds_read_b128 v[28:31], v147 offset:33792
	ds_read_b128 v[218:221], v147 offset:34816
	ds_read_b128 v[222:225], v147 offset:35840
	ds_read_b128 v[226:229], v147 offset:36864
	ds_read_b128 v[230:233], v147 offset:37888
	ds_read_b128 v[234:237], v147 offset:38912
	ds_read_b128 v[238:241], v147 offset:39936
	global_load_lds_dwordx4 v134, s[80:81]
	v_lshl_add_u64 v[88:89], s[80:81], 0, v[132:133]
	s_mov_b32 m0, s37
	s_nop 0
	global_load_lds_dwordx4 v132, s[80:81]
	s_waitcnt vmcnt(8) lgkmcnt(0)
	s_setprio 1
	s_barrier
	v_mfma_f32_16x16x32_bf16 v[64:67], v[8:11], v[24:27], v[64:67]
	v_mfma_f32_16x16x32_bf16 v[120:123], v[12:15], v[28:31], v[64:67]
	v_mfma_f32_16x16x32_bf16 v[64:67], v[16:19], v[24:27], v[68:71]
	v_mfma_f32_16x16x32_bf16 v[124:127], v[20:23], v[28:31], v[64:67]
	v_mfma_f32_16x16x32_bf16 v[64:67], v[8:11], v[218:221], v[72:75]
	v_mfma_f32_16x16x32_bf16 v[104:107], v[12:15], v[222:225], v[64:67]
	v_mfma_f32_16x16x32_bf16 v[64:67], v[16:19], v[218:221], v[76:79]
	v_mfma_f32_16x16x32_bf16 v[108:111], v[20:23], v[222:225], v[64:67]
	v_mfma_f32_16x16x32_bf16 v[64:67], v[8:11], v[226:229], v[80:83]
	v_mfma_f32_16x16x32_bf16 v[88:91], v[12:15], v[230:233], v[64:67]
	v_mfma_f32_16x16x32_bf16 v[64:67], v[16:19], v[226:229], v[84:87]
	v_mfma_f32_16x16x32_bf16 v[92:95], v[20:23], v[230:233], v[64:67]
	v_mfma_f32_16x16x32_bf16 v[64:67], v[8:11], v[234:237], v[96:99]
	v_mfma_f32_16x16x32_bf16 v[68:71], v[16:19], v[234:237], v[100:103]
	v_mfma_f32_16x16x32_bf16 v[64:67], v[12:15], v[238:241], v[64:67]
	v_mfma_f32_16x16x32_bf16 v[68:71], v[20:23], v[238:241], v[68:71]
	s_setprio 0
	s_setprio 1
	v_mfma_f32_16x16x32_bf16 v[72:75], v[202:205], v[24:27], v[112:115]
	v_mfma_f32_16x16x32_bf16 v[24:27], v[210:213], v[24:27], v[32:35]
	v_mfma_f32_16x16x32_bf16 v[116:119], v[214:217], v[28:31], v[24:27]
	v_mfma_f32_16x16x32_bf16 v[24:27], v[202:205], v[218:221], v[36:39]
	v_mfma_f32_16x16x32_bf16 v[96:99], v[206:209], v[222:225], v[24:27]
	v_mfma_f32_16x16x32_bf16 v[24:27], v[210:213], v[218:221], v[40:43]
	v_mfma_f32_16x16x32_bf16 v[100:103], v[214:217], v[222:225], v[24:27]
	v_mfma_f32_16x16x32_bf16 v[24:27], v[202:205], v[226:229], v[44:47]
	v_mfma_f32_16x16x32_bf16 v[80:83], v[206:209], v[230:233], v[24:27]
	v_mfma_f32_16x16x32_bf16 v[24:27], v[210:213], v[226:229], v[48:51]
	v_mfma_f32_16x16x32_bf16 v[84:87], v[214:217], v[230:233], v[24:27]
	v_mfma_f32_16x16x32_bf16 v[24:27], v[202:205], v[234:237], v[52:55]
	v_mfma_f32_16x16x32_bf16 v[48:51], v[206:209], v[238:241], v[24:27]
	v_mfma_f32_16x16x32_bf16 v[24:27], v[210:213], v[234:237], v[56:59]
	v_mfma_f32_16x16x32_bf16 v[112:115], v[206:209], v[28:31], v[72:75]
	v_mfma_f32_16x16x32_bf16 v[52:55], v[214:217], v[238:241], v[24:27]
	s_barrier
; #define PG8_MMA(ai, bj, At, Bt) do { __builtin_amdgcn_s_setprio(1); _Pragma("unroll") for (int m = 0; m < 4; ++m) _Pragma("unroll") for (int n = 0; n < 2; ++n) _Pragma("unroll") for (int k = 0; k < 2; ++k) \
;         acc[ai][bj][m][n] = __builtin_amdgcn_mfma_f32_16x16x32_bf16(Bt[n][k], At[m][k], acc[ai][bj][m][n], 0, 0, 0); __builtin_amdgcn_s_setprio(0); } while (0)
; template <class Epi, class Sched, bool ALIGN_EPI = false, bool SP2 = false, bool A_TILED = false>
; __device__ __forceinline__ void gemm_phase(PG8_LAS unsigned char* lds, const Gemm g, const Sched& S, const Epi& E, const int wave_s) {
;     ...
;         for (int t = PEEL ? 2 : 0; t < nt; t += 2) {
;             const bool last = (t == nt - 2);
;             const char* a1 = cA + (size_t)(t + 1) * kstepA;
;             const char* a2 = last ? nA : cA + (size_t)(t + 2) * kstepA; const char* b2 = last ? nB : cB + (size_t)(t + 2) * kstep;
;             const char* a3 = a2 + kstepA; const char* b3 = b2 + kstep;
;             if (last && has_next) S.a_ready(nxt);
;             if constexpr (SP2) {
;             PG8_ITER(PG8_MMA)
	s_setprio 0
	s_add_i32 s67, s67, s15
	s_add_i32 s69, s67, 0x2000
	s_nop 1
	v_lshl_add_u64 v[24:25], v[242:243], 0, s[64:65]
	s_mov_b32 m0, s67
	s_add_u32 s80, s76, 0x80180
	ds_read_b128 v[32:35], v147 offset:49152
	ds_read_b128 v[36:39], v147 offset:50176
	ds_read_b128 v[218:221], v147 offset:51200
	ds_read_b128 v[222:225], v147 offset:52224
	ds_read_b128 v[226:229], v147 offset:53248
	ds_read_b128 v[230:233], v147 offset:54272
	ds_read_b128 v[234:237], v147 offset:55296
	ds_read_b128 v[238:241], v147 offset:56320
	global_load_lds_dwordx4 v[24:25], off
	v_lshl_add_u64 v[24:25], v[244:245], 0, s[64:65]
	s_mov_b32 m0, s69
	s_addc_u32 s81, s77, 0
	s_add_i32 s75, s75, s15
	global_load_lds_dwordx4 v[24:25], off
	v_lshl_add_u64 v[24:25], s[80:81], 0, v[128:129]
	s_mov_b32 m0, s75
	s_add_i32 s82, s75, 0x2000
	global_load_lds_dwordx4 v128, s[80:81]
	v_lshl_add_u64 v[24:25], s[80:81], 0, v[130:131]
	s_mov_b32 m0, s82
	s_nop 0
	global_load_lds_dwordx4 v130, s[80:81]
	v_lshl_add_u64 v[24:25], v[246:247], 0, s[64:65]
	s_mov_b32 m0, s43
	s_nop 0
	global_load_lds_dwordx4 v[24:25], off
	v_lshl_add_u64 v[24:25], v[248:249], 0, s[64:65]
	s_mov_b32 m0, s44
	s_nop 0
	global_load_lds_dwordx4 v[24:25], off
	s_waitcnt vmcnt(8) lgkmcnt(0)
	s_setprio 1
	s_barrier
	v_mfma_f32_16x16x32_bf16 v[24:27], v[8:11], v[32:35], v[150:153]
	v_mfma_f32_16x16x32_bf16 v[72:75], v[12:15], v[36:39], v[24:27]
	v_mfma_f32_16x16x32_bf16 v[24:27], v[16:19], v[32:35], v[154:157]
	v_mfma_f32_16x16x32_bf16 v[76:79], v[20:23], v[36:39], v[24:27]
	v_mfma_f32_16x16x32_bf16 v[24:27], v[8:11], v[218:221], v[158:161]
	v_mfma_f32_16x16x32_bf16 v[40:43], v[12:15], v[222:225], v[24:27]
	v_mfma_f32_16x16x32_bf16 v[24:27], v[16:19], v[218:221], v[162:165]
	v_mfma_f32_16x16x32_bf16 v[0:3], v[8:11], v[234:237], v[0:3]
	v_mfma_f32_16x16x32_bf16 v[44:47], v[20:23], v[222:225], v[24:27]
	v_mfma_f32_16x16x32_bf16 v[24:27], v[8:11], v[226:229], v[166:169]
	v_mfma_f32_16x16x32_bf16 v[28:31], v[16:19], v[226:229], v[170:173]
	v_mfma_f32_16x16x32_bf16 v[8:11], v[12:15], v[238:241], v[0:3]
	v_mfma_f32_16x16x32_bf16 v[0:3], v[16:19], v[234:237], v[4:7]
	v_mfma_f32_16x16x32_bf16 v[24:27], v[12:15], v[230:233], v[24:27]
	v_mfma_f32_16x16x32_bf16 v[28:31], v[20:23], v[230:233], v[28:31]
	v_mfma_f32_16x16x32_bf16 v[12:15], v[20:23], v[238:241], v[0:3]
	s_setprio 0
	s_setprio 1
	v_mfma_f32_16x16x32_bf16 v[0:3], v[202:205], v[32:35], v[174:177]
	v_mfma_f32_16x16x32_bf16 v[56:59], v[206:209], v[36:39], v[0:3]
	v_mfma_f32_16x16x32_bf16 v[0:3], v[210:213], v[32:35], v[60:63]
	v_mfma_f32_16x16x32_bf16 v[60:63], v[214:217], v[36:39], v[0:3]
	v_mfma_f32_16x16x32_bf16 v[0:3], v[202:205], v[218:221], v[178:181]
	v_mfma_f32_16x16x32_bf16 v[32:35], v[206:209], v[222:225], v[0:3]
	v_mfma_f32_16x16x32_bf16 v[0:3], v[210:213], v[218:221], v[182:185]
	v_mfma_f32_16x16x32_bf16 v[36:39], v[214:217], v[222:225], v[0:3]
	v_mfma_f32_16x16x32_bf16 v[0:3], v[202:205], v[226:229], v[186:189]
	v_mfma_f32_16x16x32_bf16 v[16:19], v[206:209], v[230:233], v[0:3]
	v_mfma_f32_16x16x32_bf16 v[0:3], v[210:213], v[226:229], v[190:193]
	v_mfma_f32_16x16x32_bf16 v[20:23], v[214:217], v[230:233], v[0:3]
	v_mfma_f32_16x16x32_bf16 v[0:3], v[202:205], v[234:237], v[194:197]
	v_mfma_f32_16x16x32_bf16 v[4:7], v[210:213], v[234:237], v[198:201]
	v_mfma_f32_16x16x32_bf16 v[0:3], v[206:209], v[238:241], v[0:3]
	v_mfma_f32_16x16x32_bf16 v[4:7], v[214:217], v[238:241], v[4:7]
	s_barrier
	s_setprio 0
	s_add_u32 s83, s76, 0x200
	s_addc_u32 s85, s77, 0
	s_add_u32 s76, s78, 0x80180
	s_addc_u32 s77, s79, 0
	s_mov_b32 s88, 0
.LBB0_1953:
	ds_read_b128 v[150:153], v145
	ds_read_b128 v[154:157], v145 offset:1024
	ds_read_b128 v[158:161], v145 offset:2048
	ds_read_b128 v[162:165], v145 offset:3072
	ds_read_b128 v[166:169], v146
	ds_read_b128 v[170:173], v146 offset:1024
	ds_read_b128 v[174:177], v146 offset:2048
	ds_read_b128 v[178:181], v146 offset:3072
	s_add_u32 s78, s76, 0xfff80080
	s_addc_u32 s79, s77, -1
	s_cmp_eq_u32 s88, 28
	s_cselect_b32 s81, s50, s79
	s_cselect_b32 s80, s51, s78
	s_cselect_b32 s79, s52, s85
	s_cselect_b32 s78, s53, s83
	s_mov_b32 m0, s54
	v_lshl_add_u64 v[214:215], s[76:77], 0, v[138:139]
	ds_read_b128 v[182:185], v147
	ds_read_b128 v[186:189], v147 offset:1024
	ds_read_b128 v[190:193], v147 offset:2048
	ds_read_b128 v[194:197], v147 offset:3072
	ds_read_b128 v[198:201], v147 offset:4096
	ds_read_b128 v[202:205], v147 offset:5120
	ds_read_b128 v[206:209], v147 offset:6144
	ds_read_b128 v[210:213], v147 offset:7168
	global_load_lds_dwordx4 v138, s[76:77]
	v_lshl_add_u64 v[214:215], s[76:77], 0, v[136:137]
	s_mov_b32 m0, s55
	s_nop 0
	global_load_lds_dwordx4 v136, s[76:77]
	s_waitcnt vmcnt(8) lgkmcnt(0)
	s_setprio 1
	s_barrier
; #define PG8_MMA(ai, bj, At, Bt) do { __builtin_amdgcn_s_setprio(1); _Pragma("unroll") for (int m = 0; m < 4; ++m) _Pragma("unroll") for (int n = 0; n < 2; ++n) _Pragma("unroll") for (int k = 0; k < 2; ++k) \
;         acc[ai][bj][m][n] = __builtin_amdgcn_mfma_f32_16x16x32_bf16(Bt[n][k], At[m][k], acc[ai][bj][m][n], 0, 0, 0); __builtin_amdgcn_s_setprio(0); } while (0)
; template <class Epi, class Sched, bool ALIGN_EPI = false, bool SP2 = false, bool A_TILED = false>
; __device__ __forceinline__ void gemm_phase(PG8_LAS unsigned char* lds, const Gemm g, const Sched& S, const Epi& E, const int wave_s) {
;     ...
;         for (int t = PEEL ? 2 : 0; t < nt; t += 2) {
;             const bool last = (t == nt - 2);
;             const char* a1 = cA + (size_t)(t + 1) * kstepA;
;             const char* a2 = last ? nA : cA + (size_t)(t + 2) * kstepA; const char* b2 = last ? nB : cB + (size_t)(t + 2) * kstep;
;             const char* a3 = a2 + kstepA; const char* b3 = b2 + kstep;
;             if (last && has_next) S.a_ready(nxt);
;             if constexpr (SP2) {
;             PG8_ITER(PG8_MMA)
	v_mfma_f32_16x16x32_bf16 v[120:123], v[150:153], v[182:185], v[120:123]
	v_mfma_f32_16x16x32_bf16 v[124:127], v[158:161], v[182:185], v[124:127]
	v_mfma_f32_16x16x32_bf16 v[104:107], v[150:153], v[190:193], v[104:107]
	v_mfma_f32_16x16x32_bf16 v[108:111], v[158:161], v[190:193], v[108:111]
	v_mfma_f32_16x16x32_bf16 v[88:91], v[150:153], v[198:201], v[88:91]
	v_mfma_f32_16x16x32_bf16 v[92:95], v[158:161], v[198:201], v[92:95]
	v_mfma_f32_16x16x32_bf16 v[64:67], v[150:153], v[206:209], v[64:67]
	v_mfma_f32_16x16x32_bf16 v[68:71], v[158:161], v[206:209], v[68:71]
	v_mfma_f32_16x16x32_bf16 v[120:123], v[154:157], v[186:189], v[120:123]
	v_mfma_f32_16x16x32_bf16 v[124:127], v[162:165], v[186:189], v[124:127]
	v_mfma_f32_16x16x32_bf16 v[104:107], v[154:157], v[194:197], v[104:107]
	v_mfma_f32_16x16x32_bf16 v[108:111], v[162:165], v[194:197], v[108:111]
	v_mfma_f32_16x16x32_bf16 v[88:91], v[154:157], v[202:205], v[88:91]
	v_mfma_f32_16x16x32_bf16 v[92:95], v[162:165], v[202:205], v[92:95]
	v_mfma_f32_16x16x32_bf16 v[64:67], v[154:157], v[210:213], v[64:67]
	v_mfma_f32_16x16x32_bf16 v[68:71], v[162:165], v[210:213], v[68:71]
	s_setprio 0
	s_setprio 1
	v_mfma_f32_16x16x32_bf16 v[112:115], v[166:169], v[182:185], v[112:115]
	v_mfma_f32_16x16x32_bf16 v[116:119], v[174:177], v[182:185], v[116:119]
	v_mfma_f32_16x16x32_bf16 v[96:99], v[166:169], v[190:193], v[96:99]
	v_mfma_f32_16x16x32_bf16 v[100:103], v[174:177], v[190:193], v[100:103]
	v_mfma_f32_16x16x32_bf16 v[80:83], v[166:169], v[198:201], v[80:83]
	v_mfma_f32_16x16x32_bf16 v[84:87], v[174:177], v[198:201], v[84:87]
	v_mfma_f32_16x16x32_bf16 v[48:51], v[166:169], v[206:209], v[48:51]
	v_mfma_f32_16x16x32_bf16 v[52:55], v[174:177], v[206:209], v[52:55]
	v_mfma_f32_16x16x32_bf16 v[112:115], v[170:173], v[186:189], v[112:115]
	v_mfma_f32_16x16x32_bf16 v[116:119], v[178:181], v[186:189], v[116:119]
	v_mfma_f32_16x16x32_bf16 v[96:99], v[170:173], v[194:197], v[96:99]
	v_mfma_f32_16x16x32_bf16 v[100:103], v[178:181], v[194:197], v[100:103]
	v_mfma_f32_16x16x32_bf16 v[80:83], v[170:173], v[202:205], v[80:83]
	v_mfma_f32_16x16x32_bf16 v[84:87], v[178:181], v[202:205], v[84:87]
	v_mfma_f32_16x16x32_bf16 v[48:51], v[170:173], v[210:213], v[48:51]
	v_mfma_f32_16x16x32_bf16 v[52:55], v[178:181], v[210:213], v[52:55]
	s_barrier
	s_setprio 0
	s_mov_b32 m0, s56
	v_lshl_add_u64 v[214:215], s[78:79], 0, v[128:129]
	s_add_u32 s90, s78, 0x80000
	ds_read_b128 v[182:185], v147 offset:16384
	ds_read_b128 v[186:189], v147 offset:17408
	ds_read_b128 v[190:193], v147 offset:18432
	ds_read_b128 v[194:197], v147 offset:19456
	ds_read_b128 v[198:201], v147 offset:20480
	ds_read_b128 v[202:205], v147 offset:21504
	ds_read_b128 v[206:209], v147 offset:22528
	ds_read_b128 v[210:213], v147 offset:23552
	global_load_lds_dwordx4 v128, s[78:79]
	v_lshl_add_u64 v[216:217], s[78:79], 0, v[130:131]
	s_mov_b32 m0, s57
	s_addc_u32 s91, s79, 0
	global_load_lds_dwordx4 v130, s[78:79]
	v_lshl_add_u64 v[218:219], s[90:91], 0, v[128:129]
	s_mov_b32 m0, s58
	v_lshl_add_u64 v[220:221], s[80:81], 0, v[132:133]
	global_load_lds_dwordx4 v128, s[90:91]
	v_lshl_add_u64 v[218:219], s[90:91], 0, v[130:131]
	s_mov_b32 m0, s59
	s_nop 0
	global_load_lds_dwordx4 v130, s[90:91]
	v_lshl_add_u64 v[218:219], s[80:81], 0, v[134:135]
	s_mov_b32 m0, s22
	s_nop 0
	global_load_lds_dwordx4 v134, s[80:81]
	s_mov_b32 m0, s23
	s_nop 0
	global_load_lds_dwordx4 v132, s[80:81]
	s_waitcnt vmcnt(8) lgkmcnt(0)
	s_setprio 1
	s_barrier
	v_mfma_f32_16x16x32_bf16 v[72:75], v[150:153], v[182:185], v[72:75]
	v_mfma_f32_16x16x32_bf16 v[76:79], v[158:161], v[182:185], v[76:79]
	v_mfma_f32_16x16x32_bf16 v[40:43], v[150:153], v[190:193], v[40:43]
	v_mfma_f32_16x16x32_bf16 v[44:47], v[158:161], v[190:193], v[44:47]
	v_mfma_f32_16x16x32_bf16 v[24:27], v[150:153], v[198:201], v[24:27]
	v_mfma_f32_16x16x32_bf16 v[28:31], v[158:161], v[198:201], v[28:31]
	v_mfma_f32_16x16x32_bf16 v[8:11], v[150:153], v[206:209], v[8:11]
	v_mfma_f32_16x16x32_bf16 v[12:15], v[158:161], v[206:209], v[12:15]
	v_mfma_f32_16x16x32_bf16 v[72:75], v[154:157], v[186:189], v[72:75]
	v_mfma_f32_16x16x32_bf16 v[76:79], v[162:165], v[186:189], v[76:79]
	v_mfma_f32_16x16x32_bf16 v[40:43], v[154:157], v[194:197], v[40:43]
	v_mfma_f32_16x16x32_bf16 v[44:47], v[162:165], v[194:197], v[44:47]
	v_mfma_f32_16x16x32_bf16 v[24:27], v[154:157], v[202:205], v[24:27]
	v_mfma_f32_16x16x32_bf16 v[28:31], v[162:165], v[202:205], v[28:31]
	v_mfma_f32_16x16x32_bf16 v[8:11], v[154:157], v[210:213], v[8:11]
	v_mfma_f32_16x16x32_bf16 v[12:15], v[162:165], v[210:213], v[12:15]
	s_setprio 0
	s_setprio 1
	v_mfma_f32_16x16x32_bf16 v[56:59], v[166:169], v[182:185], v[56:59]
	v_mfma_f32_16x16x32_bf16 v[60:63], v[174:177], v[182:185], v[60:63]
	v_mfma_f32_16x16x32_bf16 v[32:35], v[166:169], v[190:193], v[32:35]
	v_mfma_f32_16x16x32_bf16 v[36:39], v[174:177], v[190:193], v[36:39]
	v_mfma_f32_16x16x32_bf16 v[16:19], v[166:169], v[198:201], v[16:19]
	v_mfma_f32_16x16x32_bf16 v[20:23], v[174:177], v[198:201], v[20:23]
	v_mfma_f32_16x16x32_bf16 v[0:3], v[166:169], v[206:209], v[0:3]
	v_mfma_f32_16x16x32_bf16 v[4:7], v[174:177], v[206:209], v[4:7]
	v_mfma_f32_16x16x32_bf16 v[56:59], v[170:173], v[186:189], v[56:59]
	v_mfma_f32_16x16x32_bf16 v[60:63], v[178:181], v[186:189], v[60:63]
	v_mfma_f32_16x16x32_bf16 v[32:35], v[170:173], v[194:197], v[32:35]
	v_mfma_f32_16x16x32_bf16 v[36:39], v[178:181], v[194:197], v[36:39]
	v_mfma_f32_16x16x32_bf16 v[16:19], v[170:173], v[202:205], v[16:19]
	v_mfma_f32_16x16x32_bf16 v[20:23], v[178:181], v[202:205], v[20:23]
	v_mfma_f32_16x16x32_bf16 v[0:3], v[170:173], v[210:213], v[0:3]
	v_mfma_f32_16x16x32_bf16 v[4:7], v[178:181], v[210:213], v[4:7]
	s_barrier
; #define PG8_MMA(ai, bj, At, Bt) do { __builtin_amdgcn_s_setprio(1); _Pragma("unroll") for (int m = 0; m < 4; ++m) _Pragma("unroll") for (int n = 0; n < 2; ++n) _Pragma("unroll") for (int k = 0; k < 2; ++k) \
;         acc[ai][bj][m][n] = __builtin_amdgcn_mfma_f32_16x16x32_bf16(Bt[n][k], At[m][k], acc[ai][bj][m][n], 0, 0, 0); __builtin_amdgcn_s_setprio(0); } while (0)
; template <class Epi, class Sched, bool ALIGN_EPI = false, bool SP2 = false, bool A_TILED = false>
; __device__ __forceinline__ void gemm_phase(PG8_LAS unsigned char* lds, const Gemm g, const Sched& S, const Epi& E, const int wave_s) {
;     ...
;         for (int t = PEEL ? 2 : 0; t < nt; t += 2) {
;             const bool last = (t == nt - 2);
;             const char* a1 = cA + (size_t)(t + 1) * kstepA;
;             const char* a2 = last ? nA : cA + (size_t)(t + 2) * kstepA; const char* b2 = last ? nB : cB + (size_t)(t + 2) * kstep;
;             const char* a3 = a2 + kstepA; const char* b3 = b2 + kstep;
;             if (last && has_next) S.a_ready(nxt);
;             if constexpr (SP2) {
;             PG8_ITER(PG8_MMA)
	s_setprio 0
	ds_read_b128 v[150:153], v148
	ds_read_b128 v[154:157], v148 offset:1024
	ds_read_b128 v[158:161], v148 offset:2048
	ds_read_b128 v[162:165], v148 offset:3072
	ds_read_b128 v[166:169], v149
	ds_read_b128 v[170:173], v149 offset:1024
	ds_read_b128 v[174:177], v149 offset:2048
	ds_read_b128 v[178:181], v149 offset:3072
	s_add_u32 s80, s80, 0x80000
	s_addc_u32 s81, s81, 0
	s_mov_b32 m0, s36
	v_lshl_add_u64 v[222:223], s[80:81], 0, v[134:135]
	ds_read_b128 v[182:185], v147 offset:32768
	ds_read_b128 v[186:189], v147 offset:33792
	ds_read_b128 v[190:193], v147 offset:34816
	ds_read_b128 v[194:197], v147 offset:35840
	ds_read_b128 v[198:201], v147 offset:36864
	ds_read_b128 v[202:205], v147 offset:37888
	ds_read_b128 v[206:209], v147 offset:38912
	ds_read_b128 v[210:213], v147 offset:39936
	global_load_lds_dwordx4 v134, s[80:81]
	v_lshl_add_u64 v[222:223], s[80:81], 0, v[132:133]
	s_mov_b32 m0, s37
	s_nop 0
	global_load_lds_dwordx4 v132, s[80:81]
	s_waitcnt vmcnt(8) lgkmcnt(0)
	s_setprio 1
	s_barrier
	v_mfma_f32_16x16x32_bf16 v[120:123], v[150:153], v[182:185], v[120:123]
	v_mfma_f32_16x16x32_bf16 v[124:127], v[158:161], v[182:185], v[124:127]
	v_mfma_f32_16x16x32_bf16 v[104:107], v[150:153], v[190:193], v[104:107]
	v_mfma_f32_16x16x32_bf16 v[108:111], v[158:161], v[190:193], v[108:111]
	v_mfma_f32_16x16x32_bf16 v[88:91], v[150:153], v[198:201], v[88:91]
	v_mfma_f32_16x16x32_bf16 v[92:95], v[158:161], v[198:201], v[92:95]
	v_mfma_f32_16x16x32_bf16 v[64:67], v[150:153], v[206:209], v[64:67]
	v_mfma_f32_16x16x32_bf16 v[68:71], v[158:161], v[206:209], v[68:71]
	v_mfma_f32_16x16x32_bf16 v[120:123], v[154:157], v[186:189], v[120:123]
	v_mfma_f32_16x16x32_bf16 v[124:127], v[162:165], v[186:189], v[124:127]
	v_mfma_f32_16x16x32_bf16 v[104:107], v[154:157], v[194:197], v[104:107]
	v_mfma_f32_16x16x32_bf16 v[108:111], v[162:165], v[194:197], v[108:111]
	v_mfma_f32_16x16x32_bf16 v[88:91], v[154:157], v[202:205], v[88:91]
	v_mfma_f32_16x16x32_bf16 v[92:95], v[162:165], v[202:205], v[92:95]
	v_mfma_f32_16x16x32_bf16 v[64:67], v[154:157], v[210:213], v[64:67]
	v_mfma_f32_16x16x32_bf16 v[68:71], v[162:165], v[210:213], v[68:71]
	s_setprio 0
	s_setprio 1
	v_mfma_f32_16x16x32_bf16 v[112:115], v[166:169], v[182:185], v[112:115]
	v_mfma_f32_16x16x32_bf16 v[116:119], v[174:177], v[182:185], v[116:119]
	v_mfma_f32_16x16x32_bf16 v[96:99], v[166:169], v[190:193], v[96:99]
	v_mfma_f32_16x16x32_bf16 v[100:103], v[174:177], v[190:193], v[100:103]
	v_mfma_f32_16x16x32_bf16 v[80:83], v[166:169], v[198:201], v[80:83]
	v_mfma_f32_16x16x32_bf16 v[84:87], v[174:177], v[198:201], v[84:87]
	v_mfma_f32_16x16x32_bf16 v[48:51], v[166:169], v[206:209], v[48:51]
	v_mfma_f32_16x16x32_bf16 v[52:55], v[174:177], v[206:209], v[52:55]
	v_mfma_f32_16x16x32_bf16 v[112:115], v[170:173], v[186:189], v[112:115]
	v_mfma_f32_16x16x32_bf16 v[116:119], v[178:181], v[186:189], v[116:119]
	v_mfma_f32_16x16x32_bf16 v[96:99], v[170:173], v[194:197], v[96:99]
	v_mfma_f32_16x16x32_bf16 v[100:103], v[178:181], v[194:197], v[100:103]
	v_mfma_f32_16x16x32_bf16 v[80:83], v[170:173], v[202:205], v[80:83]
	v_mfma_f32_16x16x32_bf16 v[84:87], v[178:181], v[202:205], v[84:87]
	v_mfma_f32_16x16x32_bf16 v[48:51], v[170:173], v[210:213], v[48:51]
	v_mfma_f32_16x16x32_bf16 v[52:55], v[178:181], v[210:213], v[52:55]
	s_barrier
	s_setprio 0
	s_mov_b32 m0, s67
	v_lshl_add_u64 v[214:215], v[214:215], 0, s[12:13]
	s_add_u32 s78, s78, 0x80080
	ds_read_b128 v[182:185], v147 offset:49152
	ds_read_b128 v[186:189], v147 offset:50176
	ds_read_b128 v[190:193], v147 offset:51200
	ds_read_b128 v[194:197], v147 offset:52224
	ds_read_b128 v[198:201], v147 offset:53248
	ds_read_b128 v[202:205], v147 offset:54272
	ds_read_b128 v[206:209], v147 offset:55296
	ds_read_b128 v[210:213], v147 offset:56320
	global_load_lds_dwordx4 v[214:215], off
	v_lshl_add_u64 v[214:215], v[216:217], 0, s[12:13]
	s_mov_b32 m0, s69
	s_addc_u32 s79, s79, 0
	global_load_lds_dwordx4 v[214:215], off
	v_lshl_add_u64 v[214:215], s[78:79], 0, v[128:129]
	s_mov_b32 m0, s75
	s_nop 0
	global_load_lds_dwordx4 v128, s[78:79]
	v_lshl_add_u64 v[214:215], s[78:79], 0, v[130:131]
	s_mov_b32 m0, s82
	s_nop 0
	global_load_lds_dwordx4 v130, s[78:79]
	v_lshl_add_u64 v[214:215], v[218:219], 0, s[12:13]
	s_mov_b32 m0, s43
	s_nop 0
	global_load_lds_dwordx4 v[214:215], off
	v_lshl_add_u64 v[214:215], v[220:221], 0, s[12:13]
	s_mov_b32 m0, s44
	s_nop 0
	global_load_lds_dwordx4 v[214:215], off
	s_waitcnt vmcnt(8) lgkmcnt(0)
	s_setprio 1
	s_barrier
	v_mfma_f32_16x16x32_bf16 v[72:75], v[150:153], v[182:185], v[72:75]
	v_mfma_f32_16x16x32_bf16 v[76:79], v[158:161], v[182:185], v[76:79]
	v_mfma_f32_16x16x32_bf16 v[40:43], v[150:153], v[190:193], v[40:43]
	v_mfma_f32_16x16x32_bf16 v[44:47], v[158:161], v[190:193], v[44:47]
	v_mfma_f32_16x16x32_bf16 v[24:27], v[150:153], v[198:201], v[24:27]
	v_mfma_f32_16x16x32_bf16 v[28:31], v[158:161], v[198:201], v[28:31]
	v_mfma_f32_16x16x32_bf16 v[8:11], v[150:153], v[206:209], v[8:11]
	v_mfma_f32_16x16x32_bf16 v[12:15], v[158:161], v[206:209], v[12:15]
	v_mfma_f32_16x16x32_bf16 v[72:75], v[154:157], v[186:189], v[72:75]
	v_mfma_f32_16x16x32_bf16 v[76:79], v[162:165], v[186:189], v[76:79]
	v_mfma_f32_16x16x32_bf16 v[40:43], v[154:157], v[194:197], v[40:43]
	v_mfma_f32_16x16x32_bf16 v[44:47], v[162:165], v[194:197], v[44:47]
	v_mfma_f32_16x16x32_bf16 v[24:27], v[154:157], v[202:205], v[24:27]
	v_mfma_f32_16x16x32_bf16 v[28:31], v[162:165], v[202:205], v[28:31]
	v_mfma_f32_16x16x32_bf16 v[8:11], v[154:157], v[210:213], v[8:11]
	v_mfma_f32_16x16x32_bf16 v[12:15], v[162:165], v[210:213], v[12:15]
	s_setprio 0
	s_setprio 1
	v_mfma_f32_16x16x32_bf16 v[56:59], v[166:169], v[182:185], v[56:59]
	v_mfma_f32_16x16x32_bf16 v[60:63], v[174:177], v[182:185], v[60:63]
	v_mfma_f32_16x16x32_bf16 v[32:35], v[166:169], v[190:193], v[32:35]
	v_mfma_f32_16x16x32_bf16 v[36:39], v[174:177], v[190:193], v[36:39]
	v_mfma_f32_16x16x32_bf16 v[16:19], v[166:169], v[198:201], v[16:19]
	v_mfma_f32_16x16x32_bf16 v[20:23], v[174:177], v[198:201], v[20:23]
	v_mfma_f32_16x16x32_bf16 v[0:3], v[166:169], v[206:209], v[0:3]
	v_mfma_f32_16x16x32_bf16 v[4:7], v[174:177], v[206:209], v[4:7]
	v_mfma_f32_16x16x32_bf16 v[56:59], v[170:173], v[186:189], v[56:59]
	v_mfma_f32_16x16x32_bf16 v[60:63], v[178:181], v[186:189], v[60:63]
	v_mfma_f32_16x16x32_bf16 v[32:35], v[170:173], v[194:197], v[32:35]
	v_mfma_f32_16x16x32_bf16 v[36:39], v[178:181], v[194:197], v[36:39]
	v_mfma_f32_16x16x32_bf16 v[16:19], v[170:173], v[202:205], v[16:19]
	v_mfma_f32_16x16x32_bf16 v[20:23], v[178:181], v[202:205], v[20:23]
	v_mfma_f32_16x16x32_bf16 v[0:3], v[170:173], v[210:213], v[0:3]
	v_mfma_f32_16x16x32_bf16 v[4:7], v[178:181], v[210:213], v[4:7]
	s_barrier
	s_setprio 0
	s_add_i32 s88, s88, 2
	s_add_u32 s83, s83, 0x100
	s_addc_u32 s85, s85, 0
	s_add_u32 s76, s76, 0x100
	s_addc_u32 s77, s77, 0
	s_cmp_gt_u32 s88, 29
	s_cbranch_scc0 .LBB0_1953
	s_and_b64 vcc, exec, s[60:61]
	s_cbranch_vccz .LBB0_1956
	s_barrier

; #define PG8_STAGE(bufoff, gbase, voff) do { _Pragma("unroll") for (int _i = 0; _i < 2; ++_i) \
;         __builtin_amdgcn_global_load_lds((const unsigned*)((const char*)(gbase) + (voff)[_i]), (PG8_LAS unsigned*)(lds + (bufoff) + ldsw + _i * 8192), 16, 0, 0); } while (0)
; #define PG8_WAIT_V(n) asm volatile("s_waitcnt vmcnt(" #n ")" ::: "memory")
; template <class Epi, class Sched, bool ALIGN_EPI = false, bool SP2 = false, bool A_TILED = false>
; __device__ __forceinline__ void gemm_phase(PG8_LAS unsigned char* lds, const Gemm g, const Sched& S, const Epi& E, const int wave_s) {
;     ...
;     if constexpr (SP2) {
;         PG8_STAGE(PG8_SB(0, 0), cB, voffB); PG8_STAGE(PG8_SB(0, 1), cB + hstep, voffB); PG8_STAGE(PG8_SA(0, 0), cA, voffA); PG8_STAGE(PG8_SA(0, 1), cA + hstepA, voffA);
;         if (wr == 1) PG8_BAR;
;         PG8_WAIT_V(2); PG8_BAR;
;         PG8_STAGE(PG8_SB(1, 0), cB + kstep, voffB); PG8_STAGE(PG8_SA(1, 0), cA + kstepA, voffA); PG8_STAGE(PG8_SB(1, 1), cB + hstep + kstep, voffB);
;         PG8_WAIT_V(6); PG8_BAR;
;     } else {
;         PG8_STAGE(PG8_SB(0, 0), cB, voffB); PG8_STAGE(PG8_SA(0, 0), cA, voffA); PG8_STAGE(PG8_SB(0, 1), cB + hstep, voffB); PG8_STAGE(PG8_SA(0, 1), cA + hstepA, voffA);
;         if (wr == 1) PG8_BAR;
;         PG8_WAIT_V(4); PG8_BAR;
;         PG8_STAGE(PG8_SB(1, 0), cB + kstep, voffB); PG8_STAGE(PG8_SA(1, 0), cA + kstepA, voffA); PG8_STAGE(PG8_SB(1, 1), cB + hstep + kstep, voffB);
;         PG8_WAIT_V(6); PG8_BAR;
;     }
;     for (;;) {
;         const bool has_next = Epi::AFTER_DRAIN ? false : S.next(ui + 1, nxt);
;         const char* nA = has_next ? (const char*)g.A + (size_t)nxt.pm * tstepA : cA; const char* nB = has_next ? (const char*)g.Bt + (size_t)nxt.pn * tstep : cB;
;         constexpr bool PEEL = SP2 && !Epi::AFTER_DRAIN;
;         if constexpr (PEEL) {
;             const char* a1 = cA + kstepA; const char* a2 = cA + 2 * kstepA; const char* b2 = cB + 2 * kstep; const char* a3 = a2 + kstepA; const char* b3 = b2 + kstep;
;             PG8_ITER(PG8_MMAZ)
;         } else {
; #pragma unroll
;             for (int a = 0; a < 2; ++a)
; #pragma unroll
;                 for (int b = 0; b < 2; ++b)
; #pragma unroll
;                     for (int m = 0; m < 4; ++m)
; #pragma unroll
;                         for (int n = 0; n < 2; ++n) acc[a][b][m][n] = (f32x4){0.f, 0.f, 0.f, 0.f};
.LBB0_2025:
	v_and_b32_e32 v5, 48, v4
	v_lshlrev_b32_e32 v6, 6, v4
	s_movk_i32 s36, 0x3c0
	v_lshlrev_b32_e32 v4, 2, v4
	s_mov_b64 s[64:65], 0x80
	s_and_b32 s9, s1, 3
	s_lshl_b32 s8, s23, 6
	s_lshl_b32 s23, s23, 13
	v_and_or_b32 v5, v6, s36, v5
	v_and_b32_e32 v4, 32, v4
	s_add_i32 m0, s14, 0x18000
	v_lshl_add_u64 v[2:3], v[2:3], 0, s[64:65]
	v_bitop3_b32 v6, v5, s23, v4 bitop3:0xde
	s_lshl_b32 s23, s9, 12
	s_waitcnt vmcnt(2)
	s_barrier
	global_load_lds_dwordx4 v[2:3], off
	s_add_i32 m0, s14, 0x1a000
	s_add_u32 s36, s6, 0x8000
	v_bitop3_b32 v4, v5, s23, v4 bitop3:0xde
	v_lshl_add_u64 v[0:1], v[0:1], 0, s[64:65]
	s_addc_u32 s37, s7, 0
	s_add_i32 s23, s14, 0x8000
	global_load_lds_dwordx4 v[0:1], off
	v_lshl_add_u64 v[0:1], s[36:37], 0, v[32:33]
	s_mov_b32 m0, s23
	s_mov_b64 s[40:41], 0x3460c000
	global_load_lds_dwordx4 v32, s[36:37]
	v_lshl_add_u64 v[0:1], s[36:37], 0, v[132:133]
	s_add_i32 s36, s14, 0xa000
	s_add_u32 s38, s2, 0x200080
	s_mov_b32 m0, s36
	s_addc_u32 s39, s3, 0
	global_load_lds_dwordx4 v[0:1], off
	s_add_i32 m0, s14, 0x1c000
	v_lshl_add_u64 v[0:1], s[38:39], 0, v[34:35]
	global_load_lds_dwordx4 v34, s[38:39]
	v_lshl_add_u64 v[0:1], s[38:39], 0, v[134:135]
	s_add_i32 m0, s14, 0x1e000
	s_add_u32 s37, s68, 0x14600100
	global_load_lds_dwordx4 v134, s[38:39]
	s_addc_u32 s38, s69, 0
	v_lshl_add_u64 v[0:1], s[66:67], 0, v[132:133]
	v_lshl_add_u64 v[136:137], v[0:1], 0, s[40:41]
	v_lshl_add_u64 v[0:1], s[66:67], 0, v[32:33]
	s_add_u32 s39, s66, 0x34610000
	s_waitcnt vmcnt(6)
	v_lshl_add_u64 v[138:139], v[0:1], 0, s[40:41]
	s_addc_u32 s40, s67, 0
	s_add_i32 s44, 0, 0x10000
	s_add_i32 s46, 0, 0x14000
	s_add_i32 s48, 0, 0x18000
	s_add_i32 s51, 0, 0x1c000
	v_add_u32_e32 v140, s44, v4
	v_add_u32_e32 v141, s46, v4
	s_add_i32 s44, s44, s50
	s_add_i32 s46, s46, s50
	v_add_u32_e32 v143, s48, v4
	s_add_i32 s48, s48, s50
	s_add_i32 s50, s51, s50
	s_mov_b32 s41, -2
	v_add_u32_e32 v142, 0, v6
	s_add_i32 s42, s14, 0xc000
	s_add_i32 s43, s14, 0xe000
	s_add_i32 s45, s44, 0x2000
	s_add_i32 s47, s46, 0x2000
	v_add_u32_e32 v144, s51, v4
	s_add_i32 s49, s48, 0x2000
	s_add_i32 s51, s50, 0x2000
	s_mov_b64 s[66:67], 0x10000
	v_mov_b32_e32 v0, v35
	v_mov_b32_e32 v1, v35
	v_mov_b32_e32 v2, v35
	v_mov_b32_e32 v3, v35
	v_mov_b32_e32 v4, v35
	v_mov_b32_e32 v5, v35
	v_mov_b32_e32 v6, v35
	v_mov_b32_e32 v7, v35
	v_mov_b32_e32 v40, v35
	v_mov_b32_e32 v41, v35
	v_mov_b32_e32 v42, v35
	v_mov_b32_e32 v43, v35
	v_mov_b32_e32 v44, v35
	v_mov_b32_e32 v45, v35
	v_mov_b32_e32 v46, v35
	v_mov_b32_e32 v47, v35
	v_mov_b32_e32 v88, v35
	v_mov_b32_e32 v89, v35
	v_mov_b32_e32 v90, v35
	v_mov_b32_e32 v91, v35
	v_mov_b32_e32 v92, v35
	v_mov_b32_e32 v93, v35
	v_mov_b32_e32 v94, v35
	v_mov_b32_e32 v95, v35
	v_mov_b32_e32 v112, v35
	v_mov_b32_e32 v113, v35
	v_mov_b32_e32 v114, v35
	v_mov_b32_e32 v115, v35
	v_mov_b32_e32 v124, v35
	v_mov_b32_e32 v125, v35
	v_mov_b32_e32 v126, v35
	v_mov_b32_e32 v127, v35
	v_mov_b32_e32 v24, v35
	v_mov_b32_e32 v25, v35
	v_mov_b32_e32 v26, v35
	v_mov_b32_e32 v27, v35
	v_mov_b32_e32 v36, v35
	v_mov_b32_e32 v37, v35
	v_mov_b32_e32 v38, v35
	v_mov_b32_e32 v39, v35
	v_mov_b32_e32 v80, v35
	v_mov_b32_e32 v81, v35
	v_mov_b32_e32 v82, v35
	v_mov_b32_e32 v83, v35
	v_mov_b32_e32 v84, v35
	v_mov_b32_e32 v85, v35
	v_mov_b32_e32 v86, v35
	v_mov_b32_e32 v87, v35
	v_mov_b32_e32 v120, v35
	v_mov_b32_e32 v121, v35
	v_mov_b32_e32 v122, v35
	v_mov_b32_e32 v123, v35
	v_mov_b32_e32 v116, v35
	v_mov_b32_e32 v117, v35
	v_mov_b32_e32 v118, v35
	v_mov_b32_e32 v119, v35
	v_mov_b32_e32 v104, v35
	v_mov_b32_e32 v105, v35
	v_mov_b32_e32 v106, v35
	v_mov_b32_e32 v107, v35
	v_mov_b32_e32 v100, v35
	v_mov_b32_e32 v101, v35
	v_mov_b32_e32 v102, v35
	v_mov_b32_e32 v103, v35
	v_mov_b32_e32 v96, v35
	v_mov_b32_e32 v97, v35
	v_mov_b32_e32 v98, v35
	v_mov_b32_e32 v99, v35
	v_mov_b32_e32 v108, v35
	v_mov_b32_e32 v109, v35
	v_mov_b32_e32 v110, v35
	v_mov_b32_e32 v111, v35
	v_mov_b32_e32 v64, v35
	v_mov_b32_e32 v65, v35
	v_mov_b32_e32 v66, v35
	v_mov_b32_e32 v67, v35
	v_mov_b32_e32 v72, v35
	v_mov_b32_e32 v73, v35
	v_mov_b32_e32 v74, v35
	v_mov_b32_e32 v75, v35
	v_mov_b32_e32 v48, v35
	v_mov_b32_e32 v49, v35
	v_mov_b32_e32 v50, v35
	v_mov_b32_e32 v51, v35
	v_mov_b32_e32 v56, v35
	v_mov_b32_e32 v57, v35
	v_mov_b32_e32 v58, v35
	v_mov_b32_e32 v59, v35
	v_mov_b32_e32 v16, v35
	v_mov_b32_e32 v17, v35
	v_mov_b32_e32 v18, v35
	v_mov_b32_e32 v19, v35
	v_mov_b32_e32 v28, v35
	v_mov_b32_e32 v29, v35
	v_mov_b32_e32 v30, v35
	v_mov_b32_e32 v31, v35
	v_mov_b32_e32 v68, v35
	v_mov_b32_e32 v69, v35
	v_mov_b32_e32 v70, v35
	v_mov_b32_e32 v71, v35
	v_mov_b32_e32 v128, v35
	v_mov_b32_e32 v129, v35
	v_mov_b32_e32 v130, v35
	v_mov_b32_e32 v131, v35
	v_mov_b32_e32 v52, v35
	v_mov_b32_e32 v53, v35
	v_mov_b32_e32 v54, v35
	v_mov_b32_e32 v55, v35
	v_mov_b32_e32 v76, v35
	v_mov_b32_e32 v77, v35
	v_mov_b32_e32 v78, v35
	v_mov_b32_e32 v79, v35
	v_mov_b32_e32 v20, v35
	v_mov_b32_e32 v21, v35
	v_mov_b32_e32 v22, v35
	v_mov_b32_e32 v23, v35
	v_mov_b32_e32 v60, v35
	v_mov_b32_e32 v61, v35
	v_mov_b32_e32 v62, v35
	v_mov_b32_e32 v63, v35
	v_mov_b32_e32 v12, v35
	v_mov_b32_e32 v13, v35
	v_mov_b32_e32 v14, v35
	v_mov_b32_e32 v15, v35
	v_mov_b32_e32 v8, v35
	v_mov_b32_e32 v9, v35
	v_mov_b32_e32 v10, v35
	v_mov_b32_e32 v11, v35
	s_barrier
; #define PG8_MMA(ai, bj, At, Bt) do { __builtin_amdgcn_s_setprio(1); _Pragma("unroll") for (int m = 0; m < 4; ++m) _Pragma("unroll") for (int n = 0; n < 2; ++n) _Pragma("unroll") for (int k = 0; k < 2; ++k) \
;         acc[ai][bj][m][n] = __builtin_amdgcn_mfma_f32_16x16x32_bf16(Bt[n][k], At[m][k], acc[ai][bj][m][n], 0, 0, 0); __builtin_amdgcn_s_setprio(0); } while (0)
; template <class Epi, class Sched, bool ALIGN_EPI = false, bool SP2 = false, bool A_TILED = false>
; __device__ __forceinline__ void gemm_phase(PG8_LAS unsigned char* lds, const Gemm g, const Sched& S, const Epi& E, const int wave_s) {
;     ...
;         for (int t = PEEL ? 2 : 0; t < nt; t += 2) {
;             const bool last = (t == nt - 2);
;             const char* a1 = cA + (size_t)(t + 1) * kstepA;
;             const char* a2 = last ? nA : cA + (size_t)(t + 2) * kstepA; const char* b2 = last ? nB : cB + (size_t)(t + 2) * kstep;
;             const char* a3 = a2 + kstepA; const char* b3 = b2 + kstep;
;             if (last && has_next) S.a_ready(nxt);
;             if constexpr (SP2) {
;             PG8_ITER(PG8_MMA)
.LBB0_2026:
	ds_read_b128 v[146:149], v140
	ds_read_b128 v[150:153], v140 offset:1024
	ds_read_b128 v[154:157], v140 offset:2048
	ds_read_b128 v[158:161], v140 offset:3072
	ds_read_b128 v[162:165], v141
	ds_read_b128 v[166:169], v141 offset:1024
	ds_read_b128 v[170:173], v141 offset:2048
	ds_read_b128 v[174:177], v141 offset:3072
	s_add_u32 s52, s60, s39
	s_addc_u32 s53, s61, s40
	s_add_u32 s54, s60, s37
	s_addc_u32 s55, s61, s38
	s_cmpk_eq_i32 s41, 0x7c
	s_cselect_b32 s72, s6, s52
	s_cselect_b32 s73, s7, s53
	s_cselect_b32 s70, s2, s54
	s_cselect_b32 s71, s3, s55
	s_add_u32 s68, s72, 0x8000
	s_addc_u32 s69, s73, 0
	s_mov_b32 m0, s42
	v_lshl_add_u64 v[210:211], s[60:61], 0, v[138:139]
	ds_read_b128 v[178:181], v142
	ds_read_b128 v[182:185], v142 offset:1024
	ds_read_b128 v[186:189], v142 offset:2048
	ds_read_b128 v[190:193], v142 offset:3072
	ds_read_b128 v[194:197], v142 offset:4096
	ds_read_b128 v[198:201], v142 offset:5120
	ds_read_b128 v[202:205], v142 offset:6144
	ds_read_b128 v[206:209], v142 offset:7168
	global_load_lds_dwordx4 v[210:211], off
	v_lshl_add_u64 v[210:211], s[60:61], 0, v[136:137]
	s_mov_b32 m0, s43
	s_nop 0
	global_load_lds_dwordx4 v[210:211], off
	s_waitcnt vmcnt(8) lgkmcnt(0)
	s_setprio 1
	s_barrier
	v_mfma_f32_16x16x32_bf16 v[8:11], v[146:149], v[178:181], v[8:11]
	v_mfma_f32_16x16x32_bf16 v[12:15], v[154:157], v[178:181], v[12:15]
	v_mfma_f32_16x16x32_bf16 v[60:63], v[146:149], v[186:189], v[60:63]
	v_mfma_f32_16x16x32_bf16 v[20:23], v[154:157], v[186:189], v[20:23]
	v_mfma_f32_16x16x32_bf16 v[76:79], v[146:149], v[194:197], v[76:79]
	v_mfma_f32_16x16x32_bf16 v[52:55], v[154:157], v[194:197], v[52:55]
	v_mfma_f32_16x16x32_bf16 v[128:131], v[146:149], v[202:205], v[128:131]
	v_mfma_f32_16x16x32_bf16 v[68:71], v[154:157], v[202:205], v[68:71]
	v_mfma_f32_16x16x32_bf16 v[8:11], v[150:153], v[182:185], v[8:11]
	v_mfma_f32_16x16x32_bf16 v[12:15], v[158:161], v[182:185], v[12:15]
	v_mfma_f32_16x16x32_bf16 v[60:63], v[150:153], v[190:193], v[60:63]
	v_mfma_f32_16x16x32_bf16 v[20:23], v[158:161], v[190:193], v[20:23]
	v_mfma_f32_16x16x32_bf16 v[76:79], v[150:153], v[198:201], v[76:79]
	v_mfma_f32_16x16x32_bf16 v[52:55], v[158:161], v[198:201], v[52:55]
	v_mfma_f32_16x16x32_bf16 v[128:131], v[150:153], v[206:209], v[128:131]
	v_mfma_f32_16x16x32_bf16 v[68:71], v[158:161], v[206:209], v[68:71]
	s_setprio 0
	s_setprio 1
	v_mfma_f32_16x16x32_bf16 v[28:31], v[162:165], v[178:181], v[28:31]
	v_mfma_f32_16x16x32_bf16 v[16:19], v[170:173], v[178:181], v[16:19]
	v_mfma_f32_16x16x32_bf16 v[56:59], v[162:165], v[186:189], v[56:59]
	v_mfma_f32_16x16x32_bf16 v[48:51], v[170:173], v[186:189], v[48:51]
	v_mfma_f32_16x16x32_bf16 v[72:75], v[162:165], v[194:197], v[72:75]
	v_mfma_f32_16x16x32_bf16 v[64:67], v[170:173], v[194:197], v[64:67]
	v_mfma_f32_16x16x32_bf16 v[108:111], v[162:165], v[202:205], v[108:111]
	v_mfma_f32_16x16x32_bf16 v[96:99], v[170:173], v[202:205], v[96:99]
	v_mfma_f32_16x16x32_bf16 v[28:31], v[166:169], v[182:185], v[28:31]
	v_mfma_f32_16x16x32_bf16 v[16:19], v[174:177], v[182:185], v[16:19]
	v_mfma_f32_16x16x32_bf16 v[56:59], v[166:169], v[190:193], v[56:59]
	v_mfma_f32_16x16x32_bf16 v[48:51], v[174:177], v[190:193], v[48:51]
	v_mfma_f32_16x16x32_bf16 v[72:75], v[166:169], v[198:201], v[72:75]
	v_mfma_f32_16x16x32_bf16 v[64:67], v[174:177], v[198:201], v[64:67]
	v_mfma_f32_16x16x32_bf16 v[108:111], v[166:169], v[206:209], v[108:111]
	v_mfma_f32_16x16x32_bf16 v[96:99], v[174:177], v[206:209], v[96:99]
	s_barrier
	s_setprio 0
	s_mov_b32 m0, s44
	v_lshl_add_u64 v[210:211], s[70:71], 0, v[34:35]
	s_add_u32 s52, s70, 0x200000
	ds_read_b128 v[178:181], v142 offset:16384
	ds_read_b128 v[182:185], v142 offset:17408
	ds_read_b128 v[186:189], v142 offset:18432
	ds_read_b128 v[190:193], v142 offset:19456
	ds_read_b128 v[194:197], v142 offset:20480
	ds_read_b128 v[198:201], v142 offset:21504
	ds_read_b128 v[202:205], v142 offset:22528
	ds_read_b128 v[206:209], v142 offset:23552
	global_load_lds_dwordx4 v34, s[70:71]
	v_lshl_add_u64 v[212:213], s[70:71], 0, v[134:135]
	s_mov_b32 m0, s45
	s_addc_u32 s53, s71, 0
	global_load_lds_dwordx4 v134, s[70:71]
	v_lshl_add_u64 v[214:215], s[52:53], 0, v[34:35]
	s_mov_b32 m0, s46
	s_nop 0
	global_load_lds_dwordx4 v34, s[52:53]
	v_lshl_add_u64 v[214:215], s[52:53], 0, v[134:135]
	s_mov_b32 m0, s47
	s_nop 0
	global_load_lds_dwordx4 v134, s[52:53]
	v_lshl_add_u64 v[214:215], s[72:73], 0, v[32:33]
	s_mov_b32 m0, s14
	s_nop 0
	global_load_lds_dwordx4 v32, s[72:73]
	v_lshl_add_u64 v[214:215], s[72:73], 0, v[132:133]
	s_mov_b32 m0, s15
	s_nop 0
	global_load_lds_dwordx4 v132, s[72:73]
	s_waitcnt vmcnt(8) lgkmcnt(0)
	s_setprio 1
	s_barrier
; #define PG8_MMA(ai, bj, At, Bt) do { __builtin_amdgcn_s_setprio(1); _Pragma("unroll") for (int m = 0; m < 4; ++m) _Pragma("unroll") for (int n = 0; n < 2; ++n) _Pragma("unroll") for (int k = 0; k < 2; ++k) \
;         acc[ai][bj][m][n] = __builtin_amdgcn_mfma_f32_16x16x32_bf16(Bt[n][k], At[m][k], acc[ai][bj][m][n], 0, 0, 0); __builtin_amdgcn_s_setprio(0); } while (0)
; template <class Epi, class Sched, bool ALIGN_EPI = false, bool SP2 = false, bool A_TILED = false>
; __device__ __forceinline__ void gemm_phase(PG8_LAS unsigned char* lds, const Gemm g, const Sched& S, const Epi& E, const int wave_s) {
;     ...
;         for (int t = PEEL ? 2 : 0; t < nt; t += 2) {
;             const bool last = (t == nt - 2);
;             const char* a1 = cA + (size_t)(t + 1) * kstepA;
;             const char* a2 = last ? nA : cA + (size_t)(t + 2) * kstepA; const char* b2 = last ? nB : cB + (size_t)(t + 2) * kstep;
;             const char* a3 = a2 + kstepA; const char* b3 = b2 + kstep;
;             if (last && has_next) S.a_ready(nxt);
;             if constexpr (SP2) {
;             PG8_ITER(PG8_MMA)
	v_mfma_f32_16x16x32_bf16 v[100:103], v[146:149], v[178:181], v[100:103]
	v_mfma_f32_16x16x32_bf16 v[104:107], v[154:157], v[178:181], v[104:107]
	v_mfma_f32_16x16x32_bf16 v[116:119], v[146:149], v[186:189], v[116:119]
	v_mfma_f32_16x16x32_bf16 v[120:123], v[154:157], v[186:189], v[120:123]
	v_mfma_f32_16x16x32_bf16 v[84:87], v[146:149], v[194:197], v[84:87]
	v_mfma_f32_16x16x32_bf16 v[80:83], v[154:157], v[194:197], v[80:83]
	v_mfma_f32_16x16x32_bf16 v[36:39], v[146:149], v[202:205], v[36:39]
	v_mfma_f32_16x16x32_bf16 v[24:27], v[154:157], v[202:205], v[24:27]
	v_mfma_f32_16x16x32_bf16 v[100:103], v[150:153], v[182:185], v[100:103]
	v_mfma_f32_16x16x32_bf16 v[104:107], v[158:161], v[182:185], v[104:107]
	v_mfma_f32_16x16x32_bf16 v[116:119], v[150:153], v[190:193], v[116:119]
	v_mfma_f32_16x16x32_bf16 v[120:123], v[158:161], v[190:193], v[120:123]
	v_mfma_f32_16x16x32_bf16 v[84:87], v[150:153], v[198:201], v[84:87]
	v_mfma_f32_16x16x32_bf16 v[80:83], v[158:161], v[198:201], v[80:83]
	v_mfma_f32_16x16x32_bf16 v[36:39], v[150:153], v[206:209], v[36:39]
	v_mfma_f32_16x16x32_bf16 v[24:27], v[158:161], v[206:209], v[24:27]
	s_setprio 0
	s_setprio 1
	v_mfma_f32_16x16x32_bf16 v[124:127], v[162:165], v[178:181], v[124:127]
	v_mfma_f32_16x16x32_bf16 v[112:115], v[170:173], v[178:181], v[112:115]
	v_mfma_f32_16x16x32_bf16 v[92:95], v[162:165], v[186:189], v[92:95]
	v_mfma_f32_16x16x32_bf16 v[88:91], v[170:173], v[186:189], v[88:91]
	v_mfma_f32_16x16x32_bf16 v[44:47], v[162:165], v[194:197], v[44:47]
	v_mfma_f32_16x16x32_bf16 v[40:43], v[170:173], v[194:197], v[40:43]
	v_mfma_f32_16x16x32_bf16 v[4:7], v[162:165], v[202:205], v[4:7]
	v_mfma_f32_16x16x32_bf16 v[0:3], v[170:173], v[202:205], v[0:3]
	v_mfma_f32_16x16x32_bf16 v[124:127], v[166:169], v[182:185], v[124:127]
	v_mfma_f32_16x16x32_bf16 v[112:115], v[174:177], v[182:185], v[112:115]
	v_mfma_f32_16x16x32_bf16 v[92:95], v[166:169], v[190:193], v[92:95]
	v_mfma_f32_16x16x32_bf16 v[88:91], v[174:177], v[190:193], v[88:91]
	v_mfma_f32_16x16x32_bf16 v[44:47], v[166:169], v[198:201], v[44:47]
	v_mfma_f32_16x16x32_bf16 v[40:43], v[174:177], v[198:201], v[40:43]
	v_mfma_f32_16x16x32_bf16 v[4:7], v[166:169], v[206:209], v[4:7]
	v_mfma_f32_16x16x32_bf16 v[0:3], v[174:177], v[206:209], v[0:3]
	s_barrier
	s_setprio 0
	ds_read_b128 v[146:149], v143
	ds_read_b128 v[150:153], v143 offset:1024
	ds_read_b128 v[154:157], v143 offset:2048
	ds_read_b128 v[158:161], v143 offset:3072
	ds_read_b128 v[162:165], v144
	ds_read_b128 v[166:169], v144 offset:1024
	ds_read_b128 v[170:173], v144 offset:2048
	ds_read_b128 v[174:177], v144 offset:3072
	s_add_u32 s52, s72, 0x4000
	s_addc_u32 s53, s73, 0
	s_mov_b32 m0, s21
	v_lshl_add_u64 v[214:215], s[52:53], 0, v[32:33]
	ds_read_b128 v[178:181], v142 offset:32768
	ds_read_b128 v[182:185], v142 offset:33792
	ds_read_b128 v[186:189], v142 offset:34816
	ds_read_b128 v[190:193], v142 offset:35840
	ds_read_b128 v[194:197], v142 offset:36864
	ds_read_b128 v[198:201], v142 offset:37888
	ds_read_b128 v[202:205], v142 offset:38912
	ds_read_b128 v[206:209], v142 offset:39936
	global_load_lds_dwordx4 v32, s[52:53]
	v_lshl_add_u64 v[214:215], s[52:53], 0, v[132:133]
	s_mov_b32 m0, s22
	s_nop 0
	global_load_lds_dwordx4 v132, s[52:53]
	s_waitcnt vmcnt(8) lgkmcnt(0)
	s_setprio 1
	s_barrier
	v_mfma_f32_16x16x32_bf16 v[8:11], v[146:149], v[178:181], v[8:11]
	v_mfma_f32_16x16x32_bf16 v[12:15], v[154:157], v[178:181], v[12:15]
	v_mfma_f32_16x16x32_bf16 v[60:63], v[146:149], v[186:189], v[60:63]
	v_mfma_f32_16x16x32_bf16 v[20:23], v[154:157], v[186:189], v[20:23]
	v_mfma_f32_16x16x32_bf16 v[76:79], v[146:149], v[194:197], v[76:79]
	v_mfma_f32_16x16x32_bf16 v[52:55], v[154:157], v[194:197], v[52:55]
	v_mfma_f32_16x16x32_bf16 v[128:131], v[146:149], v[202:205], v[128:131]
	v_mfma_f32_16x16x32_bf16 v[68:71], v[154:157], v[202:205], v[68:71]
	v_mfma_f32_16x16x32_bf16 v[8:11], v[150:153], v[182:185], v[8:11]
	v_mfma_f32_16x16x32_bf16 v[12:15], v[158:161], v[182:185], v[12:15]
	v_mfma_f32_16x16x32_bf16 v[60:63], v[150:153], v[190:193], v[60:63]
	v_mfma_f32_16x16x32_bf16 v[20:23], v[158:161], v[190:193], v[20:23]
	v_mfma_f32_16x16x32_bf16 v[76:79], v[150:153], v[198:201], v[76:79]
	v_mfma_f32_16x16x32_bf16 v[52:55], v[158:161], v[198:201], v[52:55]
	v_mfma_f32_16x16x32_bf16 v[128:131], v[150:153], v[206:209], v[128:131]
	v_mfma_f32_16x16x32_bf16 v[68:71], v[158:161], v[206:209], v[68:71]
	s_setprio 0
	s_setprio 1
	v_mfma_f32_16x16x32_bf16 v[28:31], v[162:165], v[178:181], v[28:31]
	v_mfma_f32_16x16x32_bf16 v[16:19], v[170:173], v[178:181], v[16:19]
	v_mfma_f32_16x16x32_bf16 v[56:59], v[162:165], v[186:189], v[56:59]
	v_mfma_f32_16x16x32_bf16 v[48:51], v[170:173], v[186:189], v[48:51]
	v_mfma_f32_16x16x32_bf16 v[72:75], v[162:165], v[194:197], v[72:75]
	v_mfma_f32_16x16x32_bf16 v[64:67], v[170:173], v[194:197], v[64:67]
	v_mfma_f32_16x16x32_bf16 v[108:111], v[162:165], v[202:205], v[108:111]
	v_mfma_f32_16x16x32_bf16 v[96:99], v[170:173], v[202:205], v[96:99]
	v_mfma_f32_16x16x32_bf16 v[28:31], v[166:169], v[182:185], v[28:31]
	v_mfma_f32_16x16x32_bf16 v[16:19], v[174:177], v[182:185], v[16:19]
	v_mfma_f32_16x16x32_bf16 v[56:59], v[166:169], v[190:193], v[56:59]
	v_mfma_f32_16x16x32_bf16 v[48:51], v[174:177], v[190:193], v[48:51]
	v_mfma_f32_16x16x32_bf16 v[72:75], v[166:169], v[198:201], v[72:75]
	v_mfma_f32_16x16x32_bf16 v[64:67], v[174:177], v[198:201], v[64:67]
	v_mfma_f32_16x16x32_bf16 v[108:111], v[166:169], v[206:209], v[108:111]
	v_mfma_f32_16x16x32_bf16 v[96:99], v[174:177], v[206:209], v[96:99]
	s_barrier
; #define PG8_MMA(ai, bj, At, Bt) do { __builtin_amdgcn_s_setprio(1); _Pragma("unroll") for (int m = 0; m < 4; ++m) _Pragma("unroll") for (int n = 0; n < 2; ++n) _Pragma("unroll") for (int k = 0; k < 2; ++k) \
;         acc[ai][bj][m][n] = __builtin_amdgcn_mfma_f32_16x16x32_bf16(Bt[n][k], At[m][k], acc[ai][bj][m][n], 0, 0, 0); __builtin_amdgcn_s_setprio(0); } while (0)
; template <class Epi, class Sched, bool ALIGN_EPI = false, bool SP2 = false, bool A_TILED = false>
; __device__ __forceinline__ void gemm_phase(PG8_LAS unsigned char* lds, const Gemm g, const Sched& S, const Epi& E, const int wave_s) {
;     ...
;         for (int t = PEEL ? 2 : 0; t < nt; t += 2) {
;             const bool last = (t == nt - 2);
;             const char* a1 = cA + (size_t)(t + 1) * kstepA;
;             const char* a2 = last ? nA : cA + (size_t)(t + 2) * kstepA; const char* b2 = last ? nB : cB + (size_t)(t + 2) * kstep;
;             const char* a3 = a2 + kstepA; const char* b3 = b2 + kstep;
;             if (last && has_next) S.a_ready(nxt);
;             if constexpr (SP2) {
;             PG8_ITER(PG8_MMA)
	s_setprio 0
	s_mov_b32 m0, s48
	v_lshl_add_u64 v[210:211], v[210:211], 0, s[64:65]
	s_add_u32 s52, s70, 0x200080
	ds_read_b128 v[178:181], v142 offset:49152
	ds_read_b128 v[182:185], v142 offset:50176
	ds_read_b128 v[186:189], v142 offset:51200
	ds_read_b128 v[190:193], v142 offset:52224
	ds_read_b128 v[194:197], v142 offset:53248
	ds_read_b128 v[198:201], v142 offset:54272
	ds_read_b128 v[202:205], v142 offset:55296
	ds_read_b128 v[206:209], v142 offset:56320
	global_load_lds_dwordx4 v[210:211], off
	v_lshl_add_u64 v[210:211], v[212:213], 0, s[64:65]
	s_mov_b32 m0, s49
	s_addc_u32 s53, s71, 0
	global_load_lds_dwordx4 v[210:211], off
	v_lshl_add_u64 v[210:211], s[52:53], 0, v[34:35]
	s_mov_b32 m0, s50
	s_nop 0
	global_load_lds_dwordx4 v34, s[52:53]
	v_lshl_add_u64 v[210:211], s[52:53], 0, v[134:135]
	s_mov_b32 m0, s51
	s_nop 0
	global_load_lds_dwordx4 v134, s[52:53]
	v_lshl_add_u64 v[210:211], s[68:69], 0, v[32:33]
	s_mov_b32 m0, s23
	s_nop 0
	global_load_lds_dwordx4 v32, s[68:69]
	v_lshl_add_u64 v[210:211], s[68:69], 0, v[132:133]
	s_mov_b32 m0, s36
	s_nop 0
	global_load_lds_dwordx4 v132, s[68:69]
	s_waitcnt vmcnt(8) lgkmcnt(0)
	s_setprio 1
	s_barrier
	v_mfma_f32_16x16x32_bf16 v[100:103], v[146:149], v[178:181], v[100:103]
	v_mfma_f32_16x16x32_bf16 v[104:107], v[154:157], v[178:181], v[104:107]
	v_mfma_f32_16x16x32_bf16 v[116:119], v[146:149], v[186:189], v[116:119]
	v_mfma_f32_16x16x32_bf16 v[120:123], v[154:157], v[186:189], v[120:123]
	v_mfma_f32_16x16x32_bf16 v[84:87], v[146:149], v[194:197], v[84:87]
	v_mfma_f32_16x16x32_bf16 v[80:83], v[154:157], v[194:197], v[80:83]
	v_mfma_f32_16x16x32_bf16 v[36:39], v[146:149], v[202:205], v[36:39]
	v_mfma_f32_16x16x32_bf16 v[24:27], v[154:157], v[202:205], v[24:27]
	v_mfma_f32_16x16x32_bf16 v[100:103], v[150:153], v[182:185], v[100:103]
	v_mfma_f32_16x16x32_bf16 v[104:107], v[158:161], v[182:185], v[104:107]
	v_mfma_f32_16x16x32_bf16 v[116:119], v[150:153], v[190:193], v[116:119]
	v_mfma_f32_16x16x32_bf16 v[120:123], v[158:161], v[190:193], v[120:123]
	v_mfma_f32_16x16x32_bf16 v[84:87], v[150:153], v[198:201], v[84:87]
	v_mfma_f32_16x16x32_bf16 v[80:83], v[158:161], v[198:201], v[80:83]
	v_mfma_f32_16x16x32_bf16 v[36:39], v[150:153], v[206:209], v[36:39]
	v_mfma_f32_16x16x32_bf16 v[24:27], v[158:161], v[206:209], v[24:27]
	s_setprio 0
	s_setprio 1
	v_mfma_f32_16x16x32_bf16 v[124:127], v[162:165], v[178:181], v[124:127]
	v_mfma_f32_16x16x32_bf16 v[112:115], v[170:173], v[178:181], v[112:115]
	v_mfma_f32_16x16x32_bf16 v[92:95], v[162:165], v[186:189], v[92:95]
	v_mfma_f32_16x16x32_bf16 v[88:91], v[170:173], v[186:189], v[88:91]
	v_mfma_f32_16x16x32_bf16 v[44:47], v[162:165], v[194:197], v[44:47]
	v_mfma_f32_16x16x32_bf16 v[40:43], v[170:173], v[194:197], v[40:43]
	v_mfma_f32_16x16x32_bf16 v[4:7], v[162:165], v[202:205], v[4:7]
	v_mfma_f32_16x16x32_bf16 v[0:3], v[170:173], v[202:205], v[0:3]
	v_mfma_f32_16x16x32_bf16 v[124:127], v[166:169], v[182:185], v[124:127]
	v_mfma_f32_16x16x32_bf16 v[112:115], v[174:177], v[182:185], v[112:115]
	v_mfma_f32_16x16x32_bf16 v[92:95], v[166:169], v[190:193], v[92:95]
	v_mfma_f32_16x16x32_bf16 v[88:91], v[174:177], v[190:193], v[88:91]
	v_mfma_f32_16x16x32_bf16 v[44:47], v[166:169], v[198:201], v[44:47]
	v_mfma_f32_16x16x32_bf16 v[40:43], v[174:177], v[198:201], v[40:43]
	v_mfma_f32_16x16x32_bf16 v[4:7], v[166:169], v[206:209], v[4:7]
	v_mfma_f32_16x16x32_bf16 v[0:3], v[174:177], v[206:209], v[0:3]
	s_barrier
	s_setprio 0
	s_add_i32 s41, s41, 2
	s_add_u32 s37, s37, 0x100
	s_addc_u32 s38, s38, 0
	s_add_u32 s39, s39, 0x10000
	s_addc_u32 s40, s40, 0
	v_lshl_add_u64 v[136:137], v[136:137], 0, s[66:67]
	s_cmpk_gt_u32 s41, 0x7d
	v_lshl_add_u64 v[138:139], v[138:139], 0, s[66:67]
	s_cbranch_scc0 .LBB0_2026
	s_waitcnt vmcnt(0)
	s_cmpk_lt_u32 s0, 0x100
	s_cbranch_scc0 .LBB0_2029
	s_barrier

; #define PG8_STAGE(bufoff, gbase, voff) do { _Pragma("unroll") for (int _i = 0; _i < 2; ++_i) \
;         __builtin_amdgcn_global_load_lds((const unsigned*)((const char*)(gbase) + (voff)[_i]), (PG8_LAS unsigned*)(lds + (bufoff) + ldsw + _i * 8192), 16, 0, 0); } while (0)
; #define PG8_WAIT_V(n) asm volatile("s_waitcnt vmcnt(" #n ")" ::: "memory")
; #define PG8_BAR __builtin_amdgcn_s_barrier()
; template <class Epi, class Sched, bool ALIGN_EPI = false, bool SP2 = false, bool A_TILED = false>
; __device__ __forceinline__ void gemm_phase(PG8_LAS unsigned char* lds, const Gemm g, const Sched& S, const Epi& E, const int wave_s) {
;     ...
;     if constexpr (SP2) {
;         PG8_STAGE(PG8_SB(0, 0), cB, voffB); PG8_STAGE(PG8_SB(0, 1), cB + hstep, voffB); PG8_STAGE(PG8_SA(0, 0), cA, voffA); PG8_STAGE(PG8_SA(0, 1), cA + hstepA, voffA);
;         if (wr == 1) PG8_BAR;
;         PG8_WAIT_V(2); PG8_BAR;
;         PG8_STAGE(PG8_SB(1, 0), cB + kstep, voffB); PG8_STAGE(PG8_SA(1, 0), cA + kstepA, voffA); PG8_STAGE(PG8_SB(1, 1), cB + hstep + kstep, voffB);
;         PG8_WAIT_V(6); PG8_BAR;
.LBB0_2411:
	s_sext_i32_i8 s44, s12
	s_mul_i32 s12, s96, 0x7c00000
	s_ashr_i32 s39, s86, 31
	s_add_u32 s2, s2, s12
	s_addc_u32 s3, s3, 0
	s_add_u32 s12, s2, 0x22600000
	s_addc_u32 s13, s3, 0
	v_and_b32_e32 v15, 48, v14
	v_lshlrev_b32_e32 v16, 6, v14
	s_movk_i32 s3, 0x3c0
	v_lshlrev_b32_e32 v14, 2, v14
	s_lshl_b32 s2, s42, 13
	v_and_or_b32 v15, v16, s3, v15
	v_and_b32_e32 v14, 32, v14
	v_bitop3_b32 v16, v15, s2, v14 bitop3:0xde
	s_lshl_b32 s2, s41, 5
	s_mov_b64 s[62:63], 0x80
	s_and_b32 s41, s2, 0x60
	s_add_i32 m0, s22, 0x18000
	v_lshl_add_u64 v[6:7], v[6:7], 0, s[62:63]
	s_lshl_b32 s40, s42, 6
	s_lshl_b32 s2, s41, 7
	s_waitcnt vmcnt(2)
	s_barrier
	global_load_lds_dwordx4 v[6:7], off
	v_lshl_add_u64 v[4:5], v[4:5], 0, s[62:63]
	s_add_i32 m0, s22, 0x1a000
	s_add_i32 s42, s22, 0x8000
	s_add_i32 s43, s22, 0xa000
	v_bitop3_b32 v140, s2, v15, v14 bitop3:0xf6
	global_load_lds_dwordx4 v[4:5], off
	v_lshl_add_u64 v[0:1], v[0:1], 0, s[62:63]
	s_mov_b32 m0, s42
	s_add_u32 s2, s78, 0x80080
	global_load_lds_dwordx4 v[0:1], off
	v_lshl_add_u64 v[0:1], v[2:3], 0, s[62:63]
	s_mov_b32 m0, s43
	s_addc_u32 s3, s79, 0
	global_load_lds_dwordx4 v[0:1], off
	s_add_i32 m0, s22, 0x1c000
	v_lshl_add_u64 v[0:1], s[2:3], 0, v[128:129]
	global_load_lds_dwordx4 v128, s[2:3]
	v_lshl_add_u64 v[0:1], s[2:3], 0, v[130:131]
	s_add_i32 m0, s22, 0x1e000
	s_cmpk_lt_u32 s45, 0x100
	global_load_lds_dwordx4 v130, s[2:3]
	v_lshlrev_b32_e32 v0, 15, v8
	v_and_b32_e32 v0, 0xffff0000, v0
	v_lshl_add_u32 v0, v9, 12, v0
	v_and_b32_e32 v1, 1, v8
	v_lshl_or_b32 v0, v1, 6, v0
	v_lshl_add_u32 v132, v10, 1, v0
	v_lshlrev_b32_e32 v0, 15, v11
	v_and_b32_e32 v0, 0xffff0000, v0
	s_waitcnt vmcnt(6)
	v_lshl_add_u32 v0, v12, 12, v0
	v_and_b32_e32 v1, 1, v11
	s_cselect_b64 s[64:65], -1, 0
	v_mov_b32_e32 v133, 0
	v_lshl_or_b32 v0, v1, 6, v0
	s_add_i32 s45, 0, 0x10000
	s_add_i32 s46, 0, 0x14000
	v_lshl_add_u32 v134, v13, 1, v0
	v_mov_b32_e32 v135, v133
	v_add_u32_e32 v141, s45, v140
	v_add_u32_e32 v142, s46, v140
	v_add_u32_e32 v143, 0, v16
	s_mov_b64 s[66:67], 0x100
	s_mov_b64 s[68:69], 0x180
	s_movk_i32 s47, 0x1400
	s_add_i32 s48, s22, 0xc000
	s_add_i32 s49, s22, 0xe000
	s_barrier
	s_branch .LBB0_2414

; template <class Epi, class Sched, bool ALIGN_EPI = false, bool SP2 = false, bool A_TILED = false>
; __device__ __forceinline__ void gemm_phase(PG8_LAS unsigned char* lds, const Gemm g, const Sched& S, const Epi& E, const int wave_s) {
;     ...
;         const bool has_next = Epi::AFTER_DRAIN ? false : S.next(ui + 1, nxt);
;         const char* nA = has_next ? (const char*)g.A + (size_t)nxt.pm * tstepA : cA; const char* nB = has_next ? (const char*)g.Bt + (size_t)nxt.pn * tstep : cB;
;         constexpr bool PEEL = SP2 && !Epi::AFTER_DRAIN;
;         if constexpr (PEEL) {
;             const char* a1 = cA + kstepA; const char* a2 = cA + 2 * kstepA; const char* b2 = cB + 2 * kstep; const char* a3 = a2 + kstepA; const char* b3 = b2 + kstep;
;             PG8_ITER(PG8_MMAZ)
.LBB0_2416:
	s_ashr_i32 s73, s72, 31
	s_lshl_b64 s[50:51], s[72:73], 20
	s_add_u32 s74, s1, s50
	ds_read_b128 v[0:3], v141
	ds_read_b128 v[4:7], v141 offset:1024
	ds_read_b128 v[8:11], v141 offset:2048
	ds_read_b128 v[12:15], v141 offset:3072
	ds_read_b128 v[16:19], v142
	ds_read_b128 v[20:23], v142 offset:1024
	ds_read_b128 v[24:27], v142 offset:2048
	ds_read_b128 v[28:31], v142 offset:3072
	s_addc_u32 s75, s8, s51
	s_ashr_i32 s71, s70, 31
	s_lshl_b64 s[50:51], s[70:71], 20
	s_add_u32 s76, s9, s50
	s_addc_u32 s77, s14, s51
	s_and_b64 s[50:51], s[2:3], exec
	s_cselect_b32 s50, s75, s81
	s_cselect_b32 s51, s74, s80
	s_cselect_b32 s52, s77, s79
	s_cselect_b32 s53, s76, s78
	s_add_u32 s54, s80, 0x80080
	s_addc_u32 s55, s81, 0
	s_mov_b32 m0, s48
	v_lshl_add_u64 v[64:65], s[54:55], 0, v[128:129]
	ds_read_b128 v[32:35], v143
	ds_read_b128 v[36:39], v143 offset:1024
	ds_read_b128 v[40:43], v143 offset:2048
	ds_read_b128 v[44:47], v143 offset:3072
	ds_read_b128 v[48:51], v143 offset:4096
	ds_read_b128 v[52:55], v143 offset:5120
	ds_read_b128 v[56:59], v143 offset:6144
	ds_read_b128 v[60:63], v143 offset:7168
	global_load_lds_dwordx4 v128, s[54:55]
	v_lshl_add_u64 v[64:65], s[54:55], 0, v[130:131]
	s_mov_b32 m0, s49
	s_nop 0
	global_load_lds_dwordx4 v130, s[54:55]
	s_waitcnt vmcnt(8) lgkmcnt(0)
	s_setprio 1
	s_barrier
	v_mfma_f32_16x16x32_bf16 v[64:67], v[0:3], v[32:35], 0
	v_mfma_f32_16x16x32_bf16 v[68:71], v[8:11], v[32:35], 0
	v_mfma_f32_16x16x32_bf16 v[72:75], v[0:3], v[40:43], 0
	v_mfma_f32_16x16x32_bf16 v[76:79], v[8:11], v[40:43], 0
	v_mfma_f32_16x16x32_bf16 v[80:83], v[0:3], v[48:51], 0
	v_mfma_f32_16x16x32_bf16 v[84:87], v[8:11], v[48:51], 0
	v_mfma_f32_16x16x32_bf16 v[88:91], v[0:3], v[56:59], 0
	v_mfma_f32_16x16x32_bf16 v[92:95], v[8:11], v[56:59], 0
	v_mfma_f32_16x16x32_bf16 v[64:67], v[4:7], v[36:39], v[64:67]
	v_mfma_f32_16x16x32_bf16 v[68:71], v[12:15], v[36:39], v[68:71]
	v_mfma_f32_16x16x32_bf16 v[72:75], v[4:7], v[44:47], v[72:75]
	v_mfma_f32_16x16x32_bf16 v[76:79], v[12:15], v[44:47], v[76:79]
	v_mfma_f32_16x16x32_bf16 v[80:83], v[4:7], v[52:55], v[80:83]
	v_mfma_f32_16x16x32_bf16 v[84:87], v[12:15], v[52:55], v[84:87]
	v_mfma_f32_16x16x32_bf16 v[88:91], v[4:7], v[60:63], v[88:91]
	v_mfma_f32_16x16x32_bf16 v[92:95], v[12:15], v[60:63], v[92:95]
	s_setprio 0
	s_setprio 1
	v_mfma_f32_16x16x32_bf16 v[96:99], v[16:19], v[32:35], 0
	v_mfma_f32_16x16x32_bf16 v[32:35], v[24:27], v[32:35], 0
	v_mfma_f32_16x16x32_bf16 v[96:99], v[20:23], v[36:39], v[96:99]
	v_mfma_f32_16x16x32_bf16 v[32:35], v[28:31], v[36:39], v[32:35]
	v_mfma_f32_16x16x32_bf16 v[36:39], v[16:19], v[40:43], 0
	v_mfma_f32_16x16x32_bf16 v[40:43], v[24:27], v[40:43], 0
	v_mfma_f32_16x16x32_bf16 v[36:39], v[20:23], v[44:47], v[36:39]
	v_mfma_f32_16x16x32_bf16 v[40:43], v[28:31], v[44:47], v[40:43]
	v_mfma_f32_16x16x32_bf16 v[44:47], v[16:19], v[48:51], 0
	v_mfma_f32_16x16x32_bf16 v[48:51], v[24:27], v[48:51], 0
	v_mfma_f32_16x16x32_bf16 v[100:103], v[28:31], v[52:55], v[48:51]
	v_mfma_f32_16x16x32_bf16 v[48:51], v[16:19], v[56:59], 0
	v_mfma_f32_16x16x32_bf16 v[104:107], v[20:23], v[60:63], v[48:51]
	v_mfma_f32_16x16x32_bf16 v[48:51], v[24:27], v[56:59], 0
	v_mfma_f32_16x16x32_bf16 v[44:47], v[20:23], v[52:55], v[44:47]
	v_mfma_f32_16x16x32_bf16 v[108:111], v[28:31], v[60:63], v[48:51]
	s_barrier
	s_setprio 0
	s_add_i32 s54, s45, s15
	v_lshl_add_u64 v[250:251], s[78:79], 0, v[128:129]
	s_add_i32 s55, s54, 0x2000
	v_lshl_add_u64 v[144:145], v[250:251], 0, s[66:67]
	s_mov_b32 m0, s54
	v_lshl_add_u64 v[252:253], s[78:79], 0, v[130:131]
	s_add_u32 s58, s78, 0x80100
	ds_read_b128 v[48:51], v143 offset:16384
	ds_read_b128 v[52:55], v143 offset:17408
	ds_read_b128 v[56:59], v143 offset:18432
	ds_read_b128 v[60:63], v143 offset:19456
	ds_read_b128 v[112:115], v143 offset:20480
	ds_read_b128 v[116:119], v143 offset:21504
	ds_read_b128 v[120:123], v143 offset:22528
	ds_read_b128 v[124:127], v143 offset:23552
	global_load_lds_dwordx4 v[144:145], off
	v_lshl_add_u64 v[144:145], v[252:253], 0, s[66:67]
	s_mov_b32 m0, s55
	s_addc_u32 s59, s79, 0
	s_add_i32 s56, s46, s15
	global_load_lds_dwordx4 v[144:145], off
	v_lshl_add_u64 v[144:145], s[58:59], 0, v[128:129]
	s_mov_b32 m0, s56
	s_add_i32 s57, s56, 0x2000
	global_load_lds_dwordx4 v128, s[58:59]
	v_lshl_add_u64 v[144:145], s[58:59], 0, v[130:131]
	s_mov_b32 m0, s57
	v_lshl_add_u64 v[136:137], s[80:81], 0, v[128:129]
	global_load_lds_dwordx4 v130, s[58:59]
	v_lshl_add_u64 v[144:145], v[136:137], 0, s[66:67]
	s_mov_b32 m0, s22
	v_lshl_add_u64 v[138:139], s[80:81], 0, v[130:131]
	global_load_lds_dwordx4 v[144:145], off
	v_lshl_add_u64 v[144:145], v[138:139], 0, s[66:67]
	s_mov_b32 m0, s23
	s_nop 0
	global_load_lds_dwordx4 v[144:145], off
	s_waitcnt vmcnt(8) lgkmcnt(0)
	s_setprio 1
	s_barrier
	v_mfma_f32_16x16x32_bf16 v[144:147], v[0:3], v[48:51], 0
	v_mfma_f32_16x16x32_bf16 v[154:157], v[0:3], v[56:59], 0
	v_mfma_f32_16x16x32_bf16 v[162:165], v[0:3], v[112:115], 0
	v_mfma_f32_16x16x32_bf16 v[0:3], v[0:3], v[120:123], 0
	v_mfma_f32_16x16x32_bf16 v[150:153], v[8:11], v[48:51], 0
	v_mfma_f32_16x16x32_bf16 v[158:161], v[8:11], v[56:59], 0
	v_mfma_f32_16x16x32_bf16 v[166:169], v[8:11], v[112:115], 0
	v_mfma_f32_16x16x32_bf16 v[170:173], v[4:7], v[124:127], v[0:3]
	v_mfma_f32_16x16x32_bf16 v[0:3], v[8:11], v[120:123], 0
	v_mfma_f32_16x16x32_bf16 v[146:149], v[4:7], v[52:55], v[144:147]
	v_mfma_f32_16x16x32_bf16 v[150:153], v[12:15], v[52:55], v[150:153]
	v_mfma_f32_16x16x32_bf16 v[154:157], v[4:7], v[60:63], v[154:157]
	v_mfma_f32_16x16x32_bf16 v[158:161], v[12:15], v[60:63], v[158:161]
	v_mfma_f32_16x16x32_bf16 v[162:165], v[4:7], v[116:119], v[162:165]
	v_mfma_f32_16x16x32_bf16 v[166:169], v[12:15], v[116:119], v[166:169]
	v_mfma_f32_16x16x32_bf16 v[174:177], v[12:15], v[124:127], v[0:3]
	s_setprio 0
	s_setprio 1
	v_mfma_f32_16x16x32_bf16 v[0:3], v[16:19], v[48:51], 0
	v_mfma_f32_16x16x32_bf16 v[178:181], v[20:23], v[52:55], v[0:3]
	v_mfma_f32_16x16x32_bf16 v[0:3], v[24:27], v[48:51], 0
	v_mfma_f32_16x16x32_bf16 v[182:185], v[28:31], v[52:55], v[0:3]
	v_mfma_f32_16x16x32_bf16 v[0:3], v[16:19], v[56:59], 0
	v_mfma_f32_16x16x32_bf16 v[186:189], v[20:23], v[60:63], v[0:3]
	v_mfma_f32_16x16x32_bf16 v[0:3], v[24:27], v[56:59], 0
	v_mfma_f32_16x16x32_bf16 v[190:193], v[28:31], v[60:63], v[0:3]
	v_mfma_f32_16x16x32_bf16 v[0:3], v[16:19], v[112:115], 0
	v_mfma_f32_16x16x32_bf16 v[194:197], v[20:23], v[116:119], v[0:3]
	v_mfma_f32_16x16x32_bf16 v[0:3], v[24:27], v[112:115], 0
	v_mfma_f32_16x16x32_bf16 v[198:201], v[28:31], v[116:119], v[0:3]
	v_mfma_f32_16x16x32_bf16 v[0:3], v[16:19], v[120:123], 0
	v_mfma_f32_16x16x32_bf16 v[202:205], v[20:23], v[124:127], v[0:3]
	v_mfma_f32_16x16x32_bf16 v[0:3], v[24:27], v[120:123], 0
	v_mfma_f32_16x16x32_bf16 v[206:209], v[28:31], v[124:127], v[0:3]
	s_barrier
	s_setprio 0
	s_add_i32 s61, 0, 0x18000
	s_add_i32 s71, 0, 0x1c000
	v_add_u32_e32 v144, s61, v140
	v_add_u32_e32 v145, s71, v140
	ds_read_b128 v[112:115], v144
	ds_read_b128 v[116:119], v144 offset:1024
	ds_read_b128 v[120:123], v144 offset:2048
	ds_read_b128 v[124:127], v144 offset:3072
	ds_read_b128 v[210:213], v145
	ds_read_b128 v[214:217], v145 offset:1024
	ds_read_b128 v[218:221], v145 offset:2048
	ds_read_b128 v[222:225], v145 offset:3072
	s_add_u32 s58, s80, 0x80100
	s_addc_u32 s59, s81, 0
	s_mov_b32 m0, s36
	v_lshl_add_u64 v[0:1], s[58:59], 0, v[128:129]
	ds_read_b128 v[48:51], v143 offset:32768
	ds_read_b128 v[52:55], v143 offset:33792
	ds_read_b128 v[226:229], v143 offset:34816
	ds_read_b128 v[230:233], v143 offset:35840
	ds_read_b128 v[234:237], v143 offset:36864
	ds_read_b128 v[238:241], v143 offset:37888
	ds_read_b128 v[242:245], v143 offset:38912
	ds_read_b128 v[246:249], v143 offset:39936
	global_load_lds_dwordx4 v128, s[58:59]
	v_lshl_add_u64 v[0:1], s[58:59], 0, v[130:131]
	s_mov_b32 m0, s37
	s_nop 0
	global_load_lds_dwordx4 v130, s[58:59]
	s_waitcnt vmcnt(8) lgkmcnt(0)
	s_setprio 1
	s_barrier
	v_mfma_f32_16x16x32_bf16 v[0:3], v[112:115], v[48:51], v[64:67]
	v_mfma_f32_16x16x32_bf16 v[24:27], v[116:119], v[52:55], v[0:3]
	v_mfma_f32_16x16x32_bf16 v[0:3], v[120:123], v[48:51], v[68:71]
	v_mfma_f32_16x16x32_bf16 v[28:31], v[124:127], v[52:55], v[0:3]
	v_mfma_f32_16x16x32_bf16 v[0:3], v[112:115], v[226:229], v[72:75]
	v_mfma_f32_16x16x32_bf16 v[16:19], v[116:119], v[230:233], v[0:3]
	v_mfma_f32_16x16x32_bf16 v[0:3], v[120:123], v[226:229], v[76:79]
	v_mfma_f32_16x16x32_bf16 v[20:23], v[124:127], v[230:233], v[0:3]
	v_mfma_f32_16x16x32_bf16 v[0:3], v[112:115], v[234:237], v[80:83]
	v_mfma_f32_16x16x32_bf16 v[8:11], v[116:119], v[238:241], v[0:3]
	v_mfma_f32_16x16x32_bf16 v[0:3], v[120:123], v[234:237], v[84:87]
	v_mfma_f32_16x16x32_bf16 v[12:15], v[124:127], v[238:241], v[0:3]
	v_mfma_f32_16x16x32_bf16 v[0:3], v[112:115], v[242:245], v[88:91]
	v_mfma_f32_16x16x32_bf16 v[4:7], v[120:123], v[242:245], v[92:95]
	v_mfma_f32_16x16x32_bf16 v[0:3], v[116:119], v[246:249], v[0:3]
	v_mfma_f32_16x16x32_bf16 v[4:7], v[124:127], v[246:249], v[4:7]
	s_setprio 0
	s_setprio 1
	v_mfma_f32_16x16x32_bf16 v[32:35], v[218:221], v[48:51], v[32:35]
	v_mfma_f32_16x16x32_bf16 v[60:63], v[222:225], v[52:55], v[32:35]
	v_mfma_f32_16x16x32_bf16 v[32:35], v[210:213], v[226:229], v[36:39]
	v_mfma_f32_16x16x32_bf16 v[56:59], v[210:213], v[48:51], v[96:99]
	v_mfma_f32_16x16x32_bf16 v[48:51], v[214:217], v[230:233], v[32:35]
	v_mfma_f32_16x16x32_bf16 v[32:35], v[218:221], v[226:229], v[40:43]
	v_mfma_f32_16x16x32_bf16 v[56:59], v[214:217], v[52:55], v[56:59]
	v_mfma_f32_16x16x32_bf16 v[52:55], v[222:225], v[230:233], v[32:35]
	v_mfma_f32_16x16x32_bf16 v[32:35], v[210:213], v[234:237], v[44:47]
	v_mfma_f32_16x16x32_bf16 v[40:43], v[214:217], v[238:241], v[32:35]
	v_mfma_f32_16x16x32_bf16 v[32:35], v[218:221], v[234:237], v[100:103]
	v_mfma_f32_16x16x32_bf16 v[44:47], v[222:225], v[238:241], v[32:35]
	v_mfma_f32_16x16x32_bf16 v[32:35], v[210:213], v[242:245], v[104:107]
	v_mfma_f32_16x16x32_bf16 v[36:39], v[218:221], v[242:245], v[108:111]
	v_mfma_f32_16x16x32_bf16 v[32:35], v[214:217], v[246:249], v[32:35]
	v_mfma_f32_16x16x32_bf16 v[36:39], v[222:225], v[246:249], v[36:39]
	s_barrier
; #define PG8_MMA(ai, bj, At, Bt) do { __builtin_amdgcn_s_setprio(1); _Pragma("unroll") for (int m = 0; m < 4; ++m) _Pragma("unroll") for (int n = 0; n < 2; ++n) _Pragma("unroll") for (int k = 0; k < 2; ++k) \
;         acc[ai][bj][m][n] = __builtin_amdgcn_mfma_f32_16x16x32_bf16(Bt[n][k], At[m][k], acc[ai][bj][m][n], 0, 0, 0); __builtin_amdgcn_s_setprio(0); } while (0)
; template <class Epi, class Sched, bool ALIGN_EPI = false, bool SP2 = false, bool A_TILED = false>
; __device__ __forceinline__ void gemm_phase(PG8_LAS unsigned char* lds, const Gemm g, const Sched& S, const Epi& E, const int wave_s) {
;     ...
;         for (int t = PEEL ? 2 : 0; t < nt; t += 2) {
;             const bool last = (t == nt - 2);
;             const char* a1 = cA + (size_t)(t + 1) * kstepA;
;             const char* a2 = last ? nA : cA + (size_t)(t + 2) * kstepA; const char* b2 = last ? nB : cB + (size_t)(t + 2) * kstep;
;             const char* a3 = a2 + kstepA; const char* b3 = b2 + kstep;
;             if (last && has_next) S.a_ready(nxt);
;             if constexpr (SP2) {
;             PG8_ITER(PG8_MMA)
	s_setprio 0
	s_add_i32 s58, s61, s15
	s_add_i32 s59, s58, 0x2000
	v_lshl_add_u64 v[64:65], v[250:251], 0, s[68:69]
	s_mov_b32 m0, s58
	s_add_u32 s82, s78, 0x80180
	ds_read_b128 v[96:99], v143 offset:49152
	ds_read_b128 v[100:103], v143 offset:50176
	ds_read_b128 v[104:107], v143 offset:51200
	ds_read_b128 v[108:111], v143 offset:52224
	ds_read_b128 v[226:229], v143 offset:53248
	ds_read_b128 v[230:233], v143 offset:54272
	ds_read_b128 v[234:237], v143 offset:55296
	ds_read_b128 v[238:241], v143 offset:56320
	global_load_lds_dwordx4 v[64:65], off
	v_lshl_add_u64 v[64:65], v[252:253], 0, s[68:69]
	s_mov_b32 m0, s59
	s_addc_u32 s83, s79, 0
	s_add_i32 s61, s71, s15
	global_load_lds_dwordx4 v[64:65], off
	v_lshl_add_u64 v[64:65], s[82:83], 0, v[128:129]
	s_mov_b32 m0, s61
	s_add_i32 s71, s61, 0x2000
	global_load_lds_dwordx4 v128, s[82:83]
	v_lshl_add_u64 v[64:65], s[82:83], 0, v[130:131]
	s_mov_b32 m0, s71
	s_nop 0
	global_load_lds_dwordx4 v130, s[82:83]
	v_lshl_add_u64 v[64:65], v[136:137], 0, s[68:69]
	s_mov_b32 m0, s42
	s_nop 0
	global_load_lds_dwordx4 v[64:65], off
	v_lshl_add_u64 v[64:65], v[138:139], 0, s[68:69]
	s_mov_b32 m0, s43
	s_nop 0
	global_load_lds_dwordx4 v[64:65], off
	s_waitcnt vmcnt(8) lgkmcnt(0)
	s_setprio 1
	s_barrier
	v_mfma_f32_16x16x32_bf16 v[64:67], v[112:115], v[96:99], v[146:149]
	v_mfma_f32_16x16x32_bf16 v[88:91], v[116:119], v[100:103], v[64:67]
	v_mfma_f32_16x16x32_bf16 v[64:67], v[120:123], v[96:99], v[150:153]
	v_mfma_f32_16x16x32_bf16 v[92:95], v[124:127], v[100:103], v[64:67]
	v_mfma_f32_16x16x32_bf16 v[64:67], v[112:115], v[104:107], v[154:157]
	v_mfma_f32_16x16x32_bf16 v[80:83], v[116:119], v[108:111], v[64:67]
	v_mfma_f32_16x16x32_bf16 v[64:67], v[120:123], v[104:107], v[158:161]
	v_mfma_f32_16x16x32_bf16 v[84:87], v[124:127], v[108:111], v[64:67]
	v_mfma_f32_16x16x32_bf16 v[64:67], v[112:115], v[226:229], v[162:165]
	v_mfma_f32_16x16x32_bf16 v[72:75], v[116:119], v[230:233], v[64:67]
	v_mfma_f32_16x16x32_bf16 v[64:67], v[120:123], v[226:229], v[166:169]
	v_mfma_f32_16x16x32_bf16 v[76:79], v[124:127], v[230:233], v[64:67]
	v_mfma_f32_16x16x32_bf16 v[64:67], v[112:115], v[234:237], v[170:173]
	v_mfma_f32_16x16x32_bf16 v[68:71], v[120:123], v[234:237], v[174:177]
	v_mfma_f32_16x16x32_bf16 v[64:67], v[116:119], v[238:241], v[64:67]
	v_mfma_f32_16x16x32_bf16 v[68:71], v[124:127], v[238:241], v[68:71]
	s_setprio 0
	s_setprio 1
	v_mfma_f32_16x16x32_bf16 v[112:115], v[210:213], v[96:99], v[178:181]
	v_mfma_f32_16x16x32_bf16 v[96:99], v[218:221], v[96:99], v[182:185]
	v_mfma_f32_16x16x32_bf16 v[124:127], v[222:225], v[100:103], v[96:99]
	v_mfma_f32_16x16x32_bf16 v[96:99], v[210:213], v[104:107], v[186:189]
	v_mfma_f32_16x16x32_bf16 v[120:123], v[214:217], v[100:103], v[112:115]
	v_mfma_f32_16x16x32_bf16 v[112:115], v[214:217], v[108:111], v[96:99]
	v_mfma_f32_16x16x32_bf16 v[96:99], v[218:221], v[104:107], v[190:193]
	v_mfma_f32_16x16x32_bf16 v[116:119], v[222:225], v[108:111], v[96:99]
	v_mfma_f32_16x16x32_bf16 v[96:99], v[210:213], v[226:229], v[194:197]
	v_mfma_f32_16x16x32_bf16 v[104:107], v[214:217], v[230:233], v[96:99]
	v_mfma_f32_16x16x32_bf16 v[96:99], v[218:221], v[226:229], v[198:201]
	v_mfma_f32_16x16x32_bf16 v[108:111], v[222:225], v[230:233], v[96:99]
	v_mfma_f32_16x16x32_bf16 v[96:99], v[210:213], v[234:237], v[202:205]
	v_mfma_f32_16x16x32_bf16 v[100:103], v[218:221], v[234:237], v[206:209]
	v_mfma_f32_16x16x32_bf16 v[96:99], v[214:217], v[238:241], v[96:99]
	v_mfma_f32_16x16x32_bf16 v[100:103], v[222:225], v[238:241], v[100:103]
	s_barrier
	s_setprio 0
	s_add_u32 s73, s78, 0x200
	s_addc_u32 s85, s79, 0
	s_add_u32 s78, s80, 0x80180
	s_addc_u32 s79, s81, 0
	s_mov_b32 s88, 0
.LBB0_2417:
	ds_read_b128 v[146:149], v141
	ds_read_b128 v[150:153], v141 offset:1024
	ds_read_b128 v[154:157], v141 offset:2048
	ds_read_b128 v[158:161], v141 offset:3072
	ds_read_b128 v[162:165], v142
	ds_read_b128 v[166:169], v142 offset:1024
	ds_read_b128 v[170:173], v142 offset:2048
	ds_read_b128 v[174:177], v142 offset:3072
	s_add_u32 s80, s78, 0xfff80080
	s_addc_u32 s81, s79, -1
	s_cmp_eq_u32 s88, 28
	s_cselect_b32 s83, s50, s81
	s_cselect_b32 s82, s51, s80
	s_cselect_b32 s81, s52, s85
	s_cselect_b32 s80, s53, s73
	s_mov_b32 m0, s48
	v_lshl_add_u64 v[136:137], s[78:79], 0, v[134:135]
	ds_read_b128 v[178:181], v143
	ds_read_b128 v[182:185], v143 offset:1024
	ds_read_b128 v[186:189], v143 offset:2048
	ds_read_b128 v[190:193], v143 offset:3072
	ds_read_b128 v[194:197], v143 offset:4096
	ds_read_b128 v[198:201], v143 offset:5120
	ds_read_b128 v[202:205], v143 offset:6144
	ds_read_b128 v[206:209], v143 offset:7168
	global_load_lds_dwordx4 v134, s[78:79]
	v_lshl_add_u64 v[136:137], s[78:79], 0, v[132:133]
	s_mov_b32 m0, s49
	s_nop 0
	global_load_lds_dwordx4 v132, s[78:79]
	s_waitcnt vmcnt(8) lgkmcnt(0)
	s_setprio 1
	s_barrier
; #define PG8_MMA(ai, bj, At, Bt) do { __builtin_amdgcn_s_setprio(1); _Pragma("unroll") for (int m = 0; m < 4; ++m) _Pragma("unroll") for (int n = 0; n < 2; ++n) _Pragma("unroll") for (int k = 0; k < 2; ++k) \
;         acc[ai][bj][m][n] = __builtin_amdgcn_mfma_f32_16x16x32_bf16(Bt[n][k], At[m][k], acc[ai][bj][m][n], 0, 0, 0); __builtin_amdgcn_s_setprio(0); } while (0)
; template <class Epi, class Sched, bool ALIGN_EPI = false, bool SP2 = false, bool A_TILED = false>
; __device__ __forceinline__ void gemm_phase(PG8_LAS unsigned char* lds, const Gemm g, const Sched& S, const Epi& E, const int wave_s) {
;     ...
;         for (int t = PEEL ? 2 : 0; t < nt; t += 2) {
;             const bool last = (t == nt - 2);
;             const char* a1 = cA + (size_t)(t + 1) * kstepA;
;             const char* a2 = last ? nA : cA + (size_t)(t + 2) * kstepA; const char* b2 = last ? nB : cB + (size_t)(t + 2) * kstep;
;             const char* a3 = a2 + kstepA; const char* b3 = b2 + kstep;
;             if (last && has_next) S.a_ready(nxt);
;             if constexpr (SP2) {
;             PG8_ITER(PG8_MMA)
	v_mfma_f32_16x16x32_bf16 v[24:27], v[146:149], v[178:181], v[24:27]
	v_mfma_f32_16x16x32_bf16 v[28:31], v[154:157], v[178:181], v[28:31]
	v_mfma_f32_16x16x32_bf16 v[16:19], v[146:149], v[186:189], v[16:19]
	v_mfma_f32_16x16x32_bf16 v[20:23], v[154:157], v[186:189], v[20:23]
	v_mfma_f32_16x16x32_bf16 v[8:11], v[146:149], v[194:197], v[8:11]
	v_mfma_f32_16x16x32_bf16 v[12:15], v[154:157], v[194:197], v[12:15]
	v_mfma_f32_16x16x32_bf16 v[0:3], v[146:149], v[202:205], v[0:3]
	v_mfma_f32_16x16x32_bf16 v[4:7], v[154:157], v[202:205], v[4:7]
	v_mfma_f32_16x16x32_bf16 v[24:27], v[150:153], v[182:185], v[24:27]
	v_mfma_f32_16x16x32_bf16 v[28:31], v[158:161], v[182:185], v[28:31]
	v_mfma_f32_16x16x32_bf16 v[16:19], v[150:153], v[190:193], v[16:19]
	v_mfma_f32_16x16x32_bf16 v[20:23], v[158:161], v[190:193], v[20:23]
	v_mfma_f32_16x16x32_bf16 v[8:11], v[150:153], v[198:201], v[8:11]
	v_mfma_f32_16x16x32_bf16 v[12:15], v[158:161], v[198:201], v[12:15]
	v_mfma_f32_16x16x32_bf16 v[0:3], v[150:153], v[206:209], v[0:3]
	v_mfma_f32_16x16x32_bf16 v[4:7], v[158:161], v[206:209], v[4:7]
	s_setprio 0
	s_setprio 1
	v_mfma_f32_16x16x32_bf16 v[56:59], v[162:165], v[178:181], v[56:59]
	v_mfma_f32_16x16x32_bf16 v[60:63], v[170:173], v[178:181], v[60:63]
	v_mfma_f32_16x16x32_bf16 v[48:51], v[162:165], v[186:189], v[48:51]
	v_mfma_f32_16x16x32_bf16 v[52:55], v[170:173], v[186:189], v[52:55]
	v_mfma_f32_16x16x32_bf16 v[40:43], v[162:165], v[194:197], v[40:43]
	v_mfma_f32_16x16x32_bf16 v[44:47], v[170:173], v[194:197], v[44:47]
	v_mfma_f32_16x16x32_bf16 v[32:35], v[162:165], v[202:205], v[32:35]
	v_mfma_f32_16x16x32_bf16 v[36:39], v[170:173], v[202:205], v[36:39]
	v_mfma_f32_16x16x32_bf16 v[56:59], v[166:169], v[182:185], v[56:59]
	v_mfma_f32_16x16x32_bf16 v[60:63], v[174:177], v[182:185], v[60:63]
	v_mfma_f32_16x16x32_bf16 v[48:51], v[166:169], v[190:193], v[48:51]
	v_mfma_f32_16x16x32_bf16 v[52:55], v[174:177], v[190:193], v[52:55]
	v_mfma_f32_16x16x32_bf16 v[40:43], v[166:169], v[198:201], v[40:43]
	v_mfma_f32_16x16x32_bf16 v[44:47], v[174:177], v[198:201], v[44:47]
	v_mfma_f32_16x16x32_bf16 v[32:35], v[166:169], v[206:209], v[32:35]
	v_mfma_f32_16x16x32_bf16 v[36:39], v[174:177], v[206:209], v[36:39]
	s_barrier
	s_setprio 0
	s_mov_b32 m0, s54
	v_lshl_add_u64 v[136:137], s[80:81], 0, v[128:129]
	s_add_u32 s90, s80, 0x80000
	ds_read_b128 v[178:181], v143 offset:16384
	ds_read_b128 v[182:185], v143 offset:17408
	ds_read_b128 v[186:189], v143 offset:18432
	ds_read_b128 v[190:193], v143 offset:19456
	ds_read_b128 v[194:197], v143 offset:20480
	ds_read_b128 v[198:201], v143 offset:21504
	ds_read_b128 v[202:205], v143 offset:22528
	ds_read_b128 v[206:209], v143 offset:23552
	global_load_lds_dwordx4 v128, s[80:81]
	v_lshl_add_u64 v[138:139], s[80:81], 0, v[130:131]
	s_mov_b32 m0, s55
	s_addc_u32 s91, s81, 0
	global_load_lds_dwordx4 v130, s[80:81]
	v_lshl_add_u64 v[210:211], s[90:91], 0, v[128:129]
	s_mov_b32 m0, s56
	v_lshl_add_u64 v[212:213], s[82:83], 0, v[130:131]
	global_load_lds_dwordx4 v128, s[90:91]
	v_lshl_add_u64 v[210:211], s[90:91], 0, v[130:131]
	s_mov_b32 m0, s57
	s_nop 0
	global_load_lds_dwordx4 v130, s[90:91]
	v_lshl_add_u64 v[210:211], s[82:83], 0, v[128:129]
	s_mov_b32 m0, s22
	s_nop 0
	global_load_lds_dwordx4 v128, s[82:83]
	s_mov_b32 m0, s23
	s_nop 0
	global_load_lds_dwordx4 v130, s[82:83]
	s_waitcnt vmcnt(8) lgkmcnt(0)
	s_setprio 1
	s_barrier
	v_mfma_f32_16x16x32_bf16 v[88:91], v[146:149], v[178:181], v[88:91]
	v_mfma_f32_16x16x32_bf16 v[92:95], v[154:157], v[178:181], v[92:95]
	v_mfma_f32_16x16x32_bf16 v[80:83], v[146:149], v[186:189], v[80:83]
	v_mfma_f32_16x16x32_bf16 v[84:87], v[154:157], v[186:189], v[84:87]
	v_mfma_f32_16x16x32_bf16 v[72:75], v[146:149], v[194:197], v[72:75]
	v_mfma_f32_16x16x32_bf16 v[76:79], v[154:157], v[194:197], v[76:79]
	v_mfma_f32_16x16x32_bf16 v[64:67], v[146:149], v[202:205], v[64:67]
	v_mfma_f32_16x16x32_bf16 v[68:71], v[154:157], v[202:205], v[68:71]
	v_mfma_f32_16x16x32_bf16 v[88:91], v[150:153], v[182:185], v[88:91]
	v_mfma_f32_16x16x32_bf16 v[92:95], v[158:161], v[182:185], v[92:95]
	v_mfma_f32_16x16x32_bf16 v[80:83], v[150:153], v[190:193], v[80:83]
	v_mfma_f32_16x16x32_bf16 v[84:87], v[158:161], v[190:193], v[84:87]
	v_mfma_f32_16x16x32_bf16 v[72:75], v[150:153], v[198:201], v[72:75]
	v_mfma_f32_16x16x32_bf16 v[76:79], v[158:161], v[198:201], v[76:79]
	v_mfma_f32_16x16x32_bf16 v[64:67], v[150:153], v[206:209], v[64:67]
	v_mfma_f32_16x16x32_bf16 v[68:71], v[158:161], v[206:209], v[68:71]
	s_setprio 0
	s_setprio 1
	v_mfma_f32_16x16x32_bf16 v[120:123], v[162:165], v[178:181], v[120:123]
	v_mfma_f32_16x16x32_bf16 v[124:127], v[170:173], v[178:181], v[124:127]
	v_mfma_f32_16x16x32_bf16 v[112:115], v[162:165], v[186:189], v[112:115]
	v_mfma_f32_16x16x32_bf16 v[116:119], v[170:173], v[186:189], v[116:119]
	v_mfma_f32_16x16x32_bf16 v[104:107], v[162:165], v[194:197], v[104:107]
	v_mfma_f32_16x16x32_bf16 v[108:111], v[170:173], v[194:197], v[108:111]
	v_mfma_f32_16x16x32_bf16 v[96:99], v[162:165], v[202:205], v[96:99]
	v_mfma_f32_16x16x32_bf16 v[100:103], v[170:173], v[202:205], v[100:103]
	v_mfma_f32_16x16x32_bf16 v[120:123], v[166:169], v[182:185], v[120:123]
	v_mfma_f32_16x16x32_bf16 v[124:127], v[174:177], v[182:185], v[124:127]
	v_mfma_f32_16x16x32_bf16 v[112:115], v[166:169], v[190:193], v[112:115]
	v_mfma_f32_16x16x32_bf16 v[116:119], v[174:177], v[190:193], v[116:119]
	v_mfma_f32_16x16x32_bf16 v[104:107], v[166:169], v[198:201], v[104:107]
	v_mfma_f32_16x16x32_bf16 v[108:111], v[174:177], v[198:201], v[108:111]
	v_mfma_f32_16x16x32_bf16 v[96:99], v[166:169], v[206:209], v[96:99]
	v_mfma_f32_16x16x32_bf16 v[100:103], v[174:177], v[206:209], v[100:103]
	s_barrier
; #define PG8_MMA(ai, bj, At, Bt) do { __builtin_amdgcn_s_setprio(1); _Pragma("unroll") for (int m = 0; m < 4; ++m) _Pragma("unroll") for (int n = 0; n < 2; ++n) _Pragma("unroll") for (int k = 0; k < 2; ++k) \
;         acc[ai][bj][m][n] = __builtin_amdgcn_mfma_f32_16x16x32_bf16(Bt[n][k], At[m][k], acc[ai][bj][m][n], 0, 0, 0); __builtin_amdgcn_s_setprio(0); } while (0)
; template <class Epi, class Sched, bool ALIGN_EPI = false, bool SP2 = false, bool A_TILED = false>
; __device__ __forceinline__ void gemm_phase(PG8_LAS unsigned char* lds, const Gemm g, const Sched& S, const Epi& E, const int wave_s) {
;     ...
;         for (int t = PEEL ? 2 : 0; t < nt; t += 2) {
;             const bool last = (t == nt - 2);
;             const char* a1 = cA + (size_t)(t + 1) * kstepA;
;             const char* a2 = last ? nA : cA + (size_t)(t + 2) * kstepA; const char* b2 = last ? nB : cB + (size_t)(t + 2) * kstep;
;             const char* a3 = a2 + kstepA; const char* b3 = b2 + kstep;
;             if (last && has_next) S.a_ready(nxt);
;             if constexpr (SP2) {
;             PG8_ITER(PG8_MMA)
	s_setprio 0
	ds_read_b128 v[146:149], v144
	ds_read_b128 v[150:153], v144 offset:1024
	ds_read_b128 v[154:157], v144 offset:2048
	ds_read_b128 v[158:161], v144 offset:3072
	ds_read_b128 v[162:165], v145
	ds_read_b128 v[166:169], v145 offset:1024
	ds_read_b128 v[170:173], v145 offset:2048
	ds_read_b128 v[174:177], v145 offset:3072
	s_add_u32 s82, s82, 0x80000
	s_addc_u32 s83, s83, 0
	s_mov_b32 m0, s36
	v_lshl_add_u64 v[214:215], s[82:83], 0, v[128:129]
	ds_read_b128 v[178:181], v143 offset:32768
	ds_read_b128 v[182:185], v143 offset:33792
	ds_read_b128 v[186:189], v143 offset:34816
	ds_read_b128 v[190:193], v143 offset:35840
	ds_read_b128 v[194:197], v143 offset:36864
	ds_read_b128 v[198:201], v143 offset:37888
	ds_read_b128 v[202:205], v143 offset:38912
	ds_read_b128 v[206:209], v143 offset:39936
	global_load_lds_dwordx4 v128, s[82:83]
	v_lshl_add_u64 v[214:215], s[82:83], 0, v[130:131]
	s_mov_b32 m0, s37
	s_nop 0
	global_load_lds_dwordx4 v130, s[82:83]
	s_waitcnt vmcnt(8) lgkmcnt(0)
	s_setprio 1
	s_barrier
	v_mfma_f32_16x16x32_bf16 v[24:27], v[146:149], v[178:181], v[24:27]
	v_mfma_f32_16x16x32_bf16 v[28:31], v[154:157], v[178:181], v[28:31]
	v_mfma_f32_16x16x32_bf16 v[16:19], v[146:149], v[186:189], v[16:19]
	v_mfma_f32_16x16x32_bf16 v[20:23], v[154:157], v[186:189], v[20:23]
	v_mfma_f32_16x16x32_bf16 v[8:11], v[146:149], v[194:197], v[8:11]
	v_mfma_f32_16x16x32_bf16 v[12:15], v[154:157], v[194:197], v[12:15]
	v_mfma_f32_16x16x32_bf16 v[0:3], v[146:149], v[202:205], v[0:3]
	v_mfma_f32_16x16x32_bf16 v[4:7], v[154:157], v[202:205], v[4:7]
	v_mfma_f32_16x16x32_bf16 v[24:27], v[150:153], v[182:185], v[24:27]
	v_mfma_f32_16x16x32_bf16 v[28:31], v[158:161], v[182:185], v[28:31]
	v_mfma_f32_16x16x32_bf16 v[16:19], v[150:153], v[190:193], v[16:19]
	v_mfma_f32_16x16x32_bf16 v[20:23], v[158:161], v[190:193], v[20:23]
	v_mfma_f32_16x16x32_bf16 v[8:11], v[150:153], v[198:201], v[8:11]
	v_mfma_f32_16x16x32_bf16 v[12:15], v[158:161], v[198:201], v[12:15]
	v_mfma_f32_16x16x32_bf16 v[0:3], v[150:153], v[206:209], v[0:3]
	v_mfma_f32_16x16x32_bf16 v[4:7], v[158:161], v[206:209], v[4:7]
	s_setprio 0
	s_setprio 1
	v_mfma_f32_16x16x32_bf16 v[56:59], v[162:165], v[178:181], v[56:59]
	v_mfma_f32_16x16x32_bf16 v[60:63], v[170:173], v[178:181], v[60:63]
	v_mfma_f32_16x16x32_bf16 v[48:51], v[162:165], v[186:189], v[48:51]
	v_mfma_f32_16x16x32_bf16 v[52:55], v[170:173], v[186:189], v[52:55]
	v_mfma_f32_16x16x32_bf16 v[40:43], v[162:165], v[194:197], v[40:43]
	v_mfma_f32_16x16x32_bf16 v[44:47], v[170:173], v[194:197], v[44:47]
	v_mfma_f32_16x16x32_bf16 v[32:35], v[162:165], v[202:205], v[32:35]
	v_mfma_f32_16x16x32_bf16 v[36:39], v[170:173], v[202:205], v[36:39]
	v_mfma_f32_16x16x32_bf16 v[56:59], v[166:169], v[182:185], v[56:59]
	v_mfma_f32_16x16x32_bf16 v[60:63], v[174:177], v[182:185], v[60:63]
	v_mfma_f32_16x16x32_bf16 v[48:51], v[166:169], v[190:193], v[48:51]
	v_mfma_f32_16x16x32_bf16 v[52:55], v[174:177], v[190:193], v[52:55]
	v_mfma_f32_16x16x32_bf16 v[40:43], v[166:169], v[198:201], v[40:43]
	v_mfma_f32_16x16x32_bf16 v[44:47], v[174:177], v[198:201], v[44:47]
	v_mfma_f32_16x16x32_bf16 v[32:35], v[166:169], v[206:209], v[32:35]
	v_mfma_f32_16x16x32_bf16 v[36:39], v[174:177], v[206:209], v[36:39]
	s_barrier
	s_setprio 0
	s_mov_b32 m0, s58
	v_lshl_add_u64 v[136:137], v[136:137], 0, s[62:63]
	s_add_u32 s80, s80, 0x80080
	ds_read_b128 v[178:181], v143 offset:49152
	ds_read_b128 v[182:185], v143 offset:50176
	ds_read_b128 v[186:189], v143 offset:51200
	ds_read_b128 v[190:193], v143 offset:52224
	ds_read_b128 v[194:197], v143 offset:53248
	ds_read_b128 v[198:201], v143 offset:54272
	ds_read_b128 v[202:205], v143 offset:55296
	ds_read_b128 v[206:209], v143 offset:56320
	global_load_lds_dwordx4 v[136:137], off
	v_lshl_add_u64 v[136:137], v[138:139], 0, s[62:63]
	s_mov_b32 m0, s59
	s_addc_u32 s81, s81, 0
	global_load_lds_dwordx4 v[136:137], off
	v_lshl_add_u64 v[136:137], s[80:81], 0, v[128:129]
	s_mov_b32 m0, s61
	s_nop 0
	global_load_lds_dwordx4 v128, s[80:81]
	v_lshl_add_u64 v[136:137], s[80:81], 0, v[130:131]
	s_mov_b32 m0, s71
	s_nop 0
	global_load_lds_dwordx4 v130, s[80:81]
	v_lshl_add_u64 v[136:137], v[210:211], 0, s[62:63]
	s_mov_b32 m0, s42
	s_nop 0
	global_load_lds_dwordx4 v[136:137], off
	v_lshl_add_u64 v[136:137], v[212:213], 0, s[62:63]
	s_mov_b32 m0, s43
	s_nop 0
	global_load_lds_dwordx4 v[136:137], off
	s_waitcnt vmcnt(8) lgkmcnt(0)
	s_setprio 1
	s_barrier
	v_mfma_f32_16x16x32_bf16 v[88:91], v[146:149], v[178:181], v[88:91]
	v_mfma_f32_16x16x32_bf16 v[92:95], v[154:157], v[178:181], v[92:95]
	v_mfma_f32_16x16x32_bf16 v[80:83], v[146:149], v[186:189], v[80:83]
	v_mfma_f32_16x16x32_bf16 v[84:87], v[154:157], v[186:189], v[84:87]
	v_mfma_f32_16x16x32_bf16 v[72:75], v[146:149], v[194:197], v[72:75]
	v_mfma_f32_16x16x32_bf16 v[76:79], v[154:157], v[194:197], v[76:79]
	v_mfma_f32_16x16x32_bf16 v[64:67], v[146:149], v[202:205], v[64:67]
	v_mfma_f32_16x16x32_bf16 v[68:71], v[154:157], v[202:205], v[68:71]
	v_mfma_f32_16x16x32_bf16 v[88:91], v[150:153], v[182:185], v[88:91]
	v_mfma_f32_16x16x32_bf16 v[92:95], v[158:161], v[182:185], v[92:95]
	v_mfma_f32_16x16x32_bf16 v[80:83], v[150:153], v[190:193], v[80:83]
	v_mfma_f32_16x16x32_bf16 v[84:87], v[158:161], v[190:193], v[84:87]
	v_mfma_f32_16x16x32_bf16 v[72:75], v[150:153], v[198:201], v[72:75]
	v_mfma_f32_16x16x32_bf16 v[76:79], v[158:161], v[198:201], v[76:79]
	v_mfma_f32_16x16x32_bf16 v[64:67], v[150:153], v[206:209], v[64:67]
	v_mfma_f32_16x16x32_bf16 v[68:71], v[158:161], v[206:209], v[68:71]
	s_setprio 0
	s_setprio 1
	v_mfma_f32_16x16x32_bf16 v[120:123], v[162:165], v[178:181], v[120:123]
	v_mfma_f32_16x16x32_bf16 v[124:127], v[170:173], v[178:181], v[124:127]
	v_mfma_f32_16x16x32_bf16 v[112:115], v[162:165], v[186:189], v[112:115]
	v_mfma_f32_16x16x32_bf16 v[116:119], v[170:173], v[186:189], v[116:119]
	v_mfma_f32_16x16x32_bf16 v[104:107], v[162:165], v[194:197], v[104:107]
	v_mfma_f32_16x16x32_bf16 v[108:111], v[170:173], v[194:197], v[108:111]
	v_mfma_f32_16x16x32_bf16 v[96:99], v[162:165], v[202:205], v[96:99]
	v_mfma_f32_16x16x32_bf16 v[100:103], v[170:173], v[202:205], v[100:103]
	v_mfma_f32_16x16x32_bf16 v[120:123], v[166:169], v[182:185], v[120:123]
	v_mfma_f32_16x16x32_bf16 v[124:127], v[174:177], v[182:185], v[124:127]
	v_mfma_f32_16x16x32_bf16 v[112:115], v[166:169], v[190:193], v[112:115]
	v_mfma_f32_16x16x32_bf16 v[116:119], v[174:177], v[190:193], v[116:119]
	v_mfma_f32_16x16x32_bf16 v[104:107], v[166:169], v[198:201], v[104:107]
	v_mfma_f32_16x16x32_bf16 v[108:111], v[174:177], v[198:201], v[108:111]
	v_mfma_f32_16x16x32_bf16 v[96:99], v[166:169], v[206:209], v[96:99]
	v_mfma_f32_16x16x32_bf16 v[100:103], v[174:177], v[206:209], v[100:103]
	s_barrier
	s_setprio 0
	s_add_i32 s88, s88, 2
	s_add_u32 s73, s73, 0x100
	s_addc_u32 s85, s85, 0
	s_add_u32 s78, s78, 0x100
	s_addc_u32 s79, s79, 0
	s_cmp_gt_u32 s88, 29
	s_cbranch_scc0 .LBB0_2417
	s_and_b64 vcc, exec, s[64:65]
	s_cbranch_vccz .LBB0_2420
	s_barrier

; #define PG8_STAGE(bufoff, gbase, voff) do { _Pragma("unroll") for (int _i = 0; _i < 2; ++_i) \
;         __builtin_amdgcn_global_load_lds((const unsigned*)((const char*)(gbase) + (voff)[_i]), (PG8_LAS unsigned*)(lds + (bufoff) + ldsw + _i * 8192), 16, 0, 0); } while (0)
; #define PG8_WAIT_V(n) asm volatile("s_waitcnt vmcnt(" #n ")" ::: "memory")
; #define PG8_BAR __builtin_amdgcn_s_barrier()
; template <class Epi, class Sched, bool ALIGN_EPI = false, bool SP2 = false, bool A_TILED = false>
; __device__ __forceinline__ void gemm_phase(PG8_LAS unsigned char* lds, const Gemm g, const Sched& S, const Epi& E, const int wave_s) {
;     ...
;     if constexpr (SP2) {
;         PG8_STAGE(PG8_SB(0, 0), cB, voffB); PG8_STAGE(PG8_SB(0, 1), cB + hstep, voffB); PG8_STAGE(PG8_SA(0, 0), cA, voffA); PG8_STAGE(PG8_SA(0, 1), cA + hstepA, voffA);
;         if (wr == 1) PG8_BAR;
;         PG8_WAIT_V(2); PG8_BAR;
;         PG8_STAGE(PG8_SB(1, 0), cB + kstep, voffB); PG8_STAGE(PG8_SA(1, 0), cA + kstepA, voffA); PG8_STAGE(PG8_SB(1, 1), cB + hstep + kstep, voffB);
;         PG8_WAIT_V(6); PG8_BAR;
.LBB0_2540:
	s_sext_i32_i8 s5, s2
	s_mul_i32 s2, s96, 0x7800000
	s_add_u32 s2, s12, s2
	s_addc_u32 s44, s13, 0
	s_add_u32 s60, s2, 0x24600000
	s_addc_u32 s61, s44, 0
	v_and_b32_e32 v15, 48, v14
	v_lshlrev_b32_e32 v16, 6, v14
	s_movk_i32 s44, 0x3c0
	v_lshlrev_b32_e32 v14, 2, v14
	s_lshl_b32 s2, s50, 13
	v_and_or_b32 v15, v16, s44, v15
	v_and_b32_e32 v14, 32, v14
	v_bitop3_b32 v16, v15, s2, v14 bitop3:0xde
	s_lshl_b32 s2, s8, 5
	s_mov_b64 s[62:63], 0x80
	s_lshl_b32 s49, s50, 6
	s_and_b32 s50, s2, 0x60
	s_add_i32 m0, s38, 0x18000
	v_lshl_add_u64 v[6:7], v[6:7], 0, s[62:63]
	s_lshl_b32 s2, s50, 7
	s_waitcnt vmcnt(2)
	s_barrier
	global_load_lds_dwordx4 v[6:7], off
	v_lshl_add_u64 v[4:5], v[4:5], 0, s[62:63]
	s_add_i32 m0, s38, 0x1a000
	s_add_i32 s51, s38, 0x8000
	s_add_i32 s52, s38, 0xa000
	global_load_lds_dwordx4 v[4:5], off
	v_lshl_add_u64 v[0:1], v[0:1], 0, s[62:63]
	s_mov_b32 m0, s51
	s_add_u32 s54, s78, 0x20080
	global_load_lds_dwordx4 v[0:1], off
	v_lshl_add_u64 v[0:1], v[2:3], 0, s[62:63]
	s_mov_b32 m0, s52
	s_addc_u32 s55, s79, 0
	global_load_lds_dwordx4 v[0:1], off
	s_add_i32 m0, s38, 0x1c000
	v_lshl_add_u64 v[0:1], s[54:55], 0, v[128:129]
	global_load_lds_dwordx4 v128, s[54:55]
	v_lshl_add_u64 v[0:1], s[54:55], 0, v[130:131]
	s_add_i32 m0, s38, 0x1e000
	s_cmpk_lt_u32 s3, 0x100
	global_load_lds_dwordx4 v130, s[54:55]
	v_lshlrev_b32_e32 v0, 13, v8
	v_and_b32_e32 v0, 0xffffc000, v0
	v_lshl_add_u32 v0, v9, 10, v0
	v_and_b32_e32 v1, 1, v8
	v_lshl_or_b32 v0, v1, 6, v0
	v_lshl_add_u32 v136, v10, 1, v0
	v_lshlrev_b32_e32 v0, 13, v12
	v_and_b32_e32 v0, 0xffffc000, v0
	s_waitcnt vmcnt(6)
	v_lshl_add_u32 v0, v11, 10, v0
	v_and_b32_e32 v1, 1, v12
	v_bitop3_b32 v148, s2, v15, v14 bitop3:0xf6
	s_cselect_b64 s[64:65], -1, 0
	v_lshl_or_b32 v0, v1, 6, v0
	s_add_i32 s53, 0, 0x10000
	s_add_i32 s54, 0, 0x14000
	s_mov_b32 s48, 0
	v_mov_b32_e32 v137, v129
	v_lshl_add_u32 v138, v13, 1, v0
	v_mov_b32_e32 v139, v129
	v_add_u32_e32 v149, s53, v148
	v_add_u32_e32 v150, s54, v148
	v_add_u32_e32 v151, 0, v16
	s_mov_b64 s[66:67], 0x100
	s_mov_b64 s[68:69], 0x180
	s_mov_b32 s55, 0xc2fc0000
	s_movk_i32 s56, 0x7f
	s_movk_i32 s57, 0x1800
	v_mov_b32_e32 v152, 0x42800000
	v_not_b32_e32 v153, 63
	s_barrier
	s_branch .LBB0_2543

; template <class Epi, class Sched, bool ALIGN_EPI = false, bool SP2 = false, bool A_TILED = false>
; __device__ __forceinline__ void gemm_phase(PG8_LAS unsigned char* lds, const Gemm g, const Sched& S, const Epi& E, const int wave_s) {
;     ...
;         const bool has_next = Epi::AFTER_DRAIN ? false : S.next(ui + 1, nxt);
;         const char* nA = has_next ? (const char*)g.A + (size_t)nxt.pm * tstepA : cA; const char* nB = has_next ? (const char*)g.Bt + (size_t)nxt.pn * tstep : cB;
;         constexpr bool PEEL = SP2 && !Epi::AFTER_DRAIN;
;         if constexpr (PEEL) {
;             const char* a1 = cA + kstepA; const char* a2 = cA + 2 * kstepA; const char* b2 = cB + 2 * kstep; const char* a3 = a2 + kstepA; const char* b3 = b2 + kstep;
;             PG8_ITER(PG8_MMAZ)
.LBB0_2545:
	s_ashr_i32 s73, s72, 31
	s_lshl_b64 s[58:59], s[72:73], 18
	s_add_u32 s74, s14, s58
	ds_read_b128 v[0:3], v149
	ds_read_b128 v[4:7], v149 offset:1024
	ds_read_b128 v[8:11], v149 offset:2048
	ds_read_b128 v[12:15], v149 offset:3072
	ds_read_b128 v[16:19], v150
	ds_read_b128 v[20:23], v150 offset:1024
	ds_read_b128 v[24:27], v150 offset:2048
	ds_read_b128 v[28:31], v150 offset:3072
	s_addc_u32 s75, s15, s59
	s_ashr_i32 s71, s70, 31
	s_lshl_b64 s[58:59], s[70:71], 18
	s_add_u32 s76, s23, s58
	s_addc_u32 s77, s36, s59
	s_and_b64 s[58:59], s[2:3], exec
	s_cselect_b32 s58, s75, s81
	s_cselect_b32 s59, s74, s80
	s_cselect_b32 s71, s77, s79
	s_cselect_b32 s73, s76, s78
	s_add_u32 s82, s80, 0x20080
	s_addc_u32 s83, s81, 0
	s_add_i32 s88, s38, 0xc000
	v_lshl_add_u64 v[64:65], s[82:83], 0, v[134:135]
	s_mov_b32 m0, s88
	s_add_i32 s89, s38, 0xe000
	ds_read_b128 v[32:35], v151
	ds_read_b128 v[36:39], v151 offset:1024
	ds_read_b128 v[40:43], v151 offset:2048
	ds_read_b128 v[44:47], v151 offset:3072
	ds_read_b128 v[48:51], v151 offset:4096
	ds_read_b128 v[52:55], v151 offset:5120
	ds_read_b128 v[56:59], v151 offset:6144
	ds_read_b128 v[60:63], v151 offset:7168
	global_load_lds_dwordx4 v134, s[82:83]
	v_lshl_add_u64 v[64:65], s[82:83], 0, v[132:133]
	s_mov_b32 m0, s89
	s_nop 0
	global_load_lds_dwordx4 v132, s[82:83]
	s_waitcnt vmcnt(8) lgkmcnt(0)
	s_setprio 1
	s_barrier
	v_mfma_f32_16x16x32_bf16 v[88:91], v[0:3], v[56:59], 0
	v_mfma_f32_16x16x32_bf16 v[64:67], v[0:3], v[32:35], 0
	v_mfma_f32_16x16x32_bf16 v[68:71], v[8:11], v[32:35], 0
	v_mfma_f32_16x16x32_bf16 v[72:75], v[0:3], v[40:43], 0
	v_mfma_f32_16x16x32_bf16 v[76:79], v[8:11], v[40:43], 0
	v_mfma_f32_16x16x32_bf16 v[80:83], v[0:3], v[48:51], 0
	v_mfma_f32_16x16x32_bf16 v[84:87], v[8:11], v[48:51], 0
	v_mfma_f32_16x16x32_bf16 v[96:99], v[4:7], v[60:63], v[88:91]
	v_mfma_f32_16x16x32_bf16 v[88:91], v[8:11], v[56:59], 0
	v_mfma_f32_16x16x32_bf16 v[64:67], v[4:7], v[36:39], v[64:67]
	v_mfma_f32_16x16x32_bf16 v[68:71], v[12:15], v[36:39], v[68:71]
	v_mfma_f32_16x16x32_bf16 v[72:75], v[4:7], v[44:47], v[72:75]
	v_mfma_f32_16x16x32_bf16 v[76:79], v[12:15], v[44:47], v[76:79]
	v_mfma_f32_16x16x32_bf16 v[80:83], v[4:7], v[52:55], v[80:83]
	v_mfma_f32_16x16x32_bf16 v[84:87], v[12:15], v[52:55], v[84:87]
	v_mfma_f32_16x16x32_bf16 v[100:103], v[12:15], v[60:63], v[88:91]
	s_setprio 0
	s_setprio 1
	v_mfma_f32_16x16x32_bf16 v[88:91], v[16:19], v[32:35], 0
	v_mfma_f32_16x16x32_bf16 v[32:35], v[24:27], v[32:35], 0
	v_mfma_f32_16x16x32_bf16 v[112:115], v[20:23], v[36:39], v[88:91]
	v_mfma_f32_16x16x32_bf16 v[32:35], v[28:31], v[36:39], v[32:35]
	v_mfma_f32_16x16x32_bf16 v[36:39], v[16:19], v[40:43], 0
	v_mfma_f32_16x16x32_bf16 v[40:43], v[24:27], v[40:43], 0
	v_mfma_f32_16x16x32_bf16 v[36:39], v[20:23], v[44:47], v[36:39]
	v_mfma_f32_16x16x32_bf16 v[40:43], v[28:31], v[44:47], v[40:43]
	v_mfma_f32_16x16x32_bf16 v[44:47], v[16:19], v[48:51], 0
	v_mfma_f32_16x16x32_bf16 v[48:51], v[24:27], v[48:51], 0
	v_mfma_f32_16x16x32_bf16 v[44:47], v[20:23], v[52:55], v[44:47]
	v_mfma_f32_16x16x32_bf16 v[48:51], v[28:31], v[52:55], v[48:51]
	v_mfma_f32_16x16x32_bf16 v[52:55], v[16:19], v[56:59], 0
	v_mfma_f32_16x16x32_bf16 v[56:59], v[24:27], v[56:59], 0
	v_mfma_f32_16x16x32_bf16 v[52:55], v[20:23], v[60:63], v[52:55]
	v_mfma_f32_16x16x32_bf16 v[56:59], v[28:31], v[60:63], v[56:59]
	s_barrier
	s_setprio 0
	s_add_i32 s90, s53, s37
	v_lshl_add_u64 v[250:251], s[78:79], 0, v[128:129]
	s_add_i32 s91, s90, 0x2000
	v_lshl_add_u64 v[144:145], v[250:251], 0, s[66:67]
	s_mov_b32 m0, s90
	v_lshl_add_u64 v[252:253], s[78:79], 0, v[130:131]
	s_add_u32 s82, s78, 0x20100
	ds_read_b128 v[60:63], v151 offset:16384
	ds_read_b128 v[88:91], v151 offset:17408
	ds_read_b128 v[92:95], v151 offset:18432
	ds_read_b128 v[104:107], v151 offset:19456
	ds_read_b128 v[108:111], v151 offset:20480
	ds_read_b128 v[116:119], v151 offset:21504
	ds_read_b128 v[120:123], v151 offset:22528
	ds_read_b128 v[124:127], v151 offset:23552
	global_load_lds_dwordx4 v[144:145], off
	v_lshl_add_u64 v[144:145], v[252:253], 0, s[66:67]
	s_mov_b32 m0, s91
	s_addc_u32 s83, s79, 0
	s_add_i32 s93, s54, s37
	global_load_lds_dwordx4 v[144:145], off
	v_lshl_add_u64 v[144:145], s[82:83], 0, v[128:129]
	s_mov_b32 m0, s93
	s_add_i32 s95, s93, 0x2000
	global_load_lds_dwordx4 v128, s[82:83]
	v_lshl_add_u64 v[144:145], s[82:83], 0, v[130:131]
	s_mov_b32 m0, s95
	v_lshl_add_u64 v[140:141], s[80:81], 0, v[134:135]
	global_load_lds_dwordx4 v130, s[82:83]
	v_lshl_add_u64 v[144:145], v[140:141], 0, s[66:67]
	s_mov_b32 m0, s38
	v_lshl_add_u64 v[142:143], s[80:81], 0, v[132:133]
	global_load_lds_dwordx4 v[144:145], off
	v_lshl_add_u64 v[144:145], v[142:143], 0, s[66:67]
	s_mov_b32 m0, s39
	s_nop 0
	global_load_lds_dwordx4 v[144:145], off
	s_waitcnt vmcnt(8) lgkmcnt(0)
	s_setprio 1
	s_barrier
	v_mfma_f32_16x16x32_bf16 v[144:147], v[0:3], v[60:63], 0
	v_mfma_f32_16x16x32_bf16 v[154:157], v[4:7], v[88:91], v[144:147]
	v_mfma_f32_16x16x32_bf16 v[144:147], v[8:11], v[60:63], 0
	v_mfma_f32_16x16x32_bf16 v[158:161], v[12:15], v[88:91], v[144:147]
	v_mfma_f32_16x16x32_bf16 v[144:147], v[0:3], v[92:95], 0
	v_mfma_f32_16x16x32_bf16 v[162:165], v[4:7], v[104:107], v[144:147]
	v_mfma_f32_16x16x32_bf16 v[144:147], v[8:11], v[92:95], 0
	v_mfma_f32_16x16x32_bf16 v[166:169], v[12:15], v[104:107], v[144:147]
	v_mfma_f32_16x16x32_bf16 v[144:147], v[0:3], v[108:111], 0
	v_mfma_f32_16x16x32_bf16 v[0:3], v[0:3], v[120:123], 0
	v_mfma_f32_16x16x32_bf16 v[170:173], v[4:7], v[116:119], v[144:147]
	v_mfma_f32_16x16x32_bf16 v[0:3], v[4:7], v[124:127], v[0:3]
	v_mfma_f32_16x16x32_bf16 v[4:7], v[8:11], v[120:123], 0
	v_mfma_f32_16x16x32_bf16 v[144:147], v[8:11], v[108:111], 0
	v_mfma_f32_16x16x32_bf16 v[4:7], v[12:15], v[124:127], v[4:7]
	v_mfma_f32_16x16x32_bf16 v[174:177], v[12:15], v[116:119], v[144:147]
	s_setprio 0
	s_setprio 1
	v_mfma_f32_16x16x32_bf16 v[8:11], v[16:19], v[60:63], 0
	v_mfma_f32_16x16x32_bf16 v[178:181], v[20:23], v[88:91], v[8:11]
	v_mfma_f32_16x16x32_bf16 v[8:11], v[24:27], v[60:63], 0
	v_mfma_f32_16x16x32_bf16 v[182:185], v[28:31], v[88:91], v[8:11]
	v_mfma_f32_16x16x32_bf16 v[8:11], v[16:19], v[92:95], 0
	v_mfma_f32_16x16x32_bf16 v[186:189], v[20:23], v[104:107], v[8:11]
	v_mfma_f32_16x16x32_bf16 v[8:11], v[24:27], v[92:95], 0
	v_mfma_f32_16x16x32_bf16 v[190:193], v[28:31], v[104:107], v[8:11]
	v_mfma_f32_16x16x32_bf16 v[8:11], v[16:19], v[108:111], 0
	v_mfma_f32_16x16x32_bf16 v[194:197], v[20:23], v[116:119], v[8:11]
	v_mfma_f32_16x16x32_bf16 v[8:11], v[24:27], v[108:111], 0
	v_mfma_f32_16x16x32_bf16 v[198:201], v[28:31], v[116:119], v[8:11]
	v_mfma_f32_16x16x32_bf16 v[8:11], v[16:19], v[120:123], 0
	v_mfma_f32_16x16x32_bf16 v[202:205], v[20:23], v[124:127], v[8:11]
	v_mfma_f32_16x16x32_bf16 v[8:11], v[24:27], v[120:123], 0
	v_mfma_f32_16x16x32_bf16 v[206:209], v[28:31], v[124:127], v[8:11]
	s_barrier
	s_setprio 0
	s_add_i32 s96, 0, 0x18000
	s_add_i32 vcc_lo, 0, 0x1c000
	v_add_u32_e32 v144, s96, v148
	v_add_u32_e32 v145, vcc_lo, v148
	s_nop 0
	ds_read_b128 v[8:11], v144
	ds_read_b128 v[12:15], v144 offset:1024
	ds_read_b128 v[16:19], v144 offset:2048
	ds_read_b128 v[20:23], v144 offset:3072
	ds_read_b128 v[210:213], v145
	ds_read_b128 v[214:217], v145 offset:1024
	ds_read_b128 v[218:221], v145 offset:2048
	ds_read_b128 v[222:225], v145 offset:3072
	s_add_u32 s82, s80, 0x20100
	s_addc_u32 s83, s81, 0
	s_mov_b32 m0, s40
	v_lshl_add_u64 v[88:89], s[82:83], 0, v[134:135]
	ds_read_b128 v[24:27], v151 offset:32768
	ds_read_b128 v[28:31], v151 offset:33792
	ds_read_b128 v[60:63], v151 offset:34816
	ds_read_b128 v[226:229], v151 offset:35840
	ds_read_b128 v[230:233], v151 offset:36864
	ds_read_b128 v[234:237], v151 offset:37888
	ds_read_b128 v[238:241], v151 offset:38912
	ds_read_b128 v[242:245], v151 offset:39936
	global_load_lds_dwordx4 v134, s[82:83]
	v_lshl_add_u64 v[88:89], s[82:83], 0, v[132:133]
	s_mov_b32 m0, s41
	s_nop 0
	global_load_lds_dwordx4 v132, s[82:83]
	s_waitcnt vmcnt(8) lgkmcnt(0)
	s_setprio 1
	s_barrier
	v_mfma_f32_16x16x32_bf16 v[64:67], v[8:11], v[24:27], v[64:67]
	v_mfma_f32_16x16x32_bf16 v[124:127], v[12:15], v[28:31], v[64:67]
	v_mfma_f32_16x16x32_bf16 v[64:67], v[16:19], v[24:27], v[68:71]
	v_mfma_f32_16x16x32_bf16 v[120:123], v[20:23], v[28:31], v[64:67]
	v_mfma_f32_16x16x32_bf16 v[64:67], v[8:11], v[60:63], v[72:75]
	v_mfma_f32_16x16x32_bf16 v[108:111], v[12:15], v[226:229], v[64:67]
	v_mfma_f32_16x16x32_bf16 v[64:67], v[16:19], v[60:63], v[76:79]
	v_mfma_f32_16x16x32_bf16 v[104:107], v[20:23], v[226:229], v[64:67]
	v_mfma_f32_16x16x32_bf16 v[64:67], v[8:11], v[230:233], v[80:83]
	v_mfma_f32_16x16x32_bf16 v[92:95], v[12:15], v[234:237], v[64:67]
	v_mfma_f32_16x16x32_bf16 v[64:67], v[16:19], v[230:233], v[84:87]
	v_mfma_f32_16x16x32_bf16 v[88:91], v[20:23], v[234:237], v[64:67]
	v_mfma_f32_16x16x32_bf16 v[64:67], v[8:11], v[238:241], v[96:99]
	v_mfma_f32_16x16x32_bf16 v[76:79], v[12:15], v[242:245], v[64:67]
	v_mfma_f32_16x16x32_bf16 v[64:67], v[16:19], v[238:241], v[100:103]
	v_mfma_f32_16x16x32_bf16 v[72:75], v[20:23], v[242:245], v[64:67]
	s_setprio 0
	s_setprio 1
	v_mfma_f32_16x16x32_bf16 v[64:67], v[210:213], v[24:27], v[112:115]
	v_mfma_f32_16x16x32_bf16 v[24:27], v[218:221], v[24:27], v[32:35]
	v_mfma_f32_16x16x32_bf16 v[112:115], v[222:225], v[28:31], v[24:27]
	v_mfma_f32_16x16x32_bf16 v[24:27], v[210:213], v[60:63], v[36:39]
	v_mfma_f32_16x16x32_bf16 v[100:103], v[214:217], v[226:229], v[24:27]
	v_mfma_f32_16x16x32_bf16 v[24:27], v[218:221], v[60:63], v[40:43]
	v_mfma_f32_16x16x32_bf16 v[96:99], v[222:225], v[226:229], v[24:27]
	v_mfma_f32_16x16x32_bf16 v[24:27], v[210:213], v[230:233], v[44:47]
	v_mfma_f32_16x16x32_bf16 v[84:87], v[214:217], v[234:237], v[24:27]
	v_mfma_f32_16x16x32_bf16 v[24:27], v[218:221], v[230:233], v[48:51]
	v_mfma_f32_16x16x32_bf16 v[80:83], v[222:225], v[234:237], v[24:27]
	v_mfma_f32_16x16x32_bf16 v[24:27], v[210:213], v[238:241], v[52:55]
	v_mfma_f32_16x16x32_bf16 v[68:71], v[214:217], v[242:245], v[24:27]
	v_mfma_f32_16x16x32_bf16 v[24:27], v[218:221], v[238:241], v[56:59]
	v_mfma_f32_16x16x32_bf16 v[116:119], v[214:217], v[28:31], v[64:67]
	v_mfma_f32_16x16x32_bf16 v[64:67], v[222:225], v[242:245], v[24:27]
	s_barrier
; #define PG8_MMA(ai, bj, At, Bt) do { __builtin_amdgcn_s_setprio(1); _Pragma("unroll") for (int m = 0; m < 4; ++m) _Pragma("unroll") for (int n = 0; n < 2; ++n) _Pragma("unroll") for (int k = 0; k < 2; ++k) \
;         acc[ai][bj][m][n] = __builtin_amdgcn_mfma_f32_16x16x32_bf16(Bt[n][k], At[m][k], acc[ai][bj][m][n], 0, 0, 0); __builtin_amdgcn_s_setprio(0); } while (0)
; template <class Epi, class Sched, bool ALIGN_EPI = false, bool SP2 = false, bool A_TILED = false>
; __device__ __forceinline__ void gemm_phase(PG8_LAS unsigned char* lds, const Gemm g, const Sched& S, const Epi& E, const int wave_s) {
;     ...
;         for (int t = PEEL ? 2 : 0; t < nt; t += 2) {
;             const bool last = (t == nt - 2);
;             const char* a1 = cA + (size_t)(t + 1) * kstepA;
;             const char* a2 = last ? nA : cA + (size_t)(t + 2) * kstepA; const char* b2 = last ? nB : cB + (size_t)(t + 2) * kstep;
;             const char* a3 = a2 + kstepA; const char* b3 = b2 + kstep;
;             if (last && has_next) S.a_ready(nxt);
;             if constexpr (SP2) {
;             PG8_ITER(PG8_MMA)
	s_setprio 0
	s_add_i32 s96, s96, s37
	s_add_i32 s97, s96, 0x2000
	s_nop 1
	v_lshl_add_u64 v[24:25], v[250:251], 0, s[68:69]
	s_mov_b32 m0, s96
	s_add_u32 s82, s78, 0x20180
	ds_read_b128 v[32:35], v151 offset:49152
	ds_read_b128 v[36:39], v151 offset:50176
	ds_read_b128 v[226:229], v151 offset:51200
	ds_read_b128 v[230:233], v151 offset:52224
	ds_read_b128 v[234:237], v151 offset:53248
	ds_read_b128 v[238:241], v151 offset:54272
	ds_read_b128 v[242:245], v151 offset:55296
	ds_read_b128 v[246:249], v151 offset:56320
	global_load_lds_dwordx4 v[24:25], off
	v_lshl_add_u64 v[24:25], v[252:253], 0, s[68:69]
	s_mov_b32 m0, s97
	s_addc_u32 s83, s79, 0
	s_add_i32 vcc_lo, vcc_lo, s37
	global_load_lds_dwordx4 v[24:25], off
	v_lshl_add_u64 v[24:25], s[82:83], 0, v[128:129]
	s_mov_b32 m0, vcc_lo
	s_add_i32 vcc_hi, vcc_lo, 0x2000
	global_load_lds_dwordx4 v128, s[82:83]
	v_lshl_add_u64 v[24:25], s[82:83], 0, v[130:131]
	s_mov_b32 m0, vcc_hi
	s_nop 0
	global_load_lds_dwordx4 v130, s[82:83]
	v_lshl_add_u64 v[24:25], v[140:141], 0, s[68:69]
	s_mov_b32 m0, s51
	s_nop 0
	global_load_lds_dwordx4 v[24:25], off
	v_lshl_add_u64 v[24:25], v[142:143], 0, s[68:69]
	s_mov_b32 m0, s52
	s_nop 0
	global_load_lds_dwordx4 v[24:25], off
	s_waitcnt vmcnt(8) lgkmcnt(0)
	s_setprio 1
	s_barrier
	v_mfma_f32_16x16x32_bf16 v[24:27], v[8:11], v[32:35], v[154:157]
	v_mfma_f32_16x16x32_bf16 v[60:63], v[12:15], v[36:39], v[24:27]
	v_mfma_f32_16x16x32_bf16 v[24:27], v[16:19], v[32:35], v[158:161]
	v_mfma_f32_16x16x32_bf16 v[56:59], v[20:23], v[36:39], v[24:27]
	v_mfma_f32_16x16x32_bf16 v[24:27], v[8:11], v[226:229], v[162:165]
	v_mfma_f32_16x16x32_bf16 v[44:47], v[12:15], v[230:233], v[24:27]
	v_mfma_f32_16x16x32_bf16 v[24:27], v[16:19], v[226:229], v[166:169]
	v_mfma_f32_16x16x32_bf16 v[40:43], v[20:23], v[230:233], v[24:27]
	v_mfma_f32_16x16x32_bf16 v[24:27], v[8:11], v[234:237], v[170:173]
	v_mfma_f32_16x16x32_bf16 v[0:3], v[8:11], v[242:245], v[0:3]
	v_mfma_f32_16x16x32_bf16 v[28:31], v[12:15], v[238:241], v[24:27]
	v_mfma_f32_16x16x32_bf16 v[24:27], v[16:19], v[234:237], v[174:177]
	v_mfma_f32_16x16x32_bf16 v[12:15], v[12:15], v[246:249], v[0:3]
	v_mfma_f32_16x16x32_bf16 v[0:3], v[16:19], v[242:245], v[4:7]
	v_mfma_f32_16x16x32_bf16 v[24:27], v[20:23], v[238:241], v[24:27]
	v_mfma_f32_16x16x32_bf16 v[8:11], v[20:23], v[246:249], v[0:3]
	s_setprio 0
	s_setprio 1
	v_mfma_f32_16x16x32_bf16 v[0:3], v[210:213], v[32:35], v[178:181]
	v_mfma_f32_16x16x32_bf16 v[52:55], v[214:217], v[36:39], v[0:3]
	v_mfma_f32_16x16x32_bf16 v[0:3], v[218:221], v[32:35], v[182:185]
	v_mfma_f32_16x16x32_bf16 v[48:51], v[222:225], v[36:39], v[0:3]
	v_mfma_f32_16x16x32_bf16 v[0:3], v[210:213], v[226:229], v[186:189]
	v_mfma_f32_16x16x32_bf16 v[36:39], v[214:217], v[230:233], v[0:3]
	v_mfma_f32_16x16x32_bf16 v[0:3], v[218:221], v[226:229], v[190:193]
	v_mfma_f32_16x16x32_bf16 v[32:35], v[222:225], v[230:233], v[0:3]
	v_mfma_f32_16x16x32_bf16 v[0:3], v[210:213], v[234:237], v[194:197]
	v_mfma_f32_16x16x32_bf16 v[20:23], v[214:217], v[238:241], v[0:3]
	v_mfma_f32_16x16x32_bf16 v[0:3], v[218:221], v[234:237], v[198:201]
	v_mfma_f32_16x16x32_bf16 v[16:19], v[222:225], v[238:241], v[0:3]
	v_mfma_f32_16x16x32_bf16 v[0:3], v[210:213], v[242:245], v[202:205]
	v_mfma_f32_16x16x32_bf16 v[4:7], v[214:217], v[246:249], v[0:3]
	v_mfma_f32_16x16x32_bf16 v[0:3], v[218:221], v[242:245], v[206:209]
	v_mfma_f32_16x16x32_bf16 v[0:3], v[222:225], v[246:249], v[0:3]
	s_barrier
	s_setprio 0
	s_add_u32 s85, s78, 0x200
	s_addc_u32 s8, s79, 0
	s_add_u32 s78, s80, 0x20180
	s_addc_u32 s79, s81, 0
	s_mov_b32 s94, 0
.LBB0_2546:
	ds_read_b128 v[154:157], v149
	ds_read_b128 v[158:161], v149 offset:1024
	ds_read_b128 v[162:165], v149 offset:2048
	ds_read_b128 v[166:169], v149 offset:3072
	ds_read_b128 v[170:173], v150
	ds_read_b128 v[174:177], v150 offset:1024
	ds_read_b128 v[178:181], v150 offset:2048
	ds_read_b128 v[182:185], v150 offset:3072
	s_add_u32 s44, s78, 0xfffe0080
	s_addc_u32 s45, s79, -1
	s_cmp_eq_u32 s94, 4
	s_cselect_b32 s83, s58, s45
	s_cselect_b32 s82, s59, s44
	s_cselect_b32 s81, s71, s8
	s_cselect_b32 s80, s73, s85
	s_mov_b32 m0, s88
	v_lshl_add_u64 v[140:141], s[78:79], 0, v[138:139]
	ds_read_b128 v[186:189], v151
	ds_read_b128 v[190:193], v151 offset:1024
	ds_read_b128 v[194:197], v151 offset:2048
	ds_read_b128 v[198:201], v151 offset:3072
	ds_read_b128 v[202:205], v151 offset:4096
	ds_read_b128 v[206:209], v151 offset:5120
	ds_read_b128 v[210:213], v151 offset:6144
	ds_read_b128 v[214:217], v151 offset:7168
	global_load_lds_dwordx4 v138, s[78:79]
	v_lshl_add_u64 v[140:141], s[78:79], 0, v[136:137]
	s_mov_b32 m0, s89
	s_nop 0
	global_load_lds_dwordx4 v136, s[78:79]
	s_waitcnt vmcnt(8) lgkmcnt(0)
	s_setprio 1
	s_barrier
	v_mfma_f32_16x16x32_bf16 v[124:127], v[154:157], v[186:189], v[124:127]
	v_mfma_f32_16x16x32_bf16 v[120:123], v[162:165], v[186:189], v[120:123]
	v_mfma_f32_16x16x32_bf16 v[108:111], v[154:157], v[194:197], v[108:111]
	v_mfma_f32_16x16x32_bf16 v[104:107], v[162:165], v[194:197], v[104:107]
	v_mfma_f32_16x16x32_bf16 v[92:95], v[154:157], v[202:205], v[92:95]
	v_mfma_f32_16x16x32_bf16 v[88:91], v[162:165], v[202:205], v[88:91]
	v_mfma_f32_16x16x32_bf16 v[76:79], v[154:157], v[210:213], v[76:79]
	v_mfma_f32_16x16x32_bf16 v[72:75], v[162:165], v[210:213], v[72:75]
	v_mfma_f32_16x16x32_bf16 v[124:127], v[158:161], v[190:193], v[124:127]
	v_mfma_f32_16x16x32_bf16 v[120:123], v[166:169], v[190:193], v[120:123]
	v_mfma_f32_16x16x32_bf16 v[108:111], v[158:161], v[198:201], v[108:111]
	v_mfma_f32_16x16x32_bf16 v[104:107], v[166:169], v[198:201], v[104:107]
	v_mfma_f32_16x16x32_bf16 v[92:95], v[158:161], v[206:209], v[92:95]
	v_mfma_f32_16x16x32_bf16 v[88:91], v[166:169], v[206:209], v[88:91]
	v_mfma_f32_16x16x32_bf16 v[76:79], v[158:161], v[214:217], v[76:79]
	v_mfma_f32_16x16x32_bf16 v[72:75], v[166:169], v[214:217], v[72:75]
	s_setprio 0
	s_setprio 1
	v_mfma_f32_16x16x32_bf16 v[116:119], v[170:173], v[186:189], v[116:119]
	v_mfma_f32_16x16x32_bf16 v[112:115], v[178:181], v[186:189], v[112:115]
	v_mfma_f32_16x16x32_bf16 v[100:103], v[170:173], v[194:197], v[100:103]
	v_mfma_f32_16x16x32_bf16 v[96:99], v[178:181], v[194:197], v[96:99]
	v_mfma_f32_16x16x32_bf16 v[84:87], v[170:173], v[202:205], v[84:87]
	v_mfma_f32_16x16x32_bf16 v[80:83], v[178:181], v[202:205], v[80:83]
	v_mfma_f32_16x16x32_bf16 v[68:71], v[170:173], v[210:213], v[68:71]
	v_mfma_f32_16x16x32_bf16 v[64:67], v[178:181], v[210:213], v[64:67]
	v_mfma_f32_16x16x32_bf16 v[116:119], v[174:177], v[190:193], v[116:119]
	v_mfma_f32_16x16x32_bf16 v[112:115], v[182:185], v[190:193], v[112:115]
	v_mfma_f32_16x16x32_bf16 v[100:103], v[174:177], v[198:201], v[100:103]
	v_mfma_f32_16x16x32_bf16 v[96:99], v[182:185], v[198:201], v[96:99]
	v_mfma_f32_16x16x32_bf16 v[84:87], v[174:177], v[206:209], v[84:87]
	v_mfma_f32_16x16x32_bf16 v[80:83], v[182:185], v[206:209], v[80:83]
	v_mfma_f32_16x16x32_bf16 v[68:71], v[174:177], v[214:217], v[68:71]
	v_mfma_f32_16x16x32_bf16 v[64:67], v[182:185], v[214:217], v[64:67]
	s_barrier
	s_setprio 0
	s_mov_b32 m0, s90
	v_lshl_add_u64 v[140:141], s[80:81], 0, v[128:129]
	s_add_u32 s44, s80, 0x20000
	ds_read_b128 v[186:189], v151 offset:16384
	ds_read_b128 v[190:193], v151 offset:17408
	ds_read_b128 v[194:197], v151 offset:18432
	ds_read_b128 v[198:201], v151 offset:19456
	ds_read_b128 v[202:205], v151 offset:20480
	ds_read_b128 v[206:209], v151 offset:21504
	ds_read_b128 v[210:213], v151 offset:22528
	ds_read_b128 v[214:217], v151 offset:23552
	global_load_lds_dwordx4 v128, s[80:81]
	v_lshl_add_u64 v[142:143], s[80:81], 0, v[130:131]
	s_mov_b32 m0, s91
	s_addc_u32 s45, s81, 0
	global_load_lds_dwordx4 v130, s[80:81]
	v_lshl_add_u64 v[146:147], s[44:45], 0, v[128:129]
	s_mov_b32 m0, s93
	v_lshl_add_u64 v[218:219], s[82:83], 0, v[132:133]
	global_load_lds_dwordx4 v128, s[44:45]
	v_lshl_add_u64 v[146:147], s[44:45], 0, v[130:131]
	s_mov_b32 m0, s95
	s_nop 0
	global_load_lds_dwordx4 v130, s[44:45]
	v_lshl_add_u64 v[146:147], s[82:83], 0, v[134:135]
	s_mov_b32 m0, s38
	s_nop 0
	global_load_lds_dwordx4 v134, s[82:83]
	s_mov_b32 m0, s39
	s_nop 0
	global_load_lds_dwordx4 v132, s[82:83]
	s_waitcnt vmcnt(8) lgkmcnt(0)
	s_setprio 1
	s_barrier
	v_mfma_f32_16x16x32_bf16 v[60:63], v[154:157], v[186:189], v[60:63]
	v_mfma_f32_16x16x32_bf16 v[56:59], v[162:165], v[186:189], v[56:59]
	v_mfma_f32_16x16x32_bf16 v[44:47], v[154:157], v[194:197], v[44:47]
	v_mfma_f32_16x16x32_bf16 v[40:43], v[162:165], v[194:197], v[40:43]
	v_mfma_f32_16x16x32_bf16 v[28:31], v[154:157], v[202:205], v[28:31]
	v_mfma_f32_16x16x32_bf16 v[24:27], v[162:165], v[202:205], v[24:27]
	v_mfma_f32_16x16x32_bf16 v[12:15], v[154:157], v[210:213], v[12:15]
	v_mfma_f32_16x16x32_bf16 v[8:11], v[162:165], v[210:213], v[8:11]
	v_mfma_f32_16x16x32_bf16 v[60:63], v[158:161], v[190:193], v[60:63]
	v_mfma_f32_16x16x32_bf16 v[56:59], v[166:169], v[190:193], v[56:59]
	v_mfma_f32_16x16x32_bf16 v[44:47], v[158:161], v[198:201], v[44:47]
	v_mfma_f32_16x16x32_bf16 v[40:43], v[166:169], v[198:201], v[40:43]
	v_mfma_f32_16x16x32_bf16 v[28:31], v[158:161], v[206:209], v[28:31]
	v_mfma_f32_16x16x32_bf16 v[24:27], v[166:169], v[206:209], v[24:27]
	v_mfma_f32_16x16x32_bf16 v[12:15], v[158:161], v[214:217], v[12:15]
	v_mfma_f32_16x16x32_bf16 v[8:11], v[166:169], v[214:217], v[8:11]
	s_setprio 0
	s_setprio 1
	v_mfma_f32_16x16x32_bf16 v[52:55], v[170:173], v[186:189], v[52:55]
	v_mfma_f32_16x16x32_bf16 v[48:51], v[178:181], v[186:189], v[48:51]
	v_mfma_f32_16x16x32_bf16 v[36:39], v[170:173], v[194:197], v[36:39]
	v_mfma_f32_16x16x32_bf16 v[32:35], v[178:181], v[194:197], v[32:35]
	v_mfma_f32_16x16x32_bf16 v[20:23], v[170:173], v[202:205], v[20:23]
	v_mfma_f32_16x16x32_bf16 v[16:19], v[178:181], v[202:205], v[16:19]
	v_mfma_f32_16x16x32_bf16 v[4:7], v[170:173], v[210:213], v[4:7]
	v_mfma_f32_16x16x32_bf16 v[0:3], v[178:181], v[210:213], v[0:3]
	v_mfma_f32_16x16x32_bf16 v[52:55], v[174:177], v[190:193], v[52:55]
	v_mfma_f32_16x16x32_bf16 v[48:51], v[182:185], v[190:193], v[48:51]
	v_mfma_f32_16x16x32_bf16 v[36:39], v[174:177], v[198:201], v[36:39]
	v_mfma_f32_16x16x32_bf16 v[32:35], v[182:185], v[198:201], v[32:35]
	v_mfma_f32_16x16x32_bf16 v[20:23], v[174:177], v[206:209], v[20:23]
	v_mfma_f32_16x16x32_bf16 v[16:19], v[182:185], v[206:209], v[16:19]
	v_mfma_f32_16x16x32_bf16 v[4:7], v[174:177], v[214:217], v[4:7]
	v_mfma_f32_16x16x32_bf16 v[0:3], v[182:185], v[214:217], v[0:3]
	s_barrier
; #define PG8_MMA(ai, bj, At, Bt) do { __builtin_amdgcn_s_setprio(1); _Pragma("unroll") for (int m = 0; m < 4; ++m) _Pragma("unroll") for (int n = 0; n < 2; ++n) _Pragma("unroll") for (int k = 0; k < 2; ++k) \
;         acc[ai][bj][m][n] = __builtin_amdgcn_mfma_f32_16x16x32_bf16(Bt[n][k], At[m][k], acc[ai][bj][m][n], 0, 0, 0); __builtin_amdgcn_s_setprio(0); } while (0)
; template <class Epi, class Sched, bool ALIGN_EPI = false, bool SP2 = false, bool A_TILED = false>
; __device__ __forceinline__ void gemm_phase(PG8_LAS unsigned char* lds, const Gemm g, const Sched& S, const Epi& E, const int wave_s) {
;     ...
;         for (int t = PEEL ? 2 : 0; t < nt; t += 2) {
;             const bool last = (t == nt - 2);
;             const char* a1 = cA + (size_t)(t + 1) * kstepA;
;             const char* a2 = last ? nA : cA + (size_t)(t + 2) * kstepA; const char* b2 = last ? nB : cB + (size_t)(t + 2) * kstep;
;             const char* a3 = a2 + kstepA; const char* b3 = b2 + kstep;
;             if (last && has_next) S.a_ready(nxt);
;             if constexpr (SP2) {
;             PG8_ITER(PG8_MMA)
	s_setprio 0
	ds_read_b128 v[154:157], v144
	ds_read_b128 v[158:161], v144 offset:1024
	ds_read_b128 v[162:165], v144 offset:2048
	ds_read_b128 v[166:169], v144 offset:3072
	ds_read_b128 v[170:173], v145
	ds_read_b128 v[174:177], v145 offset:1024
	ds_read_b128 v[178:181], v145 offset:2048
	ds_read_b128 v[182:185], v145 offset:3072
	s_add_u32 s44, s82, 0x20000
	s_addc_u32 s45, s83, 0
	s_mov_b32 m0, s40
	v_lshl_add_u64 v[220:221], s[44:45], 0, v[134:135]
	ds_read_b128 v[186:189], v151 offset:32768
	ds_read_b128 v[190:193], v151 offset:33792
	ds_read_b128 v[194:197], v151 offset:34816
	ds_read_b128 v[198:201], v151 offset:35840
	ds_read_b128 v[202:205], v151 offset:36864
	ds_read_b128 v[206:209], v151 offset:37888
	ds_read_b128 v[210:213], v151 offset:38912
	ds_read_b128 v[214:217], v151 offset:39936
	global_load_lds_dwordx4 v134, s[44:45]
	v_lshl_add_u64 v[220:221], s[44:45], 0, v[132:133]
	s_mov_b32 m0, s41
	s_nop 0
	global_load_lds_dwordx4 v132, s[44:45]
	s_waitcnt vmcnt(8) lgkmcnt(0)
	s_setprio 1
	s_barrier
	v_mfma_f32_16x16x32_bf16 v[124:127], v[154:157], v[186:189], v[124:127]
	v_mfma_f32_16x16x32_bf16 v[120:123], v[162:165], v[186:189], v[120:123]
	v_mfma_f32_16x16x32_bf16 v[108:111], v[154:157], v[194:197], v[108:111]
	v_mfma_f32_16x16x32_bf16 v[104:107], v[162:165], v[194:197], v[104:107]
	v_mfma_f32_16x16x32_bf16 v[92:95], v[154:157], v[202:205], v[92:95]
	v_mfma_f32_16x16x32_bf16 v[88:91], v[162:165], v[202:205], v[88:91]
	v_mfma_f32_16x16x32_bf16 v[76:79], v[154:157], v[210:213], v[76:79]
	v_mfma_f32_16x16x32_bf16 v[72:75], v[162:165], v[210:213], v[72:75]
	v_mfma_f32_16x16x32_bf16 v[124:127], v[158:161], v[190:193], v[124:127]
	v_mfma_f32_16x16x32_bf16 v[120:123], v[166:169], v[190:193], v[120:123]
	v_mfma_f32_16x16x32_bf16 v[108:111], v[158:161], v[198:201], v[108:111]
	v_mfma_f32_16x16x32_bf16 v[104:107], v[166:169], v[198:201], v[104:107]
	v_mfma_f32_16x16x32_bf16 v[92:95], v[158:161], v[206:209], v[92:95]
	v_mfma_f32_16x16x32_bf16 v[88:91], v[166:169], v[206:209], v[88:91]
	v_mfma_f32_16x16x32_bf16 v[76:79], v[158:161], v[214:217], v[76:79]
	v_mfma_f32_16x16x32_bf16 v[72:75], v[166:169], v[214:217], v[72:75]
	s_setprio 0
	s_setprio 1
	v_mfma_f32_16x16x32_bf16 v[116:119], v[170:173], v[186:189], v[116:119]
	v_mfma_f32_16x16x32_bf16 v[112:115], v[178:181], v[186:189], v[112:115]
	v_mfma_f32_16x16x32_bf16 v[100:103], v[170:173], v[194:197], v[100:103]
	v_mfma_f32_16x16x32_bf16 v[96:99], v[178:181], v[194:197], v[96:99]
	v_mfma_f32_16x16x32_bf16 v[84:87], v[170:173], v[202:205], v[84:87]
	v_mfma_f32_16x16x32_bf16 v[80:83], v[178:181], v[202:205], v[80:83]
	v_mfma_f32_16x16x32_bf16 v[68:71], v[170:173], v[210:213], v[68:71]
	v_mfma_f32_16x16x32_bf16 v[64:67], v[178:181], v[210:213], v[64:67]
	v_mfma_f32_16x16x32_bf16 v[116:119], v[174:177], v[190:193], v[116:119]
	v_mfma_f32_16x16x32_bf16 v[112:115], v[182:185], v[190:193], v[112:115]
	v_mfma_f32_16x16x32_bf16 v[100:103], v[174:177], v[198:201], v[100:103]
	v_mfma_f32_16x16x32_bf16 v[96:99], v[182:185], v[198:201], v[96:99]
	v_mfma_f32_16x16x32_bf16 v[84:87], v[174:177], v[206:209], v[84:87]
	v_mfma_f32_16x16x32_bf16 v[80:83], v[182:185], v[206:209], v[80:83]
	v_mfma_f32_16x16x32_bf16 v[68:71], v[174:177], v[214:217], v[68:71]
	v_mfma_f32_16x16x32_bf16 v[64:67], v[182:185], v[214:217], v[64:67]
	s_barrier
	s_setprio 0
	s_mov_b32 m0, s96
	v_lshl_add_u64 v[140:141], v[140:141], 0, s[62:63]
	s_add_u32 s44, s80, 0x20080
	ds_read_b128 v[186:189], v151 offset:49152
	ds_read_b128 v[190:193], v151 offset:50176
	ds_read_b128 v[194:197], v151 offset:51200
	ds_read_b128 v[198:201], v151 offset:52224
	ds_read_b128 v[202:205], v151 offset:53248
	ds_read_b128 v[206:209], v151 offset:54272
	ds_read_b128 v[210:213], v151 offset:55296
	ds_read_b128 v[214:217], v151 offset:56320
	global_load_lds_dwordx4 v[140:141], off
	v_lshl_add_u64 v[140:141], v[142:143], 0, s[62:63]
	s_mov_b32 m0, s97
	s_addc_u32 s45, s81, 0
	global_load_lds_dwordx4 v[140:141], off
	v_lshl_add_u64 v[140:141], s[44:45], 0, v[128:129]
	s_mov_b32 m0, vcc_lo
	s_nop 0
	global_load_lds_dwordx4 v128, s[44:45]
	v_lshl_add_u64 v[140:141], s[44:45], 0, v[130:131]
	s_mov_b32 m0, vcc_hi
	s_nop 0
	global_load_lds_dwordx4 v130, s[44:45]
	v_lshl_add_u64 v[140:141], v[146:147], 0, s[62:63]
	s_mov_b32 m0, s51
	s_nop 0
	global_load_lds_dwordx4 v[140:141], off
	v_lshl_add_u64 v[140:141], v[218:219], 0, s[62:63]
	s_mov_b32 m0, s52
	s_nop 0
	global_load_lds_dwordx4 v[140:141], off
	s_waitcnt vmcnt(8) lgkmcnt(0)
	s_setprio 1
	s_barrier
	v_mfma_f32_16x16x32_bf16 v[60:63], v[154:157], v[186:189], v[60:63]
	v_mfma_f32_16x16x32_bf16 v[56:59], v[162:165], v[186:189], v[56:59]
	v_mfma_f32_16x16x32_bf16 v[44:47], v[154:157], v[194:197], v[44:47]
	v_mfma_f32_16x16x32_bf16 v[40:43], v[162:165], v[194:197], v[40:43]
	v_mfma_f32_16x16x32_bf16 v[28:31], v[154:157], v[202:205], v[28:31]
	v_mfma_f32_16x16x32_bf16 v[24:27], v[162:165], v[202:205], v[24:27]
	v_mfma_f32_16x16x32_bf16 v[12:15], v[154:157], v[210:213], v[12:15]
	v_mfma_f32_16x16x32_bf16 v[8:11], v[162:165], v[210:213], v[8:11]
	v_mfma_f32_16x16x32_bf16 v[60:63], v[158:161], v[190:193], v[60:63]
	v_mfma_f32_16x16x32_bf16 v[56:59], v[166:169], v[190:193], v[56:59]
	v_mfma_f32_16x16x32_bf16 v[44:47], v[158:161], v[198:201], v[44:47]
	v_mfma_f32_16x16x32_bf16 v[40:43], v[166:169], v[198:201], v[40:43]
	v_mfma_f32_16x16x32_bf16 v[28:31], v[158:161], v[206:209], v[28:31]
	v_mfma_f32_16x16x32_bf16 v[24:27], v[166:169], v[206:209], v[24:27]
	v_mfma_f32_16x16x32_bf16 v[12:15], v[158:161], v[214:217], v[12:15]
	v_mfma_f32_16x16x32_bf16 v[8:11], v[166:169], v[214:217], v[8:11]
	s_setprio 0
	s_setprio 1
	v_mfma_f32_16x16x32_bf16 v[52:55], v[170:173], v[186:189], v[52:55]
	v_mfma_f32_16x16x32_bf16 v[48:51], v[178:181], v[186:189], v[48:51]
	v_mfma_f32_16x16x32_bf16 v[36:39], v[170:173], v[194:197], v[36:39]
	v_mfma_f32_16x16x32_bf16 v[32:35], v[178:181], v[194:197], v[32:35]
	v_mfma_f32_16x16x32_bf16 v[20:23], v[170:173], v[202:205], v[20:23]
	v_mfma_f32_16x16x32_bf16 v[16:19], v[178:181], v[202:205], v[16:19]
	v_mfma_f32_16x16x32_bf16 v[4:7], v[170:173], v[210:213], v[4:7]
	v_mfma_f32_16x16x32_bf16 v[0:3], v[178:181], v[210:213], v[0:3]
	v_mfma_f32_16x16x32_bf16 v[52:55], v[174:177], v[190:193], v[52:55]
	v_mfma_f32_16x16x32_bf16 v[48:51], v[182:185], v[190:193], v[48:51]
	v_mfma_f32_16x16x32_bf16 v[36:39], v[174:177], v[198:201], v[36:39]
	v_mfma_f32_16x16x32_bf16 v[32:35], v[182:185], v[198:201], v[32:35]
	v_mfma_f32_16x16x32_bf16 v[20:23], v[174:177], v[206:209], v[20:23]
	v_mfma_f32_16x16x32_bf16 v[16:19], v[182:185], v[206:209], v[16:19]
	v_mfma_f32_16x16x32_bf16 v[4:7], v[174:177], v[214:217], v[4:7]
	v_mfma_f32_16x16x32_bf16 v[0:3], v[182:185], v[214:217], v[0:3]
	s_barrier
	s_setprio 0
	s_add_i32 s94, s94, 2
	s_add_u32 s85, s85, 0x100
	s_addc_u32 s8, s8, 0
	s_add_u32 s78, s78, 0x100
	s_addc_u32 s79, s79, 0
	s_cmp_gt_u32 s94, 5
	s_cbranch_scc0 .LBB0_2546
	s_and_b64 vcc, exec, s[64:65]
	s_cbranch_vccz .LBB0_2549
	s_barrier

; #define PG8_STAGE(bufoff, gbase, voff) do { _Pragma("unroll") for (int _i = 0; _i < 2; ++_i) \
;         __builtin_amdgcn_global_load_lds((const unsigned*)((const char*)(gbase) + (voff)[_i]), (PG8_LAS unsigned*)(lds + (bufoff) + ldsw + _i * 8192), 16, 0, 0); } while (0)
; #define PG8_WAIT_V(n) asm volatile("s_waitcnt vmcnt(" #n ")" ::: "memory")
; #define PG8_BAR __builtin_amdgcn_s_barrier()
; template <class Epi, class Sched, bool ALIGN_EPI = false, bool SP2 = false, bool A_TILED = false>
; __device__ __forceinline__ void gemm_phase(PG8_LAS unsigned char* lds, const Gemm g, const Sched& S, const Epi& E, const int wave_s) {
;     ...
;     unsigned voffA[2], voffB[2];
; #pragma unroll
;     for (int i = 0; i < 2; ++i) { int R, C; stage_rc(tid * 16 + i * 8192, R, C); const int Rb = Epi::PERM ? ((R & ~31) + perm32(R & 31)) : R;
;         voffA[i] = A_TILED ? (unsigned)(tid * 16 + i * 8192) : (unsigned)(R * K + C) * 2u; voffB[i] = (unsigned)(Rb * K + C) * 2u; }
;     const size_t kstep = (size_t)(BK * 2);
;     const size_t hstep = (size_t)HALF * K * 2;
;     const size_t tstep = 2 * hstep;
;     const size_t kstepA = A_TILED ? (size_t)32768 : kstep, hstepA = A_TILED ? (size_t)16384 : hstep, tstepA = A_TILED ? (size_t)nt * 32768 : tstep;
;     const unsigned ldsw = (unsigned)wid * 1024u;
;     const int aoff = lds_byte(wr * 64 + fr, fq * 8), boff = lds_byte(wc * 32 + fr, fq * 8);
;     ...
;     if constexpr (SP2) {
;         PG8_STAGE(PG8_SB(0, 0), cB, voffB); PG8_STAGE(PG8_SB(0, 1), cB + hstep, voffB); PG8_STAGE(PG8_SA(0, 0), cA, voffA); PG8_STAGE(PG8_SA(0, 1), cA + hstepA, voffA);
;         if (wr == 1) PG8_BAR;
;         PG8_WAIT_V(2); PG8_BAR;
;         PG8_STAGE(PG8_SB(1, 0), cB + kstep, voffB); PG8_STAGE(PG8_SA(1, 0), cA + kstepA, voffA); PG8_STAGE(PG8_SB(1, 1), cB + hstep + kstep, voffB);
;         PG8_WAIT_V(6); PG8_BAR;
;     } else {
;         PG8_STAGE(PG8_SB(0, 0), cB, voffB); PG8_STAGE(PG8_SA(0, 0), cA, voffA); PG8_STAGE(PG8_SB(0, 1), cB + hstep, voffB); PG8_STAGE(PG8_SA(0, 1), cA + hstepA, voffA);
;         if (wr == 1) PG8_BAR;
;         PG8_WAIT_V(4); PG8_BAR;
;         PG8_STAGE(PG8_SB(1, 0), cB + kstep, voffB); PG8_STAGE(PG8_SA(1, 0), cA + kstepA, voffA); PG8_STAGE(PG8_SB(1, 1), cB + hstep + kstep, voffB);
;         PG8_WAIT_V(6); PG8_BAR;
.LBB0_2556:
	s_mul_i32 s40, s96, 0x7000000
	s_add_u32 s12, s12, s40
	s_addc_u32 s13, s13, 0
	s_add_u32 s12, s12, 0x25e00000
	s_addc_u32 s13, s13, 0
	s_lshl_b32 s41, s41, 5
	s_mov_b64 s[44:45], 0x80
	s_and_b32 s41, s41, 0x60
	s_add_i32 m0, s0, 0x18000
	v_lshl_add_u64 v[6:7], v[6:7], 0, s[44:45]
	s_lshl_b32 s40, s42, 6
	s_lshl_b32 s48, s42, 13
	s_lshl_b32 s49, s41, 7
	s_waitcnt vmcnt(2)
	s_barrier
	global_load_lds_dwordx4 v[6:7], off
	v_lshl_add_u64 v[4:5], v[4:5], 0, s[44:45]
	s_add_i32 m0, s0, 0x1a000
	s_add_i32 s42, s0, 0x8000
	s_add_i32 s43, s0, 0xa000
	global_load_lds_dwordx4 v[4:5], off
	v_lshl_add_u64 v[0:1], v[0:1], 0, s[44:45]
	s_mov_b32 m0, s42
	s_add_u32 s46, s74, 0x20080
	global_load_lds_dwordx4 v[0:1], off
	v_lshl_add_u64 v[0:1], v[2:3], 0, s[44:45]
	s_mov_b32 m0, s43
	s_addc_u32 s47, s75, 0
	global_load_lds_dwordx4 v[0:1], off
	s_add_i32 m0, s0, 0x1c000
	v_lshl_add_u64 v[0:1], s[46:47], 0, v[128:129]
	global_load_lds_dwordx4 v128, s[46:47]
	v_lshl_add_u64 v[0:1], s[46:47], 0, v[130:131]
	s_add_i32 m0, s0, 0x1e000
	s_sext_i32_i8 s50, s2
	global_load_lds_dwordx4 v130, s[46:47]
	v_and_b32_e32 v0, 48, v10
	v_lshlrev_b32_e32 v1, 6, v10
	s_movk_i32 s2, 0x3c0
	v_and_or_b32 v0, v1, s2, v0
	v_lshlrev_b32_e32 v1, 2, v10
	v_and_b32_e32 v1, 32, v1
	v_bitop3_b32 v2, v0, s48, v1 bitop3:0xde
	v_bitop3_b32 v146, s49, v0, v1 bitop3:0xf6
	v_lshlrev_b32_e32 v0, 13, v8
	v_and_b32_e32 v0, 0xffffc000, v0
	v_lshl_add_u32 v0, v9, 10, v0
	v_and_b32_e32 v1, 1, v8
	v_lshl_or_b32 v0, v1, 6, v0
	v_lshl_add_u32 v136, v11, 1, v0
	v_lshlrev_b32_e32 v0, 13, v13
	v_and_b32_e32 v0, 0xffffc000, v0
	s_waitcnt vmcnt(6)
	s_cmpk_lt_u32 s3, 0x100
	v_lshl_add_u32 v0, v12, 10, v0
	v_and_b32_e32 v1, 1, v13
	s_cselect_b64 s[46:47], -1, 0
	v_mov_b32_e32 v137, 0
	v_lshl_or_b32 v0, v1, 6, v0
	s_add_i32 s48, 0, 0x10000
	s_add_i32 s49, 0, 0x14000
	v_lshl_add_u32 v138, v14, 1, v0
	v_mov_b32_e32 v139, v137
	s_mov_b64 s[60:61], 0x100
	v_add_u32_e32 v147, s48, v146
	v_add_u32_e32 v148, s49, v146
	v_add_u32_e32 v149, 0, v2
	s_mov_b64 s[62:63], 0x180
	s_barrier
	s_branch .LBB0_2559

; template <class Epi, class Sched, bool ALIGN_EPI = false, bool SP2 = false, bool A_TILED = false>
; __device__ __forceinline__ void gemm_phase(PG8_LAS unsigned char* lds, const Gemm g, const Sched& S, const Epi& E, const int wave_s) {
;     ...
;         const bool has_next = Epi::AFTER_DRAIN ? false : S.next(ui + 1, nxt);
;         const char* nA = has_next ? (const char*)g.A + (size_t)nxt.pm * tstepA : cA; const char* nB = has_next ? (const char*)g.Bt + (size_t)nxt.pn * tstep : cB;
;         constexpr bool PEEL = SP2 && !Epi::AFTER_DRAIN;
;         if constexpr (PEEL) {
;             const char* a1 = cA + kstepA; const char* a2 = cA + 2 * kstepA; const char* b2 = cB + 2 * kstep; const char* a3 = a2 + kstepA; const char* b3 = b2 + kstep;
;             PG8_ITER(PG8_MMAZ)
.LBB0_2565:
	s_ashr_i32 s67, s66, 31
	ds_read_b128 v[0:3], v147
	ds_read_b128 v[4:7], v147 offset:1024
	ds_read_b128 v[8:11], v147 offset:2048
	ds_read_b128 v[12:15], v147 offset:3072
	ds_read_b128 v[16:19], v148
	ds_read_b128 v[20:23], v148 offset:1024
	ds_read_b128 v[24:27], v148 offset:2048
	ds_read_b128 v[28:31], v148 offset:3072
	s_lshl_b64 s[52:53], s[66:67], 18
	s_add_u32 s68, s8, s52
	s_addc_u32 s69, s14, s53
	s_and_b64 s[52:53], s[2:3], exec
	s_cselect_b32 s51, s69, s77
	s_cselect_b32 s52, s68, s76
	s_ashr_i32 s65, s64, 31
	s_lshl_b64 s[54:55], s[64:65], 18
	s_add_u32 s72, s15, s54
	s_addc_u32 s73, s23, s55
	s_and_b64 s[54:55], s[2:3], exec
	s_cselect_b32 s53, s73, s75
	s_cselect_b32 s54, s72, s74
	s_add_u32 s56, s76, 0x20080
	s_addc_u32 s57, s77, 0
	s_add_i32 s55, s0, 0xc000
	v_lshl_add_u64 v[64:65], s[56:57], 0, v[134:135]
	s_mov_b32 m0, s55
	ds_read_b128 v[32:35], v149
	ds_read_b128 v[36:39], v149 offset:1024
	ds_read_b128 v[40:43], v149 offset:2048
	ds_read_b128 v[44:47], v149 offset:3072
	ds_read_b128 v[48:51], v149 offset:4096
	ds_read_b128 v[52:55], v149 offset:5120
	ds_read_b128 v[56:59], v149 offset:6144
	ds_read_b128 v[60:63], v149 offset:7168
	global_load_lds_dwordx4 v134, s[56:57]
	v_lshl_add_u64 v[64:65], s[56:57], 0, v[132:133]
	s_add_i32 s56, s0, 0xe000
	s_mov_b32 m0, s56
	s_nop 0
	global_load_lds_dwordx4 v[64:65], off
	s_waitcnt vmcnt(8) lgkmcnt(0)
	s_setprio 1
	s_barrier
	v_mfma_f32_16x16x32_bf16 v[88:91], v[0:3], v[56:59], 0
	v_mfma_f32_16x16x32_bf16 v[64:67], v[0:3], v[32:35], 0
	v_mfma_f32_16x16x32_bf16 v[68:71], v[8:11], v[32:35], 0
	v_mfma_f32_16x16x32_bf16 v[72:75], v[0:3], v[40:43], 0
	v_mfma_f32_16x16x32_bf16 v[76:79], v[8:11], v[40:43], 0
	v_mfma_f32_16x16x32_bf16 v[80:83], v[0:3], v[48:51], 0
	v_mfma_f32_16x16x32_bf16 v[84:87], v[8:11], v[48:51], 0
	v_mfma_f32_16x16x32_bf16 v[92:95], v[4:7], v[60:63], v[88:91]
	v_mfma_f32_16x16x32_bf16 v[88:91], v[8:11], v[56:59], 0
	v_mfma_f32_16x16x32_bf16 v[64:67], v[4:7], v[36:39], v[64:67]
	v_mfma_f32_16x16x32_bf16 v[68:71], v[12:15], v[36:39], v[68:71]
	v_mfma_f32_16x16x32_bf16 v[72:75], v[4:7], v[44:47], v[72:75]
	v_mfma_f32_16x16x32_bf16 v[76:79], v[12:15], v[44:47], v[76:79]
	v_mfma_f32_16x16x32_bf16 v[80:83], v[4:7], v[52:55], v[80:83]
	v_mfma_f32_16x16x32_bf16 v[84:87], v[12:15], v[52:55], v[84:87]
	v_mfma_f32_16x16x32_bf16 v[100:103], v[12:15], v[60:63], v[88:91]
	s_setprio 0
	s_setprio 1
	v_mfma_f32_16x16x32_bf16 v[88:91], v[16:19], v[32:35], 0
	v_mfma_f32_16x16x32_bf16 v[32:35], v[24:27], v[32:35], 0
	v_mfma_f32_16x16x32_bf16 v[108:111], v[20:23], v[36:39], v[88:91]
	v_mfma_f32_16x16x32_bf16 v[32:35], v[28:31], v[36:39], v[32:35]
	v_mfma_f32_16x16x32_bf16 v[36:39], v[16:19], v[40:43], 0
	v_mfma_f32_16x16x32_bf16 v[40:43], v[24:27], v[40:43], 0
	v_mfma_f32_16x16x32_bf16 v[36:39], v[20:23], v[44:47], v[36:39]
	v_mfma_f32_16x16x32_bf16 v[40:43], v[28:31], v[44:47], v[40:43]
	v_mfma_f32_16x16x32_bf16 v[44:47], v[16:19], v[48:51], 0
	v_mfma_f32_16x16x32_bf16 v[48:51], v[24:27], v[48:51], 0
	v_mfma_f32_16x16x32_bf16 v[44:47], v[20:23], v[52:55], v[44:47]
	v_mfma_f32_16x16x32_bf16 v[52:55], v[28:31], v[52:55], v[48:51]
	v_mfma_f32_16x16x32_bf16 v[48:51], v[16:19], v[56:59], 0
	v_mfma_f32_16x16x32_bf16 v[150:153], v[20:23], v[60:63], v[48:51]
	v_mfma_f32_16x16x32_bf16 v[48:51], v[24:27], v[56:59], 0
	v_mfma_f32_16x16x32_bf16 v[154:157], v[28:31], v[60:63], v[48:51]
	s_barrier
	s_setprio 0
	s_add_i32 s57, s48, s36
	v_lshl_add_u64 v[250:251], s[74:75], 0, v[128:129]
	s_add_i32 s58, s57, 0x2000
	v_lshl_add_u64 v[120:121], v[250:251], 0, s[60:61]
	s_mov_b32 m0, s57
	v_lshl_add_u64 v[252:253], s[74:75], 0, v[130:131]
	s_add_u32 s78, s74, 0x20100
	ds_read_b128 v[48:51], v149 offset:16384
	ds_read_b128 v[56:59], v149 offset:17408
	ds_read_b128 v[60:63], v149 offset:18432
	ds_read_b128 v[88:91], v149 offset:19456
	ds_read_b128 v[96:99], v149 offset:20480
	ds_read_b128 v[104:107], v149 offset:21504
	ds_read_b128 v[112:115], v149 offset:22528
	ds_read_b128 v[116:119], v149 offset:23552
	global_load_lds_dwordx4 v[120:121], off
	v_lshl_add_u64 v[120:121], v[252:253], 0, s[60:61]
	s_mov_b32 m0, s58
	s_addc_u32 s79, s75, 0
	s_add_i32 s59, s49, s36
	global_load_lds_dwordx4 v[120:121], off
	v_lshl_add_u64 v[120:121], s[78:79], 0, v[128:129]
	s_mov_b32 m0, s59
	s_add_i32 s65, s59, 0x2000
	global_load_lds_dwordx4 v128, s[78:79]
	v_lshl_add_u64 v[120:121], s[78:79], 0, v[130:131]
	s_mov_b32 m0, s65
	v_lshl_add_u64 v[140:141], s[76:77], 0, v[134:135]
	global_load_lds_dwordx4 v130, s[78:79]
	v_lshl_add_u64 v[120:121], v[140:141], 0, s[60:61]
	s_mov_b32 m0, s0
	v_lshl_add_u64 v[142:143], s[76:77], 0, v[132:133]
	global_load_lds_dwordx4 v[120:121], off
	v_lshl_add_u64 v[120:121], v[142:143], 0, s[60:61]
	s_mov_b32 m0, s1
	s_nop 0
	global_load_lds_dwordx4 v[120:121], off
	s_waitcnt vmcnt(8) lgkmcnt(0)
	s_setprio 1
	s_barrier
	v_mfma_f32_16x16x32_bf16 v[120:123], v[0:3], v[48:51], 0
	v_mfma_f32_16x16x32_bf16 v[158:161], v[4:7], v[56:59], v[120:123]
	v_mfma_f32_16x16x32_bf16 v[120:123], v[8:11], v[48:51], 0
	v_mfma_f32_16x16x32_bf16 v[162:165], v[12:15], v[56:59], v[120:123]
	v_mfma_f32_16x16x32_bf16 v[120:123], v[0:3], v[60:63], 0
	v_mfma_f32_16x16x32_bf16 v[166:169], v[4:7], v[88:91], v[120:123]
	v_mfma_f32_16x16x32_bf16 v[120:123], v[8:11], v[60:63], 0
	v_mfma_f32_16x16x32_bf16 v[170:173], v[12:15], v[88:91], v[120:123]
	v_mfma_f32_16x16x32_bf16 v[120:123], v[0:3], v[96:99], 0
	v_mfma_f32_16x16x32_bf16 v[0:3], v[0:3], v[112:115], 0
	v_mfma_f32_16x16x32_bf16 v[174:177], v[4:7], v[104:107], v[120:123]
	v_mfma_f32_16x16x32_bf16 v[0:3], v[4:7], v[116:119], v[0:3]
	v_mfma_f32_16x16x32_bf16 v[4:7], v[8:11], v[112:115], 0
	v_mfma_f32_16x16x32_bf16 v[120:123], v[8:11], v[96:99], 0
	v_mfma_f32_16x16x32_bf16 v[4:7], v[12:15], v[116:119], v[4:7]
	v_mfma_f32_16x16x32_bf16 v[178:181], v[12:15], v[104:107], v[120:123]
	s_setprio 0
	s_setprio 1
	v_mfma_f32_16x16x32_bf16 v[8:11], v[16:19], v[48:51], 0
	v_mfma_f32_16x16x32_bf16 v[182:185], v[20:23], v[56:59], v[8:11]
	v_mfma_f32_16x16x32_bf16 v[8:11], v[24:27], v[48:51], 0
	v_mfma_f32_16x16x32_bf16 v[186:189], v[28:31], v[56:59], v[8:11]
	v_mfma_f32_16x16x32_bf16 v[8:11], v[16:19], v[60:63], 0
	v_mfma_f32_16x16x32_bf16 v[190:193], v[20:23], v[88:91], v[8:11]
	v_mfma_f32_16x16x32_bf16 v[8:11], v[24:27], v[60:63], 0
	v_mfma_f32_16x16x32_bf16 v[194:197], v[28:31], v[88:91], v[8:11]
	v_mfma_f32_16x16x32_bf16 v[8:11], v[16:19], v[96:99], 0
	v_mfma_f32_16x16x32_bf16 v[198:201], v[20:23], v[104:107], v[8:11]
	v_mfma_f32_16x16x32_bf16 v[8:11], v[24:27], v[96:99], 0
	v_mfma_f32_16x16x32_bf16 v[202:205], v[28:31], v[104:107], v[8:11]
	v_mfma_f32_16x16x32_bf16 v[8:11], v[16:19], v[112:115], 0
	v_mfma_f32_16x16x32_bf16 v[206:209], v[20:23], v[116:119], v[8:11]
	v_mfma_f32_16x16x32_bf16 v[8:11], v[24:27], v[112:115], 0
	v_mfma_f32_16x16x32_bf16 v[210:213], v[28:31], v[116:119], v[8:11]
	s_barrier
	s_setprio 0
	s_add_i32 s67, 0, 0x18000
	s_add_i32 s80, 0, 0x1c000
	v_add_u32_e32 v144, s67, v146
	v_add_u32_e32 v145, s80, v146
	s_nop 0
	ds_read_b128 v[8:11], v144
	ds_read_b128 v[12:15], v144 offset:1024
	ds_read_b128 v[16:19], v144 offset:2048
	ds_read_b128 v[20:23], v144 offset:3072
	ds_read_b128 v[214:217], v145
	ds_read_b128 v[218:221], v145 offset:1024
	ds_read_b128 v[222:225], v145 offset:2048
	ds_read_b128 v[226:229], v145 offset:3072
	s_add_u32 s78, s76, 0x20100
	s_addc_u32 s79, s77, 0
	s_mov_b32 m0, s37
	v_lshl_add_u64 v[48:49], s[78:79], 0, v[134:135]
	ds_read_b128 v[24:27], v149 offset:32768
	ds_read_b128 v[28:31], v149 offset:33792
	ds_read_b128 v[60:63], v149 offset:34816
	ds_read_b128 v[230:233], v149 offset:35840
	ds_read_b128 v[234:237], v149 offset:36864
	ds_read_b128 v[238:241], v149 offset:37888
	ds_read_b128 v[242:245], v149 offset:38912
	ds_read_b128 v[246:249], v149 offset:39936
	global_load_lds_dwordx4 v134, s[78:79]
	v_lshl_add_u64 v[48:49], s[78:79], 0, v[132:133]
	s_mov_b32 m0, s38
	s_nop 0
	global_load_lds_dwordx4 v132, s[78:79]
	s_waitcnt vmcnt(8) lgkmcnt(0)
	s_setprio 1
	s_barrier
	v_mfma_f32_16x16x32_bf16 v[48:51], v[8:11], v[24:27], v[64:67]
	v_mfma_f32_16x16x32_bf16 v[120:123], v[12:15], v[28:31], v[48:51]
	v_mfma_f32_16x16x32_bf16 v[48:51], v[16:19], v[24:27], v[68:71]
	v_mfma_f32_16x16x32_bf16 v[112:115], v[20:23], v[28:31], v[48:51]
	v_mfma_f32_16x16x32_bf16 v[48:51], v[8:11], v[60:63], v[72:75]
	v_mfma_f32_16x16x32_bf16 v[104:107], v[12:15], v[230:233], v[48:51]
	v_mfma_f32_16x16x32_bf16 v[48:51], v[16:19], v[60:63], v[76:79]
	v_mfma_f32_16x16x32_bf16 v[96:99], v[20:23], v[230:233], v[48:51]
	v_mfma_f32_16x16x32_bf16 v[48:51], v[8:11], v[234:237], v[80:83]
	v_mfma_f32_16x16x32_bf16 v[88:91], v[12:15], v[238:241], v[48:51]
	v_mfma_f32_16x16x32_bf16 v[48:51], v[16:19], v[234:237], v[84:87]
	v_mfma_f32_16x16x32_bf16 v[80:83], v[20:23], v[238:241], v[48:51]
	v_mfma_f32_16x16x32_bf16 v[48:51], v[8:11], v[242:245], v[92:95]
	v_mfma_f32_16x16x32_bf16 v[56:59], v[12:15], v[246:249], v[48:51]
	v_mfma_f32_16x16x32_bf16 v[48:51], v[16:19], v[242:245], v[100:103]
	v_mfma_f32_16x16x32_bf16 v[48:51], v[20:23], v[246:249], v[48:51]
	s_setprio 0
	s_setprio 1
	v_mfma_f32_16x16x32_bf16 v[64:67], v[214:217], v[24:27], v[108:111]
	v_mfma_f32_16x16x32_bf16 v[24:27], v[222:225], v[24:27], v[32:35]
	v_mfma_f32_16x16x32_bf16 v[116:119], v[226:229], v[28:31], v[24:27]
	v_mfma_f32_16x16x32_bf16 v[24:27], v[214:217], v[60:63], v[36:39]
	v_mfma_f32_16x16x32_bf16 v[108:111], v[218:221], v[230:233], v[24:27]
	v_mfma_f32_16x16x32_bf16 v[24:27], v[222:225], v[60:63], v[40:43]
	v_mfma_f32_16x16x32_bf16 v[100:103], v[226:229], v[230:233], v[24:27]
	v_mfma_f32_16x16x32_bf16 v[24:27], v[214:217], v[234:237], v[44:47]
	v_mfma_f32_16x16x32_bf16 v[92:95], v[218:221], v[238:241], v[24:27]
	v_mfma_f32_16x16x32_bf16 v[24:27], v[222:225], v[234:237], v[52:55]
	v_mfma_f32_16x16x32_bf16 v[84:87], v[226:229], v[238:241], v[24:27]
	v_mfma_f32_16x16x32_bf16 v[24:27], v[214:217], v[242:245], v[150:153]
	v_mfma_f32_16x16x32_bf16 v[60:63], v[218:221], v[246:249], v[24:27]
	v_mfma_f32_16x16x32_bf16 v[24:27], v[222:225], v[242:245], v[154:157]
	v_mfma_f32_16x16x32_bf16 v[124:127], v[218:221], v[28:31], v[64:67]
	v_mfma_f32_16x16x32_bf16 v[52:55], v[226:229], v[246:249], v[24:27]
	s_barrier
; #define PG8_MMA(ai, bj, At, Bt) do { __builtin_amdgcn_s_setprio(1); _Pragma("unroll") for (int m = 0; m < 4; ++m) _Pragma("unroll") for (int n = 0; n < 2; ++n) _Pragma("unroll") for (int k = 0; k < 2; ++k) \
;         acc[ai][bj][m][n] = __builtin_amdgcn_mfma_f32_16x16x32_bf16(Bt[n][k], At[m][k], acc[ai][bj][m][n], 0, 0, 0); __builtin_amdgcn_s_setprio(0); } while (0)
; template <class Epi, class Sched, bool ALIGN_EPI = false, bool SP2 = false, bool A_TILED = false>
; __device__ __forceinline__ void gemm_phase(PG8_LAS unsigned char* lds, const Gemm g, const Sched& S, const Epi& E, const int wave_s) {
;     ...
;         for (int t = PEEL ? 2 : 0; t < nt; t += 2) {
;             const bool last = (t == nt - 2);
;             const char* a1 = cA + (size_t)(t + 1) * kstepA;
;             const char* a2 = last ? nA : cA + (size_t)(t + 2) * kstepA; const char* b2 = last ? nB : cB + (size_t)(t + 2) * kstep;
;             const char* a3 = a2 + kstepA; const char* b3 = b2 + kstep;
;             if (last && has_next) S.a_ready(nxt);
;             if constexpr (SP2) {
;             PG8_ITER(PG8_MMA)
	s_setprio 0
	s_add_i32 s67, s67, s36
	s_add_i32 s71, s67, 0x2000
	s_nop 1
	v_lshl_add_u64 v[24:25], v[250:251], 0, s[62:63]
	s_mov_b32 m0, s67
	s_add_u32 s78, s74, 0x20180
	ds_read_b128 v[32:35], v149 offset:49152
	ds_read_b128 v[36:39], v149 offset:50176
	ds_read_b128 v[150:153], v149 offset:51200
	ds_read_b128 v[154:157], v149 offset:52224
	ds_read_b128 v[230:233], v149 offset:53248
	ds_read_b128 v[234:237], v149 offset:54272
	ds_read_b128 v[238:241], v149 offset:55296
	ds_read_b128 v[242:245], v149 offset:56320
	global_load_lds_dwordx4 v[24:25], off
	v_lshl_add_u64 v[24:25], v[252:253], 0, s[62:63]
	s_mov_b32 m0, s71
	s_addc_u32 s79, s75, 0
	s_add_i32 s80, s80, s36
	global_load_lds_dwordx4 v[24:25], off
	v_lshl_add_u64 v[24:25], s[78:79], 0, v[128:129]
	s_mov_b32 m0, s80
	s_add_i32 s81, s80, 0x2000
	global_load_lds_dwordx4 v128, s[78:79]
	v_lshl_add_u64 v[24:25], s[78:79], 0, v[130:131]
	s_mov_b32 m0, s81
	s_nop 0
	global_load_lds_dwordx4 v130, s[78:79]
	v_lshl_add_u64 v[24:25], v[140:141], 0, s[62:63]
	s_mov_b32 m0, s42
	s_nop 0
	global_load_lds_dwordx4 v[24:25], off
	v_lshl_add_u64 v[24:25], v[142:143], 0, s[62:63]
	s_mov_b32 m0, s43
	s_nop 0
	global_load_lds_dwordx4 v[24:25], off
	s_waitcnt vmcnt(8) lgkmcnt(0)
	s_setprio 1
	s_barrier
	v_mfma_f32_16x16x32_bf16 v[24:27], v[8:11], v[32:35], v[158:161]
	v_mfma_f32_16x16x32_bf16 v[76:79], v[12:15], v[36:39], v[24:27]
	v_mfma_f32_16x16x32_bf16 v[24:27], v[16:19], v[32:35], v[162:165]
	v_mfma_f32_16x16x32_bf16 v[72:75], v[20:23], v[36:39], v[24:27]
	v_mfma_f32_16x16x32_bf16 v[24:27], v[8:11], v[150:153], v[166:169]
	v_mfma_f32_16x16x32_bf16 v[44:47], v[12:15], v[154:157], v[24:27]
	v_mfma_f32_16x16x32_bf16 v[24:27], v[16:19], v[150:153], v[170:173]
	v_mfma_f32_16x16x32_bf16 v[40:43], v[20:23], v[154:157], v[24:27]
	v_mfma_f32_16x16x32_bf16 v[24:27], v[8:11], v[230:233], v[174:177]
	v_mfma_f32_16x16x32_bf16 v[0:3], v[8:11], v[238:241], v[0:3]
	v_mfma_f32_16x16x32_bf16 v[28:31], v[12:15], v[234:237], v[24:27]
	v_mfma_f32_16x16x32_bf16 v[24:27], v[16:19], v[230:233], v[178:181]
	v_mfma_f32_16x16x32_bf16 v[12:15], v[12:15], v[242:245], v[0:3]
	v_mfma_f32_16x16x32_bf16 v[0:3], v[16:19], v[238:241], v[4:7]
	v_mfma_f32_16x16x32_bf16 v[24:27], v[20:23], v[234:237], v[24:27]
	v_mfma_f32_16x16x32_bf16 v[8:11], v[20:23], v[242:245], v[0:3]
	s_setprio 0
	s_setprio 1
	v_mfma_f32_16x16x32_bf16 v[0:3], v[214:217], v[32:35], v[182:185]
	v_mfma_f32_16x16x32_bf16 v[68:71], v[218:221], v[36:39], v[0:3]
	v_mfma_f32_16x16x32_bf16 v[0:3], v[222:225], v[32:35], v[186:189]
	v_mfma_f32_16x16x32_bf16 v[64:67], v[226:229], v[36:39], v[0:3]
	v_mfma_f32_16x16x32_bf16 v[0:3], v[214:217], v[150:153], v[190:193]
	v_mfma_f32_16x16x32_bf16 v[36:39], v[218:221], v[154:157], v[0:3]
	v_mfma_f32_16x16x32_bf16 v[0:3], v[222:225], v[150:153], v[194:197]
	v_mfma_f32_16x16x32_bf16 v[32:35], v[226:229], v[154:157], v[0:3]
	v_mfma_f32_16x16x32_bf16 v[0:3], v[214:217], v[230:233], v[198:201]
	v_mfma_f32_16x16x32_bf16 v[20:23], v[218:221], v[234:237], v[0:3]
	v_mfma_f32_16x16x32_bf16 v[0:3], v[222:225], v[230:233], v[202:205]
	v_mfma_f32_16x16x32_bf16 v[16:19], v[226:229], v[234:237], v[0:3]
	v_mfma_f32_16x16x32_bf16 v[0:3], v[214:217], v[238:241], v[206:209]
	v_mfma_f32_16x16x32_bf16 v[4:7], v[218:221], v[242:245], v[0:3]
	v_mfma_f32_16x16x32_bf16 v[0:3], v[222:225], v[238:241], v[210:213]
	v_mfma_f32_16x16x32_bf16 v[0:3], v[226:229], v[242:245], v[0:3]
	s_barrier
	s_setprio 0
	s_add_u32 s82, s74, 0x200
	s_addc_u32 s83, s75, 0
	s_add_u32 s74, s76, 0x20180
	s_addc_u32 s75, s77, 0
	s_mov_b32 s85, 0
.LBB0_2566:
	ds_read_b128 v[150:153], v147
	ds_read_b128 v[154:157], v147 offset:1024
	ds_read_b128 v[158:161], v147 offset:2048
	ds_read_b128 v[162:165], v147 offset:3072
	ds_read_b128 v[166:169], v148
	ds_read_b128 v[170:173], v148 offset:1024
	ds_read_b128 v[174:177], v148 offset:2048
	ds_read_b128 v[178:181], v148 offset:3072
	s_add_u32 s76, s74, 0xfffe0080
	s_addc_u32 s77, s75, -1
	s_cmp_eq_u32 s85, 4
	s_cselect_b32 s79, s51, s77
	s_cselect_b32 s78, s52, s76
	s_cselect_b32 s77, s53, s83
	s_cselect_b32 s76, s54, s82
	s_mov_b32 m0, s55
	v_lshl_add_u64 v[140:141], s[74:75], 0, v[138:139]
	ds_read_b128 v[182:185], v149
	ds_read_b128 v[186:189], v149 offset:1024
	ds_read_b128 v[190:193], v149 offset:2048
	ds_read_b128 v[194:197], v149 offset:3072
	ds_read_b128 v[198:201], v149 offset:4096
	ds_read_b128 v[202:205], v149 offset:5120
	ds_read_b128 v[206:209], v149 offset:6144
	ds_read_b128 v[210:213], v149 offset:7168
	global_load_lds_dwordx4 v138, s[74:75]
	v_lshl_add_u64 v[140:141], s[74:75], 0, v[136:137]
	s_mov_b32 m0, s56
	s_nop 0
	global_load_lds_dwordx4 v136, s[74:75]
	s_waitcnt vmcnt(8) lgkmcnt(0)
	s_setprio 1
	s_barrier
	v_mfma_f32_16x16x32_bf16 v[120:123], v[150:153], v[182:185], v[120:123]
	v_mfma_f32_16x16x32_bf16 v[112:115], v[158:161], v[182:185], v[112:115]
	v_mfma_f32_16x16x32_bf16 v[104:107], v[150:153], v[190:193], v[104:107]
	v_mfma_f32_16x16x32_bf16 v[96:99], v[158:161], v[190:193], v[96:99]
	v_mfma_f32_16x16x32_bf16 v[88:91], v[150:153], v[198:201], v[88:91]
	v_mfma_f32_16x16x32_bf16 v[80:83], v[158:161], v[198:201], v[80:83]
	v_mfma_f32_16x16x32_bf16 v[56:59], v[150:153], v[206:209], v[56:59]
	v_mfma_f32_16x16x32_bf16 v[48:51], v[158:161], v[206:209], v[48:51]
	v_mfma_f32_16x16x32_bf16 v[120:123], v[154:157], v[186:189], v[120:123]
	v_mfma_f32_16x16x32_bf16 v[112:115], v[162:165], v[186:189], v[112:115]
	v_mfma_f32_16x16x32_bf16 v[104:107], v[154:157], v[194:197], v[104:107]
	v_mfma_f32_16x16x32_bf16 v[96:99], v[162:165], v[194:197], v[96:99]
	v_mfma_f32_16x16x32_bf16 v[88:91], v[154:157], v[202:205], v[88:91]
	v_mfma_f32_16x16x32_bf16 v[80:83], v[162:165], v[202:205], v[80:83]
	v_mfma_f32_16x16x32_bf16 v[56:59], v[154:157], v[210:213], v[56:59]
	v_mfma_f32_16x16x32_bf16 v[48:51], v[162:165], v[210:213], v[48:51]
	s_setprio 0
	s_setprio 1
	v_mfma_f32_16x16x32_bf16 v[124:127], v[166:169], v[182:185], v[124:127]
	v_mfma_f32_16x16x32_bf16 v[116:119], v[174:177], v[182:185], v[116:119]
	v_mfma_f32_16x16x32_bf16 v[108:111], v[166:169], v[190:193], v[108:111]
	v_mfma_f32_16x16x32_bf16 v[100:103], v[174:177], v[190:193], v[100:103]
	v_mfma_f32_16x16x32_bf16 v[92:95], v[166:169], v[198:201], v[92:95]
	v_mfma_f32_16x16x32_bf16 v[84:87], v[174:177], v[198:201], v[84:87]
	v_mfma_f32_16x16x32_bf16 v[60:63], v[166:169], v[206:209], v[60:63]
	v_mfma_f32_16x16x32_bf16 v[52:55], v[174:177], v[206:209], v[52:55]
	v_mfma_f32_16x16x32_bf16 v[124:127], v[170:173], v[186:189], v[124:127]
	v_mfma_f32_16x16x32_bf16 v[116:119], v[178:181], v[186:189], v[116:119]
	v_mfma_f32_16x16x32_bf16 v[108:111], v[170:173], v[194:197], v[108:111]
	v_mfma_f32_16x16x32_bf16 v[100:103], v[178:181], v[194:197], v[100:103]
	v_mfma_f32_16x16x32_bf16 v[92:95], v[170:173], v[202:205], v[92:95]
	v_mfma_f32_16x16x32_bf16 v[84:87], v[178:181], v[202:205], v[84:87]
	v_mfma_f32_16x16x32_bf16 v[60:63], v[170:173], v[210:213], v[60:63]
	v_mfma_f32_16x16x32_bf16 v[52:55], v[178:181], v[210:213], v[52:55]
	s_barrier
	s_setprio 0
	s_mov_b32 m0, s57
	v_lshl_add_u64 v[140:141], s[76:77], 0, v[128:129]
	s_add_u32 s88, s76, 0x20000
	ds_read_b128 v[182:185], v149 offset:16384
	ds_read_b128 v[186:189], v149 offset:17408
	ds_read_b128 v[190:193], v149 offset:18432
	ds_read_b128 v[194:197], v149 offset:19456
	ds_read_b128 v[198:201], v149 offset:20480
	ds_read_b128 v[202:205], v149 offset:21504
	ds_read_b128 v[206:209], v149 offset:22528
	ds_read_b128 v[210:213], v149 offset:23552
	global_load_lds_dwordx4 v128, s[76:77]
	v_lshl_add_u64 v[142:143], s[76:77], 0, v[130:131]
	s_mov_b32 m0, s58
	s_addc_u32 s89, s77, 0
	global_load_lds_dwordx4 v130, s[76:77]
	v_lshl_add_u64 v[214:215], s[88:89], 0, v[128:129]
	s_mov_b32 m0, s59
	v_lshl_add_u64 v[216:217], s[78:79], 0, v[132:133]
	global_load_lds_dwordx4 v128, s[88:89]
	v_lshl_add_u64 v[214:215], s[88:89], 0, v[130:131]
	s_mov_b32 m0, s65
	s_nop 0
	global_load_lds_dwordx4 v130, s[88:89]
	v_lshl_add_u64 v[214:215], s[78:79], 0, v[134:135]
	s_mov_b32 m0, s0
	s_nop 0
	global_load_lds_dwordx4 v134, s[78:79]
	s_mov_b32 m0, s1
	s_nop 0
	global_load_lds_dwordx4 v132, s[78:79]
	s_waitcnt vmcnt(8) lgkmcnt(0)
	s_setprio 1
	s_barrier
	v_mfma_f32_16x16x32_bf16 v[76:79], v[150:153], v[182:185], v[76:79]
	v_mfma_f32_16x16x32_bf16 v[72:75], v[158:161], v[182:185], v[72:75]
	v_mfma_f32_16x16x32_bf16 v[44:47], v[150:153], v[190:193], v[44:47]
	v_mfma_f32_16x16x32_bf16 v[40:43], v[158:161], v[190:193], v[40:43]
	v_mfma_f32_16x16x32_bf16 v[28:31], v[150:153], v[198:201], v[28:31]
	v_mfma_f32_16x16x32_bf16 v[24:27], v[158:161], v[198:201], v[24:27]
	v_mfma_f32_16x16x32_bf16 v[12:15], v[150:153], v[206:209], v[12:15]
	v_mfma_f32_16x16x32_bf16 v[8:11], v[158:161], v[206:209], v[8:11]
	v_mfma_f32_16x16x32_bf16 v[76:79], v[154:157], v[186:189], v[76:79]
	v_mfma_f32_16x16x32_bf16 v[72:75], v[162:165], v[186:189], v[72:75]
	v_mfma_f32_16x16x32_bf16 v[44:47], v[154:157], v[194:197], v[44:47]
	v_mfma_f32_16x16x32_bf16 v[40:43], v[162:165], v[194:197], v[40:43]
	v_mfma_f32_16x16x32_bf16 v[28:31], v[154:157], v[202:205], v[28:31]
	v_mfma_f32_16x16x32_bf16 v[24:27], v[162:165], v[202:205], v[24:27]
	v_mfma_f32_16x16x32_bf16 v[12:15], v[154:157], v[210:213], v[12:15]
	v_mfma_f32_16x16x32_bf16 v[8:11], v[162:165], v[210:213], v[8:11]
	s_setprio 0
	s_setprio 1
	v_mfma_f32_16x16x32_bf16 v[68:71], v[166:169], v[182:185], v[68:71]
	v_mfma_f32_16x16x32_bf16 v[64:67], v[174:177], v[182:185], v[64:67]
	v_mfma_f32_16x16x32_bf16 v[36:39], v[166:169], v[190:193], v[36:39]
	v_mfma_f32_16x16x32_bf16 v[32:35], v[174:177], v[190:193], v[32:35]
	v_mfma_f32_16x16x32_bf16 v[20:23], v[166:169], v[198:201], v[20:23]
	v_mfma_f32_16x16x32_bf16 v[16:19], v[174:177], v[198:201], v[16:19]
	v_mfma_f32_16x16x32_bf16 v[4:7], v[166:169], v[206:209], v[4:7]
	v_mfma_f32_16x16x32_bf16 v[0:3], v[174:177], v[206:209], v[0:3]
	v_mfma_f32_16x16x32_bf16 v[68:71], v[170:173], v[186:189], v[68:71]
	v_mfma_f32_16x16x32_bf16 v[64:67], v[178:181], v[186:189], v[64:67]
	v_mfma_f32_16x16x32_bf16 v[36:39], v[170:173], v[194:197], v[36:39]
	v_mfma_f32_16x16x32_bf16 v[32:35], v[178:181], v[194:197], v[32:35]
	v_mfma_f32_16x16x32_bf16 v[20:23], v[170:173], v[202:205], v[20:23]
	v_mfma_f32_16x16x32_bf16 v[16:19], v[178:181], v[202:205], v[16:19]
	v_mfma_f32_16x16x32_bf16 v[4:7], v[170:173], v[210:213], v[4:7]
	v_mfma_f32_16x16x32_bf16 v[0:3], v[178:181], v[210:213], v[0:3]
	s_barrier
; #define PG8_MMA(ai, bj, At, Bt) do { __builtin_amdgcn_s_setprio(1); _Pragma("unroll") for (int m = 0; m < 4; ++m) _Pragma("unroll") for (int n = 0; n < 2; ++n) _Pragma("unroll") for (int k = 0; k < 2; ++k) \
;         acc[ai][bj][m][n] = __builtin_amdgcn_mfma_f32_16x16x32_bf16(Bt[n][k], At[m][k], acc[ai][bj][m][n], 0, 0, 0); __builtin_amdgcn_s_setprio(0); } while (0)
; template <class Epi, class Sched, bool ALIGN_EPI = false, bool SP2 = false, bool A_TILED = false>
; __device__ __forceinline__ void gemm_phase(PG8_LAS unsigned char* lds, const Gemm g, const Sched& S, const Epi& E, const int wave_s) {
;     ...
;         for (int t = PEEL ? 2 : 0; t < nt; t += 2) {
;             const bool last = (t == nt - 2);
;             const char* a1 = cA + (size_t)(t + 1) * kstepA;
;             const char* a2 = last ? nA : cA + (size_t)(t + 2) * kstepA; const char* b2 = last ? nB : cB + (size_t)(t + 2) * kstep;
;             const char* a3 = a2 + kstepA; const char* b3 = b2 + kstep;
;             if (last && has_next) S.a_ready(nxt);
;             if constexpr (SP2) {
;             PG8_ITER(PG8_MMA)
	s_setprio 0
	ds_read_b128 v[150:153], v144
	ds_read_b128 v[154:157], v144 offset:1024
	ds_read_b128 v[158:161], v144 offset:2048
	ds_read_b128 v[162:165], v144 offset:3072
	ds_read_b128 v[166:169], v145
	ds_read_b128 v[170:173], v145 offset:1024
	ds_read_b128 v[174:177], v145 offset:2048
	ds_read_b128 v[178:181], v145 offset:3072
	s_add_u32 s78, s78, 0x20000
	s_addc_u32 s79, s79, 0
	s_mov_b32 m0, s37
	v_lshl_add_u64 v[218:219], s[78:79], 0, v[134:135]
	ds_read_b128 v[182:185], v149 offset:32768
	ds_read_b128 v[186:189], v149 offset:33792
	ds_read_b128 v[190:193], v149 offset:34816
	ds_read_b128 v[194:197], v149 offset:35840
	ds_read_b128 v[198:201], v149 offset:36864
	ds_read_b128 v[202:205], v149 offset:37888
	ds_read_b128 v[206:209], v149 offset:38912
	ds_read_b128 v[210:213], v149 offset:39936
	global_load_lds_dwordx4 v134, s[78:79]
	v_lshl_add_u64 v[218:219], s[78:79], 0, v[132:133]
	s_mov_b32 m0, s38
	s_nop 0
	global_load_lds_dwordx4 v132, s[78:79]
	s_waitcnt vmcnt(8) lgkmcnt(0)
	s_setprio 1
	s_barrier
	v_mfma_f32_16x16x32_bf16 v[120:123], v[150:153], v[182:185], v[120:123]
	v_mfma_f32_16x16x32_bf16 v[112:115], v[158:161], v[182:185], v[112:115]
	v_mfma_f32_16x16x32_bf16 v[104:107], v[150:153], v[190:193], v[104:107]
	v_mfma_f32_16x16x32_bf16 v[96:99], v[158:161], v[190:193], v[96:99]
	v_mfma_f32_16x16x32_bf16 v[88:91], v[150:153], v[198:201], v[88:91]
	v_mfma_f32_16x16x32_bf16 v[80:83], v[158:161], v[198:201], v[80:83]
	v_mfma_f32_16x16x32_bf16 v[56:59], v[150:153], v[206:209], v[56:59]
	v_mfma_f32_16x16x32_bf16 v[48:51], v[158:161], v[206:209], v[48:51]
	v_mfma_f32_16x16x32_bf16 v[120:123], v[154:157], v[186:189], v[120:123]
	v_mfma_f32_16x16x32_bf16 v[112:115], v[162:165], v[186:189], v[112:115]
	v_mfma_f32_16x16x32_bf16 v[104:107], v[154:157], v[194:197], v[104:107]
	v_mfma_f32_16x16x32_bf16 v[96:99], v[162:165], v[194:197], v[96:99]
	v_mfma_f32_16x16x32_bf16 v[88:91], v[154:157], v[202:205], v[88:91]
	v_mfma_f32_16x16x32_bf16 v[80:83], v[162:165], v[202:205], v[80:83]
	v_mfma_f32_16x16x32_bf16 v[56:59], v[154:157], v[210:213], v[56:59]
	v_mfma_f32_16x16x32_bf16 v[48:51], v[162:165], v[210:213], v[48:51]
	s_setprio 0
	s_setprio 1
	v_mfma_f32_16x16x32_bf16 v[124:127], v[166:169], v[182:185], v[124:127]
	v_mfma_f32_16x16x32_bf16 v[116:119], v[174:177], v[182:185], v[116:119]
	v_mfma_f32_16x16x32_bf16 v[108:111], v[166:169], v[190:193], v[108:111]
	v_mfma_f32_16x16x32_bf16 v[100:103], v[174:177], v[190:193], v[100:103]
	v_mfma_f32_16x16x32_bf16 v[92:95], v[166:169], v[198:201], v[92:95]
	v_mfma_f32_16x16x32_bf16 v[84:87], v[174:177], v[198:201], v[84:87]
	v_mfma_f32_16x16x32_bf16 v[60:63], v[166:169], v[206:209], v[60:63]
	v_mfma_f32_16x16x32_bf16 v[52:55], v[174:177], v[206:209], v[52:55]
	v_mfma_f32_16x16x32_bf16 v[124:127], v[170:173], v[186:189], v[124:127]
	v_mfma_f32_16x16x32_bf16 v[116:119], v[178:181], v[186:189], v[116:119]
	v_mfma_f32_16x16x32_bf16 v[108:111], v[170:173], v[194:197], v[108:111]
	v_mfma_f32_16x16x32_bf16 v[100:103], v[178:181], v[194:197], v[100:103]
	v_mfma_f32_16x16x32_bf16 v[92:95], v[170:173], v[202:205], v[92:95]
	v_mfma_f32_16x16x32_bf16 v[84:87], v[178:181], v[202:205], v[84:87]
	v_mfma_f32_16x16x32_bf16 v[60:63], v[170:173], v[210:213], v[60:63]
	v_mfma_f32_16x16x32_bf16 v[52:55], v[178:181], v[210:213], v[52:55]
	s_barrier
	s_setprio 0
	s_mov_b32 m0, s67
	v_lshl_add_u64 v[140:141], v[140:141], 0, s[44:45]
	s_add_u32 s76, s76, 0x20080
	ds_read_b128 v[182:185], v149 offset:49152
	ds_read_b128 v[186:189], v149 offset:50176
	ds_read_b128 v[190:193], v149 offset:51200
	ds_read_b128 v[194:197], v149 offset:52224
	ds_read_b128 v[198:201], v149 offset:53248
	ds_read_b128 v[202:205], v149 offset:54272
	ds_read_b128 v[206:209], v149 offset:55296
	ds_read_b128 v[210:213], v149 offset:56320
	global_load_lds_dwordx4 v[140:141], off
	v_lshl_add_u64 v[140:141], v[142:143], 0, s[44:45]
	s_mov_b32 m0, s71
	s_addc_u32 s77, s77, 0
	global_load_lds_dwordx4 v[140:141], off
	v_lshl_add_u64 v[140:141], s[76:77], 0, v[128:129]
	s_mov_b32 m0, s80
	s_nop 0
	global_load_lds_dwordx4 v128, s[76:77]
	v_lshl_add_u64 v[140:141], s[76:77], 0, v[130:131]
	s_mov_b32 m0, s81
	s_nop 0
	global_load_lds_dwordx4 v130, s[76:77]
	v_lshl_add_u64 v[140:141], v[214:215], 0, s[44:45]
	s_mov_b32 m0, s42
	s_nop 0
	global_load_lds_dwordx4 v[140:141], off
	v_lshl_add_u64 v[140:141], v[216:217], 0, s[44:45]
	s_mov_b32 m0, s43
	s_nop 0
	global_load_lds_dwordx4 v[140:141], off
	s_waitcnt vmcnt(8) lgkmcnt(0)
	s_setprio 1
	s_barrier
	v_mfma_f32_16x16x32_bf16 v[76:79], v[150:153], v[182:185], v[76:79]
	v_mfma_f32_16x16x32_bf16 v[72:75], v[158:161], v[182:185], v[72:75]
	v_mfma_f32_16x16x32_bf16 v[44:47], v[150:153], v[190:193], v[44:47]
	v_mfma_f32_16x16x32_bf16 v[40:43], v[158:161], v[190:193], v[40:43]
	v_mfma_f32_16x16x32_bf16 v[28:31], v[150:153], v[198:201], v[28:31]
	v_mfma_f32_16x16x32_bf16 v[24:27], v[158:161], v[198:201], v[24:27]
	v_mfma_f32_16x16x32_bf16 v[12:15], v[150:153], v[206:209], v[12:15]
	v_mfma_f32_16x16x32_bf16 v[8:11], v[158:161], v[206:209], v[8:11]
	v_mfma_f32_16x16x32_bf16 v[76:79], v[154:157], v[186:189], v[76:79]
	v_mfma_f32_16x16x32_bf16 v[72:75], v[162:165], v[186:189], v[72:75]
	v_mfma_f32_16x16x32_bf16 v[44:47], v[154:157], v[194:197], v[44:47]
	v_mfma_f32_16x16x32_bf16 v[40:43], v[162:165], v[194:197], v[40:43]
	v_mfma_f32_16x16x32_bf16 v[28:31], v[154:157], v[202:205], v[28:31]
	v_mfma_f32_16x16x32_bf16 v[24:27], v[162:165], v[202:205], v[24:27]
	v_mfma_f32_16x16x32_bf16 v[12:15], v[154:157], v[210:213], v[12:15]
	v_mfma_f32_16x16x32_bf16 v[8:11], v[162:165], v[210:213], v[8:11]
	s_setprio 0
	s_setprio 1
	v_mfma_f32_16x16x32_bf16 v[68:71], v[166:169], v[182:185], v[68:71]
	v_mfma_f32_16x16x32_bf16 v[64:67], v[174:177], v[182:185], v[64:67]
	v_mfma_f32_16x16x32_bf16 v[36:39], v[166:169], v[190:193], v[36:39]
	v_mfma_f32_16x16x32_bf16 v[32:35], v[174:177], v[190:193], v[32:35]
	v_mfma_f32_16x16x32_bf16 v[20:23], v[166:169], v[198:201], v[20:23]
	v_mfma_f32_16x16x32_bf16 v[16:19], v[174:177], v[198:201], v[16:19]
	v_mfma_f32_16x16x32_bf16 v[4:7], v[166:169], v[206:209], v[4:7]
	v_mfma_f32_16x16x32_bf16 v[0:3], v[174:177], v[206:209], v[0:3]
	v_mfma_f32_16x16x32_bf16 v[68:71], v[170:173], v[186:189], v[68:71]
	v_mfma_f32_16x16x32_bf16 v[64:67], v[178:181], v[186:189], v[64:67]
	v_mfma_f32_16x16x32_bf16 v[36:39], v[170:173], v[194:197], v[36:39]
	v_mfma_f32_16x16x32_bf16 v[32:35], v[178:181], v[194:197], v[32:35]
	v_mfma_f32_16x16x32_bf16 v[20:23], v[170:173], v[202:205], v[20:23]
	v_mfma_f32_16x16x32_bf16 v[16:19], v[178:181], v[202:205], v[16:19]
	v_mfma_f32_16x16x32_bf16 v[4:7], v[170:173], v[210:213], v[4:7]
	v_mfma_f32_16x16x32_bf16 v[0:3], v[178:181], v[210:213], v[0:3]
	s_barrier
	s_setprio 0
	s_add_i32 s85, s85, 2
	s_add_u32 s82, s82, 0x100
	s_addc_u32 s83, s83, 0
	s_add_u32 s74, s74, 0x100
	s_addc_u32 s75, s75, 0
	s_cmp_gt_u32 s85, 5
	s_cbranch_scc0 .LBB0_2566
	s_and_b64 vcc, exec, s[46:47]
	s_cbranch_vccz .LBB0_2569
	s_barrier

; #define PG8_STAGE(bufoff, gbase, voff) do { _Pragma("unroll") for (int _i = 0; _i < 2; ++_i) \
;         __builtin_amdgcn_global_load_lds((const unsigned*)((const char*)(gbase) + (voff)[_i]), (PG8_LAS unsigned*)(lds + (bufoff) + ldsw + _i * 8192), 16, 0, 0); } while (0)
; #define PG8_WAIT_V(n) asm volatile("s_waitcnt vmcnt(" #n ")" ::: "memory")
; #define PG8_BAR __builtin_amdgcn_s_barrier()
; template <class Epi, class Sched, bool ALIGN_EPI = false, bool SP2 = false, bool A_TILED = false>
; __device__ __forceinline__ void gemm_phase(PG8_LAS unsigned char* lds, const Gemm g, const Sched& S, const Epi& E, const int wave_s) {
;     ...
;     if constexpr (SP2) {
;         PG8_STAGE(PG8_SB(0, 0), cB, voffB); PG8_STAGE(PG8_SB(0, 1), cB + hstep, voffB); PG8_STAGE(PG8_SA(0, 0), cA, voffA); PG8_STAGE(PG8_SA(0, 1), cA + hstepA, voffA);
;         if (wr == 1) PG8_BAR;
;         PG8_WAIT_V(2); PG8_BAR;
;         PG8_STAGE(PG8_SB(1, 0), cB + kstep, voffB); PG8_STAGE(PG8_SA(1, 0), cA + kstepA, voffA); PG8_STAGE(PG8_SB(1, 1), cB + hstep + kstep, voffB);
;         PG8_WAIT_V(6); PG8_BAR;
;     } else {
;         PG8_STAGE(PG8_SB(0, 0), cB, voffB); PG8_STAGE(PG8_SA(0, 0), cA, voffA); PG8_STAGE(PG8_SB(0, 1), cB + hstep, voffB); PG8_STAGE(PG8_SA(0, 1), cA + hstepA, voffA);
;         if (wr == 1) PG8_BAR;
;         PG8_WAIT_V(4); PG8_BAR;
;         PG8_STAGE(PG8_SB(1, 0), cB + kstep, voffB); PG8_STAGE(PG8_SA(1, 0), cA + kstepA, voffA); PG8_STAGE(PG8_SB(1, 1), cB + hstep + kstep, voffB);
;         PG8_WAIT_V(6); PG8_BAR;
;     ...
; #pragma unroll
;             for (int a = 0; a < 2; ++a)
; #pragma unroll
;                 for (int b = 0; b < 2; ++b)
; #pragma unroll
;                     for (int m = 0; m < 4; ++m)
; #pragma unroll
;                         for (int n = 0; n < 2; ++n) acc[a][b][m][n] = (f32x4){0.f, 0.f, 0.f, 0.f};
.LBB0_2728:
	v_and_b32_e32 v15, 48, v8
	v_lshlrev_b32_e32 v16, 6, v8
	s_movk_i32 s36, 0x3c0
	v_lshlrev_b32_e32 v8, 2, v8
	s_and_b32 s9, s1, 3
	s_lshl_b32 s8, s23, 6
	s_lshl_b32 s23, s23, 13
	v_and_or_b32 v15, v16, s36, v15
	v_and_b32_e32 v8, 32, v8
	s_mov_b64 s[60:61], 0x80
	v_bitop3_b32 v16, v15, s23, v8 bitop3:0xde
	s_lshl_b32 s23, s9, 12
	s_add_i32 m0, s14, 0x18000
	v_lshl_add_u64 v[6:7], v[6:7], 0, s[60:61]
	v_bitop3_b32 v8, v15, s23, v8 bitop3:0xde
	s_waitcnt vmcnt(2)
	s_barrier
	global_load_lds_dwordx4 v[6:7], off
	v_lshl_add_u64 v[4:5], v[4:5], 0, s[60:61]
	s_add_i32 m0, s14, 0x1a000
	s_add_i32 s23, s14, 0x8000
	s_add_i32 s36, s14, 0xa000
	global_load_lds_dwordx4 v[4:5], off
	v_lshl_add_u64 v[2:3], v[2:3], 0, s[60:61]
	s_mov_b32 m0, s23
	s_add_u32 s38, s2, 0x80080
	global_load_lds_dwordx4 v[2:3], off
	v_lshl_add_u64 v[0:1], v[0:1], 0, s[60:61]
	s_mov_b32 m0, s36
	s_addc_u32 s39, s3, 0
	global_load_lds_dwordx4 v[0:1], off
	s_add_i32 m0, s14, 0x1c000
	v_lshl_add_u64 v[0:1], s[38:39], 0, v[34:35]
	global_load_lds_dwordx4 v34, s[38:39]
	v_lshl_add_u64 v[0:1], s[38:39], 0, v[134:135]
	s_add_i32 m0, s14, 0x1e000
	s_mov_b64 s[40:41], 0x20680080
	global_load_lds_dwordx4 v134, s[38:39]
	v_lshlrev_b32_e32 v0, 15, v12
	v_and_b32_e32 v0, 0xffff0000, v0
	v_lshl_add_u32 v0, v13, 12, v0
	v_and_b32_e32 v1, 1, v12
	v_lshl_or_b32 v0, v1, 6, v0
	v_lshl_add_u32 v0, v14, 1, v0
	v_mov_b32_e32 v1, v35
	v_lshl_add_u64 v[0:1], s[62:63], 0, v[0:1]
	v_lshl_add_u64 v[136:137], v[0:1], 0, s[40:41]
	v_lshlrev_b32_e32 v0, 15, v9
	v_and_b32_e32 v0, 0xffff0000, v0
	v_lshl_add_u32 v0, v10, 12, v0
	v_and_b32_e32 v1, 1, v9
	s_add_u32 s37, s64, 0x9e00100
	v_lshl_or_b32 v0, v1, 6, v0
	s_addc_u32 s38, s65, 0
	v_lshl_add_u32 v0, v11, 1, v0
	v_mov_b32_e32 v1, v35
	v_lshl_add_u64 v[0:1], s[62:63], 0, v[0:1]
	s_add_u32 s39, s62, 0x20600100
	s_waitcnt vmcnt(6)
	v_lshl_add_u64 v[138:139], v[0:1], 0, s[40:41]
	s_addc_u32 s40, s63, 0
	s_add_i32 s47, 0, 0x10000
	s_add_i32 s49, 0, 0x14000
	s_add_i32 s51, 0, 0x18000
	s_add_i32 s54, 0, 0x1c000
	v_add_u32_e32 v140, s47, v8
	v_add_u32_e32 v141, s49, v8
	s_add_i32 s47, s47, s53
	s_add_i32 s49, s49, s53
	v_add_u32_e32 v143, s51, v8
	s_add_i32 s51, s51, s53
	s_add_i32 s53, s54, s53
	s_mov_b32 s41, -2
	v_add_u32_e32 v142, 0, v16
	s_add_i32 s42, s14, 0xc000
	s_add_i32 s43, s14, 0xe000
	s_add_i32 s48, s47, 0x2000
	s_add_i32 s50, s49, 0x2000
	v_add_u32_e32 v144, s54, v8
	s_add_i32 s52, s51, 0x2000
	s_add_i32 s54, s53, 0x2000
	s_mov_b64 s[62:63], 0x100
	v_mov_b32_e32 v0, v35
	v_mov_b32_e32 v1, v35
	v_mov_b32_e32 v2, v35
	v_mov_b32_e32 v3, v35
	v_mov_b32_e32 v4, v35
	v_mov_b32_e32 v5, v35
	v_mov_b32_e32 v6, v35
	v_mov_b32_e32 v7, v35
	v_mov_b32_e32 v40, v35
	v_mov_b32_e32 v41, v35
	v_mov_b32_e32 v42, v35
	v_mov_b32_e32 v43, v35
	v_mov_b32_e32 v44, v35
	v_mov_b32_e32 v45, v35
	v_mov_b32_e32 v46, v35
	v_mov_b32_e32 v47, v35
	v_mov_b32_e32 v88, v35
	v_mov_b32_e32 v89, v35
	v_mov_b32_e32 v90, v35
	v_mov_b32_e32 v91, v35
	v_mov_b32_e32 v92, v35
	v_mov_b32_e32 v93, v35
	v_mov_b32_e32 v94, v35
	v_mov_b32_e32 v95, v35
	v_mov_b32_e32 v112, v35
	v_mov_b32_e32 v113, v35
	v_mov_b32_e32 v114, v35
	v_mov_b32_e32 v115, v35
	v_mov_b32_e32 v124, v35
	v_mov_b32_e32 v125, v35
	v_mov_b32_e32 v126, v35
	v_mov_b32_e32 v127, v35
	v_mov_b32_e32 v28, v35
	v_mov_b32_e32 v29, v35
	v_mov_b32_e32 v30, v35
	v_mov_b32_e32 v31, v35
	v_mov_b32_e32 v36, v35
	v_mov_b32_e32 v37, v35
	v_mov_b32_e32 v38, v35
	v_mov_b32_e32 v39, v35
	v_mov_b32_e32 v80, v35
	v_mov_b32_e32 v81, v35
	v_mov_b32_e32 v82, v35
	v_mov_b32_e32 v83, v35
	v_mov_b32_e32 v84, v35
	v_mov_b32_e32 v85, v35
	v_mov_b32_e32 v86, v35
	v_mov_b32_e32 v87, v35
	v_mov_b32_e32 v120, v35
	v_mov_b32_e32 v121, v35
	v_mov_b32_e32 v122, v35
	v_mov_b32_e32 v123, v35
	v_mov_b32_e32 v116, v35
	v_mov_b32_e32 v117, v35
	v_mov_b32_e32 v118, v35
	v_mov_b32_e32 v119, v35
	v_mov_b32_e32 v104, v35
	v_mov_b32_e32 v105, v35
	v_mov_b32_e32 v106, v35
	v_mov_b32_e32 v107, v35
	v_mov_b32_e32 v100, v35
	v_mov_b32_e32 v101, v35
	v_mov_b32_e32 v102, v35
	v_mov_b32_e32 v103, v35
	v_mov_b32_e32 v96, v35
	v_mov_b32_e32 v97, v35
	v_mov_b32_e32 v98, v35
	v_mov_b32_e32 v99, v35
	v_mov_b32_e32 v108, v35
	v_mov_b32_e32 v109, v35
	v_mov_b32_e32 v110, v35
	v_mov_b32_e32 v111, v35
	v_mov_b32_e32 v64, v35
	v_mov_b32_e32 v65, v35
	v_mov_b32_e32 v66, v35
	v_mov_b32_e32 v67, v35
	v_mov_b32_e32 v72, v35
	v_mov_b32_e32 v73, v35
	v_mov_b32_e32 v74, v35
	v_mov_b32_e32 v75, v35
	v_mov_b32_e32 v48, v35
	v_mov_b32_e32 v49, v35
	v_mov_b32_e32 v50, v35
	v_mov_b32_e32 v51, v35
	v_mov_b32_e32 v56, v35
	v_mov_b32_e32 v57, v35
	v_mov_b32_e32 v58, v35
	v_mov_b32_e32 v59, v35
	v_mov_b32_e32 v16, v35
	v_mov_b32_e32 v17, v35
	v_mov_b32_e32 v18, v35
	v_mov_b32_e32 v19, v35
	v_mov_b32_e32 v24, v35
	v_mov_b32_e32 v25, v35
	v_mov_b32_e32 v26, v35
	v_mov_b32_e32 v27, v35
	v_mov_b32_e32 v68, v35
	v_mov_b32_e32 v69, v35
	v_mov_b32_e32 v70, v35
	v_mov_b32_e32 v71, v35
	v_mov_b32_e32 v128, v35
	v_mov_b32_e32 v129, v35
	v_mov_b32_e32 v130, v35
	v_mov_b32_e32 v131, v35
	v_mov_b32_e32 v52, v35
	v_mov_b32_e32 v53, v35
	v_mov_b32_e32 v54, v35
	v_mov_b32_e32 v55, v35
	v_mov_b32_e32 v76, v35
	v_mov_b32_e32 v77, v35
	v_mov_b32_e32 v78, v35
	v_mov_b32_e32 v79, v35
	v_mov_b32_e32 v20, v35
	v_mov_b32_e32 v21, v35
	v_mov_b32_e32 v22, v35
	v_mov_b32_e32 v23, v35
	v_mov_b32_e32 v60, v35
	v_mov_b32_e32 v61, v35
	v_mov_b32_e32 v62, v35
	v_mov_b32_e32 v63, v35
	v_mov_b32_e32 v12, v35
	v_mov_b32_e32 v13, v35
	v_mov_b32_e32 v14, v35
	v_mov_b32_e32 v15, v35
	v_mov_b32_e32 v8, v35
	v_mov_b32_e32 v9, v35
	v_mov_b32_e32 v10, v35
	v_mov_b32_e32 v11, v35
	s_barrier
; #define PG8_MMA(ai, bj, At, Bt) do { __builtin_amdgcn_s_setprio(1); _Pragma("unroll") for (int m = 0; m < 4; ++m) _Pragma("unroll") for (int n = 0; n < 2; ++n) _Pragma("unroll") for (int k = 0; k < 2; ++k) \
;         acc[ai][bj][m][n] = __builtin_amdgcn_mfma_f32_16x16x32_bf16(Bt[n][k], At[m][k], acc[ai][bj][m][n], 0, 0, 0); __builtin_amdgcn_s_setprio(0); } while (0)
; template <class Epi, class Sched, bool ALIGN_EPI = false, bool SP2 = false, bool A_TILED = false>
; __device__ __forceinline__ void gemm_phase(PG8_LAS unsigned char* lds, const Gemm g, const Sched& S, const Epi& E, const int wave_s) {
;     ...
;         for (int t = PEEL ? 2 : 0; t < nt; t += 2) {
;             const bool last = (t == nt - 2);
;             const char* a1 = cA + (size_t)(t + 1) * kstepA;
;             const char* a2 = last ? nA : cA + (size_t)(t + 2) * kstepA; const char* b2 = last ? nB : cB + (size_t)(t + 2) * kstep;
;             const char* a3 = a2 + kstepA; const char* b3 = b2 + kstep;
;             if (last && has_next) S.a_ready(nxt);
;             if constexpr (SP2) {
;             PG8_ITER(PG8_MMA)
.LBB0_2729:
	ds_read_b128 v[146:149], v140
	ds_read_b128 v[150:153], v140 offset:1024
	ds_read_b128 v[154:157], v140 offset:2048
	ds_read_b128 v[158:161], v140 offset:3072
	ds_read_b128 v[162:165], v141
	ds_read_b128 v[166:169], v141 offset:1024
	ds_read_b128 v[170:173], v141 offset:2048
	ds_read_b128 v[174:177], v141 offset:3072
	s_add_u32 s55, s44, s39
	s_addc_u32 s56, s45, s40
	s_add_u32 s57, s44, s37
	s_addc_u32 s58, s45, s38
	s_cmp_eq_u32 s41, 28
	s_cselect_b32 s67, s7, s56
	s_cselect_b32 s66, s6, s55
	s_cselect_b32 s65, s3, s58
	s_cselect_b32 s64, s2, s57
	s_mov_b32 m0, s42
	v_lshl_add_u64 v[210:211], s[44:45], 0, v[138:139]
	ds_read_b128 v[178:181], v142
	ds_read_b128 v[182:185], v142 offset:1024
	ds_read_b128 v[186:189], v142 offset:2048
	ds_read_b128 v[190:193], v142 offset:3072
	ds_read_b128 v[194:197], v142 offset:4096
	ds_read_b128 v[198:201], v142 offset:5120
	ds_read_b128 v[202:205], v142 offset:6144
	ds_read_b128 v[206:209], v142 offset:7168
	global_load_lds_dwordx4 v[210:211], off
	v_lshl_add_u64 v[210:211], s[44:45], 0, v[136:137]
	s_mov_b32 m0, s43
	s_nop 0
	global_load_lds_dwordx4 v[210:211], off
	s_waitcnt vmcnt(8) lgkmcnt(0)
	s_setprio 1
	s_barrier
	v_mfma_f32_16x16x32_bf16 v[8:11], v[146:149], v[178:181], v[8:11]
	v_mfma_f32_16x16x32_bf16 v[12:15], v[154:157], v[178:181], v[12:15]
	v_mfma_f32_16x16x32_bf16 v[60:63], v[146:149], v[186:189], v[60:63]
	v_mfma_f32_16x16x32_bf16 v[20:23], v[154:157], v[186:189], v[20:23]
	v_mfma_f32_16x16x32_bf16 v[76:79], v[146:149], v[194:197], v[76:79]
	v_mfma_f32_16x16x32_bf16 v[52:55], v[154:157], v[194:197], v[52:55]
	v_mfma_f32_16x16x32_bf16 v[128:131], v[146:149], v[202:205], v[128:131]
	v_mfma_f32_16x16x32_bf16 v[68:71], v[154:157], v[202:205], v[68:71]
	v_mfma_f32_16x16x32_bf16 v[8:11], v[150:153], v[182:185], v[8:11]
	v_mfma_f32_16x16x32_bf16 v[12:15], v[158:161], v[182:185], v[12:15]
	v_mfma_f32_16x16x32_bf16 v[60:63], v[150:153], v[190:193], v[60:63]
	v_mfma_f32_16x16x32_bf16 v[20:23], v[158:161], v[190:193], v[20:23]
	v_mfma_f32_16x16x32_bf16 v[76:79], v[150:153], v[198:201], v[76:79]
	v_mfma_f32_16x16x32_bf16 v[52:55], v[158:161], v[198:201], v[52:55]
	v_mfma_f32_16x16x32_bf16 v[128:131], v[150:153], v[206:209], v[128:131]
	v_mfma_f32_16x16x32_bf16 v[68:71], v[158:161], v[206:209], v[68:71]
	s_setprio 0
	s_setprio 1
	v_mfma_f32_16x16x32_bf16 v[24:27], v[162:165], v[178:181], v[24:27]
	v_mfma_f32_16x16x32_bf16 v[16:19], v[170:173], v[178:181], v[16:19]
	v_mfma_f32_16x16x32_bf16 v[56:59], v[162:165], v[186:189], v[56:59]
	v_mfma_f32_16x16x32_bf16 v[48:51], v[170:173], v[186:189], v[48:51]
	v_mfma_f32_16x16x32_bf16 v[72:75], v[162:165], v[194:197], v[72:75]
	v_mfma_f32_16x16x32_bf16 v[64:67], v[170:173], v[194:197], v[64:67]
	v_mfma_f32_16x16x32_bf16 v[108:111], v[162:165], v[202:205], v[108:111]
	v_mfma_f32_16x16x32_bf16 v[96:99], v[170:173], v[202:205], v[96:99]
	v_mfma_f32_16x16x32_bf16 v[24:27], v[166:169], v[182:185], v[24:27]
	v_mfma_f32_16x16x32_bf16 v[16:19], v[174:177], v[182:185], v[16:19]
	v_mfma_f32_16x16x32_bf16 v[56:59], v[166:169], v[190:193], v[56:59]
	v_mfma_f32_16x16x32_bf16 v[48:51], v[174:177], v[190:193], v[48:51]
	v_mfma_f32_16x16x32_bf16 v[72:75], v[166:169], v[198:201], v[72:75]
	v_mfma_f32_16x16x32_bf16 v[64:67], v[174:177], v[198:201], v[64:67]
	v_mfma_f32_16x16x32_bf16 v[108:111], v[166:169], v[206:209], v[108:111]
	v_mfma_f32_16x16x32_bf16 v[96:99], v[174:177], v[206:209], v[96:99]
	s_barrier
	s_setprio 0
	s_mov_b32 m0, s47
	v_lshl_add_u64 v[210:211], s[64:65], 0, v[34:35]
	s_add_u32 s56, s64, 0x80000
	ds_read_b128 v[178:181], v142 offset:16384
	ds_read_b128 v[182:185], v142 offset:17408
	ds_read_b128 v[186:189], v142 offset:18432
	ds_read_b128 v[190:193], v142 offset:19456
	ds_read_b128 v[194:197], v142 offset:20480
	ds_read_b128 v[198:201], v142 offset:21504
	ds_read_b128 v[202:205], v142 offset:22528
	ds_read_b128 v[206:209], v142 offset:23552
	global_load_lds_dwordx4 v34, s[64:65]
	v_lshl_add_u64 v[212:213], s[64:65], 0, v[134:135]
	s_mov_b32 m0, s48
	s_addc_u32 s57, s65, 0
	global_load_lds_dwordx4 v134, s[64:65]
	v_lshl_add_u64 v[214:215], s[56:57], 0, v[34:35]
	s_mov_b32 m0, s49
	v_lshl_add_u64 v[216:217], s[66:67], 0, v[132:133]
	global_load_lds_dwordx4 v34, s[56:57]
	v_lshl_add_u64 v[214:215], s[56:57], 0, v[134:135]
	s_mov_b32 m0, s50
	s_nop 0
	global_load_lds_dwordx4 v134, s[56:57]
	v_lshl_add_u64 v[214:215], s[66:67], 0, v[32:33]
	s_mov_b32 m0, s14
	s_nop 0
	global_load_lds_dwordx4 v32, s[66:67]
	s_mov_b32 m0, s15
	s_nop 0
	global_load_lds_dwordx4 v132, s[66:67]
	s_waitcnt vmcnt(8) lgkmcnt(0)
	s_setprio 1
	s_barrier
	v_mfma_f32_16x16x32_bf16 v[100:103], v[146:149], v[178:181], v[100:103]
	v_mfma_f32_16x16x32_bf16 v[104:107], v[154:157], v[178:181], v[104:107]
	v_mfma_f32_16x16x32_bf16 v[116:119], v[146:149], v[186:189], v[116:119]
	v_mfma_f32_16x16x32_bf16 v[120:123], v[154:157], v[186:189], v[120:123]
	v_mfma_f32_16x16x32_bf16 v[84:87], v[146:149], v[194:197], v[84:87]
	v_mfma_f32_16x16x32_bf16 v[80:83], v[154:157], v[194:197], v[80:83]
	v_mfma_f32_16x16x32_bf16 v[36:39], v[146:149], v[202:205], v[36:39]
	v_mfma_f32_16x16x32_bf16 v[28:31], v[154:157], v[202:205], v[28:31]
	v_mfma_f32_16x16x32_bf16 v[100:103], v[150:153], v[182:185], v[100:103]
	v_mfma_f32_16x16x32_bf16 v[104:107], v[158:161], v[182:185], v[104:107]
	v_mfma_f32_16x16x32_bf16 v[116:119], v[150:153], v[190:193], v[116:119]
	v_mfma_f32_16x16x32_bf16 v[120:123], v[158:161], v[190:193], v[120:123]
	v_mfma_f32_16x16x32_bf16 v[84:87], v[150:153], v[198:201], v[84:87]
	v_mfma_f32_16x16x32_bf16 v[80:83], v[158:161], v[198:201], v[80:83]
	v_mfma_f32_16x16x32_bf16 v[36:39], v[150:153], v[206:209], v[36:39]
	v_mfma_f32_16x16x32_bf16 v[28:31], v[158:161], v[206:209], v[28:31]
	s_setprio 0
	s_setprio 1
	v_mfma_f32_16x16x32_bf16 v[124:127], v[162:165], v[178:181], v[124:127]
	v_mfma_f32_16x16x32_bf16 v[112:115], v[170:173], v[178:181], v[112:115]
	v_mfma_f32_16x16x32_bf16 v[92:95], v[162:165], v[186:189], v[92:95]
	v_mfma_f32_16x16x32_bf16 v[88:91], v[170:173], v[186:189], v[88:91]
	v_mfma_f32_16x16x32_bf16 v[44:47], v[162:165], v[194:197], v[44:47]
	v_mfma_f32_16x16x32_bf16 v[40:43], v[170:173], v[194:197], v[40:43]
	v_mfma_f32_16x16x32_bf16 v[4:7], v[162:165], v[202:205], v[4:7]
	v_mfma_f32_16x16x32_bf16 v[0:3], v[170:173], v[202:205], v[0:3]
	v_mfma_f32_16x16x32_bf16 v[124:127], v[166:169], v[182:185], v[124:127]
	v_mfma_f32_16x16x32_bf16 v[112:115], v[174:177], v[182:185], v[112:115]
	v_mfma_f32_16x16x32_bf16 v[92:95], v[166:169], v[190:193], v[92:95]
	v_mfma_f32_16x16x32_bf16 v[88:91], v[174:177], v[190:193], v[88:91]
	v_mfma_f32_16x16x32_bf16 v[44:47], v[166:169], v[198:201], v[44:47]
	v_mfma_f32_16x16x32_bf16 v[40:43], v[174:177], v[198:201], v[40:43]
	v_mfma_f32_16x16x32_bf16 v[4:7], v[166:169], v[206:209], v[4:7]
	v_mfma_f32_16x16x32_bf16 v[0:3], v[174:177], v[206:209], v[0:3]
	s_barrier
	s_setprio 0
	ds_read_b128 v[146:149], v143
	ds_read_b128 v[150:153], v143 offset:1024
	ds_read_b128 v[154:157], v143 offset:2048
	ds_read_b128 v[158:161], v143 offset:3072
	ds_read_b128 v[162:165], v144
	ds_read_b128 v[166:169], v144 offset:1024
	ds_read_b128 v[170:173], v144 offset:2048
	ds_read_b128 v[174:177], v144 offset:3072
	s_add_u32 s56, s66, 0x80000
	s_addc_u32 s57, s67, 0
	s_mov_b32 m0, s21
	v_lshl_add_u64 v[218:219], s[56:57], 0, v[32:33]
	ds_read_b128 v[178:181], v142 offset:32768
	ds_read_b128 v[182:185], v142 offset:33792
	ds_read_b128 v[186:189], v142 offset:34816
	ds_read_b128 v[190:193], v142 offset:35840
	ds_read_b128 v[194:197], v142 offset:36864
	ds_read_b128 v[198:201], v142 offset:37888
	ds_read_b128 v[202:205], v142 offset:38912
	ds_read_b128 v[206:209], v142 offset:39936
	global_load_lds_dwordx4 v32, s[56:57]
	v_lshl_add_u64 v[218:219], s[56:57], 0, v[132:133]
	s_mov_b32 m0, s22
	s_nop 0
	global_load_lds_dwordx4 v132, s[56:57]
	s_waitcnt vmcnt(8) lgkmcnt(0)
	s_setprio 1
	s_barrier
	v_mfma_f32_16x16x32_bf16 v[8:11], v[146:149], v[178:181], v[8:11]
	v_mfma_f32_16x16x32_bf16 v[12:15], v[154:157], v[178:181], v[12:15]
	v_mfma_f32_16x16x32_bf16 v[60:63], v[146:149], v[186:189], v[60:63]
	v_mfma_f32_16x16x32_bf16 v[20:23], v[154:157], v[186:189], v[20:23]
	v_mfma_f32_16x16x32_bf16 v[76:79], v[146:149], v[194:197], v[76:79]
	v_mfma_f32_16x16x32_bf16 v[52:55], v[154:157], v[194:197], v[52:55]
	v_mfma_f32_16x16x32_bf16 v[128:131], v[146:149], v[202:205], v[128:131]
	v_mfma_f32_16x16x32_bf16 v[68:71], v[154:157], v[202:205], v[68:71]
	v_mfma_f32_16x16x32_bf16 v[8:11], v[150:153], v[182:185], v[8:11]
	v_mfma_f32_16x16x32_bf16 v[12:15], v[158:161], v[182:185], v[12:15]
	v_mfma_f32_16x16x32_bf16 v[60:63], v[150:153], v[190:193], v[60:63]
	v_mfma_f32_16x16x32_bf16 v[20:23], v[158:161], v[190:193], v[20:23]
	v_mfma_f32_16x16x32_bf16 v[76:79], v[150:153], v[198:201], v[76:79]
	v_mfma_f32_16x16x32_bf16 v[52:55], v[158:161], v[198:201], v[52:55]
	v_mfma_f32_16x16x32_bf16 v[128:131], v[150:153], v[206:209], v[128:131]
	v_mfma_f32_16x16x32_bf16 v[68:71], v[158:161], v[206:209], v[68:71]
	s_setprio 0
	s_setprio 1
	v_mfma_f32_16x16x32_bf16 v[24:27], v[162:165], v[178:181], v[24:27]
	v_mfma_f32_16x16x32_bf16 v[16:19], v[170:173], v[178:181], v[16:19]
	v_mfma_f32_16x16x32_bf16 v[56:59], v[162:165], v[186:189], v[56:59]
	v_mfma_f32_16x16x32_bf16 v[48:51], v[170:173], v[186:189], v[48:51]
	v_mfma_f32_16x16x32_bf16 v[72:75], v[162:165], v[194:197], v[72:75]
	v_mfma_f32_16x16x32_bf16 v[64:67], v[170:173], v[194:197], v[64:67]
	v_mfma_f32_16x16x32_bf16 v[108:111], v[162:165], v[202:205], v[108:111]
	v_mfma_f32_16x16x32_bf16 v[96:99], v[170:173], v[202:205], v[96:99]
	v_mfma_f32_16x16x32_bf16 v[24:27], v[166:169], v[182:185], v[24:27]
	v_mfma_f32_16x16x32_bf16 v[16:19], v[174:177], v[182:185], v[16:19]
	v_mfma_f32_16x16x32_bf16 v[56:59], v[166:169], v[190:193], v[56:59]
	v_mfma_f32_16x16x32_bf16 v[48:51], v[174:177], v[190:193], v[48:51]
	v_mfma_f32_16x16x32_bf16 v[72:75], v[166:169], v[198:201], v[72:75]
	v_mfma_f32_16x16x32_bf16 v[64:67], v[174:177], v[198:201], v[64:67]
	v_mfma_f32_16x16x32_bf16 v[108:111], v[166:169], v[206:209], v[108:111]
	v_mfma_f32_16x16x32_bf16 v[96:99], v[174:177], v[206:209], v[96:99]
	s_barrier
; #define PG8_MMA(ai, bj, At, Bt) do { __builtin_amdgcn_s_setprio(1); _Pragma("unroll") for (int m = 0; m < 4; ++m) _Pragma("unroll") for (int n = 0; n < 2; ++n) _Pragma("unroll") for (int k = 0; k < 2; ++k) \
;         acc[ai][bj][m][n] = __builtin_amdgcn_mfma_f32_16x16x32_bf16(Bt[n][k], At[m][k], acc[ai][bj][m][n], 0, 0, 0); __builtin_amdgcn_s_setprio(0); } while (0)
; template <class Epi, class Sched, bool ALIGN_EPI = false, bool SP2 = false, bool A_TILED = false>
; __device__ __forceinline__ void gemm_phase(PG8_LAS unsigned char* lds, const Gemm g, const Sched& S, const Epi& E, const int wave_s) {
;     ...
;         for (int t = PEEL ? 2 : 0; t < nt; t += 2) {
;             const bool last = (t == nt - 2);
;             const char* a1 = cA + (size_t)(t + 1) * kstepA;
;             const char* a2 = last ? nA : cA + (size_t)(t + 2) * kstepA; const char* b2 = last ? nB : cB + (size_t)(t + 2) * kstep;
;             const char* a3 = a2 + kstepA; const char* b3 = b2 + kstep;
;             if (last && has_next) S.a_ready(nxt);
;             if constexpr (SP2) {
;             PG8_ITER(PG8_MMA)
	s_setprio 0
	s_mov_b32 m0, s51
	v_lshl_add_u64 v[210:211], v[210:211], 0, s[60:61]
	s_add_u32 s56, s64, 0x80080
	ds_read_b128 v[178:181], v142 offset:49152
	ds_read_b128 v[182:185], v142 offset:50176
	ds_read_b128 v[186:189], v142 offset:51200
	ds_read_b128 v[190:193], v142 offset:52224
	ds_read_b128 v[194:197], v142 offset:53248
	ds_read_b128 v[198:201], v142 offset:54272
	ds_read_b128 v[202:205], v142 offset:55296
	ds_read_b128 v[206:209], v142 offset:56320
	global_load_lds_dwordx4 v[210:211], off
	v_lshl_add_u64 v[210:211], v[212:213], 0, s[60:61]
	s_mov_b32 m0, s52
	s_addc_u32 s57, s65, 0
	global_load_lds_dwordx4 v[210:211], off
	v_lshl_add_u64 v[210:211], s[56:57], 0, v[34:35]
	s_mov_b32 m0, s53
	s_nop 0
	global_load_lds_dwordx4 v34, s[56:57]
	v_lshl_add_u64 v[210:211], s[56:57], 0, v[134:135]
	s_mov_b32 m0, s54
	s_nop 0
	global_load_lds_dwordx4 v134, s[56:57]
	v_lshl_add_u64 v[210:211], v[214:215], 0, s[60:61]
	s_mov_b32 m0, s23
	s_nop 0
	global_load_lds_dwordx4 v[210:211], off
	v_lshl_add_u64 v[210:211], v[216:217], 0, s[60:61]
	s_mov_b32 m0, s36
	s_nop 0
	global_load_lds_dwordx4 v[210:211], off
	s_waitcnt vmcnt(8) lgkmcnt(0)
	s_setprio 1
	s_barrier
	v_mfma_f32_16x16x32_bf16 v[100:103], v[146:149], v[178:181], v[100:103]
	v_mfma_f32_16x16x32_bf16 v[104:107], v[154:157], v[178:181], v[104:107]
	v_mfma_f32_16x16x32_bf16 v[116:119], v[146:149], v[186:189], v[116:119]
	v_mfma_f32_16x16x32_bf16 v[120:123], v[154:157], v[186:189], v[120:123]
	v_mfma_f32_16x16x32_bf16 v[84:87], v[146:149], v[194:197], v[84:87]
	v_mfma_f32_16x16x32_bf16 v[80:83], v[154:157], v[194:197], v[80:83]
	v_mfma_f32_16x16x32_bf16 v[36:39], v[146:149], v[202:205], v[36:39]
	v_mfma_f32_16x16x32_bf16 v[28:31], v[154:157], v[202:205], v[28:31]
	v_mfma_f32_16x16x32_bf16 v[100:103], v[150:153], v[182:185], v[100:103]
	v_mfma_f32_16x16x32_bf16 v[104:107], v[158:161], v[182:185], v[104:107]
	v_mfma_f32_16x16x32_bf16 v[116:119], v[150:153], v[190:193], v[116:119]
	v_mfma_f32_16x16x32_bf16 v[120:123], v[158:161], v[190:193], v[120:123]
	v_mfma_f32_16x16x32_bf16 v[84:87], v[150:153], v[198:201], v[84:87]
	v_mfma_f32_16x16x32_bf16 v[80:83], v[158:161], v[198:201], v[80:83]
	v_mfma_f32_16x16x32_bf16 v[36:39], v[150:153], v[206:209], v[36:39]
	v_mfma_f32_16x16x32_bf16 v[28:31], v[158:161], v[206:209], v[28:31]
	s_setprio 0
	s_setprio 1
	v_mfma_f32_16x16x32_bf16 v[124:127], v[162:165], v[178:181], v[124:127]
	v_mfma_f32_16x16x32_bf16 v[112:115], v[170:173], v[178:181], v[112:115]
	v_mfma_f32_16x16x32_bf16 v[92:95], v[162:165], v[186:189], v[92:95]
	v_mfma_f32_16x16x32_bf16 v[88:91], v[170:173], v[186:189], v[88:91]
	v_mfma_f32_16x16x32_bf16 v[44:47], v[162:165], v[194:197], v[44:47]
	v_mfma_f32_16x16x32_bf16 v[40:43], v[170:173], v[194:197], v[40:43]
	v_mfma_f32_16x16x32_bf16 v[4:7], v[162:165], v[202:205], v[4:7]
	v_mfma_f32_16x16x32_bf16 v[0:3], v[170:173], v[202:205], v[0:3]
	v_mfma_f32_16x16x32_bf16 v[124:127], v[166:169], v[182:185], v[124:127]
	v_mfma_f32_16x16x32_bf16 v[112:115], v[174:177], v[182:185], v[112:115]
	v_mfma_f32_16x16x32_bf16 v[92:95], v[166:169], v[190:193], v[92:95]
	v_mfma_f32_16x16x32_bf16 v[88:91], v[174:177], v[190:193], v[88:91]
	v_mfma_f32_16x16x32_bf16 v[44:47], v[166:169], v[198:201], v[44:47]
	v_mfma_f32_16x16x32_bf16 v[40:43], v[174:177], v[198:201], v[40:43]
	v_mfma_f32_16x16x32_bf16 v[4:7], v[166:169], v[206:209], v[4:7]
	v_mfma_f32_16x16x32_bf16 v[0:3], v[174:177], v[206:209], v[0:3]
	s_barrier
	s_setprio 0
	s_add_i32 s41, s41, 2
	s_add_u32 s37, s37, 0x100
	s_addc_u32 s38, s38, 0
	s_add_u32 s39, s39, 0x100
	s_addc_u32 s40, s40, 0
	v_lshl_add_u64 v[136:137], v[136:137], 0, s[62:63]
	s_cmp_gt_u32 s41, 29
	v_lshl_add_u64 v[138:139], v[138:139], 0, s[62:63]
	s_cbranch_scc0 .LBB0_2729
	s_waitcnt vmcnt(0)
	s_cmpk_lt_u32 s0, 0x100
	s_cbranch_scc0 .LBB0_2732
	s_barrier

; #define PG8_STAGE(bufoff, gbase, voff) do { _Pragma("unroll") for (int _i = 0; _i < 2; ++_i) \
;         __builtin_amdgcn_global_load_lds((const unsigned*)((const char*)(gbase) + (voff)[_i]), (PG8_LAS unsigned*)(lds + (bufoff) + ldsw + _i * 8192), 16, 0, 0); } while (0)
; #define PG8_WAIT_V(n) asm volatile("s_waitcnt vmcnt(" #n ")" ::: "memory")
; #define PG8_BAR __builtin_amdgcn_s_barrier()
; template <class Epi, class Sched, bool ALIGN_EPI = false, bool SP2 = false, bool A_TILED = false>
; __device__ __forceinline__ void gemm_phase(PG8_LAS unsigned char* lds, const Gemm g, const Sched& S, const Epi& E, const int wave_s) {
;     ...
;     unsigned voffA[2], voffB[2];
; #pragma unroll
;     for (int i = 0; i < 2; ++i) { int R, C; stage_rc(tid * 16 + i * 8192, R, C); const int Rb = Epi::PERM ? ((R & ~31) + perm32(R & 31)) : R;
;         voffA[i] = A_TILED ? (unsigned)(tid * 16 + i * 8192) : (unsigned)(R * K + C) * 2u; voffB[i] = (unsigned)(Rb * K + C) * 2u; }
;     const size_t kstep = (size_t)(BK * 2);
;     const size_t hstep = (size_t)HALF * K * 2;
;     const size_t tstep = 2 * hstep;
;     const size_t kstepA = A_TILED ? (size_t)32768 : kstep, hstepA = A_TILED ? (size_t)16384 : hstep, tstepA = A_TILED ? (size_t)nt * 32768 : tstep;
;     const unsigned ldsw = (unsigned)wid * 1024u;
;     const int aoff = lds_byte(wr * 64 + fr, fq * 8), boff = lds_byte(wc * 32 + fr, fq * 8);
;     ...
;     if constexpr (SP2) {
;         PG8_STAGE(PG8_SB(0, 0), cB, voffB); PG8_STAGE(PG8_SB(0, 1), cB + hstep, voffB); PG8_STAGE(PG8_SA(0, 0), cA, voffA); PG8_STAGE(PG8_SA(0, 1), cA + hstepA, voffA);
;         if (wr == 1) PG8_BAR;
;         PG8_WAIT_V(2); PG8_BAR;
;         PG8_STAGE(PG8_SB(1, 0), cB + kstep, voffB); PG8_STAGE(PG8_SA(1, 0), cA + kstepA, voffA); PG8_STAGE(PG8_SB(1, 1), cB + hstep + kstep, voffB);
;         PG8_WAIT_V(6); PG8_BAR;
;     } else {
;         PG8_STAGE(PG8_SB(0, 0), cB, voffB); PG8_STAGE(PG8_SA(0, 0), cA, voffA); PG8_STAGE(PG8_SB(0, 1), cB + hstep, voffB); PG8_STAGE(PG8_SA(0, 1), cA + hstepA, voffA);
;         if (wr == 1) PG8_BAR;
;         PG8_WAIT_V(4); PG8_BAR;
;         PG8_STAGE(PG8_SB(1, 0), cB + kstep, voffB); PG8_STAGE(PG8_SA(1, 0), cA + kstepA, voffA); PG8_STAGE(PG8_SB(1, 1), cB + hstep + kstep, voffB);
;         PG8_WAIT_V(6); PG8_BAR;
.LBB0_2831:
	s_ashr_i32 s40, s86, 31
	s_add_u32 s41, s2, 0x34600000
	s_addc_u32 s42, s3, 0
	s_lshl_b32 s47, s12, 13
	s_mov_b64 s[12:13], 0x80
	s_and_b32 s2, s46, 3
	s_add_i32 m0, s22, 0x18000
	v_lshl_add_u64 v[6:7], v[6:7], 0, s[12:13]
	s_lshl_b32 s49, s2, 12
	s_waitcnt vmcnt(2)
	s_barrier
	global_load_lds_dwordx4 v[6:7], off
	v_lshl_add_u64 v[4:5], v[4:5], 0, s[12:13]
	s_add_i32 m0, s22, 0x1a000
	s_add_i32 s43, s22, 0x8000
	s_add_i32 s48, s22, 0xa000
	global_load_lds_dwordx4 v[4:5], off
	v_lshl_add_u64 v[0:1], v[0:1], 0, s[12:13]
	s_mov_b32 m0, s43
	s_add_u32 s2, s72, 0x80080
	global_load_lds_dwordx4 v[0:1], off
	v_lshl_add_u64 v[0:1], v[2:3], 0, s[12:13]
	s_mov_b32 m0, s48
	s_addc_u32 s3, s73, 0
	global_load_lds_dwordx4 v[0:1], off
	s_add_i32 m0, s22, 0x1c000
	v_lshl_add_u64 v[0:1], s[2:3], 0, v[128:129]
	global_load_lds_dwordx4 v128, s[2:3]
	v_lshl_add_u64 v[0:1], s[2:3], 0, v[130:131]
	s_add_i32 m0, s22, 0x1e000
	s_cmpk_lt_u32 s45, 0x100
	global_load_lds_dwordx4 v130, s[2:3]
	v_and_b32_e32 v0, 15, v8
	v_and_b32_e32 v1, 48, v8
	v_lshl_or_b32 v0, v0, 6, v1
	v_lshlrev_b32_e32 v1, 2, v8
	v_and_b32_e32 v1, 32, v1
	v_bitop3_b32 v2, v0, s47, v1 bitop3:0xde
	v_bitop3_b32 v144, v0, s49, v1 bitop3:0xde
	v_lshlrev_b32_e32 v0, 15, v9
	v_and_b32_e32 v0, 0xffff0000, v0
	v_lshl_add_u32 v0, v10, 12, v0
	v_and_b32_e32 v1, 1, v9
	v_lshl_or_b32 v0, v1, 6, v0
	v_lshl_add_u32 v136, v11, 1, v0
	v_lshlrev_b32_e32 v0, 15, v13
	v_and_b32_e32 v0, 0xffff0000, v0
	s_waitcnt vmcnt(6)
	v_lshl_add_u32 v0, v12, 12, v0
	v_and_b32_e32 v1, 1, v13
	s_sext_i32_i16 s53, s44
	s_cselect_b64 s[44:45], -1, 0
	s_and_b32 s2, s15, 0x400
	v_mov_b32_e32 v137, 0
	v_lshl_or_b32 v0, v1, 6, v0
	s_add_i32 s51, 0, 0x10000
	s_add_i32 s52, 0, 0x14000
	s_bfe_u32 s49, s46, 0x10001
	s_or_b32 s50, s2, s47
	v_lshl_add_u32 v138, v14, 1, v0
	v_mov_b32_e32 v139, v137
	v_mov_b64_e32 v[140:141], 0x200
	v_mov_b64_e32 v[142:143], 0x1ff
	v_add_u32_e32 v145, s51, v144
	v_add_u32_e32 v146, s52, v144
	v_add_u32_e32 v147, 0, v2
	s_mov_b64 s[46:47], 0x100
	s_mov_b64 s[60:61], 0x180
	s_barrier
	s_branch .LBB0_2834

; template <class Epi, class Sched, bool ALIGN_EPI = false, bool SP2 = false, bool A_TILED = false>
; __device__ __forceinline__ void gemm_phase(PG8_LAS unsigned char* lds, const Gemm g, const Sched& S, const Epi& E, const int wave_s) {
;     ...
;         const bool has_next = Epi::AFTER_DRAIN ? false : S.next(ui + 1, nxt);
;         const char* nA = has_next ? (const char*)g.A + (size_t)nxt.pm * tstepA : cA; const char* nB = has_next ? (const char*)g.Bt + (size_t)nxt.pn * tstep : cB;
;         constexpr bool PEEL = SP2 && !Epi::AFTER_DRAIN;
;         if constexpr (PEEL) {
;             const char* a1 = cA + kstepA; const char* a2 = cA + 2 * kstepA; const char* b2 = cB + 2 * kstep; const char* a3 = a2 + kstepA; const char* b3 = b2 + kstep;
;             PG8_ITER(PG8_MMAZ)
.LBB0_2840:
	s_ashr_i32 s65, s64, 31
	s_lshl_b64 s[54:55], s[64:65], 20
	s_add_u32 s66, s1, s54
	ds_read_b128 v[0:3], v145
	ds_read_b128 v[4:7], v145 offset:1024
	ds_read_b128 v[8:11], v145 offset:2048
	ds_read_b128 v[12:15], v145 offset:3072
	ds_read_b128 v[16:19], v146
	ds_read_b128 v[20:23], v146 offset:1024
	ds_read_b128 v[24:27], v146 offset:2048
	ds_read_b128 v[28:31], v146 offset:3072
	s_addc_u32 s67, s8, s55
	s_ashr_i32 s63, s62, 31
	s_lshl_b64 s[54:55], s[62:63], 20
	s_add_u32 s68, s9, s54
	s_addc_u32 s69, s14, s55
	s_and_b64 s[54:55], s[2:3], exec
	s_cselect_b32 s54, s67, s75
	s_cselect_b32 s55, s66, s74
	s_cselect_b32 s56, s69, s73
	s_cselect_b32 s57, s68, s72
	s_add_u32 s76, s74, 0x80080
	s_addc_u32 s77, s75, 0
	s_add_i32 s58, s22, 0xc000
	v_lshl_add_u64 v[64:65], s[76:77], 0, v[134:135]
	s_mov_b32 m0, s58
	s_add_i32 s59, s22, 0xe000
	ds_read_b128 v[32:35], v147
	ds_read_b128 v[36:39], v147 offset:1024
	ds_read_b128 v[40:43], v147 offset:2048
	ds_read_b128 v[44:47], v147 offset:3072
	ds_read_b128 v[48:51], v147 offset:4096
	ds_read_b128 v[52:55], v147 offset:5120
	ds_read_b128 v[56:59], v147 offset:6144
	ds_read_b128 v[60:63], v147 offset:7168
	global_load_lds_dwordx4 v134, s[76:77]
	v_lshl_add_u64 v[64:65], s[76:77], 0, v[132:133]
	s_mov_b32 m0, s59
	s_nop 0
	global_load_lds_dwordx4 v132, s[76:77]
	s_waitcnt vmcnt(8) lgkmcnt(0)
	s_setprio 1
	s_barrier
	v_mfma_f32_16x16x32_bf16 v[88:91], v[0:3], v[56:59], 0
	v_mfma_f32_16x16x32_bf16 v[64:67], v[0:3], v[32:35], 0
	v_mfma_f32_16x16x32_bf16 v[68:71], v[8:11], v[32:35], 0
	v_mfma_f32_16x16x32_bf16 v[72:75], v[0:3], v[40:43], 0
	v_mfma_f32_16x16x32_bf16 v[76:79], v[8:11], v[40:43], 0
	v_mfma_f32_16x16x32_bf16 v[80:83], v[0:3], v[48:51], 0
	v_mfma_f32_16x16x32_bf16 v[84:87], v[8:11], v[48:51], 0
	v_mfma_f32_16x16x32_bf16 v[96:99], v[4:7], v[60:63], v[88:91]
	v_mfma_f32_16x16x32_bf16 v[88:91], v[8:11], v[56:59], 0
	v_mfma_f32_16x16x32_bf16 v[64:67], v[4:7], v[36:39], v[64:67]
	v_mfma_f32_16x16x32_bf16 v[68:71], v[12:15], v[36:39], v[68:71]
	v_mfma_f32_16x16x32_bf16 v[72:75], v[4:7], v[44:47], v[72:75]
	v_mfma_f32_16x16x32_bf16 v[76:79], v[12:15], v[44:47], v[76:79]
	v_mfma_f32_16x16x32_bf16 v[80:83], v[4:7], v[52:55], v[80:83]
	v_mfma_f32_16x16x32_bf16 v[84:87], v[12:15], v[52:55], v[84:87]
	v_mfma_f32_16x16x32_bf16 v[100:103], v[12:15], v[60:63], v[88:91]
	s_setprio 0
	s_setprio 1
	v_mfma_f32_16x16x32_bf16 v[88:91], v[16:19], v[32:35], 0
	v_mfma_f32_16x16x32_bf16 v[32:35], v[24:27], v[32:35], 0
	v_mfma_f32_16x16x32_bf16 v[112:115], v[20:23], v[36:39], v[88:91]
	v_mfma_f32_16x16x32_bf16 v[32:35], v[28:31], v[36:39], v[32:35]
	v_mfma_f32_16x16x32_bf16 v[36:39], v[16:19], v[40:43], 0
	v_mfma_f32_16x16x32_bf16 v[40:43], v[24:27], v[40:43], 0
	v_mfma_f32_16x16x32_bf16 v[36:39], v[20:23], v[44:47], v[36:39]
	v_mfma_f32_16x16x32_bf16 v[40:43], v[28:31], v[44:47], v[40:43]
	v_mfma_f32_16x16x32_bf16 v[44:47], v[16:19], v[48:51], 0
	v_mfma_f32_16x16x32_bf16 v[48:51], v[24:27], v[48:51], 0
	v_mfma_f32_16x16x32_bf16 v[44:47], v[20:23], v[52:55], v[44:47]
	v_mfma_f32_16x16x32_bf16 v[48:51], v[28:31], v[52:55], v[48:51]
	v_mfma_f32_16x16x32_bf16 v[52:55], v[16:19], v[56:59], 0
	v_mfma_f32_16x16x32_bf16 v[56:59], v[24:27], v[56:59], 0
	v_mfma_f32_16x16x32_bf16 v[52:55], v[20:23], v[60:63], v[52:55]
	v_mfma_f32_16x16x32_bf16 v[56:59], v[28:31], v[60:63], v[56:59]
	s_barrier
	s_setprio 0
	s_add_i32 s63, s51, s15
	v_lshl_add_u64 v[242:243], s[72:73], 0, v[128:129]
	s_add_i32 s65, s63, 0x2000
	v_lshl_add_u64 v[148:149], v[242:243], 0, s[46:47]
	s_mov_b32 m0, s63
	v_lshl_add_u64 v[244:245], s[72:73], 0, v[130:131]
	s_add_u32 s76, s72, 0x80100
	ds_read_b128 v[60:63], v147 offset:16384
	ds_read_b128 v[88:91], v147 offset:17408
	ds_read_b128 v[92:95], v147 offset:18432
	ds_read_b128 v[104:107], v147 offset:19456
	ds_read_b128 v[108:111], v147 offset:20480
	ds_read_b128 v[116:119], v147 offset:21504
	ds_read_b128 v[120:123], v147 offset:22528
	ds_read_b128 v[124:127], v147 offset:23552
	global_load_lds_dwordx4 v[148:149], off
	v_lshl_add_u64 v[148:149], v[244:245], 0, s[46:47]
	s_mov_b32 m0, s65
	s_addc_u32 s77, s73, 0
	s_add_i32 s71, s52, s15
	global_load_lds_dwordx4 v[148:149], off
	v_lshl_add_u64 v[148:149], s[76:77], 0, v[128:129]
	s_mov_b32 m0, s71
	s_add_i32 s78, s71, 0x2000
	global_load_lds_dwordx4 v128, s[76:77]
	v_lshl_add_u64 v[148:149], s[76:77], 0, v[130:131]
	s_mov_b32 m0, s78
	v_lshl_add_u64 v[246:247], s[74:75], 0, v[134:135]
	global_load_lds_dwordx4 v130, s[76:77]
	v_lshl_add_u64 v[148:149], v[246:247], 0, s[46:47]
	s_mov_b32 m0, s22
	v_lshl_add_u64 v[248:249], s[74:75], 0, v[132:133]
	global_load_lds_dwordx4 v[148:149], off
	v_lshl_add_u64 v[148:149], v[248:249], 0, s[46:47]
	s_mov_b32 m0, s23
	s_nop 0
	global_load_lds_dwordx4 v[148:149], off
	s_waitcnt vmcnt(8) lgkmcnt(0)
	s_setprio 1
	s_barrier
	v_mfma_f32_16x16x32_bf16 v[148:151], v[0:3], v[60:63], 0
	v_mfma_f32_16x16x32_bf16 v[158:161], v[0:3], v[92:95], 0
	v_mfma_f32_16x16x32_bf16 v[166:169], v[0:3], v[108:111], 0
	v_mfma_f32_16x16x32_bf16 v[0:3], v[0:3], v[120:123], 0
	v_mfma_f32_16x16x32_bf16 v[150:153], v[4:7], v[88:91], v[148:151]
	v_mfma_f32_16x16x32_bf16 v[158:161], v[4:7], v[104:107], v[158:161]
	v_mfma_f32_16x16x32_bf16 v[166:169], v[4:7], v[116:119], v[166:169]
	v_mfma_f32_16x16x32_bf16 v[0:3], v[4:7], v[124:127], v[0:3]
	v_mfma_f32_16x16x32_bf16 v[4:7], v[8:11], v[120:123], 0
	v_mfma_f32_16x16x32_bf16 v[154:157], v[8:11], v[60:63], 0
	v_mfma_f32_16x16x32_bf16 v[162:165], v[8:11], v[92:95], 0
	v_mfma_f32_16x16x32_bf16 v[170:173], v[8:11], v[108:111], 0
	v_mfma_f32_16x16x32_bf16 v[4:7], v[12:15], v[124:127], v[4:7]
	v_mfma_f32_16x16x32_bf16 v[154:157], v[12:15], v[88:91], v[154:157]
	v_mfma_f32_16x16x32_bf16 v[162:165], v[12:15], v[104:107], v[162:165]
	v_mfma_f32_16x16x32_bf16 v[170:173], v[12:15], v[116:119], v[170:173]
	s_setprio 0
	s_setprio 1
	v_mfma_f32_16x16x32_bf16 v[8:11], v[16:19], v[60:63], 0
	v_mfma_f32_16x16x32_bf16 v[174:177], v[20:23], v[88:91], v[8:11]
	v_mfma_f32_16x16x32_bf16 v[8:11], v[24:27], v[60:63], 0
	v_mfma_f32_16x16x32_bf16 v[60:63], v[28:31], v[88:91], v[8:11]
	v_mfma_f32_16x16x32_bf16 v[8:11], v[16:19], v[92:95], 0
	v_mfma_f32_16x16x32_bf16 v[178:181], v[20:23], v[104:107], v[8:11]
	v_mfma_f32_16x16x32_bf16 v[8:11], v[24:27], v[92:95], 0
	v_mfma_f32_16x16x32_bf16 v[182:185], v[28:31], v[104:107], v[8:11]
	v_mfma_f32_16x16x32_bf16 v[8:11], v[16:19], v[108:111], 0
	v_mfma_f32_16x16x32_bf16 v[186:189], v[20:23], v[116:119], v[8:11]
	v_mfma_f32_16x16x32_bf16 v[8:11], v[24:27], v[108:111], 0
	v_mfma_f32_16x16x32_bf16 v[190:193], v[28:31], v[116:119], v[8:11]
	v_mfma_f32_16x16x32_bf16 v[8:11], v[16:19], v[120:123], 0
	v_mfma_f32_16x16x32_bf16 v[194:197], v[20:23], v[124:127], v[8:11]
	v_mfma_f32_16x16x32_bf16 v[8:11], v[24:27], v[120:123], 0
	v_mfma_f32_16x16x32_bf16 v[198:201], v[28:31], v[124:127], v[8:11]
	s_barrier
	s_setprio 0
	s_add_i32 s79, 0, 0x18000
	s_add_i32 s81, 0, 0x1c000
	v_add_u32_e32 v148, s79, v144
	v_add_u32_e32 v149, s81, v144
	s_nop 0
	ds_read_b128 v[8:11], v148
	ds_read_b128 v[12:15], v148 offset:1024
	ds_read_b128 v[16:19], v148 offset:2048
	ds_read_b128 v[20:23], v148 offset:3072
	ds_read_b128 v[202:205], v149
	ds_read_b128 v[206:209], v149 offset:1024
	ds_read_b128 v[210:213], v149 offset:2048
	ds_read_b128 v[214:217], v149 offset:3072
	s_add_u32 s76, s74, 0x80100
	s_addc_u32 s77, s75, 0
	s_mov_b32 m0, s36
	v_lshl_add_u64 v[88:89], s[76:77], 0, v[134:135]
	ds_read_b128 v[24:27], v147 offset:32768
	ds_read_b128 v[28:31], v147 offset:33792
	ds_read_b128 v[218:221], v147 offset:34816
	ds_read_b128 v[222:225], v147 offset:35840
	ds_read_b128 v[226:229], v147 offset:36864
	ds_read_b128 v[230:233], v147 offset:37888
	ds_read_b128 v[234:237], v147 offset:38912
	ds_read_b128 v[238:241], v147 offset:39936
	global_load_lds_dwordx4 v134, s[76:77]
	v_lshl_add_u64 v[88:89], s[76:77], 0, v[132:133]
	s_mov_b32 m0, s37
	s_nop 0
	global_load_lds_dwordx4 v132, s[76:77]
	s_waitcnt vmcnt(8) lgkmcnt(0)
	s_setprio 1
	s_barrier
	v_mfma_f32_16x16x32_bf16 v[64:67], v[8:11], v[24:27], v[64:67]
	v_mfma_f32_16x16x32_bf16 v[120:123], v[12:15], v[28:31], v[64:67]
	v_mfma_f32_16x16x32_bf16 v[64:67], v[16:19], v[24:27], v[68:71]
	v_mfma_f32_16x16x32_bf16 v[124:127], v[20:23], v[28:31], v[64:67]
	v_mfma_f32_16x16x32_bf16 v[64:67], v[8:11], v[218:221], v[72:75]
	v_mfma_f32_16x16x32_bf16 v[104:107], v[12:15], v[222:225], v[64:67]
	v_mfma_f32_16x16x32_bf16 v[64:67], v[16:19], v[218:221], v[76:79]
	v_mfma_f32_16x16x32_bf16 v[108:111], v[20:23], v[222:225], v[64:67]
	v_mfma_f32_16x16x32_bf16 v[64:67], v[8:11], v[226:229], v[80:83]
	v_mfma_f32_16x16x32_bf16 v[88:91], v[12:15], v[230:233], v[64:67]
	v_mfma_f32_16x16x32_bf16 v[64:67], v[16:19], v[226:229], v[84:87]
	v_mfma_f32_16x16x32_bf16 v[92:95], v[20:23], v[230:233], v[64:67]
	v_mfma_f32_16x16x32_bf16 v[64:67], v[8:11], v[234:237], v[96:99]
	v_mfma_f32_16x16x32_bf16 v[68:71], v[16:19], v[234:237], v[100:103]
	v_mfma_f32_16x16x32_bf16 v[64:67], v[12:15], v[238:241], v[64:67]
	v_mfma_f32_16x16x32_bf16 v[68:71], v[20:23], v[238:241], v[68:71]
	s_setprio 0
	s_setprio 1
	v_mfma_f32_16x16x32_bf16 v[72:75], v[202:205], v[24:27], v[112:115]
	v_mfma_f32_16x16x32_bf16 v[24:27], v[210:213], v[24:27], v[32:35]
	v_mfma_f32_16x16x32_bf16 v[116:119], v[214:217], v[28:31], v[24:27]
	v_mfma_f32_16x16x32_bf16 v[24:27], v[202:205], v[218:221], v[36:39]
	v_mfma_f32_16x16x32_bf16 v[96:99], v[206:209], v[222:225], v[24:27]
	v_mfma_f32_16x16x32_bf16 v[24:27], v[210:213], v[218:221], v[40:43]
	v_mfma_f32_16x16x32_bf16 v[100:103], v[214:217], v[222:225], v[24:27]
	v_mfma_f32_16x16x32_bf16 v[24:27], v[202:205], v[226:229], v[44:47]
	v_mfma_f32_16x16x32_bf16 v[80:83], v[206:209], v[230:233], v[24:27]
	v_mfma_f32_16x16x32_bf16 v[24:27], v[210:213], v[226:229], v[48:51]
	v_mfma_f32_16x16x32_bf16 v[84:87], v[214:217], v[230:233], v[24:27]
	v_mfma_f32_16x16x32_bf16 v[24:27], v[202:205], v[234:237], v[52:55]
	v_mfma_f32_16x16x32_bf16 v[48:51], v[206:209], v[238:241], v[24:27]
	v_mfma_f32_16x16x32_bf16 v[24:27], v[210:213], v[234:237], v[56:59]
	v_mfma_f32_16x16x32_bf16 v[112:115], v[206:209], v[28:31], v[72:75]
	v_mfma_f32_16x16x32_bf16 v[52:55], v[214:217], v[238:241], v[24:27]
	s_barrier
; #define PG8_MMA(ai, bj, At, Bt) do { __builtin_amdgcn_s_setprio(1); _Pragma("unroll") for (int m = 0; m < 4; ++m) _Pragma("unroll") for (int n = 0; n < 2; ++n) _Pragma("unroll") for (int k = 0; k < 2; ++k) \
;         acc[ai][bj][m][n] = __builtin_amdgcn_mfma_f32_16x16x32_bf16(Bt[n][k], At[m][k], acc[ai][bj][m][n], 0, 0, 0); __builtin_amdgcn_s_setprio(0); } while (0)
; template <class Epi, class Sched, bool ALIGN_EPI = false, bool SP2 = false, bool A_TILED = false>
; __device__ __forceinline__ void gemm_phase(PG8_LAS unsigned char* lds, const Gemm g, const Sched& S, const Epi& E, const int wave_s) {
;     ...
;         for (int t = PEEL ? 2 : 0; t < nt; t += 2) {
;             const bool last = (t == nt - 2);
;             const char* a1 = cA + (size_t)(t + 1) * kstepA;
;             const char* a2 = last ? nA : cA + (size_t)(t + 2) * kstepA; const char* b2 = last ? nB : cB + (size_t)(t + 2) * kstep;
;             const char* a3 = a2 + kstepA; const char* b3 = b2 + kstep;
;             if (last && has_next) S.a_ready(nxt);
;             if constexpr (SP2) {
;             PG8_ITER(PG8_MMA)
	s_setprio 0
	s_add_i32 s79, s79, s15
	s_add_i32 s80, s79, 0x2000
	s_nop 1
	v_lshl_add_u64 v[24:25], v[242:243], 0, s[60:61]
	s_mov_b32 m0, s79
	s_add_u32 s76, s72, 0x80180
	ds_read_b128 v[32:35], v147 offset:49152
	ds_read_b128 v[36:39], v147 offset:50176
	ds_read_b128 v[218:221], v147 offset:51200
	ds_read_b128 v[222:225], v147 offset:52224
	ds_read_b128 v[226:229], v147 offset:53248
	ds_read_b128 v[230:233], v147 offset:54272
	ds_read_b128 v[234:237], v147 offset:55296
	ds_read_b128 v[238:241], v147 offset:56320
	global_load_lds_dwordx4 v[24:25], off
	v_lshl_add_u64 v[24:25], v[244:245], 0, s[60:61]
	s_mov_b32 m0, s80
	s_addc_u32 s77, s73, 0
	s_add_i32 s81, s81, s15
	global_load_lds_dwordx4 v[24:25], off
	v_lshl_add_u64 v[24:25], s[76:77], 0, v[128:129]
	s_mov_b32 m0, s81
	s_add_i32 s82, s81, 0x2000
	global_load_lds_dwordx4 v128, s[76:77]
	v_lshl_add_u64 v[24:25], s[76:77], 0, v[130:131]
	s_mov_b32 m0, s82
	s_nop 0
	global_load_lds_dwordx4 v130, s[76:77]
	v_lshl_add_u64 v[24:25], v[246:247], 0, s[60:61]
	s_mov_b32 m0, s43
	s_nop 0
	global_load_lds_dwordx4 v[24:25], off
	v_lshl_add_u64 v[24:25], v[248:249], 0, s[60:61]
	s_mov_b32 m0, s48
	s_nop 0
	global_load_lds_dwordx4 v[24:25], off
	s_waitcnt vmcnt(8) lgkmcnt(0)
	s_setprio 1
	s_barrier
	v_mfma_f32_16x16x32_bf16 v[24:27], v[8:11], v[32:35], v[150:153]
	v_mfma_f32_16x16x32_bf16 v[72:75], v[12:15], v[36:39], v[24:27]
	v_mfma_f32_16x16x32_bf16 v[24:27], v[16:19], v[32:35], v[154:157]
	v_mfma_f32_16x16x32_bf16 v[76:79], v[20:23], v[36:39], v[24:27]
	v_mfma_f32_16x16x32_bf16 v[24:27], v[8:11], v[218:221], v[158:161]
	v_mfma_f32_16x16x32_bf16 v[40:43], v[12:15], v[222:225], v[24:27]
	v_mfma_f32_16x16x32_bf16 v[24:27], v[16:19], v[218:221], v[162:165]
	v_mfma_f32_16x16x32_bf16 v[0:3], v[8:11], v[234:237], v[0:3]
	v_mfma_f32_16x16x32_bf16 v[44:47], v[20:23], v[222:225], v[24:27]
	v_mfma_f32_16x16x32_bf16 v[24:27], v[8:11], v[226:229], v[166:169]
	v_mfma_f32_16x16x32_bf16 v[28:31], v[16:19], v[226:229], v[170:173]
	v_mfma_f32_16x16x32_bf16 v[8:11], v[12:15], v[238:241], v[0:3]
	v_mfma_f32_16x16x32_bf16 v[0:3], v[16:19], v[234:237], v[4:7]
	v_mfma_f32_16x16x32_bf16 v[24:27], v[12:15], v[230:233], v[24:27]
	v_mfma_f32_16x16x32_bf16 v[28:31], v[20:23], v[230:233], v[28:31]
	v_mfma_f32_16x16x32_bf16 v[12:15], v[20:23], v[238:241], v[0:3]
	s_setprio 0
	s_setprio 1
	v_mfma_f32_16x16x32_bf16 v[0:3], v[202:205], v[32:35], v[174:177]
	v_mfma_f32_16x16x32_bf16 v[56:59], v[206:209], v[36:39], v[0:3]
	v_mfma_f32_16x16x32_bf16 v[0:3], v[210:213], v[32:35], v[60:63]
	v_mfma_f32_16x16x32_bf16 v[60:63], v[214:217], v[36:39], v[0:3]
	v_mfma_f32_16x16x32_bf16 v[0:3], v[202:205], v[218:221], v[178:181]
	v_mfma_f32_16x16x32_bf16 v[32:35], v[206:209], v[222:225], v[0:3]
	v_mfma_f32_16x16x32_bf16 v[0:3], v[210:213], v[218:221], v[182:185]
	v_mfma_f32_16x16x32_bf16 v[36:39], v[214:217], v[222:225], v[0:3]
	v_mfma_f32_16x16x32_bf16 v[0:3], v[202:205], v[226:229], v[186:189]
	v_mfma_f32_16x16x32_bf16 v[16:19], v[206:209], v[230:233], v[0:3]
	v_mfma_f32_16x16x32_bf16 v[0:3], v[210:213], v[226:229], v[190:193]
	v_mfma_f32_16x16x32_bf16 v[20:23], v[214:217], v[230:233], v[0:3]
	v_mfma_f32_16x16x32_bf16 v[0:3], v[202:205], v[234:237], v[194:197]
	v_mfma_f32_16x16x32_bf16 v[4:7], v[210:213], v[234:237], v[198:201]
	v_mfma_f32_16x16x32_bf16 v[0:3], v[206:209], v[238:241], v[0:3]
	v_mfma_f32_16x16x32_bf16 v[4:7], v[214:217], v[238:241], v[4:7]
	s_barrier
	s_setprio 0
	s_add_u32 s83, s72, 0x200
	s_addc_u32 s85, s73, 0
	s_add_u32 s72, s74, 0x80180
	s_addc_u32 s73, s75, 0
	s_mov_b32 s88, 0
.LBB0_2841:
	ds_read_b128 v[150:153], v145
	ds_read_b128 v[154:157], v145 offset:1024
	ds_read_b128 v[158:161], v145 offset:2048
	ds_read_b128 v[162:165], v145 offset:3072
	ds_read_b128 v[166:169], v146
	ds_read_b128 v[170:173], v146 offset:1024
	ds_read_b128 v[174:177], v146 offset:2048
	ds_read_b128 v[178:181], v146 offset:3072
	s_add_u32 s74, s72, 0xfff80080
	s_addc_u32 s75, s73, -1
	s_cmp_eq_u32 s88, 28
	s_cselect_b32 s77, s54, s75
	s_cselect_b32 s76, s55, s74
	s_cselect_b32 s75, s56, s85
	s_cselect_b32 s74, s57, s83
	s_mov_b32 m0, s58
	v_lshl_add_u64 v[214:215], s[72:73], 0, v[138:139]
	ds_read_b128 v[182:185], v147
	ds_read_b128 v[186:189], v147 offset:1024
	ds_read_b128 v[190:193], v147 offset:2048
	ds_read_b128 v[194:197], v147 offset:3072
	ds_read_b128 v[198:201], v147 offset:4096
	ds_read_b128 v[202:205], v147 offset:5120
	ds_read_b128 v[206:209], v147 offset:6144
	ds_read_b128 v[210:213], v147 offset:7168
	global_load_lds_dwordx4 v138, s[72:73]
	v_lshl_add_u64 v[214:215], s[72:73], 0, v[136:137]
	s_mov_b32 m0, s59
	s_nop 0
	global_load_lds_dwordx4 v136, s[72:73]
	s_waitcnt vmcnt(8) lgkmcnt(0)
	s_setprio 1
	s_barrier
	v_mfma_f32_16x16x32_bf16 v[120:123], v[150:153], v[182:185], v[120:123]
	v_mfma_f32_16x16x32_bf16 v[124:127], v[158:161], v[182:185], v[124:127]
	v_mfma_f32_16x16x32_bf16 v[104:107], v[150:153], v[190:193], v[104:107]
	v_mfma_f32_16x16x32_bf16 v[108:111], v[158:161], v[190:193], v[108:111]
	v_mfma_f32_16x16x32_bf16 v[88:91], v[150:153], v[198:201], v[88:91]
	v_mfma_f32_16x16x32_bf16 v[92:95], v[158:161], v[198:201], v[92:95]
	v_mfma_f32_16x16x32_bf16 v[64:67], v[150:153], v[206:209], v[64:67]
	v_mfma_f32_16x16x32_bf16 v[68:71], v[158:161], v[206:209], v[68:71]
	v_mfma_f32_16x16x32_bf16 v[120:123], v[154:157], v[186:189], v[120:123]
	v_mfma_f32_16x16x32_bf16 v[124:127], v[162:165], v[186:189], v[124:127]
	v_mfma_f32_16x16x32_bf16 v[104:107], v[154:157], v[194:197], v[104:107]
	v_mfma_f32_16x16x32_bf16 v[108:111], v[162:165], v[194:197], v[108:111]
	v_mfma_f32_16x16x32_bf16 v[88:91], v[154:157], v[202:205], v[88:91]
	v_mfma_f32_16x16x32_bf16 v[92:95], v[162:165], v[202:205], v[92:95]
	v_mfma_f32_16x16x32_bf16 v[64:67], v[154:157], v[210:213], v[64:67]
	v_mfma_f32_16x16x32_bf16 v[68:71], v[162:165], v[210:213], v[68:71]
	s_setprio 0
	s_setprio 1
	v_mfma_f32_16x16x32_bf16 v[112:115], v[166:169], v[182:185], v[112:115]
	v_mfma_f32_16x16x32_bf16 v[116:119], v[174:177], v[182:185], v[116:119]
	v_mfma_f32_16x16x32_bf16 v[96:99], v[166:169], v[190:193], v[96:99]
	v_mfma_f32_16x16x32_bf16 v[100:103], v[174:177], v[190:193], v[100:103]
	v_mfma_f32_16x16x32_bf16 v[80:83], v[166:169], v[198:201], v[80:83]
	v_mfma_f32_16x16x32_bf16 v[84:87], v[174:177], v[198:201], v[84:87]
	v_mfma_f32_16x16x32_bf16 v[48:51], v[166:169], v[206:209], v[48:51]
	v_mfma_f32_16x16x32_bf16 v[52:55], v[174:177], v[206:209], v[52:55]
	v_mfma_f32_16x16x32_bf16 v[112:115], v[170:173], v[186:189], v[112:115]
	v_mfma_f32_16x16x32_bf16 v[116:119], v[178:181], v[186:189], v[116:119]
	v_mfma_f32_16x16x32_bf16 v[96:99], v[170:173], v[194:197], v[96:99]
	v_mfma_f32_16x16x32_bf16 v[100:103], v[178:181], v[194:197], v[100:103]
	v_mfma_f32_16x16x32_bf16 v[80:83], v[170:173], v[202:205], v[80:83]
	v_mfma_f32_16x16x32_bf16 v[84:87], v[178:181], v[202:205], v[84:87]
	v_mfma_f32_16x16x32_bf16 v[48:51], v[170:173], v[210:213], v[48:51]
	v_mfma_f32_16x16x32_bf16 v[52:55], v[178:181], v[210:213], v[52:55]
	s_barrier
	s_setprio 0
	s_mov_b32 m0, s63
	v_lshl_add_u64 v[214:215], s[74:75], 0, v[128:129]
	s_add_u32 s90, s74, 0x80000
	ds_read_b128 v[182:185], v147 offset:16384
	ds_read_b128 v[186:189], v147 offset:17408
	ds_read_b128 v[190:193], v147 offset:18432
	ds_read_b128 v[194:197], v147 offset:19456
	ds_read_b128 v[198:201], v147 offset:20480
	ds_read_b128 v[202:205], v147 offset:21504
	ds_read_b128 v[206:209], v147 offset:22528
	ds_read_b128 v[210:213], v147 offset:23552
	global_load_lds_dwordx4 v128, s[74:75]
	v_lshl_add_u64 v[216:217], s[74:75], 0, v[130:131]
	s_mov_b32 m0, s65
	s_addc_u32 s91, s75, 0
	global_load_lds_dwordx4 v130, s[74:75]
	v_lshl_add_u64 v[218:219], s[90:91], 0, v[128:129]
	s_mov_b32 m0, s71
	v_lshl_add_u64 v[220:221], s[76:77], 0, v[132:133]
	global_load_lds_dwordx4 v128, s[90:91]
	v_lshl_add_u64 v[218:219], s[90:91], 0, v[130:131]
	s_mov_b32 m0, s78
	s_nop 0
	global_load_lds_dwordx4 v130, s[90:91]
	v_lshl_add_u64 v[218:219], s[76:77], 0, v[134:135]
	s_mov_b32 m0, s22
	s_nop 0
	global_load_lds_dwordx4 v134, s[76:77]
	s_mov_b32 m0, s23
	s_nop 0
	global_load_lds_dwordx4 v132, s[76:77]
	s_waitcnt vmcnt(8) lgkmcnt(0)
	s_setprio 1
	s_barrier
	v_mfma_f32_16x16x32_bf16 v[72:75], v[150:153], v[182:185], v[72:75]
	v_mfma_f32_16x16x32_bf16 v[76:79], v[158:161], v[182:185], v[76:79]
	v_mfma_f32_16x16x32_bf16 v[40:43], v[150:153], v[190:193], v[40:43]
	v_mfma_f32_16x16x32_bf16 v[44:47], v[158:161], v[190:193], v[44:47]
	v_mfma_f32_16x16x32_bf16 v[24:27], v[150:153], v[198:201], v[24:27]
	v_mfma_f32_16x16x32_bf16 v[28:31], v[158:161], v[198:201], v[28:31]
	v_mfma_f32_16x16x32_bf16 v[8:11], v[150:153], v[206:209], v[8:11]
	v_mfma_f32_16x16x32_bf16 v[12:15], v[158:161], v[206:209], v[12:15]
	v_mfma_f32_16x16x32_bf16 v[72:75], v[154:157], v[186:189], v[72:75]
	v_mfma_f32_16x16x32_bf16 v[76:79], v[162:165], v[186:189], v[76:79]
	v_mfma_f32_16x16x32_bf16 v[40:43], v[154:157], v[194:197], v[40:43]
	v_mfma_f32_16x16x32_bf16 v[44:47], v[162:165], v[194:197], v[44:47]
	v_mfma_f32_16x16x32_bf16 v[24:27], v[154:157], v[202:205], v[24:27]
	v_mfma_f32_16x16x32_bf16 v[28:31], v[162:165], v[202:205], v[28:31]
	v_mfma_f32_16x16x32_bf16 v[8:11], v[154:157], v[210:213], v[8:11]
	v_mfma_f32_16x16x32_bf16 v[12:15], v[162:165], v[210:213], v[12:15]
	s_setprio 0
	s_setprio 1
	v_mfma_f32_16x16x32_bf16 v[56:59], v[166:169], v[182:185], v[56:59]
	v_mfma_f32_16x16x32_bf16 v[60:63], v[174:177], v[182:185], v[60:63]
	v_mfma_f32_16x16x32_bf16 v[32:35], v[166:169], v[190:193], v[32:35]
	v_mfma_f32_16x16x32_bf16 v[36:39], v[174:177], v[190:193], v[36:39]
	v_mfma_f32_16x16x32_bf16 v[16:19], v[166:169], v[198:201], v[16:19]
	v_mfma_f32_16x16x32_bf16 v[20:23], v[174:177], v[198:201], v[20:23]
	v_mfma_f32_16x16x32_bf16 v[0:3], v[166:169], v[206:209], v[0:3]
	v_mfma_f32_16x16x32_bf16 v[4:7], v[174:177], v[206:209], v[4:7]
	v_mfma_f32_16x16x32_bf16 v[56:59], v[170:173], v[186:189], v[56:59]
	v_mfma_f32_16x16x32_bf16 v[60:63], v[178:181], v[186:189], v[60:63]
	v_mfma_f32_16x16x32_bf16 v[32:35], v[170:173], v[194:197], v[32:35]
	v_mfma_f32_16x16x32_bf16 v[36:39], v[178:181], v[194:197], v[36:39]
	v_mfma_f32_16x16x32_bf16 v[16:19], v[170:173], v[202:205], v[16:19]
	v_mfma_f32_16x16x32_bf16 v[20:23], v[178:181], v[202:205], v[20:23]
	v_mfma_f32_16x16x32_bf16 v[0:3], v[170:173], v[210:213], v[0:3]
	v_mfma_f32_16x16x32_bf16 v[4:7], v[178:181], v[210:213], v[4:7]
	s_barrier
; #define PG8_MMA(ai, bj, At, Bt) do { __builtin_amdgcn_s_setprio(1); _Pragma("unroll") for (int m = 0; m < 4; ++m) _Pragma("unroll") for (int n = 0; n < 2; ++n) _Pragma("unroll") for (int k = 0; k < 2; ++k) \
;         acc[ai][bj][m][n] = __builtin_amdgcn_mfma_f32_16x16x32_bf16(Bt[n][k], At[m][k], acc[ai][bj][m][n], 0, 0, 0); __builtin_amdgcn_s_setprio(0); } while (0)
; template <class Epi, class Sched, bool ALIGN_EPI = false, bool SP2 = false, bool A_TILED = false>
; __device__ __forceinline__ void gemm_phase(PG8_LAS unsigned char* lds, const Gemm g, const Sched& S, const Epi& E, const int wave_s) {
;     ...
;         for (int t = PEEL ? 2 : 0; t < nt; t += 2) {
;             const bool last = (t == nt - 2);
;             const char* a1 = cA + (size_t)(t + 1) * kstepA;
;             const char* a2 = last ? nA : cA + (size_t)(t + 2) * kstepA; const char* b2 = last ? nB : cB + (size_t)(t + 2) * kstep;
;             const char* a3 = a2 + kstepA; const char* b3 = b2 + kstep;
;             if (last && has_next) S.a_ready(nxt);
;             if constexpr (SP2) {
;             PG8_ITER(PG8_MMA)
	s_setprio 0
	ds_read_b128 v[150:153], v148
	ds_read_b128 v[154:157], v148 offset:1024
	ds_read_b128 v[158:161], v148 offset:2048
	ds_read_b128 v[162:165], v148 offset:3072
	ds_read_b128 v[166:169], v149
	ds_read_b128 v[170:173], v149 offset:1024
	ds_read_b128 v[174:177], v149 offset:2048
	ds_read_b128 v[178:181], v149 offset:3072
	s_add_u32 s76, s76, 0x80000
	s_addc_u32 s77, s77, 0
	s_mov_b32 m0, s36
	v_lshl_add_u64 v[222:223], s[76:77], 0, v[134:135]
	ds_read_b128 v[182:185], v147 offset:32768
	ds_read_b128 v[186:189], v147 offset:33792
	ds_read_b128 v[190:193], v147 offset:34816
	ds_read_b128 v[194:197], v147 offset:35840
	ds_read_b128 v[198:201], v147 offset:36864
	ds_read_b128 v[202:205], v147 offset:37888
	ds_read_b128 v[206:209], v147 offset:38912
	ds_read_b128 v[210:213], v147 offset:39936
	global_load_lds_dwordx4 v134, s[76:77]
	v_lshl_add_u64 v[222:223], s[76:77], 0, v[132:133]
	s_mov_b32 m0, s37
	s_nop 0
	global_load_lds_dwordx4 v132, s[76:77]
	s_waitcnt vmcnt(8) lgkmcnt(0)
	s_setprio 1
	s_barrier
	v_mfma_f32_16x16x32_bf16 v[120:123], v[150:153], v[182:185], v[120:123]
	v_mfma_f32_16x16x32_bf16 v[124:127], v[158:161], v[182:185], v[124:127]
	v_mfma_f32_16x16x32_bf16 v[104:107], v[150:153], v[190:193], v[104:107]
	v_mfma_f32_16x16x32_bf16 v[108:111], v[158:161], v[190:193], v[108:111]
	v_mfma_f32_16x16x32_bf16 v[88:91], v[150:153], v[198:201], v[88:91]
	v_mfma_f32_16x16x32_bf16 v[92:95], v[158:161], v[198:201], v[92:95]
	v_mfma_f32_16x16x32_bf16 v[64:67], v[150:153], v[206:209], v[64:67]
	v_mfma_f32_16x16x32_bf16 v[68:71], v[158:161], v[206:209], v[68:71]
	v_mfma_f32_16x16x32_bf16 v[120:123], v[154:157], v[186:189], v[120:123]
	v_mfma_f32_16x16x32_bf16 v[124:127], v[162:165], v[186:189], v[124:127]
	v_mfma_f32_16x16x32_bf16 v[104:107], v[154:157], v[194:197], v[104:107]
	v_mfma_f32_16x16x32_bf16 v[108:111], v[162:165], v[194:197], v[108:111]
	v_mfma_f32_16x16x32_bf16 v[88:91], v[154:157], v[202:205], v[88:91]
	v_mfma_f32_16x16x32_bf16 v[92:95], v[162:165], v[202:205], v[92:95]
	v_mfma_f32_16x16x32_bf16 v[64:67], v[154:157], v[210:213], v[64:67]
	v_mfma_f32_16x16x32_bf16 v[68:71], v[162:165], v[210:213], v[68:71]
	s_setprio 0
	s_setprio 1
	v_mfma_f32_16x16x32_bf16 v[112:115], v[166:169], v[182:185], v[112:115]
	v_mfma_f32_16x16x32_bf16 v[116:119], v[174:177], v[182:185], v[116:119]
	v_mfma_f32_16x16x32_bf16 v[96:99], v[166:169], v[190:193], v[96:99]
	v_mfma_f32_16x16x32_bf16 v[100:103], v[174:177], v[190:193], v[100:103]
	v_mfma_f32_16x16x32_bf16 v[80:83], v[166:169], v[198:201], v[80:83]
	v_mfma_f32_16x16x32_bf16 v[84:87], v[174:177], v[198:201], v[84:87]
	v_mfma_f32_16x16x32_bf16 v[48:51], v[166:169], v[206:209], v[48:51]
	v_mfma_f32_16x16x32_bf16 v[52:55], v[174:177], v[206:209], v[52:55]
	v_mfma_f32_16x16x32_bf16 v[112:115], v[170:173], v[186:189], v[112:115]
	v_mfma_f32_16x16x32_bf16 v[116:119], v[178:181], v[186:189], v[116:119]
	v_mfma_f32_16x16x32_bf16 v[96:99], v[170:173], v[194:197], v[96:99]
	v_mfma_f32_16x16x32_bf16 v[100:103], v[178:181], v[194:197], v[100:103]
	v_mfma_f32_16x16x32_bf16 v[80:83], v[170:173], v[202:205], v[80:83]
	v_mfma_f32_16x16x32_bf16 v[84:87], v[178:181], v[202:205], v[84:87]
	v_mfma_f32_16x16x32_bf16 v[48:51], v[170:173], v[210:213], v[48:51]
	v_mfma_f32_16x16x32_bf16 v[52:55], v[178:181], v[210:213], v[52:55]
	s_barrier
	s_setprio 0
	s_mov_b32 m0, s79
	v_lshl_add_u64 v[214:215], v[214:215], 0, s[12:13]
	s_add_u32 s74, s74, 0x80080
	ds_read_b128 v[182:185], v147 offset:49152
	ds_read_b128 v[186:189], v147 offset:50176
	ds_read_b128 v[190:193], v147 offset:51200
	ds_read_b128 v[194:197], v147 offset:52224
	ds_read_b128 v[198:201], v147 offset:53248
	ds_read_b128 v[202:205], v147 offset:54272
	ds_read_b128 v[206:209], v147 offset:55296
	ds_read_b128 v[210:213], v147 offset:56320
	global_load_lds_dwordx4 v[214:215], off
	v_lshl_add_u64 v[214:215], v[216:217], 0, s[12:13]
	s_mov_b32 m0, s80
	s_addc_u32 s75, s75, 0
	global_load_lds_dwordx4 v[214:215], off
	v_lshl_add_u64 v[214:215], s[74:75], 0, v[128:129]
	s_mov_b32 m0, s81
	s_nop 0
	global_load_lds_dwordx4 v128, s[74:75]
	v_lshl_add_u64 v[214:215], s[74:75], 0, v[130:131]
	s_mov_b32 m0, s82
	s_nop 0
	global_load_lds_dwordx4 v130, s[74:75]
	v_lshl_add_u64 v[214:215], v[218:219], 0, s[12:13]
	s_mov_b32 m0, s43
	s_nop 0
	global_load_lds_dwordx4 v[214:215], off
	v_lshl_add_u64 v[214:215], v[220:221], 0, s[12:13]
	s_mov_b32 m0, s48
	s_nop 0
	global_load_lds_dwordx4 v[214:215], off
	s_waitcnt vmcnt(8) lgkmcnt(0)
	s_setprio 1
	s_barrier
	v_mfma_f32_16x16x32_bf16 v[72:75], v[150:153], v[182:185], v[72:75]
	v_mfma_f32_16x16x32_bf16 v[76:79], v[158:161], v[182:185], v[76:79]
	v_mfma_f32_16x16x32_bf16 v[40:43], v[150:153], v[190:193], v[40:43]
	v_mfma_f32_16x16x32_bf16 v[44:47], v[158:161], v[190:193], v[44:47]
	v_mfma_f32_16x16x32_bf16 v[24:27], v[150:153], v[198:201], v[24:27]
	v_mfma_f32_16x16x32_bf16 v[28:31], v[158:161], v[198:201], v[28:31]
	v_mfma_f32_16x16x32_bf16 v[8:11], v[150:153], v[206:209], v[8:11]
	v_mfma_f32_16x16x32_bf16 v[12:15], v[158:161], v[206:209], v[12:15]
	v_mfma_f32_16x16x32_bf16 v[72:75], v[154:157], v[186:189], v[72:75]
	v_mfma_f32_16x16x32_bf16 v[76:79], v[162:165], v[186:189], v[76:79]
	v_mfma_f32_16x16x32_bf16 v[40:43], v[154:157], v[194:197], v[40:43]
	v_mfma_f32_16x16x32_bf16 v[44:47], v[162:165], v[194:197], v[44:47]
	v_mfma_f32_16x16x32_bf16 v[24:27], v[154:157], v[202:205], v[24:27]
	v_mfma_f32_16x16x32_bf16 v[28:31], v[162:165], v[202:205], v[28:31]
	v_mfma_f32_16x16x32_bf16 v[8:11], v[154:157], v[210:213], v[8:11]
	v_mfma_f32_16x16x32_bf16 v[12:15], v[162:165], v[210:213], v[12:15]
	s_setprio 0
	s_setprio 1
	v_mfma_f32_16x16x32_bf16 v[56:59], v[166:169], v[182:185], v[56:59]
	v_mfma_f32_16x16x32_bf16 v[60:63], v[174:177], v[182:185], v[60:63]
	v_mfma_f32_16x16x32_bf16 v[32:35], v[166:169], v[190:193], v[32:35]
	v_mfma_f32_16x16x32_bf16 v[36:39], v[174:177], v[190:193], v[36:39]
	v_mfma_f32_16x16x32_bf16 v[16:19], v[166:169], v[198:201], v[16:19]
	v_mfma_f32_16x16x32_bf16 v[20:23], v[174:177], v[198:201], v[20:23]
	v_mfma_f32_16x16x32_bf16 v[0:3], v[166:169], v[206:209], v[0:3]
	v_mfma_f32_16x16x32_bf16 v[4:7], v[174:177], v[206:209], v[4:7]
	v_mfma_f32_16x16x32_bf16 v[56:59], v[170:173], v[186:189], v[56:59]
	v_mfma_f32_16x16x32_bf16 v[60:63], v[178:181], v[186:189], v[60:63]
	v_mfma_f32_16x16x32_bf16 v[32:35], v[170:173], v[194:197], v[32:35]
	v_mfma_f32_16x16x32_bf16 v[36:39], v[178:181], v[194:197], v[36:39]
	v_mfma_f32_16x16x32_bf16 v[16:19], v[170:173], v[202:205], v[16:19]
	v_mfma_f32_16x16x32_bf16 v[20:23], v[178:181], v[202:205], v[20:23]
	v_mfma_f32_16x16x32_bf16 v[0:3], v[170:173], v[210:213], v[0:3]
	v_mfma_f32_16x16x32_bf16 v[4:7], v[178:181], v[210:213], v[4:7]
	s_barrier
	s_setprio 0
	s_add_i32 s88, s88, 2
	s_add_u32 s83, s83, 0x100
	s_addc_u32 s85, s85, 0
	s_add_u32 s72, s72, 0x100
	s_addc_u32 s73, s73, 0
	s_cmp_gt_u32 s88, 29
	s_cbranch_scc0 .LBB0_2841
	s_and_b64 vcc, exec, s[44:45]
	s_cbranch_vccz .LBB0_2844
	s_barrier

; #define PG8_STAGE(bufoff, gbase, voff) do { _Pragma("unroll") for (int _i = 0; _i < 2; ++_i) \
;         __builtin_amdgcn_global_load_lds((const unsigned*)((const char*)(gbase) + (voff)[_i]), (PG8_LAS unsigned*)(lds + (bufoff) + ldsw + _i * 8192), 16, 0, 0); } while (0)
; #define PG8_WAIT_V(n) asm volatile("s_waitcnt vmcnt(" #n ")" ::: "memory")
; #define PG8_BAR __builtin_amdgcn_s_barrier()
; template <class Epi, class Sched, bool ALIGN_EPI = false, bool SP2 = false, bool A_TILED = false>
; __device__ __forceinline__ void gemm_phase(PG8_LAS unsigned char* lds, const Gemm g, const Sched& S, const Epi& E, const int wave_s) {
;     ...
;     if constexpr (SP2) {
;         PG8_STAGE(PG8_SB(0, 0), cB, voffB); PG8_STAGE(PG8_SB(0, 1), cB + hstep, voffB); PG8_STAGE(PG8_SA(0, 0), cA, voffA); PG8_STAGE(PG8_SA(0, 1), cA + hstepA, voffA);
;         if (wr == 1) PG8_BAR;
;         PG8_WAIT_V(2); PG8_BAR;
;         PG8_STAGE(PG8_SB(1, 0), cB + kstep, voffB); PG8_STAGE(PG8_SA(1, 0), cA + kstepA, voffA); PG8_STAGE(PG8_SB(1, 1), cB + hstep + kstep, voffB);
;         PG8_WAIT_V(6); PG8_BAR;
;     } else {
;         PG8_STAGE(PG8_SB(0, 0), cB, voffB); PG8_STAGE(PG8_SA(0, 0), cA, voffA); PG8_STAGE(PG8_SB(0, 1), cB + hstep, voffB); PG8_STAGE(PG8_SA(0, 1), cA + hstepA, voffA);
;         if (wr == 1) PG8_BAR;
;         PG8_WAIT_V(4); PG8_BAR;
;         PG8_STAGE(PG8_SB(1, 0), cB + kstep, voffB); PG8_STAGE(PG8_SA(1, 0), cA + kstepA, voffA); PG8_STAGE(PG8_SB(1, 1), cB + hstep + kstep, voffB);
;         PG8_WAIT_V(6); PG8_BAR;
;     ...
; #pragma unroll
;             for (int a = 0; a < 2; ++a)
; #pragma unroll
;                 for (int b = 0; b < 2; ++b)
; #pragma unroll
;                     for (int m = 0; m < 4; ++m)
; #pragma unroll
;                         for (int n = 0; n < 2; ++n) acc[a][b][m][n] = (f32x4){0.f, 0.f, 0.f, 0.f};
.LBB0_2913:
	v_and_b32_e32 v5, 48, v4
	v_lshlrev_b32_e32 v6, 6, v4
	s_movk_i32 s36, 0x3c0
	v_lshlrev_b32_e32 v4, 2, v4
	s_mov_b64 s[60:61], 0x80
	s_and_b32 s9, s1, 3
	s_lshl_b32 s8, s23, 6
	s_lshl_b32 s23, s23, 13
	v_and_or_b32 v5, v6, s36, v5
	v_and_b32_e32 v4, 32, v4
	s_add_i32 m0, s14, 0x18000
	v_lshl_add_u64 v[2:3], v[2:3], 0, s[60:61]
	v_bitop3_b32 v6, v5, s23, v4 bitop3:0xde
	s_lshl_b32 s23, s9, 12
	s_waitcnt vmcnt(2)
	s_barrier
	global_load_lds_dwordx4 v[2:3], off
	s_add_i32 m0, s14, 0x1a000
	s_add_u32 s36, s6, 0x8000
	v_bitop3_b32 v4, v5, s23, v4 bitop3:0xde
	v_lshl_add_u64 v[0:1], v[0:1], 0, s[60:61]
	s_addc_u32 s37, s7, 0
	s_add_i32 s23, s14, 0x8000
	global_load_lds_dwordx4 v[0:1], off
	v_lshl_add_u64 v[0:1], s[36:37], 0, v[32:33]
	s_mov_b32 m0, s23
	s_mov_b64 s[40:41], 0x3460c000
	global_load_lds_dwordx4 v32, s[36:37]
	v_lshl_add_u64 v[0:1], s[36:37], 0, v[132:133]
	s_add_i32 s36, s14, 0xa000
	s_add_u32 s38, s2, 0x200080
	s_mov_b32 m0, s36
	s_addc_u32 s39, s3, 0
	global_load_lds_dwordx4 v[0:1], off
	s_add_i32 m0, s14, 0x1c000
	v_lshl_add_u64 v[0:1], s[38:39], 0, v[34:35]
	global_load_lds_dwordx4 v34, s[38:39]
	v_lshl_add_u64 v[0:1], s[38:39], 0, v[134:135]
	s_add_i32 m0, s14, 0x1e000
	s_add_u32 s37, s64, 0x16600100
	global_load_lds_dwordx4 v134, s[38:39]
	s_addc_u32 s38, s65, 0
	v_lshl_add_u64 v[0:1], s[62:63], 0, v[132:133]
	v_lshl_add_u64 v[136:137], v[0:1], 0, s[40:41]
	v_lshl_add_u64 v[0:1], s[62:63], 0, v[32:33]
	s_add_u32 s39, s62, 0x34610000
	s_waitcnt vmcnt(6)
	v_lshl_add_u64 v[138:139], v[0:1], 0, s[40:41]
	s_addc_u32 s40, s63, 0
	s_add_i32 s47, 0, 0x10000
	s_add_i32 s49, 0, 0x14000
	s_add_i32 s51, 0, 0x18000
	s_add_i32 s54, 0, 0x1c000
	v_add_u32_e32 v140, s47, v4
	v_add_u32_e32 v141, s49, v4
	s_add_i32 s47, s47, s53
	s_add_i32 s49, s49, s53
	v_add_u32_e32 v143, s51, v4
	s_add_i32 s51, s51, s53
	s_add_i32 s53, s54, s53
	s_mov_b32 s41, -2
	v_add_u32_e32 v142, 0, v6
	s_add_i32 s42, s14, 0xc000
	s_add_i32 s43, s14, 0xe000
	s_add_i32 s48, s47, 0x2000
	s_add_i32 s50, s49, 0x2000
	v_add_u32_e32 v144, s54, v4
	s_add_i32 s52, s51, 0x2000
	s_add_i32 s54, s53, 0x2000
	s_mov_b64 s[62:63], 0x10000
	v_mov_b32_e32 v0, v35
	v_mov_b32_e32 v1, v35
	v_mov_b32_e32 v2, v35
	v_mov_b32_e32 v3, v35
	v_mov_b32_e32 v4, v35
	v_mov_b32_e32 v5, v35
	v_mov_b32_e32 v6, v35
	v_mov_b32_e32 v7, v35
	v_mov_b32_e32 v40, v35
	v_mov_b32_e32 v41, v35
	v_mov_b32_e32 v42, v35
	v_mov_b32_e32 v43, v35
	v_mov_b32_e32 v44, v35
	v_mov_b32_e32 v45, v35
	v_mov_b32_e32 v46, v35
	v_mov_b32_e32 v47, v35
	v_mov_b32_e32 v88, v35
	v_mov_b32_e32 v89, v35
	v_mov_b32_e32 v90, v35
	v_mov_b32_e32 v91, v35
	v_mov_b32_e32 v92, v35
	v_mov_b32_e32 v93, v35
	v_mov_b32_e32 v94, v35
	v_mov_b32_e32 v95, v35
	v_mov_b32_e32 v112, v35
	v_mov_b32_e32 v113, v35
	v_mov_b32_e32 v114, v35
	v_mov_b32_e32 v115, v35
	v_mov_b32_e32 v124, v35
	v_mov_b32_e32 v125, v35
	v_mov_b32_e32 v126, v35
	v_mov_b32_e32 v127, v35
	v_mov_b32_e32 v24, v35
	v_mov_b32_e32 v25, v35
	v_mov_b32_e32 v26, v35
	v_mov_b32_e32 v27, v35
	v_mov_b32_e32 v36, v35
	v_mov_b32_e32 v37, v35
	v_mov_b32_e32 v38, v35
	v_mov_b32_e32 v39, v35
	v_mov_b32_e32 v80, v35
	v_mov_b32_e32 v81, v35
	v_mov_b32_e32 v82, v35
	v_mov_b32_e32 v83, v35
	v_mov_b32_e32 v84, v35
	v_mov_b32_e32 v85, v35
	v_mov_b32_e32 v86, v35
	v_mov_b32_e32 v87, v35
	v_mov_b32_e32 v120, v35
	v_mov_b32_e32 v121, v35
	v_mov_b32_e32 v122, v35
	v_mov_b32_e32 v123, v35
	v_mov_b32_e32 v116, v35
	v_mov_b32_e32 v117, v35
	v_mov_b32_e32 v118, v35
	v_mov_b32_e32 v119, v35
	v_mov_b32_e32 v104, v35
	v_mov_b32_e32 v105, v35
	v_mov_b32_e32 v106, v35
	v_mov_b32_e32 v107, v35
	v_mov_b32_e32 v100, v35
	v_mov_b32_e32 v101, v35
	v_mov_b32_e32 v102, v35
	v_mov_b32_e32 v103, v35
	v_mov_b32_e32 v96, v35
	v_mov_b32_e32 v97, v35
	v_mov_b32_e32 v98, v35
	v_mov_b32_e32 v99, v35
	v_mov_b32_e32 v108, v35
	v_mov_b32_e32 v109, v35
	v_mov_b32_e32 v110, v35
	v_mov_b32_e32 v111, v35
	v_mov_b32_e32 v64, v35
	v_mov_b32_e32 v65, v35
	v_mov_b32_e32 v66, v35
	v_mov_b32_e32 v67, v35
	v_mov_b32_e32 v72, v35
	v_mov_b32_e32 v73, v35
	v_mov_b32_e32 v74, v35
	v_mov_b32_e32 v75, v35
	v_mov_b32_e32 v48, v35
	v_mov_b32_e32 v49, v35
	v_mov_b32_e32 v50, v35
	v_mov_b32_e32 v51, v35
	v_mov_b32_e32 v56, v35
	v_mov_b32_e32 v57, v35
	v_mov_b32_e32 v58, v35
	v_mov_b32_e32 v59, v35
	v_mov_b32_e32 v16, v35
	v_mov_b32_e32 v17, v35
	v_mov_b32_e32 v18, v35
	v_mov_b32_e32 v19, v35
	v_mov_b32_e32 v28, v35
	v_mov_b32_e32 v29, v35
	v_mov_b32_e32 v30, v35
	v_mov_b32_e32 v31, v35
	v_mov_b32_e32 v68, v35
	v_mov_b32_e32 v69, v35
	v_mov_b32_e32 v70, v35
	v_mov_b32_e32 v71, v35
	v_mov_b32_e32 v128, v35
	v_mov_b32_e32 v129, v35
	v_mov_b32_e32 v130, v35
	v_mov_b32_e32 v131, v35
	v_mov_b32_e32 v52, v35
	v_mov_b32_e32 v53, v35
	v_mov_b32_e32 v54, v35
	v_mov_b32_e32 v55, v35
	v_mov_b32_e32 v76, v35
	v_mov_b32_e32 v77, v35
	v_mov_b32_e32 v78, v35
	v_mov_b32_e32 v79, v35
	v_mov_b32_e32 v20, v35
	v_mov_b32_e32 v21, v35
	v_mov_b32_e32 v22, v35
	v_mov_b32_e32 v23, v35
	v_mov_b32_e32 v60, v35
	v_mov_b32_e32 v61, v35
	v_mov_b32_e32 v62, v35
	v_mov_b32_e32 v63, v35
	v_mov_b32_e32 v12, v35
	v_mov_b32_e32 v13, v35
	v_mov_b32_e32 v14, v35
	v_mov_b32_e32 v15, v35
	v_mov_b32_e32 v8, v35
	v_mov_b32_e32 v9, v35
	v_mov_b32_e32 v10, v35
	v_mov_b32_e32 v11, v35
	s_barrier
; #define PG8_MMA(ai, bj, At, Bt) do { __builtin_amdgcn_s_setprio(1); _Pragma("unroll") for (int m = 0; m < 4; ++m) _Pragma("unroll") for (int n = 0; n < 2; ++n) _Pragma("unroll") for (int k = 0; k < 2; ++k) \
;         acc[ai][bj][m][n] = __builtin_amdgcn_mfma_f32_16x16x32_bf16(Bt[n][k], At[m][k], acc[ai][bj][m][n], 0, 0, 0); __builtin_amdgcn_s_setprio(0); } while (0)
; template <class Epi, class Sched, bool ALIGN_EPI = false, bool SP2 = false, bool A_TILED = false>
; __device__ __forceinline__ void gemm_phase(PG8_LAS unsigned char* lds, const Gemm g, const Sched& S, const Epi& E, const int wave_s) {
;     ...
;         for (int t = PEEL ? 2 : 0; t < nt; t += 2) {
;             const bool last = (t == nt - 2);
;             const char* a1 = cA + (size_t)(t + 1) * kstepA;
;             const char* a2 = last ? nA : cA + (size_t)(t + 2) * kstepA; const char* b2 = last ? nB : cB + (size_t)(t + 2) * kstep;
;             const char* a3 = a2 + kstepA; const char* b3 = b2 + kstep;
;             if (last && has_next) S.a_ready(nxt);
;             if constexpr (SP2) {
;             PG8_ITER(PG8_MMA)
.LBB0_2914:
	ds_read_b128 v[146:149], v140
	ds_read_b128 v[150:153], v140 offset:1024
	ds_read_b128 v[154:157], v140 offset:2048
	ds_read_b128 v[158:161], v140 offset:3072
	ds_read_b128 v[162:165], v141
	ds_read_b128 v[166:169], v141 offset:1024
	ds_read_b128 v[170:173], v141 offset:2048
	ds_read_b128 v[174:177], v141 offset:3072
	s_add_u32 s55, s44, s39
	s_addc_u32 s56, s45, s40
	s_add_u32 s57, s44, s37
	s_addc_u32 s58, s45, s38
	s_cmpk_eq_i32 s41, 0x7c
	s_cselect_b32 s68, s6, s55
	s_cselect_b32 s69, s7, s56
	s_cselect_b32 s66, s2, s57
	s_cselect_b32 s67, s3, s58
	s_add_u32 s64, s68, 0x8000
	s_addc_u32 s65, s69, 0
	s_mov_b32 m0, s42
	v_lshl_add_u64 v[210:211], s[44:45], 0, v[138:139]
	ds_read_b128 v[178:181], v142
	ds_read_b128 v[182:185], v142 offset:1024
	ds_read_b128 v[186:189], v142 offset:2048
	ds_read_b128 v[190:193], v142 offset:3072
	ds_read_b128 v[194:197], v142 offset:4096
	ds_read_b128 v[198:201], v142 offset:5120
	ds_read_b128 v[202:205], v142 offset:6144
	ds_read_b128 v[206:209], v142 offset:7168
	global_load_lds_dwordx4 v[210:211], off
	v_lshl_add_u64 v[210:211], s[44:45], 0, v[136:137]
	s_mov_b32 m0, s43
	s_nop 0
	global_load_lds_dwordx4 v[210:211], off
	s_waitcnt vmcnt(8) lgkmcnt(0)
	s_setprio 1
	s_barrier
	v_mfma_f32_16x16x32_bf16 v[8:11], v[146:149], v[178:181], v[8:11]
	v_mfma_f32_16x16x32_bf16 v[12:15], v[154:157], v[178:181], v[12:15]
	v_mfma_f32_16x16x32_bf16 v[60:63], v[146:149], v[186:189], v[60:63]
	v_mfma_f32_16x16x32_bf16 v[20:23], v[154:157], v[186:189], v[20:23]
	v_mfma_f32_16x16x32_bf16 v[76:79], v[146:149], v[194:197], v[76:79]
	v_mfma_f32_16x16x32_bf16 v[52:55], v[154:157], v[194:197], v[52:55]
	v_mfma_f32_16x16x32_bf16 v[128:131], v[146:149], v[202:205], v[128:131]
	v_mfma_f32_16x16x32_bf16 v[68:71], v[154:157], v[202:205], v[68:71]
	v_mfma_f32_16x16x32_bf16 v[8:11], v[150:153], v[182:185], v[8:11]
	v_mfma_f32_16x16x32_bf16 v[12:15], v[158:161], v[182:185], v[12:15]
	v_mfma_f32_16x16x32_bf16 v[60:63], v[150:153], v[190:193], v[60:63]
	v_mfma_f32_16x16x32_bf16 v[20:23], v[158:161], v[190:193], v[20:23]
	v_mfma_f32_16x16x32_bf16 v[76:79], v[150:153], v[198:201], v[76:79]
	v_mfma_f32_16x16x32_bf16 v[52:55], v[158:161], v[198:201], v[52:55]
	v_mfma_f32_16x16x32_bf16 v[128:131], v[150:153], v[206:209], v[128:131]
	v_mfma_f32_16x16x32_bf16 v[68:71], v[158:161], v[206:209], v[68:71]
	s_setprio 0
	s_setprio 1
	v_mfma_f32_16x16x32_bf16 v[28:31], v[162:165], v[178:181], v[28:31]
	v_mfma_f32_16x16x32_bf16 v[16:19], v[170:173], v[178:181], v[16:19]
	v_mfma_f32_16x16x32_bf16 v[56:59], v[162:165], v[186:189], v[56:59]
	v_mfma_f32_16x16x32_bf16 v[48:51], v[170:173], v[186:189], v[48:51]
	v_mfma_f32_16x16x32_bf16 v[72:75], v[162:165], v[194:197], v[72:75]
	v_mfma_f32_16x16x32_bf16 v[64:67], v[170:173], v[194:197], v[64:67]
	v_mfma_f32_16x16x32_bf16 v[108:111], v[162:165], v[202:205], v[108:111]
	v_mfma_f32_16x16x32_bf16 v[96:99], v[170:173], v[202:205], v[96:99]
	v_mfma_f32_16x16x32_bf16 v[28:31], v[166:169], v[182:185], v[28:31]
	v_mfma_f32_16x16x32_bf16 v[16:19], v[174:177], v[182:185], v[16:19]
	v_mfma_f32_16x16x32_bf16 v[56:59], v[166:169], v[190:193], v[56:59]
	v_mfma_f32_16x16x32_bf16 v[48:51], v[174:177], v[190:193], v[48:51]
	v_mfma_f32_16x16x32_bf16 v[72:75], v[166:169], v[198:201], v[72:75]
	v_mfma_f32_16x16x32_bf16 v[64:67], v[174:177], v[198:201], v[64:67]
	v_mfma_f32_16x16x32_bf16 v[108:111], v[166:169], v[206:209], v[108:111]
	v_mfma_f32_16x16x32_bf16 v[96:99], v[174:177], v[206:209], v[96:99]
	s_barrier
	s_setprio 0
	s_mov_b32 m0, s47
	v_lshl_add_u64 v[210:211], s[66:67], 0, v[34:35]
	s_add_u32 s56, s66, 0x200000
	ds_read_b128 v[178:181], v142 offset:16384
	ds_read_b128 v[182:185], v142 offset:17408
	ds_read_b128 v[186:189], v142 offset:18432
	ds_read_b128 v[190:193], v142 offset:19456
	ds_read_b128 v[194:197], v142 offset:20480
	ds_read_b128 v[198:201], v142 offset:21504
	ds_read_b128 v[202:205], v142 offset:22528
	ds_read_b128 v[206:209], v142 offset:23552
	global_load_lds_dwordx4 v34, s[66:67]
	v_lshl_add_u64 v[212:213], s[66:67], 0, v[134:135]
	s_mov_b32 m0, s48
	s_addc_u32 s57, s67, 0
	global_load_lds_dwordx4 v134, s[66:67]
	v_lshl_add_u64 v[214:215], s[56:57], 0, v[34:35]
	s_mov_b32 m0, s49
	s_nop 0
	global_load_lds_dwordx4 v34, s[56:57]
	v_lshl_add_u64 v[214:215], s[56:57], 0, v[134:135]
	s_mov_b32 m0, s50
	s_nop 0
	global_load_lds_dwordx4 v134, s[56:57]
	v_lshl_add_u64 v[214:215], s[68:69], 0, v[32:33]
	s_mov_b32 m0, s14
	s_nop 0
	global_load_lds_dwordx4 v32, s[68:69]
	v_lshl_add_u64 v[214:215], s[68:69], 0, v[132:133]
	s_mov_b32 m0, s15
	s_nop 0
	global_load_lds_dwordx4 v132, s[68:69]
	s_waitcnt vmcnt(8) lgkmcnt(0)
	s_setprio 1
	s_barrier
	v_mfma_f32_16x16x32_bf16 v[100:103], v[146:149], v[178:181], v[100:103]
	v_mfma_f32_16x16x32_bf16 v[104:107], v[154:157], v[178:181], v[104:107]
	v_mfma_f32_16x16x32_bf16 v[116:119], v[146:149], v[186:189], v[116:119]
	v_mfma_f32_16x16x32_bf16 v[120:123], v[154:157], v[186:189], v[120:123]
	v_mfma_f32_16x16x32_bf16 v[84:87], v[146:149], v[194:197], v[84:87]
	v_mfma_f32_16x16x32_bf16 v[80:83], v[154:157], v[194:197], v[80:83]
	v_mfma_f32_16x16x32_bf16 v[36:39], v[146:149], v[202:205], v[36:39]
	v_mfma_f32_16x16x32_bf16 v[24:27], v[154:157], v[202:205], v[24:27]
	v_mfma_f32_16x16x32_bf16 v[100:103], v[150:153], v[182:185], v[100:103]
	v_mfma_f32_16x16x32_bf16 v[104:107], v[158:161], v[182:185], v[104:107]
	v_mfma_f32_16x16x32_bf16 v[116:119], v[150:153], v[190:193], v[116:119]
	v_mfma_f32_16x16x32_bf16 v[120:123], v[158:161], v[190:193], v[120:123]
	v_mfma_f32_16x16x32_bf16 v[84:87], v[150:153], v[198:201], v[84:87]
	v_mfma_f32_16x16x32_bf16 v[80:83], v[158:161], v[198:201], v[80:83]
	v_mfma_f32_16x16x32_bf16 v[36:39], v[150:153], v[206:209], v[36:39]
	v_mfma_f32_16x16x32_bf16 v[24:27], v[158:161], v[206:209], v[24:27]
	s_setprio 0
	s_setprio 1
	v_mfma_f32_16x16x32_bf16 v[124:127], v[162:165], v[178:181], v[124:127]
	v_mfma_f32_16x16x32_bf16 v[112:115], v[170:173], v[178:181], v[112:115]
	v_mfma_f32_16x16x32_bf16 v[92:95], v[162:165], v[186:189], v[92:95]
	v_mfma_f32_16x16x32_bf16 v[88:91], v[170:173], v[186:189], v[88:91]
	v_mfma_f32_16x16x32_bf16 v[44:47], v[162:165], v[194:197], v[44:47]
	v_mfma_f32_16x16x32_bf16 v[40:43], v[170:173], v[194:197], v[40:43]
	v_mfma_f32_16x16x32_bf16 v[4:7], v[162:165], v[202:205], v[4:7]
	v_mfma_f32_16x16x32_bf16 v[0:3], v[170:173], v[202:205], v[0:3]
	v_mfma_f32_16x16x32_bf16 v[124:127], v[166:169], v[182:185], v[124:127]
	v_mfma_f32_16x16x32_bf16 v[112:115], v[174:177], v[182:185], v[112:115]
	v_mfma_f32_16x16x32_bf16 v[92:95], v[166:169], v[190:193], v[92:95]
	v_mfma_f32_16x16x32_bf16 v[88:91], v[174:177], v[190:193], v[88:91]
	v_mfma_f32_16x16x32_bf16 v[44:47], v[166:169], v[198:201], v[44:47]
	v_mfma_f32_16x16x32_bf16 v[40:43], v[174:177], v[198:201], v[40:43]
	v_mfma_f32_16x16x32_bf16 v[4:7], v[166:169], v[206:209], v[4:7]
	v_mfma_f32_16x16x32_bf16 v[0:3], v[174:177], v[206:209], v[0:3]
	s_barrier
	s_setprio 0
	ds_read_b128 v[146:149], v143
	ds_read_b128 v[150:153], v143 offset:1024
	ds_read_b128 v[154:157], v143 offset:2048
	ds_read_b128 v[158:161], v143 offset:3072
	ds_read_b128 v[162:165], v144
	ds_read_b128 v[166:169], v144 offset:1024
	ds_read_b128 v[170:173], v144 offset:2048
	ds_read_b128 v[174:177], v144 offset:3072
	s_add_u32 s56, s68, 0x4000
	s_addc_u32 s57, s69, 0
	s_mov_b32 m0, s21
	v_lshl_add_u64 v[214:215], s[56:57], 0, v[32:33]
	ds_read_b128 v[178:181], v142 offset:32768
	ds_read_b128 v[182:185], v142 offset:33792
	ds_read_b128 v[186:189], v142 offset:34816
	ds_read_b128 v[190:193], v142 offset:35840
	ds_read_b128 v[194:197], v142 offset:36864
	ds_read_b128 v[198:201], v142 offset:37888
	ds_read_b128 v[202:205], v142 offset:38912
	ds_read_b128 v[206:209], v142 offset:39936
	global_load_lds_dwordx4 v32, s[56:57]
	v_lshl_add_u64 v[214:215], s[56:57], 0, v[132:133]
	s_mov_b32 m0, s22
	s_nop 0
	global_load_lds_dwordx4 v132, s[56:57]
	s_waitcnt vmcnt(8) lgkmcnt(0)
	s_setprio 1
	s_barrier
	v_mfma_f32_16x16x32_bf16 v[8:11], v[146:149], v[178:181], v[8:11]
	v_mfma_f32_16x16x32_bf16 v[12:15], v[154:157], v[178:181], v[12:15]
	v_mfma_f32_16x16x32_bf16 v[60:63], v[146:149], v[186:189], v[60:63]
	v_mfma_f32_16x16x32_bf16 v[20:23], v[154:157], v[186:189], v[20:23]
	v_mfma_f32_16x16x32_bf16 v[76:79], v[146:149], v[194:197], v[76:79]
	v_mfma_f32_16x16x32_bf16 v[52:55], v[154:157], v[194:197], v[52:55]
	v_mfma_f32_16x16x32_bf16 v[128:131], v[146:149], v[202:205], v[128:131]
	v_mfma_f32_16x16x32_bf16 v[68:71], v[154:157], v[202:205], v[68:71]
	v_mfma_f32_16x16x32_bf16 v[8:11], v[150:153], v[182:185], v[8:11]
	v_mfma_f32_16x16x32_bf16 v[12:15], v[158:161], v[182:185], v[12:15]
	v_mfma_f32_16x16x32_bf16 v[60:63], v[150:153], v[190:193], v[60:63]
	v_mfma_f32_16x16x32_bf16 v[20:23], v[158:161], v[190:193], v[20:23]
	v_mfma_f32_16x16x32_bf16 v[76:79], v[150:153], v[198:201], v[76:79]
	v_mfma_f32_16x16x32_bf16 v[52:55], v[158:161], v[198:201], v[52:55]
	v_mfma_f32_16x16x32_bf16 v[128:131], v[150:153], v[206:209], v[128:131]
	v_mfma_f32_16x16x32_bf16 v[68:71], v[158:161], v[206:209], v[68:71]
	s_setprio 0
	s_setprio 1
	v_mfma_f32_16x16x32_bf16 v[28:31], v[162:165], v[178:181], v[28:31]
	v_mfma_f32_16x16x32_bf16 v[16:19], v[170:173], v[178:181], v[16:19]
	v_mfma_f32_16x16x32_bf16 v[56:59], v[162:165], v[186:189], v[56:59]
	v_mfma_f32_16x16x32_bf16 v[48:51], v[170:173], v[186:189], v[48:51]
	v_mfma_f32_16x16x32_bf16 v[72:75], v[162:165], v[194:197], v[72:75]
	v_mfma_f32_16x16x32_bf16 v[64:67], v[170:173], v[194:197], v[64:67]
	v_mfma_f32_16x16x32_bf16 v[108:111], v[162:165], v[202:205], v[108:111]
	v_mfma_f32_16x16x32_bf16 v[96:99], v[170:173], v[202:205], v[96:99]
	v_mfma_f32_16x16x32_bf16 v[28:31], v[166:169], v[182:185], v[28:31]
	v_mfma_f32_16x16x32_bf16 v[16:19], v[174:177], v[182:185], v[16:19]
	v_mfma_f32_16x16x32_bf16 v[56:59], v[166:169], v[190:193], v[56:59]
	v_mfma_f32_16x16x32_bf16 v[48:51], v[174:177], v[190:193], v[48:51]
	v_mfma_f32_16x16x32_bf16 v[72:75], v[166:169], v[198:201], v[72:75]
	v_mfma_f32_16x16x32_bf16 v[64:67], v[174:177], v[198:201], v[64:67]
	v_mfma_f32_16x16x32_bf16 v[108:111], v[166:169], v[206:209], v[108:111]
	v_mfma_f32_16x16x32_bf16 v[96:99], v[174:177], v[206:209], v[96:99]
	s_barrier
; #define PG8_MMA(ai, bj, At, Bt) do { __builtin_amdgcn_s_setprio(1); _Pragma("unroll") for (int m = 0; m < 4; ++m) _Pragma("unroll") for (int n = 0; n < 2; ++n) _Pragma("unroll") for (int k = 0; k < 2; ++k) \
;         acc[ai][bj][m][n] = __builtin_amdgcn_mfma_f32_16x16x32_bf16(Bt[n][k], At[m][k], acc[ai][bj][m][n], 0, 0, 0); __builtin_amdgcn_s_setprio(0); } while (0)
; template <class Epi, class Sched, bool ALIGN_EPI = false, bool SP2 = false, bool A_TILED = false>
; __device__ __forceinline__ void gemm_phase(PG8_LAS unsigned char* lds, const Gemm g, const Sched& S, const Epi& E, const int wave_s) {
;     ...
;         for (int t = PEEL ? 2 : 0; t < nt; t += 2) {
;             const bool last = (t == nt - 2);
;             const char* a1 = cA + (size_t)(t + 1) * kstepA;
;             const char* a2 = last ? nA : cA + (size_t)(t + 2) * kstepA; const char* b2 = last ? nB : cB + (size_t)(t + 2) * kstep;
;             const char* a3 = a2 + kstepA; const char* b3 = b2 + kstep;
;             if (last && has_next) S.a_ready(nxt);
;             if constexpr (SP2) {
;             PG8_ITER(PG8_MMA)
	s_setprio 0
	s_mov_b32 m0, s51
	v_lshl_add_u64 v[210:211], v[210:211], 0, s[60:61]
	s_add_u32 s56, s66, 0x200080
	ds_read_b128 v[178:181], v142 offset:49152
	ds_read_b128 v[182:185], v142 offset:50176
	ds_read_b128 v[186:189], v142 offset:51200
	ds_read_b128 v[190:193], v142 offset:52224
	ds_read_b128 v[194:197], v142 offset:53248
	ds_read_b128 v[198:201], v142 offset:54272
	ds_read_b128 v[202:205], v142 offset:55296
	ds_read_b128 v[206:209], v142 offset:56320
	global_load_lds_dwordx4 v[210:211], off
	v_lshl_add_u64 v[210:211], v[212:213], 0, s[60:61]
	s_mov_b32 m0, s52
	s_addc_u32 s57, s67, 0
	global_load_lds_dwordx4 v[210:211], off
	v_lshl_add_u64 v[210:211], s[56:57], 0, v[34:35]
	s_mov_b32 m0, s53
	s_nop 0
	global_load_lds_dwordx4 v34, s[56:57]
	v_lshl_add_u64 v[210:211], s[56:57], 0, v[134:135]
	s_mov_b32 m0, s54
	s_nop 0
	global_load_lds_dwordx4 v134, s[56:57]
	v_lshl_add_u64 v[210:211], s[64:65], 0, v[32:33]
	s_mov_b32 m0, s23
	s_nop 0
	global_load_lds_dwordx4 v32, s[64:65]
	v_lshl_add_u64 v[210:211], s[64:65], 0, v[132:133]
	s_mov_b32 m0, s36
	s_nop 0
	global_load_lds_dwordx4 v132, s[64:65]
	s_waitcnt vmcnt(8) lgkmcnt(0)
	s_setprio 1
	s_barrier
	v_mfma_f32_16x16x32_bf16 v[100:103], v[146:149], v[178:181], v[100:103]
	v_mfma_f32_16x16x32_bf16 v[104:107], v[154:157], v[178:181], v[104:107]
	v_mfma_f32_16x16x32_bf16 v[116:119], v[146:149], v[186:189], v[116:119]
	v_mfma_f32_16x16x32_bf16 v[120:123], v[154:157], v[186:189], v[120:123]
	v_mfma_f32_16x16x32_bf16 v[84:87], v[146:149], v[194:197], v[84:87]
	v_mfma_f32_16x16x32_bf16 v[80:83], v[154:157], v[194:197], v[80:83]
	v_mfma_f32_16x16x32_bf16 v[36:39], v[146:149], v[202:205], v[36:39]
	v_mfma_f32_16x16x32_bf16 v[24:27], v[154:157], v[202:205], v[24:27]
	v_mfma_f32_16x16x32_bf16 v[100:103], v[150:153], v[182:185], v[100:103]
	v_mfma_f32_16x16x32_bf16 v[104:107], v[158:161], v[182:185], v[104:107]
	v_mfma_f32_16x16x32_bf16 v[116:119], v[150:153], v[190:193], v[116:119]
	v_mfma_f32_16x16x32_bf16 v[120:123], v[158:161], v[190:193], v[120:123]
	v_mfma_f32_16x16x32_bf16 v[84:87], v[150:153], v[198:201], v[84:87]
	v_mfma_f32_16x16x32_bf16 v[80:83], v[158:161], v[198:201], v[80:83]
	v_mfma_f32_16x16x32_bf16 v[36:39], v[150:153], v[206:209], v[36:39]
	v_mfma_f32_16x16x32_bf16 v[24:27], v[158:161], v[206:209], v[24:27]
	s_setprio 0
	s_setprio 1
	v_mfma_f32_16x16x32_bf16 v[124:127], v[162:165], v[178:181], v[124:127]
	v_mfma_f32_16x16x32_bf16 v[112:115], v[170:173], v[178:181], v[112:115]
	v_mfma_f32_16x16x32_bf16 v[92:95], v[162:165], v[186:189], v[92:95]
	v_mfma_f32_16x16x32_bf16 v[88:91], v[170:173], v[186:189], v[88:91]
	v_mfma_f32_16x16x32_bf16 v[44:47], v[162:165], v[194:197], v[44:47]
	v_mfma_f32_16x16x32_bf16 v[40:43], v[170:173], v[194:197], v[40:43]
	v_mfma_f32_16x16x32_bf16 v[4:7], v[162:165], v[202:205], v[4:7]
	v_mfma_f32_16x16x32_bf16 v[0:3], v[170:173], v[202:205], v[0:3]
	v_mfma_f32_16x16x32_bf16 v[124:127], v[166:169], v[182:185], v[124:127]
	v_mfma_f32_16x16x32_bf16 v[112:115], v[174:177], v[182:185], v[112:115]
	v_mfma_f32_16x16x32_bf16 v[92:95], v[166:169], v[190:193], v[92:95]
	v_mfma_f32_16x16x32_bf16 v[88:91], v[174:177], v[190:193], v[88:91]
	v_mfma_f32_16x16x32_bf16 v[44:47], v[166:169], v[198:201], v[44:47]
	v_mfma_f32_16x16x32_bf16 v[40:43], v[174:177], v[198:201], v[40:43]
	v_mfma_f32_16x16x32_bf16 v[4:7], v[166:169], v[206:209], v[4:7]
	v_mfma_f32_16x16x32_bf16 v[0:3], v[174:177], v[206:209], v[0:3]
	s_barrier
	s_setprio 0
	s_add_i32 s41, s41, 2
	s_add_u32 s37, s37, 0x100
	s_addc_u32 s38, s38, 0
	s_add_u32 s39, s39, 0x10000
	s_addc_u32 s40, s40, 0
	v_lshl_add_u64 v[136:137], v[136:137], 0, s[62:63]
	s_cmpk_gt_u32 s41, 0x7d
	v_lshl_add_u64 v[138:139], v[138:139], 0, s[62:63]
	s_cbranch_scc0 .LBB0_2914
	s_waitcnt vmcnt(0)
	s_cmpk_lt_u32 s0, 0x100
	s_cbranch_scc0 .LBB0_2917
	s_barrier

; #define PG8_STAGE(bufoff, gbase, voff) do { _Pragma("unroll") for (int _i = 0; _i < 2; ++_i) \
;         __builtin_amdgcn_global_load_lds((const unsigned*)((const char*)(gbase) + (voff)[_i]), (PG8_LAS unsigned*)(lds + (bufoff) + ldsw + _i * 8192), 16, 0, 0); } while (0)
; #define PG8_WAIT_V(n) asm volatile("s_waitcnt vmcnt(" #n ")" ::: "memory")
; #define PG8_BAR __builtin_amdgcn_s_barrier()
; template <class Epi, class Sched, bool ALIGN_EPI = false, bool SP2 = false, bool A_TILED = false>
; __device__ __forceinline__ void gemm_phase(PG8_LAS unsigned char* lds, const Gemm g, const Sched& S, const Epi& E, const int wave_s) {
;     ...
;     unsigned voffA[2], voffB[2];
; #pragma unroll
;     for (int i = 0; i < 2; ++i) { int R, C; stage_rc(tid * 16 + i * 8192, R, C); const int Rb = Epi::PERM ? ((R & ~31) + perm32(R & 31)) : R;
;         voffA[i] = A_TILED ? (unsigned)(tid * 16 + i * 8192) : (unsigned)(R * K + C) * 2u; voffB[i] = (unsigned)(Rb * K + C) * 2u; }
;     const size_t kstep = (size_t)(BK * 2);
;     const size_t hstep = (size_t)HALF * K * 2;
;     const size_t tstep = 2 * hstep;
;     const size_t kstepA = A_TILED ? (size_t)32768 : kstep, hstepA = A_TILED ? (size_t)16384 : hstep, tstepA = A_TILED ? (size_t)nt * 32768 : tstep;
;     const unsigned ldsw = (unsigned)wid * 1024u;
;     const int aoff = lds_byte(wr * 64 + fr, fq * 8), boff = lds_byte(wc * 32 + fr, fq * 8);
;     ...
;     if constexpr (SP2) {
;         PG8_STAGE(PG8_SB(0, 0), cB, voffB); PG8_STAGE(PG8_SB(0, 1), cB + hstep, voffB); PG8_STAGE(PG8_SA(0, 0), cA, voffA); PG8_STAGE(PG8_SA(0, 1), cA + hstepA, voffA);
;         if (wr == 1) PG8_BAR;
;         PG8_WAIT_V(2); PG8_BAR;
;         PG8_STAGE(PG8_SB(1, 0), cB + kstep, voffB); PG8_STAGE(PG8_SA(1, 0), cA + kstepA, voffA); PG8_STAGE(PG8_SB(1, 1), cB + hstep + kstep, voffB);
;         PG8_WAIT_V(6); PG8_BAR;
;     } else {
;         PG8_STAGE(PG8_SB(0, 0), cB, voffB); PG8_STAGE(PG8_SA(0, 0), cA, voffA); PG8_STAGE(PG8_SB(0, 1), cB + hstep, voffB); PG8_STAGE(PG8_SA(0, 1), cA + hstepA, voffA);
;         if (wr == 1) PG8_BAR;
;         PG8_WAIT_V(4); PG8_BAR;
;         PG8_STAGE(PG8_SB(1, 0), cB + kstep, voffB); PG8_STAGE(PG8_SA(1, 0), cA + kstepA, voffA); PG8_STAGE(PG8_SB(1, 1), cB + hstep + kstep, voffB);
;         PG8_WAIT_V(6); PG8_BAR;
.LBB0_3336:
	s_ashr_i32 s56, s86, 31
	s_add_u32 s0, s0, s29
	s_addc_u32 s1, s1, 0
	s_add_u32 s6, s0, 0x22600000
	s_addc_u32 s7, s1, 0
	s_lshl_b32 s57, s13, 6
	s_lshl_b32 s16, s13, 13
	s_lshl_b32 s0, s12, 5
	s_mov_b64 s[12:13], 0x80
	s_and_b32 s58, s0, 0x60
	s_add_i32 m0, s41, 0x18000
	v_lshl_add_u64 v[6:7], v[6:7], 0, s[12:13]
	s_lshl_b32 s17, s58, 7
	s_waitcnt vmcnt(2)
	s_barrier
	global_load_lds_dwordx4 v[6:7], off
	v_lshl_add_u64 v[4:5], v[4:5], 0, s[12:13]
	s_add_i32 m0, s41, 0x1a000
	s_add_i32 s59, s41, 0x8000
	s_add_i32 s60, s41, 0xa000
	global_load_lds_dwordx4 v[4:5], off
	v_lshl_add_u64 v[0:1], v[0:1], 0, s[12:13]
	s_mov_b32 m0, s59
	s_add_u32 s0, s42, 0x80080
	global_load_lds_dwordx4 v[0:1], off
	v_lshl_add_u64 v[0:1], v[2:3], 0, s[12:13]
	s_mov_b32 m0, s60
	s_addc_u32 s1, s43, 0
	global_load_lds_dwordx4 v[0:1], off
	s_add_i32 m0, s41, 0x1c000
	v_lshl_add_u64 v[0:1], s[0:1], 0, v[128:129]
	global_load_lds_dwordx4 v128, s[0:1]
	v_lshl_add_u64 v[0:1], s[0:1], 0, v[130:131]
	s_add_i32 m0, s41, 0x1e000
	s_movk_i32 s0, 0x3c0
	global_load_lds_dwordx4 v[0:1], off
	v_and_b32_e32 v0, 48, v8
	v_lshlrev_b32_e32 v1, 6, v8
	v_and_or_b32 v0, v1, s0, v0
	v_lshlrev_b32_e32 v1, 2, v8
	v_and_b32_e32 v1, 32, v1
	v_bitop3_b32 v2, v0, s16, v1 bitop3:0xde
	v_bitop3_b32 v148, s17, v0, v1 bitop3:0xf6
	v_lshlrev_b32_e32 v0, 15, v9
	v_and_b32_e32 v0, 0xffff0000, v0
	v_lshl_add_u32 v0, v10, 12, v0
	v_and_b32_e32 v1, 1, v9
	v_lshl_or_b32 v0, v1, 6, v0
	v_lshl_add_u32 v136, v11, 1, v0
	v_lshlrev_b32_e32 v0, 15, v13
	v_and_b32_e32 v0, 0xffff0000, v0
	s_waitcnt vmcnt(6)
	s_cmpk_lt_u32 s15, 0x100
	v_lshl_add_u32 v0, v12, 12, v0
	v_and_b32_e32 v1, 1, v13
	s_sext_i32_i16 s66, s14
	s_cselect_b64 s[14:15], -1, 0
	v_mov_b32_e32 v137, 0
	v_lshl_or_b32 v0, v1, 6, v0
	s_add_i32 s61, 0, 0x10000
	s_add_i32 s62, 0, 0x14000
	v_lshl_add_u32 v138, v14, 1, v0
	v_mov_b32_e32 v139, v137
	s_mov_b64 s[16:17], 0x180
	v_add_u32_e32 v149, s61, v148
	v_add_u32_e32 v150, s62, v148
	v_add_u32_e32 v151, 0, v2
	s_mov_b64 s[20:21], 0x100
	s_movk_i32 s63, 0x3000
	s_add_i32 s64, s41, 0xc000
	s_add_i32 s65, s41, 0xe000
	s_barrier
	s_branch .LBB0_3339

; template <class Epi, class Sched, bool ALIGN_EPI = false, bool SP2 = false, bool A_TILED = false>
; __device__ __forceinline__ void gemm_phase(PG8_LAS unsigned char* lds, const Gemm g, const Sched& S, const Epi& E, const int wave_s) {
;     ...
;         const char* nA = has_next ? (const char*)g.A + (size_t)nxt.pm * tstepA : cA; const char* nB = has_next ? (const char*)g.Bt + (size_t)nxt.pn * tstep : cB;
;         constexpr bool PEEL = SP2 && !Epi::AFTER_DRAIN;
;         if constexpr (PEEL) {
;             const char* a1 = cA + kstepA; const char* a2 = cA + 2 * kstepA; const char* b2 = cB + 2 * kstep; const char* a3 = a2 + kstepA; const char* b3 = b2 + kstep;
;             PG8_ITER(PG8_MMAZ)
.LBB0_3341:
	s_ashr_i32 s25, s24, 31
	ds_read_b128 v[0:3], v149
	ds_read_b128 v[4:7], v149 offset:1024
	ds_read_b128 v[8:11], v149 offset:2048
	ds_read_b128 v[12:15], v149 offset:3072
	ds_read_b128 v[16:19], v150
	ds_read_b128 v[20:23], v150 offset:1024
	ds_read_b128 v[24:27], v150 offset:2048
	ds_read_b128 v[28:31], v150 offset:3072
	s_lshl_b64 s[26:27], s[24:25], 20
	s_add_u32 s26, s9, s26
	s_addc_u32 s27, s36, s27
	s_and_b64 s[38:39], s[0:1], exec
	s_cselect_b32 s25, s27, s45
	s_cselect_b32 s67, s26, s44
	s_ashr_i32 s23, s22, 31
	s_lshl_b64 s[38:39], s[22:23], 20
	s_add_u32 s38, s37, s38
	s_addc_u32 s39, s48, s39
	s_and_b64 s[46:47], s[0:1], exec
	s_cselect_b32 s23, s39, s43
	s_cselect_b32 s68, s38, s42
	s_add_u32 s46, s44, 0x80080
	s_addc_u32 s47, s45, 0
	s_mov_b32 m0, s64
	v_lshl_add_u64 v[64:65], s[46:47], 0, v[134:135]
	ds_read_b128 v[32:35], v151
	ds_read_b128 v[36:39], v151 offset:1024
	ds_read_b128 v[40:43], v151 offset:2048
	ds_read_b128 v[44:47], v151 offset:3072
	ds_read_b128 v[48:51], v151 offset:4096
	ds_read_b128 v[52:55], v151 offset:5120
	ds_read_b128 v[56:59], v151 offset:6144
	ds_read_b128 v[60:63], v151 offset:7168
	global_load_lds_dwordx4 v134, s[46:47]
	v_lshl_add_u64 v[64:65], s[46:47], 0, v[132:133]
	s_mov_b32 m0, s65
	s_nop 0
	global_load_lds_dwordx4 v132, s[46:47]
	s_waitcnt vmcnt(8) lgkmcnt(0)
	s_setprio 1
	s_barrier
	v_mfma_f32_16x16x32_bf16 v[88:91], v[0:3], v[56:59], 0
	v_mfma_f32_16x16x32_bf16 v[64:67], v[0:3], v[32:35], 0
	v_mfma_f32_16x16x32_bf16 v[68:71], v[8:11], v[32:35], 0
	v_mfma_f32_16x16x32_bf16 v[72:75], v[0:3], v[40:43], 0
	v_mfma_f32_16x16x32_bf16 v[76:79], v[8:11], v[40:43], 0
	v_mfma_f32_16x16x32_bf16 v[80:83], v[0:3], v[48:51], 0
	v_mfma_f32_16x16x32_bf16 v[84:87], v[8:11], v[48:51], 0
	v_mfma_f32_16x16x32_bf16 v[92:95], v[4:7], v[60:63], v[88:91]
	v_mfma_f32_16x16x32_bf16 v[88:91], v[8:11], v[56:59], 0
	v_mfma_f32_16x16x32_bf16 v[64:67], v[4:7], v[36:39], v[64:67]
	v_mfma_f32_16x16x32_bf16 v[68:71], v[12:15], v[36:39], v[68:71]
	v_mfma_f32_16x16x32_bf16 v[72:75], v[4:7], v[44:47], v[72:75]
	v_mfma_f32_16x16x32_bf16 v[76:79], v[12:15], v[44:47], v[76:79]
	v_mfma_f32_16x16x32_bf16 v[80:83], v[4:7], v[52:55], v[80:83]
	v_mfma_f32_16x16x32_bf16 v[84:87], v[12:15], v[52:55], v[84:87]
	v_mfma_f32_16x16x32_bf16 v[100:103], v[12:15], v[60:63], v[88:91]
	s_setprio 0
	s_setprio 1
	v_mfma_f32_16x16x32_bf16 v[88:91], v[16:19], v[32:35], 0
	v_mfma_f32_16x16x32_bf16 v[32:35], v[24:27], v[32:35], 0
	v_mfma_f32_16x16x32_bf16 v[108:111], v[20:23], v[36:39], v[88:91]
	v_mfma_f32_16x16x32_bf16 v[32:35], v[28:31], v[36:39], v[32:35]
	v_mfma_f32_16x16x32_bf16 v[36:39], v[16:19], v[40:43], 0
	v_mfma_f32_16x16x32_bf16 v[40:43], v[24:27], v[40:43], 0
	v_mfma_f32_16x16x32_bf16 v[36:39], v[20:23], v[44:47], v[36:39]
	v_mfma_f32_16x16x32_bf16 v[40:43], v[28:31], v[44:47], v[40:43]
	v_mfma_f32_16x16x32_bf16 v[44:47], v[16:19], v[48:51], 0
	v_mfma_f32_16x16x32_bf16 v[48:51], v[24:27], v[48:51], 0
	v_mfma_f32_16x16x32_bf16 v[44:47], v[20:23], v[52:55], v[44:47]
	v_mfma_f32_16x16x32_bf16 v[52:55], v[28:31], v[52:55], v[48:51]
	v_mfma_f32_16x16x32_bf16 v[48:51], v[16:19], v[56:59], 0
	v_mfma_f32_16x16x32_bf16 v[152:155], v[20:23], v[60:63], v[48:51]
	v_mfma_f32_16x16x32_bf16 v[48:51], v[24:27], v[56:59], 0
	v_mfma_f32_16x16x32_bf16 v[156:159], v[28:31], v[60:63], v[48:51]
	s_barrier
	s_setprio 0
	s_add_i32 s69, s61, s49
	v_lshl_add_u64 v[146:147], s[42:43], 0, v[128:129]
	s_add_i32 s70, s69, 0x2000
	v_lshl_add_u64 v[120:121], v[146:147], 0, s[20:21]
	s_mov_b32 m0, s69
	v_lshl_add_u64 v[252:253], s[42:43], 0, v[130:131]
	s_add_u32 s46, s42, 0x80100
	ds_read_b128 v[48:51], v151 offset:16384
	ds_read_b128 v[56:59], v151 offset:17408
	ds_read_b128 v[60:63], v151 offset:18432
	ds_read_b128 v[88:91], v151 offset:19456
	ds_read_b128 v[96:99], v151 offset:20480
	ds_read_b128 v[104:107], v151 offset:21504
	ds_read_b128 v[112:115], v151 offset:22528
	ds_read_b128 v[116:119], v151 offset:23552
	global_load_lds_dwordx4 v[120:121], off
	v_lshl_add_u64 v[120:121], v[252:253], 0, s[20:21]
	s_mov_b32 m0, s70
	s_addc_u32 s47, s43, 0
	s_add_i32 s71, s62, s49
	global_load_lds_dwordx4 v[120:121], off
	v_lshl_add_u64 v[120:121], s[46:47], 0, v[128:129]
	s_mov_b32 m0, s71
	s_add_i32 s72, s71, 0x2000
	global_load_lds_dwordx4 v128, s[46:47]
	v_lshl_add_u64 v[120:121], s[46:47], 0, v[130:131]
	s_mov_b32 m0, s72
	v_lshl_add_u64 v[140:141], s[44:45], 0, v[134:135]
	global_load_lds_dwordx4 v130, s[46:47]
	v_lshl_add_u64 v[120:121], v[140:141], 0, s[20:21]
	s_mov_b32 m0, s41
	v_lshl_add_u64 v[142:143], s[44:45], 0, v[132:133]
	global_load_lds_dwordx4 v[120:121], off
	v_lshl_add_u64 v[120:121], v[142:143], 0, s[20:21]
	s_mov_b32 m0, s52
	s_nop 0
	global_load_lds_dwordx4 v[120:121], off
	s_waitcnt vmcnt(8) lgkmcnt(0)
	s_setprio 1
	s_barrier
	v_mfma_f32_16x16x32_bf16 v[120:123], v[0:3], v[48:51], 0
	v_mfma_f32_16x16x32_bf16 v[160:163], v[4:7], v[56:59], v[120:123]
	v_mfma_f32_16x16x32_bf16 v[120:123], v[8:11], v[48:51], 0
	v_mfma_f32_16x16x32_bf16 v[164:167], v[12:15], v[56:59], v[120:123]
	v_mfma_f32_16x16x32_bf16 v[120:123], v[0:3], v[60:63], 0
	v_mfma_f32_16x16x32_bf16 v[168:171], v[4:7], v[88:91], v[120:123]
	v_mfma_f32_16x16x32_bf16 v[120:123], v[8:11], v[60:63], 0
	v_mfma_f32_16x16x32_bf16 v[172:175], v[12:15], v[88:91], v[120:123]
	v_mfma_f32_16x16x32_bf16 v[120:123], v[0:3], v[96:99], 0
	v_mfma_f32_16x16x32_bf16 v[0:3], v[0:3], v[112:115], 0
	v_mfma_f32_16x16x32_bf16 v[176:179], v[4:7], v[104:107], v[120:123]
	v_mfma_f32_16x16x32_bf16 v[0:3], v[4:7], v[116:119], v[0:3]
	v_mfma_f32_16x16x32_bf16 v[4:7], v[8:11], v[112:115], 0
	v_mfma_f32_16x16x32_bf16 v[120:123], v[8:11], v[96:99], 0
	v_mfma_f32_16x16x32_bf16 v[4:7], v[12:15], v[116:119], v[4:7]
	v_mfma_f32_16x16x32_bf16 v[180:183], v[12:15], v[104:107], v[120:123]
	s_setprio 0
	s_setprio 1
	v_mfma_f32_16x16x32_bf16 v[8:11], v[16:19], v[48:51], 0
	v_mfma_f32_16x16x32_bf16 v[12:15], v[20:23], v[56:59], v[8:11]
	v_mfma_f32_16x16x32_bf16 v[8:11], v[24:27], v[48:51], 0
	v_mfma_f32_16x16x32_bf16 v[184:187], v[28:31], v[56:59], v[8:11]
	v_mfma_f32_16x16x32_bf16 v[8:11], v[16:19], v[60:63], 0
	v_mfma_f32_16x16x32_bf16 v[188:191], v[20:23], v[88:91], v[8:11]
	v_mfma_f32_16x16x32_bf16 v[8:11], v[24:27], v[60:63], 0
	v_mfma_f32_16x16x32_bf16 v[192:195], v[28:31], v[88:91], v[8:11]
	v_mfma_f32_16x16x32_bf16 v[8:11], v[16:19], v[96:99], 0
	v_mfma_f32_16x16x32_bf16 v[196:199], v[20:23], v[104:107], v[8:11]
	v_mfma_f32_16x16x32_bf16 v[8:11], v[24:27], v[96:99], 0
	v_mfma_f32_16x16x32_bf16 v[200:203], v[28:31], v[104:107], v[8:11]
	v_mfma_f32_16x16x32_bf16 v[8:11], v[16:19], v[112:115], 0
	v_mfma_f32_16x16x32_bf16 v[204:207], v[20:23], v[116:119], v[8:11]
	v_mfma_f32_16x16x32_bf16 v[8:11], v[24:27], v[112:115], 0
	v_mfma_f32_16x16x32_bf16 v[208:211], v[28:31], v[116:119], v[8:11]
	s_barrier
	s_setprio 0
	s_add_i32 s73, 0, 0x18000
	s_add_i32 s75, 0, 0x1c000
	v_add_u32_e32 v144, s73, v148
	v_add_u32_e32 v145, s75, v148
	s_nop 0
	ds_read_b128 v[8:11], v144
	ds_read_b128 v[20:23], v144 offset:1024
	ds_read_b128 v[28:31], v144 offset:2048
	ds_read_b128 v[212:215], v144 offset:3072
	ds_read_b128 v[216:219], v145
	ds_read_b128 v[220:223], v145 offset:1024
	ds_read_b128 v[224:227], v145 offset:2048
	ds_read_b128 v[228:231], v145 offset:3072
	s_add_u32 s46, s44, 0x80100
	s_addc_u32 s47, s45, 0
	s_mov_b32 m0, s53
	v_lshl_add_u64 v[48:49], s[46:47], 0, v[134:135]
	ds_read_b128 v[16:19], v151 offset:32768
	ds_read_b128 v[24:27], v151 offset:33792
	ds_read_b128 v[60:63], v151 offset:34816
	ds_read_b128 v[232:235], v151 offset:35840
	ds_read_b128 v[236:239], v151 offset:36864
	ds_read_b128 v[240:243], v151 offset:37888
	ds_read_b128 v[244:247], v151 offset:38912
	ds_read_b128 v[248:251], v151 offset:39936
	global_load_lds_dwordx4 v134, s[46:47]
	v_lshl_add_u64 v[48:49], s[46:47], 0, v[132:133]
	s_mov_b32 m0, s54
	s_nop 0
	global_load_lds_dwordx4 v132, s[46:47]
	s_waitcnt vmcnt(8) lgkmcnt(0)
	s_setprio 1
	s_barrier
	v_mfma_f32_16x16x32_bf16 v[48:51], v[8:11], v[16:19], v[64:67]
	v_mfma_f32_16x16x32_bf16 v[120:123], v[20:23], v[24:27], v[48:51]
	v_mfma_f32_16x16x32_bf16 v[48:51], v[28:31], v[16:19], v[68:71]
	v_mfma_f32_16x16x32_bf16 v[112:115], v[212:215], v[24:27], v[48:51]
	v_mfma_f32_16x16x32_bf16 v[48:51], v[8:11], v[60:63], v[72:75]
	v_mfma_f32_16x16x32_bf16 v[104:107], v[20:23], v[232:235], v[48:51]
	v_mfma_f32_16x16x32_bf16 v[48:51], v[28:31], v[60:63], v[76:79]
	v_mfma_f32_16x16x32_bf16 v[96:99], v[212:215], v[232:235], v[48:51]
	v_mfma_f32_16x16x32_bf16 v[48:51], v[8:11], v[236:239], v[80:83]
	v_mfma_f32_16x16x32_bf16 v[88:91], v[20:23], v[240:243], v[48:51]
	v_mfma_f32_16x16x32_bf16 v[48:51], v[28:31], v[236:239], v[84:87]
	v_mfma_f32_16x16x32_bf16 v[80:83], v[212:215], v[240:243], v[48:51]
	v_mfma_f32_16x16x32_bf16 v[48:51], v[8:11], v[244:247], v[92:95]
	v_mfma_f32_16x16x32_bf16 v[56:59], v[20:23], v[248:251], v[48:51]
	v_mfma_f32_16x16x32_bf16 v[48:51], v[28:31], v[244:247], v[100:103]
	v_mfma_f32_16x16x32_bf16 v[48:51], v[212:215], v[248:251], v[48:51]
	s_setprio 0
	s_setprio 1
	v_mfma_f32_16x16x32_bf16 v[64:67], v[216:219], v[16:19], v[108:111]
	v_mfma_f32_16x16x32_bf16 v[16:19], v[224:227], v[16:19], v[32:35]
	v_mfma_f32_16x16x32_bf16 v[116:119], v[228:231], v[24:27], v[16:19]
	v_mfma_f32_16x16x32_bf16 v[16:19], v[216:219], v[60:63], v[36:39]
	v_mfma_f32_16x16x32_bf16 v[108:111], v[220:223], v[232:235], v[16:19]
	v_mfma_f32_16x16x32_bf16 v[16:19], v[224:227], v[60:63], v[40:43]
	v_mfma_f32_16x16x32_bf16 v[100:103], v[228:231], v[232:235], v[16:19]
	v_mfma_f32_16x16x32_bf16 v[16:19], v[216:219], v[236:239], v[44:47]
	v_mfma_f32_16x16x32_bf16 v[92:95], v[220:223], v[240:243], v[16:19]
	v_mfma_f32_16x16x32_bf16 v[16:19], v[224:227], v[236:239], v[52:55]
	v_mfma_f32_16x16x32_bf16 v[84:87], v[228:231], v[240:243], v[16:19]
	v_mfma_f32_16x16x32_bf16 v[16:19], v[216:219], v[244:247], v[152:155]
	v_mfma_f32_16x16x32_bf16 v[60:63], v[220:223], v[248:251], v[16:19]
	v_mfma_f32_16x16x32_bf16 v[16:19], v[224:227], v[244:247], v[156:159]
	v_mfma_f32_16x16x32_bf16 v[124:127], v[220:223], v[24:27], v[64:67]
	v_mfma_f32_16x16x32_bf16 v[52:55], v[228:231], v[248:251], v[16:19]
	s_barrier
; #define PG8_MMA(ai, bj, At, Bt) do { __builtin_amdgcn_s_setprio(1); _Pragma("unroll") for (int m = 0; m < 4; ++m) _Pragma("unroll") for (int n = 0; n < 2; ++n) _Pragma("unroll") for (int k = 0; k < 2; ++k) \
;         acc[ai][bj][m][n] = __builtin_amdgcn_mfma_f32_16x16x32_bf16(Bt[n][k], At[m][k], acc[ai][bj][m][n], 0, 0, 0); __builtin_amdgcn_s_setprio(0); } while (0)
; template <class Epi, class Sched, bool ALIGN_EPI = false, bool SP2 = false, bool A_TILED = false>
; __device__ __forceinline__ void gemm_phase(PG8_LAS unsigned char* lds, const Gemm g, const Sched& S, const Epi& E, const int wave_s) {
;     ...
;         for (int t = PEEL ? 2 : 0; t < nt; t += 2) {
;             const bool last = (t == nt - 2);
;             const char* a1 = cA + (size_t)(t + 1) * kstepA;
;             const char* a2 = last ? nA : cA + (size_t)(t + 2) * kstepA; const char* b2 = last ? nB : cB + (size_t)(t + 2) * kstep;
;             const char* a3 = a2 + kstepA; const char* b3 = b2 + kstep;
;             if (last && has_next) S.a_ready(nxt);
;             if constexpr (SP2) {
;             PG8_ITER(PG8_MMA)
	s_setprio 0
	s_add_i32 s73, s73, s49
	s_add_i32 s74, s73, 0x2000
	s_nop 1
	v_lshl_add_u64 v[16:17], v[146:147], 0, s[16:17]
	s_mov_b32 m0, s73
	s_add_u32 s46, s42, 0x80180
	ds_read_b128 v[36:39], v151 offset:49152
	ds_read_b128 v[44:47], v151 offset:50176
	ds_read_b128 v[152:155], v151 offset:51200
	ds_read_b128 v[156:159], v151 offset:52224
	ds_read_b128 v[232:235], v151 offset:53248
	ds_read_b128 v[236:239], v151 offset:54272
	ds_read_b128 v[240:243], v151 offset:55296
	ds_read_b128 v[244:247], v151 offset:56320
	global_load_lds_dwordx4 v[16:17], off
	v_lshl_add_u64 v[16:17], v[252:253], 0, s[16:17]
	s_mov_b32 m0, s74
	s_addc_u32 s47, s43, 0
	s_add_i32 s75, s75, s49
	global_load_lds_dwordx4 v[16:17], off
	v_lshl_add_u64 v[16:17], s[46:47], 0, v[128:129]
	s_mov_b32 m0, s75
	s_add_i32 s76, s75, 0x2000
	global_load_lds_dwordx4 v128, s[46:47]
	v_lshl_add_u64 v[16:17], s[46:47], 0, v[130:131]
	s_mov_b32 m0, s76
	s_nop 0
	global_load_lds_dwordx4 v130, s[46:47]
	v_lshl_add_u64 v[16:17], v[140:141], 0, s[16:17]
	s_mov_b32 m0, s59
	s_nop 0
	global_load_lds_dwordx4 v[16:17], off
	v_lshl_add_u64 v[16:17], v[142:143], 0, s[16:17]
	s_mov_b32 m0, s60
	s_nop 0
	global_load_lds_dwordx4 v[16:17], off
	s_waitcnt vmcnt(8) lgkmcnt(0)
	s_setprio 1
	s_barrier
	v_mfma_f32_16x16x32_bf16 v[16:19], v[8:11], v[36:39], v[160:163]
	v_mfma_f32_16x16x32_bf16 v[72:75], v[20:23], v[44:47], v[16:19]
	v_mfma_f32_16x16x32_bf16 v[16:19], v[28:31], v[36:39], v[164:167]
	v_mfma_f32_16x16x32_bf16 v[64:67], v[212:215], v[44:47], v[16:19]
	v_mfma_f32_16x16x32_bf16 v[16:19], v[8:11], v[152:155], v[168:171]
	v_mfma_f32_16x16x32_bf16 v[40:43], v[20:23], v[156:159], v[16:19]
	v_mfma_f32_16x16x32_bf16 v[16:19], v[28:31], v[152:155], v[172:175]
	v_mfma_f32_16x16x32_bf16 v[32:35], v[212:215], v[156:159], v[16:19]
	v_mfma_f32_16x16x32_bf16 v[16:19], v[8:11], v[232:235], v[176:179]
	v_mfma_f32_16x16x32_bf16 v[0:3], v[8:11], v[240:243], v[0:3]
	v_mfma_f32_16x16x32_bf16 v[24:27], v[20:23], v[236:239], v[16:19]
	v_mfma_f32_16x16x32_bf16 v[16:19], v[28:31], v[232:235], v[180:183]
	v_mfma_f32_16x16x32_bf16 v[8:11], v[20:23], v[244:247], v[0:3]
	v_mfma_f32_16x16x32_bf16 v[0:3], v[28:31], v[240:243], v[4:7]
	v_mfma_f32_16x16x32_bf16 v[16:19], v[212:215], v[236:239], v[16:19]
	v_mfma_f32_16x16x32_bf16 v[0:3], v[212:215], v[244:247], v[0:3]
	s_setprio 0
	s_setprio 1
	v_mfma_f32_16x16x32_bf16 v[4:7], v[216:219], v[36:39], v[12:15]
	v_mfma_f32_16x16x32_bf16 v[76:79], v[220:223], v[44:47], v[4:7]
	v_mfma_f32_16x16x32_bf16 v[4:7], v[224:227], v[36:39], v[184:187]
	v_mfma_f32_16x16x32_bf16 v[68:71], v[228:231], v[44:47], v[4:7]
	v_mfma_f32_16x16x32_bf16 v[4:7], v[216:219], v[152:155], v[188:191]
	v_mfma_f32_16x16x32_bf16 v[44:47], v[220:223], v[156:159], v[4:7]
	v_mfma_f32_16x16x32_bf16 v[4:7], v[224:227], v[152:155], v[192:195]
	v_mfma_f32_16x16x32_bf16 v[36:39], v[228:231], v[156:159], v[4:7]
	v_mfma_f32_16x16x32_bf16 v[4:7], v[216:219], v[232:235], v[196:199]
	v_mfma_f32_16x16x32_bf16 v[28:31], v[220:223], v[236:239], v[4:7]
	v_mfma_f32_16x16x32_bf16 v[4:7], v[224:227], v[232:235], v[200:203]
	v_mfma_f32_16x16x32_bf16 v[20:23], v[228:231], v[236:239], v[4:7]
	v_mfma_f32_16x16x32_bf16 v[4:7], v[216:219], v[240:243], v[204:207]
	v_mfma_f32_16x16x32_bf16 v[12:15], v[220:223], v[244:247], v[4:7]
	v_mfma_f32_16x16x32_bf16 v[4:7], v[224:227], v[240:243], v[208:211]
	v_mfma_f32_16x16x32_bf16 v[4:7], v[228:231], v[244:247], v[4:7]
	s_barrier
	s_setprio 0
	s_add_u32 s77, s42, 0x200
	s_addc_u32 s78, s43, 0
	s_add_u32 s42, s44, 0x80180
	s_addc_u32 s43, s45, 0
	s_mov_b32 s79, 0
.LBB0_3342:
	ds_read_b128 v[152:155], v149
	ds_read_b128 v[156:159], v149 offset:1024
	ds_read_b128 v[160:163], v149 offset:2048
	ds_read_b128 v[164:167], v149 offset:3072
	ds_read_b128 v[168:171], v150
	ds_read_b128 v[172:175], v150 offset:1024
	ds_read_b128 v[176:179], v150 offset:2048
	ds_read_b128 v[180:183], v150 offset:3072
	s_add_u32 s44, s42, 0xfff80080
	s_addc_u32 s45, s43, -1
	s_cmp_eq_u32 s79, 28
	s_cselect_b32 s47, s25, s45
	s_cselect_b32 s46, s67, s44
	s_cselect_b32 s45, s23, s78
	s_cselect_b32 s44, s68, s77
	s_mov_b32 m0, s64
	v_lshl_add_u64 v[140:141], s[42:43], 0, v[138:139]
	ds_read_b128 v[184:187], v151
	ds_read_b128 v[188:191], v151 offset:1024
	ds_read_b128 v[192:195], v151 offset:2048
	ds_read_b128 v[196:199], v151 offset:3072
	ds_read_b128 v[200:203], v151 offset:4096
	ds_read_b128 v[204:207], v151 offset:5120
	ds_read_b128 v[208:211], v151 offset:6144
	ds_read_b128 v[212:215], v151 offset:7168
	global_load_lds_dwordx4 v138, s[42:43]
	v_lshl_add_u64 v[140:141], s[42:43], 0, v[136:137]
	s_mov_b32 m0, s65
	s_nop 0
	global_load_lds_dwordx4 v136, s[42:43]
	s_waitcnt vmcnt(8) lgkmcnt(0)
	s_setprio 1
	s_barrier
	v_mfma_f32_16x16x32_bf16 v[120:123], v[152:155], v[184:187], v[120:123]
	v_mfma_f32_16x16x32_bf16 v[112:115], v[160:163], v[184:187], v[112:115]
	v_mfma_f32_16x16x32_bf16 v[104:107], v[152:155], v[192:195], v[104:107]
	v_mfma_f32_16x16x32_bf16 v[96:99], v[160:163], v[192:195], v[96:99]
	v_mfma_f32_16x16x32_bf16 v[88:91], v[152:155], v[200:203], v[88:91]
	v_mfma_f32_16x16x32_bf16 v[80:83], v[160:163], v[200:203], v[80:83]
	v_mfma_f32_16x16x32_bf16 v[56:59], v[152:155], v[208:211], v[56:59]
	v_mfma_f32_16x16x32_bf16 v[48:51], v[160:163], v[208:211], v[48:51]
	v_mfma_f32_16x16x32_bf16 v[120:123], v[156:159], v[188:191], v[120:123]
	v_mfma_f32_16x16x32_bf16 v[112:115], v[164:167], v[188:191], v[112:115]
	v_mfma_f32_16x16x32_bf16 v[104:107], v[156:159], v[196:199], v[104:107]
	v_mfma_f32_16x16x32_bf16 v[96:99], v[164:167], v[196:199], v[96:99]
	v_mfma_f32_16x16x32_bf16 v[88:91], v[156:159], v[204:207], v[88:91]
	v_mfma_f32_16x16x32_bf16 v[80:83], v[164:167], v[204:207], v[80:83]
	v_mfma_f32_16x16x32_bf16 v[56:59], v[156:159], v[212:215], v[56:59]
	v_mfma_f32_16x16x32_bf16 v[48:51], v[164:167], v[212:215], v[48:51]
	s_setprio 0
	s_setprio 1
	v_mfma_f32_16x16x32_bf16 v[124:127], v[168:171], v[184:187], v[124:127]
	v_mfma_f32_16x16x32_bf16 v[116:119], v[176:179], v[184:187], v[116:119]
	v_mfma_f32_16x16x32_bf16 v[108:111], v[168:171], v[192:195], v[108:111]
	v_mfma_f32_16x16x32_bf16 v[100:103], v[176:179], v[192:195], v[100:103]
	v_mfma_f32_16x16x32_bf16 v[92:95], v[168:171], v[200:203], v[92:95]
	v_mfma_f32_16x16x32_bf16 v[84:87], v[176:179], v[200:203], v[84:87]
	v_mfma_f32_16x16x32_bf16 v[60:63], v[168:171], v[208:211], v[60:63]
	v_mfma_f32_16x16x32_bf16 v[52:55], v[176:179], v[208:211], v[52:55]
	v_mfma_f32_16x16x32_bf16 v[124:127], v[172:175], v[188:191], v[124:127]
	v_mfma_f32_16x16x32_bf16 v[116:119], v[180:183], v[188:191], v[116:119]
	v_mfma_f32_16x16x32_bf16 v[108:111], v[172:175], v[196:199], v[108:111]
	v_mfma_f32_16x16x32_bf16 v[100:103], v[180:183], v[196:199], v[100:103]
	v_mfma_f32_16x16x32_bf16 v[92:95], v[172:175], v[204:207], v[92:95]
	v_mfma_f32_16x16x32_bf16 v[84:87], v[180:183], v[204:207], v[84:87]
	v_mfma_f32_16x16x32_bf16 v[60:63], v[172:175], v[212:215], v[60:63]
	v_mfma_f32_16x16x32_bf16 v[52:55], v[180:183], v[212:215], v[52:55]
	s_barrier
	s_setprio 0
	s_mov_b32 m0, s69
	v_lshl_add_u64 v[140:141], s[44:45], 0, v[128:129]
	s_add_u32 s80, s44, 0x80000
	ds_read_b128 v[184:187], v151 offset:16384
	ds_read_b128 v[188:191], v151 offset:17408
	ds_read_b128 v[192:195], v151 offset:18432
	ds_read_b128 v[196:199], v151 offset:19456
	ds_read_b128 v[200:203], v151 offset:20480
	ds_read_b128 v[204:207], v151 offset:21504
	ds_read_b128 v[208:211], v151 offset:22528
	ds_read_b128 v[212:215], v151 offset:23552
	global_load_lds_dwordx4 v128, s[44:45]
	v_lshl_add_u64 v[142:143], s[44:45], 0, v[130:131]
	s_mov_b32 m0, s70
	s_addc_u32 s81, s45, 0
	global_load_lds_dwordx4 v130, s[44:45]
	v_lshl_add_u64 v[146:147], s[80:81], 0, v[128:129]
	s_mov_b32 m0, s71
	v_lshl_add_u64 v[216:217], s[46:47], 0, v[132:133]
	global_load_lds_dwordx4 v128, s[80:81]
	v_lshl_add_u64 v[146:147], s[80:81], 0, v[130:131]
	s_mov_b32 m0, s72
	s_nop 0
	global_load_lds_dwordx4 v130, s[80:81]
	v_lshl_add_u64 v[146:147], s[46:47], 0, v[134:135]
	s_mov_b32 m0, s41
	s_nop 0
	global_load_lds_dwordx4 v134, s[46:47]
	s_mov_b32 m0, s52
	s_nop 0
	global_load_lds_dwordx4 v132, s[46:47]
	s_waitcnt vmcnt(8) lgkmcnt(0)
	s_setprio 1
	s_barrier
	v_mfma_f32_16x16x32_bf16 v[72:75], v[152:155], v[184:187], v[72:75]
	v_mfma_f32_16x16x32_bf16 v[64:67], v[160:163], v[184:187], v[64:67]
	v_mfma_f32_16x16x32_bf16 v[40:43], v[152:155], v[192:195], v[40:43]
	v_mfma_f32_16x16x32_bf16 v[32:35], v[160:163], v[192:195], v[32:35]
	v_mfma_f32_16x16x32_bf16 v[24:27], v[152:155], v[200:203], v[24:27]
	v_mfma_f32_16x16x32_bf16 v[16:19], v[160:163], v[200:203], v[16:19]
	v_mfma_f32_16x16x32_bf16 v[8:11], v[152:155], v[208:211], v[8:11]
	v_mfma_f32_16x16x32_bf16 v[0:3], v[160:163], v[208:211], v[0:3]
	v_mfma_f32_16x16x32_bf16 v[72:75], v[156:159], v[188:191], v[72:75]
	v_mfma_f32_16x16x32_bf16 v[64:67], v[164:167], v[188:191], v[64:67]
	v_mfma_f32_16x16x32_bf16 v[40:43], v[156:159], v[196:199], v[40:43]
	v_mfma_f32_16x16x32_bf16 v[32:35], v[164:167], v[196:199], v[32:35]
	v_mfma_f32_16x16x32_bf16 v[24:27], v[156:159], v[204:207], v[24:27]
	v_mfma_f32_16x16x32_bf16 v[16:19], v[164:167], v[204:207], v[16:19]
	v_mfma_f32_16x16x32_bf16 v[8:11], v[156:159], v[212:215], v[8:11]
	v_mfma_f32_16x16x32_bf16 v[0:3], v[164:167], v[212:215], v[0:3]
	s_setprio 0
	s_setprio 1
	v_mfma_f32_16x16x32_bf16 v[76:79], v[168:171], v[184:187], v[76:79]
	v_mfma_f32_16x16x32_bf16 v[68:71], v[176:179], v[184:187], v[68:71]
	v_mfma_f32_16x16x32_bf16 v[44:47], v[168:171], v[192:195], v[44:47]
	v_mfma_f32_16x16x32_bf16 v[36:39], v[176:179], v[192:195], v[36:39]
	v_mfma_f32_16x16x32_bf16 v[28:31], v[168:171], v[200:203], v[28:31]
	v_mfma_f32_16x16x32_bf16 v[20:23], v[176:179], v[200:203], v[20:23]
	v_mfma_f32_16x16x32_bf16 v[12:15], v[168:171], v[208:211], v[12:15]
	v_mfma_f32_16x16x32_bf16 v[4:7], v[176:179], v[208:211], v[4:7]
	v_mfma_f32_16x16x32_bf16 v[76:79], v[172:175], v[188:191], v[76:79]
	v_mfma_f32_16x16x32_bf16 v[68:71], v[180:183], v[188:191], v[68:71]
	v_mfma_f32_16x16x32_bf16 v[44:47], v[172:175], v[196:199], v[44:47]
	v_mfma_f32_16x16x32_bf16 v[36:39], v[180:183], v[196:199], v[36:39]
	v_mfma_f32_16x16x32_bf16 v[28:31], v[172:175], v[204:207], v[28:31]
	v_mfma_f32_16x16x32_bf16 v[20:23], v[180:183], v[204:207], v[20:23]
	v_mfma_f32_16x16x32_bf16 v[12:15], v[172:175], v[212:215], v[12:15]
	v_mfma_f32_16x16x32_bf16 v[4:7], v[180:183], v[212:215], v[4:7]
	s_barrier
; #define PG8_MMA(ai, bj, At, Bt) do { __builtin_amdgcn_s_setprio(1); _Pragma("unroll") for (int m = 0; m < 4; ++m) _Pragma("unroll") for (int n = 0; n < 2; ++n) _Pragma("unroll") for (int k = 0; k < 2; ++k) \
;         acc[ai][bj][m][n] = __builtin_amdgcn_mfma_f32_16x16x32_bf16(Bt[n][k], At[m][k], acc[ai][bj][m][n], 0, 0, 0); __builtin_amdgcn_s_setprio(0); } while (0)
; template <class Epi, class Sched, bool ALIGN_EPI = false, bool SP2 = false, bool A_TILED = false>
; __device__ __forceinline__ void gemm_phase(PG8_LAS unsigned char* lds, const Gemm g, const Sched& S, const Epi& E, const int wave_s) {
;     ...
; #pragma nounroll
;         for (int t = PEEL ? 2 : 0; t < nt; t += 2) {
;             const bool last = (t == nt - 2);
;             const char* a1 = cA + (size_t)(t + 1) * kstepA;
;             const char* a2 = last ? nA : cA + (size_t)(t + 2) * kstepA; const char* b2 = last ? nB : cB + (size_t)(t + 2) * kstep;
;             const char* a3 = a2 + kstepA; const char* b3 = b2 + kstep;
;             if (last && has_next) S.a_ready(nxt);
;             if constexpr (SP2) {
;             PG8_ITER(PG8_MMA)
	s_setprio 0
	ds_read_b128 v[152:155], v144
	ds_read_b128 v[156:159], v144 offset:1024
	ds_read_b128 v[160:163], v144 offset:2048
	ds_read_b128 v[164:167], v144 offset:3072
	ds_read_b128 v[168:171], v145
	ds_read_b128 v[172:175], v145 offset:1024
	ds_read_b128 v[176:179], v145 offset:2048
	ds_read_b128 v[180:183], v145 offset:3072
	s_add_u32 s46, s46, 0x80000
	s_addc_u32 s47, s47, 0
	s_mov_b32 m0, s53
	v_lshl_add_u64 v[218:219], s[46:47], 0, v[134:135]
	ds_read_b128 v[184:187], v151 offset:32768
	ds_read_b128 v[188:191], v151 offset:33792
	ds_read_b128 v[192:195], v151 offset:34816
	ds_read_b128 v[196:199], v151 offset:35840
	ds_read_b128 v[200:203], v151 offset:36864
	ds_read_b128 v[204:207], v151 offset:37888
	ds_read_b128 v[208:211], v151 offset:38912
	ds_read_b128 v[212:215], v151 offset:39936
	global_load_lds_dwordx4 v134, s[46:47]
	v_lshl_add_u64 v[218:219], s[46:47], 0, v[132:133]
	s_mov_b32 m0, s54
	s_nop 0
	global_load_lds_dwordx4 v132, s[46:47]
	s_waitcnt vmcnt(8) lgkmcnt(0)
	s_setprio 1
	s_barrier
	v_mfma_f32_16x16x32_bf16 v[120:123], v[152:155], v[184:187], v[120:123]
	v_mfma_f32_16x16x32_bf16 v[112:115], v[160:163], v[184:187], v[112:115]
	v_mfma_f32_16x16x32_bf16 v[104:107], v[152:155], v[192:195], v[104:107]
	v_mfma_f32_16x16x32_bf16 v[96:99], v[160:163], v[192:195], v[96:99]
	v_mfma_f32_16x16x32_bf16 v[88:91], v[152:155], v[200:203], v[88:91]
	v_mfma_f32_16x16x32_bf16 v[80:83], v[160:163], v[200:203], v[80:83]
	v_mfma_f32_16x16x32_bf16 v[56:59], v[152:155], v[208:211], v[56:59]
	v_mfma_f32_16x16x32_bf16 v[48:51], v[160:163], v[208:211], v[48:51]
	v_mfma_f32_16x16x32_bf16 v[120:123], v[156:159], v[188:191], v[120:123]
	v_mfma_f32_16x16x32_bf16 v[112:115], v[164:167], v[188:191], v[112:115]
	v_mfma_f32_16x16x32_bf16 v[104:107], v[156:159], v[196:199], v[104:107]
	v_mfma_f32_16x16x32_bf16 v[96:99], v[164:167], v[196:199], v[96:99]
	v_mfma_f32_16x16x32_bf16 v[88:91], v[156:159], v[204:207], v[88:91]
	v_mfma_f32_16x16x32_bf16 v[80:83], v[164:167], v[204:207], v[80:83]
	v_mfma_f32_16x16x32_bf16 v[56:59], v[156:159], v[212:215], v[56:59]
	v_mfma_f32_16x16x32_bf16 v[48:51], v[164:167], v[212:215], v[48:51]
	s_setprio 0
	s_setprio 1
	v_mfma_f32_16x16x32_bf16 v[124:127], v[168:171], v[184:187], v[124:127]
	v_mfma_f32_16x16x32_bf16 v[116:119], v[176:179], v[184:187], v[116:119]
	v_mfma_f32_16x16x32_bf16 v[108:111], v[168:171], v[192:195], v[108:111]
	v_mfma_f32_16x16x32_bf16 v[100:103], v[176:179], v[192:195], v[100:103]
	v_mfma_f32_16x16x32_bf16 v[92:95], v[168:171], v[200:203], v[92:95]
	v_mfma_f32_16x16x32_bf16 v[84:87], v[176:179], v[200:203], v[84:87]
	v_mfma_f32_16x16x32_bf16 v[60:63], v[168:171], v[208:211], v[60:63]
	v_mfma_f32_16x16x32_bf16 v[52:55], v[176:179], v[208:211], v[52:55]
	v_mfma_f32_16x16x32_bf16 v[124:127], v[172:175], v[188:191], v[124:127]
	v_mfma_f32_16x16x32_bf16 v[116:119], v[180:183], v[188:191], v[116:119]
	v_mfma_f32_16x16x32_bf16 v[108:111], v[172:175], v[196:199], v[108:111]
	v_mfma_f32_16x16x32_bf16 v[100:103], v[180:183], v[196:199], v[100:103]
	v_mfma_f32_16x16x32_bf16 v[92:95], v[172:175], v[204:207], v[92:95]
	v_mfma_f32_16x16x32_bf16 v[84:87], v[180:183], v[204:207], v[84:87]
	v_mfma_f32_16x16x32_bf16 v[60:63], v[172:175], v[212:215], v[60:63]
	v_mfma_f32_16x16x32_bf16 v[52:55], v[180:183], v[212:215], v[52:55]
	s_barrier
	s_setprio 0
	s_mov_b32 m0, s73
	v_lshl_add_u64 v[140:141], v[140:141], 0, s[12:13]
	s_add_u32 s44, s44, 0x80080
	ds_read_b128 v[184:187], v151 offset:49152
	ds_read_b128 v[188:191], v151 offset:50176
	ds_read_b128 v[192:195], v151 offset:51200
	ds_read_b128 v[196:199], v151 offset:52224
	ds_read_b128 v[200:203], v151 offset:53248
	ds_read_b128 v[204:207], v151 offset:54272
	ds_read_b128 v[208:211], v151 offset:55296
	ds_read_b128 v[212:215], v151 offset:56320
	global_load_lds_dwordx4 v[140:141], off
	v_lshl_add_u64 v[140:141], v[142:143], 0, s[12:13]
	s_mov_b32 m0, s74
	s_addc_u32 s45, s45, 0
	global_load_lds_dwordx4 v[140:141], off
	v_lshl_add_u64 v[140:141], s[44:45], 0, v[128:129]
	s_mov_b32 m0, s75
	s_nop 0
	global_load_lds_dwordx4 v128, s[44:45]
	v_lshl_add_u64 v[140:141], s[44:45], 0, v[130:131]
	s_mov_b32 m0, s76
	s_nop 0
	global_load_lds_dwordx4 v130, s[44:45]
	v_lshl_add_u64 v[140:141], v[146:147], 0, s[12:13]
	s_mov_b32 m0, s59
	s_nop 0
	global_load_lds_dwordx4 v[140:141], off
	v_lshl_add_u64 v[140:141], v[216:217], 0, s[12:13]
	s_mov_b32 m0, s60
	s_nop 0
	global_load_lds_dwordx4 v[140:141], off
	s_waitcnt vmcnt(8) lgkmcnt(0)
	s_setprio 1
	s_barrier
	v_mfma_f32_16x16x32_bf16 v[72:75], v[152:155], v[184:187], v[72:75]
	v_mfma_f32_16x16x32_bf16 v[64:67], v[160:163], v[184:187], v[64:67]
	v_mfma_f32_16x16x32_bf16 v[40:43], v[152:155], v[192:195], v[40:43]
	v_mfma_f32_16x16x32_bf16 v[32:35], v[160:163], v[192:195], v[32:35]
	v_mfma_f32_16x16x32_bf16 v[24:27], v[152:155], v[200:203], v[24:27]
	v_mfma_f32_16x16x32_bf16 v[16:19], v[160:163], v[200:203], v[16:19]
	v_mfma_f32_16x16x32_bf16 v[8:11], v[152:155], v[208:211], v[8:11]
	v_mfma_f32_16x16x32_bf16 v[0:3], v[160:163], v[208:211], v[0:3]
	v_mfma_f32_16x16x32_bf16 v[72:75], v[156:159], v[188:191], v[72:75]
	v_mfma_f32_16x16x32_bf16 v[64:67], v[164:167], v[188:191], v[64:67]
	v_mfma_f32_16x16x32_bf16 v[40:43], v[156:159], v[196:199], v[40:43]
	v_mfma_f32_16x16x32_bf16 v[32:35], v[164:167], v[196:199], v[32:35]
	v_mfma_f32_16x16x32_bf16 v[24:27], v[156:159], v[204:207], v[24:27]
	v_mfma_f32_16x16x32_bf16 v[16:19], v[164:167], v[204:207], v[16:19]
	v_mfma_f32_16x16x32_bf16 v[8:11], v[156:159], v[212:215], v[8:11]
	v_mfma_f32_16x16x32_bf16 v[0:3], v[164:167], v[212:215], v[0:3]
	s_setprio 0
	s_setprio 1
	v_mfma_f32_16x16x32_bf16 v[76:79], v[168:171], v[184:187], v[76:79]
	v_mfma_f32_16x16x32_bf16 v[68:71], v[176:179], v[184:187], v[68:71]
	v_mfma_f32_16x16x32_bf16 v[44:47], v[168:171], v[192:195], v[44:47]
	v_mfma_f32_16x16x32_bf16 v[36:39], v[176:179], v[192:195], v[36:39]
	v_mfma_f32_16x16x32_bf16 v[28:31], v[168:171], v[200:203], v[28:31]
	v_mfma_f32_16x16x32_bf16 v[20:23], v[176:179], v[200:203], v[20:23]
	v_mfma_f32_16x16x32_bf16 v[12:15], v[168:171], v[208:211], v[12:15]
	v_mfma_f32_16x16x32_bf16 v[4:7], v[176:179], v[208:211], v[4:7]
	v_mfma_f32_16x16x32_bf16 v[76:79], v[172:175], v[188:191], v[76:79]
	v_mfma_f32_16x16x32_bf16 v[68:71], v[180:183], v[188:191], v[68:71]
	v_mfma_f32_16x16x32_bf16 v[44:47], v[172:175], v[196:199], v[44:47]
	v_mfma_f32_16x16x32_bf16 v[36:39], v[180:183], v[196:199], v[36:39]
	v_mfma_f32_16x16x32_bf16 v[28:31], v[172:175], v[204:207], v[28:31]
	v_mfma_f32_16x16x32_bf16 v[20:23], v[180:183], v[204:207], v[20:23]
	v_mfma_f32_16x16x32_bf16 v[12:15], v[172:175], v[212:215], v[12:15]
	v_mfma_f32_16x16x32_bf16 v[4:7], v[180:183], v[212:215], v[4:7]
	s_barrier
	s_setprio 0
	s_add_i32 s79, s79, 2
	s_add_u32 s77, s77, 0x100
	s_addc_u32 s78, s78, 0
	s_add_u32 s42, s42, 0x100
	s_addc_u32 s43, s43, 0
	s_cmp_gt_u32 s79, 29
	s_cbranch_scc0 .LBB0_3342
	s_and_b64 vcc, exec, s[14:15]
	s_cbranch_vccz .LBB0_3345
	s_barrier

; #define PG8_STAGE(bufoff, gbase, voff) do { _Pragma("unroll") for (int _i = 0; _i < 2; ++_i) \
;         __builtin_amdgcn_global_load_lds((const unsigned*)((const char*)(gbase) + (voff)[_i]), (PG8_LAS unsigned*)(lds + (bufoff) + ldsw + _i * 8192), 16, 0, 0); } while (0)
; #define PG8_WAIT_V(n) asm volatile("s_waitcnt vmcnt(" #n ")" ::: "memory")
; template <class Epi, class Sched, bool ALIGN_EPI = false, bool SP2 = false, bool A_TILED = false>
; __device__ __forceinline__ void gemm_phase(PG8_LAS unsigned char* lds, const Gemm g, const Sched& S, const Epi& E, const int wave_s) {
;     ...
;     if constexpr (SP2) {
;         PG8_STAGE(PG8_SB(0, 0), cB, voffB); PG8_STAGE(PG8_SB(0, 1), cB + hstep, voffB); PG8_STAGE(PG8_SA(0, 0), cA, voffA); PG8_STAGE(PG8_SA(0, 1), cA + hstepA, voffA);
;         if (wr == 1) PG8_BAR;
;         PG8_WAIT_V(2); PG8_BAR;
;         PG8_STAGE(PG8_SB(1, 0), cB + kstep, voffB); PG8_STAGE(PG8_SA(1, 0), cA + kstepA, voffA); PG8_STAGE(PG8_SB(1, 1), cB + hstep + kstep, voffB);
;         PG8_WAIT_V(6); PG8_BAR;
;     } else {
;         PG8_STAGE(PG8_SB(0, 0), cB, voffB); PG8_STAGE(PG8_SA(0, 0), cA, voffA); PG8_STAGE(PG8_SB(0, 1), cB + hstep, voffB); PG8_STAGE(PG8_SA(0, 1), cA + hstepA, voffA);
;         if (wr == 1) PG8_BAR;
;         PG8_WAIT_V(4); PG8_BAR;
;         PG8_STAGE(PG8_SB(1, 0), cB + kstep, voffB); PG8_STAGE(PG8_SA(1, 0), cA + kstepA, voffA); PG8_STAGE(PG8_SB(1, 1), cB + hstep + kstep, voffB);
;         PG8_WAIT_V(6); PG8_BAR;
;     }
;     for (;;) {
;         const bool has_next = Epi::AFTER_DRAIN ? false : S.next(ui + 1, nxt);
;         const char* nA = has_next ? (const char*)g.A + (size_t)nxt.pm * tstepA : cA; const char* nB = has_next ? (const char*)g.Bt + (size_t)nxt.pn * tstep : cB;
;         constexpr bool PEEL = SP2 && !Epi::AFTER_DRAIN;
;         if constexpr (PEEL) {
;             const char* a1 = cA + kstepA; const char* a2 = cA + 2 * kstepA; const char* b2 = cB + 2 * kstep; const char* a3 = a2 + kstepA; const char* b3 = b2 + kstep;
;             PG8_ITER(PG8_MMAZ)
;         } else {
; #pragma unroll
;             for (int a = 0; a < 2; ++a)
; #pragma unroll
;                 for (int b = 0; b < 2; ++b)
; #pragma unroll
;                     for (int m = 0; m < 4; ++m)
; #pragma unroll
;                         for (int n = 0; n < 2; ++n) acc[a][b][m][n] = (f32x4){0.f, 0.f, 0.f, 0.f};
.LBB0_3607:
	v_and_b32_e32 v15, 48, v8
	v_lshlrev_b32_e32 v16, 6, v8
	s_movk_i32 s15, 0x3c0
	v_lshlrev_b32_e32 v8, 2, v8
	s_and_b32 s26, s25, 3
	s_lshl_b32 s13, s14, 6
	s_lshl_b32 s14, s14, 13
	v_and_or_b32 v15, v16, s15, v15
	v_and_b32_e32 v8, 32, v8
	v_bitop3_b32 v16, v15, s14, v8 bitop3:0xde
	s_lshl_b32 s14, s26, 12
	v_bitop3_b32 v8, v15, s14, v8 bitop3:0xde
	s_mov_b64 s[14:15], 0x80
	s_add_i32 m0, s27, 0x18000
	v_lshl_add_u64 v[6:7], v[6:7], 0, s[14:15]
	s_waitcnt vmcnt(2)
	s_barrier
	global_load_lds_dwordx4 v[6:7], off
	v_lshl_add_u64 v[4:5], v[4:5], 0, s[14:15]
	s_add_i32 m0, s27, 0x1a000
	s_add_i32 s39, s27, 0x8000
	s_add_i32 s40, s27, 0xa000
	global_load_lds_dwordx4 v[4:5], off
	v_lshl_add_u64 v[2:3], v[2:3], 0, s[14:15]
	s_mov_b32 m0, s39
	s_add_u32 s42, s0, 0x80080
	global_load_lds_dwordx4 v[2:3], off
	v_lshl_add_u64 v[0:1], v[0:1], 0, s[14:15]
	s_mov_b32 m0, s40
	s_addc_u32 s43, s1, 0
	global_load_lds_dwordx4 v[0:1], off
	s_add_i32 m0, s27, 0x1c000
	v_lshl_add_u64 v[0:1], s[42:43], 0, v[34:35]
	global_load_lds_dwordx4 v34, s[42:43]
	v_lshl_add_u64 v[0:1], s[42:43], 0, v[134:135]
	s_add_i32 m0, s27, 0x1e000
	s_add_u32 s41, s20, 0x3a00100
	global_load_lds_dwordx4 v134, s[42:43]
	v_lshlrev_b32_e32 v0, 15, v12
	v_and_b32_e32 v0, 0xffff0000, v0
	v_lshl_add_u32 v0, v13, 12, v0
	v_and_b32_e32 v1, 1, v12
	v_lshl_or_b32 v0, v1, 6, v0
	v_lshl_add_u32 v0, v14, 1, v0
	v_mov_b32_e32 v1, v35
	s_addc_u32 s42, s21, 0
	v_lshl_add_u64 v[0:1], s[16:17], 0, v[0:1]
	s_mov_b64 s[20:21], 0x20680080
	v_lshl_add_u64 v[136:137], v[0:1], 0, s[20:21]
	v_lshlrev_b32_e32 v0, 15, v9
	v_and_b32_e32 v0, 0xffff0000, v0
	v_lshl_add_u32 v0, v10, 12, v0
	v_and_b32_e32 v1, 1, v9
	v_lshl_or_b32 v0, v1, 6, v0
	s_add_u32 s43, s16, 0x20600100
	s_waitcnt vmcnt(6)
	v_lshl_add_u32 v0, v11, 1, v0
	v_mov_b32_e32 v1, v35
	s_addc_u32 s44, s17, 0
	s_add_i32 s48, 0, 0x10000
	s_add_i32 s50, 0, 0x14000
	s_add_i32 s52, 0, 0x18000
	s_add_i32 s54, 0, 0x1c000
	v_lshl_add_u64 v[0:1], s[16:17], 0, v[0:1]
	v_add_u32_e32 v140, s48, v8
	v_add_u32_e32 v141, s50, v8
	s_add_i32 s48, s48, s22
	s_add_i32 s50, s50, s22
	v_add_u32_e32 v143, s52, v8
	v_add_u32_e32 v144, s54, v8
	s_add_i32 s52, s52, s22
	s_add_i32 s54, s54, s22
	v_lshl_add_u64 v[138:139], v[0:1], 0, s[20:21]
	s_mov_b32 s45, -2
	v_add_u32_e32 v142, 0, v16
	s_add_i32 s46, s27, 0xc000
	s_add_i32 s47, s27, 0xe000
	s_add_i32 s49, s48, 0x2000
	s_add_i32 s51, s50, 0x2000
	s_add_i32 s53, s52, 0x2000
	s_add_i32 s55, s54, 0x2000
	s_mov_b64 s[16:17], 0x100
	v_mov_b32_e32 v0, v35
	v_mov_b32_e32 v1, v35
	v_mov_b32_e32 v2, v35
	v_mov_b32_e32 v3, v35
	v_mov_b32_e32 v4, v35
	v_mov_b32_e32 v5, v35
	v_mov_b32_e32 v6, v35
	v_mov_b32_e32 v7, v35
	v_mov_b32_e32 v40, v35
	v_mov_b32_e32 v41, v35
	v_mov_b32_e32 v42, v35
	v_mov_b32_e32 v43, v35
	v_mov_b32_e32 v44, v35
	v_mov_b32_e32 v45, v35
	v_mov_b32_e32 v46, v35
	v_mov_b32_e32 v47, v35
	v_mov_b32_e32 v88, v35
	v_mov_b32_e32 v89, v35
	v_mov_b32_e32 v90, v35
	v_mov_b32_e32 v91, v35
	v_mov_b32_e32 v92, v35
	v_mov_b32_e32 v93, v35
	v_mov_b32_e32 v94, v35
	v_mov_b32_e32 v95, v35
	v_mov_b32_e32 v112, v35
	v_mov_b32_e32 v113, v35
	v_mov_b32_e32 v114, v35
	v_mov_b32_e32 v115, v35
	v_mov_b32_e32 v124, v35
	v_mov_b32_e32 v125, v35
	v_mov_b32_e32 v126, v35
	v_mov_b32_e32 v127, v35
	v_mov_b32_e32 v28, v35
	v_mov_b32_e32 v29, v35
	v_mov_b32_e32 v30, v35
	v_mov_b32_e32 v31, v35
	v_mov_b32_e32 v36, v35
	v_mov_b32_e32 v37, v35
	v_mov_b32_e32 v38, v35
	v_mov_b32_e32 v39, v35
	v_mov_b32_e32 v80, v35
	v_mov_b32_e32 v81, v35
	v_mov_b32_e32 v82, v35
	v_mov_b32_e32 v83, v35
	v_mov_b32_e32 v84, v35
	v_mov_b32_e32 v85, v35
	v_mov_b32_e32 v86, v35
	v_mov_b32_e32 v87, v35
	v_mov_b32_e32 v120, v35
	v_mov_b32_e32 v121, v35
	v_mov_b32_e32 v122, v35
	v_mov_b32_e32 v123, v35
	v_mov_b32_e32 v116, v35
	v_mov_b32_e32 v117, v35
	v_mov_b32_e32 v118, v35
	v_mov_b32_e32 v119, v35
	v_mov_b32_e32 v104, v35
	v_mov_b32_e32 v105, v35
	v_mov_b32_e32 v106, v35
	v_mov_b32_e32 v107, v35
	v_mov_b32_e32 v100, v35
	v_mov_b32_e32 v101, v35
	v_mov_b32_e32 v102, v35
	v_mov_b32_e32 v103, v35
	v_mov_b32_e32 v96, v35
	v_mov_b32_e32 v97, v35
	v_mov_b32_e32 v98, v35
	v_mov_b32_e32 v99, v35
	v_mov_b32_e32 v108, v35
	v_mov_b32_e32 v109, v35
	v_mov_b32_e32 v110, v35
	v_mov_b32_e32 v111, v35
	v_mov_b32_e32 v64, v35
	v_mov_b32_e32 v65, v35
	v_mov_b32_e32 v66, v35
	v_mov_b32_e32 v67, v35
	v_mov_b32_e32 v72, v35
	v_mov_b32_e32 v73, v35
	v_mov_b32_e32 v74, v35
	v_mov_b32_e32 v75, v35
	v_mov_b32_e32 v48, v35
	v_mov_b32_e32 v49, v35
	v_mov_b32_e32 v50, v35
	v_mov_b32_e32 v51, v35
	v_mov_b32_e32 v56, v35
	v_mov_b32_e32 v57, v35
	v_mov_b32_e32 v58, v35
	v_mov_b32_e32 v59, v35
	v_mov_b32_e32 v16, v35
	v_mov_b32_e32 v17, v35
	v_mov_b32_e32 v18, v35
	v_mov_b32_e32 v19, v35
	v_mov_b32_e32 v24, v35
	v_mov_b32_e32 v25, v35
	v_mov_b32_e32 v26, v35
	v_mov_b32_e32 v27, v35
	v_mov_b32_e32 v68, v35
	v_mov_b32_e32 v69, v35
	v_mov_b32_e32 v70, v35
	v_mov_b32_e32 v71, v35
	v_mov_b32_e32 v128, v35
	v_mov_b32_e32 v129, v35
	v_mov_b32_e32 v130, v35
	v_mov_b32_e32 v131, v35
	v_mov_b32_e32 v52, v35
	v_mov_b32_e32 v53, v35
	v_mov_b32_e32 v54, v35
	v_mov_b32_e32 v55, v35
	v_mov_b32_e32 v76, v35
	v_mov_b32_e32 v77, v35
	v_mov_b32_e32 v78, v35
	v_mov_b32_e32 v79, v35
	v_mov_b32_e32 v20, v35
	v_mov_b32_e32 v21, v35
	v_mov_b32_e32 v22, v35
	v_mov_b32_e32 v23, v35
	v_mov_b32_e32 v60, v35
	v_mov_b32_e32 v61, v35
	v_mov_b32_e32 v62, v35
	v_mov_b32_e32 v63, v35
	v_mov_b32_e32 v12, v35
	v_mov_b32_e32 v13, v35
	v_mov_b32_e32 v14, v35
	v_mov_b32_e32 v15, v35
	v_mov_b32_e32 v8, v35
	v_mov_b32_e32 v9, v35
	v_mov_b32_e32 v10, v35
	v_mov_b32_e32 v11, v35
	s_barrier
; #define PG8_MMA(ai, bj, At, Bt) do { __builtin_amdgcn_s_setprio(1); _Pragma("unroll") for (int m = 0; m < 4; ++m) _Pragma("unroll") for (int n = 0; n < 2; ++n) _Pragma("unroll") for (int k = 0; k < 2; ++k) \
;         acc[ai][bj][m][n] = __builtin_amdgcn_mfma_f32_16x16x32_bf16(Bt[n][k], At[m][k], acc[ai][bj][m][n], 0, 0, 0); __builtin_amdgcn_s_setprio(0); } while (0)
; template <class Epi, class Sched, bool ALIGN_EPI = false, bool SP2 = false, bool A_TILED = false>
; __device__ __forceinline__ void gemm_phase(PG8_LAS unsigned char* lds, const Gemm g, const Sched& S, const Epi& E, const int wave_s) {
;     ...
;         for (int t = PEEL ? 2 : 0; t < nt; t += 2) {
;             const bool last = (t == nt - 2);
;             const char* a1 = cA + (size_t)(t + 1) * kstepA;
;             const char* a2 = last ? nA : cA + (size_t)(t + 2) * kstepA; const char* b2 = last ? nB : cB + (size_t)(t + 2) * kstep;
;             const char* a3 = a2 + kstepA; const char* b3 = b2 + kstep;
;             if (last && has_next) S.a_ready(nxt);
;             if constexpr (SP2) {
;             PG8_ITER(PG8_MMA)
.LBB0_3608:
	ds_read_b128 v[146:149], v140
	ds_read_b128 v[150:153], v140 offset:1024
	ds_read_b128 v[154:157], v140 offset:2048
	ds_read_b128 v[158:161], v140 offset:3072
	ds_read_b128 v[162:165], v141
	ds_read_b128 v[166:169], v141 offset:1024
	ds_read_b128 v[170:173], v141 offset:2048
	ds_read_b128 v[174:177], v141 offset:3072
	s_add_u32 s20, s8, s43
	s_addc_u32 s21, s9, s44
	s_add_u32 s56, s8, s41
	s_addc_u32 s57, s9, s42
	s_cmp_eq_u32 s45, 28
	s_cselect_b32 s23, s5, s21
	s_cselect_b32 s22, s4, s20
	s_cselect_b32 s21, s1, s57
	s_cselect_b32 s20, s0, s56
	s_mov_b32 m0, s46
	v_lshl_add_u64 v[210:211], s[8:9], 0, v[138:139]
	ds_read_b128 v[178:181], v142
	ds_read_b128 v[182:185], v142 offset:1024
	ds_read_b128 v[186:189], v142 offset:2048
	ds_read_b128 v[190:193], v142 offset:3072
	ds_read_b128 v[194:197], v142 offset:4096
	ds_read_b128 v[198:201], v142 offset:5120
	ds_read_b128 v[202:205], v142 offset:6144
	ds_read_b128 v[206:209], v142 offset:7168
	global_load_lds_dwordx4 v[210:211], off
	v_lshl_add_u64 v[210:211], s[8:9], 0, v[136:137]
	s_mov_b32 m0, s47
	s_nop 0
	global_load_lds_dwordx4 v[210:211], off
	s_waitcnt vmcnt(8) lgkmcnt(0)
	s_setprio 1
	s_barrier
	v_mfma_f32_16x16x32_bf16 v[8:11], v[146:149], v[178:181], v[8:11]
	v_mfma_f32_16x16x32_bf16 v[12:15], v[154:157], v[178:181], v[12:15]
	v_mfma_f32_16x16x32_bf16 v[60:63], v[146:149], v[186:189], v[60:63]
	v_mfma_f32_16x16x32_bf16 v[20:23], v[154:157], v[186:189], v[20:23]
	v_mfma_f32_16x16x32_bf16 v[76:79], v[146:149], v[194:197], v[76:79]
	v_mfma_f32_16x16x32_bf16 v[52:55], v[154:157], v[194:197], v[52:55]
	v_mfma_f32_16x16x32_bf16 v[128:131], v[146:149], v[202:205], v[128:131]
	v_mfma_f32_16x16x32_bf16 v[68:71], v[154:157], v[202:205], v[68:71]
	v_mfma_f32_16x16x32_bf16 v[8:11], v[150:153], v[182:185], v[8:11]
	v_mfma_f32_16x16x32_bf16 v[12:15], v[158:161], v[182:185], v[12:15]
	v_mfma_f32_16x16x32_bf16 v[60:63], v[150:153], v[190:193], v[60:63]
	v_mfma_f32_16x16x32_bf16 v[20:23], v[158:161], v[190:193], v[20:23]
	v_mfma_f32_16x16x32_bf16 v[76:79], v[150:153], v[198:201], v[76:79]
	v_mfma_f32_16x16x32_bf16 v[52:55], v[158:161], v[198:201], v[52:55]
	v_mfma_f32_16x16x32_bf16 v[128:131], v[150:153], v[206:209], v[128:131]
	v_mfma_f32_16x16x32_bf16 v[68:71], v[158:161], v[206:209], v[68:71]
	s_setprio 0
	s_setprio 1
	v_mfma_f32_16x16x32_bf16 v[24:27], v[162:165], v[178:181], v[24:27]
	v_mfma_f32_16x16x32_bf16 v[16:19], v[170:173], v[178:181], v[16:19]
	v_mfma_f32_16x16x32_bf16 v[56:59], v[162:165], v[186:189], v[56:59]
	v_mfma_f32_16x16x32_bf16 v[48:51], v[170:173], v[186:189], v[48:51]
	v_mfma_f32_16x16x32_bf16 v[72:75], v[162:165], v[194:197], v[72:75]
	v_mfma_f32_16x16x32_bf16 v[64:67], v[170:173], v[194:197], v[64:67]
	v_mfma_f32_16x16x32_bf16 v[108:111], v[162:165], v[202:205], v[108:111]
	v_mfma_f32_16x16x32_bf16 v[96:99], v[170:173], v[202:205], v[96:99]
	v_mfma_f32_16x16x32_bf16 v[24:27], v[166:169], v[182:185], v[24:27]
	v_mfma_f32_16x16x32_bf16 v[16:19], v[174:177], v[182:185], v[16:19]
	v_mfma_f32_16x16x32_bf16 v[56:59], v[166:169], v[190:193], v[56:59]
	v_mfma_f32_16x16x32_bf16 v[48:51], v[174:177], v[190:193], v[48:51]
	v_mfma_f32_16x16x32_bf16 v[72:75], v[166:169], v[198:201], v[72:75]
	v_mfma_f32_16x16x32_bf16 v[64:67], v[174:177], v[198:201], v[64:67]
	v_mfma_f32_16x16x32_bf16 v[108:111], v[166:169], v[206:209], v[108:111]
	v_mfma_f32_16x16x32_bf16 v[96:99], v[174:177], v[206:209], v[96:99]
	s_barrier
	s_setprio 0
	s_mov_b32 m0, s48
	v_lshl_add_u64 v[210:211], s[20:21], 0, v[34:35]
	s_add_u32 s56, s20, 0x80000
	ds_read_b128 v[178:181], v142 offset:16384
	ds_read_b128 v[182:185], v142 offset:17408
	ds_read_b128 v[186:189], v142 offset:18432
	ds_read_b128 v[190:193], v142 offset:19456
	ds_read_b128 v[194:197], v142 offset:20480
	ds_read_b128 v[198:201], v142 offset:21504
	ds_read_b128 v[202:205], v142 offset:22528
	ds_read_b128 v[206:209], v142 offset:23552
	global_load_lds_dwordx4 v34, s[20:21]
	v_lshl_add_u64 v[212:213], s[20:21], 0, v[134:135]
	s_mov_b32 m0, s49
	s_addc_u32 s57, s21, 0
	global_load_lds_dwordx4 v134, s[20:21]
	v_lshl_add_u64 v[214:215], s[56:57], 0, v[34:35]
	s_mov_b32 m0, s50
	v_lshl_add_u64 v[216:217], s[22:23], 0, v[132:133]
	global_load_lds_dwordx4 v34, s[56:57]
	v_lshl_add_u64 v[214:215], s[56:57], 0, v[134:135]
	s_mov_b32 m0, s51
	s_nop 0
	global_load_lds_dwordx4 v134, s[56:57]
	v_lshl_add_u64 v[214:215], s[22:23], 0, v[32:33]
	s_mov_b32 m0, s27
	s_nop 0
	global_load_lds_dwordx4 v32, s[22:23]
	s_mov_b32 m0, s36
	s_nop 0
	global_load_lds_dwordx4 v132, s[22:23]
	s_waitcnt vmcnt(8) lgkmcnt(0)
	s_setprio 1
	s_barrier
	v_mfma_f32_16x16x32_bf16 v[100:103], v[146:149], v[178:181], v[100:103]
	v_mfma_f32_16x16x32_bf16 v[104:107], v[154:157], v[178:181], v[104:107]
	v_mfma_f32_16x16x32_bf16 v[116:119], v[146:149], v[186:189], v[116:119]
	v_mfma_f32_16x16x32_bf16 v[120:123], v[154:157], v[186:189], v[120:123]
	v_mfma_f32_16x16x32_bf16 v[84:87], v[146:149], v[194:197], v[84:87]
	v_mfma_f32_16x16x32_bf16 v[80:83], v[154:157], v[194:197], v[80:83]
	v_mfma_f32_16x16x32_bf16 v[36:39], v[146:149], v[202:205], v[36:39]
	v_mfma_f32_16x16x32_bf16 v[28:31], v[154:157], v[202:205], v[28:31]
	v_mfma_f32_16x16x32_bf16 v[100:103], v[150:153], v[182:185], v[100:103]
	v_mfma_f32_16x16x32_bf16 v[104:107], v[158:161], v[182:185], v[104:107]
	v_mfma_f32_16x16x32_bf16 v[116:119], v[150:153], v[190:193], v[116:119]
	v_mfma_f32_16x16x32_bf16 v[120:123], v[158:161], v[190:193], v[120:123]
	v_mfma_f32_16x16x32_bf16 v[84:87], v[150:153], v[198:201], v[84:87]
	v_mfma_f32_16x16x32_bf16 v[80:83], v[158:161], v[198:201], v[80:83]
	v_mfma_f32_16x16x32_bf16 v[36:39], v[150:153], v[206:209], v[36:39]
	v_mfma_f32_16x16x32_bf16 v[28:31], v[158:161], v[206:209], v[28:31]
	s_setprio 0
	s_setprio 1
	v_mfma_f32_16x16x32_bf16 v[124:127], v[162:165], v[178:181], v[124:127]
	v_mfma_f32_16x16x32_bf16 v[112:115], v[170:173], v[178:181], v[112:115]
	v_mfma_f32_16x16x32_bf16 v[92:95], v[162:165], v[186:189], v[92:95]
	v_mfma_f32_16x16x32_bf16 v[88:91], v[170:173], v[186:189], v[88:91]
	v_mfma_f32_16x16x32_bf16 v[44:47], v[162:165], v[194:197], v[44:47]
	v_mfma_f32_16x16x32_bf16 v[40:43], v[170:173], v[194:197], v[40:43]
	v_mfma_f32_16x16x32_bf16 v[4:7], v[162:165], v[202:205], v[4:7]
	v_mfma_f32_16x16x32_bf16 v[0:3], v[170:173], v[202:205], v[0:3]
	v_mfma_f32_16x16x32_bf16 v[124:127], v[166:169], v[182:185], v[124:127]
	v_mfma_f32_16x16x32_bf16 v[112:115], v[174:177], v[182:185], v[112:115]
	v_mfma_f32_16x16x32_bf16 v[92:95], v[166:169], v[190:193], v[92:95]
	v_mfma_f32_16x16x32_bf16 v[88:91], v[174:177], v[190:193], v[88:91]
	v_mfma_f32_16x16x32_bf16 v[44:47], v[166:169], v[198:201], v[44:47]
	v_mfma_f32_16x16x32_bf16 v[40:43], v[174:177], v[198:201], v[40:43]
	v_mfma_f32_16x16x32_bf16 v[4:7], v[166:169], v[206:209], v[4:7]
	v_mfma_f32_16x16x32_bf16 v[0:3], v[174:177], v[206:209], v[0:3]
	s_barrier
	s_setprio 0
	ds_read_b128 v[146:149], v143
	ds_read_b128 v[150:153], v143 offset:1024
	ds_read_b128 v[154:157], v143 offset:2048
	ds_read_b128 v[158:161], v143 offset:3072
	ds_read_b128 v[162:165], v144
	ds_read_b128 v[166:169], v144 offset:1024
	ds_read_b128 v[170:173], v144 offset:2048
	ds_read_b128 v[174:177], v144 offset:3072
	s_add_u32 s22, s22, 0x80000
	s_addc_u32 s23, s23, 0
	s_mov_b32 m0, s37
	v_lshl_add_u64 v[218:219], s[22:23], 0, v[32:33]
	ds_read_b128 v[178:181], v142 offset:32768
	ds_read_b128 v[182:185], v142 offset:33792
	ds_read_b128 v[186:189], v142 offset:34816
	ds_read_b128 v[190:193], v142 offset:35840
	ds_read_b128 v[194:197], v142 offset:36864
	ds_read_b128 v[198:201], v142 offset:37888
	ds_read_b128 v[202:205], v142 offset:38912
	ds_read_b128 v[206:209], v142 offset:39936
	global_load_lds_dwordx4 v32, s[22:23]
	v_lshl_add_u64 v[218:219], s[22:23], 0, v[132:133]
	s_mov_b32 m0, s38
	s_nop 0
	global_load_lds_dwordx4 v132, s[22:23]
	s_waitcnt vmcnt(8) lgkmcnt(0)
	s_setprio 1
	s_barrier
	v_mfma_f32_16x16x32_bf16 v[8:11], v[146:149], v[178:181], v[8:11]
	v_mfma_f32_16x16x32_bf16 v[12:15], v[154:157], v[178:181], v[12:15]
	v_mfma_f32_16x16x32_bf16 v[60:63], v[146:149], v[186:189], v[60:63]
	v_mfma_f32_16x16x32_bf16 v[20:23], v[154:157], v[186:189], v[20:23]
	v_mfma_f32_16x16x32_bf16 v[76:79], v[146:149], v[194:197], v[76:79]
	v_mfma_f32_16x16x32_bf16 v[52:55], v[154:157], v[194:197], v[52:55]
	v_mfma_f32_16x16x32_bf16 v[128:131], v[146:149], v[202:205], v[128:131]
	v_mfma_f32_16x16x32_bf16 v[68:71], v[154:157], v[202:205], v[68:71]
	v_mfma_f32_16x16x32_bf16 v[8:11], v[150:153], v[182:185], v[8:11]
	v_mfma_f32_16x16x32_bf16 v[12:15], v[158:161], v[182:185], v[12:15]
	v_mfma_f32_16x16x32_bf16 v[60:63], v[150:153], v[190:193], v[60:63]
	v_mfma_f32_16x16x32_bf16 v[20:23], v[158:161], v[190:193], v[20:23]
	v_mfma_f32_16x16x32_bf16 v[76:79], v[150:153], v[198:201], v[76:79]
	v_mfma_f32_16x16x32_bf16 v[52:55], v[158:161], v[198:201], v[52:55]
	v_mfma_f32_16x16x32_bf16 v[128:131], v[150:153], v[206:209], v[128:131]
	v_mfma_f32_16x16x32_bf16 v[68:71], v[158:161], v[206:209], v[68:71]
	s_setprio 0
	s_setprio 1
	v_mfma_f32_16x16x32_bf16 v[24:27], v[162:165], v[178:181], v[24:27]
	v_mfma_f32_16x16x32_bf16 v[16:19], v[170:173], v[178:181], v[16:19]
	v_mfma_f32_16x16x32_bf16 v[56:59], v[162:165], v[186:189], v[56:59]
	v_mfma_f32_16x16x32_bf16 v[48:51], v[170:173], v[186:189], v[48:51]
	v_mfma_f32_16x16x32_bf16 v[72:75], v[162:165], v[194:197], v[72:75]
	v_mfma_f32_16x16x32_bf16 v[64:67], v[170:173], v[194:197], v[64:67]
	v_mfma_f32_16x16x32_bf16 v[108:111], v[162:165], v[202:205], v[108:111]
	v_mfma_f32_16x16x32_bf16 v[96:99], v[170:173], v[202:205], v[96:99]
	v_mfma_f32_16x16x32_bf16 v[24:27], v[166:169], v[182:185], v[24:27]
	v_mfma_f32_16x16x32_bf16 v[16:19], v[174:177], v[182:185], v[16:19]
	v_mfma_f32_16x16x32_bf16 v[56:59], v[166:169], v[190:193], v[56:59]
	v_mfma_f32_16x16x32_bf16 v[48:51], v[174:177], v[190:193], v[48:51]
	v_mfma_f32_16x16x32_bf16 v[72:75], v[166:169], v[198:201], v[72:75]
	v_mfma_f32_16x16x32_bf16 v[64:67], v[174:177], v[198:201], v[64:67]
	v_mfma_f32_16x16x32_bf16 v[108:111], v[166:169], v[206:209], v[108:111]
	v_mfma_f32_16x16x32_bf16 v[96:99], v[174:177], v[206:209], v[96:99]
	s_barrier
; #define PG8_MMA(ai, bj, At, Bt) do { __builtin_amdgcn_s_setprio(1); _Pragma("unroll") for (int m = 0; m < 4; ++m) _Pragma("unroll") for (int n = 0; n < 2; ++n) _Pragma("unroll") for (int k = 0; k < 2; ++k) \
;         acc[ai][bj][m][n] = __builtin_amdgcn_mfma_f32_16x16x32_bf16(Bt[n][k], At[m][k], acc[ai][bj][m][n], 0, 0, 0); __builtin_amdgcn_s_setprio(0); } while (0)
; template <class Epi, class Sched, bool ALIGN_EPI = false, bool SP2 = false, bool A_TILED = false>
; __device__ __forceinline__ void gemm_phase(PG8_LAS unsigned char* lds, const Gemm g, const Sched& S, const Epi& E, const int wave_s) {
;     ...
; #pragma nounroll
;         for (int t = PEEL ? 2 : 0; t < nt; t += 2) {
;             const bool last = (t == nt - 2);
;             const char* a1 = cA + (size_t)(t + 1) * kstepA;
;             const char* a2 = last ? nA : cA + (size_t)(t + 2) * kstepA; const char* b2 = last ? nB : cB + (size_t)(t + 2) * kstep;
;             const char* a3 = a2 + kstepA; const char* b3 = b2 + kstep;
;             if (last && has_next) S.a_ready(nxt);
;             if constexpr (SP2) {
;             PG8_ITER(PG8_MMA)
	s_setprio 0
	s_mov_b32 m0, s52
	v_lshl_add_u64 v[210:211], v[210:211], 0, s[14:15]
	s_add_u32 s20, s20, 0x80080
	ds_read_b128 v[178:181], v142 offset:49152
	ds_read_b128 v[182:185], v142 offset:50176
	ds_read_b128 v[186:189], v142 offset:51200
	ds_read_b128 v[190:193], v142 offset:52224
	ds_read_b128 v[194:197], v142 offset:53248
	ds_read_b128 v[198:201], v142 offset:54272
	ds_read_b128 v[202:205], v142 offset:55296
	ds_read_b128 v[206:209], v142 offset:56320
	global_load_lds_dwordx4 v[210:211], off
	v_lshl_add_u64 v[210:211], v[212:213], 0, s[14:15]
	s_mov_b32 m0, s53
	s_addc_u32 s21, s21, 0
	global_load_lds_dwordx4 v[210:211], off
	v_lshl_add_u64 v[210:211], s[20:21], 0, v[34:35]
	s_mov_b32 m0, s54
	s_nop 0
	global_load_lds_dwordx4 v34, s[20:21]
	v_lshl_add_u64 v[210:211], s[20:21], 0, v[134:135]
	s_mov_b32 m0, s55
	s_nop 0
	global_load_lds_dwordx4 v134, s[20:21]
	v_lshl_add_u64 v[210:211], v[214:215], 0, s[14:15]
	s_mov_b32 m0, s39
	s_nop 0
	global_load_lds_dwordx4 v[210:211], off
	v_lshl_add_u64 v[210:211], v[216:217], 0, s[14:15]
	s_mov_b32 m0, s40
	s_nop 0
	global_load_lds_dwordx4 v[210:211], off
	s_waitcnt vmcnt(8) lgkmcnt(0)
	s_setprio 1
	s_barrier
	v_mfma_f32_16x16x32_bf16 v[100:103], v[146:149], v[178:181], v[100:103]
	v_mfma_f32_16x16x32_bf16 v[104:107], v[154:157], v[178:181], v[104:107]
	v_mfma_f32_16x16x32_bf16 v[116:119], v[146:149], v[186:189], v[116:119]
	v_mfma_f32_16x16x32_bf16 v[120:123], v[154:157], v[186:189], v[120:123]
	v_mfma_f32_16x16x32_bf16 v[84:87], v[146:149], v[194:197], v[84:87]
	v_mfma_f32_16x16x32_bf16 v[80:83], v[154:157], v[194:197], v[80:83]
	v_mfma_f32_16x16x32_bf16 v[36:39], v[146:149], v[202:205], v[36:39]
	v_mfma_f32_16x16x32_bf16 v[28:31], v[154:157], v[202:205], v[28:31]
	v_mfma_f32_16x16x32_bf16 v[100:103], v[150:153], v[182:185], v[100:103]
	v_mfma_f32_16x16x32_bf16 v[104:107], v[158:161], v[182:185], v[104:107]
	v_mfma_f32_16x16x32_bf16 v[116:119], v[150:153], v[190:193], v[116:119]
	v_mfma_f32_16x16x32_bf16 v[120:123], v[158:161], v[190:193], v[120:123]
	v_mfma_f32_16x16x32_bf16 v[84:87], v[150:153], v[198:201], v[84:87]
	v_mfma_f32_16x16x32_bf16 v[80:83], v[158:161], v[198:201], v[80:83]
	v_mfma_f32_16x16x32_bf16 v[36:39], v[150:153], v[206:209], v[36:39]
	v_mfma_f32_16x16x32_bf16 v[28:31], v[158:161], v[206:209], v[28:31]
	s_setprio 0
	s_setprio 1
	v_mfma_f32_16x16x32_bf16 v[124:127], v[162:165], v[178:181], v[124:127]
	v_mfma_f32_16x16x32_bf16 v[112:115], v[170:173], v[178:181], v[112:115]
	v_mfma_f32_16x16x32_bf16 v[92:95], v[162:165], v[186:189], v[92:95]
	v_mfma_f32_16x16x32_bf16 v[88:91], v[170:173], v[186:189], v[88:91]
	v_mfma_f32_16x16x32_bf16 v[44:47], v[162:165], v[194:197], v[44:47]
	v_mfma_f32_16x16x32_bf16 v[40:43], v[170:173], v[194:197], v[40:43]
	v_mfma_f32_16x16x32_bf16 v[4:7], v[162:165], v[202:205], v[4:7]
	v_mfma_f32_16x16x32_bf16 v[0:3], v[170:173], v[202:205], v[0:3]
	v_mfma_f32_16x16x32_bf16 v[124:127], v[166:169], v[182:185], v[124:127]
	v_mfma_f32_16x16x32_bf16 v[112:115], v[174:177], v[182:185], v[112:115]
	v_mfma_f32_16x16x32_bf16 v[92:95], v[166:169], v[190:193], v[92:95]
	v_mfma_f32_16x16x32_bf16 v[88:91], v[174:177], v[190:193], v[88:91]
	v_mfma_f32_16x16x32_bf16 v[44:47], v[166:169], v[198:201], v[44:47]
	v_mfma_f32_16x16x32_bf16 v[40:43], v[174:177], v[198:201], v[40:43]
	v_mfma_f32_16x16x32_bf16 v[4:7], v[166:169], v[206:209], v[4:7]
	v_mfma_f32_16x16x32_bf16 v[0:3], v[174:177], v[206:209], v[0:3]
	s_barrier
	s_setprio 0
	s_add_i32 s45, s45, 2
	s_add_u32 s41, s41, 0x100
	s_addc_u32 s42, s42, 0
	s_add_u32 s43, s43, 0x100
	s_addc_u32 s44, s44, 0
	v_lshl_add_u64 v[136:137], v[136:137], 0, s[16:17]
	s_cmp_gt_u32 s45, 29
	v_lshl_add_u64 v[138:139], v[138:139], 0, s[16:17]
	s_cbranch_scc0 .LBB0_3608
	s_waitcnt vmcnt(0)
	s_cmpk_lt_u32 s24, 0x100
	s_cbranch_scc0 .LBB0_3611
	s_barrier

; #define PG8_STAGE(bufoff, gbase, voff) do { _Pragma("unroll") for (int _i = 0; _i < 2; ++_i) \
;         __builtin_amdgcn_global_load_lds((const unsigned*)((const char*)(gbase) + (voff)[_i]), (PG8_LAS unsigned*)(lds + (bufoff) + ldsw + _i * 8192), 16, 0, 0); } while (0)
; #define PG8_WAIT_V(n) asm volatile("s_waitcnt vmcnt(" #n ")" ::: "memory")
; #define PG8_BAR __builtin_amdgcn_s_barrier()
; template <class Epi, class Sched, bool ALIGN_EPI = false, bool SP2 = false, bool A_TILED = false>
; __device__ __forceinline__ void gemm_phase(PG8_LAS unsigned char* lds, const Gemm g, const Sched& S, const Epi& E, const int wave_s) {
;     ...
;     if constexpr (SP2) {
;         PG8_STAGE(PG8_SB(0, 0), cB, voffB); PG8_STAGE(PG8_SB(0, 1), cB + hstep, voffB); PG8_STAGE(PG8_SA(0, 0), cA, voffA); PG8_STAGE(PG8_SA(0, 1), cA + hstepA, voffA);
;         if (wr == 1) PG8_BAR;
;         PG8_WAIT_V(2); PG8_BAR;
;         PG8_STAGE(PG8_SB(1, 0), cB + kstep, voffB); PG8_STAGE(PG8_SA(1, 0), cA + kstepA, voffA); PG8_STAGE(PG8_SB(1, 1), cB + hstep + kstep, voffB);
;         PG8_WAIT_V(6); PG8_BAR;
;     } else {
;         PG8_STAGE(PG8_SB(0, 0), cB, voffB); PG8_STAGE(PG8_SA(0, 0), cA, voffA); PG8_STAGE(PG8_SB(0, 1), cB + hstep, voffB); PG8_STAGE(PG8_SA(0, 1), cA + hstepA, voffA);
;         if (wr == 1) PG8_BAR;
;         PG8_WAIT_V(4); PG8_BAR;
;         PG8_STAGE(PG8_SB(1, 0), cB + kstep, voffB); PG8_STAGE(PG8_SA(1, 0), cA + kstepA, voffA); PG8_STAGE(PG8_SB(1, 1), cB + hstep + kstep, voffB);
;         PG8_WAIT_V(6); PG8_BAR;
.LBB0_3710:
	s_ashr_i32 s53, s86, 31
	s_add_u32 s54, s0, 0x34600000
	s_addc_u32 s55, s1, 0
	s_lshl_b32 s13, s6, 13
	s_mov_b64 s[6:7], 0x80
	s_and_b32 s0, s12, 3
	s_add_i32 m0, s47, 0x18000
	v_lshl_add_u64 v[6:7], v[6:7], 0, s[6:7]
	s_lshl_b32 s14, s0, 12
	s_waitcnt vmcnt(2)
	s_barrier
	global_load_lds_dwordx4 v[6:7], off
	v_lshl_add_u64 v[4:5], v[4:5], 0, s[6:7]
	s_add_i32 m0, s47, 0x1a000
	s_add_i32 s56, s47, 0x8000
	s_add_i32 s57, s47, 0xa000
	global_load_lds_dwordx4 v[4:5], off
	v_lshl_add_u64 v[0:1], v[0:1], 0, s[6:7]
	s_mov_b32 m0, s56
	s_add_u32 s0, s26, 0x80080
	global_load_lds_dwordx4 v[0:1], off
	v_lshl_add_u64 v[0:1], v[2:3], 0, s[6:7]
	s_mov_b32 m0, s57
	s_addc_u32 s1, s27, 0
	global_load_lds_dwordx4 v[0:1], off
	s_add_i32 m0, s47, 0x1c000
	v_lshl_add_u64 v[0:1], s[0:1], 0, v[128:129]
	global_load_lds_dwordx4 v128, s[0:1]
	v_lshl_add_u64 v[0:1], s[0:1], 0, v[130:131]
	s_add_i32 m0, s47, 0x1e000
	s_cmpk_lt_u32 s9, 0x100
	global_load_lds_dwordx4 v130, s[0:1]
	v_and_b32_e32 v0, 15, v8
	v_and_b32_e32 v1, 48, v8
	v_lshl_or_b32 v0, v0, 6, v1
	v_lshlrev_b32_e32 v1, 2, v8
	v_and_b32_e32 v1, 32, v1
	v_bitop3_b32 v2, v0, s13, v1 bitop3:0xde
	v_bitop3_b32 v144, v0, s14, v1 bitop3:0xde
	v_lshlrev_b32_e32 v0, 15, v9
	v_and_b32_e32 v0, 0xffff0000, v0
	v_lshl_add_u32 v0, v10, 12, v0
	v_and_b32_e32 v1, 1, v9
	v_lshl_or_b32 v0, v1, 6, v0
	v_lshl_add_u32 v136, v11, 1, v0
	v_lshlrev_b32_e32 v0, 15, v13
	v_and_b32_e32 v0, 0xffff0000, v0
	s_waitcnt vmcnt(6)
	v_lshl_add_u32 v0, v12, 12, v0
	v_and_b32_e32 v1, 1, v13
	s_sext_i32_i16 s25, s8
	s_cselect_b64 s[8:9], -1, 0
	s_and_b32 s0, s45, 0x400
	v_mov_b32_e32 v137, 0
	v_lshl_or_b32 v0, v1, 6, v0
	s_add_i32 s60, 0, 0x10000
	s_add_i32 s61, 0, 0x14000
	s_bfe_u32 s58, s12, 0x10001
	s_or_b32 s59, s0, s13
	v_lshl_add_u32 v138, v14, 1, v0
	v_mov_b32_e32 v139, v137
	v_mov_b64_e32 v[140:141], 0x200
	v_mov_b64_e32 v[142:143], 0x1ff
	v_add_u32_e32 v145, s60, v144
	v_add_u32_e32 v146, s61, v144
	v_add_u32_e32 v147, 0, v2
	s_mov_b64 s[12:13], 0x100
	s_mov_b64 s[14:15], 0x180
	s_barrier
	s_branch .LBB0_3713

; template <class Epi, class Sched, bool ALIGN_EPI = false, bool SP2 = false, bool A_TILED = false>
; __device__ __forceinline__ void gemm_phase(PG8_LAS unsigned char* lds, const Gemm g, const Sched& S, const Epi& E, const int wave_s) {
;     ...
;         const char* nA = has_next ? (const char*)g.A + (size_t)nxt.pm * tstepA : cA; const char* nB = has_next ? (const char*)g.Bt + (size_t)nxt.pn * tstep : cB;
;         constexpr bool PEEL = SP2 && !Epi::AFTER_DRAIN;
;         if constexpr (PEEL) {
;             const char* a1 = cA + kstepA; const char* a2 = cA + 2 * kstepA; const char* b2 = cB + 2 * kstep; const char* a3 = a2 + kstepA; const char* b3 = b2 + kstep;
;             PG8_ITER(PG8_MMAZ)
.LBB0_3719:
	s_ashr_i32 s19, s18, 31
	s_lshl_b64 s[20:21], s[18:19], 20
	s_add_u32 s20, s41, s20
	ds_read_b128 v[0:3], v145
	ds_read_b128 v[4:7], v145 offset:1024
	ds_read_b128 v[8:11], v145 offset:2048
	ds_read_b128 v[12:15], v145 offset:3072
	ds_read_b128 v[16:19], v146
	ds_read_b128 v[20:23], v146 offset:1024
	ds_read_b128 v[24:27], v146 offset:2048
	ds_read_b128 v[28:31], v146 offset:3072
	s_addc_u32 s21, s42, s21
	s_ashr_i32 s17, s16, 31
	s_lshl_b64 s[22:23], s[16:17], 20
	s_add_u32 s22, s43, s22
	s_addc_u32 s23, s44, s23
	s_and_b64 s[38:39], s[0:1], exec
	s_cselect_b32 s17, s21, s37
	s_cselect_b32 s19, s20, s36
	s_cselect_b32 s62, s23, s27
	s_cselect_b32 s63, s22, s26
	s_add_u32 s38, s36, 0x80080
	s_addc_u32 s39, s37, 0
	s_add_i32 s64, s47, 0xc000
	v_lshl_add_u64 v[64:65], s[38:39], 0, v[134:135]
	s_mov_b32 m0, s64
	s_add_i32 s65, s47, 0xe000
	ds_read_b128 v[32:35], v147
	ds_read_b128 v[36:39], v147 offset:1024
	ds_read_b128 v[40:43], v147 offset:2048
	ds_read_b128 v[44:47], v147 offset:3072
	ds_read_b128 v[48:51], v147 offset:4096
	ds_read_b128 v[52:55], v147 offset:5120
	ds_read_b128 v[56:59], v147 offset:6144
	ds_read_b128 v[60:63], v147 offset:7168
	global_load_lds_dwordx4 v134, s[38:39]
	v_lshl_add_u64 v[64:65], s[38:39], 0, v[132:133]
	s_mov_b32 m0, s65
	s_nop 0
	global_load_lds_dwordx4 v132, s[38:39]
	s_waitcnt vmcnt(8) lgkmcnt(0)
	s_setprio 1
	s_barrier
	v_mfma_f32_16x16x32_bf16 v[88:91], v[0:3], v[56:59], 0
	v_mfma_f32_16x16x32_bf16 v[64:67], v[0:3], v[32:35], 0
	v_mfma_f32_16x16x32_bf16 v[68:71], v[8:11], v[32:35], 0
	v_mfma_f32_16x16x32_bf16 v[72:75], v[0:3], v[40:43], 0
	v_mfma_f32_16x16x32_bf16 v[76:79], v[8:11], v[40:43], 0
	v_mfma_f32_16x16x32_bf16 v[80:83], v[0:3], v[48:51], 0
	v_mfma_f32_16x16x32_bf16 v[84:87], v[8:11], v[48:51], 0
	v_mfma_f32_16x16x32_bf16 v[96:99], v[4:7], v[60:63], v[88:91]
	v_mfma_f32_16x16x32_bf16 v[88:91], v[8:11], v[56:59], 0
	v_mfma_f32_16x16x32_bf16 v[64:67], v[4:7], v[36:39], v[64:67]
	v_mfma_f32_16x16x32_bf16 v[68:71], v[12:15], v[36:39], v[68:71]
	v_mfma_f32_16x16x32_bf16 v[72:75], v[4:7], v[44:47], v[72:75]
	v_mfma_f32_16x16x32_bf16 v[76:79], v[12:15], v[44:47], v[76:79]
	v_mfma_f32_16x16x32_bf16 v[80:83], v[4:7], v[52:55], v[80:83]
	v_mfma_f32_16x16x32_bf16 v[84:87], v[12:15], v[52:55], v[84:87]
	v_mfma_f32_16x16x32_bf16 v[100:103], v[12:15], v[60:63], v[88:91]
	s_setprio 0
	s_setprio 1
	v_mfma_f32_16x16x32_bf16 v[88:91], v[16:19], v[32:35], 0
	v_mfma_f32_16x16x32_bf16 v[32:35], v[24:27], v[32:35], 0
	v_mfma_f32_16x16x32_bf16 v[112:115], v[20:23], v[36:39], v[88:91]
	v_mfma_f32_16x16x32_bf16 v[32:35], v[28:31], v[36:39], v[32:35]
	v_mfma_f32_16x16x32_bf16 v[36:39], v[16:19], v[40:43], 0
	v_mfma_f32_16x16x32_bf16 v[40:43], v[24:27], v[40:43], 0
	v_mfma_f32_16x16x32_bf16 v[36:39], v[20:23], v[44:47], v[36:39]
	v_mfma_f32_16x16x32_bf16 v[40:43], v[28:31], v[44:47], v[40:43]
	v_mfma_f32_16x16x32_bf16 v[44:47], v[16:19], v[48:51], 0
	v_mfma_f32_16x16x32_bf16 v[48:51], v[24:27], v[48:51], 0
	v_mfma_f32_16x16x32_bf16 v[44:47], v[20:23], v[52:55], v[44:47]
	v_mfma_f32_16x16x32_bf16 v[48:51], v[28:31], v[52:55], v[48:51]
	v_mfma_f32_16x16x32_bf16 v[52:55], v[16:19], v[56:59], 0
	v_mfma_f32_16x16x32_bf16 v[56:59], v[24:27], v[56:59], 0
	v_mfma_f32_16x16x32_bf16 v[52:55], v[20:23], v[60:63], v[52:55]
	v_mfma_f32_16x16x32_bf16 v[56:59], v[28:31], v[60:63], v[56:59]
	s_barrier
	s_setprio 0
	s_add_i32 s66, s60, s45
	v_lshl_add_u64 v[242:243], s[26:27], 0, v[128:129]
	s_add_i32 s67, s66, 0x2000
	v_lshl_add_u64 v[148:149], v[242:243], 0, s[12:13]
	s_mov_b32 m0, s66
	v_lshl_add_u64 v[244:245], s[26:27], 0, v[130:131]
	s_add_u32 s38, s26, 0x80100
	ds_read_b128 v[60:63], v147 offset:16384
	ds_read_b128 v[88:91], v147 offset:17408
	ds_read_b128 v[92:95], v147 offset:18432
	ds_read_b128 v[104:107], v147 offset:19456
	ds_read_b128 v[108:111], v147 offset:20480
	ds_read_b128 v[116:119], v147 offset:21504
	ds_read_b128 v[120:123], v147 offset:22528
	ds_read_b128 v[124:127], v147 offset:23552
	global_load_lds_dwordx4 v[148:149], off
	v_lshl_add_u64 v[148:149], v[244:245], 0, s[12:13]
	s_mov_b32 m0, s67
	s_addc_u32 s39, s27, 0
	s_add_i32 s68, s61, s45
	global_load_lds_dwordx4 v[148:149], off
	v_lshl_add_u64 v[148:149], s[38:39], 0, v[128:129]
	s_mov_b32 m0, s68
	s_add_i32 s69, s68, 0x2000
	global_load_lds_dwordx4 v128, s[38:39]
	v_lshl_add_u64 v[148:149], s[38:39], 0, v[130:131]
	s_mov_b32 m0, s69
	v_lshl_add_u64 v[246:247], s[36:37], 0, v[134:135]
	global_load_lds_dwordx4 v130, s[38:39]
	v_lshl_add_u64 v[148:149], v[246:247], 0, s[12:13]
	s_mov_b32 m0, s47
	v_lshl_add_u64 v[248:249], s[36:37], 0, v[132:133]
	global_load_lds_dwordx4 v[148:149], off
	v_lshl_add_u64 v[148:149], v[248:249], 0, s[12:13]
	s_mov_b32 m0, s48
	s_nop 0
	global_load_lds_dwordx4 v[148:149], off
	s_waitcnt vmcnt(8) lgkmcnt(0)
	s_setprio 1
	s_barrier
	v_mfma_f32_16x16x32_bf16 v[148:151], v[0:3], v[60:63], 0
	v_mfma_f32_16x16x32_bf16 v[158:161], v[0:3], v[92:95], 0
	v_mfma_f32_16x16x32_bf16 v[166:169], v[0:3], v[108:111], 0
	v_mfma_f32_16x16x32_bf16 v[0:3], v[0:3], v[120:123], 0
	v_mfma_f32_16x16x32_bf16 v[150:153], v[4:7], v[88:91], v[148:151]
	v_mfma_f32_16x16x32_bf16 v[158:161], v[4:7], v[104:107], v[158:161]
	v_mfma_f32_16x16x32_bf16 v[166:169], v[4:7], v[116:119], v[166:169]
	v_mfma_f32_16x16x32_bf16 v[0:3], v[4:7], v[124:127], v[0:3]
	v_mfma_f32_16x16x32_bf16 v[4:7], v[8:11], v[120:123], 0
	v_mfma_f32_16x16x32_bf16 v[154:157], v[8:11], v[60:63], 0
	v_mfma_f32_16x16x32_bf16 v[162:165], v[8:11], v[92:95], 0
	v_mfma_f32_16x16x32_bf16 v[170:173], v[8:11], v[108:111], 0
	v_mfma_f32_16x16x32_bf16 v[4:7], v[12:15], v[124:127], v[4:7]
	v_mfma_f32_16x16x32_bf16 v[154:157], v[12:15], v[88:91], v[154:157]
	v_mfma_f32_16x16x32_bf16 v[162:165], v[12:15], v[104:107], v[162:165]
	v_mfma_f32_16x16x32_bf16 v[170:173], v[12:15], v[116:119], v[170:173]
	s_setprio 0
	s_setprio 1
	v_mfma_f32_16x16x32_bf16 v[8:11], v[16:19], v[60:63], 0
	v_mfma_f32_16x16x32_bf16 v[174:177], v[20:23], v[88:91], v[8:11]
	v_mfma_f32_16x16x32_bf16 v[8:11], v[24:27], v[60:63], 0
	v_mfma_f32_16x16x32_bf16 v[60:63], v[28:31], v[88:91], v[8:11]
	v_mfma_f32_16x16x32_bf16 v[8:11], v[16:19], v[92:95], 0
	v_mfma_f32_16x16x32_bf16 v[178:181], v[20:23], v[104:107], v[8:11]
	v_mfma_f32_16x16x32_bf16 v[8:11], v[24:27], v[92:95], 0
	v_mfma_f32_16x16x32_bf16 v[182:185], v[28:31], v[104:107], v[8:11]
	v_mfma_f32_16x16x32_bf16 v[8:11], v[16:19], v[108:111], 0
	v_mfma_f32_16x16x32_bf16 v[186:189], v[20:23], v[116:119], v[8:11]
	v_mfma_f32_16x16x32_bf16 v[8:11], v[24:27], v[108:111], 0
	v_mfma_f32_16x16x32_bf16 v[190:193], v[28:31], v[116:119], v[8:11]
	v_mfma_f32_16x16x32_bf16 v[8:11], v[16:19], v[120:123], 0
	v_mfma_f32_16x16x32_bf16 v[194:197], v[20:23], v[124:127], v[8:11]
	v_mfma_f32_16x16x32_bf16 v[8:11], v[24:27], v[120:123], 0
	v_mfma_f32_16x16x32_bf16 v[198:201], v[28:31], v[124:127], v[8:11]
	s_barrier
	s_setprio 0
	s_add_i32 s70, 0, 0x18000
	s_add_i32 s72, 0, 0x1c000
	v_add_u32_e32 v148, s70, v144
	v_add_u32_e32 v149, s72, v144
	s_nop 0
	ds_read_b128 v[8:11], v148
	ds_read_b128 v[12:15], v148 offset:1024
	ds_read_b128 v[16:19], v148 offset:2048
	ds_read_b128 v[20:23], v148 offset:3072
	ds_read_b128 v[202:205], v149
	ds_read_b128 v[206:209], v149 offset:1024
	ds_read_b128 v[210:213], v149 offset:2048
	ds_read_b128 v[214:217], v149 offset:3072
	s_add_u32 s38, s36, 0x80100
	s_addc_u32 s39, s37, 0
	s_mov_b32 m0, s49
	v_lshl_add_u64 v[88:89], s[38:39], 0, v[134:135]
	ds_read_b128 v[24:27], v147 offset:32768
	ds_read_b128 v[28:31], v147 offset:33792
	ds_read_b128 v[218:221], v147 offset:34816
	ds_read_b128 v[222:225], v147 offset:35840
	ds_read_b128 v[226:229], v147 offset:36864
	ds_read_b128 v[230:233], v147 offset:37888
	ds_read_b128 v[234:237], v147 offset:38912
	ds_read_b128 v[238:241], v147 offset:39936
	global_load_lds_dwordx4 v134, s[38:39]
	v_lshl_add_u64 v[88:89], s[38:39], 0, v[132:133]
	s_mov_b32 m0, s50
	s_nop 0
	global_load_lds_dwordx4 v132, s[38:39]
	s_waitcnt vmcnt(8) lgkmcnt(0)
	s_setprio 1
	s_barrier
	v_mfma_f32_16x16x32_bf16 v[64:67], v[8:11], v[24:27], v[64:67]
	v_mfma_f32_16x16x32_bf16 v[120:123], v[12:15], v[28:31], v[64:67]
	v_mfma_f32_16x16x32_bf16 v[64:67], v[16:19], v[24:27], v[68:71]
	v_mfma_f32_16x16x32_bf16 v[124:127], v[20:23], v[28:31], v[64:67]
	v_mfma_f32_16x16x32_bf16 v[64:67], v[8:11], v[218:221], v[72:75]
	v_mfma_f32_16x16x32_bf16 v[104:107], v[12:15], v[222:225], v[64:67]
	v_mfma_f32_16x16x32_bf16 v[64:67], v[16:19], v[218:221], v[76:79]
	v_mfma_f32_16x16x32_bf16 v[108:111], v[20:23], v[222:225], v[64:67]
	v_mfma_f32_16x16x32_bf16 v[64:67], v[8:11], v[226:229], v[80:83]
	v_mfma_f32_16x16x32_bf16 v[88:91], v[12:15], v[230:233], v[64:67]
	v_mfma_f32_16x16x32_bf16 v[64:67], v[16:19], v[226:229], v[84:87]
	v_mfma_f32_16x16x32_bf16 v[92:95], v[20:23], v[230:233], v[64:67]
	v_mfma_f32_16x16x32_bf16 v[64:67], v[8:11], v[234:237], v[96:99]
	v_mfma_f32_16x16x32_bf16 v[68:71], v[16:19], v[234:237], v[100:103]
	v_mfma_f32_16x16x32_bf16 v[64:67], v[12:15], v[238:241], v[64:67]
	v_mfma_f32_16x16x32_bf16 v[68:71], v[20:23], v[238:241], v[68:71]
	s_setprio 0
	s_setprio 1
	v_mfma_f32_16x16x32_bf16 v[72:75], v[202:205], v[24:27], v[112:115]
	v_mfma_f32_16x16x32_bf16 v[24:27], v[210:213], v[24:27], v[32:35]
	v_mfma_f32_16x16x32_bf16 v[116:119], v[214:217], v[28:31], v[24:27]
	v_mfma_f32_16x16x32_bf16 v[24:27], v[202:205], v[218:221], v[36:39]
	v_mfma_f32_16x16x32_bf16 v[96:99], v[206:209], v[222:225], v[24:27]
	v_mfma_f32_16x16x32_bf16 v[24:27], v[210:213], v[218:221], v[40:43]
	v_mfma_f32_16x16x32_bf16 v[100:103], v[214:217], v[222:225], v[24:27]
	v_mfma_f32_16x16x32_bf16 v[24:27], v[202:205], v[226:229], v[44:47]
	v_mfma_f32_16x16x32_bf16 v[80:83], v[206:209], v[230:233], v[24:27]
	v_mfma_f32_16x16x32_bf16 v[24:27], v[210:213], v[226:229], v[48:51]
	v_mfma_f32_16x16x32_bf16 v[84:87], v[214:217], v[230:233], v[24:27]
	v_mfma_f32_16x16x32_bf16 v[24:27], v[202:205], v[234:237], v[52:55]
	v_mfma_f32_16x16x32_bf16 v[48:51], v[206:209], v[238:241], v[24:27]
	v_mfma_f32_16x16x32_bf16 v[24:27], v[210:213], v[234:237], v[56:59]
	v_mfma_f32_16x16x32_bf16 v[112:115], v[206:209], v[28:31], v[72:75]
	v_mfma_f32_16x16x32_bf16 v[52:55], v[214:217], v[238:241], v[24:27]
	s_barrier
; #define PG8_MMA(ai, bj, At, Bt) do { __builtin_amdgcn_s_setprio(1); _Pragma("unroll") for (int m = 0; m < 4; ++m) _Pragma("unroll") for (int n = 0; n < 2; ++n) _Pragma("unroll") for (int k = 0; k < 2; ++k) \
;         acc[ai][bj][m][n] = __builtin_amdgcn_mfma_f32_16x16x32_bf16(Bt[n][k], At[m][k], acc[ai][bj][m][n], 0, 0, 0); __builtin_amdgcn_s_setprio(0); } while (0)
; template <class Epi, class Sched, bool ALIGN_EPI = false, bool SP2 = false, bool A_TILED = false>
; __device__ __forceinline__ void gemm_phase(PG8_LAS unsigned char* lds, const Gemm g, const Sched& S, const Epi& E, const int wave_s) {
;     ...
;         for (int t = PEEL ? 2 : 0; t < nt; t += 2) {
;             const bool last = (t == nt - 2);
;             const char* a1 = cA + (size_t)(t + 1) * kstepA;
;             const char* a2 = last ? nA : cA + (size_t)(t + 2) * kstepA; const char* b2 = last ? nB : cB + (size_t)(t + 2) * kstep;
;             const char* a3 = a2 + kstepA; const char* b3 = b2 + kstep;
;             if (last && has_next) S.a_ready(nxt);
;             if constexpr (SP2) {
;             PG8_ITER(PG8_MMA)
	s_setprio 0
	s_add_i32 s70, s70, s45
	s_add_i32 s71, s70, 0x2000
	s_nop 1
	v_lshl_add_u64 v[24:25], v[242:243], 0, s[14:15]
	s_mov_b32 m0, s70
	s_add_u32 s38, s26, 0x80180
	ds_read_b128 v[32:35], v147 offset:49152
	ds_read_b128 v[36:39], v147 offset:50176
	ds_read_b128 v[218:221], v147 offset:51200
	ds_read_b128 v[222:225], v147 offset:52224
	ds_read_b128 v[226:229], v147 offset:53248
	ds_read_b128 v[230:233], v147 offset:54272
	ds_read_b128 v[234:237], v147 offset:55296
	ds_read_b128 v[238:241], v147 offset:56320
	global_load_lds_dwordx4 v[24:25], off
	v_lshl_add_u64 v[24:25], v[244:245], 0, s[14:15]
	s_mov_b32 m0, s71
	s_addc_u32 s39, s27, 0
	s_add_i32 s72, s72, s45
	global_load_lds_dwordx4 v[24:25], off
	v_lshl_add_u64 v[24:25], s[38:39], 0, v[128:129]
	s_mov_b32 m0, s72
	s_add_i32 s73, s72, 0x2000
	global_load_lds_dwordx4 v128, s[38:39]
	v_lshl_add_u64 v[24:25], s[38:39], 0, v[130:131]
	s_mov_b32 m0, s73
	s_nop 0
	global_load_lds_dwordx4 v130, s[38:39]
	v_lshl_add_u64 v[24:25], v[246:247], 0, s[14:15]
	s_mov_b32 m0, s56
	s_nop 0
	global_load_lds_dwordx4 v[24:25], off
	v_lshl_add_u64 v[24:25], v[248:249], 0, s[14:15]
	s_mov_b32 m0, s57
	s_nop 0
	global_load_lds_dwordx4 v[24:25], off
	s_waitcnt vmcnt(8) lgkmcnt(0)
	s_setprio 1
	s_barrier
	v_mfma_f32_16x16x32_bf16 v[24:27], v[8:11], v[32:35], v[150:153]
	v_mfma_f32_16x16x32_bf16 v[72:75], v[12:15], v[36:39], v[24:27]
	v_mfma_f32_16x16x32_bf16 v[24:27], v[16:19], v[32:35], v[154:157]
	v_mfma_f32_16x16x32_bf16 v[76:79], v[20:23], v[36:39], v[24:27]
	v_mfma_f32_16x16x32_bf16 v[24:27], v[8:11], v[218:221], v[158:161]
	v_mfma_f32_16x16x32_bf16 v[40:43], v[12:15], v[222:225], v[24:27]
	v_mfma_f32_16x16x32_bf16 v[24:27], v[16:19], v[218:221], v[162:165]
	v_mfma_f32_16x16x32_bf16 v[0:3], v[8:11], v[234:237], v[0:3]
	v_mfma_f32_16x16x32_bf16 v[44:47], v[20:23], v[222:225], v[24:27]
	v_mfma_f32_16x16x32_bf16 v[24:27], v[8:11], v[226:229], v[166:169]
	v_mfma_f32_16x16x32_bf16 v[28:31], v[16:19], v[226:229], v[170:173]
	v_mfma_f32_16x16x32_bf16 v[8:11], v[12:15], v[238:241], v[0:3]
	v_mfma_f32_16x16x32_bf16 v[0:3], v[16:19], v[234:237], v[4:7]
	v_mfma_f32_16x16x32_bf16 v[24:27], v[12:15], v[230:233], v[24:27]
	v_mfma_f32_16x16x32_bf16 v[28:31], v[20:23], v[230:233], v[28:31]
	v_mfma_f32_16x16x32_bf16 v[12:15], v[20:23], v[238:241], v[0:3]
	s_setprio 0
	s_setprio 1
	v_mfma_f32_16x16x32_bf16 v[0:3], v[202:205], v[32:35], v[174:177]
	v_mfma_f32_16x16x32_bf16 v[56:59], v[206:209], v[36:39], v[0:3]
	v_mfma_f32_16x16x32_bf16 v[0:3], v[210:213], v[32:35], v[60:63]
	v_mfma_f32_16x16x32_bf16 v[60:63], v[214:217], v[36:39], v[0:3]
	v_mfma_f32_16x16x32_bf16 v[0:3], v[202:205], v[218:221], v[178:181]
	v_mfma_f32_16x16x32_bf16 v[32:35], v[206:209], v[222:225], v[0:3]
	v_mfma_f32_16x16x32_bf16 v[0:3], v[210:213], v[218:221], v[182:185]
	v_mfma_f32_16x16x32_bf16 v[36:39], v[214:217], v[222:225], v[0:3]
	v_mfma_f32_16x16x32_bf16 v[0:3], v[202:205], v[226:229], v[186:189]
	v_mfma_f32_16x16x32_bf16 v[16:19], v[206:209], v[230:233], v[0:3]
	v_mfma_f32_16x16x32_bf16 v[0:3], v[210:213], v[226:229], v[190:193]
	v_mfma_f32_16x16x32_bf16 v[20:23], v[214:217], v[230:233], v[0:3]
	v_mfma_f32_16x16x32_bf16 v[0:3], v[202:205], v[234:237], v[194:197]
	v_mfma_f32_16x16x32_bf16 v[4:7], v[210:213], v[234:237], v[198:201]
	v_mfma_f32_16x16x32_bf16 v[0:3], v[206:209], v[238:241], v[0:3]
	v_mfma_f32_16x16x32_bf16 v[4:7], v[214:217], v[238:241], v[4:7]
	s_barrier
	s_setprio 0
	s_add_u32 s74, s26, 0x200
	s_addc_u32 s75, s27, 0
	s_add_u32 s26, s36, 0x80180
	s_addc_u32 s27, s37, 0
	s_mov_b32 s76, 0
.LBB0_3720:
	ds_read_b128 v[150:153], v145
	ds_read_b128 v[154:157], v145 offset:1024
	ds_read_b128 v[158:161], v145 offset:2048
	ds_read_b128 v[162:165], v145 offset:3072
	ds_read_b128 v[166:169], v146
	ds_read_b128 v[170:173], v146 offset:1024
	ds_read_b128 v[174:177], v146 offset:2048
	ds_read_b128 v[178:181], v146 offset:3072
	s_add_u32 s36, s26, 0xfff80080
	s_addc_u32 s37, s27, -1
	s_cmp_eq_u32 s76, 28
	s_cselect_b32 s39, s17, s37
	s_cselect_b32 s38, s19, s36
	s_cselect_b32 s37, s62, s75
	s_cselect_b32 s36, s63, s74
	s_mov_b32 m0, s64
	v_lshl_add_u64 v[214:215], s[26:27], 0, v[138:139]
	ds_read_b128 v[182:185], v147
	ds_read_b128 v[186:189], v147 offset:1024
	ds_read_b128 v[190:193], v147 offset:2048
	ds_read_b128 v[194:197], v147 offset:3072
	ds_read_b128 v[198:201], v147 offset:4096
	ds_read_b128 v[202:205], v147 offset:5120
	ds_read_b128 v[206:209], v147 offset:6144
	ds_read_b128 v[210:213], v147 offset:7168
	global_load_lds_dwordx4 v138, s[26:27]
	v_lshl_add_u64 v[214:215], s[26:27], 0, v[136:137]
	s_mov_b32 m0, s65
	s_nop 0
	global_load_lds_dwordx4 v136, s[26:27]
	s_waitcnt vmcnt(8) lgkmcnt(0)
	s_setprio 1
	s_barrier
	v_mfma_f32_16x16x32_bf16 v[120:123], v[150:153], v[182:185], v[120:123]
	v_mfma_f32_16x16x32_bf16 v[124:127], v[158:161], v[182:185], v[124:127]
	v_mfma_f32_16x16x32_bf16 v[104:107], v[150:153], v[190:193], v[104:107]
	v_mfma_f32_16x16x32_bf16 v[108:111], v[158:161], v[190:193], v[108:111]
	v_mfma_f32_16x16x32_bf16 v[88:91], v[150:153], v[198:201], v[88:91]
	v_mfma_f32_16x16x32_bf16 v[92:95], v[158:161], v[198:201], v[92:95]
	v_mfma_f32_16x16x32_bf16 v[64:67], v[150:153], v[206:209], v[64:67]
	v_mfma_f32_16x16x32_bf16 v[68:71], v[158:161], v[206:209], v[68:71]
	v_mfma_f32_16x16x32_bf16 v[120:123], v[154:157], v[186:189], v[120:123]
	v_mfma_f32_16x16x32_bf16 v[124:127], v[162:165], v[186:189], v[124:127]
	v_mfma_f32_16x16x32_bf16 v[104:107], v[154:157], v[194:197], v[104:107]
	v_mfma_f32_16x16x32_bf16 v[108:111], v[162:165], v[194:197], v[108:111]
	v_mfma_f32_16x16x32_bf16 v[88:91], v[154:157], v[202:205], v[88:91]
	v_mfma_f32_16x16x32_bf16 v[92:95], v[162:165], v[202:205], v[92:95]
	v_mfma_f32_16x16x32_bf16 v[64:67], v[154:157], v[210:213], v[64:67]
	v_mfma_f32_16x16x32_bf16 v[68:71], v[162:165], v[210:213], v[68:71]
	s_setprio 0
	s_setprio 1
	v_mfma_f32_16x16x32_bf16 v[112:115], v[166:169], v[182:185], v[112:115]
	v_mfma_f32_16x16x32_bf16 v[116:119], v[174:177], v[182:185], v[116:119]
	v_mfma_f32_16x16x32_bf16 v[96:99], v[166:169], v[190:193], v[96:99]
	v_mfma_f32_16x16x32_bf16 v[100:103], v[174:177], v[190:193], v[100:103]
	v_mfma_f32_16x16x32_bf16 v[80:83], v[166:169], v[198:201], v[80:83]
	v_mfma_f32_16x16x32_bf16 v[84:87], v[174:177], v[198:201], v[84:87]
	v_mfma_f32_16x16x32_bf16 v[48:51], v[166:169], v[206:209], v[48:51]
	v_mfma_f32_16x16x32_bf16 v[52:55], v[174:177], v[206:209], v[52:55]
	v_mfma_f32_16x16x32_bf16 v[112:115], v[170:173], v[186:189], v[112:115]
	v_mfma_f32_16x16x32_bf16 v[116:119], v[178:181], v[186:189], v[116:119]
	v_mfma_f32_16x16x32_bf16 v[96:99], v[170:173], v[194:197], v[96:99]
	v_mfma_f32_16x16x32_bf16 v[100:103], v[178:181], v[194:197], v[100:103]
	v_mfma_f32_16x16x32_bf16 v[80:83], v[170:173], v[202:205], v[80:83]
	v_mfma_f32_16x16x32_bf16 v[84:87], v[178:181], v[202:205], v[84:87]
	v_mfma_f32_16x16x32_bf16 v[48:51], v[170:173], v[210:213], v[48:51]
	v_mfma_f32_16x16x32_bf16 v[52:55], v[178:181], v[210:213], v[52:55]
	s_barrier
	s_setprio 0
	s_mov_b32 m0, s66
	v_lshl_add_u64 v[214:215], s[36:37], 0, v[128:129]
	s_add_u32 s78, s36, 0x80000
	ds_read_b128 v[182:185], v147 offset:16384
	ds_read_b128 v[186:189], v147 offset:17408
	ds_read_b128 v[190:193], v147 offset:18432
	ds_read_b128 v[194:197], v147 offset:19456
	ds_read_b128 v[198:201], v147 offset:20480
	ds_read_b128 v[202:205], v147 offset:21504
	ds_read_b128 v[206:209], v147 offset:22528
	ds_read_b128 v[210:213], v147 offset:23552
	global_load_lds_dwordx4 v128, s[36:37]
	v_lshl_add_u64 v[216:217], s[36:37], 0, v[130:131]
	s_mov_b32 m0, s67
	s_addc_u32 s79, s37, 0
	global_load_lds_dwordx4 v130, s[36:37]
	v_lshl_add_u64 v[218:219], s[78:79], 0, v[128:129]
	s_mov_b32 m0, s68
	v_lshl_add_u64 v[220:221], s[38:39], 0, v[132:133]
	global_load_lds_dwordx4 v128, s[78:79]
	v_lshl_add_u64 v[218:219], s[78:79], 0, v[130:131]
	s_mov_b32 m0, s69
	s_nop 0
	global_load_lds_dwordx4 v130, s[78:79]
	v_lshl_add_u64 v[218:219], s[38:39], 0, v[134:135]
	s_mov_b32 m0, s47
	s_nop 0
	global_load_lds_dwordx4 v134, s[38:39]
	s_mov_b32 m0, s48
	s_nop 0
	global_load_lds_dwordx4 v132, s[38:39]
	s_waitcnt vmcnt(8) lgkmcnt(0)
	s_setprio 1
	s_barrier
	v_mfma_f32_16x16x32_bf16 v[72:75], v[150:153], v[182:185], v[72:75]
	v_mfma_f32_16x16x32_bf16 v[76:79], v[158:161], v[182:185], v[76:79]
	v_mfma_f32_16x16x32_bf16 v[40:43], v[150:153], v[190:193], v[40:43]
	v_mfma_f32_16x16x32_bf16 v[44:47], v[158:161], v[190:193], v[44:47]
	v_mfma_f32_16x16x32_bf16 v[24:27], v[150:153], v[198:201], v[24:27]
	v_mfma_f32_16x16x32_bf16 v[28:31], v[158:161], v[198:201], v[28:31]
	v_mfma_f32_16x16x32_bf16 v[8:11], v[150:153], v[206:209], v[8:11]
	v_mfma_f32_16x16x32_bf16 v[12:15], v[158:161], v[206:209], v[12:15]
	v_mfma_f32_16x16x32_bf16 v[72:75], v[154:157], v[186:189], v[72:75]
	v_mfma_f32_16x16x32_bf16 v[76:79], v[162:165], v[186:189], v[76:79]
	v_mfma_f32_16x16x32_bf16 v[40:43], v[154:157], v[194:197], v[40:43]
	v_mfma_f32_16x16x32_bf16 v[44:47], v[162:165], v[194:197], v[44:47]
	v_mfma_f32_16x16x32_bf16 v[24:27], v[154:157], v[202:205], v[24:27]
	v_mfma_f32_16x16x32_bf16 v[28:31], v[162:165], v[202:205], v[28:31]
	v_mfma_f32_16x16x32_bf16 v[8:11], v[154:157], v[210:213], v[8:11]
	v_mfma_f32_16x16x32_bf16 v[12:15], v[162:165], v[210:213], v[12:15]
	s_setprio 0
	s_setprio 1
	v_mfma_f32_16x16x32_bf16 v[56:59], v[166:169], v[182:185], v[56:59]
	v_mfma_f32_16x16x32_bf16 v[60:63], v[174:177], v[182:185], v[60:63]
	v_mfma_f32_16x16x32_bf16 v[32:35], v[166:169], v[190:193], v[32:35]
	v_mfma_f32_16x16x32_bf16 v[36:39], v[174:177], v[190:193], v[36:39]
	v_mfma_f32_16x16x32_bf16 v[16:19], v[166:169], v[198:201], v[16:19]
	v_mfma_f32_16x16x32_bf16 v[20:23], v[174:177], v[198:201], v[20:23]
	v_mfma_f32_16x16x32_bf16 v[0:3], v[166:169], v[206:209], v[0:3]
	v_mfma_f32_16x16x32_bf16 v[4:7], v[174:177], v[206:209], v[4:7]
	v_mfma_f32_16x16x32_bf16 v[56:59], v[170:173], v[186:189], v[56:59]
	v_mfma_f32_16x16x32_bf16 v[60:63], v[178:181], v[186:189], v[60:63]
	v_mfma_f32_16x16x32_bf16 v[32:35], v[170:173], v[194:197], v[32:35]
	v_mfma_f32_16x16x32_bf16 v[36:39], v[178:181], v[194:197], v[36:39]
	v_mfma_f32_16x16x32_bf16 v[16:19], v[170:173], v[202:205], v[16:19]
	v_mfma_f32_16x16x32_bf16 v[20:23], v[178:181], v[202:205], v[20:23]
	v_mfma_f32_16x16x32_bf16 v[0:3], v[170:173], v[210:213], v[0:3]
	v_mfma_f32_16x16x32_bf16 v[4:7], v[178:181], v[210:213], v[4:7]
	s_barrier
; #define PG8_MMA(ai, bj, At, Bt) do { __builtin_amdgcn_s_setprio(1); _Pragma("unroll") for (int m = 0; m < 4; ++m) _Pragma("unroll") for (int n = 0; n < 2; ++n) _Pragma("unroll") for (int k = 0; k < 2; ++k) \
;         acc[ai][bj][m][n] = __builtin_amdgcn_mfma_f32_16x16x32_bf16(Bt[n][k], At[m][k], acc[ai][bj][m][n], 0, 0, 0); __builtin_amdgcn_s_setprio(0); } while (0)
; template <class Epi, class Sched, bool ALIGN_EPI = false, bool SP2 = false, bool A_TILED = false>
; __device__ __forceinline__ void gemm_phase(PG8_LAS unsigned char* lds, const Gemm g, const Sched& S, const Epi& E, const int wave_s) {
;     ...
; #pragma nounroll
;         for (int t = PEEL ? 2 : 0; t < nt; t += 2) {
;             const bool last = (t == nt - 2);
;             const char* a1 = cA + (size_t)(t + 1) * kstepA;
;             const char* a2 = last ? nA : cA + (size_t)(t + 2) * kstepA; const char* b2 = last ? nB : cB + (size_t)(t + 2) * kstep;
;             const char* a3 = a2 + kstepA; const char* b3 = b2 + kstep;
;             if (last && has_next) S.a_ready(nxt);
;             if constexpr (SP2) {
;             PG8_ITER(PG8_MMA)
	s_setprio 0
	ds_read_b128 v[150:153], v148
	ds_read_b128 v[154:157], v148 offset:1024
	ds_read_b128 v[158:161], v148 offset:2048
	ds_read_b128 v[162:165], v148 offset:3072
	ds_read_b128 v[166:169], v149
	ds_read_b128 v[170:173], v149 offset:1024
	ds_read_b128 v[174:177], v149 offset:2048
	ds_read_b128 v[178:181], v149 offset:3072
	s_add_u32 s38, s38, 0x80000
	s_addc_u32 s39, s39, 0
	s_mov_b32 m0, s49
	v_lshl_add_u64 v[222:223], s[38:39], 0, v[134:135]
	ds_read_b128 v[182:185], v147 offset:32768
	ds_read_b128 v[186:189], v147 offset:33792
	ds_read_b128 v[190:193], v147 offset:34816
	ds_read_b128 v[194:197], v147 offset:35840
	ds_read_b128 v[198:201], v147 offset:36864
	ds_read_b128 v[202:205], v147 offset:37888
	ds_read_b128 v[206:209], v147 offset:38912
	ds_read_b128 v[210:213], v147 offset:39936
	global_load_lds_dwordx4 v134, s[38:39]
	v_lshl_add_u64 v[222:223], s[38:39], 0, v[132:133]
	s_mov_b32 m0, s50
	s_nop 0
	global_load_lds_dwordx4 v132, s[38:39]
	s_waitcnt vmcnt(8) lgkmcnt(0)
	s_setprio 1
	s_barrier
	v_mfma_f32_16x16x32_bf16 v[120:123], v[150:153], v[182:185], v[120:123]
	v_mfma_f32_16x16x32_bf16 v[124:127], v[158:161], v[182:185], v[124:127]
	v_mfma_f32_16x16x32_bf16 v[104:107], v[150:153], v[190:193], v[104:107]
	v_mfma_f32_16x16x32_bf16 v[108:111], v[158:161], v[190:193], v[108:111]
	v_mfma_f32_16x16x32_bf16 v[88:91], v[150:153], v[198:201], v[88:91]
	v_mfma_f32_16x16x32_bf16 v[92:95], v[158:161], v[198:201], v[92:95]
	v_mfma_f32_16x16x32_bf16 v[64:67], v[150:153], v[206:209], v[64:67]
	v_mfma_f32_16x16x32_bf16 v[68:71], v[158:161], v[206:209], v[68:71]
	v_mfma_f32_16x16x32_bf16 v[120:123], v[154:157], v[186:189], v[120:123]
	v_mfma_f32_16x16x32_bf16 v[124:127], v[162:165], v[186:189], v[124:127]
	v_mfma_f32_16x16x32_bf16 v[104:107], v[154:157], v[194:197], v[104:107]
	v_mfma_f32_16x16x32_bf16 v[108:111], v[162:165], v[194:197], v[108:111]
	v_mfma_f32_16x16x32_bf16 v[88:91], v[154:157], v[202:205], v[88:91]
	v_mfma_f32_16x16x32_bf16 v[92:95], v[162:165], v[202:205], v[92:95]
	v_mfma_f32_16x16x32_bf16 v[64:67], v[154:157], v[210:213], v[64:67]
	v_mfma_f32_16x16x32_bf16 v[68:71], v[162:165], v[210:213], v[68:71]
	s_setprio 0
	s_setprio 1
	v_mfma_f32_16x16x32_bf16 v[112:115], v[166:169], v[182:185], v[112:115]
	v_mfma_f32_16x16x32_bf16 v[116:119], v[174:177], v[182:185], v[116:119]
	v_mfma_f32_16x16x32_bf16 v[96:99], v[166:169], v[190:193], v[96:99]
	v_mfma_f32_16x16x32_bf16 v[100:103], v[174:177], v[190:193], v[100:103]
	v_mfma_f32_16x16x32_bf16 v[80:83], v[166:169], v[198:201], v[80:83]
	v_mfma_f32_16x16x32_bf16 v[84:87], v[174:177], v[198:201], v[84:87]
	v_mfma_f32_16x16x32_bf16 v[48:51], v[166:169], v[206:209], v[48:51]
	v_mfma_f32_16x16x32_bf16 v[52:55], v[174:177], v[206:209], v[52:55]
	v_mfma_f32_16x16x32_bf16 v[112:115], v[170:173], v[186:189], v[112:115]
	v_mfma_f32_16x16x32_bf16 v[116:119], v[178:181], v[186:189], v[116:119]
	v_mfma_f32_16x16x32_bf16 v[96:99], v[170:173], v[194:197], v[96:99]
	v_mfma_f32_16x16x32_bf16 v[100:103], v[178:181], v[194:197], v[100:103]
	v_mfma_f32_16x16x32_bf16 v[80:83], v[170:173], v[202:205], v[80:83]
	v_mfma_f32_16x16x32_bf16 v[84:87], v[178:181], v[202:205], v[84:87]
	v_mfma_f32_16x16x32_bf16 v[48:51], v[170:173], v[210:213], v[48:51]
	v_mfma_f32_16x16x32_bf16 v[52:55], v[178:181], v[210:213], v[52:55]
	s_barrier
	s_setprio 0
	s_mov_b32 m0, s70
	v_lshl_add_u64 v[214:215], v[214:215], 0, s[6:7]
	s_add_u32 s36, s36, 0x80080
	ds_read_b128 v[182:185], v147 offset:49152
	ds_read_b128 v[186:189], v147 offset:50176
	ds_read_b128 v[190:193], v147 offset:51200
	ds_read_b128 v[194:197], v147 offset:52224
	ds_read_b128 v[198:201], v147 offset:53248
	ds_read_b128 v[202:205], v147 offset:54272
	ds_read_b128 v[206:209], v147 offset:55296
	ds_read_b128 v[210:213], v147 offset:56320
	global_load_lds_dwordx4 v[214:215], off
	v_lshl_add_u64 v[214:215], v[216:217], 0, s[6:7]
	s_mov_b32 m0, s71
	s_addc_u32 s37, s37, 0
	global_load_lds_dwordx4 v[214:215], off
	v_lshl_add_u64 v[214:215], s[36:37], 0, v[128:129]
	s_mov_b32 m0, s72
	s_nop 0
	global_load_lds_dwordx4 v128, s[36:37]
	v_lshl_add_u64 v[214:215], s[36:37], 0, v[130:131]
	s_mov_b32 m0, s73
	s_nop 0
	global_load_lds_dwordx4 v130, s[36:37]
	v_lshl_add_u64 v[214:215], v[218:219], 0, s[6:7]
	s_mov_b32 m0, s56
	s_nop 0
	global_load_lds_dwordx4 v[214:215], off
	v_lshl_add_u64 v[214:215], v[220:221], 0, s[6:7]
	s_mov_b32 m0, s57
	s_nop 0
	global_load_lds_dwordx4 v[214:215], off
	s_waitcnt vmcnt(8) lgkmcnt(0)
	s_setprio 1
	s_barrier
	v_mfma_f32_16x16x32_bf16 v[72:75], v[150:153], v[182:185], v[72:75]
	v_mfma_f32_16x16x32_bf16 v[76:79], v[158:161], v[182:185], v[76:79]
	v_mfma_f32_16x16x32_bf16 v[40:43], v[150:153], v[190:193], v[40:43]
	v_mfma_f32_16x16x32_bf16 v[44:47], v[158:161], v[190:193], v[44:47]
	v_mfma_f32_16x16x32_bf16 v[24:27], v[150:153], v[198:201], v[24:27]
	v_mfma_f32_16x16x32_bf16 v[28:31], v[158:161], v[198:201], v[28:31]
	v_mfma_f32_16x16x32_bf16 v[8:11], v[150:153], v[206:209], v[8:11]
	v_mfma_f32_16x16x32_bf16 v[12:15], v[158:161], v[206:209], v[12:15]
	v_mfma_f32_16x16x32_bf16 v[72:75], v[154:157], v[186:189], v[72:75]
	v_mfma_f32_16x16x32_bf16 v[76:79], v[162:165], v[186:189], v[76:79]
	v_mfma_f32_16x16x32_bf16 v[40:43], v[154:157], v[194:197], v[40:43]
	v_mfma_f32_16x16x32_bf16 v[44:47], v[162:165], v[194:197], v[44:47]
	v_mfma_f32_16x16x32_bf16 v[24:27], v[154:157], v[202:205], v[24:27]
	v_mfma_f32_16x16x32_bf16 v[28:31], v[162:165], v[202:205], v[28:31]
	v_mfma_f32_16x16x32_bf16 v[8:11], v[154:157], v[210:213], v[8:11]
	v_mfma_f32_16x16x32_bf16 v[12:15], v[162:165], v[210:213], v[12:15]
	s_setprio 0
	s_setprio 1
	v_mfma_f32_16x16x32_bf16 v[56:59], v[166:169], v[182:185], v[56:59]
	v_mfma_f32_16x16x32_bf16 v[60:63], v[174:177], v[182:185], v[60:63]
	v_mfma_f32_16x16x32_bf16 v[32:35], v[166:169], v[190:193], v[32:35]
	v_mfma_f32_16x16x32_bf16 v[36:39], v[174:177], v[190:193], v[36:39]
	v_mfma_f32_16x16x32_bf16 v[16:19], v[166:169], v[198:201], v[16:19]
	v_mfma_f32_16x16x32_bf16 v[20:23], v[174:177], v[198:201], v[20:23]
	v_mfma_f32_16x16x32_bf16 v[0:3], v[166:169], v[206:209], v[0:3]
	v_mfma_f32_16x16x32_bf16 v[4:7], v[174:177], v[206:209], v[4:7]
	v_mfma_f32_16x16x32_bf16 v[56:59], v[170:173], v[186:189], v[56:59]
	v_mfma_f32_16x16x32_bf16 v[60:63], v[178:181], v[186:189], v[60:63]
	v_mfma_f32_16x16x32_bf16 v[32:35], v[170:173], v[194:197], v[32:35]
	v_mfma_f32_16x16x32_bf16 v[36:39], v[178:181], v[194:197], v[36:39]
	v_mfma_f32_16x16x32_bf16 v[16:19], v[170:173], v[202:205], v[16:19]
	v_mfma_f32_16x16x32_bf16 v[20:23], v[178:181], v[202:205], v[20:23]
	v_mfma_f32_16x16x32_bf16 v[0:3], v[170:173], v[210:213], v[0:3]
	v_mfma_f32_16x16x32_bf16 v[4:7], v[178:181], v[210:213], v[4:7]
	s_barrier
	s_setprio 0
	s_add_i32 s76, s76, 2
	s_add_u32 s74, s74, 0x100
	s_addc_u32 s75, s75, 0
	s_add_u32 s26, s26, 0x100
	s_addc_u32 s27, s27, 0
	s_cmp_gt_u32 s76, 29
	s_cbranch_scc0 .LBB0_3720
	s_and_b64 vcc, exec, s[8:9]
	s_cbranch_vccz .LBB0_3723
	s_barrier

; #define PG8_STAGE(bufoff, gbase, voff) do { _Pragma("unroll") for (int _i = 0; _i < 2; ++_i) \
;         __builtin_amdgcn_global_load_lds((const unsigned*)((const char*)(gbase) + (voff)[_i]), (PG8_LAS unsigned*)(lds + (bufoff) + ldsw + _i * 8192), 16, 0, 0); } while (0)
; #define PG8_WAIT_V(n) asm volatile("s_waitcnt vmcnt(" #n ")" ::: "memory")
; template <class Epi, class Sched, bool ALIGN_EPI = false, bool SP2 = false, bool A_TILED = false>
; __device__ __forceinline__ void gemm_phase(PG8_LAS unsigned char* lds, const Gemm g, const Sched& S, const Epi& E, const int wave_s) {
;     ...
;     if constexpr (SP2) {
;         PG8_STAGE(PG8_SB(0, 0), cB, voffB); PG8_STAGE(PG8_SB(0, 1), cB + hstep, voffB); PG8_STAGE(PG8_SA(0, 0), cA, voffA); PG8_STAGE(PG8_SA(0, 1), cA + hstepA, voffA);
;         if (wr == 1) PG8_BAR;
;         PG8_WAIT_V(2); PG8_BAR;
;         PG8_STAGE(PG8_SB(1, 0), cB + kstep, voffB); PG8_STAGE(PG8_SA(1, 0), cA + kstepA, voffA); PG8_STAGE(PG8_SB(1, 1), cB + hstep + kstep, voffB);
;         PG8_WAIT_V(6); PG8_BAR;
;     } else {
;         PG8_STAGE(PG8_SB(0, 0), cB, voffB); PG8_STAGE(PG8_SA(0, 0), cA, voffA); PG8_STAGE(PG8_SB(0, 1), cB + hstep, voffB); PG8_STAGE(PG8_SA(0, 1), cA + hstepA, voffA);
;         if (wr == 1) PG8_BAR;
;         PG8_WAIT_V(4); PG8_BAR;
;         PG8_STAGE(PG8_SB(1, 0), cB + kstep, voffB); PG8_STAGE(PG8_SA(1, 0), cA + kstepA, voffA); PG8_STAGE(PG8_SB(1, 1), cB + hstep + kstep, voffB);
;         PG8_WAIT_V(6); PG8_BAR;
;     }
;     for (;;) {
;         const bool has_next = Epi::AFTER_DRAIN ? false : S.next(ui + 1, nxt);
;         const char* nA = has_next ? (const char*)g.A + (size_t)nxt.pm * tstepA : cA; const char* nB = has_next ? (const char*)g.Bt + (size_t)nxt.pn * tstep : cB;
;         constexpr bool PEEL = SP2 && !Epi::AFTER_DRAIN;
;         if constexpr (PEEL) {
;             const char* a1 = cA + kstepA; const char* a2 = cA + 2 * kstepA; const char* b2 = cB + 2 * kstep; const char* a3 = a2 + kstepA; const char* b3 = b2 + kstep;
;             PG8_ITER(PG8_MMAZ)
;         } else {
; #pragma unroll
;             for (int a = 0; a < 2; ++a)
; #pragma unroll
;                 for (int b = 0; b < 2; ++b)
; #pragma unroll
;                     for (int m = 0; m < 4; ++m)
; #pragma unroll
;                         for (int n = 0; n < 2; ++n) acc[a][b][m][n] = (f32x4){0.f, 0.f, 0.f, 0.f};
.LBB0_3792:
	v_and_b32_e32 v5, 48, v4
	v_lshlrev_b32_e32 v6, 6, v4
	s_movk_i32 s13, 0x3c0
	v_lshlrev_b32_e32 v4, 2, v4
	s_and_b32 s24, s23, 3
	s_lshl_b32 s9, s12, 6
	s_lshl_b32 s12, s12, 13
	v_and_or_b32 v5, v6, s13, v5
	v_and_b32_e32 v4, 32, v4
	v_bitop3_b32 v6, v5, s12, v4 bitop3:0xde
	s_lshl_b32 s12, s24, 12
	v_bitop3_b32 v4, v5, s12, v4 bitop3:0xde
	s_mov_b64 s[12:13], 0x80
	s_add_i32 m0, s25, 0x18000
	v_lshl_add_u64 v[2:3], v[2:3], 0, s[12:13]
	s_waitcnt vmcnt(2)
	s_barrier
	global_load_lds_dwordx4 v[2:3], off
	s_add_i32 m0, s25, 0x1a000
	s_add_u32 s20, s4, 0x8000
	v_lshl_add_u64 v[0:1], v[0:1], 0, s[12:13]
	s_addc_u32 s21, s5, 0
	s_add_i32 s36, s25, 0x8000
	global_load_lds_dwordx4 v[0:1], off
	v_lshl_add_u64 v[0:1], s[20:21], 0, v[128:129]
	s_mov_b32 m0, s36
	s_add_i32 s37, s25, 0xa000
	global_load_lds_dwordx4 v128, s[20:21]
	v_lshl_add_u64 v[0:1], s[20:21], 0, v[132:133]
	s_add_u32 s20, s0, 0x200080
	s_mov_b32 m0, s37
	s_addc_u32 s21, s1, 0
	global_load_lds_dwordx4 v[0:1], off
	s_add_i32 m0, s25, 0x1c000
	v_lshl_add_u64 v[0:1], s[20:21], 0, v[130:131]
	global_load_lds_dwordx4 v130, s[20:21]
	v_lshl_add_u64 v[0:1], s[20:21], 0, v[134:135]
	s_add_i32 m0, s25, 0x1e000
	s_add_u32 s38, s16, 0x18600100
	global_load_lds_dwordx4 v134, s[20:21]
	s_addc_u32 s39, s17, 0
	s_add_u32 s40, s14, 0x34610000
	s_waitcnt vmcnt(6)
	v_lshl_add_u64 v[0:1], s[14:15], 0, v[132:133]
	s_mov_b64 s[16:17], 0x3460c000
	s_addc_u32 s41, s15, 0
	s_add_i32 s45, 0, 0x10000
	s_add_i32 s47, 0, 0x14000
	s_add_i32 s49, 0, 0x18000
	s_add_i32 s51, 0, 0x1c000
	v_lshl_add_u64 v[136:137], v[0:1], 0, s[16:17]
	v_lshl_add_u64 v[0:1], s[14:15], 0, v[128:129]
	v_add_u32_e32 v140, s45, v4
	v_add_u32_e32 v141, s47, v4
	s_add_i32 s45, s45, s18
	s_add_i32 s47, s47, s18
	v_add_u32_e32 v143, s49, v4
	v_add_u32_e32 v144, s51, v4
	s_add_i32 s49, s49, s18
	s_add_i32 s51, s51, s18
	v_readlane_b32 s56, v254, 43
	v_lshl_add_u64 v[138:139], v[0:1], 0, s[16:17]
	s_mov_b32 s42, -2
	v_add_u32_e32 v142, 0, v6
	s_add_i32 s43, s25, 0xc000
	s_add_i32 s44, s25, 0xe000
	s_add_i32 s46, s45, 0x2000
	s_add_i32 s48, s47, 0x2000
	s_add_i32 s50, s49, 0x2000
	s_add_i32 s52, s51, 0x2000
	s_mov_b64 s[14:15], 0x10000
	v_mov_b32_e32 v0, v131
	v_mov_b32_e32 v1, v131
	v_mov_b32_e32 v2, v131
	v_mov_b32_e32 v3, v131
	v_mov_b32_e32 v4, v131
	v_mov_b32_e32 v5, v131
	v_mov_b32_e32 v6, v131
	v_mov_b32_e32 v7, v131
	v_mov_b32_e32 v16, v131
	v_mov_b32_e32 v17, v131
	v_mov_b32_e32 v18, v131
	v_mov_b32_e32 v19, v131
	v_mov_b32_e32 v20, v131
	v_mov_b32_e32 v21, v131
	v_mov_b32_e32 v22, v131
	v_mov_b32_e32 v23, v131
	v_mov_b32_e32 v48, v131
	v_mov_b32_e32 v49, v131
	v_mov_b32_e32 v50, v131
	v_mov_b32_e32 v51, v131
	v_mov_b32_e32 v52, v131
	v_mov_b32_e32 v53, v131
	v_mov_b32_e32 v54, v131
	v_mov_b32_e32 v55, v131
	v_mov_b32_e32 v112, v131
	v_mov_b32_e32 v113, v131
	v_mov_b32_e32 v114, v131
	v_mov_b32_e32 v115, v131
	v_mov_b32_e32 v116, v131
	v_mov_b32_e32 v117, v131
	v_mov_b32_e32 v118, v131
	v_mov_b32_e32 v119, v131
	v_mov_b32_e32 v8, v131
	v_mov_b32_e32 v9, v131
	v_mov_b32_e32 v10, v131
	v_mov_b32_e32 v11, v131
	v_mov_b32_e32 v12, v131
	v_mov_b32_e32 v13, v131
	v_mov_b32_e32 v14, v131
	v_mov_b32_e32 v15, v131
	v_mov_b32_e32 v24, v131
	v_mov_b32_e32 v25, v131
	v_mov_b32_e32 v26, v131
	v_mov_b32_e32 v27, v131
	v_mov_b32_e32 v28, v131
	v_mov_b32_e32 v29, v131
	v_mov_b32_e32 v30, v131
	v_mov_b32_e32 v31, v131
	v_mov_b32_e32 v72, v131
	v_mov_b32_e32 v73, v131
	v_mov_b32_e32 v74, v131
	v_mov_b32_e32 v75, v131
	v_mov_b32_e32 v88, v131
	v_mov_b32_e32 v89, v131
	v_mov_b32_e32 v90, v131
	v_mov_b32_e32 v91, v131
	v_mov_b32_e32 v120, v131
	v_mov_b32_e32 v121, v131
	v_mov_b32_e32 v122, v131
	v_mov_b32_e32 v123, v131
	v_mov_b32_e32 v124, v131
	v_mov_b32_e32 v125, v131
	v_mov_b32_e32 v126, v131
	v_mov_b32_e32 v127, v131
	v_mov_b32_e32 v96, v131
	v_mov_b32_e32 v97, v131
	v_mov_b32_e32 v98, v131
	v_mov_b32_e32 v99, v131
	v_mov_b32_e32 v100, v131
	v_mov_b32_e32 v101, v131
	v_mov_b32_e32 v102, v131
	v_mov_b32_e32 v103, v131
	v_mov_b32_e32 v56, v131
	v_mov_b32_e32 v57, v131
	v_mov_b32_e32 v58, v131
	v_mov_b32_e32 v59, v131
	v_mov_b32_e32 v60, v131
	v_mov_b32_e32 v61, v131
	v_mov_b32_e32 v62, v131
	v_mov_b32_e32 v63, v131
	v_mov_b32_e32 v64, v131
	v_mov_b32_e32 v65, v131
	v_mov_b32_e32 v66, v131
	v_mov_b32_e32 v67, v131
	v_mov_b32_e32 v68, v131
	v_mov_b32_e32 v69, v131
	v_mov_b32_e32 v70, v131
	v_mov_b32_e32 v71, v131
	v_mov_b32_e32 v44, v131
	v_mov_b32_e32 v45, v131
	v_mov_b32_e32 v46, v131
	v_mov_b32_e32 v47, v131
	v_mov_b32_e32 v40, v131
	v_mov_b32_e32 v41, v131
	v_mov_b32_e32 v42, v131
	v_mov_b32_e32 v43, v131
	v_mov_b32_e32 v104, v131
	v_mov_b32_e32 v105, v131
	v_mov_b32_e32 v106, v131
	v_mov_b32_e32 v107, v131
	v_mov_b32_e32 v108, v131
	v_mov_b32_e32 v109, v131
	v_mov_b32_e32 v110, v131
	v_mov_b32_e32 v111, v131
	v_mov_b32_e32 v84, v131
	v_mov_b32_e32 v85, v131
	v_mov_b32_e32 v86, v131
	v_mov_b32_e32 v87, v131
	v_mov_b32_e32 v92, v131
	v_mov_b32_e32 v93, v131
	v_mov_b32_e32 v94, v131
	v_mov_b32_e32 v95, v131
	v_mov_b32_e32 v80, v131
	v_mov_b32_e32 v81, v131
	v_mov_b32_e32 v82, v131
	v_mov_b32_e32 v83, v131
	v_mov_b32_e32 v76, v131
	v_mov_b32_e32 v77, v131
	v_mov_b32_e32 v78, v131
	v_mov_b32_e32 v79, v131
	v_mov_b32_e32 v36, v131
	v_mov_b32_e32 v37, v131
	v_mov_b32_e32 v38, v131
	v_mov_b32_e32 v39, v131
	v_mov_b32_e32 v32, v131
	v_mov_b32_e32 v33, v131
	v_mov_b32_e32 v34, v131
	v_mov_b32_e32 v35, v131
	v_readlane_b32 s58, v254, 45
	v_readlane_b32 s59, v254, 46
	s_barrier
	v_readlane_b32 s57, v254, 44
; #define PG8_MMA(ai, bj, At, Bt) do { __builtin_amdgcn_s_setprio(1); _Pragma("unroll") for (int m = 0; m < 4; ++m) _Pragma("unroll") for (int n = 0; n < 2; ++n) _Pragma("unroll") for (int k = 0; k < 2; ++k) \
;         acc[ai][bj][m][n] = __builtin_amdgcn_mfma_f32_16x16x32_bf16(Bt[n][k], At[m][k], acc[ai][bj][m][n], 0, 0, 0); __builtin_amdgcn_s_setprio(0); } while (0)
; template <class Epi, class Sched, bool ALIGN_EPI = false, bool SP2 = false, bool A_TILED = false>
; __device__ __forceinline__ void gemm_phase(PG8_LAS unsigned char* lds, const Gemm g, const Sched& S, const Epi& E, const int wave_s) {
;     ...
;         for (int t = PEEL ? 2 : 0; t < nt; t += 2) {
;             const bool last = (t == nt - 2);
;             const char* a1 = cA + (size_t)(t + 1) * kstepA;
;             const char* a2 = last ? nA : cA + (size_t)(t + 2) * kstepA; const char* b2 = last ? nB : cB + (size_t)(t + 2) * kstep;
;             const char* a3 = a2 + kstepA; const char* b3 = b2 + kstep;
;             if (last && has_next) S.a_ready(nxt);
;             if constexpr (SP2) {
;             PG8_ITER(PG8_MMA)
.LBB0_3793:
	ds_read_b128 v[146:149], v140
	ds_read_b128 v[150:153], v140 offset:1024
	ds_read_b128 v[154:157], v140 offset:2048
	ds_read_b128 v[158:161], v140 offset:3072
	ds_read_b128 v[162:165], v141
	ds_read_b128 v[166:169], v141 offset:1024
	ds_read_b128 v[170:173], v141 offset:2048
	ds_read_b128 v[174:177], v141 offset:3072
	s_add_u32 s16, s58, s40
	s_addc_u32 s17, s59, s41
	s_add_u32 s18, s58, s38
	s_addc_u32 s19, s59, s39
	s_cmpk_eq_i32 s42, 0x7c
	s_cselect_b32 s20, s4, s16
	s_cselect_b32 s21, s5, s17
	s_cselect_b32 s18, s0, s18
	s_cselect_b32 s19, s1, s19
	s_add_u32 s16, s20, 0x8000
	s_addc_u32 s17, s21, 0
	s_mov_b32 m0, s43
	v_lshl_add_u64 v[210:211], s[58:59], 0, v[138:139]
	ds_read_b128 v[178:181], v142
	ds_read_b128 v[182:185], v142 offset:1024
	ds_read_b128 v[186:189], v142 offset:2048
	ds_read_b128 v[190:193], v142 offset:3072
	ds_read_b128 v[194:197], v142 offset:4096
	ds_read_b128 v[198:201], v142 offset:5120
	ds_read_b128 v[202:205], v142 offset:6144
	ds_read_b128 v[206:209], v142 offset:7168
	global_load_lds_dwordx4 v[210:211], off
	v_lshl_add_u64 v[210:211], s[58:59], 0, v[136:137]
	s_mov_b32 m0, s44
	s_nop 0
	global_load_lds_dwordx4 v[210:211], off
	s_waitcnt vmcnt(8) lgkmcnt(0)
	s_setprio 1
	s_barrier
	v_mfma_f32_16x16x32_bf16 v[32:35], v[146:149], v[178:181], v[32:35]
	v_mfma_f32_16x16x32_bf16 v[36:39], v[154:157], v[178:181], v[36:39]
	v_mfma_f32_16x16x32_bf16 v[76:79], v[146:149], v[186:189], v[76:79]
	v_mfma_f32_16x16x32_bf16 v[80:83], v[154:157], v[186:189], v[80:83]
	v_mfma_f32_16x16x32_bf16 v[92:95], v[146:149], v[194:197], v[92:95]
	v_mfma_f32_16x16x32_bf16 v[84:87], v[154:157], v[194:197], v[84:87]
	v_mfma_f32_16x16x32_bf16 v[108:111], v[146:149], v[202:205], v[108:111]
	v_mfma_f32_16x16x32_bf16 v[104:107], v[154:157], v[202:205], v[104:107]
	v_mfma_f32_16x16x32_bf16 v[32:35], v[150:153], v[182:185], v[32:35]
	v_mfma_f32_16x16x32_bf16 v[36:39], v[158:161], v[182:185], v[36:39]
	v_mfma_f32_16x16x32_bf16 v[76:79], v[150:153], v[190:193], v[76:79]
	v_mfma_f32_16x16x32_bf16 v[80:83], v[158:161], v[190:193], v[80:83]
	v_mfma_f32_16x16x32_bf16 v[92:95], v[150:153], v[198:201], v[92:95]
	v_mfma_f32_16x16x32_bf16 v[84:87], v[158:161], v[198:201], v[84:87]
	v_mfma_f32_16x16x32_bf16 v[108:111], v[150:153], v[206:209], v[108:111]
	v_mfma_f32_16x16x32_bf16 v[104:107], v[158:161], v[206:209], v[104:107]
	s_setprio 0
	s_setprio 1
	v_mfma_f32_16x16x32_bf16 v[40:43], v[162:165], v[178:181], v[40:43]
	v_mfma_f32_16x16x32_bf16 v[44:47], v[170:173], v[178:181], v[44:47]
	v_mfma_f32_16x16x32_bf16 v[68:71], v[162:165], v[186:189], v[68:71]
	v_mfma_f32_16x16x32_bf16 v[64:67], v[170:173], v[186:189], v[64:67]
	v_mfma_f32_16x16x32_bf16 v[60:63], v[162:165], v[194:197], v[60:63]
	v_mfma_f32_16x16x32_bf16 v[56:59], v[170:173], v[194:197], v[56:59]
	v_mfma_f32_16x16x32_bf16 v[100:103], v[162:165], v[202:205], v[100:103]
	v_mfma_f32_16x16x32_bf16 v[96:99], v[170:173], v[202:205], v[96:99]
	v_mfma_f32_16x16x32_bf16 v[40:43], v[166:169], v[182:185], v[40:43]
	v_mfma_f32_16x16x32_bf16 v[44:47], v[174:177], v[182:185], v[44:47]
	v_mfma_f32_16x16x32_bf16 v[68:71], v[166:169], v[190:193], v[68:71]
	v_mfma_f32_16x16x32_bf16 v[64:67], v[174:177], v[190:193], v[64:67]
	v_mfma_f32_16x16x32_bf16 v[60:63], v[166:169], v[198:201], v[60:63]
	v_mfma_f32_16x16x32_bf16 v[56:59], v[174:177], v[198:201], v[56:59]
	v_mfma_f32_16x16x32_bf16 v[100:103], v[166:169], v[206:209], v[100:103]
	v_mfma_f32_16x16x32_bf16 v[96:99], v[174:177], v[206:209], v[96:99]
	s_barrier
	s_setprio 0
	s_mov_b32 m0, s45
	v_lshl_add_u64 v[210:211], s[18:19], 0, v[130:131]
	s_add_u32 s54, s18, 0x200000
	ds_read_b128 v[178:181], v142 offset:16384
	ds_read_b128 v[182:185], v142 offset:17408
	ds_read_b128 v[186:189], v142 offset:18432
	ds_read_b128 v[190:193], v142 offset:19456
	ds_read_b128 v[194:197], v142 offset:20480
	ds_read_b128 v[198:201], v142 offset:21504
	ds_read_b128 v[202:205], v142 offset:22528
	ds_read_b128 v[206:209], v142 offset:23552
	global_load_lds_dwordx4 v130, s[18:19]
	v_lshl_add_u64 v[212:213], s[18:19], 0, v[134:135]
	s_mov_b32 m0, s46
	s_addc_u32 s55, s19, 0
	global_load_lds_dwordx4 v134, s[18:19]
	v_lshl_add_u64 v[214:215], s[54:55], 0, v[130:131]
	s_mov_b32 m0, s47
	s_nop 0
	global_load_lds_dwordx4 v130, s[54:55]
	v_lshl_add_u64 v[214:215], s[54:55], 0, v[134:135]
	s_mov_b32 m0, s48
	s_nop 0
	global_load_lds_dwordx4 v134, s[54:55]
	v_lshl_add_u64 v[214:215], s[20:21], 0, v[128:129]
	s_mov_b32 m0, s25
	s_nop 0
	global_load_lds_dwordx4 v128, s[20:21]
	v_lshl_add_u64 v[214:215], s[20:21], 0, v[132:133]
	s_mov_b32 m0, s26
	s_nop 0
	global_load_lds_dwordx4 v132, s[20:21]
	s_waitcnt vmcnt(8) lgkmcnt(0)
	s_setprio 1
	s_barrier
	v_mfma_f32_16x16x32_bf16 v[124:127], v[146:149], v[178:181], v[124:127]
	v_mfma_f32_16x16x32_bf16 v[120:123], v[154:157], v[178:181], v[120:123]
	v_mfma_f32_16x16x32_bf16 v[88:91], v[146:149], v[186:189], v[88:91]
	v_mfma_f32_16x16x32_bf16 v[72:75], v[154:157], v[186:189], v[72:75]
	v_mfma_f32_16x16x32_bf16 v[28:31], v[146:149], v[194:197], v[28:31]
	v_mfma_f32_16x16x32_bf16 v[24:27], v[154:157], v[194:197], v[24:27]
	v_mfma_f32_16x16x32_bf16 v[12:15], v[146:149], v[202:205], v[12:15]
	v_mfma_f32_16x16x32_bf16 v[8:11], v[154:157], v[202:205], v[8:11]
	v_mfma_f32_16x16x32_bf16 v[124:127], v[150:153], v[182:185], v[124:127]
	v_mfma_f32_16x16x32_bf16 v[120:123], v[158:161], v[182:185], v[120:123]
	v_mfma_f32_16x16x32_bf16 v[88:91], v[150:153], v[190:193], v[88:91]
	v_mfma_f32_16x16x32_bf16 v[72:75], v[158:161], v[190:193], v[72:75]
	v_mfma_f32_16x16x32_bf16 v[28:31], v[150:153], v[198:201], v[28:31]
	v_mfma_f32_16x16x32_bf16 v[24:27], v[158:161], v[198:201], v[24:27]
	v_mfma_f32_16x16x32_bf16 v[12:15], v[150:153], v[206:209], v[12:15]
	v_mfma_f32_16x16x32_bf16 v[8:11], v[158:161], v[206:209], v[8:11]
	s_setprio 0
	s_setprio 1
	v_mfma_f32_16x16x32_bf16 v[116:119], v[162:165], v[178:181], v[116:119]
	v_mfma_f32_16x16x32_bf16 v[112:115], v[170:173], v[178:181], v[112:115]
	v_mfma_f32_16x16x32_bf16 v[52:55], v[162:165], v[186:189], v[52:55]
	v_mfma_f32_16x16x32_bf16 v[48:51], v[170:173], v[186:189], v[48:51]
	v_mfma_f32_16x16x32_bf16 v[20:23], v[162:165], v[194:197], v[20:23]
	v_mfma_f32_16x16x32_bf16 v[16:19], v[170:173], v[194:197], v[16:19]
	v_mfma_f32_16x16x32_bf16 v[4:7], v[162:165], v[202:205], v[4:7]
	v_mfma_f32_16x16x32_bf16 v[0:3], v[170:173], v[202:205], v[0:3]
	v_mfma_f32_16x16x32_bf16 v[116:119], v[166:169], v[182:185], v[116:119]
	v_mfma_f32_16x16x32_bf16 v[112:115], v[174:177], v[182:185], v[112:115]
	v_mfma_f32_16x16x32_bf16 v[52:55], v[166:169], v[190:193], v[52:55]
	v_mfma_f32_16x16x32_bf16 v[48:51], v[174:177], v[190:193], v[48:51]
	v_mfma_f32_16x16x32_bf16 v[20:23], v[166:169], v[198:201], v[20:23]
	v_mfma_f32_16x16x32_bf16 v[16:19], v[174:177], v[198:201], v[16:19]
	v_mfma_f32_16x16x32_bf16 v[4:7], v[166:169], v[206:209], v[4:7]
	v_mfma_f32_16x16x32_bf16 v[0:3], v[174:177], v[206:209], v[0:3]
	s_barrier
	s_setprio 0
	ds_read_b128 v[146:149], v143
	ds_read_b128 v[150:153], v143 offset:1024
	ds_read_b128 v[154:157], v143 offset:2048
	ds_read_b128 v[158:161], v143 offset:3072
	ds_read_b128 v[162:165], v144
	ds_read_b128 v[166:169], v144 offset:1024
	ds_read_b128 v[170:173], v144 offset:2048
	ds_read_b128 v[174:177], v144 offset:3072
	s_add_u32 s20, s20, 0x4000
	s_addc_u32 s21, s21, 0
	s_mov_b32 m0, s27
	v_lshl_add_u64 v[214:215], s[20:21], 0, v[128:129]
	ds_read_b128 v[178:181], v142 offset:32768
	ds_read_b128 v[182:185], v142 offset:33792
	ds_read_b128 v[186:189], v142 offset:34816
	ds_read_b128 v[190:193], v142 offset:35840
	ds_read_b128 v[194:197], v142 offset:36864
	ds_read_b128 v[198:201], v142 offset:37888
	ds_read_b128 v[202:205], v142 offset:38912
	ds_read_b128 v[206:209], v142 offset:39936
	global_load_lds_dwordx4 v128, s[20:21]
	v_lshl_add_u64 v[214:215], s[20:21], 0, v[132:133]
	s_mov_b32 m0, s34
	s_nop 0
	global_load_lds_dwordx4 v132, s[20:21]
	s_waitcnt vmcnt(8) lgkmcnt(0)
	s_setprio 1
	s_barrier
	v_mfma_f32_16x16x32_bf16 v[32:35], v[146:149], v[178:181], v[32:35]
	v_mfma_f32_16x16x32_bf16 v[36:39], v[154:157], v[178:181], v[36:39]
	v_mfma_f32_16x16x32_bf16 v[76:79], v[146:149], v[186:189], v[76:79]
	v_mfma_f32_16x16x32_bf16 v[80:83], v[154:157], v[186:189], v[80:83]
	v_mfma_f32_16x16x32_bf16 v[92:95], v[146:149], v[194:197], v[92:95]
	v_mfma_f32_16x16x32_bf16 v[84:87], v[154:157], v[194:197], v[84:87]
	v_mfma_f32_16x16x32_bf16 v[108:111], v[146:149], v[202:205], v[108:111]
	v_mfma_f32_16x16x32_bf16 v[104:107], v[154:157], v[202:205], v[104:107]
	v_mfma_f32_16x16x32_bf16 v[32:35], v[150:153], v[182:185], v[32:35]
	v_mfma_f32_16x16x32_bf16 v[36:39], v[158:161], v[182:185], v[36:39]
	v_mfma_f32_16x16x32_bf16 v[76:79], v[150:153], v[190:193], v[76:79]
	v_mfma_f32_16x16x32_bf16 v[80:83], v[158:161], v[190:193], v[80:83]
	v_mfma_f32_16x16x32_bf16 v[92:95], v[150:153], v[198:201], v[92:95]
	v_mfma_f32_16x16x32_bf16 v[84:87], v[158:161], v[198:201], v[84:87]
	v_mfma_f32_16x16x32_bf16 v[108:111], v[150:153], v[206:209], v[108:111]
	v_mfma_f32_16x16x32_bf16 v[104:107], v[158:161], v[206:209], v[104:107]
	s_setprio 0
	s_setprio 1
	v_mfma_f32_16x16x32_bf16 v[40:43], v[162:165], v[178:181], v[40:43]
	v_mfma_f32_16x16x32_bf16 v[44:47], v[170:173], v[178:181], v[44:47]
	v_mfma_f32_16x16x32_bf16 v[68:71], v[162:165], v[186:189], v[68:71]
	v_mfma_f32_16x16x32_bf16 v[64:67], v[170:173], v[186:189], v[64:67]
	v_mfma_f32_16x16x32_bf16 v[60:63], v[162:165], v[194:197], v[60:63]
	v_mfma_f32_16x16x32_bf16 v[56:59], v[170:173], v[194:197], v[56:59]
	v_mfma_f32_16x16x32_bf16 v[100:103], v[162:165], v[202:205], v[100:103]
	v_mfma_f32_16x16x32_bf16 v[96:99], v[170:173], v[202:205], v[96:99]
	v_mfma_f32_16x16x32_bf16 v[40:43], v[166:169], v[182:185], v[40:43]
	v_mfma_f32_16x16x32_bf16 v[44:47], v[174:177], v[182:185], v[44:47]
	v_mfma_f32_16x16x32_bf16 v[68:71], v[166:169], v[190:193], v[68:71]
	v_mfma_f32_16x16x32_bf16 v[64:67], v[174:177], v[190:193], v[64:67]
	v_mfma_f32_16x16x32_bf16 v[60:63], v[166:169], v[198:201], v[60:63]
	v_mfma_f32_16x16x32_bf16 v[56:59], v[174:177], v[198:201], v[56:59]
	v_mfma_f32_16x16x32_bf16 v[100:103], v[166:169], v[206:209], v[100:103]
	v_mfma_f32_16x16x32_bf16 v[96:99], v[174:177], v[206:209], v[96:99]
	s_barrier
; #define PG8_MMA(ai, bj, At, Bt) do { __builtin_amdgcn_s_setprio(1); _Pragma("unroll") for (int m = 0; m < 4; ++m) _Pragma("unroll") for (int n = 0; n < 2; ++n) _Pragma("unroll") for (int k = 0; k < 2; ++k) \
;         acc[ai][bj][m][n] = __builtin_amdgcn_mfma_f32_16x16x32_bf16(Bt[n][k], At[m][k], acc[ai][bj][m][n], 0, 0, 0); __builtin_amdgcn_s_setprio(0); } while (0)
; template <class Epi, class Sched, bool ALIGN_EPI = false, bool SP2 = false, bool A_TILED = false>
; __device__ __forceinline__ void gemm_phase(PG8_LAS unsigned char* lds, const Gemm g, const Sched& S, const Epi& E, const int wave_s) {
;     ...
; #pragma nounroll
;         for (int t = PEEL ? 2 : 0; t < nt; t += 2) {
;             const bool last = (t == nt - 2);
;             const char* a1 = cA + (size_t)(t + 1) * kstepA;
;             const char* a2 = last ? nA : cA + (size_t)(t + 2) * kstepA; const char* b2 = last ? nB : cB + (size_t)(t + 2) * kstep;
;             const char* a3 = a2 + kstepA; const char* b3 = b2 + kstep;
;             if (last && has_next) S.a_ready(nxt);
;             if constexpr (SP2) {
;             PG8_ITER(PG8_MMA)
	s_setprio 0
	s_mov_b32 m0, s49
	v_lshl_add_u64 v[210:211], v[210:211], 0, s[12:13]
	s_add_u32 s18, s18, 0x200080
	ds_read_b128 v[178:181], v142 offset:49152
	ds_read_b128 v[182:185], v142 offset:50176
	ds_read_b128 v[186:189], v142 offset:51200
	ds_read_b128 v[190:193], v142 offset:52224
	ds_read_b128 v[194:197], v142 offset:53248
	ds_read_b128 v[198:201], v142 offset:54272
	ds_read_b128 v[202:205], v142 offset:55296
	ds_read_b128 v[206:209], v142 offset:56320
	global_load_lds_dwordx4 v[210:211], off
	v_lshl_add_u64 v[210:211], v[212:213], 0, s[12:13]
	s_mov_b32 m0, s50
	s_addc_u32 s19, s19, 0
	global_load_lds_dwordx4 v[210:211], off
	v_lshl_add_u64 v[210:211], s[18:19], 0, v[130:131]
	s_mov_b32 m0, s51
	s_nop 0
	global_load_lds_dwordx4 v130, s[18:19]
	v_lshl_add_u64 v[210:211], s[18:19], 0, v[134:135]
	s_mov_b32 m0, s52
	s_nop 0
	global_load_lds_dwordx4 v134, s[18:19]
	v_lshl_add_u64 v[210:211], s[16:17], 0, v[128:129]
	s_mov_b32 m0, s36
	s_nop 0
	global_load_lds_dwordx4 v128, s[16:17]
	v_lshl_add_u64 v[210:211], s[16:17], 0, v[132:133]
	s_mov_b32 m0, s37
	s_nop 0
	global_load_lds_dwordx4 v132, s[16:17]
	s_waitcnt vmcnt(8) lgkmcnt(0)
	s_setprio 1
	s_barrier
	v_mfma_f32_16x16x32_bf16 v[124:127], v[146:149], v[178:181], v[124:127]
	v_mfma_f32_16x16x32_bf16 v[120:123], v[154:157], v[178:181], v[120:123]
	v_mfma_f32_16x16x32_bf16 v[88:91], v[146:149], v[186:189], v[88:91]
	v_mfma_f32_16x16x32_bf16 v[72:75], v[154:157], v[186:189], v[72:75]
	v_mfma_f32_16x16x32_bf16 v[28:31], v[146:149], v[194:197], v[28:31]
	v_mfma_f32_16x16x32_bf16 v[24:27], v[154:157], v[194:197], v[24:27]
	v_mfma_f32_16x16x32_bf16 v[12:15], v[146:149], v[202:205], v[12:15]
	v_mfma_f32_16x16x32_bf16 v[8:11], v[154:157], v[202:205], v[8:11]
	v_mfma_f32_16x16x32_bf16 v[124:127], v[150:153], v[182:185], v[124:127]
	v_mfma_f32_16x16x32_bf16 v[120:123], v[158:161], v[182:185], v[120:123]
	v_mfma_f32_16x16x32_bf16 v[88:91], v[150:153], v[190:193], v[88:91]
	v_mfma_f32_16x16x32_bf16 v[72:75], v[158:161], v[190:193], v[72:75]
	v_mfma_f32_16x16x32_bf16 v[28:31], v[150:153], v[198:201], v[28:31]
	v_mfma_f32_16x16x32_bf16 v[24:27], v[158:161], v[198:201], v[24:27]
	v_mfma_f32_16x16x32_bf16 v[12:15], v[150:153], v[206:209], v[12:15]
	v_mfma_f32_16x16x32_bf16 v[8:11], v[158:161], v[206:209], v[8:11]
	s_setprio 0
	s_setprio 1
	v_mfma_f32_16x16x32_bf16 v[116:119], v[162:165], v[178:181], v[116:119]
	v_mfma_f32_16x16x32_bf16 v[112:115], v[170:173], v[178:181], v[112:115]
	v_mfma_f32_16x16x32_bf16 v[52:55], v[162:165], v[186:189], v[52:55]
	v_mfma_f32_16x16x32_bf16 v[48:51], v[170:173], v[186:189], v[48:51]
	v_mfma_f32_16x16x32_bf16 v[20:23], v[162:165], v[194:197], v[20:23]
	v_mfma_f32_16x16x32_bf16 v[16:19], v[170:173], v[194:197], v[16:19]
	v_mfma_f32_16x16x32_bf16 v[4:7], v[162:165], v[202:205], v[4:7]
	v_mfma_f32_16x16x32_bf16 v[0:3], v[170:173], v[202:205], v[0:3]
	v_mfma_f32_16x16x32_bf16 v[116:119], v[166:169], v[182:185], v[116:119]
	v_mfma_f32_16x16x32_bf16 v[112:115], v[174:177], v[182:185], v[112:115]
	v_mfma_f32_16x16x32_bf16 v[52:55], v[166:169], v[190:193], v[52:55]
	v_mfma_f32_16x16x32_bf16 v[48:51], v[174:177], v[190:193], v[48:51]
	v_mfma_f32_16x16x32_bf16 v[20:23], v[166:169], v[198:201], v[20:23]
	v_mfma_f32_16x16x32_bf16 v[16:19], v[174:177], v[198:201], v[16:19]
	v_mfma_f32_16x16x32_bf16 v[4:7], v[166:169], v[206:209], v[4:7]
	v_mfma_f32_16x16x32_bf16 v[0:3], v[174:177], v[206:209], v[0:3]
	s_barrier
	s_setprio 0
	s_add_i32 s42, s42, 2
	s_add_u32 s38, s38, 0x100
	s_addc_u32 s39, s39, 0
	s_add_u32 s40, s40, 0x10000
	s_addc_u32 s41, s41, 0
	v_lshl_add_u64 v[136:137], v[136:137], 0, s[14:15]
	s_cmpk_gt_u32 s42, 0x7d
	v_lshl_add_u64 v[138:139], v[138:139], 0, s[14:15]
	s_cbranch_scc0 .LBB0_3793
	s_waitcnt vmcnt(0)
	s_cmpk_lt_u32 s22, 0x100
	s_cbranch_scc0 .LBB0_3796
	s_barrier
